# v25: v16 + row-wise phases (norm/readout/final norm): nt flag dropped from the 8-byte row loads (plain loads through L1)
# baseline (speedup 1.0000x reference)
; #define GAS __attribute__((address_space(1)))
; #define LAS __attribute__((address_space(3)))
; __device__ __forceinline__ void relaunder(Frame& F) { int t = mk_tid(); asm volatile("" : "+v"(t)); F.tid = t; F.lane = t & 63; F.wave = __builtin_amdgcn_readfirstlane(t >> 6); }
; #define NR_LOAD(dst, k_) do { const GAS v2u* xr_ = (const GAS v2u*)(X + (size_t)(nw + 2048 * (k_)) * D) + F.lane; \
;         _Pragma("unroll") for (int j = 0; j < 8; ++j) dst[j] = __builtin_nontemporal_load(xr_ + 64 * j); } while (0)
; __device__ __forceinline__ void norm_mod_phase2(const Args& a, Frame& F, const float* gain, const float* modl, int sh_off, int sc_off, int nrows, const float* slab_gate) {
;     relaunder(F);
;     static_assert(ML == 8 * 2048 && MC <= 2048, "8 latent rows and at most one context row per wave of 2048");
;     const int nw = F.vcu * NWAVES + F.wave;
;     bf16* X = (bf16*)(a.ws + WS_X); bf16* HN = (bf16*)(a.ws + WS_HN);
;     LAS float* CA = (LAS float*)F.lds; LAS float* CB = CA + 5 * D;
;     v2u r0[8], r1[8], r2[8], r3[8], r4[8], r5[8], r6[8], r7[8];
;     ...
;     NR_LOAD(r0, 0); NR_LOAD(r1, 1); NR_LOAD(r2, 2); NR_LOAD(r3, 3); NR_LOAD(r4, 4); NR_LOAD(r5, 5); NR_LOAD(r6, 6); NR_LOAD(r7, 7);
;     { const GAS f32x4* g4 = (const GAS f32x4*)gain;
;       for (int q = F.tid; q < 5 * D / 4; q += NWAVES * 64) { const int bq = q >> 9, cq = q & 511; const GAS f32x4* mb4 = (const GAS f32x4*)(modl + (size_t)bq * MOD_LD);
;           ((LAS f32x4*)CA)[q] = g4[cq] * (mb4[sc_off / 4 + cq] + 1.0f); ((LAS f32x4*)CB)[q] = mb4[sh_off / 4 + cq]; } }
;     asm volatile("s_waitcnt lgkmcnt(0)" ::: "memory"); __builtin_amdgcn_s_barrier(); asm volatile("" ::: "memory");
.LBB0_215:
	s_andn2_b64 vcc, exec, s[4:5]
	s_cbranch_vccnz .LBB0_224
	s_getreg_b32 s4, hwreg(HW_REG_HW_ID, 0, 6)
	s_lshl_b32 s4, s4, 2
	s_add_i32 s4, s4, 0
	s_add_i32 s4, s4, 0x20540
	v_mov_b32_e32 v0, s4
	ds_read_b32 v0, v0
	v_mov_b64_e32 v[2:3], s[0:1]
	v_mbcnt_lo_u32_b32 v4, -1, 0
	v_mbcnt_hi_u32_b32 v4, -1, v4
	s_mov_b64 s[20:21], 0x400000
	v_mov_b32_e32 v7, v1
	s_waitcnt lgkmcnt(0)
	v_readfirstlane_b32 s4, v0
	s_nop 1
	v_lshl_add_u32 v142, s4, 6, v4
	v_mov_b32_e32 v128, s72
	v_mov_b32_e32 v129, s73
	v_readfirstlane_b32 s4, v142
	s_ashr_i32 s4, s4, 6
	s_add_i32 s4, s4, s91
	s_ashr_i32 s5, s4, 31
	s_add_i32 s36, s4, 0x800
	s_add_i32 s30, s4, 0x1000
	s_add_i32 s26, s4, 0x1800
	s_add_i32 s22, s4, 0x2000
	s_add_i32 s18, s4, 0x2800
	v_and_b32_e32 v143, 63, v142
	s_lshl_b64 s[6:7], s[4:5], 12
	s_ashr_i32 s37, s36, 31
	s_ashr_i32 s31, s30, 31
	s_ashr_i32 s27, s26, 31
	s_ashr_i32 s23, s22, 31
	s_ashr_i32 s19, s18, 31
	v_lshlrev_b32_e32 v6, 3, v143
	s_lshl_b64 s[8:9], s[36:37], 12
	s_lshl_b64 s[10:11], s[30:31], 12
	s_lshl_b64 s[12:13], s[26:27], 12
	s_lshl_b64 s[14:15], s[22:23], 12
	s_lshl_b64 s[16:17], s[18:19], 12
	s_waitcnt vmcnt(0) lgkmcnt(0)
	v_lshl_add_u64 v[8:9], v[128:129], 0, s[20:21]
	v_lshl_add_u64 v[2:3], v[8:9], 0, s[6:7]
	v_lshl_add_u64 v[4:5], v[8:9], 0, s[8:9]
	v_lshl_add_u64 v[10:11], v[8:9], 0, s[10:11]
	v_lshl_add_u64 v[12:13], v[8:9], 0, s[12:13]
	v_lshl_add_u64 v[14:15], v[8:9], 0, s[14:15]
	v_lshl_add_u64 v[16:17], v[8:9], 0, s[16:17]
	v_lshl_add_u64 v[2:3], v[2:3], 0, v[6:7]
	v_lshl_add_u64 v[4:5], v[4:5], 0, v[6:7]
	v_lshl_add_u64 v[10:11], v[10:11], 0, v[6:7]
	v_lshl_add_u64 v[12:13], v[12:13], 0, v[6:7]
	v_lshl_add_u64 v[14:15], v[14:15], 0, v[6:7]
	v_lshl_add_u64 v[16:17], v[16:17], 0, v[6:7]
	v_and_b32_e32 v184, 0x1ff, v142
	v_lshlrev_b32_e32 v184, 4, v184
	v_mov_b32_e32 v185, 0
	v_mov_b32_e32 v186, s76
	v_lshlrev_b32_e32 v186, 13, v186
	v_mov_b32_e32 v187, 0
	v_lshl_add_u64 v[188:189], v[74:75], 0, v[186:187]
	v_lshl_add_u64 v[188:189], v[188:189], 0, v[184:185]
	global_load_dwordx4 v[192:195], v[188:189], off
	v_add_u32_e32 v196, 0x2000, v184
	v_mov_b32_e32 v201, v184
	v_add_u32_e32 v197, 0xe000, v184
	v_add_u32_e32 v202, 0xc000, v184
	v_add_u32_e32 v198, 0x1a000, v184
	v_add_u32_e32 v203, 0x18000, v184
	v_add_u32_e32 v199, 0x26000, v184
	v_add_u32_e32 v204, 0x24000, v184
	v_add_u32_e32 v200, 0x32000, v184
	v_add_u32_e32 v205, 0x30000, v184
	global_load_dwordx4 v[208:211], v196, s[86:87]
	global_load_dwordx4 v[228:231], v201, s[86:87]
	global_load_dwordx4 v[212:215], v197, s[86:87]
	global_load_dwordx4 v[232:235], v202, s[86:87]
	global_load_dwordx4 v[216:219], v198, s[86:87]
	global_load_dwordx4 v[236:239], v203, s[86:87]
	global_load_dwordx4 v[220:223], v199, s[86:87]
	global_load_dwordx4 v[240:243], v204, s[86:87]
	global_load_dwordx4 v[224:227], v200, s[86:87]
	global_load_dwordx4 v[244:247], v205, s[86:87]
	global_load_dwordx2 v[140:141], v[2:3], off
	global_load_dwordx2 v[138:139], v[2:3], off offset:512
	global_load_dwordx2 v[136:137], v[2:3], off offset:1024
	global_load_dwordx2 v[132:133], v[2:3], off offset:1536
	global_load_dwordx2 v[134:135], v[2:3], off offset:2048
	global_load_dwordx2 v[124:125], v[2:3], off offset:2560
	global_load_dwordx2 v[126:127], v[2:3], off offset:3072
	global_load_dwordx2 v[130:131], v[2:3], off offset:3584
	global_load_dwordx2 v[122:123], v[4:5], off
	global_load_dwordx2 v[120:121], v[4:5], off offset:512
	global_load_dwordx2 v[118:119], v[4:5], off offset:1024
	global_load_dwordx2 v[116:117], v[4:5], off offset:1536
	global_load_dwordx2 v[114:115], v[4:5], off offset:2048
	global_load_dwordx2 v[112:113], v[4:5], off offset:2560
	global_load_dwordx2 v[110:111], v[4:5], off offset:3072
	global_load_dwordx2 v[108:109], v[4:5], off offset:3584
	global_load_dwordx2 v[106:107], v[10:11], off
	global_load_dwordx2 v[104:105], v[10:11], off offset:512
	global_load_dwordx2 v[102:103], v[10:11], off offset:1024
	global_load_dwordx2 v[100:101], v[10:11], off offset:1536
	global_load_dwordx2 v[98:99], v[10:11], off offset:2048
	global_load_dwordx2 v[96:97], v[10:11], off offset:2560
	global_load_dwordx2 v[94:95], v[10:11], off offset:3072
	global_load_dwordx2 v[92:93], v[10:11], off offset:3584
	global_load_dwordx2 v[90:91], v[12:13], off
	global_load_dwordx2 v[88:89], v[12:13], off offset:512
	global_load_dwordx2 v[86:87], v[12:13], off offset:1024
	global_load_dwordx2 v[84:85], v[12:13], off offset:1536
	global_load_dwordx2 v[82:83], v[12:13], off offset:2048
	global_load_dwordx2 v[80:81], v[12:13], off offset:2560
	global_load_dwordx2 v[78:79], v[12:13], off offset:3072
	global_load_dwordx2 v[76:77], v[12:13], off offset:3584
	global_load_dwordx2 v[72:73], v[14:15], off
	global_load_dwordx2 v[70:71], v[14:15], off offset:512
	global_load_dwordx2 v[68:69], v[14:15], off offset:1024
	global_load_dwordx2 v[66:67], v[14:15], off offset:1536
	global_load_dwordx2 v[64:65], v[14:15], off offset:2048
	global_load_dwordx2 v[62:63], v[14:15], off offset:2560
	global_load_dwordx2 v[60:61], v[14:15], off offset:3072
	global_load_dwordx2 v[58:59], v[14:15], off offset:3584
	global_load_dwordx2 v[56:57], v[16:17], off
	global_load_dwordx2 v[54:55], v[16:17], off offset:512
	global_load_dwordx2 v[52:53], v[16:17], off offset:1024
	global_load_dwordx2 v[50:51], v[16:17], off offset:1536
	global_load_dwordx2 v[48:49], v[16:17], off offset:2048
	global_load_dwordx2 v[46:47], v[16:17], off offset:2560
	global_load_dwordx2 v[44:45], v[16:17], off offset:3072
	global_load_dwordx2 v[42:43], v[16:17], off offset:3584
	s_add_i32 s14, s4, 0x3000
	s_ashr_i32 s15, s14, 31
	s_lshl_b64 s[6:7], s[14:15], 12
	s_add_i32 s10, s4, 0x3800
	v_lshl_add_u64 v[2:3], v[8:9], 0, s[6:7]
	s_ashr_i32 s11, s10, 31
	v_lshl_add_u64 v[2:3], v[2:3], 0, v[6:7]
	s_lshl_b64 s[6:7], s[10:11], 12
	global_load_dwordx2 v[40:41], v[2:3], off
	global_load_dwordx2 v[38:39], v[2:3], off offset:512
	global_load_dwordx2 v[36:37], v[2:3], off offset:1024
	global_load_dwordx2 v[34:35], v[2:3], off offset:1536
	global_load_dwordx2 v[32:33], v[2:3], off offset:2048
	global_load_dwordx2 v[30:31], v[2:3], off offset:2560
	global_load_dwordx2 v[28:29], v[2:3], off offset:3072
	global_load_dwordx2 v[26:27], v[2:3], off offset:3584
	v_lshl_add_u64 v[2:3], v[8:9], 0, s[6:7]
	v_lshl_add_u64 v[2:3], v[2:3], 0, v[6:7]
	global_load_dwordx2 v[24:25], v[2:3], off
	global_load_dwordx2 v[22:23], v[2:3], off offset:512
	global_load_dwordx2 v[20:21], v[2:3], off offset:1024
	global_load_dwordx2 v[18:19], v[2:3], off offset:1536
	global_load_dwordx2 v[16:17], v[2:3], off offset:2048
	global_load_dwordx2 v[14:15], v[2:3], off offset:2560
	global_load_dwordx2 v[12:13], v[2:3], off offset:3072
	global_load_dwordx2 v[10:11], v[2:3], off offset:3584
	s_waitcnt vmcnt(62)
; #define GAS __attribute__((address_space(1)))
; #define LAS __attribute__((address_space(3)))
; __device__ __forceinline__ void norm_mod_phase2(const Args& a, Frame& F, const float* gain, const float* modl, int sh_off, int sc_off, int nrows, const float* slab_gate) {
;     ...
;     { const GAS f32x4* g4 = (const GAS f32x4*)gain;
;       for (int q = F.tid; q < 5 * D / 4; q += NWAVES * 64) { const int bq = q >> 9, cq = q & 511; const GAS f32x4* mb4 = (const GAS f32x4*)(modl + (size_t)bq * MOD_LD);
;           ((LAS f32x4*)CA)[q] = g4[cq] * (mb4[sc_off / 4 + cq] + 1.0f); ((LAS f32x4*)CB)[q] = mb4[sh_off / 4 + cq]; } }
;     asm volatile("s_waitcnt lgkmcnt(0)" ::: "memory"); __builtin_amdgcn_s_barrier(); asm volatile("" ::: "memory");
;     NR_FINISH(r0, nw,            (nw) >> 12);
	v_lshl_add_u32 v184, v142, 4, 0
	v_add_u32_e32 v185, 0xa000, v184
	v_pk_add_f32 v[210:211], v[210:211], 1.0 op_sel_hi:[1,0]
	v_pk_add_f32 v[208:209], v[208:209], 1.0 op_sel_hi:[1,0]
	v_pk_mul_f32 v[210:211], v[194:195], v[210:211]
	v_pk_mul_f32 v[208:209], v[192:193], v[208:209]
	ds_write_b128 v184, v[208:211]
	ds_write_b128 v185, v[228:231]
	v_pk_add_f32 v[214:215], v[214:215], 1.0 op_sel_hi:[1,0]
	v_pk_add_f32 v[212:213], v[212:213], 1.0 op_sel_hi:[1,0]
	v_pk_mul_f32 v[214:215], v[194:195], v[214:215]
	v_pk_mul_f32 v[212:213], v[192:193], v[212:213]
	ds_write_b128 v184, v[212:215] offset:8192
	ds_write_b128 v185, v[232:235] offset:8192
	v_pk_add_f32 v[218:219], v[218:219], 1.0 op_sel_hi:[1,0]
	v_pk_add_f32 v[216:217], v[216:217], 1.0 op_sel_hi:[1,0]
	v_pk_mul_f32 v[218:219], v[194:195], v[218:219]
	v_pk_mul_f32 v[216:217], v[192:193], v[216:217]
	ds_write_b128 v184, v[216:219] offset:16384
	ds_write_b128 v185, v[236:239] offset:16384
	v_pk_add_f32 v[222:223], v[222:223], 1.0 op_sel_hi:[1,0]
	v_pk_add_f32 v[220:221], v[220:221], 1.0 op_sel_hi:[1,0]
	v_pk_mul_f32 v[222:223], v[194:195], v[222:223]
	v_pk_mul_f32 v[220:221], v[192:193], v[220:221]
	ds_write_b128 v184, v[220:223] offset:24576
	ds_write_b128 v185, v[240:243] offset:24576
	v_pk_add_f32 v[226:227], v[226:227], 1.0 op_sel_hi:[1,0]
	v_pk_add_f32 v[224:225], v[224:225], 1.0 op_sel_hi:[1,0]
	v_pk_mul_f32 v[226:227], v[194:195], v[226:227]
	v_pk_mul_f32 v[224:225], v[192:193], v[224:225]
	ds_write_b128 v184, v[224:227] offset:32768
	ds_write_b128 v185, v[244:247] offset:32768
	s_waitcnt vmcnt(62)
	v_cvt_f32_f16_sdwa v153, v140 dst_sel:DWORD dst_unused:UNUSED_PAD src0_sel:WORD_1
	v_cvt_f32_f16_sdwa v149, v138 dst_sel:DWORD dst_unused:UNUSED_PAD src0_sel:WORD_1
	v_cvt_f32_f16_e32 v152, v140
	v_cvt_f32_f16_sdwa v155, v141 dst_sel:DWORD dst_unused:UNUSED_PAD src0_sel:WORD_1
	v_cvt_f32_f16_e32 v148, v138
	v_cvt_f32_f16_sdwa v151, v139 dst_sel:DWORD dst_unused:UNUSED_PAD src0_sel:WORD_1
	v_cvt_f32_f16_e32 v154, v141
	v_cvt_f32_f16_e32 v150, v139
	s_waitcnt vmcnt(61)
	v_cvt_f32_f16_sdwa v139, v136 dst_sel:DWORD dst_unused:UNUSED_PAD src0_sel:WORD_1
	v_cvt_f32_f16_sdwa v141, v137 dst_sel:DWORD dst_unused:UNUSED_PAD src0_sel:WORD_1
	s_mov_b64 s[6:7], 0x8c00000
	v_mov_b32_e32 v74, v153
	v_mov_b32_e32 v75, v149
	v_cvt_f32_f16_e32 v138, v136
	v_cvt_f32_f16_e32 v140, v137
	v_lshl_add_u64 v[2:3], v[128:129], 0, s[6:7]
	v_mov_b32_e32 v4, v152
	v_mov_b32_e32 v5, v148
	v_pk_mul_f32 v[74:75], v[74:75], v[74:75]
	v_mov_b32_e32 v128, v155
	v_mov_b32_e32 v129, v151
	v_pk_fma_f32 v[4:5], v[4:5], v[4:5], v[74:75]
	v_mov_b32_e32 v74, v154
	v_mov_b32_e32 v75, v150
	v_pk_mul_f32 v[128:129], v[128:129], v[128:129]
	s_waitcnt vmcnt(60)
	v_cvt_f32_f16_sdwa v145, v132 dst_sel:DWORD dst_unused:UNUSED_PAD src0_sel:WORD_1
	v_pk_fma_f32 v[74:75], v[74:75], v[74:75], v[128:129]
	v_mov_b32_e32 v128, v139
	v_mov_b32_e32 v129, v141
	v_pk_add_f32 v[4:5], v[4:5], v[74:75]
	v_mov_b32_e32 v74, v138
	v_mov_b32_e32 v75, v140
	v_pk_mul_f32 v[128:129], v[128:129], v[128:129]
	v_cvt_f32_f16_e32 v144, v132
	v_cvt_f32_f16_sdwa v147, v133 dst_sel:DWORD dst_unused:UNUSED_PAD src0_sel:WORD_1
	v_pk_fma_f32 v[74:75], v[74:75], v[74:75], v[128:129]
	v_cvt_f32_f16_e32 v146, v133
	s_waitcnt vmcnt(59)
	v_cvt_f32_f16_sdwa v129, v134 dst_sel:DWORD dst_unused:UNUSED_PAD src0_sel:WORD_1
	v_cvt_f32_f16_e32 v128, v134
	v_cvt_f32_f16_sdwa v133, v135 dst_sel:DWORD dst_unused:UNUSED_PAD src0_sel:WORD_1
	v_cvt_f32_f16_e32 v132, v135
	v_mul_f32_e32 v0, v145, v145
	v_pk_fma_f32 v[136:137], v[144:145], v[144:145], v[0:1] op_sel_hi:[1,1,0]
	v_mul_f32_e32 v0, v147, v147
	v_pk_add_f32 v[4:5], v[4:5], v[4:5] op_sel:[0,1] op_sel_hi:[1,0]
	v_pk_add_f32 v[74:75], v[74:75], v[74:75] op_sel:[0,1] op_sel_hi:[1,0]
	v_pk_fma_f32 v[156:157], v[146:147], v[146:147], v[0:1] op_sel_hi:[1,1,0]
	v_pk_mul_f32 v[134:135], v[128:129], v[128:129]
	v_pk_mul_f32 v[158:159], v[132:133], v[132:133]
	v_mov_b32_e32 v5, v134
	v_mov_b32_e32 v75, v135
	v_mov_b32_e32 v137, v158
	v_mov_b32_e32 v157, v159
	v_pk_add_f32 v[4:5], v[4:5], v[74:75]
	v_pk_add_f32 v[74:75], v[136:137], v[156:157]
	s_waitcnt vmcnt(58)
	v_cvt_f32_f16_sdwa v135, v124 dst_sel:DWORD dst_unused:UNUSED_PAD src0_sel:WORD_1
	v_cvt_f32_f16_sdwa v137, v125 dst_sel:DWORD dst_unused:UNUSED_PAD src0_sel:WORD_1
	v_cvt_f32_f16_e32 v134, v124
	v_cvt_f32_f16_e32 v136, v125
	v_pk_add_f32 v[4:5], v[4:5], v[74:75]
	v_mov_b32_e32 v74, v135
	v_mov_b32_e32 v75, v137
	v_pk_add_f32 v[156:157], v[4:5], v[4:5] op_sel:[0,1] op_sel_hi:[1,0]
	v_mov_b32_e32 v4, v134
	v_mov_b32_e32 v5, v136
	v_pk_mul_f32 v[74:75], v[74:75], v[74:75]
	s_waitcnt vmcnt(57)
	v_cvt_f32_f16_sdwa v125, v127 dst_sel:DWORD dst_unused:UNUSED_PAD src0_sel:WORD_1
	v_pk_fma_f32 v[4:5], v[4:5], v[4:5], v[74:75]
	v_cvt_f32_f16_e32 v124, v127
	v_pk_add_f32 v[158:159], v[4:5], v[4:5] op_sel:[0,1] op_sel_hi:[1,0]
	v_cvt_f32_f16_sdwa v5, v126 dst_sel:DWORD dst_unused:UNUSED_PAD src0_sel:WORD_1
	v_cvt_f32_f16_e32 v4, v126
	s_waitcnt vmcnt(56)
	v_cvt_f32_f16_sdwa v75, v130 dst_sel:DWORD dst_unused:UNUSED_PAD src0_sel:WORD_1
	v_cvt_f32_f16_e32 v74, v130
	v_cvt_f32_f16_sdwa v127, v131 dst_sel:DWORD dst_unused:UNUSED_PAD src0_sel:WORD_1
	v_cvt_f32_f16_e32 v126, v131
	v_mul_f32_e32 v0, v5, v5
	v_pk_fma_f32 v[160:161], v[4:5], v[4:5], v[0:1] op_sel_hi:[1,1,0]
	v_mul_f32_e32 v0, v125, v125
	v_pk_fma_f32 v[162:163], v[124:125], v[124:125], v[0:1] op_sel_hi:[1,1,0]
	v_pk_mul_f32 v[130:131], v[74:75], v[74:75]
	v_pk_mul_f32 v[164:165], v[126:127], v[126:127]
	v_mov_b32_e32 v157, v130
	v_mov_b32_e32 v159, v131
	v_mov_b32_e32 v161, v164
	v_mov_b32_e32 v163, v165
	v_pk_add_f32 v[130:131], v[156:157], v[158:159]
	v_pk_add_f32 v[156:157], v[160:161], v[162:163]
	s_lshl_b64 s[8:9], s[4:5], 11
	v_pk_add_f32 v[130:131], v[130:131], v[156:157]
	s_lshl_b64 s[12:13], s[10:11], 11
	v_add_f32_e32 v0, v130, v131
	s_waitcnt lgkmcnt(0)
	s_barrier
	s_lshl_b64 s[40:41], s[36:37], 11
	v_add_f32_dpp v0, v0, v0 quad_perm:[1,0,3,2] row_mask:0xf bank_mask:0xf bound_ctrl:1
	s_lshl_b64 s[34:35], s[30:31], 11
	s_lshl_b64 s[28:29], s[26:27], 11
	v_add_f32_dpp v0, v0, v0 quad_perm:[2,3,0,1] row_mask:0xf bank_mask:0xf bound_ctrl:1
	s_lshl_b64 s[24:25], s[22:23], 11
	s_lshl_b64 s[20:21], s[18:19], 11
	v_add_f32_dpp v0, v0, v0 row_half_mirror row_mask:0xf bank_mask:0xf bound_ctrl:1
	s_lshl_b64 s[16:17], s[14:15], 11
	s_nop 0
	v_add_f32_dpp v0, v0, v0 row_mirror row_mask:0xf bank_mask:0xf bound_ctrl:1
	s_nop 0
	v_readlane_b32 s5, v0, 16
	v_readlane_b32 s11, v0, 48
	v_readlane_b32 s6, v0, 0
	v_readlane_b32 s7, v0, 32
	v_mov_b32_e32 v130, s5
	v_mov_b32_e32 v131, s11
	v_pk_add_f32 v[130:131], s[6:7], v[130:131]
	s_lshl_b32 s5, s4, 1
	v_add_f32_e32 v0, v130, v131
	v_fmamk_f32 v0, v0, 0x3a000000, v252
	v_cmp_gt_f32_e32 vcc, s55, v0
	v_mul_f32_e32 v7, 0x4f800000, v0
	s_and_b32 s5, s5, 0xffffe000
	v_cndmask_b32_e32 v0, v0, v7, vcc
	v_sqrt_f32_e32 v7, v0
	s_add_i32 s5, s5, 0
	v_add_u32_e32 v130, -1, v7
	v_fma_f32 v131, -v130, v7, v0
	v_cmp_ge_f32_e64 s[6:7], 0, v131
	v_add_u32_e32 v131, 1, v7
	s_nop 0
	v_cndmask_b32_e64 v130, v7, v130, s[6:7]
	v_fma_f32 v7, -v131, v7, v0
	v_cmp_lt_f32_e64 s[6:7], 0, v7
	s_nop 1
	v_cndmask_b32_e64 v7, v130, v131, s[6:7]
	v_mul_f32_e32 v130, 0x37800000, v7
	v_cndmask_b32_e32 v7, v7, v130, vcc
	v_cmp_class_f32_e32 vcc, v0, v253
	s_nop 1
	v_cndmask_b32_e32 v0, v7, v0, vcc
	v_div_scale_f32 v7, s[6:7], v0, v0, 1.0
	v_rcp_f32_e32 v130, v7
	s_nop 0
	v_fma_f32 v131, -v7, v130, 1.0
	v_fmac_f32_e32 v130, v131, v130
	v_div_scale_f32 v131, vcc, 1.0, v0, 1.0
	v_mul_f32_e32 v142, v131, v130
	v_fma_f32 v156, -v7, v142, v131
	v_fmac_f32_e32 v142, v156, v130
	v_fma_f32 v7, -v7, v142, v131
	v_div_fmas_f32 v7, v7, v130, v142
	v_div_fixup_f32 v142, v7, v0, 1.0
	v_lshlrev_b32_e32 v0, 4, v143
	v_add_u32_e32 v164, s5, v0
	v_pk_mul_f32 v[160:161], v[152:153], v[142:143] op_sel_hi:[1,0]
	v_pk_mul_f32 v[162:163], v[154:155], v[142:143] op_sel_hi:[1,0]
	ds_read_b128 v[152:155], v164
	ds_read_b128 v[156:159], v164 offset:40960
	v_lshl_add_u64 v[130:131], s[8:9], 1, v[2:3]
	v_mov_b32_e32 v7, v1
	v_lshl_add_u64 v[130:131], v[130:131], 0, v[6:7]
	v_pk_mul_f32 v[128:129], v[128:129], v[142:143] op_sel_hi:[1,0]
	s_waitcnt lgkmcnt(0)
	v_pk_fma_f32 v[154:155], v[154:155], v[162:163], v[158:159]
	v_pk_fma_f32 v[152:153], v[152:153], v[160:161], v[156:157]
	v_pk_mul_f32 v[156:157], v[148:149], v[142:143] op_sel_hi:[1,0]
	v_cvt_pk_bf16_f32 v152, v152, v153
	v_cvt_pk_bf16_f32 v153, v154, v155
	global_store_dwordx2 v[130:131], v[152:153], off
	v_pk_mul_f32 v[158:159], v[150:151], v[142:143] op_sel_hi:[1,0]
	ds_read_b128 v[148:151], v164 offset:1024
	ds_read_b128 v[152:155], v164 offset:41984
	v_pk_mul_f32 v[132:133], v[132:133], v[142:143] op_sel_hi:[1,0]
	v_pk_mul_f32 v[4:5], v[4:5], v[142:143] op_sel_hi:[1,0]
	v_pk_mul_f32 v[124:125], v[124:125], v[142:143] op_sel_hi:[1,0]
	s_waitcnt lgkmcnt(0)
	v_pk_fma_f32 v[150:151], v[150:151], v[158:159], v[154:155]
	v_pk_fma_f32 v[148:149], v[148:149], v[156:157], v[152:153]
	v_pk_mul_f32 v[152:153], v[138:139], v[142:143] op_sel_hi:[1,0]
	v_cvt_pk_bf16_f32 v148, v148, v149
	v_cvt_pk_bf16_f32 v149, v150, v151
	global_store_dwordx2 v[130:131], v[148:149], off offset:512
	v_pk_mul_f32 v[154:155], v[140:141], v[142:143] op_sel_hi:[1,0]
	ds_read_b128 v[138:141], v164 offset:2048
	ds_read_b128 v[148:151], v164 offset:43008
	s_waitcnt lgkmcnt(0)
	v_pk_fma_f32 v[140:141], v[140:141], v[154:155], v[150:151]
	v_pk_fma_f32 v[138:139], v[138:139], v[152:153], v[148:149]
	v_pk_mul_f32 v[148:149], v[144:145], v[142:143] op_sel_hi:[1,0]
	v_cvt_pk_bf16_f32 v138, v138, v139
	v_cvt_pk_bf16_f32 v139, v140, v141
	global_store_dwordx2 v[130:131], v[138:139], off offset:1024
	v_pk_mul_f32 v[150:151], v[146:147], v[142:143] op_sel_hi:[1,0]
	ds_read_b128 v[138:141], v164 offset:3072
	ds_read_b128 v[144:147], v164 offset:44032
	s_waitcnt lgkmcnt(0)
	v_pk_fma_f32 v[140:141], v[150:151], v[140:141], v[146:147]
	v_pk_fma_f32 v[138:139], v[148:149], v[138:139], v[144:145]
	s_nop 0
	v_cvt_pk_bf16_f32 v138, v138, v139
	v_cvt_pk_bf16_f32 v139, v140, v141
	global_store_dwordx2 v[130:131], v[138:139], off offset:1536
	ds_read_b128 v[138:141], v164 offset:4096
	ds_read_b128 v[144:147], v164 offset:45056
	s_waitcnt lgkmcnt(0)
	v_pk_fma_f32 v[132:133], v[132:133], v[140:141], v[146:147]
	v_pk_fma_f32 v[128:129], v[128:129], v[138:139], v[144:145]
	v_pk_mul_f32 v[140:141], v[136:137], v[142:143] op_sel_hi:[1,0]
	v_cvt_pk_bf16_f32 v128, v128, v129
	v_cvt_pk_bf16_f32 v129, v132, v133
	global_store_dwordx2 v[130:131], v[128:129], off offset:2048
	v_pk_mul_f32 v[128:129], v[134:135], v[142:143] op_sel_hi:[1,0]
	ds_read_b128 v[132:135], v164 offset:5120
	ds_read_b128 v[136:139], v164 offset:46080
	s_waitcnt lgkmcnt(0)
	v_pk_fma_f32 v[134:135], v[140:141], v[134:135], v[138:139]
	v_pk_fma_f32 v[128:129], v[128:129], v[132:133], v[136:137]
	s_nop 0
	v_cvt_pk_bf16_f32 v128, v128, v129
	v_cvt_pk_bf16_f32 v129, v134, v135
	global_store_dwordx2 v[130:131], v[128:129], off offset:2560
	ds_read_b128 v[132:135], v164 offset:6144
	ds_read_b128 v[136:139], v164 offset:47104
	s_waitcnt vmcnt(58)
	v_cvt_f32_f16_sdwa v129, v117 dst_sel:DWORD dst_unused:UNUSED_PAD src0_sel:WORD_1
	v_cvt_f32_f16_e32 v128, v117
	s_waitcnt lgkmcnt(0)
	v_pk_fma_f32 v[124:125], v[124:125], v[134:135], v[138:139]
	v_pk_fma_f32 v[4:5], v[4:5], v[132:133], v[136:137]
	v_cvt_f32_f16_sdwa v137, v122 dst_sel:DWORD dst_unused:UNUSED_PAD src0_sel:WORD_1
	v_cvt_pk_bf16_f32 v4, v4, v5
	v_cvt_pk_bf16_f32 v5, v124, v125
	global_store_dwordx2 v[130:131], v[4:5], off offset:3072
	v_pk_mul_f32 v[4:5], v[74:75], v[142:143] op_sel_hi:[1,0]
	v_pk_mul_f32 v[74:75], v[126:127], v[142:143] op_sel_hi:[1,0]
	ds_read_b128 v[124:127], v164 offset:7168
	ds_read_b128 v[132:135], v164 offset:48128
	v_cvt_f32_f16_e32 v136, v122
	v_cvt_f32_f16_sdwa v139, v123 dst_sel:DWORD dst_unused:UNUSED_PAD src0_sel:WORD_1
	v_cvt_f32_f16_e32 v138, v123
	v_cvt_f32_f16_sdwa v123, v118 dst_sel:DWORD dst_unused:UNUSED_PAD src0_sel:WORD_1
	s_waitcnt lgkmcnt(0)
	v_pk_fma_f32 v[4:5], v[4:5], v[124:125], v[132:133]
	v_cvt_f32_f16_sdwa v133, v120 dst_sel:DWORD dst_unused:UNUSED_PAD src0_sel:WORD_1
	v_pk_fma_f32 v[74:75], v[74:75], v[126:127], v[134:135]
	v_cvt_f32_f16_e32 v132, v120
	v_cvt_f32_f16_sdwa v135, v121 dst_sel:DWORD dst_unused:UNUSED_PAD src0_sel:WORD_1
	v_cvt_f32_f16_e32 v134, v121
	v_cvt_f32_f16_sdwa v125, v119 dst_sel:DWORD dst_unused:UNUSED_PAD src0_sel:WORD_1
	v_cvt_f32_f16_sdwa v127, v116 dst_sel:DWORD dst_unused:UNUSED_PAD src0_sel:WORD_1
	v_cvt_pk_bf16_f32 v4, v4, v5
	v_cvt_pk_bf16_f32 v5, v74, v75
	v_mov_b32_e32 v74, v137
	v_mov_b32_e32 v75, v133
	v_cvt_f32_f16_e32 v122, v118
	v_cvt_f32_f16_e32 v124, v119
	v_cvt_f32_f16_e32 v126, v116
	global_store_dwordx2 v[130:131], v[4:5], off offset:3584
	v_mov_b32_e32 v4, v136
	v_mov_b32_e32 v5, v132
	v_pk_mul_f32 v[74:75], v[74:75], v[74:75]
	v_mov_b32_e32 v120, v139
	v_mov_b32_e32 v121, v135
	v_pk_fma_f32 v[4:5], v[4:5], v[4:5], v[74:75]
	v_mov_b32_e32 v74, v138
	v_mov_b32_e32 v75, v134
	v_pk_mul_f32 v[120:121], v[120:121], v[120:121]
	v_mov_b32_e32 v118, v123
	v_pk_fma_f32 v[74:75], v[74:75], v[74:75], v[120:121]
	v_mov_b32_e32 v119, v125
	v_mul_f32_e32 v116, v127, v127
	v_pk_add_f32 v[4:5], v[4:5], v[74:75]
	v_mov_b32_e32 v74, v122
	v_mov_b32_e32 v75, v124
	v_pk_mul_f32 v[118:119], v[118:119], v[118:119]
	v_pk_fma_f32 v[120:121], v[126:127], v[126:127], v[116:117] op_sel_hi:[1,1,0]
	v_mul_f32_e32 v116, v129, v129
	v_pk_fma_f32 v[74:75], v[74:75], v[74:75], v[118:119]
	v_pk_fma_f32 v[130:131], v[128:129], v[128:129], v[116:117] op_sel_hi:[1,1,0]
	s_waitcnt vmcnt(59)
	v_cvt_f32_f16_sdwa v117, v114 dst_sel:DWORD dst_unused:UNUSED_PAD src0_sel:WORD_1
	v_cvt_f32_f16_e32 v116, v114
	v_cvt_f32_f16_sdwa v119, v115 dst_sel:DWORD dst_unused:UNUSED_PAD src0_sel:WORD_1
	v_cvt_f32_f16_e32 v118, v115
	v_pk_add_f32 v[4:5], v[4:5], v[4:5] op_sel:[0,1] op_sel_hi:[1,0]
	v_pk_add_f32 v[74:75], v[74:75], v[74:75] op_sel:[0,1] op_sel_hi:[1,0]
	v_pk_mul_f32 v[114:115], v[116:117], v[116:117]
	v_pk_mul_f32 v[140:141], v[118:119], v[118:119]
	v_mov_b32_e32 v5, v114
	v_mov_b32_e32 v75, v115
	v_mov_b32_e32 v121, v140
	v_mov_b32_e32 v131, v141
	v_pk_add_f32 v[4:5], v[4:5], v[74:75]
	v_pk_add_f32 v[74:75], v[120:121], v[130:131]
	s_waitcnt vmcnt(58)
	v_cvt_f32_f16_sdwa v115, v112 dst_sel:DWORD dst_unused:UNUSED_PAD src0_sel:WORD_1
	v_cvt_f32_f16_sdwa v121, v113 dst_sel:DWORD dst_unused:UNUSED_PAD src0_sel:WORD_1
	v_cvt_f32_f16_e32 v114, v112
	v_cvt_f32_f16_e32 v120, v113
	v_pk_add_f32 v[4:5], v[4:5], v[74:75]
	v_mov_b32_e32 v74, v115
	v_mov_b32_e32 v75, v121
	v_pk_add_f32 v[130:131], v[4:5], v[4:5] op_sel:[0,1] op_sel_hi:[1,0]
	v_mov_b32_e32 v4, v114
	v_mov_b32_e32 v5, v120
	v_pk_mul_f32 v[74:75], v[74:75], v[74:75]
	s_waitcnt vmcnt(57)
	v_cvt_f32_f16_sdwa v113, v111 dst_sel:DWORD dst_unused:UNUSED_PAD src0_sel:WORD_1
	v_pk_fma_f32 v[4:5], v[4:5], v[4:5], v[74:75]
	v_cvt_f32_f16_e32 v112, v111
	v_pk_add_f32 v[140:141], v[4:5], v[4:5] op_sel:[0,1] op_sel_hi:[1,0]
	v_cvt_f32_f16_sdwa v5, v110 dst_sel:DWORD dst_unused:UNUSED_PAD src0_sel:WORD_1
	v_cvt_f32_f16_e32 v4, v110
	s_waitcnt vmcnt(56)
	v_cvt_f32_f16_sdwa v111, v109 dst_sel:DWORD dst_unused:UNUSED_PAD src0_sel:WORD_1
	v_cvt_f32_f16_e32 v110, v109
	v_mul_f32_e32 v74, v5, v5
	v_pk_fma_f32 v[144:145], v[4:5], v[4:5], v[74:75] op_sel_hi:[1,1,0]
	v_mul_f32_e32 v74, v113, v113
	v_pk_fma_f32 v[146:147], v[112:113], v[112:113], v[74:75] op_sel_hi:[1,1,0]
	v_cvt_f32_f16_sdwa v75, v108 dst_sel:DWORD dst_unused:UNUSED_PAD src0_sel:WORD_1
	v_cvt_f32_f16_e32 v74, v108
	v_pk_mul_f32 v[148:149], v[110:111], v[110:111]
	v_pk_mul_f32 v[108:109], v[74:75], v[74:75]
	s_nop 0
	v_mov_b32_e32 v131, v108
	v_mov_b32_e32 v141, v109
	v_mov_b32_e32 v145, v148
	v_mov_b32_e32 v147, v149
	v_pk_add_f32 v[108:109], v[130:131], v[140:141]
	v_pk_add_f32 v[130:131], v[144:145], v[146:147]
	s_nop 0
	v_pk_add_f32 v[108:109], v[108:109], v[130:131]
	s_nop 0
	v_add_f32_e32 v108, v108, v109
	s_nop 1
	v_add_f32_dpp v108, v108, v108 quad_perm:[1,0,3,2] row_mask:0xf bank_mask:0xf bound_ctrl:1
	s_nop 1
	v_add_f32_dpp v108, v108, v108 quad_perm:[2,3,0,1] row_mask:0xf bank_mask:0xf bound_ctrl:1
	s_nop 1
	v_add_f32_dpp v108, v108, v108 row_half_mirror row_mask:0xf bank_mask:0xf bound_ctrl:1
	s_nop 1
	v_add_f32_dpp v108, v108, v108 row_mirror row_mask:0xf bank_mask:0xf bound_ctrl:1
	s_nop 0
	v_readlane_b32 s5, v108, 16
	v_readlane_b32 s11, v108, 48
	v_readlane_b32 s6, v108, 0
	v_readlane_b32 s7, v108, 32
	v_mov_b32_e32 v108, s5
	v_mov_b32_e32 v109, s11
	v_pk_add_f32 v[108:109], s[6:7], v[108:109]
	s_lshl_b32 s5, s36, 1
	v_add_f32_e32 v108, v108, v109
	v_fmamk_f32 v108, v108, 0x3a000000, v252
	v_cmp_gt_f32_e32 vcc, s55, v108
	v_mul_f32_e32 v109, 0x4f800000, v108
	s_and_b32 s5, s5, 0xffffe000
	v_cndmask_b32_e32 v108, v108, v109, vcc
	v_sqrt_f32_e32 v109, v108
	s_add_i32 s5, s5, 0
	v_add_u32_e32 v130, -1, v109
	v_fma_f32 v131, -v130, v109, v108
	v_cmp_ge_f32_e64 s[6:7], 0, v131
	v_add_u32_e32 v131, 1, v109
	s_nop 0
	v_cndmask_b32_e64 v130, v109, v130, s[6:7]
	v_fma_f32 v109, -v131, v109, v108
	v_cmp_lt_f32_e64 s[6:7], 0, v109
	s_nop 1
	v_cndmask_b32_e64 v109, v130, v131, s[6:7]
	v_mul_f32_e32 v130, 0x37800000, v109
	v_cndmask_b32_e32 v109, v109, v130, vcc
	v_cmp_class_f32_e32 vcc, v108, v253
	s_nop 1
	v_cndmask_b32_e32 v108, v109, v108, vcc
	v_div_scale_f32 v109, s[6:7], v108, v108, 1.0
	v_rcp_f32_e32 v130, v109
	s_nop 0
	v_fma_f32 v131, -v109, v130, 1.0
	v_fmac_f32_e32 v130, v131, v130
	v_div_scale_f32 v131, vcc, 1.0, v108, 1.0
	v_mul_f32_e32 v140, v131, v130
	v_fma_f32 v141, -v109, v140, v131
	v_fmac_f32_e32 v140, v141, v130
	v_fma_f32 v109, -v109, v140, v131
	v_div_fmas_f32 v109, v109, v130, v140
	v_div_fixup_f32 v130, v109, v108, 1.0
	v_pk_mul_f32 v[140:141], v[136:137], v[130:131] op_sel_hi:[1,0]
	v_pk_mul_f32 v[148:149], v[138:139], v[130:131] op_sel_hi:[1,0]
	v_add_u32_e32 v131, s5, v0
	ds_read_b128 v[136:139], v131
	ds_read_b128 v[144:147], v131 offset:40960
	v_lshl_add_u64 v[108:109], s[40:41], 1, v[2:3]
	v_lshl_add_u64 v[108:109], v[108:109], 0, v[6:7]
	v_pk_mul_f32 v[4:5], v[4:5], v[130:131] op_sel_hi:[1,0]
	s_waitcnt lgkmcnt(0)
	v_pk_fma_f32 v[138:139], v[138:139], v[148:149], v[146:147]
	v_pk_fma_f32 v[136:137], v[136:137], v[140:141], v[144:145]
	v_pk_mul_f32 v[140:141], v[132:133], v[130:131] op_sel_hi:[1,0]
	v_cvt_pk_bf16_f32 v136, v136, v137
	v_cvt_pk_bf16_f32 v137, v138, v139
	global_store_dwordx2 v[108:109], v[136:137], off
	v_pk_mul_f32 v[144:145], v[134:135], v[130:131] op_sel_hi:[1,0]
	ds_read_b128 v[132:135], v131 offset:1024
	ds_read_b128 v[136:139], v131 offset:41984
	s_waitcnt lgkmcnt(0)
	v_pk_fma_f32 v[134:135], v[134:135], v[144:145], v[138:139]
	v_pk_fma_f32 v[132:133], v[132:133], v[140:141], v[136:137]
	v_pk_mul_f32 v[136:137], v[122:123], v[130:131] op_sel_hi:[1,0]
	v_cvt_pk_bf16_f32 v132, v132, v133
	v_cvt_pk_bf16_f32 v133, v134, v135
	global_store_dwordx2 v[108:109], v[132:133], off offset:512
	v_pk_mul_f32 v[138:139], v[124:125], v[130:131] op_sel_hi:[1,0]
	ds_read_b128 v[122:125], v131 offset:2048
	ds_read_b128 v[132:135], v131 offset:43008
	s_waitcnt lgkmcnt(0)
	v_pk_fma_f32 v[124:125], v[124:125], v[138:139], v[134:135]
	v_pk_fma_f32 v[122:123], v[122:123], v[136:137], v[132:133]
	v_pk_mul_f32 v[132:133], v[126:127], v[130:131] op_sel_hi:[1,0]
	v_cvt_pk_bf16_f32 v122, v122, v123
	v_cvt_pk_bf16_f32 v123, v124, v125
	global_store_dwordx2 v[108:109], v[122:123], off offset:1024
	v_pk_mul_f32 v[134:135], v[128:129], v[130:131] op_sel_hi:[1,0]
	ds_read_b128 v[122:125], v131 offset:3072
	ds_read_b128 v[126:129], v131 offset:44032
	s_waitcnt lgkmcnt(0)
	v_pk_fma_f32 v[124:125], v[134:135], v[124:125], v[128:129]
	v_pk_fma_f32 v[122:123], v[132:133], v[122:123], v[126:127]
	v_pk_mul_f32 v[126:127], v[116:117], v[130:131] op_sel_hi:[1,0]
	v_cvt_pk_bf16_f32 v122, v122, v123
	v_cvt_pk_bf16_f32 v123, v124, v125
	global_store_dwordx2 v[108:109], v[122:123], off offset:1536
	v_pk_mul_f32 v[128:129], v[118:119], v[130:131] op_sel_hi:[1,0]
	ds_read_b128 v[116:119], v131 offset:4096
	ds_read_b128 v[122:125], v131 offset:45056
	s_waitcnt lgkmcnt(0)
	v_pk_fma_f32 v[118:119], v[128:129], v[118:119], v[124:125]
	v_pk_fma_f32 v[116:117], v[126:127], v[116:117], v[122:123]
	v_pk_mul_f32 v[122:123], v[114:115], v[130:131] op_sel_hi:[1,0]
	v_cvt_pk_bf16_f32 v116, v116, v117
	v_cvt_pk_bf16_f32 v117, v118, v119
	global_store_dwordx2 v[108:109], v[116:117], off offset:2048
	v_pk_mul_f32 v[124:125], v[120:121], v[130:131] op_sel_hi:[1,0]
	ds_read_b128 v[114:117], v131 offset:5120
	ds_read_b128 v[118:121], v131 offset:46080
	s_waitcnt lgkmcnt(0)
	v_pk_fma_f32 v[116:117], v[124:125], v[116:117], v[120:121]
	v_pk_fma_f32 v[114:115], v[122:123], v[114:115], v[118:119]
	v_pk_mul_f32 v[120:121], v[112:113], v[130:131] op_sel_hi:[1,0]
	v_cvt_pk_bf16_f32 v114, v114, v115
	v_cvt_pk_bf16_f32 v115, v116, v117
	global_store_dwordx2 v[108:109], v[114:115], off offset:2560
	ds_read_b128 v[112:115], v131 offset:6144
	ds_read_b128 v[116:119], v131 offset:47104
	s_waitcnt vmcnt(61)
	v_cvt_f32_f16_sdwa v123, v107 dst_sel:DWORD dst_unused:UNUSED_PAD src0_sel:WORD_1
	v_cvt_f32_f16_e32 v122, v107
	s_waitcnt vmcnt(59)
	v_cvt_f32_f16_sdwa v107, v102 dst_sel:DWORD dst_unused:UNUSED_PAD src0_sel:WORD_1
	s_waitcnt lgkmcnt(0)
	v_pk_fma_f32 v[114:115], v[120:121], v[114:115], v[118:119]
	v_pk_fma_f32 v[4:5], v[4:5], v[112:113], v[116:117]
	v_cvt_f32_f16_sdwa v121, v106 dst_sel:DWORD dst_unused:UNUSED_PAD src0_sel:WORD_1
	v_cvt_pk_bf16_f32 v4, v4, v5
	v_cvt_pk_bf16_f32 v5, v114, v115
	global_store_dwordx2 v[108:109], v[4:5], off offset:3072
	v_pk_mul_f32 v[4:5], v[74:75], v[130:131] op_sel_hi:[1,0]
	v_pk_mul_f32 v[74:75], v[110:111], v[130:131] op_sel_hi:[1,0]
	ds_read_b128 v[110:113], v131 offset:7168
	ds_read_b128 v[114:117], v131 offset:48128
	v_cvt_f32_f16_e32 v120, v106
	v_cvt_f32_f16_sdwa v119, v105 dst_sel:DWORD dst_unused:UNUSED_PAD src0_sel:WORD_1
	v_cvt_f32_f16_e32 v118, v105
	v_cvt_f32_f16_e32 v106, v102
	s_waitcnt lgkmcnt(0)
	v_pk_fma_f32 v[74:75], v[74:75], v[112:113], v[116:117]
	v_cvt_f32_f16_sdwa v117, v104 dst_sel:DWORD dst_unused:UNUSED_PAD src0_sel:WORD_1
	v_pk_fma_f32 v[4:5], v[4:5], v[110:111], v[114:115]
	v_cvt_f32_f16_e32 v116, v104
	v_cvt_pk_bf16_f32 v4, v4, v5
	v_cvt_pk_bf16_f32 v5, v74, v75
	global_store_dwordx2 v[108:109], v[4:5], off offset:3584
	v_cvt_f32_f16_sdwa v109, v103 dst_sel:DWORD dst_unused:UNUSED_PAD src0_sel:WORD_1
	s_waitcnt vmcnt(60)
	v_cvt_f32_f16_sdwa v111, v100 dst_sel:DWORD dst_unused:UNUSED_PAD src0_sel:WORD_1
	v_mov_b32_e32 v74, v121
	v_mov_b32_e32 v75, v117
	v_cvt_f32_f16_e32 v108, v103
	v_cvt_f32_f16_e32 v110, v100
	v_cvt_f32_f16_sdwa v113, v101 dst_sel:DWORD dst_unused:UNUSED_PAD src0_sel:WORD_1
	v_mov_b32_e32 v4, v120
	v_mov_b32_e32 v5, v116
	v_pk_mul_f32 v[74:75], v[74:75], v[74:75]
	v_mov_b32_e32 v104, v123
	v_mov_b32_e32 v105, v119
	v_cvt_f32_f16_e32 v112, v101
	v_pk_fma_f32 v[4:5], v[4:5], v[4:5], v[74:75]
	v_mov_b32_e32 v74, v122
	v_mov_b32_e32 v75, v118
	v_pk_mul_f32 v[104:105], v[104:105], v[104:105]
	v_mov_b32_e32 v102, v107
	v_pk_fma_f32 v[74:75], v[74:75], v[74:75], v[104:105]
	v_mov_b32_e32 v103, v109
	v_mul_f32_e32 v100, v111, v111
	v_pk_add_f32 v[4:5], v[4:5], v[74:75]
	v_mov_b32_e32 v74, v106
	v_mov_b32_e32 v75, v108
	v_pk_mul_f32 v[102:103], v[102:103], v[102:103]
	v_pk_fma_f32 v[104:105], v[110:111], v[110:111], v[100:101] op_sel_hi:[1,1,0]
	v_mul_f32_e32 v100, v113, v113
	v_pk_fma_f32 v[74:75], v[74:75], v[74:75], v[102:103]
	v_pk_fma_f32 v[114:115], v[112:113], v[112:113], v[100:101] op_sel_hi:[1,1,0]
	s_waitcnt vmcnt(59)
	v_cvt_f32_f16_sdwa v101, v98 dst_sel:DWORD dst_unused:UNUSED_PAD src0_sel:WORD_1
	v_cvt_f32_f16_e32 v100, v98
	v_cvt_f32_f16_sdwa v103, v99 dst_sel:DWORD dst_unused:UNUSED_PAD src0_sel:WORD_1
	v_cvt_f32_f16_e32 v102, v99
	v_pk_add_f32 v[4:5], v[4:5], v[4:5] op_sel:[0,1] op_sel_hi:[1,0]
	v_pk_add_f32 v[74:75], v[74:75], v[74:75] op_sel:[0,1] op_sel_hi:[1,0]
	v_pk_mul_f32 v[98:99], v[100:101], v[100:101]
	v_pk_mul_f32 v[124:125], v[102:103], v[102:103]
	v_mov_b32_e32 v5, v98
	v_mov_b32_e32 v75, v99
	v_mov_b32_e32 v105, v124
	v_mov_b32_e32 v115, v125
	v_pk_add_f32 v[4:5], v[4:5], v[74:75]
	v_pk_add_f32 v[74:75], v[104:105], v[114:115]
	s_waitcnt vmcnt(58)
	v_cvt_f32_f16_sdwa v99, v96 dst_sel:DWORD dst_unused:UNUSED_PAD src0_sel:WORD_1
	v_cvt_f32_f16_sdwa v105, v97 dst_sel:DWORD dst_unused:UNUSED_PAD src0_sel:WORD_1
	v_cvt_f32_f16_e32 v98, v96
	v_cvt_f32_f16_e32 v104, v97
	v_pk_add_f32 v[4:5], v[4:5], v[74:75]
	v_mov_b32_e32 v74, v99
	v_mov_b32_e32 v75, v105
	v_pk_add_f32 v[114:115], v[4:5], v[4:5] op_sel:[0,1] op_sel_hi:[1,0]
	v_mov_b32_e32 v4, v98
	v_mov_b32_e32 v5, v104
	v_pk_mul_f32 v[74:75], v[74:75], v[74:75]
	s_waitcnt vmcnt(57)
	v_cvt_f32_f16_sdwa v97, v95 dst_sel:DWORD dst_unused:UNUSED_PAD src0_sel:WORD_1
	v_pk_fma_f32 v[4:5], v[4:5], v[4:5], v[74:75]
	v_cvt_f32_f16_e32 v96, v95
	v_pk_add_f32 v[124:125], v[4:5], v[4:5] op_sel:[0,1] op_sel_hi:[1,0]
	v_cvt_f32_f16_sdwa v5, v94 dst_sel:DWORD dst_unused:UNUSED_PAD src0_sel:WORD_1
	v_cvt_f32_f16_e32 v4, v94
	s_waitcnt vmcnt(56)
	v_cvt_f32_f16_sdwa v95, v93 dst_sel:DWORD dst_unused:UNUSED_PAD src0_sel:WORD_1
	v_cvt_f32_f16_e32 v94, v93
	v_mul_f32_e32 v74, v5, v5
	v_pk_fma_f32 v[126:127], v[4:5], v[4:5], v[74:75] op_sel_hi:[1,1,0]
	v_mul_f32_e32 v74, v97, v97
	v_pk_fma_f32 v[128:129], v[96:97], v[96:97], v[74:75] op_sel_hi:[1,1,0]
	v_cvt_f32_f16_sdwa v75, v92 dst_sel:DWORD dst_unused:UNUSED_PAD src0_sel:WORD_1
	v_cvt_f32_f16_e32 v74, v92
	v_pk_mul_f32 v[130:131], v[94:95], v[94:95]
	v_pk_mul_f32 v[92:93], v[74:75], v[74:75]
	s_nop 0
	v_mov_b32_e32 v115, v92
	v_mov_b32_e32 v125, v93
	v_mov_b32_e32 v127, v130
	v_mov_b32_e32 v129, v131
	v_pk_add_f32 v[92:93], v[114:115], v[124:125]
	v_pk_add_f32 v[114:115], v[126:127], v[128:129]
	s_nop 0
	v_pk_add_f32 v[92:93], v[92:93], v[114:115]
	s_nop 0
	v_add_f32_e32 v92, v92, v93
	s_nop 1
	v_add_f32_dpp v92, v92, v92 quad_perm:[1,0,3,2] row_mask:0xf bank_mask:0xf bound_ctrl:1
	s_nop 1
	v_add_f32_dpp v92, v92, v92 quad_perm:[2,3,0,1] row_mask:0xf bank_mask:0xf bound_ctrl:1
	s_nop 1
	v_add_f32_dpp v92, v92, v92 row_half_mirror row_mask:0xf bank_mask:0xf bound_ctrl:1
	s_nop 1
	v_add_f32_dpp v92, v92, v92 row_mirror row_mask:0xf bank_mask:0xf bound_ctrl:1
	s_nop 0
	v_readlane_b32 s5, v92, 16
	v_readlane_b32 s11, v92, 48
	v_readlane_b32 s6, v92, 0
	v_readlane_b32 s7, v92, 32
	v_mov_b32_e32 v92, s5
	v_mov_b32_e32 v93, s11
	v_pk_add_f32 v[92:93], s[6:7], v[92:93]
	s_lshl_b32 s5, s30, 1
	v_add_f32_e32 v92, v92, v93
	v_fmamk_f32 v92, v92, 0x3a000000, v252
	v_cmp_gt_f32_e32 vcc, s55, v92
	v_mul_f32_e32 v93, 0x4f800000, v92
	s_and_b32 s5, s5, 0xffffe000
	v_cndmask_b32_e32 v92, v92, v93, vcc
	v_sqrt_f32_e32 v93, v92
	s_add_i32 s5, s5, 0
	v_add_u32_e32 v114, -1, v93
	v_fma_f32 v115, -v114, v93, v92
	v_cmp_ge_f32_e64 s[6:7], 0, v115
	v_add_u32_e32 v115, 1, v93
	s_nop 0
	v_cndmask_b32_e64 v114, v93, v114, s[6:7]
	v_fma_f32 v93, -v115, v93, v92
	v_cmp_lt_f32_e64 s[6:7], 0, v93
	s_nop 1
	v_cndmask_b32_e64 v93, v114, v115, s[6:7]
	v_mul_f32_e32 v114, 0x37800000, v93
	v_cndmask_b32_e32 v93, v93, v114, vcc
	v_cmp_class_f32_e32 vcc, v92, v253
	s_nop 1
	v_cndmask_b32_e32 v92, v93, v92, vcc
	v_div_scale_f32 v93, s[6:7], v92, v92, 1.0
	v_rcp_f32_e32 v114, v93
	s_nop 0
	v_fma_f32 v115, -v93, v114, 1.0
	v_fmac_f32_e32 v114, v115, v114
	v_div_scale_f32 v115, vcc, 1.0, v92, 1.0
	v_mul_f32_e32 v124, v115, v114
	v_fma_f32 v125, -v93, v124, v115
	v_fmac_f32_e32 v124, v125, v114
	v_fma_f32 v93, -v93, v124, v115
	v_div_fmas_f32 v93, v93, v114, v124
	v_div_fixup_f32 v114, v93, v92, 1.0
	v_pk_mul_f32 v[128:129], v[120:121], v[114:115] op_sel_hi:[1,0]
	v_pk_mul_f32 v[130:131], v[122:123], v[114:115] op_sel_hi:[1,0]
	v_add_u32_e32 v115, s5, v0
	ds_read_b128 v[120:123], v115
	ds_read_b128 v[124:127], v115 offset:40960
	v_lshl_add_u64 v[92:93], s[34:35], 1, v[2:3]
	v_lshl_add_u64 v[92:93], v[92:93], 0, v[6:7]
	v_pk_mul_f32 v[4:5], v[4:5], v[114:115] op_sel_hi:[1,0]
	s_waitcnt lgkmcnt(0)
	v_pk_fma_f32 v[122:123], v[122:123], v[130:131], v[126:127]
	v_pk_fma_f32 v[120:121], v[120:121], v[128:129], v[124:125]
	v_pk_mul_f32 v[124:125], v[116:117], v[114:115] op_sel_hi:[1,0]
	v_cvt_pk_bf16_f32 v120, v120, v121
	v_cvt_pk_bf16_f32 v121, v122, v123
	global_store_dwordx2 v[92:93], v[120:121], off
	v_pk_mul_f32 v[126:127], v[118:119], v[114:115] op_sel_hi:[1,0]
	ds_read_b128 v[116:119], v115 offset:1024
	ds_read_b128 v[120:123], v115 offset:41984
	s_waitcnt lgkmcnt(0)
	v_pk_fma_f32 v[118:119], v[118:119], v[126:127], v[122:123]
	v_pk_fma_f32 v[116:117], v[116:117], v[124:125], v[120:121]
	v_pk_mul_f32 v[120:121], v[106:107], v[114:115] op_sel_hi:[1,0]
	v_cvt_pk_bf16_f32 v116, v116, v117
	v_cvt_pk_bf16_f32 v117, v118, v119
	global_store_dwordx2 v[92:93], v[116:117], off offset:512
	v_pk_mul_f32 v[122:123], v[108:109], v[114:115] op_sel_hi:[1,0]
	ds_read_b128 v[106:109], v115 offset:2048
	ds_read_b128 v[116:119], v115 offset:43008
	s_waitcnt lgkmcnt(0)
	v_pk_fma_f32 v[108:109], v[108:109], v[122:123], v[118:119]
	v_pk_fma_f32 v[106:107], v[106:107], v[120:121], v[116:117]
	v_pk_mul_f32 v[116:117], v[110:111], v[114:115] op_sel_hi:[1,0]
	v_cvt_pk_bf16_f32 v106, v106, v107
	v_cvt_pk_bf16_f32 v107, v108, v109
	global_store_dwordx2 v[92:93], v[106:107], off offset:1024
	v_pk_mul_f32 v[118:119], v[112:113], v[114:115] op_sel_hi:[1,0]
	ds_read_b128 v[106:109], v115 offset:3072
	ds_read_b128 v[110:113], v115 offset:44032
	s_waitcnt lgkmcnt(0)
	v_pk_fma_f32 v[108:109], v[118:119], v[108:109], v[112:113]
	v_pk_fma_f32 v[106:107], v[116:117], v[106:107], v[110:111]
	v_pk_mul_f32 v[110:111], v[100:101], v[114:115] op_sel_hi:[1,0]
	v_cvt_pk_bf16_f32 v106, v106, v107
	v_cvt_pk_bf16_f32 v107, v108, v109
	global_store_dwordx2 v[92:93], v[106:107], off offset:1536
	v_pk_mul_f32 v[112:113], v[102:103], v[114:115] op_sel_hi:[1,0]
	ds_read_b128 v[100:103], v115 offset:4096
	ds_read_b128 v[106:109], v115 offset:45056
	s_waitcnt lgkmcnt(0)
	v_pk_fma_f32 v[102:103], v[112:113], v[102:103], v[108:109]
	v_pk_fma_f32 v[100:101], v[110:111], v[100:101], v[106:107]
	v_pk_mul_f32 v[106:107], v[98:99], v[114:115] op_sel_hi:[1,0]
	v_cvt_pk_bf16_f32 v100, v100, v101
	v_cvt_pk_bf16_f32 v101, v102, v103
	global_store_dwordx2 v[92:93], v[100:101], off offset:2048
	v_pk_mul_f32 v[108:109], v[104:105], v[114:115] op_sel_hi:[1,0]
	ds_read_b128 v[98:101], v115 offset:5120
	ds_read_b128 v[102:105], v115 offset:46080
	s_waitcnt lgkmcnt(0)
	v_pk_fma_f32 v[100:101], v[108:109], v[100:101], v[104:105]
	v_pk_fma_f32 v[98:99], v[106:107], v[98:99], v[102:103]
	v_pk_mul_f32 v[104:105], v[96:97], v[114:115] op_sel_hi:[1,0]
	v_cvt_pk_bf16_f32 v98, v98, v99
	v_cvt_pk_bf16_f32 v99, v100, v101
	global_store_dwordx2 v[92:93], v[98:99], off offset:2560
	ds_read_b128 v[96:99], v115 offset:6144
	ds_read_b128 v[100:103], v115 offset:47104
	s_waitcnt vmcnt(61)
	v_cvt_f32_f16_sdwa v107, v91 dst_sel:DWORD dst_unused:UNUSED_PAD src0_sel:WORD_1
	v_cvt_f32_f16_e32 v106, v91
	s_waitcnt vmcnt(59)
	v_cvt_f32_f16_sdwa v91, v86 dst_sel:DWORD dst_unused:UNUSED_PAD src0_sel:WORD_1
	s_waitcnt lgkmcnt(0)
	v_pk_fma_f32 v[98:99], v[104:105], v[98:99], v[102:103]
	v_pk_fma_f32 v[4:5], v[4:5], v[96:97], v[100:101]
	v_cvt_f32_f16_sdwa v105, v90 dst_sel:DWORD dst_unused:UNUSED_PAD src0_sel:WORD_1
	v_cvt_pk_bf16_f32 v4, v4, v5
	v_cvt_pk_bf16_f32 v5, v98, v99
	global_store_dwordx2 v[92:93], v[4:5], off offset:3072
	v_pk_mul_f32 v[4:5], v[74:75], v[114:115] op_sel_hi:[1,0]
	v_pk_mul_f32 v[74:75], v[94:95], v[114:115] op_sel_hi:[1,0]
	ds_read_b128 v[94:97], v115 offset:7168
	ds_read_b128 v[98:101], v115 offset:48128
	v_cvt_f32_f16_e32 v104, v90
	v_cvt_f32_f16_sdwa v103, v89 dst_sel:DWORD dst_unused:UNUSED_PAD src0_sel:WORD_1
	v_cvt_f32_f16_e32 v102, v89
	v_cvt_f32_f16_e32 v90, v86
	s_waitcnt lgkmcnt(0)
	v_pk_fma_f32 v[74:75], v[74:75], v[96:97], v[100:101]
	v_cvt_f32_f16_sdwa v101, v88 dst_sel:DWORD dst_unused:UNUSED_PAD src0_sel:WORD_1
	v_pk_fma_f32 v[4:5], v[4:5], v[94:95], v[98:99]
	v_cvt_f32_f16_e32 v100, v88
	v_cvt_pk_bf16_f32 v4, v4, v5
	v_cvt_pk_bf16_f32 v5, v74, v75
	global_store_dwordx2 v[92:93], v[4:5], off offset:3584
	v_cvt_f32_f16_sdwa v93, v87 dst_sel:DWORD dst_unused:UNUSED_PAD src0_sel:WORD_1
	s_waitcnt vmcnt(60)
	v_cvt_f32_f16_sdwa v95, v84 dst_sel:DWORD dst_unused:UNUSED_PAD src0_sel:WORD_1
	v_mov_b32_e32 v74, v105
	v_mov_b32_e32 v75, v101
	v_cvt_f32_f16_e32 v92, v87
	v_cvt_f32_f16_e32 v94, v84
	v_cvt_f32_f16_sdwa v97, v85 dst_sel:DWORD dst_unused:UNUSED_PAD src0_sel:WORD_1
	v_mov_b32_e32 v4, v104
	v_mov_b32_e32 v5, v100
	v_pk_mul_f32 v[74:75], v[74:75], v[74:75]
	v_mov_b32_e32 v88, v107
	v_mov_b32_e32 v89, v103
	v_cvt_f32_f16_e32 v96, v85
	v_pk_fma_f32 v[4:5], v[4:5], v[4:5], v[74:75]
	v_mov_b32_e32 v74, v106
	v_mov_b32_e32 v75, v102
	v_pk_mul_f32 v[88:89], v[88:89], v[88:89]
	v_mov_b32_e32 v86, v91
	v_pk_fma_f32 v[74:75], v[74:75], v[74:75], v[88:89]
	v_mov_b32_e32 v87, v93
	v_mul_f32_e32 v84, v95, v95
	v_pk_add_f32 v[4:5], v[4:5], v[74:75]
	v_mov_b32_e32 v74, v90
	v_mov_b32_e32 v75, v92
	v_pk_mul_f32 v[86:87], v[86:87], v[86:87]
	v_pk_fma_f32 v[88:89], v[94:95], v[94:95], v[84:85] op_sel_hi:[1,1,0]
	v_mul_f32_e32 v84, v97, v97
	v_pk_fma_f32 v[74:75], v[74:75], v[74:75], v[86:87]
	v_pk_fma_f32 v[98:99], v[96:97], v[96:97], v[84:85] op_sel_hi:[1,1,0]
	s_waitcnt vmcnt(59)
	v_cvt_f32_f16_sdwa v85, v82 dst_sel:DWORD dst_unused:UNUSED_PAD src0_sel:WORD_1
	v_cvt_f32_f16_e32 v84, v82
	v_cvt_f32_f16_sdwa v87, v83 dst_sel:DWORD dst_unused:UNUSED_PAD src0_sel:WORD_1
	v_cvt_f32_f16_e32 v86, v83
	v_pk_add_f32 v[4:5], v[4:5], v[4:5] op_sel:[0,1] op_sel_hi:[1,0]
	v_pk_add_f32 v[74:75], v[74:75], v[74:75] op_sel:[0,1] op_sel_hi:[1,0]
	v_pk_mul_f32 v[82:83], v[84:85], v[84:85]
	v_pk_mul_f32 v[108:109], v[86:87], v[86:87]
	v_mov_b32_e32 v5, v82
	v_mov_b32_e32 v75, v83
	v_mov_b32_e32 v89, v108
	v_mov_b32_e32 v99, v109
	v_pk_add_f32 v[4:5], v[4:5], v[74:75]
	v_pk_add_f32 v[74:75], v[88:89], v[98:99]
	s_waitcnt vmcnt(58)
	v_cvt_f32_f16_sdwa v83, v80 dst_sel:DWORD dst_unused:UNUSED_PAD src0_sel:WORD_1
	v_cvt_f32_f16_sdwa v89, v81 dst_sel:DWORD dst_unused:UNUSED_PAD src0_sel:WORD_1
	v_cvt_f32_f16_e32 v82, v80
	v_cvt_f32_f16_e32 v88, v81
	v_pk_add_f32 v[4:5], v[4:5], v[74:75]
	v_mov_b32_e32 v74, v83
	v_mov_b32_e32 v75, v89
	v_pk_add_f32 v[98:99], v[4:5], v[4:5] op_sel:[0,1] op_sel_hi:[1,0]
	v_mov_b32_e32 v4, v82
	v_mov_b32_e32 v5, v88
	v_pk_mul_f32 v[74:75], v[74:75], v[74:75]
	s_waitcnt vmcnt(57)
	v_cvt_f32_f16_sdwa v81, v79 dst_sel:DWORD dst_unused:UNUSED_PAD src0_sel:WORD_1
	v_pk_fma_f32 v[4:5], v[4:5], v[4:5], v[74:75]
	v_cvt_f32_f16_e32 v80, v79
	v_pk_add_f32 v[108:109], v[4:5], v[4:5] op_sel:[0,1] op_sel_hi:[1,0]
	v_cvt_f32_f16_sdwa v5, v78 dst_sel:DWORD dst_unused:UNUSED_PAD src0_sel:WORD_1
	v_cvt_f32_f16_e32 v4, v78
	s_waitcnt vmcnt(56)
	v_cvt_f32_f16_sdwa v79, v77 dst_sel:DWORD dst_unused:UNUSED_PAD src0_sel:WORD_1
	v_cvt_f32_f16_e32 v78, v77
	v_mul_f32_e32 v74, v5, v5
	v_pk_fma_f32 v[110:111], v[4:5], v[4:5], v[74:75] op_sel_hi:[1,1,0]
	v_mul_f32_e32 v74, v81, v81
	v_pk_fma_f32 v[112:113], v[80:81], v[80:81], v[74:75] op_sel_hi:[1,1,0]
	v_cvt_f32_f16_sdwa v75, v76 dst_sel:DWORD dst_unused:UNUSED_PAD src0_sel:WORD_1
	v_cvt_f32_f16_e32 v74, v76
	v_pk_mul_f32 v[114:115], v[78:79], v[78:79]
	v_pk_mul_f32 v[76:77], v[74:75], v[74:75]
	s_nop 0
	v_mov_b32_e32 v99, v76
	v_mov_b32_e32 v109, v77
	v_mov_b32_e32 v111, v114
	v_mov_b32_e32 v113, v115
	v_pk_add_f32 v[76:77], v[98:99], v[108:109]
	v_pk_add_f32 v[98:99], v[110:111], v[112:113]
	s_nop 0
	v_pk_add_f32 v[76:77], v[76:77], v[98:99]
	s_nop 0
	v_add_f32_e32 v76, v76, v77
	s_nop 1
	v_add_f32_dpp v76, v76, v76 quad_perm:[1,0,3,2] row_mask:0xf bank_mask:0xf bound_ctrl:1
	s_nop 1
	v_add_f32_dpp v76, v76, v76 quad_perm:[2,3,0,1] row_mask:0xf bank_mask:0xf bound_ctrl:1
	s_nop 1
	v_add_f32_dpp v76, v76, v76 row_half_mirror row_mask:0xf bank_mask:0xf bound_ctrl:1
	s_nop 1
	v_add_f32_dpp v76, v76, v76 row_mirror row_mask:0xf bank_mask:0xf bound_ctrl:1
	s_nop 0
	v_readlane_b32 s5, v76, 16
	v_readlane_b32 s11, v76, 48
	v_readlane_b32 s6, v76, 0
	v_readlane_b32 s7, v76, 32
	v_mov_b32_e32 v76, s5
	v_mov_b32_e32 v77, s11
	v_pk_add_f32 v[76:77], s[6:7], v[76:77]
	s_lshl_b32 s5, s26, 1
	v_add_f32_e32 v76, v76, v77
	v_fmamk_f32 v76, v76, 0x3a000000, v252
	v_cmp_gt_f32_e32 vcc, s55, v76
	v_mul_f32_e32 v77, 0x4f800000, v76
	s_and_b32 s5, s5, 0xffffe000
	v_cndmask_b32_e32 v76, v76, v77, vcc
	v_sqrt_f32_e32 v77, v76
	s_add_i32 s5, s5, 0
	v_add_u32_e32 v98, -1, v77
	v_fma_f32 v99, -v98, v77, v76
	v_cmp_ge_f32_e64 s[6:7], 0, v99
	v_add_u32_e32 v99, 1, v77
	s_nop 0
	v_cndmask_b32_e64 v98, v77, v98, s[6:7]
	v_fma_f32 v77, -v99, v77, v76
	v_cmp_lt_f32_e64 s[6:7], 0, v77
	s_nop 1
	v_cndmask_b32_e64 v77, v98, v99, s[6:7]
	v_mul_f32_e32 v98, 0x37800000, v77
	v_cndmask_b32_e32 v77, v77, v98, vcc
	v_cmp_class_f32_e32 vcc, v76, v253
	s_nop 1
	v_cndmask_b32_e32 v76, v77, v76, vcc
	v_div_scale_f32 v77, s[6:7], v76, v76, 1.0
	v_rcp_f32_e32 v98, v77
	s_nop 0
	v_fma_f32 v99, -v77, v98, 1.0
	v_fmac_f32_e32 v98, v99, v98
	v_div_scale_f32 v99, vcc, 1.0, v76, 1.0
	v_mul_f32_e32 v108, v99, v98
	v_fma_f32 v109, -v77, v108, v99
	v_fmac_f32_e32 v108, v109, v98
	v_fma_f32 v77, -v77, v108, v99
	v_div_fmas_f32 v77, v77, v98, v108
	v_div_fixup_f32 v98, v77, v76, 1.0
	v_pk_mul_f32 v[112:113], v[104:105], v[98:99] op_sel_hi:[1,0]
	v_pk_mul_f32 v[114:115], v[106:107], v[98:99] op_sel_hi:[1,0]
	v_add_u32_e32 v99, s5, v0
	ds_read_b128 v[104:107], v99
	ds_read_b128 v[108:111], v99 offset:40960
	v_lshl_add_u64 v[76:77], s[28:29], 1, v[2:3]
	v_lshl_add_u64 v[76:77], v[76:77], 0, v[6:7]
	v_pk_mul_f32 v[4:5], v[4:5], v[98:99] op_sel_hi:[1,0]
	s_waitcnt lgkmcnt(0)
	v_pk_fma_f32 v[106:107], v[106:107], v[114:115], v[110:111]
	v_pk_fma_f32 v[104:105], v[104:105], v[112:113], v[108:109]
	v_pk_mul_f32 v[108:109], v[100:101], v[98:99] op_sel_hi:[1,0]
	v_cvt_pk_bf16_f32 v104, v104, v105
	v_cvt_pk_bf16_f32 v105, v106, v107
	global_store_dwordx2 v[76:77], v[104:105], off
	v_pk_mul_f32 v[110:111], v[102:103], v[98:99] op_sel_hi:[1,0]
	ds_read_b128 v[100:103], v99 offset:1024
	ds_read_b128 v[104:107], v99 offset:41984
	s_waitcnt lgkmcnt(0)
	v_pk_fma_f32 v[102:103], v[102:103], v[110:111], v[106:107]
	v_pk_fma_f32 v[100:101], v[100:101], v[108:109], v[104:105]
	v_pk_mul_f32 v[104:105], v[90:91], v[98:99] op_sel_hi:[1,0]
	v_cvt_pk_bf16_f32 v100, v100, v101
	v_cvt_pk_bf16_f32 v101, v102, v103
	global_store_dwordx2 v[76:77], v[100:101], off offset:512
	v_pk_mul_f32 v[106:107], v[92:93], v[98:99] op_sel_hi:[1,0]
	ds_read_b128 v[90:93], v99 offset:2048
	ds_read_b128 v[100:103], v99 offset:43008
	s_waitcnt lgkmcnt(0)
	v_pk_fma_f32 v[92:93], v[92:93], v[106:107], v[102:103]
	v_pk_fma_f32 v[90:91], v[90:91], v[104:105], v[100:101]
	v_pk_mul_f32 v[100:101], v[94:95], v[98:99] op_sel_hi:[1,0]
	v_cvt_pk_bf16_f32 v90, v90, v91
	v_cvt_pk_bf16_f32 v91, v92, v93
	global_store_dwordx2 v[76:77], v[90:91], off offset:1024
	v_pk_mul_f32 v[102:103], v[96:97], v[98:99] op_sel_hi:[1,0]
	ds_read_b128 v[90:93], v99 offset:3072
	ds_read_b128 v[94:97], v99 offset:44032
	s_waitcnt lgkmcnt(0)
	v_pk_fma_f32 v[92:93], v[102:103], v[92:93], v[96:97]
	v_pk_fma_f32 v[90:91], v[100:101], v[90:91], v[94:95]
	v_pk_mul_f32 v[94:95], v[84:85], v[98:99] op_sel_hi:[1,0]
	v_cvt_pk_bf16_f32 v90, v90, v91
	v_cvt_pk_bf16_f32 v91, v92, v93
	global_store_dwordx2 v[76:77], v[90:91], off offset:1536
	v_pk_mul_f32 v[96:97], v[86:87], v[98:99] op_sel_hi:[1,0]
	ds_read_b128 v[84:87], v99 offset:4096
	ds_read_b128 v[90:93], v99 offset:45056
	s_waitcnt lgkmcnt(0)
	v_pk_fma_f32 v[86:87], v[96:97], v[86:87], v[92:93]
	v_pk_fma_f32 v[84:85], v[94:95], v[84:85], v[90:91]
	v_pk_mul_f32 v[90:91], v[82:83], v[98:99] op_sel_hi:[1,0]
	v_cvt_pk_bf16_f32 v84, v84, v85
	v_cvt_pk_bf16_f32 v85, v86, v87
	global_store_dwordx2 v[76:77], v[84:85], off offset:2048
	v_pk_mul_f32 v[92:93], v[88:89], v[98:99] op_sel_hi:[1,0]
	ds_read_b128 v[82:85], v99 offset:5120
	ds_read_b128 v[86:89], v99 offset:46080
	s_waitcnt lgkmcnt(0)
	v_pk_fma_f32 v[84:85], v[92:93], v[84:85], v[88:89]
	v_pk_fma_f32 v[82:83], v[90:91], v[82:83], v[86:87]
	v_pk_mul_f32 v[88:89], v[80:81], v[98:99] op_sel_hi:[1,0]
	v_cvt_pk_bf16_f32 v82, v82, v83
	v_cvt_pk_bf16_f32 v83, v84, v85
	global_store_dwordx2 v[76:77], v[82:83], off offset:2560
	ds_read_b128 v[80:83], v99 offset:6144
	ds_read_b128 v[84:87], v99 offset:47104
	s_waitcnt vmcnt(61)
	v_cvt_f32_f16_sdwa v91, v73 dst_sel:DWORD dst_unused:UNUSED_PAD src0_sel:WORD_1
	v_cvt_f32_f16_e32 v90, v73
	s_waitcnt lgkmcnt(0)
	v_pk_fma_f32 v[82:83], v[88:89], v[82:83], v[86:87]
	v_pk_fma_f32 v[4:5], v[4:5], v[80:81], v[84:85]
	v_cvt_f32_f16_sdwa v89, v72 dst_sel:DWORD dst_unused:UNUSED_PAD src0_sel:WORD_1
	v_cvt_pk_bf16_f32 v4, v4, v5
	v_cvt_pk_bf16_f32 v5, v82, v83
	global_store_dwordx2 v[76:77], v[4:5], off offset:3072
	v_pk_mul_f32 v[4:5], v[74:75], v[98:99] op_sel_hi:[1,0]
	v_pk_mul_f32 v[74:75], v[78:79], v[98:99] op_sel_hi:[1,0]
	ds_read_b128 v[78:81], v99 offset:7168
	ds_read_b128 v[82:85], v99 offset:48128
	v_cvt_f32_f16_e32 v88, v72
	s_waitcnt vmcnt(61)
	v_cvt_f32_f16_sdwa v87, v71 dst_sel:DWORD dst_unused:UNUSED_PAD src0_sel:WORD_1
	v_cvt_f32_f16_e32 v86, v71
	v_mov_b32_e32 v72, v91
	s_waitcnt lgkmcnt(0)
	v_pk_fma_f32 v[74:75], v[74:75], v[80:81], v[84:85]
	v_cvt_f32_f16_sdwa v85, v70 dst_sel:DWORD dst_unused:UNUSED_PAD src0_sel:WORD_1
	v_cvt_f32_f16_e32 v84, v70
	v_pk_fma_f32 v[4:5], v[4:5], v[78:79], v[82:83]
	v_mov_b32_e32 v70, v89
	v_cvt_pk_bf16_f32 v4, v4, v5
	v_cvt_pk_bf16_f32 v5, v74, v75
	global_store_dwordx2 v[76:77], v[4:5], off offset:3584
	v_mov_b32_e32 v71, v85
	s_waitcnt vmcnt(61)
	v_cvt_f32_f16_sdwa v75, v68 dst_sel:DWORD dst_unused:UNUSED_PAD src0_sel:WORD_1
	v_cvt_f32_f16_sdwa v77, v69 dst_sel:DWORD dst_unused:UNUSED_PAD src0_sel:WORD_1
	v_mov_b32_e32 v4, v88
	v_mov_b32_e32 v5, v84
	v_pk_mul_f32 v[70:71], v[70:71], v[70:71]
	v_mov_b32_e32 v73, v87
	v_cvt_f32_f16_e32 v74, v68
	v_cvt_f32_f16_e32 v76, v69
	s_waitcnt vmcnt(60)
	v_cvt_f32_f16_sdwa v79, v66 dst_sel:DWORD dst_unused:UNUSED_PAD src0_sel:WORD_1
	v_pk_fma_f32 v[4:5], v[4:5], v[4:5], v[70:71]
	v_mov_b32_e32 v70, v90
	v_mov_b32_e32 v71, v86
	v_pk_mul_f32 v[72:73], v[72:73], v[72:73]
	v_cvt_f32_f16_e32 v78, v66
	v_cvt_f32_f16_sdwa v81, v67 dst_sel:DWORD dst_unused:UNUSED_PAD src0_sel:WORD_1
	v_pk_fma_f32 v[70:71], v[70:71], v[70:71], v[72:73]
	v_cvt_f32_f16_e32 v80, v67
	v_pk_add_f32 v[4:5], v[4:5], v[70:71]
	v_mov_b32_e32 v70, v75
	v_mov_b32_e32 v71, v77
	v_mov_b32_e32 v68, v74
	v_mov_b32_e32 v69, v76
	v_pk_mul_f32 v[70:71], v[70:71], v[70:71]
	v_mul_f32_e32 v66, v79, v79
	v_pk_fma_f32 v[68:69], v[68:69], v[68:69], v[70:71]
	v_pk_fma_f32 v[72:73], v[78:79], v[78:79], v[66:67] op_sel_hi:[1,1,0]
	v_mul_f32_e32 v66, v81, v81
	v_pk_add_f32 v[70:71], v[68:69], v[68:69] op_sel:[0,1] op_sel_hi:[1,0]
	v_pk_fma_f32 v[82:83], v[80:81], v[80:81], v[66:67] op_sel_hi:[1,1,0]
	s_waitcnt vmcnt(59)
	v_cvt_f32_f16_sdwa v67, v64 dst_sel:DWORD dst_unused:UNUSED_PAD src0_sel:WORD_1
	v_cvt_f32_f16_e32 v66, v64
	v_cvt_f32_f16_sdwa v69, v65 dst_sel:DWORD dst_unused:UNUSED_PAD src0_sel:WORD_1
	v_cvt_f32_f16_e32 v68, v65
	v_pk_add_f32 v[4:5], v[4:5], v[4:5] op_sel:[0,1] op_sel_hi:[1,0]
	v_pk_mul_f32 v[64:65], v[66:67], v[66:67]
	v_pk_mul_f32 v[92:93], v[68:69], v[68:69]
	v_mov_b32_e32 v5, v64
	v_mov_b32_e32 v71, v65
	v_mov_b32_e32 v73, v92
	v_mov_b32_e32 v83, v93
	v_pk_add_f32 v[4:5], v[4:5], v[70:71]
	v_pk_add_f32 v[64:65], v[72:73], v[82:83]
	s_waitcnt vmcnt(58)
	v_cvt_f32_f16_sdwa v71, v62 dst_sel:DWORD dst_unused:UNUSED_PAD src0_sel:WORD_1
	v_cvt_f32_f16_sdwa v73, v63 dst_sel:DWORD dst_unused:UNUSED_PAD src0_sel:WORD_1
	v_cvt_f32_f16_e32 v70, v62
	v_cvt_f32_f16_e32 v72, v63
	v_pk_add_f32 v[4:5], v[4:5], v[64:65]
	v_mov_b32_e32 v62, v71
	v_mov_b32_e32 v63, v73
	v_pk_add_f32 v[82:83], v[4:5], v[4:5] op_sel:[0,1] op_sel_hi:[1,0]
	v_mov_b32_e32 v4, v70
	v_mov_b32_e32 v5, v72
	v_pk_mul_f32 v[62:63], v[62:63], v[62:63]
	s_waitcnt vmcnt(56)
	v_cvt_f32_f16_sdwa v65, v59 dst_sel:DWORD dst_unused:UNUSED_PAD src0_sel:WORD_1
	v_pk_fma_f32 v[4:5], v[4:5], v[4:5], v[62:63]
	v_cvt_f32_f16_sdwa v63, v61 dst_sel:DWORD dst_unused:UNUSED_PAD src0_sel:WORD_1
	v_pk_add_f32 v[92:93], v[4:5], v[4:5] op_sel:[0,1] op_sel_hi:[1,0]
	v_cvt_f32_f16_sdwa v5, v60 dst_sel:DWORD dst_unused:UNUSED_PAD src0_sel:WORD_1
	v_cvt_f32_f16_e32 v4, v60
	v_cvt_f32_f16_e32 v62, v61
	v_cvt_f32_f16_e32 v64, v59
	v_mul_f32_e32 v60, v5, v5
	v_pk_fma_f32 v[94:95], v[4:5], v[4:5], v[60:61] op_sel_hi:[1,1,0]
	v_mul_f32_e32 v60, v63, v63
	v_pk_fma_f32 v[96:97], v[62:63], v[62:63], v[60:61] op_sel_hi:[1,1,0]
	v_cvt_f32_f16_sdwa v61, v58 dst_sel:DWORD dst_unused:UNUSED_PAD src0_sel:WORD_1
	v_cvt_f32_f16_e32 v60, v58
	v_pk_mul_f32 v[98:99], v[64:65], v[64:65]
	v_pk_mul_f32 v[58:59], v[60:61], v[60:61]
	s_nop 0
	v_mov_b32_e32 v83, v58
	v_mov_b32_e32 v93, v59
	v_mov_b32_e32 v95, v98
	v_mov_b32_e32 v97, v99
	v_pk_add_f32 v[58:59], v[82:83], v[92:93]
	v_pk_add_f32 v[82:83], v[94:95], v[96:97]
	s_nop 0
	v_pk_add_f32 v[58:59], v[58:59], v[82:83]
	s_nop 0
	v_add_f32_e32 v58, v58, v59
	s_nop 1
	v_add_f32_dpp v58, v58, v58 quad_perm:[1,0,3,2] row_mask:0xf bank_mask:0xf bound_ctrl:1
	s_nop 1
	v_add_f32_dpp v58, v58, v58 quad_perm:[2,3,0,1] row_mask:0xf bank_mask:0xf bound_ctrl:1
	s_nop 1
	v_add_f32_dpp v58, v58, v58 row_half_mirror row_mask:0xf bank_mask:0xf bound_ctrl:1
	s_nop 1
	v_add_f32_dpp v58, v58, v58 row_mirror row_mask:0xf bank_mask:0xf bound_ctrl:1
	s_nop 0
	v_readlane_b32 s5, v58, 16
	v_readlane_b32 s11, v58, 48
	v_readlane_b32 s6, v58, 0
	v_readlane_b32 s7, v58, 32
	v_mov_b32_e32 v58, s5
	v_mov_b32_e32 v59, s11
	v_pk_add_f32 v[58:59], s[6:7], v[58:59]
	s_lshl_b32 s5, s22, 1
	v_add_f32_e32 v58, v58, v59
	v_fmamk_f32 v58, v58, 0x3a000000, v252
	v_cmp_gt_f32_e32 vcc, s55, v58
	v_mul_f32_e32 v59, 0x4f800000, v58
	s_and_b32 s5, s5, 0xffffe000
	v_cndmask_b32_e32 v58, v58, v59, vcc
	v_sqrt_f32_e32 v59, v58
	s_add_i32 s5, s5, 0
	v_add_u32_e32 v82, -1, v59
	v_fma_f32 v83, -v82, v59, v58
	v_cmp_ge_f32_e64 s[6:7], 0, v83
	v_add_u32_e32 v83, 1, v59
	s_nop 0
	v_cndmask_b32_e64 v82, v59, v82, s[6:7]
	v_fma_f32 v59, -v83, v59, v58
	v_cmp_lt_f32_e64 s[6:7], 0, v59
	s_nop 1
	v_cndmask_b32_e64 v59, v82, v83, s[6:7]
	v_mul_f32_e32 v82, 0x37800000, v59
	v_cndmask_b32_e32 v59, v59, v82, vcc
	v_cmp_class_f32_e32 vcc, v58, v253
	s_nop 1
	v_cndmask_b32_e32 v58, v59, v58, vcc
	v_div_scale_f32 v59, s[6:7], v58, v58, 1.0
	v_rcp_f32_e32 v82, v59
	s_nop 0
	v_fma_f32 v83, -v59, v82, 1.0
	v_fmac_f32_e32 v82, v83, v82
	v_div_scale_f32 v83, vcc, 1.0, v58, 1.0
	v_mul_f32_e32 v92, v83, v82
	v_fma_f32 v93, -v59, v92, v83
	v_fmac_f32_e32 v92, v93, v82
	v_fma_f32 v59, -v59, v92, v83
	v_div_fmas_f32 v59, v59, v82, v92
	v_div_fixup_f32 v82, v59, v58, 1.0
	v_pk_mul_f32 v[96:97], v[88:89], v[82:83] op_sel_hi:[1,0]
	v_pk_mul_f32 v[98:99], v[90:91], v[82:83] op_sel_hi:[1,0]
	v_add_u32_e32 v83, s5, v0
	ds_read_b128 v[88:91], v83
	ds_read_b128 v[92:95], v83 offset:40960
	v_lshl_add_u64 v[58:59], s[24:25], 1, v[2:3]
	v_lshl_add_u64 v[58:59], v[58:59], 0, v[6:7]
	v_pk_mul_f32 v[4:5], v[4:5], v[82:83] op_sel_hi:[1,0]
	v_pk_mul_f32 v[62:63], v[62:63], v[82:83] op_sel_hi:[1,0]
	s_waitcnt lgkmcnt(0)
	v_pk_fma_f32 v[90:91], v[90:91], v[98:99], v[94:95]
	v_pk_fma_f32 v[88:89], v[88:89], v[96:97], v[92:93]
	v_pk_mul_f32 v[92:93], v[84:85], v[82:83] op_sel_hi:[1,0]
	v_cvt_pk_bf16_f32 v88, v88, v89
	v_cvt_pk_bf16_f32 v89, v90, v91
	global_store_dwordx2 v[58:59], v[88:89], off
	v_pk_mul_f32 v[94:95], v[86:87], v[82:83] op_sel_hi:[1,0]
	ds_read_b128 v[84:87], v83 offset:1024
	ds_read_b128 v[88:91], v83 offset:41984
	s_waitcnt lgkmcnt(0)
	v_pk_fma_f32 v[86:87], v[86:87], v[94:95], v[90:91]
	v_pk_fma_f32 v[84:85], v[84:85], v[92:93], v[88:89]
	v_pk_mul_f32 v[88:89], v[74:75], v[82:83] op_sel_hi:[1,0]
	v_cvt_pk_bf16_f32 v84, v84, v85
	v_cvt_pk_bf16_f32 v85, v86, v87
	global_store_dwordx2 v[58:59], v[84:85], off offset:512
	v_pk_mul_f32 v[90:91], v[76:77], v[82:83] op_sel_hi:[1,0]
	ds_read_b128 v[74:77], v83 offset:2048
	ds_read_b128 v[84:87], v83 offset:43008
	s_waitcnt lgkmcnt(0)
	v_pk_fma_f32 v[76:77], v[76:77], v[90:91], v[86:87]
	v_pk_fma_f32 v[74:75], v[74:75], v[88:89], v[84:85]
	v_pk_mul_f32 v[84:85], v[78:79], v[82:83] op_sel_hi:[1,0]
	v_cvt_pk_bf16_f32 v74, v74, v75
	v_cvt_pk_bf16_f32 v75, v76, v77
	global_store_dwordx2 v[58:59], v[74:75], off offset:1024
	v_pk_mul_f32 v[86:87], v[80:81], v[82:83] op_sel_hi:[1,0]
	ds_read_b128 v[74:77], v83 offset:3072
	ds_read_b128 v[78:81], v83 offset:44032
	s_waitcnt lgkmcnt(0)
	v_pk_fma_f32 v[76:77], v[86:87], v[76:77], v[80:81]
	v_pk_fma_f32 v[74:75], v[84:85], v[74:75], v[78:79]
	v_pk_mul_f32 v[78:79], v[66:67], v[82:83] op_sel_hi:[1,0]
	v_cvt_pk_bf16_f32 v74, v74, v75
	v_cvt_pk_bf16_f32 v75, v76, v77
	global_store_dwordx2 v[58:59], v[74:75], off offset:1536
	v_pk_mul_f32 v[80:81], v[68:69], v[82:83] op_sel_hi:[1,0]
	ds_read_b128 v[66:69], v83 offset:4096
	ds_read_b128 v[74:77], v83 offset:45056
	s_waitcnt lgkmcnt(0)
	v_pk_fma_f32 v[68:69], v[80:81], v[68:69], v[76:77]
	v_pk_fma_f32 v[66:67], v[78:79], v[66:67], v[74:75]
	v_pk_mul_f32 v[74:75], v[70:71], v[82:83] op_sel_hi:[1,0]
	v_cvt_pk_bf16_f32 v66, v66, v67
	v_cvt_pk_bf16_f32 v67, v68, v69
	global_store_dwordx2 v[58:59], v[66:67], off offset:2048
	v_pk_mul_f32 v[76:77], v[72:73], v[82:83] op_sel_hi:[1,0]
	ds_read_b128 v[66:69], v83 offset:5120
	ds_read_b128 v[70:73], v83 offset:46080
	s_waitcnt lgkmcnt(0)
	v_pk_fma_f32 v[68:69], v[76:77], v[68:69], v[72:73]
	v_pk_fma_f32 v[66:67], v[74:75], v[66:67], v[70:71]
	s_waitcnt vmcnt(60)
	v_cvt_f32_f16_sdwa v75, v57 dst_sel:DWORD dst_unused:UNUSED_PAD src0_sel:WORD_1
	v_cvt_pk_bf16_f32 v66, v66, v67
	v_cvt_pk_bf16_f32 v67, v68, v69
	global_store_dwordx2 v[58:59], v[66:67], off offset:2560
	ds_read_b128 v[66:69], v83 offset:6144
	ds_read_b128 v[70:73], v83 offset:47104
	v_cvt_f32_f16_e32 v74, v57
	s_waitcnt lgkmcnt(0)
	v_pk_fma_f32 v[62:63], v[62:63], v[68:69], v[72:73]
	v_pk_fma_f32 v[4:5], v[4:5], v[66:67], v[70:71]
	v_pk_mul_f32 v[68:69], v[64:65], v[82:83] op_sel_hi:[1,0]
	v_cvt_pk_bf16_f32 v4, v4, v5
	v_cvt_pk_bf16_f32 v5, v62, v63
	global_store_dwordx2 v[58:59], v[4:5], off offset:3072
	v_pk_mul_f32 v[4:5], v[60:61], v[82:83] op_sel_hi:[1,0]
	ds_read_b128 v[60:63], v83 offset:7168
	ds_read_b128 v[64:67], v83 offset:48128
	v_cvt_f32_f16_sdwa v73, v56 dst_sel:DWORD dst_unused:UNUSED_PAD src0_sel:WORD_1
	v_cvt_f32_f16_e32 v72, v56
	s_waitcnt vmcnt(61)
	v_cvt_f32_f16_sdwa v71, v55 dst_sel:DWORD dst_unused:UNUSED_PAD src0_sel:WORD_1
	v_cvt_f32_f16_e32 v70, v55
	s_waitcnt lgkmcnt(0)
	v_pk_fma_f32 v[62:63], v[68:69], v[62:63], v[66:67]
	v_cvt_f32_f16_sdwa v69, v54 dst_sel:DWORD dst_unused:UNUSED_PAD src0_sel:WORD_1
	v_cvt_f32_f16_e32 v68, v54
	v_pk_fma_f32 v[4:5], v[4:5], v[60:61], v[64:65]
	v_mov_b32_e32 v54, v73
	v_cvt_pk_bf16_f32 v4, v4, v5
	v_cvt_pk_bf16_f32 v5, v62, v63
	global_store_dwordx2 v[58:59], v[4:5], off offset:3584
	v_mov_b32_e32 v55, v69
	s_waitcnt vmcnt(61)
	v_cvt_f32_f16_sdwa v59, v52 dst_sel:DWORD dst_unused:UNUSED_PAD src0_sel:WORD_1
	v_cvt_f32_f16_sdwa v61, v53 dst_sel:DWORD dst_unused:UNUSED_PAD src0_sel:WORD_1
	v_mov_b32_e32 v4, v72
	v_mov_b32_e32 v5, v68
	v_pk_mul_f32 v[54:55], v[54:55], v[54:55]
	v_mov_b32_e32 v56, v75
	v_mov_b32_e32 v57, v71
	v_cvt_f32_f16_e32 v58, v52
	v_cvt_f32_f16_e32 v60, v53
	s_waitcnt vmcnt(60)
	v_cvt_f32_f16_sdwa v63, v50 dst_sel:DWORD dst_unused:UNUSED_PAD src0_sel:WORD_1
	v_pk_fma_f32 v[4:5], v[4:5], v[4:5], v[54:55]
	v_mov_b32_e32 v54, v74
	v_mov_b32_e32 v55, v70
	v_pk_mul_f32 v[56:57], v[56:57], v[56:57]
	v_cvt_f32_f16_e32 v62, v50
	v_cvt_f32_f16_sdwa v65, v51 dst_sel:DWORD dst_unused:UNUSED_PAD src0_sel:WORD_1
	v_pk_fma_f32 v[54:55], v[54:55], v[54:55], v[56:57]
	v_cvt_f32_f16_e32 v64, v51
	v_pk_add_f32 v[4:5], v[4:5], v[54:55]
	v_mov_b32_e32 v54, v59
	v_mov_b32_e32 v55, v61
	v_mov_b32_e32 v52, v58
	v_mov_b32_e32 v53, v60
	v_pk_mul_f32 v[54:55], v[54:55], v[54:55]
	v_mul_f32_e32 v50, v63, v63
	v_pk_fma_f32 v[52:53], v[52:53], v[52:53], v[54:55]
	v_pk_fma_f32 v[56:57], v[62:63], v[62:63], v[50:51] op_sel_hi:[1,1,0]
	v_mul_f32_e32 v50, v65, v65
	v_pk_add_f32 v[54:55], v[52:53], v[52:53] op_sel:[0,1] op_sel_hi:[1,0]
	v_pk_fma_f32 v[66:67], v[64:65], v[64:65], v[50:51] op_sel_hi:[1,1,0]
	s_waitcnt vmcnt(59)
	v_cvt_f32_f16_sdwa v51, v48 dst_sel:DWORD dst_unused:UNUSED_PAD src0_sel:WORD_1
	v_cvt_f32_f16_e32 v50, v48
	v_cvt_f32_f16_sdwa v53, v49 dst_sel:DWORD dst_unused:UNUSED_PAD src0_sel:WORD_1
	v_cvt_f32_f16_e32 v52, v49
	v_pk_add_f32 v[4:5], v[4:5], v[4:5] op_sel:[0,1] op_sel_hi:[1,0]
	v_pk_mul_f32 v[48:49], v[50:51], v[50:51]
	v_pk_mul_f32 v[76:77], v[52:53], v[52:53]
	v_mov_b32_e32 v5, v48
	v_mov_b32_e32 v55, v49
	v_mov_b32_e32 v57, v76
	v_mov_b32_e32 v67, v77
	v_pk_add_f32 v[4:5], v[4:5], v[54:55]
	v_pk_add_f32 v[48:49], v[56:57], v[66:67]
	s_waitcnt vmcnt(58)
	v_cvt_f32_f16_sdwa v55, v46 dst_sel:DWORD dst_unused:UNUSED_PAD src0_sel:WORD_1
	v_cvt_f32_f16_sdwa v57, v47 dst_sel:DWORD dst_unused:UNUSED_PAD src0_sel:WORD_1
	v_cvt_f32_f16_e32 v54, v46
	v_cvt_f32_f16_e32 v56, v47
	v_pk_add_f32 v[4:5], v[4:5], v[48:49]
	v_mov_b32_e32 v46, v55
	v_mov_b32_e32 v47, v57
	v_pk_add_f32 v[66:67], v[4:5], v[4:5] op_sel:[0,1] op_sel_hi:[1,0]
	v_mov_b32_e32 v4, v54
	v_mov_b32_e32 v5, v56
	v_pk_mul_f32 v[46:47], v[46:47], v[46:47]
	s_waitcnt vmcnt(56)
	v_cvt_f32_f16_sdwa v49, v43 dst_sel:DWORD dst_unused:UNUSED_PAD src0_sel:WORD_1
	v_pk_fma_f32 v[4:5], v[4:5], v[4:5], v[46:47]
	v_cvt_f32_f16_sdwa v47, v45 dst_sel:DWORD dst_unused:UNUSED_PAD src0_sel:WORD_1
	v_pk_add_f32 v[76:77], v[4:5], v[4:5] op_sel:[0,1] op_sel_hi:[1,0]
	v_cvt_f32_f16_sdwa v5, v44 dst_sel:DWORD dst_unused:UNUSED_PAD src0_sel:WORD_1
	v_cvt_f32_f16_e32 v4, v44
	v_cvt_f32_f16_e32 v46, v45
	v_cvt_f32_f16_e32 v48, v43
	v_mul_f32_e32 v44, v5, v5
	v_pk_fma_f32 v[78:79], v[4:5], v[4:5], v[44:45] op_sel_hi:[1,1,0]
	v_mul_f32_e32 v44, v47, v47
	v_pk_fma_f32 v[80:81], v[46:47], v[46:47], v[44:45] op_sel_hi:[1,1,0]
	v_cvt_f32_f16_sdwa v45, v42 dst_sel:DWORD dst_unused:UNUSED_PAD src0_sel:WORD_1
	v_cvt_f32_f16_e32 v44, v42
	v_pk_mul_f32 v[82:83], v[48:49], v[48:49]
	v_pk_mul_f32 v[42:43], v[44:45], v[44:45]
	s_nop 0
	v_mov_b32_e32 v67, v42
	v_mov_b32_e32 v77, v43
	v_mov_b32_e32 v79, v82
	v_mov_b32_e32 v81, v83
	v_pk_add_f32 v[42:43], v[66:67], v[76:77]
	v_pk_add_f32 v[66:67], v[78:79], v[80:81]
	s_nop 0
	v_pk_add_f32 v[42:43], v[42:43], v[66:67]
	s_nop 0
	v_add_f32_e32 v42, v42, v43
	s_nop 1
	v_add_f32_dpp v42, v42, v42 quad_perm:[1,0,3,2] row_mask:0xf bank_mask:0xf bound_ctrl:1
	s_nop 1
	v_add_f32_dpp v42, v42, v42 quad_perm:[2,3,0,1] row_mask:0xf bank_mask:0xf bound_ctrl:1
	s_nop 1
	v_add_f32_dpp v42, v42, v42 row_half_mirror row_mask:0xf bank_mask:0xf bound_ctrl:1
	s_nop 1
	v_add_f32_dpp v42, v42, v42 row_mirror row_mask:0xf bank_mask:0xf bound_ctrl:1
	s_nop 0
	v_readlane_b32 s5, v42, 16
	v_readlane_b32 s11, v42, 48
	v_readlane_b32 s6, v42, 0
	v_readlane_b32 s7, v42, 32
	v_mov_b32_e32 v42, s5
	v_mov_b32_e32 v43, s11
	v_pk_add_f32 v[42:43], s[6:7], v[42:43]
	s_lshl_b32 s5, s18, 1
	v_add_f32_e32 v42, v42, v43
	v_fmamk_f32 v42, v42, 0x3a000000, v252
	v_cmp_gt_f32_e32 vcc, s55, v42
	v_mul_f32_e32 v43, 0x4f800000, v42
	s_and_b32 s5, s5, 0xffffe000
	v_cndmask_b32_e32 v42, v42, v43, vcc
	v_sqrt_f32_e32 v43, v42
	s_add_i32 s5, s5, 0
	v_add_u32_e32 v66, -1, v43
	v_fma_f32 v67, -v66, v43, v42
	v_cmp_ge_f32_e64 s[6:7], 0, v67
	v_add_u32_e32 v67, 1, v43
	s_nop 0
	v_cndmask_b32_e64 v66, v43, v66, s[6:7]
	v_fma_f32 v43, -v67, v43, v42
	v_cmp_lt_f32_e64 s[6:7], 0, v43
	s_nop 1
	v_cndmask_b32_e64 v43, v66, v67, s[6:7]
	v_mul_f32_e32 v66, 0x37800000, v43
	v_cndmask_b32_e32 v43, v43, v66, vcc
	v_cmp_class_f32_e32 vcc, v42, v253
	s_nop 1
	v_cndmask_b32_e32 v42, v43, v42, vcc
	v_div_scale_f32 v43, s[6:7], v42, v42, 1.0
	v_rcp_f32_e32 v66, v43
	s_nop 0
	v_fma_f32 v67, -v43, v66, 1.0
	v_fmac_f32_e32 v66, v67, v66
	v_div_scale_f32 v67, vcc, 1.0, v42, 1.0
	v_mul_f32_e32 v76, v67, v66
	v_fma_f32 v77, -v43, v76, v67
	v_fmac_f32_e32 v76, v77, v66
	v_fma_f32 v43, -v43, v76, v67
	v_div_fmas_f32 v43, v43, v66, v76
	v_div_fixup_f32 v66, v43, v42, 1.0
	v_pk_mul_f32 v[80:81], v[72:73], v[66:67] op_sel_hi:[1,0]
	v_pk_mul_f32 v[82:83], v[74:75], v[66:67] op_sel_hi:[1,0]
	v_add_u32_e32 v67, s5, v0
	ds_read_b128 v[72:75], v67
	ds_read_b128 v[76:79], v67 offset:40960
	v_lshl_add_u64 v[42:43], s[20:21], 1, v[2:3]
	v_lshl_add_u64 v[42:43], v[42:43], 0, v[6:7]
	v_pk_mul_f32 v[4:5], v[4:5], v[66:67] op_sel_hi:[1,0]
	v_pk_mul_f32 v[46:47], v[46:47], v[66:67] op_sel_hi:[1,0]
	s_waitcnt lgkmcnt(0)
	v_pk_fma_f32 v[74:75], v[74:75], v[82:83], v[78:79]
	v_pk_fma_f32 v[72:73], v[72:73], v[80:81], v[76:77]
	v_pk_mul_f32 v[76:77], v[68:69], v[66:67] op_sel_hi:[1,0]
	v_cvt_pk_bf16_f32 v72, v72, v73
	v_cvt_pk_bf16_f32 v73, v74, v75
	global_store_dwordx2 v[42:43], v[72:73], off
	v_pk_mul_f32 v[78:79], v[70:71], v[66:67] op_sel_hi:[1,0]
	ds_read_b128 v[68:71], v67 offset:1024
	ds_read_b128 v[72:75], v67 offset:41984
	s_waitcnt lgkmcnt(0)
	v_pk_fma_f32 v[70:71], v[70:71], v[78:79], v[74:75]
	v_pk_fma_f32 v[68:69], v[68:69], v[76:77], v[72:73]
	v_pk_mul_f32 v[72:73], v[58:59], v[66:67] op_sel_hi:[1,0]
	v_cvt_pk_bf16_f32 v68, v68, v69
	v_cvt_pk_bf16_f32 v69, v70, v71
	global_store_dwordx2 v[42:43], v[68:69], off offset:512
	v_pk_mul_f32 v[74:75], v[60:61], v[66:67] op_sel_hi:[1,0]
	ds_read_b128 v[58:61], v67 offset:2048
	ds_read_b128 v[68:71], v67 offset:43008
	s_waitcnt lgkmcnt(0)
	v_pk_fma_f32 v[60:61], v[60:61], v[74:75], v[70:71]
	v_pk_fma_f32 v[58:59], v[58:59], v[72:73], v[68:69]
	v_pk_mul_f32 v[68:69], v[62:63], v[66:67] op_sel_hi:[1,0]
	v_cvt_pk_bf16_f32 v58, v58, v59
	v_cvt_pk_bf16_f32 v59, v60, v61
	global_store_dwordx2 v[42:43], v[58:59], off offset:1024
	v_pk_mul_f32 v[70:71], v[64:65], v[66:67] op_sel_hi:[1,0]
	ds_read_b128 v[58:61], v67 offset:3072
	ds_read_b128 v[62:65], v67 offset:44032
	s_waitcnt lgkmcnt(0)
	v_pk_fma_f32 v[60:61], v[70:71], v[60:61], v[64:65]
	v_pk_fma_f32 v[58:59], v[68:69], v[58:59], v[62:63]
	v_pk_mul_f32 v[62:63], v[50:51], v[66:67] op_sel_hi:[1,0]
	v_cvt_pk_bf16_f32 v58, v58, v59
	v_cvt_pk_bf16_f32 v59, v60, v61
	global_store_dwordx2 v[42:43], v[58:59], off offset:1536
	v_pk_mul_f32 v[64:65], v[52:53], v[66:67] op_sel_hi:[1,0]
	ds_read_b128 v[50:53], v67 offset:4096
	ds_read_b128 v[58:61], v67 offset:45056
	s_waitcnt lgkmcnt(0)
	v_pk_fma_f32 v[52:53], v[64:65], v[52:53], v[60:61]
	v_pk_fma_f32 v[50:51], v[62:63], v[50:51], v[58:59]
	v_pk_mul_f32 v[58:59], v[54:55], v[66:67] op_sel_hi:[1,0]
	v_cvt_pk_bf16_f32 v50, v50, v51
	v_cvt_pk_bf16_f32 v51, v52, v53
	global_store_dwordx2 v[42:43], v[50:51], off offset:2048
	v_pk_mul_f32 v[60:61], v[56:57], v[66:67] op_sel_hi:[1,0]
	ds_read_b128 v[50:53], v67 offset:5120
	ds_read_b128 v[54:57], v67 offset:46080
	s_waitcnt lgkmcnt(0)
	v_pk_fma_f32 v[52:53], v[60:61], v[52:53], v[56:57]
	v_pk_fma_f32 v[50:51], v[58:59], v[50:51], v[54:55]
	s_waitcnt vmcnt(60)
	v_cvt_f32_f16_sdwa v59, v41 dst_sel:DWORD dst_unused:UNUSED_PAD src0_sel:WORD_1
	v_cvt_pk_bf16_f32 v50, v50, v51
	v_cvt_pk_bf16_f32 v51, v52, v53
	global_store_dwordx2 v[42:43], v[50:51], off offset:2560
	ds_read_b128 v[50:53], v67 offset:6144
	ds_read_b128 v[54:57], v67 offset:47104
	v_cvt_f32_f16_e32 v58, v41
	s_waitcnt lgkmcnt(0)
	v_pk_fma_f32 v[46:47], v[46:47], v[52:53], v[56:57]
	v_pk_fma_f32 v[4:5], v[4:5], v[50:51], v[54:55]
	v_pk_mul_f32 v[52:53], v[48:49], v[66:67] op_sel_hi:[1,0]
	v_cvt_pk_bf16_f32 v4, v4, v5
	v_cvt_pk_bf16_f32 v5, v46, v47
	global_store_dwordx2 v[42:43], v[4:5], off offset:3072
	v_pk_mul_f32 v[4:5], v[44:45], v[66:67] op_sel_hi:[1,0]
	ds_read_b128 v[44:47], v67 offset:7168
	ds_read_b128 v[48:51], v67 offset:48128
	v_cvt_f32_f16_sdwa v57, v40 dst_sel:DWORD dst_unused:UNUSED_PAD src0_sel:WORD_1
	v_cvt_f32_f16_e32 v56, v40
	s_waitcnt vmcnt(61)
	v_cvt_f32_f16_sdwa v55, v39 dst_sel:DWORD dst_unused:UNUSED_PAD src0_sel:WORD_1
	v_cvt_f32_f16_e32 v54, v39
	s_waitcnt lgkmcnt(0)
	v_pk_fma_f32 v[46:47], v[52:53], v[46:47], v[50:51]
	v_cvt_f32_f16_sdwa v53, v38 dst_sel:DWORD dst_unused:UNUSED_PAD src0_sel:WORD_1
	v_cvt_f32_f16_e32 v52, v38
	v_pk_fma_f32 v[4:5], v[4:5], v[44:45], v[48:49]
	v_mov_b32_e32 v38, v57
	v_cvt_pk_bf16_f32 v4, v4, v5
	v_cvt_pk_bf16_f32 v5, v46, v47
	global_store_dwordx2 v[42:43], v[4:5], off offset:3584
	v_mov_b32_e32 v39, v53
	s_waitcnt vmcnt(61)
	v_cvt_f32_f16_sdwa v43, v36 dst_sel:DWORD dst_unused:UNUSED_PAD src0_sel:WORD_1
	v_cvt_f32_f16_sdwa v45, v37 dst_sel:DWORD dst_unused:UNUSED_PAD src0_sel:WORD_1
	v_mov_b32_e32 v4, v56
	v_mov_b32_e32 v5, v52
	v_pk_mul_f32 v[38:39], v[38:39], v[38:39]
	v_mov_b32_e32 v40, v59
	v_mov_b32_e32 v41, v55
	v_cvt_f32_f16_e32 v42, v36
	v_cvt_f32_f16_e32 v44, v37
	s_waitcnt vmcnt(60)
	v_cvt_f32_f16_sdwa v47, v34 dst_sel:DWORD dst_unused:UNUSED_PAD src0_sel:WORD_1
	v_pk_fma_f32 v[4:5], v[4:5], v[4:5], v[38:39]
	v_mov_b32_e32 v38, v58
	v_mov_b32_e32 v39, v54
	v_pk_mul_f32 v[40:41], v[40:41], v[40:41]
	v_cvt_f32_f16_e32 v46, v34
	v_cvt_f32_f16_sdwa v49, v35 dst_sel:DWORD dst_unused:UNUSED_PAD src0_sel:WORD_1
	v_pk_fma_f32 v[38:39], v[38:39], v[38:39], v[40:41]
	v_cvt_f32_f16_e32 v48, v35
	v_pk_add_f32 v[4:5], v[4:5], v[38:39]
	v_mov_b32_e32 v38, v43
	v_mov_b32_e32 v39, v45
	v_mov_b32_e32 v36, v42
	v_mov_b32_e32 v37, v44
	v_pk_mul_f32 v[38:39], v[38:39], v[38:39]
	v_mul_f32_e32 v34, v47, v47
	v_pk_fma_f32 v[36:37], v[36:37], v[36:37], v[38:39]
	v_pk_fma_f32 v[40:41], v[46:47], v[46:47], v[34:35] op_sel_hi:[1,1,0]
	v_mul_f32_e32 v34, v49, v49
	v_pk_add_f32 v[38:39], v[36:37], v[36:37] op_sel:[0,1] op_sel_hi:[1,0]
	v_pk_fma_f32 v[50:51], v[48:49], v[48:49], v[34:35] op_sel_hi:[1,1,0]
	s_waitcnt vmcnt(59)
	v_cvt_f32_f16_sdwa v35, v32 dst_sel:DWORD dst_unused:UNUSED_PAD src0_sel:WORD_1
	v_cvt_f32_f16_e32 v34, v32
	v_cvt_f32_f16_sdwa v37, v33 dst_sel:DWORD dst_unused:UNUSED_PAD src0_sel:WORD_1
	v_cvt_f32_f16_e32 v36, v33
	v_pk_add_f32 v[4:5], v[4:5], v[4:5] op_sel:[0,1] op_sel_hi:[1,0]
	v_pk_mul_f32 v[32:33], v[34:35], v[34:35]
	v_pk_mul_f32 v[60:61], v[36:37], v[36:37]
	v_mov_b32_e32 v5, v32
	v_mov_b32_e32 v39, v33
	v_mov_b32_e32 v41, v60
	v_mov_b32_e32 v51, v61
	v_pk_add_f32 v[4:5], v[4:5], v[38:39]
	v_pk_add_f32 v[32:33], v[40:41], v[50:51]
	s_waitcnt vmcnt(58)
	v_cvt_f32_f16_sdwa v39, v30 dst_sel:DWORD dst_unused:UNUSED_PAD src0_sel:WORD_1
	v_cvt_f32_f16_sdwa v41, v31 dst_sel:DWORD dst_unused:UNUSED_PAD src0_sel:WORD_1
	v_cvt_f32_f16_e32 v38, v30
	v_cvt_f32_f16_e32 v40, v31
	v_pk_add_f32 v[4:5], v[4:5], v[32:33]
	v_mov_b32_e32 v30, v39
	v_mov_b32_e32 v31, v41
	v_pk_add_f32 v[50:51], v[4:5], v[4:5] op_sel:[0,1] op_sel_hi:[1,0]
	v_mov_b32_e32 v4, v38
	v_mov_b32_e32 v5, v40
	v_pk_mul_f32 v[30:31], v[30:31], v[30:31]
	s_waitcnt vmcnt(56)
	v_cvt_f32_f16_sdwa v33, v27 dst_sel:DWORD dst_unused:UNUSED_PAD src0_sel:WORD_1
	v_pk_fma_f32 v[4:5], v[4:5], v[4:5], v[30:31]
	v_cvt_f32_f16_sdwa v31, v29 dst_sel:DWORD dst_unused:UNUSED_PAD src0_sel:WORD_1
	v_pk_add_f32 v[60:61], v[4:5], v[4:5] op_sel:[0,1] op_sel_hi:[1,0]
	v_cvt_f32_f16_sdwa v5, v28 dst_sel:DWORD dst_unused:UNUSED_PAD src0_sel:WORD_1
	v_cvt_f32_f16_e32 v4, v28
	v_cvt_f32_f16_e32 v30, v29
	v_cvt_f32_f16_e32 v32, v27
	v_mul_f32_e32 v28, v5, v5
	v_pk_fma_f32 v[62:63], v[4:5], v[4:5], v[28:29] op_sel_hi:[1,1,0]
	v_mul_f32_e32 v28, v31, v31
	v_pk_fma_f32 v[64:65], v[30:31], v[30:31], v[28:29] op_sel_hi:[1,1,0]
	v_cvt_f32_f16_sdwa v29, v26 dst_sel:DWORD dst_unused:UNUSED_PAD src0_sel:WORD_1
	v_cvt_f32_f16_e32 v28, v26
	v_pk_mul_f32 v[66:67], v[32:33], v[32:33]
	v_pk_mul_f32 v[26:27], v[28:29], v[28:29]
	s_nop 0
	v_mov_b32_e32 v51, v26
	v_mov_b32_e32 v61, v27
	v_mov_b32_e32 v63, v66
	v_mov_b32_e32 v65, v67
	v_pk_add_f32 v[26:27], v[50:51], v[60:61]
	v_pk_add_f32 v[50:51], v[62:63], v[64:65]
	s_nop 0
	v_pk_add_f32 v[26:27], v[26:27], v[50:51]
	s_nop 0
	v_add_f32_e32 v26, v26, v27
	s_nop 1
	v_add_f32_dpp v26, v26, v26 quad_perm:[1,0,3,2] row_mask:0xf bank_mask:0xf bound_ctrl:1
	s_nop 1
	v_add_f32_dpp v26, v26, v26 quad_perm:[2,3,0,1] row_mask:0xf bank_mask:0xf bound_ctrl:1
	s_nop 1
	v_add_f32_dpp v26, v26, v26 row_half_mirror row_mask:0xf bank_mask:0xf bound_ctrl:1
	s_nop 1
	v_add_f32_dpp v26, v26, v26 row_mirror row_mask:0xf bank_mask:0xf bound_ctrl:1
	s_nop 0
	v_readlane_b32 s5, v26, 16
	v_readlane_b32 s11, v26, 48
	v_readlane_b32 s6, v26, 0
	v_readlane_b32 s7, v26, 32
	v_mov_b32_e32 v26, s5
	v_mov_b32_e32 v27, s11
	v_pk_add_f32 v[26:27], s[6:7], v[26:27]
	s_lshl_b32 s5, s14, 1
	v_add_f32_e32 v26, v26, v27
	v_fmamk_f32 v26, v26, 0x3a000000, v252
	v_cmp_gt_f32_e32 vcc, s55, v26
	v_mul_f32_e32 v27, 0x4f800000, v26
	s_and_b32 s5, s5, 0xffffe000
	v_cndmask_b32_e32 v26, v26, v27, vcc
	v_sqrt_f32_e32 v27, v26
	s_add_i32 s5, s5, 0
	v_add_u32_e32 v50, -1, v27
	v_fma_f32 v51, -v50, v27, v26
	v_cmp_ge_f32_e64 s[6:7], 0, v51
	v_add_u32_e32 v51, 1, v27
	s_nop 0
	v_cndmask_b32_e64 v50, v27, v50, s[6:7]
	v_fma_f32 v27, -v51, v27, v26
	v_cmp_lt_f32_e64 s[6:7], 0, v27
	s_nop 1
	v_cndmask_b32_e64 v27, v50, v51, s[6:7]
	v_mul_f32_e32 v50, 0x37800000, v27
	v_cndmask_b32_e32 v27, v27, v50, vcc
	v_cmp_class_f32_e32 vcc, v26, v253
	s_nop 1
	v_cndmask_b32_e32 v26, v27, v26, vcc
	v_div_scale_f32 v27, s[6:7], v26, v26, 1.0
	v_rcp_f32_e32 v50, v27
	s_nop 0
	v_fma_f32 v51, -v27, v50, 1.0
	v_fmac_f32_e32 v50, v51, v50
	v_div_scale_f32 v51, vcc, 1.0, v26, 1.0
	v_mul_f32_e32 v60, v51, v50
	v_fma_f32 v61, -v27, v60, v51
	v_fmac_f32_e32 v60, v61, v50
	v_fma_f32 v27, -v27, v60, v51
	v_div_fmas_f32 v27, v27, v50, v60
	v_div_fixup_f32 v50, v27, v26, 1.0
	v_pk_mul_f32 v[64:65], v[56:57], v[50:51] op_sel_hi:[1,0]
	v_pk_mul_f32 v[66:67], v[58:59], v[50:51] op_sel_hi:[1,0]
	v_add_u32_e32 v51, s5, v0
	ds_read_b128 v[56:59], v51
	ds_read_b128 v[60:63], v51 offset:40960
	v_lshl_add_u64 v[26:27], s[16:17], 1, v[2:3]
	v_lshl_add_u64 v[26:27], v[26:27], 0, v[6:7]
	v_pk_mul_f32 v[4:5], v[4:5], v[50:51] op_sel_hi:[1,0]
	v_pk_mul_f32 v[30:31], v[30:31], v[50:51] op_sel_hi:[1,0]
	s_waitcnt lgkmcnt(0)
	v_pk_fma_f32 v[58:59], v[58:59], v[66:67], v[62:63]
	v_pk_fma_f32 v[56:57], v[56:57], v[64:65], v[60:61]
	v_pk_mul_f32 v[60:61], v[52:53], v[50:51] op_sel_hi:[1,0]
	v_cvt_pk_bf16_f32 v56, v56, v57
	v_cvt_pk_bf16_f32 v57, v58, v59
	global_store_dwordx2 v[26:27], v[56:57], off
	v_pk_mul_f32 v[62:63], v[54:55], v[50:51] op_sel_hi:[1,0]
	ds_read_b128 v[52:55], v51 offset:1024
	ds_read_b128 v[56:59], v51 offset:41984
	s_waitcnt lgkmcnt(0)
	v_pk_fma_f32 v[54:55], v[54:55], v[62:63], v[58:59]
	v_pk_fma_f32 v[52:53], v[52:53], v[60:61], v[56:57]
	v_pk_mul_f32 v[56:57], v[42:43], v[50:51] op_sel_hi:[1,0]
	v_cvt_pk_bf16_f32 v52, v52, v53
	v_cvt_pk_bf16_f32 v53, v54, v55
	global_store_dwordx2 v[26:27], v[52:53], off offset:512
	v_pk_mul_f32 v[58:59], v[44:45], v[50:51] op_sel_hi:[1,0]
	ds_read_b128 v[42:45], v51 offset:2048
	ds_read_b128 v[52:55], v51 offset:43008
	s_waitcnt lgkmcnt(0)
	v_pk_fma_f32 v[44:45], v[44:45], v[58:59], v[54:55]
	v_pk_fma_f32 v[42:43], v[42:43], v[56:57], v[52:53]
	v_pk_mul_f32 v[52:53], v[46:47], v[50:51] op_sel_hi:[1,0]
	v_cvt_pk_bf16_f32 v42, v42, v43
	v_cvt_pk_bf16_f32 v43, v44, v45
	global_store_dwordx2 v[26:27], v[42:43], off offset:1024
	v_pk_mul_f32 v[54:55], v[48:49], v[50:51] op_sel_hi:[1,0]
	ds_read_b128 v[42:45], v51 offset:3072
	ds_read_b128 v[46:49], v51 offset:44032
	s_waitcnt lgkmcnt(0)
	v_pk_fma_f32 v[44:45], v[54:55], v[44:45], v[48:49]
	v_pk_fma_f32 v[42:43], v[52:53], v[42:43], v[46:47]
	v_pk_mul_f32 v[46:47], v[34:35], v[50:51] op_sel_hi:[1,0]
	v_cvt_pk_bf16_f32 v42, v42, v43
	v_cvt_pk_bf16_f32 v43, v44, v45
	global_store_dwordx2 v[26:27], v[42:43], off offset:1536
	v_pk_mul_f32 v[48:49], v[36:37], v[50:51] op_sel_hi:[1,0]
	ds_read_b128 v[34:37], v51 offset:4096
	ds_read_b128 v[42:45], v51 offset:45056
	s_waitcnt lgkmcnt(0)
	v_pk_fma_f32 v[36:37], v[48:49], v[36:37], v[44:45]
	v_pk_fma_f32 v[34:35], v[46:47], v[34:35], v[42:43]
	v_pk_mul_f32 v[42:43], v[38:39], v[50:51] op_sel_hi:[1,0]
	v_cvt_pk_bf16_f32 v34, v34, v35
	v_cvt_pk_bf16_f32 v35, v36, v37
	global_store_dwordx2 v[26:27], v[34:35], off offset:2048
	v_pk_mul_f32 v[44:45], v[40:41], v[50:51] op_sel_hi:[1,0]
	ds_read_b128 v[34:37], v51 offset:5120
	ds_read_b128 v[38:41], v51 offset:46080
	s_waitcnt lgkmcnt(0)
	v_pk_fma_f32 v[36:37], v[44:45], v[36:37], v[40:41]
	v_pk_fma_f32 v[34:35], v[42:43], v[34:35], v[38:39]
	s_waitcnt vmcnt(60)
	v_cvt_f32_f16_sdwa v43, v25 dst_sel:DWORD dst_unused:UNUSED_PAD src0_sel:WORD_1
	v_cvt_pk_bf16_f32 v34, v34, v35
	v_cvt_pk_bf16_f32 v35, v36, v37
	global_store_dwordx2 v[26:27], v[34:35], off offset:2560
	ds_read_b128 v[34:37], v51 offset:6144
	ds_read_b128 v[38:41], v51 offset:47104
	v_cvt_f32_f16_e32 v42, v25
	s_waitcnt lgkmcnt(0)
	v_pk_fma_f32 v[30:31], v[30:31], v[36:37], v[40:41]
	v_pk_fma_f32 v[4:5], v[4:5], v[34:35], v[38:39]
	v_pk_mul_f32 v[36:37], v[32:33], v[50:51] op_sel_hi:[1,0]
	v_cvt_pk_bf16_f32 v4, v4, v5
	v_cvt_pk_bf16_f32 v5, v30, v31
	global_store_dwordx2 v[26:27], v[4:5], off offset:3072
	v_pk_mul_f32 v[4:5], v[28:29], v[50:51] op_sel_hi:[1,0]
	ds_read_b128 v[28:31], v51 offset:7168
	ds_read_b128 v[32:35], v51 offset:48128
	v_cvt_f32_f16_sdwa v41, v24 dst_sel:DWORD dst_unused:UNUSED_PAD src0_sel:WORD_1
	v_cvt_f32_f16_e32 v40, v24
	s_waitcnt vmcnt(61)
	v_cvt_f32_f16_sdwa v39, v23 dst_sel:DWORD dst_unused:UNUSED_PAD src0_sel:WORD_1
	v_cvt_f32_f16_e32 v38, v23
	s_waitcnt lgkmcnt(0)
	v_pk_fma_f32 v[30:31], v[36:37], v[30:31], v[34:35]
	v_cvt_f32_f16_sdwa v37, v22 dst_sel:DWORD dst_unused:UNUSED_PAD src0_sel:WORD_1
	v_cvt_f32_f16_e32 v36, v22
	v_pk_fma_f32 v[4:5], v[4:5], v[28:29], v[32:33]
	v_mov_b32_e32 v22, v41
	v_cvt_pk_bf16_f32 v4, v4, v5
	v_cvt_pk_bf16_f32 v5, v30, v31
	global_store_dwordx2 v[26:27], v[4:5], off offset:3584
	v_mov_b32_e32 v23, v37
	s_waitcnt vmcnt(61)
	v_cvt_f32_f16_sdwa v27, v20 dst_sel:DWORD dst_unused:UNUSED_PAD src0_sel:WORD_1
	v_cvt_f32_f16_sdwa v29, v21 dst_sel:DWORD dst_unused:UNUSED_PAD src0_sel:WORD_1
	v_mov_b32_e32 v4, v40
	v_mov_b32_e32 v5, v36
	v_pk_mul_f32 v[22:23], v[22:23], v[22:23]
	v_mov_b32_e32 v24, v43
	v_mov_b32_e32 v25, v39
	v_cvt_f32_f16_e32 v26, v20
	v_cvt_f32_f16_e32 v28, v21
	s_waitcnt vmcnt(60)
	v_cvt_f32_f16_sdwa v31, v18 dst_sel:DWORD dst_unused:UNUSED_PAD src0_sel:WORD_1
	v_pk_fma_f32 v[4:5], v[4:5], v[4:5], v[22:23]
	v_mov_b32_e32 v22, v42
	v_mov_b32_e32 v23, v38
	v_pk_mul_f32 v[24:25], v[24:25], v[24:25]
	v_cvt_f32_f16_e32 v30, v18
	v_cvt_f32_f16_sdwa v33, v19 dst_sel:DWORD dst_unused:UNUSED_PAD src0_sel:WORD_1
	v_pk_fma_f32 v[22:23], v[22:23], v[22:23], v[24:25]
	v_cvt_f32_f16_e32 v32, v19
	v_pk_add_f32 v[4:5], v[4:5], v[22:23]
	v_mov_b32_e32 v22, v27
	v_mov_b32_e32 v23, v29
	v_mov_b32_e32 v20, v26
	v_mov_b32_e32 v21, v28
	v_pk_mul_f32 v[22:23], v[22:23], v[22:23]
	v_mul_f32_e32 v18, v31, v31
	v_pk_fma_f32 v[20:21], v[20:21], v[20:21], v[22:23]
	v_pk_fma_f32 v[24:25], v[30:31], v[30:31], v[18:19] op_sel_hi:[1,1,0]
	v_mul_f32_e32 v18, v33, v33
	v_pk_add_f32 v[22:23], v[20:21], v[20:21] op_sel:[0,1] op_sel_hi:[1,0]
	v_pk_fma_f32 v[34:35], v[32:33], v[32:33], v[18:19] op_sel_hi:[1,1,0]
	s_waitcnt vmcnt(59)
	v_cvt_f32_f16_sdwa v19, v16 dst_sel:DWORD dst_unused:UNUSED_PAD src0_sel:WORD_1
	v_cvt_f32_f16_e32 v18, v16
	v_cvt_f32_f16_sdwa v21, v17 dst_sel:DWORD dst_unused:UNUSED_PAD src0_sel:WORD_1
	v_cvt_f32_f16_e32 v20, v17
	v_pk_add_f32 v[4:5], v[4:5], v[4:5] op_sel:[0,1] op_sel_hi:[1,0]
	v_pk_mul_f32 v[16:17], v[18:19], v[18:19]
	v_pk_mul_f32 v[44:45], v[20:21], v[20:21]
	v_mov_b32_e32 v5, v16
	v_mov_b32_e32 v23, v17
	v_mov_b32_e32 v25, v44
	v_mov_b32_e32 v35, v45
	v_pk_add_f32 v[4:5], v[4:5], v[22:23]
	v_pk_add_f32 v[16:17], v[24:25], v[34:35]
	s_waitcnt vmcnt(58)
	v_cvt_f32_f16_sdwa v23, v14 dst_sel:DWORD dst_unused:UNUSED_PAD src0_sel:WORD_1
	v_cvt_f32_f16_sdwa v25, v15 dst_sel:DWORD dst_unused:UNUSED_PAD src0_sel:WORD_1
	v_cvt_f32_f16_e32 v22, v14
	v_cvt_f32_f16_e32 v24, v15
	v_pk_add_f32 v[4:5], v[4:5], v[16:17]
	v_mov_b32_e32 v14, v23
	v_mov_b32_e32 v15, v25
	v_pk_add_f32 v[34:35], v[4:5], v[4:5] op_sel:[0,1] op_sel_hi:[1,0]
	v_mov_b32_e32 v4, v22
	v_mov_b32_e32 v5, v24
	v_pk_mul_f32 v[14:15], v[14:15], v[14:15]
	s_waitcnt vmcnt(56)
	v_cvt_f32_f16_sdwa v17, v11 dst_sel:DWORD dst_unused:UNUSED_PAD src0_sel:WORD_1
	v_pk_fma_f32 v[4:5], v[4:5], v[4:5], v[14:15]
	v_cvt_f32_f16_sdwa v15, v13 dst_sel:DWORD dst_unused:UNUSED_PAD src0_sel:WORD_1
	v_pk_add_f32 v[44:45], v[4:5], v[4:5] op_sel:[0,1] op_sel_hi:[1,0]
	v_cvt_f32_f16_sdwa v5, v12 dst_sel:DWORD dst_unused:UNUSED_PAD src0_sel:WORD_1
	v_cvt_f32_f16_e32 v4, v12
	v_cvt_f32_f16_e32 v14, v13
	v_cvt_f32_f16_e32 v16, v11
	v_mul_f32_e32 v12, v5, v5
	v_pk_fma_f32 v[46:47], v[4:5], v[4:5], v[12:13] op_sel_hi:[1,1,0]
	v_mul_f32_e32 v12, v15, v15
	v_pk_fma_f32 v[48:49], v[14:15], v[14:15], v[12:13] op_sel_hi:[1,1,0]
	v_cvt_f32_f16_sdwa v13, v10 dst_sel:DWORD dst_unused:UNUSED_PAD src0_sel:WORD_1
	v_cvt_f32_f16_e32 v12, v10
	v_pk_mul_f32 v[50:51], v[16:17], v[16:17]
	v_pk_mul_f32 v[10:11], v[12:13], v[12:13]
	s_nop 0
	v_mov_b32_e32 v35, v10
	v_mov_b32_e32 v45, v11
	v_mov_b32_e32 v47, v50
	v_mov_b32_e32 v49, v51
	v_pk_add_f32 v[10:11], v[34:35], v[44:45]
	v_pk_add_f32 v[34:35], v[46:47], v[48:49]
	s_nop 0
	v_pk_add_f32 v[10:11], v[10:11], v[34:35]
	s_nop 0
	v_add_f32_e32 v10, v10, v11
	s_nop 1
	v_add_f32_dpp v10, v10, v10 quad_perm:[1,0,3,2] row_mask:0xf bank_mask:0xf bound_ctrl:1
	s_nop 1
	v_add_f32_dpp v10, v10, v10 quad_perm:[2,3,0,1] row_mask:0xf bank_mask:0xf bound_ctrl:1
	s_nop 1
	v_add_f32_dpp v10, v10, v10 row_half_mirror row_mask:0xf bank_mask:0xf bound_ctrl:1
	s_nop 1
	v_add_f32_dpp v10, v10, v10 row_mirror row_mask:0xf bank_mask:0xf bound_ctrl:1
	s_nop 0
	v_readlane_b32 s5, v10, 16
	v_readlane_b32 s11, v10, 48
	v_readlane_b32 s6, v10, 0
	v_readlane_b32 s7, v10, 32
	v_mov_b32_e32 v10, s5
	v_mov_b32_e32 v11, s11
	v_pk_add_f32 v[10:11], s[6:7], v[10:11]
	s_lshl_b32 s5, s10, 1
	v_add_f32_e32 v10, v10, v11
	v_fmamk_f32 v10, v10, 0x3a000000, v252
	v_cmp_gt_f32_e32 vcc, s55, v10
	v_mul_f32_e32 v11, 0x4f800000, v10
	s_and_b32 s5, s5, 0xffffe000
	v_cndmask_b32_e32 v10, v10, v11, vcc
	v_sqrt_f32_e32 v11, v10
	s_add_i32 s5, s5, 0
	s_cmpk_lt_i32 s4, 0x400
	v_add_u32_e32 v34, -1, v11
	v_fma_f32 v35, -v34, v11, v10
	v_cmp_ge_f32_e64 s[6:7], 0, v35
	v_add_u32_e32 v35, 1, v11
	s_nop 0
	v_cndmask_b32_e64 v34, v11, v34, s[6:7]
	v_fma_f32 v11, -v35, v11, v10
	v_cmp_lt_f32_e64 s[6:7], 0, v11
	s_nop 1
	v_cndmask_b32_e64 v11, v34, v35, s[6:7]
	v_mul_f32_e32 v34, 0x37800000, v11
	v_cndmask_b32_e32 v11, v11, v34, vcc
	v_cmp_class_f32_e32 vcc, v10, v253
	s_nop 1
	v_cndmask_b32_e32 v10, v11, v10, vcc
	v_div_scale_f32 v11, s[6:7], v10, v10, 1.0
	v_rcp_f32_e32 v34, v11
	s_nop 0
	v_fma_f32 v35, -v11, v34, 1.0
	v_fmac_f32_e32 v34, v35, v34
	v_div_scale_f32 v35, vcc, 1.0, v10, 1.0
	v_mul_f32_e32 v44, v35, v34
	v_fma_f32 v45, -v11, v44, v35
	v_fmac_f32_e32 v44, v45, v34
	v_fma_f32 v11, -v11, v44, v35
	v_div_fmas_f32 v11, v11, v34, v44
	v_div_fixup_f32 v34, v11, v10, 1.0
	v_pk_mul_f32 v[48:49], v[40:41], v[34:35] op_sel_hi:[1,0]
	v_pk_mul_f32 v[50:51], v[42:43], v[34:35] op_sel_hi:[1,0]
	v_add_u32_e32 v35, s5, v0
	ds_read_b128 v[40:43], v35
	ds_read_b128 v[44:47], v35 offset:40960
	v_lshl_add_u64 v[10:11], s[12:13], 1, v[2:3]
	v_lshl_add_u64 v[10:11], v[10:11], 0, v[6:7]
	v_pk_mul_f32 v[4:5], v[4:5], v[34:35] op_sel_hi:[1,0]
	v_pk_mul_f32 v[14:15], v[14:15], v[34:35] op_sel_hi:[1,0]
	s_waitcnt lgkmcnt(0)
; #define GAS __attribute__((address_space(1)))
; __device__ __forceinline__ void norm_mod_phase2(const Args& a, Frame& F, const float* gain, const float* modl, int sh_off, int sc_off, int nrows, const float* slab_gate) {
;     ...
;     if (ML + nw < nrows) {
;         const int r = ML + nw, rc = nw;
;         const GAS v2u* xr = (const GAS v2u*)(X + (size_t)r * D) + F.lane;
; #pragma unroll
;         for (int j = 0; j < 8; ++j) r0[j] = xr[64 * j];
;         if (slab_gate != nullptr) { const GAS f32x4* sl = (const GAS f32x4*)((const float*)(a.ws + WS_SLAB) + (size_t)rc * D) + F.lane;
; #pragma unroll
;             for (int j = 0; j < 8; ++j) { const f32x4 p = (sl[64 * j] + sl[64 * j + (size_t)MC * D / 4]) + (sl[64 * j + 2 * ((size_t)MC * D / 4)] + sl[64 * j + 3 * ((size_t)MC * D / 4)]);
	v_pk_fma_f32 v[42:43], v[42:43], v[50:51], v[46:47]
	v_pk_fma_f32 v[40:41], v[40:41], v[48:49], v[44:45]
	v_pk_mul_f32 v[44:45], v[36:37], v[34:35] op_sel_hi:[1,0]
	v_cvt_pk_bf16_f32 v40, v40, v41
	v_cvt_pk_bf16_f32 v41, v42, v43
	global_store_dwordx2 v[10:11], v[40:41], off
	v_pk_mul_f32 v[46:47], v[38:39], v[34:35] op_sel_hi:[1,0]
	ds_read_b128 v[36:39], v35 offset:1024
	ds_read_b128 v[40:43], v35 offset:41984
	s_waitcnt lgkmcnt(0)
	v_pk_fma_f32 v[38:39], v[38:39], v[46:47], v[42:43]
	v_pk_fma_f32 v[36:37], v[36:37], v[44:45], v[40:41]
	v_pk_mul_f32 v[40:41], v[26:27], v[34:35] op_sel_hi:[1,0]
	v_cvt_pk_bf16_f32 v36, v36, v37
	v_cvt_pk_bf16_f32 v37, v38, v39
	global_store_dwordx2 v[10:11], v[36:37], off offset:512
	v_pk_mul_f32 v[42:43], v[28:29], v[34:35] op_sel_hi:[1,0]
	ds_read_b128 v[26:29], v35 offset:2048
	ds_read_b128 v[36:39], v35 offset:43008
	s_waitcnt lgkmcnt(0)
	v_pk_fma_f32 v[28:29], v[28:29], v[42:43], v[38:39]
	v_pk_fma_f32 v[26:27], v[26:27], v[40:41], v[36:37]
	v_pk_mul_f32 v[36:37], v[30:31], v[34:35] op_sel_hi:[1,0]
	v_cvt_pk_bf16_f32 v26, v26, v27
	v_cvt_pk_bf16_f32 v27, v28, v29
	global_store_dwordx2 v[10:11], v[26:27], off offset:1024
	v_pk_mul_f32 v[38:39], v[32:33], v[34:35] op_sel_hi:[1,0]
	ds_read_b128 v[26:29], v35 offset:3072
	ds_read_b128 v[30:33], v35 offset:44032
	s_waitcnt lgkmcnt(0)
	v_pk_fma_f32 v[28:29], v[38:39], v[28:29], v[32:33]
	v_pk_fma_f32 v[26:27], v[36:37], v[26:27], v[30:31]
	v_pk_mul_f32 v[30:31], v[18:19], v[34:35] op_sel_hi:[1,0]
	v_cvt_pk_bf16_f32 v26, v26, v27
	v_cvt_pk_bf16_f32 v27, v28, v29
	global_store_dwordx2 v[10:11], v[26:27], off offset:1536
	v_pk_mul_f32 v[32:33], v[20:21], v[34:35] op_sel_hi:[1,0]
	ds_read_b128 v[18:21], v35 offset:4096
	ds_read_b128 v[26:29], v35 offset:45056
	s_waitcnt lgkmcnt(0)
	v_pk_fma_f32 v[20:21], v[32:33], v[20:21], v[28:29]
	v_pk_fma_f32 v[18:19], v[30:31], v[18:19], v[26:27]
	v_pk_mul_f32 v[26:27], v[22:23], v[34:35] op_sel_hi:[1,0]
	v_cvt_pk_bf16_f32 v18, v18, v19
	v_cvt_pk_bf16_f32 v19, v20, v21
	global_store_dwordx2 v[10:11], v[18:19], off offset:2048
	v_pk_mul_f32 v[28:29], v[24:25], v[34:35] op_sel_hi:[1,0]
	ds_read_b128 v[18:21], v35 offset:5120
	ds_read_b128 v[22:25], v35 offset:46080
	s_waitcnt lgkmcnt(0)
	v_pk_fma_f32 v[20:21], v[28:29], v[20:21], v[24:25]
	v_pk_fma_f32 v[18:19], v[26:27], v[18:19], v[22:23]
	s_nop 0
	v_cvt_pk_bf16_f32 v18, v18, v19
	v_cvt_pk_bf16_f32 v19, v20, v21
	global_store_dwordx2 v[10:11], v[18:19], off offset:2560
	ds_read_b128 v[18:21], v35 offset:6144
	ds_read_b128 v[22:25], v35 offset:47104
	s_waitcnt lgkmcnt(0)
	v_pk_fma_f32 v[14:15], v[14:15], v[20:21], v[24:25]
	v_pk_fma_f32 v[4:5], v[4:5], v[18:19], v[22:23]
	v_pk_mul_f32 v[20:21], v[16:17], v[34:35] op_sel_hi:[1,0]
	v_cvt_pk_bf16_f32 v4, v4, v5
	v_cvt_pk_bf16_f32 v5, v14, v15
	global_store_dwordx2 v[10:11], v[4:5], off offset:3072
	v_pk_mul_f32 v[4:5], v[12:13], v[34:35] op_sel_hi:[1,0]
	ds_read_b128 v[12:15], v35 offset:7168
	ds_read_b128 v[16:19], v35 offset:48128
	s_waitcnt lgkmcnt(0)
	v_pk_fma_f32 v[14:15], v[20:21], v[14:15], v[18:19]
	v_pk_fma_f32 v[4:5], v[4:5], v[12:13], v[16:17]
	s_nop 0
	v_cvt_pk_bf16_f32 v4, v4, v5
	v_cvt_pk_bf16_f32 v5, v14, v15
	global_store_dwordx2 v[10:11], v[4:5], off offset:3584
	s_cbranch_scc0 .LBB0_223
	s_addk_i32 s4, 0x4000
	s_ashr_i32 s5, s4, 31
	s_lshl_b64 s[6:7], s[4:5], 12
	v_lshl_add_u64 v[4:5], v[8:9], 0, s[6:7]
	v_lshl_add_u64 v[18:19], v[4:5], 0, v[6:7]
	global_load_dwordx2 v[22:23], v[18:19], off
	global_load_dwordx2 v[20:21], v[18:19], off offset:512
	global_load_dwordx2 v[16:17], v[18:19], off offset:1024
	global_load_dwordx2 v[12:13], v[18:19], off offset:1536
	global_load_dwordx2 v[14:15], v[18:19], off offset:2048
	global_load_dwordx2 v[10:11], v[18:19], off offset:2560
	global_load_dwordx2 v[8:9], v[18:19], off offset:3072
	global_load_dwordx2 v[4:5], v[18:19], off offset:3584
	v_lshlrev_b32_e32 v40, 2, v143
	s_cmp_eq_u32 s76, 0
	s_cbranch_scc1 .LBB0_222
	v_mov_b32_e32 v24, s72
	v_mov_b32_e32 v25, s73
	v_lshl_add_u64 v[24:25], s[8:9], 2, v[24:25]
	v_lshl_add_u64 v[24:25], v[24:25], 0, v[0:1]
	v_lshlrev_b32_e32 v0, 2, v40
	v_lshl_add_u64 v[26:27], s[86:87], 0, v[0:1]
	v_add_co_u32_e32 v28, vcc, 0x58400000, v24
	s_nop 1
	v_addc_co_u32_e32 v29, vcc, 0, v25, vcc
	v_add_co_u32_e32 v30, vcc, 0x58c00000, v24
	s_nop 1
	v_addc_co_u32_e32 v31, vcc, 0, v25, vcc
	v_add_co_u32_e32 v32, vcc, 0x59400000, v24
	s_nop 1
	v_addc_co_u32_e32 v33, vcc, 0, v25, vcc
	v_add_co_u32_e32 v34, vcc, 0x59c00000, v24
	s_nop 1
	v_addc_co_u32_e32 v35, vcc, 0, v25, vcc
	v_add_co_u32_e32 v36, vcc, 0x58401000, v24
	s_nop 1
	v_addc_co_u32_e32 v37, vcc, 0, v25, vcc
	v_add_co_u32_e32 v38, vcc, 0x58c01000, v24
	s_nop 1
	v_addc_co_u32_e32 v39, vcc, 0, v25, vcc
	v_add_co_u32_e32 v42, vcc, 0x59401000, v24
	s_nop 1
	v_addc_co_u32_e32 v43, vcc, 0, v25, vcc
	v_add_co_u32_e32 v44, vcc, 0x59c01000, v24
	s_nop 1
	v_addc_co_u32_e32 v45, vcc, 0, v25, vcc
	v_add_co_u32_e32 v48, vcc, 0xffffe000, v26
	s_nop 1
	v_addc_co_u32_e32 v49, vcc, -1, v27, vcc
	v_add_co_u32_e32 v50, vcc, 0xfffff000, v26
	s_nop 1
	v_addc_co_u32_e32 v51, vcc, -1, v27, vcc
	global_load_dwordx4 v[94:97], v[28:29], off
	global_load_dwordx4 v[98:101], v[30:31], off
	global_load_dwordx4 v[102:105], v[32:33], off
	global_load_dwordx4 v[106:109], v[34:35], off
	global_load_dwordx4 v[110:113], v[48:49], off
	global_load_dwordx4 v[114:117], v[28:29], off offset:1024
	global_load_dwordx4 v[118:121], v[30:31], off offset:1024
	global_load_dwordx4 v[122:125], v[32:33], off offset:1024
	global_load_dwordx4 v[126:129], v[34:35], off offset:1024
	global_load_dwordx4 v[130:133], v[48:49], off offset:1024
	global_load_dwordx4 v[134:137], v[28:29], off offset:2048
	global_load_dwordx4 v[138:141], v[30:31], off offset:2048
	global_load_dwordx4 v[142:145], v[32:33], off offset:2048
	global_load_dwordx4 v[146:149], v[34:35], off offset:2048
	global_load_dwordx4 v[150:153], v[48:49], off offset:2048
	global_load_dwordx4 v[154:157], v[28:29], off offset:3072
	global_load_dwordx4 v[158:161], v[30:31], off offset:3072
	global_load_dwordx4 v[162:165], v[32:33], off offset:3072
	global_load_dwordx4 v[170:173], v[34:35], off offset:3072
	global_load_dwordx4 v[174:177], v[48:49], off offset:3072
	s_waitcnt vmcnt(15)
; #define GAS __attribute__((address_space(1)))
; __device__ __forceinline__ unsigned xpk2(float lo, float hi) { if (XRES_F16) { const f32x2_t v = {lo, hi}; const f16x2_t h = __builtin_convertvector(v, f16x2_t); return __builtin_bit_cast(unsigned, h); } return pk2(lo, hi); }
; __device__ __forceinline__ float xlo(unsigned w) { if (XRES_F16) { const f16x2_t h = __builtin_bit_cast(f16x2_t, w); return (float)h[0]; } return __builtin_bit_cast(float, w << 16); }
; __device__ __forceinline__ float xhi(unsigned w) { if (XRES_F16) { const f16x2_t h = __builtin_bit_cast(f16x2_t, w); return (float)h[1]; } return __builtin_bit_cast(float, w & 0xffff0000u); }
; __device__ __forceinline__ void norm_mod_phase2(const Args& a, Frame& F, const float* gain, const float* modl, int sh_off, int sc_off, int nrows, const float* slab_gate) {
;     ...
;         if (slab_gate != nullptr) { const GAS f32x4* sl = (const GAS f32x4*)((const float*)(a.ws + WS_SLAB) + (size_t)rc * D) + F.lane;
; #pragma unroll
;             for (int j = 0; j < 8; ++j) { const f32x4 p = (sl[64 * j] + sl[64 * j + (size_t)MC * D / 4]) + (sl[64 * j + 2 * ((size_t)MC * D / 4)] + sl[64 * j + 3 * ((size_t)MC * D / 4)]);
;                 const f32x4 x = (f32x4){xlo(r0[j].x), xhi(r0[j].x), xlo(r0[j].y), xhi(r0[j].y)} + *(const GAS f32x4*)(slab_gate + 256 * j + 4 * F.lane) * p;
;                 v2u w; w.x = xpk2(x[0], x[1]); w.y = xpk2(x[2], x[3]); ((GAS v2u*)(X + (size_t)r * D) + F.lane)[64 * j] = w; r0[j] = w; } }
	v_pk_add_f32 v[220:221], v[94:95], v[98:99]
	v_pk_add_f32 v[222:223], v[96:97], v[100:101]
	v_pk_add_f32 v[224:225], v[102:103], v[106:107]
	v_pk_add_f32 v[226:227], v[104:105], v[108:109]
	v_cvt_f32_f16_e32 v232, v22
	v_cvt_f32_f16_sdwa v233, v22 dst_sel:DWORD dst_unused:UNUSED_PAD src0_sel:WORD_1
	v_cvt_f32_f16_e32 v234, v23
	v_cvt_f32_f16_sdwa v235, v23 dst_sel:DWORD dst_unused:UNUSED_PAD src0_sel:WORD_1
	v_pk_add_f32 v[228:229], v[220:221], v[224:225]
	v_pk_add_f32 v[230:231], v[222:223], v[226:227]
	s_nop 1
	v_pk_fma_f32 v[236:237], v[110:111], v[228:229], v[232:233]
	v_pk_fma_f32 v[238:239], v[112:113], v[230:231], v[234:235]
	s_nop 1
	v_cvt_pk_f16_f32 v22, v236, v237
	v_cvt_pk_f16_f32 v23, v238, v239
	global_store_dwordx2 v[18:19], v[22:23], off
	global_load_dwordx4 v[94:97], v[36:37], off
	global_load_dwordx4 v[98:101], v[38:39], off
	global_load_dwordx4 v[102:105], v[42:43], off
	global_load_dwordx4 v[106:109], v[44:45], off
	global_load_dwordx4 v[110:113], v[50:51], off
	s_waitcnt vmcnt(16)
	v_pk_add_f32 v[220:221], v[114:115], v[118:119]
	v_pk_add_f32 v[222:223], v[116:117], v[120:121]
	v_pk_add_f32 v[224:225], v[122:123], v[126:127]
	v_pk_add_f32 v[226:227], v[124:125], v[128:129]
	v_cvt_f32_f16_e32 v232, v20
	v_cvt_f32_f16_sdwa v233, v20 dst_sel:DWORD dst_unused:UNUSED_PAD src0_sel:WORD_1
	v_cvt_f32_f16_e32 v234, v21
	v_cvt_f32_f16_sdwa v235, v21 dst_sel:DWORD dst_unused:UNUSED_PAD src0_sel:WORD_1
	v_pk_add_f32 v[228:229], v[220:221], v[224:225]
	v_pk_add_f32 v[230:231], v[222:223], v[226:227]
	s_nop 1
	v_pk_fma_f32 v[236:237], v[130:131], v[228:229], v[232:233]
	v_pk_fma_f32 v[238:239], v[132:133], v[230:231], v[234:235]
	s_nop 1
	v_cvt_pk_f16_f32 v20, v236, v237
	v_cvt_pk_f16_f32 v21, v238, v239
	global_store_dwordx2 v[18:19], v[20:21], off offset:512
	global_load_dwordx4 v[114:117], v[36:37], off offset:1024
	global_load_dwordx4 v[118:121], v[38:39], off offset:1024
	global_load_dwordx4 v[122:125], v[42:43], off offset:1024
	global_load_dwordx4 v[126:129], v[44:45], off offset:1024
	global_load_dwordx4 v[130:133], v[50:51], off offset:1024
	s_waitcnt vmcnt(17)
	v_pk_add_f32 v[220:221], v[134:135], v[138:139]
	v_pk_add_f32 v[222:223], v[136:137], v[140:141]
	v_pk_add_f32 v[224:225], v[142:143], v[146:147]
	v_pk_add_f32 v[226:227], v[144:145], v[148:149]
	v_cvt_f32_f16_e32 v232, v16
	v_cvt_f32_f16_sdwa v233, v16 dst_sel:DWORD dst_unused:UNUSED_PAD src0_sel:WORD_1
	v_cvt_f32_f16_e32 v234, v17
	v_cvt_f32_f16_sdwa v235, v17 dst_sel:DWORD dst_unused:UNUSED_PAD src0_sel:WORD_1
	v_pk_add_f32 v[228:229], v[220:221], v[224:225]
	v_pk_add_f32 v[230:231], v[222:223], v[226:227]
	s_nop 1
	v_pk_fma_f32 v[236:237], v[150:151], v[228:229], v[232:233]
	v_pk_fma_f32 v[238:239], v[152:153], v[230:231], v[234:235]
	s_nop 1
	v_cvt_pk_f16_f32 v16, v236, v237
	v_cvt_pk_f16_f32 v17, v238, v239
	global_store_dwordx2 v[18:19], v[16:17], off offset:1024
	global_load_dwordx4 v[134:137], v[36:37], off offset:2048
	global_load_dwordx4 v[138:141], v[38:39], off offset:2048
	global_load_dwordx4 v[142:145], v[42:43], off offset:2048
	global_load_dwordx4 v[146:149], v[44:45], off offset:2048
	global_load_dwordx4 v[150:153], v[50:51], off offset:2048
	s_waitcnt vmcnt(18)
; #define GAS __attribute__((address_space(1)))
; __device__ __forceinline__ unsigned xpk2(float lo, float hi) { if (XRES_F16) { const f32x2_t v = {lo, hi}; const f16x2_t h = __builtin_convertvector(v, f16x2_t); return __builtin_bit_cast(unsigned, h); } return pk2(lo, hi); }
; __device__ __forceinline__ float xlo(unsigned w) { if (XRES_F16) { const f16x2_t h = __builtin_bit_cast(f16x2_t, w); return (float)h[0]; } return __builtin_bit_cast(float, w << 16); }
; __device__ __forceinline__ float xhi(unsigned w) { if (XRES_F16) { const f16x2_t h = __builtin_bit_cast(f16x2_t, w); return (float)h[1]; } return __builtin_bit_cast(float, w & 0xffff0000u); }
; __device__ __forceinline__ void norm_mod_phase2(const Args& a, Frame& F, const float* gain, const float* modl, int sh_off, int sc_off, int nrows, const float* slab_gate) {
;     ...
;         if (slab_gate != nullptr) { const GAS f32x4* sl = (const GAS f32x4*)((const float*)(a.ws + WS_SLAB) + (size_t)rc * D) + F.lane;
; #pragma unroll
;             for (int j = 0; j < 8; ++j) { const f32x4 p = (sl[64 * j] + sl[64 * j + (size_t)MC * D / 4]) + (sl[64 * j + 2 * ((size_t)MC * D / 4)] + sl[64 * j + 3 * ((size_t)MC * D / 4)]);
;                 const f32x4 x = (f32x4){xlo(r0[j].x), xhi(r0[j].x), xlo(r0[j].y), xhi(r0[j].y)} + *(const GAS f32x4*)(slab_gate + 256 * j + 4 * F.lane) * p;
;                 v2u w; w.x = xpk2(x[0], x[1]); w.y = xpk2(x[2], x[3]); ((GAS v2u*)(X + (size_t)r * D) + F.lane)[64 * j] = w; r0[j] = w; } }
	v_pk_add_f32 v[220:221], v[154:155], v[158:159]
	v_pk_add_f32 v[222:223], v[156:157], v[160:161]
	v_pk_add_f32 v[224:225], v[162:163], v[170:171]
	v_pk_add_f32 v[226:227], v[164:165], v[172:173]
	v_cvt_f32_f16_e32 v232, v12
	v_cvt_f32_f16_sdwa v233, v12 dst_sel:DWORD dst_unused:UNUSED_PAD src0_sel:WORD_1
	v_cvt_f32_f16_e32 v234, v13
	v_cvt_f32_f16_sdwa v235, v13 dst_sel:DWORD dst_unused:UNUSED_PAD src0_sel:WORD_1
	v_pk_add_f32 v[228:229], v[220:221], v[224:225]
	v_pk_add_f32 v[230:231], v[222:223], v[226:227]
	s_nop 1
	v_pk_fma_f32 v[236:237], v[174:175], v[228:229], v[232:233]
	v_pk_fma_f32 v[238:239], v[176:177], v[230:231], v[234:235]
	s_nop 1
	v_cvt_pk_f16_f32 v12, v236, v237
	v_cvt_pk_f16_f32 v13, v238, v239
	global_store_dwordx2 v[18:19], v[12:13], off offset:1536
	global_load_dwordx4 v[154:157], v[36:37], off offset:3072
	global_load_dwordx4 v[158:161], v[38:39], off offset:3072
	global_load_dwordx4 v[162:165], v[42:43], off offset:3072
	global_load_dwordx4 v[170:173], v[44:45], off offset:3072
	global_load_dwordx4 v[174:177], v[50:51], off offset:3072
	s_waitcnt vmcnt(18)
	v_pk_add_f32 v[220:221], v[94:95], v[98:99]
	v_pk_add_f32 v[222:223], v[96:97], v[100:101]
	v_pk_add_f32 v[224:225], v[102:103], v[106:107]
	v_pk_add_f32 v[226:227], v[104:105], v[108:109]
	v_cvt_f32_f16_e32 v232, v14
	v_cvt_f32_f16_sdwa v233, v14 dst_sel:DWORD dst_unused:UNUSED_PAD src0_sel:WORD_1
	v_cvt_f32_f16_e32 v234, v15
	v_cvt_f32_f16_sdwa v235, v15 dst_sel:DWORD dst_unused:UNUSED_PAD src0_sel:WORD_1
	v_pk_add_f32 v[228:229], v[220:221], v[224:225]
	v_pk_add_f32 v[230:231], v[222:223], v[226:227]
	s_nop 1
	v_pk_fma_f32 v[236:237], v[110:111], v[228:229], v[232:233]
	v_pk_fma_f32 v[238:239], v[112:113], v[230:231], v[234:235]
	s_nop 1
	v_cvt_pk_f16_f32 v14, v236, v237
	v_cvt_pk_f16_f32 v15, v238, v239
	global_store_dwordx2 v[18:19], v[14:15], off offset:2048
	s_waitcnt vmcnt(13)
	v_pk_add_f32 v[220:221], v[114:115], v[118:119]
	v_pk_add_f32 v[222:223], v[116:117], v[120:121]
	v_pk_add_f32 v[224:225], v[122:123], v[126:127]
	v_pk_add_f32 v[226:227], v[124:125], v[128:129]
	v_cvt_f32_f16_e32 v232, v10
	v_cvt_f32_f16_sdwa v233, v10 dst_sel:DWORD dst_unused:UNUSED_PAD src0_sel:WORD_1
	v_cvt_f32_f16_e32 v234, v11
	v_cvt_f32_f16_sdwa v235, v11 dst_sel:DWORD dst_unused:UNUSED_PAD src0_sel:WORD_1
	v_pk_add_f32 v[228:229], v[220:221], v[224:225]
	v_pk_add_f32 v[230:231], v[222:223], v[226:227]
	s_nop 1
	v_pk_fma_f32 v[236:237], v[130:131], v[228:229], v[232:233]
	v_pk_fma_f32 v[238:239], v[132:133], v[230:231], v[234:235]
	s_nop 1
	v_cvt_pk_f16_f32 v10, v236, v237
	v_cvt_pk_f16_f32 v11, v238, v239
	global_store_dwordx2 v[18:19], v[10:11], off offset:2560
	s_waitcnt vmcnt(8)
	v_pk_add_f32 v[220:221], v[134:135], v[138:139]
	v_pk_add_f32 v[222:223], v[136:137], v[140:141]
	v_pk_add_f32 v[224:225], v[142:143], v[146:147]
	v_pk_add_f32 v[226:227], v[144:145], v[148:149]
	v_cvt_f32_f16_e32 v232, v8
	v_cvt_f32_f16_sdwa v233, v8 dst_sel:DWORD dst_unused:UNUSED_PAD src0_sel:WORD_1
	v_cvt_f32_f16_e32 v234, v9
	v_cvt_f32_f16_sdwa v235, v9 dst_sel:DWORD dst_unused:UNUSED_PAD src0_sel:WORD_1
	v_pk_add_f32 v[228:229], v[220:221], v[224:225]
	v_pk_add_f32 v[230:231], v[222:223], v[226:227]
	s_nop 1
	v_pk_fma_f32 v[236:237], v[150:151], v[228:229], v[232:233]
	v_pk_fma_f32 v[238:239], v[152:153], v[230:231], v[234:235]
	s_nop 1
	v_cvt_pk_f16_f32 v8, v236, v237
	v_cvt_pk_f16_f32 v9, v238, v239
	global_store_dwordx2 v[18:19], v[8:9], off offset:3072
	s_waitcnt vmcnt(3)
	v_pk_add_f32 v[220:221], v[154:155], v[158:159]
	v_pk_add_f32 v[222:223], v[156:157], v[160:161]
	v_pk_add_f32 v[224:225], v[162:163], v[170:171]
	v_pk_add_f32 v[226:227], v[164:165], v[172:173]
	v_cvt_f32_f16_e32 v232, v4
	v_cvt_f32_f16_sdwa v233, v4 dst_sel:DWORD dst_unused:UNUSED_PAD src0_sel:WORD_1
	v_cvt_f32_f16_e32 v234, v5
	v_cvt_f32_f16_sdwa v235, v5 dst_sel:DWORD dst_unused:UNUSED_PAD src0_sel:WORD_1
	v_pk_add_f32 v[228:229], v[220:221], v[224:225]
	v_pk_add_f32 v[230:231], v[222:223], v[226:227]
	s_nop 1
	v_pk_fma_f32 v[236:237], v[174:175], v[228:229], v[232:233]
	v_pk_fma_f32 v[238:239], v[176:177], v[230:231], v[234:235]
	s_nop 1
	v_cvt_pk_f16_f32 v4, v236, v237
	v_cvt_pk_f16_f32 v5, v238, v239
	global_store_dwordx2 v[18:19], v[4:5], off offset:3584

; #define GAS __attribute__((address_space(1)))
; template <bool HG>
; __device__ __forceinline__ void readout_phase(const Args& a, Frame& F, const float* gain, int nrows) {
;     ...
;     for (int r = gw; r < nrows; r += NGW) {
;         const GAS v2u* f = (const GAS v2u*)(OF + (size_t)r * D) + F.lane; const GAS v2u* bk = (const GAS v2u*)(OB + (size_t)r * D) + F.lane;
;         const GAS v2u* g8 = (const GAS v2u*)(G + (size_t)r * D) + F.lane;
;         f32x4 v[8]; float ssj[8]; float tot = 0.f;
; #pragma unroll
;         for (int j = 0; j < 8; ++j) { const v2u fa = EW_NT ? __builtin_nontemporal_load(f + 64 * j) : f[64 * j], fb = EW_NT ? __builtin_nontemporal_load(bk + 64 * j) : bk[64 * j]; v[j] = (f32x4){bflo(fa.x) + bflo(fb.x), bfhi(fa.x) + bfhi(fb.x), bflo(fa.y) + bflo(fb.y), bfhi(fa.y) + bfhi(fb.y)}; ssj[j] = (v[j][0] * v[j][0] + v[j][1] * v[j][1]) + (v[j][2] * v[j][2] + v[j][3] * v[j][3]); tot += ssj[j]; }
;         float rs_all = 0.f;
;         if (HG) rs_all = 1.0f / sqrtf(wave_sum(tot) * (1.0f / D) + EPS);
.LBB0_574:
	v_lshl_add_u64 v[50:51], v[18:19], 0, v[0:1]
	v_add_co_u32_e32 v2, vcc, 0xf7800000, v50
	v_lshl_add_u64 v[20:21], v[50:51], 0, s[52:53]
	s_nop 0
	v_addc_co_u32_e32 v3, vcc, -1, v51, vcc
	global_load_dwordx2 v[2:3], v[2:3], off
	s_nop 0
	global_load_dwordx2 v[4:5], v[50:51], off
	s_mov_b32 s8, 0xf3400000
	s_mov_b32 s9, -1
	s_add_i32 s6, s6, s42
	v_lshl_add_u64 v[18:19], v[18:19], 0, s[74:75]
	s_cmp_lt_i32 s6, s47
	s_waitcnt vmcnt(1)
	v_lshlrev_b32_e32 v22, 16, v2
	v_and_b32_e32 v23, 0xffff0000, v2
	s_waitcnt vmcnt(0)
	v_lshlrev_b32_e32 v24, 16, v4
	v_and_b32_e32 v25, 0xffff0000, v4
	v_lshlrev_b32_e32 v2, 16, v3
	v_and_b32_e32 v3, 0xffff0000, v3
	v_lshlrev_b32_e32 v4, 16, v5
	v_and_b32_e32 v5, 0xffff0000, v5
	v_pk_add_f32 v[54:55], v[2:3], v[4:5]
	global_load_dwordx2 v[4:5], v[20:21], off offset:512
	global_load_dwordx2 v[26:27], v[50:51], off offset:512
	global_load_dwordx2 v[30:31], v[20:21], off offset:1024
	global_load_dwordx2 v[32:33], v[50:51], off offset:1024
	v_mul_f32_e32 v2, v55, v55
	v_pk_add_f32 v[52:53], v[22:23], v[24:25]
	v_pk_fma_f32 v[24:25], v[54:55], v[54:55], v[2:3] op_sel_hi:[1,1,0]
	v_pk_mul_f32 v[22:23], v[52:53], v[52:53]
	s_waitcnt vmcnt(3)
	v_lshlrev_b32_e32 v2, 16, v4
	v_and_b32_e32 v3, 0xffff0000, v4
	s_waitcnt vmcnt(2)
	v_lshlrev_b32_e32 v28, 16, v26
	v_and_b32_e32 v29, 0xffff0000, v26
	v_pk_add_f32 v[2:3], v[2:3], v[28:29]
	v_lshlrev_b32_e32 v26, 16, v27
	v_mul_f32_e32 v4, v3, v3
	v_pk_fma_f32 v[28:29], v[2:3], v[2:3], v[4:5] op_sel_hi:[1,1,0]
	v_lshlrev_b32_e32 v4, 16, v5
	v_and_b32_e32 v5, 0xffff0000, v5
	v_and_b32_e32 v27, 0xffff0000, v27
	v_pk_add_f32 v[44:45], v[4:5], v[26:27]
	s_waitcnt vmcnt(1)
	v_lshlrev_b32_e32 v34, 16, v30
	v_mul_f32_e32 v4, v45, v45
	v_pk_fma_f32 v[26:27], v[44:45], v[44:45], v[4:5] op_sel_hi:[1,1,0]
	s_waitcnt vmcnt(0)
	v_lshlrev_b32_e32 v4, 16, v32
	v_and_b32_e32 v5, 0xffff0000, v32
	v_and_b32_e32 v35, 0xffff0000, v30
	v_pk_add_f32 v[4:5], v[34:35], v[4:5]
	v_lshlrev_b32_e32 v32, 16, v33
	v_lshlrev_b32_e32 v30, 16, v31
	v_and_b32_e32 v33, 0xffff0000, v33
	v_and_b32_e32 v31, 0xffff0000, v31
	v_pk_add_f32 v[40:41], v[30:31], v[32:33]
	v_pk_mov_b32 v[22:23], v[22:23], v[4:5] op_sel:[1,0]
	v_pk_mul_f32 v[30:31], v[4:5], v[4:5]
	v_pk_mul_f32 v[32:33], v[40:41], v[40:41]
	v_pk_fma_f32 v[34:35], v[52:53], v[52:53], v[22:23]
	v_pk_mul_f32 v[22:23], v[4:5], v[22:23] op_sel_hi:[0,1]
	v_mov_b32_e32 v35, v23
	v_mov_b32_e32 v25, v31
	v_mov_b32_e32 v29, v32
	v_mov_b32_e32 v27, v33
	v_pk_add_f32 v[22:23], v[34:35], v[24:25]
	v_pk_add_f32 v[24:25], v[28:29], v[26:27]
	s_nop 0
	v_pk_add_f32 v[22:23], v[22:23], v[24:25]
	global_load_dwordx2 v[24:25], v[20:21], off offset:1536
	global_load_dwordx2 v[26:27], v[50:51], off offset:1536
	v_pk_add_f32 v[22:23], v[22:23], v[22:23] op_sel:[0,1] op_sel_hi:[1,0]
	s_waitcnt vmcnt(1)
	v_lshlrev_b32_e32 v29, 16, v25
	v_lshlrev_b32_e32 v28, 16, v24
	s_waitcnt vmcnt(0)
	v_lshlrev_b32_e32 v31, 16, v27
	v_lshlrev_b32_e32 v30, 16, v26
	v_and_b32_e32 v25, 0xffff0000, v25
	v_and_b32_e32 v24, 0xffff0000, v24
	v_and_b32_e32 v27, 0xffff0000, v27
	v_and_b32_e32 v26, 0xffff0000, v26
	v_pk_add_f32 v[42:43], v[28:29], v[30:31]
	v_pk_add_f32 v[46:47], v[24:25], v[26:27]
	global_load_dwordx2 v[26:27], v[20:21], off offset:2048
	global_load_dwordx2 v[28:29], v[50:51], off offset:2048
	v_pk_mul_f32 v[24:25], v[46:47], v[46:47]
	s_waitcnt vmcnt(1)
	v_lshlrev_b32_e32 v30, 16, v26
	v_and_b32_e32 v31, 0xffff0000, v26
	s_waitcnt vmcnt(0)
	v_lshlrev_b32_e32 v32, 16, v28
	v_and_b32_e32 v33, 0xffff0000, v28
	v_pk_add_f32 v[38:39], v[30:31], v[32:33]
	v_lshlrev_b32_e32 v28, 16, v29
	v_mul_f32_e32 v26, v39, v39
	v_pk_fma_f32 v[34:35], v[38:39], v[38:39], v[26:27] op_sel_hi:[1,1,0]
	v_lshlrev_b32_e32 v26, 16, v27
	v_and_b32_e32 v27, 0xffff0000, v27
	v_and_b32_e32 v29, 0xffff0000, v29
	v_pk_add_f32 v[48:49], v[26:27], v[28:29]
	v_pk_fma_f32 v[24:25], v[42:43], v[42:43], v[24:25]
	v_mul_f32_e32 v26, v49, v49
	v_pk_fma_f32 v[36:37], v[48:49], v[48:49], v[26:27] op_sel_hi:[1,1,0]
	global_load_dwordx2 v[26:27], v[20:21], off offset:2560
	global_load_dwordx2 v[28:29], v[50:51], off offset:2560
	v_pk_add_f32 v[24:25], v[24:25], v[24:25] op_sel:[0,1] op_sel_hi:[1,0]
	s_waitcnt vmcnt(1)
	v_lshlrev_b32_e32 v32, 16, v26
	s_waitcnt vmcnt(0)
	v_lshlrev_b32_e32 v30, 16, v28
	v_and_b32_e32 v31, 0xffff0000, v28
	v_and_b32_e32 v33, 0xffff0000, v26
	v_lshlrev_b32_e32 v28, 16, v29
	v_lshlrev_b32_e32 v26, 16, v27
	v_and_b32_e32 v29, 0xffff0000, v29
	v_and_b32_e32 v27, 0xffff0000, v27
	v_pk_add_f32 v[30:31], v[32:33], v[30:31]
	v_pk_add_f32 v[32:33], v[26:27], v[28:29]
	global_load_dwordx2 v[28:29], v[20:21], off offset:3072
	global_load_dwordx2 v[60:61], v[50:51], off offset:3072
	s_nop 0
	global_load_dwordx2 v[20:21], v[20:21], off offset:3584
	s_nop 0
	global_load_dwordx2 v[64:65], v[50:51], off offset:3584
	v_pk_mul_f32 v[56:57], v[30:31], v[30:31]
	v_pk_mul_f32 v[58:59], v[32:33], v[32:33]
	v_mov_b32_e32 v66, v56
	v_mov_b32_e32 v68, v57
	s_waitcnt vmcnt(3)
	v_lshlrev_b32_e32 v26, 16, v28
	v_and_b32_e32 v27, 0xffff0000, v28
	s_waitcnt vmcnt(2)
	v_lshlrev_b32_e32 v62, 16, v60
	v_and_b32_e32 v63, 0xffff0000, v60
	v_pk_add_f32 v[26:27], v[26:27], v[62:63]
	s_waitcnt vmcnt(1)
	v_lshlrev_b32_e32 v35, 16, v20
	v_mul_f32_e32 v28, v27, v27
	s_waitcnt vmcnt(0)
; #define GAS __attribute__((address_space(1)))
; template <bool HG>
; __device__ __forceinline__ void readout_phase(const Args& a, Frame& F, const float* gain, int nrows) {
;     ...
;         if (HG) rs_all = 1.0f / sqrtf(wave_sum(tot) * (1.0f / D) + EPS);
;         GAS v2u* o8 = (GAS v2u*)(HN + (size_t)r * D) + F.lane;
; #pragma unroll
;         for (int j = 0; j < 8; ++j) {
;             float rs = rs_all; f32x4 gn = {1.f, 1.f, 1.f, 1.f};
;             if (!HG) rs = 1.0f / sqrtf(wave_sum(ssj[j]) * (1.0f / 256.0f) + EPS);
;             else gn = *(const GAS f32x4*)(gain + 256 * j + 4 * F.lane);
;             const v2u gw2 = EW_NT ? __builtin_nontemporal_load(g8 + 64 * j) : g8[64 * j];
;             const f32x4 gt = {bflo(gw2.x), bfhi(gw2.x), bflo(gw2.y), bfhi(gw2.y)};
;             const f32x4 y = (v[j] * rs) * gn * gt;
	v_lshlrev_b32_e32 v37, 16, v64
	v_pk_fma_f32 v[62:63], v[26:27], v[26:27], v[28:29] op_sel_hi:[1,1,0]
	v_lshlrev_b32_e32 v28, 16, v29
	v_and_b32_e32 v29, 0xffff0000, v29
	v_lshlrev_b32_e32 v60, 16, v61
	v_and_b32_e32 v61, 0xffff0000, v61
	v_and_b32_e32 v67, 0xffff0000, v20
	v_and_b32_e32 v69, 0xffff0000, v64
	v_mov_b32_e32 v23, v35
	v_mov_b32_e32 v25, v37
	v_pk_add_f32 v[28:29], v[28:29], v[60:61]
	v_lshlrev_b32_e32 v64, 16, v65
	v_lshlrev_b32_e32 v20, 16, v21
	v_and_b32_e32 v65, 0xffff0000, v65
	v_and_b32_e32 v21, 0xffff0000, v21
	v_pk_add_f32 v[22:23], v[22:23], v[24:25]
	v_pk_add_f32 v[34:35], v[34:35], v[36:37]
	v_pk_add_f32 v[24:25], v[66:67], v[68:69]
	v_mov_b32_e32 v66, v58
	v_mov_b32_e32 v68, v59
	v_mul_f32_e32 v60, v29, v29
	v_pk_add_f32 v[20:21], v[20:21], v[64:65]
	v_pk_add_f32 v[36:37], v[66:67], v[68:69]
	v_pk_add_f32 v[56:57], v[22:23], v[34:35]
	v_pk_mul_f32 v[34:35], v[22:23], v[34:35]
	v_pk_fma_f32 v[60:61], v[28:29], v[28:29], v[60:61] op_sel_hi:[1,1,0]
	v_pk_mul_f32 v[64:65], v[20:21], v[20:21]
	v_mov_b32_e32 v57, v35
	v_pk_add_f32 v[34:35], v[24:25], v[36:37]
	v_pk_mul_f32 v[36:37], v[24:25], v[36:37]
	v_mov_b32_e32 v63, v64
	v_mov_b32_e32 v35, v37
	v_mov_b32_e32 v61, v65
	v_pk_add_f32 v[34:35], v[56:57], v[34:35]
	v_pk_add_f32 v[36:37], v[62:63], v[60:61]
	s_nop 0
	v_pk_add_f32 v[34:35], v[34:35], v[36:37]
	s_nop 0
	v_add_f32_e32 v22, v34, v35
	v_lshl_add_u64 v[34:35], v[50:51], 0, s[8:9]
	s_nop 0
	v_add_f32_dpp v22, v22, v22 quad_perm:[1,0,3,2] row_mask:0xf bank_mask:0xf bound_ctrl:1
	s_nop 1
	v_add_f32_dpp v22, v22, v22 quad_perm:[2,3,0,1] row_mask:0xf bank_mask:0xf bound_ctrl:1
	s_nop 1
	v_add_f32_dpp v22, v22, v22 row_half_mirror row_mask:0xf bank_mask:0xf bound_ctrl:1
	s_nop 1
	v_add_f32_dpp v22, v22, v22 row_mirror row_mask:0xf bank_mask:0xf bound_ctrl:1
	s_nop 0
	v_readlane_b32 s7, v22, 16
	v_readlane_b32 s10, v22, 48
	v_readlane_b32 s8, v22, 0
	v_readlane_b32 s9, v22, 32
	v_mov_b32_e32 v36, s7
	v_mov_b32_e32 v37, s10
	v_pk_add_f32 v[36:37], s[8:9], v[36:37]
	s_mov_b32 s7, 0xf3400000
	v_add_f32_e32 v22, v36, v37
	v_fmamk_f32 v22, v22, 0x3a000000, v252
	v_cmp_gt_f32_e32 vcc, s55, v22
	v_mul_f32_e32 v24, 0x4f800000, v22
	s_nop 0
	v_cndmask_b32_e32 v22, v22, v24, vcc
	v_sqrt_f32_e32 v24, v22
	s_nop 0
	v_add_u32_e32 v36, -1, v24
	v_fma_f32 v37, -v36, v24, v22
	v_cmp_ge_f32_e64 s[8:9], 0, v37
	v_add_u32_e32 v37, 1, v24
	s_nop 0
	v_cndmask_b32_e64 v36, v24, v36, s[8:9]
	v_fma_f32 v24, -v37, v24, v22
	v_cmp_lt_f32_e64 s[8:9], 0, v24
	s_nop 1
	v_cndmask_b32_e64 v24, v36, v37, s[8:9]
	v_mul_f32_e32 v36, 0x37800000, v24
	v_cndmask_b32_e32 v24, v24, v36, vcc
	v_cmp_class_f32_e32 vcc, v22, v253
	s_nop 1
	v_cndmask_b32_e32 v22, v24, v22, vcc
	v_div_scale_f32 v24, s[8:9], v22, v22, 1.0
	v_rcp_f32_e32 v36, v24
	s_nop 0
	v_fma_f32 v37, -v24, v36, 1.0
	v_fmac_f32_e32 v36, v37, v36
	v_div_scale_f32 v37, vcc, 1.0, v22, 1.0
	v_mul_f32_e32 v56, v37, v36
	v_fma_f32 v57, -v24, v56, v37
	v_fmac_f32_e32 v56, v57, v36
	v_fma_f32 v24, -v24, v56, v37
	v_div_fmas_f32 v24, v24, v36, v56
	v_add_co_u32_e32 v60, vcc, s7, v50
	global_load_dwordx4 v[56:59], v[8:9], off
	s_nop 0
	v_addc_co_u32_e32 v61, vcc, -1, v51, vcc
	global_load_dwordx2 v[60:61], v[60:61], off
	v_div_fixup_f32 v22, v24, v22, 1.0
	v_pk_mul_f32 v[54:55], v[54:55], v[22:23] op_sel_hi:[1,0]
	v_pk_mul_f32 v[52:53], v[52:53], v[22:23] op_sel_hi:[1,0]
	v_lshl_add_u64 v[36:37], v[50:51], 0, s[12:13]
	v_add_co_u32_e32 v50, vcc, s67, v50
	v_pk_mul_f32 v[44:45], v[44:45], v[22:23] op_sel_hi:[1,0]
	s_nop 0
	v_addc_co_u32_e32 v51, vcc, -1, v51, vcc
	v_pk_mul_f32 v[2:3], v[2:3], v[22:23] op_sel_hi:[1,0]
	v_pk_mul_f32 v[40:41], v[40:41], v[22:23] op_sel_hi:[1,0]
	v_pk_mul_f32 v[4:5], v[4:5], v[22:23] op_sel_hi:[1,0]
	v_pk_mul_f32 v[38:39], v[38:39], v[22:23] op_sel_hi:[1,0]
	v_pk_mul_f32 v[32:33], v[32:33], v[22:23] op_sel_hi:[1,0]
	v_pk_mul_f32 v[30:31], v[30:31], v[22:23] op_sel_hi:[1,0]
	v_pk_mul_f32 v[28:29], v[28:29], v[22:23] op_sel_hi:[1,0]
	v_pk_mul_f32 v[26:27], v[26:27], v[22:23] op_sel_hi:[1,0]
	v_mov_b32_e32 v24, v23
	v_pk_mul_f32 v[20:21], v[20:21], v[22:23] op_sel_hi:[1,0]
	s_waitcnt vmcnt(1)
	v_pk_mul_f32 v[52:53], v[56:57], v[52:53]
	v_pk_mul_f32 v[54:55], v[58:59], v[54:55]
	s_waitcnt vmcnt(0)
; #define GAS __attribute__((address_space(1)))
; __device__ __forceinline__ unsigned pk2(float lo, float hi) { const f32x2_t v = {lo, hi}; const bf16x2_t b = __builtin_convertvector(v, bf16x2_t); return __builtin_bit_cast(unsigned, b); }
; template <bool HG>
; __device__ __forceinline__ void readout_phase(const Args& a, Frame& F, const float* gain, int nrows) {
;     ...
; #pragma unroll
;         for (int j = 0; j < 8; ++j) {
;             float rs = rs_all; f32x4 gn = {1.f, 1.f, 1.f, 1.f};
;             if (!HG) rs = 1.0f / sqrtf(wave_sum(ssj[j]) * (1.0f / 256.0f) + EPS);
;             else gn = *(const GAS f32x4*)(gain + 256 * j + 4 * F.lane);
;             const v2u gw2 = EW_NT ? __builtin_nontemporal_load(g8 + 64 * j) : g8[64 * j];
;             const f32x4 gt = {bflo(gw2.x), bfhi(gw2.x), bflo(gw2.y), bfhi(gw2.y)};
;             const f32x4 y = (v[j] * rs) * gn * gt;
;             v2u w; w.x = pk2(y[0], y[1]); w.y = pk2(y[2], y[3]); o8[64 * j] = w; }
	v_lshlrev_b32_e32 v62, 16, v60
	v_and_b32_e32 v63, 0xffff0000, v60
	v_lshlrev_b32_e32 v60, 16, v61
	v_and_b32_e32 v61, 0xffff0000, v61
	v_pk_mul_f32 v[54:55], v[54:55], v[60:61]
	v_pk_mul_f32 v[52:53], v[52:53], v[62:63]
	s_nop 0
	v_cvt_pk_bf16_f32 v52, v52, v53
	v_cvt_pk_bf16_f32 v53, v54, v55
	global_store_dwordx2 v[50:51], v[52:53], off
	global_load_dwordx4 v[50:53], v[8:9], off offset:1024
	s_nop 0
	global_load_dwordx2 v[54:55], v[34:35], off offset:512
	s_waitcnt vmcnt(1)
	v_pk_mul_f32 v[2:3], v[50:51], v[2:3]
	s_waitcnt vmcnt(0)
	v_lshlrev_b32_e32 v56, 16, v54
	v_and_b32_e32 v57, 0xffff0000, v54
	v_lshlrev_b32_e32 v54, 16, v55
	v_and_b32_e32 v55, 0xffff0000, v55
	v_pk_mul_f32 v[44:45], v[52:53], v[44:45]
	v_pk_mul_f32 v[2:3], v[2:3], v[56:57]
	v_pk_mul_f32 v[44:45], v[44:45], v[54:55]
	v_cvt_pk_bf16_f32 v2, v2, v3
	v_cvt_pk_bf16_f32 v3, v44, v45
	global_store_dwordx2 v[36:37], v[2:3], off offset:512
	global_load_dwordx4 v[50:53], v[8:9], off offset:2048
	s_nop 0
	global_load_dwordx2 v[2:3], v[34:35], off offset:1024
	s_waitcnt vmcnt(1)
	v_pk_mul_f32 v[4:5], v[50:51], v[4:5]
	s_waitcnt vmcnt(0)
	v_lshlrev_b32_e32 v44, 16, v2
	v_and_b32_e32 v45, 0xffff0000, v2
	v_lshlrev_b32_e32 v2, 16, v3
	v_and_b32_e32 v3, 0xffff0000, v3
	v_pk_mul_f32 v[40:41], v[52:53], v[40:41]
	v_pk_mul_f32 v[4:5], v[4:5], v[44:45]
	v_pk_mul_f32 v[2:3], v[40:41], v[2:3]
	v_cvt_pk_bf16_f32 v4, v4, v5
	v_cvt_pk_bf16_f32 v5, v2, v3
	global_store_dwordx2 v[36:37], v[4:5], off offset:1024
	global_load_dwordx4 v[2:5], v[8:9], off offset:3072
	s_nop 0
	global_load_dwordx2 v[40:41], v[34:35], off offset:1536
	v_mov_b32_e32 v50, v43
	v_mov_b32_e32 v51, v47
	v_mov_b32_e32 v43, v46
	v_pk_mul_f32 v[50:51], v[50:51], v[22:23] op_sel_hi:[1,0]
	v_pk_mul_f32 v[42:43], v[42:43], v[22:23] op_sel_hi:[1,0]
	s_waitcnt vmcnt(1)
	v_pk_mul_f32 v[4:5], v[50:51], v[4:5]
	s_waitcnt vmcnt(0)
	v_lshlrev_b32_e32 v44, 16, v40
	v_and_b32_e32 v45, 0xffff0000, v40
	v_lshlrev_b32_e32 v40, 16, v41
	v_and_b32_e32 v41, 0xffff0000, v41
	v_pk_mul_f32 v[2:3], v[42:43], v[2:3]
	v_pk_mul_f32 v[4:5], v[4:5], v[40:41]
	v_pk_mul_f32 v[2:3], v[2:3], v[44:45]
	v_pk_mul_f32 v[44:45], v[48:49], v[22:23] op_sel_hi:[1,0]
	v_cvt_pk_bf16_f32 v2, v2, v3
	v_cvt_pk_bf16_f32 v3, v4, v5
	global_store_dwordx2 v[36:37], v[2:3], off offset:1536
	global_load_dwordx4 v[2:5], v[10:11], off
	s_nop 0
	global_load_dwordx2 v[40:41], v[34:35], off offset:2048
	v_pk_mul_f32 v[22:23], v[24:25], v[22:23] op_sel_hi:[1,0]
	s_waitcnt vmcnt(1)
	v_pk_mul_f32 v[2:3], v[38:39], v[2:3]
	s_waitcnt vmcnt(0)
	v_lshlrev_b32_e32 v42, 16, v40
	v_and_b32_e32 v43, 0xffff0000, v40
	v_lshlrev_b32_e32 v40, 16, v41
	v_and_b32_e32 v41, 0xffff0000, v41
	v_pk_mul_f32 v[4:5], v[44:45], v[4:5]
	v_pk_mul_f32 v[2:3], v[2:3], v[42:43]
	v_pk_mul_f32 v[4:5], v[4:5], v[40:41]
	v_cvt_pk_bf16_f32 v2, v2, v3
	v_cvt_pk_bf16_f32 v3, v4, v5
	global_store_dwordx2 v[36:37], v[2:3], off offset:2048
	global_load_dwordx4 v[2:5], v[12:13], off
	s_nop 0
	global_load_dwordx2 v[38:39], v[34:35], off offset:2560
	s_waitcnt vmcnt(1)
	v_pk_mul_f32 v[2:3], v[30:31], v[2:3]
	s_waitcnt vmcnt(0)
	v_lshlrev_b32_e32 v40, 16, v38
	v_and_b32_e32 v41, 0xffff0000, v38
	v_lshlrev_b32_e32 v38, 16, v39
	v_and_b32_e32 v39, 0xffff0000, v39
	v_pk_mul_f32 v[4:5], v[32:33], v[4:5]
	v_pk_mul_f32 v[2:3], v[2:3], v[40:41]
	v_pk_mul_f32 v[4:5], v[4:5], v[38:39]
	v_cvt_pk_bf16_f32 v2, v2, v3
	v_cvt_pk_bf16_f32 v3, v4, v5
	global_store_dwordx2 v[36:37], v[2:3], off offset:2560
	global_load_dwordx4 v[2:5], v[14:15], off
	s_nop 0
	global_load_dwordx2 v[30:31], v[34:35], off offset:3072
	s_waitcnt vmcnt(1)
	v_pk_mul_f32 v[2:3], v[26:27], v[2:3]
	s_waitcnt vmcnt(0)
	v_lshlrev_b32_e32 v32, 16, v30
	v_and_b32_e32 v33, 0xffff0000, v30
	v_lshlrev_b32_e32 v30, 16, v31
	v_and_b32_e32 v31, 0xffff0000, v31
	v_pk_mul_f32 v[4:5], v[28:29], v[4:5]
	v_pk_mul_f32 v[2:3], v[2:3], v[32:33]
	v_pk_mul_f32 v[4:5], v[4:5], v[30:31]
	v_cvt_pk_bf16_f32 v2, v2, v3
	v_cvt_pk_bf16_f32 v3, v4, v5
	global_store_dwordx2 v[36:37], v[2:3], off offset:3072
	global_load_dwordx4 v[2:5], v[16:17], off
	s_nop 0
	global_load_dwordx2 v[26:27], v[34:35], off offset:3584
	s_waitcnt vmcnt(1)
	v_pk_mul_f32 v[2:3], v[22:23], v[2:3]
	s_waitcnt vmcnt(0)
	v_lshlrev_b32_e32 v28, 16, v26
	v_and_b32_e32 v29, 0xffff0000, v26
	v_lshlrev_b32_e32 v26, 16, v27
	v_and_b32_e32 v27, 0xffff0000, v27
	v_pk_mul_f32 v[4:5], v[20:21], v[4:5]
	v_pk_mul_f32 v[2:3], v[2:3], v[28:29]
	v_pk_mul_f32 v[4:5], v[4:5], v[26:27]
	v_cvt_pk_bf16_f32 v2, v2, v3
	v_cvt_pk_bf16_f32 v3, v4, v5
	global_store_dwordx2 v[36:37], v[2:3], off offset:3584
	s_cbranch_scc1 .LBB0_574

; #define GAS __attribute__((address_space(1)))
; #define LAS __attribute__((address_space(3)))
; template <bool HG>
; __device__ __forceinline__ void readout_phase2(const Args& a, Frame& F, const float* gain, int nrows) {
;     ...
;     const int nw = F.vcu * NWAVES + F.wave;
;     const bf16* OF = (const bf16*)(a.ws + WS_OF); const bf16* OB = (const bf16*)(a.ws + WS_OB);
;     const bf16* G = (const bf16*)(a.ws + WS_ACT) + (size_t)(HG ? 6 : 3) * ACT_STRIDE; bf16* HN = (bf16*)(a.ws + WS_HN);
;     LAS float* GL = (LAS float*)F.lds;
;     v2u f0[8], b0[8], g0[8], f1[8], b1[8], g1[8], f2[8], b2[8], g2[8];
;     ...
;     RO_LOAD(f0, b0, g0, nw); RO_LOAD(f1, b1, g1, nw + 2048); RO_LOAD(f2, b2, g2, nw + 2 * 2048);
;     if (HG) { for (int q = F.tid; q < D / 4; q += NWAVES * 64) ((LAS f32x4*)GL)[q] = ((const GAS f32x4*)gain)[q];
.LBB0_576:
	s_andn2_b64 vcc, exec, s[8:9]
	s_cbranch_vccnz .LBB0_583
	s_getreg_b32 s6, hwreg(HW_REG_HW_ID, 0, 6)
	s_lshl_b32 s6, s6, 2
	s_add_i32 s6, s6, 0
	s_add_i32 s6, s6, 0x20540
	v_mov_b32_e32 v0, s6
	ds_read_b32 v0, v0
	v_mov_b64_e32 v[2:3], s[0:1]
	s_waitcnt lgkmcnt(0)
	v_readfirstlane_b32 s6, v0
	v_mbcnt_lo_u32_b32 v0, -1, 0
	v_mbcnt_hi_u32_b32 v0, -1, v0
	s_nop 1
	v_lshl_add_u32 v100, s6, 6, v0
	v_mov_b32_e32 v2, s72
	v_mov_b32_e32 v3, s73
	v_readfirstlane_b32 s6, v100
	s_ashr_i32 s6, s6, 6
	s_add_i32 s10, s6, s91
	s_mov_b64 s[6:7], 0x2ac00000
	s_ashr_i32 s11, s10, 31
	v_and_b32_e32 v166, 63, v100
	v_lshlrev_b32_e32 v0, 3, v166
	s_add_i32 s8, s10, 0x800
	s_ashr_i32 s9, s8, 31
	s_add_i32 s12, s10, 0x1000
	s_ashr_i32 s13, s12, 31
	s_waitcnt vmcnt(0) lgkmcnt(0)
	v_lshl_add_u64 v[36:37], v[2:3], 0, s[6:7]
	s_mov_b64 s[6:7], 0x33400000
	v_lshl_add_u64 v[38:39], v[2:3], 0, s[6:7]
	s_mov_b64 s[6:7], 0x26800000
	v_lshl_add_u64 v[40:41], v[2:3], 0, s[6:7]
	s_lshl_b64 s[6:7], s[10:11], 12
	v_lshl_add_u64 v[8:9], v[38:39], 0, s[6:7]
	v_lshl_add_u64 v[4:5], v[36:37], 0, s[6:7]
	v_lshl_add_u64 v[42:43], v[8:9], 0, v[0:1]
	v_lshl_add_u64 v[8:9], v[40:41], 0, s[6:7]
	v_lshl_add_u64 v[4:5], v[4:5], 0, v[0:1]
	v_lshl_add_u64 v[44:45], v[8:9], 0, v[0:1]
	s_lshl_b64 s[6:7], s[8:9], 12
	v_lshl_add_u64 v[184:185], s[84:85], 2, v[6:7]
	v_mov_b32_e32 v186, v100
	v_mov_b32_e32 v187, 0
	v_lshl_add_u64 v[184:185], v[186:187], 4, v[184:185]
	global_load_dwordx4 v[188:191], v[184:185], off
	global_load_dwordx2 v[156:157], v[4:5], off
	global_load_dwordx2 v[154:155], v[42:43], off
	global_load_dwordx2 v[8:9], v[44:45], off
	global_load_dwordx2 v[152:153], v[4:5], off offset:512
	global_load_dwordx2 v[150:151], v[42:43], off offset:512
	global_load_dwordx2 v[10:11], v[44:45], off offset:512
	global_load_dwordx2 v[148:149], v[4:5], off offset:1024
	global_load_dwordx2 v[140:141], v[42:43], off offset:1024
	global_load_dwordx2 v[14:15], v[44:45], off offset:1024
	global_load_dwordx2 v[90:91], v[4:5], off offset:1536
	global_load_dwordx2 v[80:81], v[42:43], off offset:1536
	global_load_dwordx2 v[18:19], v[44:45], off offset:1536
	global_load_dwordx2 v[34:35], v[4:5], off offset:2048
	global_load_dwordx2 v[32:33], v[42:43], off offset:2048
	global_load_dwordx2 v[22:23], v[44:45], off offset:2048
	global_load_dwordx2 v[28:29], v[4:5], off offset:2560
	global_load_dwordx2 v[24:25], v[42:43], off offset:2560
	global_load_dwordx2 v[26:27], v[44:45], off offset:2560
	global_load_dwordx2 v[20:21], v[4:5], off offset:3072
	global_load_dwordx2 v[16:17], v[42:43], off offset:3072
	global_load_dwordx2 v[30:31], v[44:45], off offset:3072
	global_load_dwordx2 v[12:13], v[4:5], off offset:3584
	s_nop 0
	global_load_dwordx2 v[4:5], v[42:43], off offset:3584
	global_load_dwordx2 v[76:77], v[44:45], off offset:3584
	v_lshl_add_u64 v[42:43], v[36:37], 0, s[6:7]
	v_lshl_add_u64 v[44:45], v[38:39], 0, s[6:7]
	v_lshl_add_u64 v[42:43], v[42:43], 0, v[0:1]
	v_lshl_add_u64 v[48:49], v[44:45], 0, v[0:1]
	v_lshl_add_u64 v[44:45], v[40:41], 0, s[6:7]
	s_lshl_b64 s[6:7], s[12:13], 12
	v_lshl_add_u64 v[50:51], v[44:45], 0, v[0:1]
	global_load_dwordx2 v[146:147], v[42:43], off
	global_load_dwordx2 v[144:145], v[48:49], off
	global_load_dwordx2 v[72:73], v[50:51], off
	global_load_dwordx2 v[142:143], v[42:43], off offset:512
	global_load_dwordx2 v[138:139], v[48:49], off offset:512
	global_load_dwordx2 v[70:71], v[50:51], off offset:512
	global_load_dwordx2 v[128:129], v[42:43], off offset:1024
	global_load_dwordx2 v[126:127], v[48:49], off offset:1024
	global_load_dwordx2 v[66:67], v[50:51], off offset:1024
	global_load_dwordx2 v[120:121], v[42:43], off offset:1536
	global_load_dwordx2 v[118:119], v[48:49], off offset:1536
	global_load_dwordx2 v[60:61], v[50:51], off offset:1536
	global_load_dwordx2 v[108:109], v[42:43], off offset:2048
	global_load_dwordx2 v[106:107], v[48:49], off offset:2048
	global_load_dwordx2 v[54:55], v[50:51], off offset:2048
	global_load_dwordx2 v[98:99], v[42:43], off offset:2560
	global_load_dwordx2 v[96:97], v[48:49], off offset:2560
	global_load_dwordx2 v[46:47], v[50:51], off offset:2560
	global_load_dwordx2 v[84:85], v[42:43], off offset:3072
	global_load_dwordx2 v[82:83], v[48:49], off offset:3072
	global_load_dwordx2 v[44:45], v[50:51], off offset:3072
	global_load_dwordx2 v[78:79], v[42:43], off offset:3584
	global_load_dwordx2 v[74:75], v[48:49], off offset:3584
	s_nop 0
	global_load_dwordx2 v[42:43], v[50:51], off offset:3584
	v_lshl_add_u64 v[48:49], v[36:37], 0, s[6:7]
	v_lshl_add_u64 v[86:87], v[48:49], 0, v[0:1]
	v_lshl_add_u64 v[48:49], v[38:39], 0, s[6:7]
	v_lshl_add_u64 v[50:51], v[48:49], 0, v[0:1]
	v_lshl_add_u64 v[48:49], v[40:41], 0, s[6:7]
	v_lshl_add_u64 v[158:159], v[48:49], 0, v[0:1]
	global_load_dwordx2 v[136:137], v[86:87], off
	global_load_dwordx2 v[134:135], v[50:51], off
	global_load_dwordx2 v[68:69], v[158:159], off
	global_load_dwordx2 v[132:133], v[86:87], off offset:512
	global_load_dwordx2 v[130:131], v[50:51], off offset:512
	global_load_dwordx2 v[64:65], v[158:159], off offset:512
	global_load_dwordx2 v[124:125], v[86:87], off offset:1024
	global_load_dwordx2 v[122:123], v[50:51], off offset:1024
	global_load_dwordx2 v[58:59], v[158:159], off offset:1024
	global_load_dwordx2 v[114:115], v[86:87], off offset:1536
	global_load_dwordx2 v[116:117], v[50:51], off offset:1536
	global_load_dwordx2 v[62:63], v[158:159], off offset:1536
	global_load_dwordx2 v[112:113], v[86:87], off offset:2048
	global_load_dwordx2 v[110:111], v[50:51], off offset:2048
	global_load_dwordx2 v[56:57], v[158:159], off offset:2048
	global_load_dwordx2 v[104:105], v[86:87], off offset:2560
	global_load_dwordx2 v[102:103], v[50:51], off offset:2560
	global_load_dwordx2 v[52:53], v[158:159], off offset:2560
	global_load_dwordx2 v[94:95], v[86:87], off offset:3072
	global_load_dwordx2 v[92:93], v[50:51], off offset:3072
	global_load_dwordx2 v[48:49], v[158:159], off offset:3072
	s_nop 0
	global_load_dwordx2 v[86:87], v[86:87], off offset:3584
	s_nop 0
	global_load_dwordx2 v[88:89], v[50:51], off offset:3584
	s_nop 0
	global_load_dwordx2 v[50:51], v[158:159], off offset:3584
	s_waitcnt vmcnt(62)
; #define GAS __attribute__((address_space(1)))
; #define LAS __attribute__((address_space(3)))
; template <bool HG>
; __device__ __forceinline__ void readout_phase2(const Args& a, Frame& F, const float* gain, int nrows) {
;     ...
;     if (HG) { for (int q = F.tid; q < D / 4; q += NWAVES * 64) ((LAS f32x4*)GL)[q] = ((const GAS f32x4*)gain)[q];
	v_lshl_add_u32 v184, v100, 4, 0
	ds_write_b128 v184, v[188:191]
	s_waitcnt vmcnt(62)
	v_lshlrev_b32_e32 v6, 16, v156
	v_and_b32_e32 v7, 0xffff0000, v156
	v_lshlrev_b32_e32 v100, 16, v154
	v_and_b32_e32 v101, 0xffff0000, v154
	v_pk_add_f32 v[6:7], v[6:7], v[100:101]
	v_lshlrev_b32_e32 v100, 16, v157
	v_and_b32_e32 v101, 0xffff0000, v157
	v_lshlrev_b32_e32 v154, 16, v155
	v_and_b32_e32 v155, 0xffff0000, v155
	v_pk_add_f32 v[154:155], v[100:101], v[154:155]
	v_lshlrev_b32_e32 v100, 16, v152
	v_and_b32_e32 v101, 0xffff0000, v152
	v_lshlrev_b32_e32 v156, 16, v150
	v_and_b32_e32 v157, 0xffff0000, v150
	v_pk_add_f32 v[100:101], v[100:101], v[156:157]
	v_lshlrev_b32_e32 v152, 16, v153
	v_and_b32_e32 v153, 0xffff0000, v153
	v_lshlrev_b32_e32 v150, 16, v151
	v_and_b32_e32 v151, 0xffff0000, v151
	v_pk_add_f32 v[150:151], v[152:153], v[150:151]
	v_mov_b32_e32 v156, v7
	v_mov_b32_e32 v157, v101
	v_mov_b32_e32 v152, v6
	v_mov_b32_e32 v153, v100
	v_pk_mul_f32 v[156:157], v[156:157], v[156:157]
	v_mov_b32_e32 v158, v155
	v_mov_b32_e32 v159, v151
	v_pk_fma_f32 v[152:153], v[152:153], v[152:153], v[156:157]
	v_mov_b32_e32 v156, v154
	v_mov_b32_e32 v157, v150
	v_pk_mul_f32 v[158:159], v[158:159], v[158:159]
	s_lshl_b64 s[18:19], s[8:9], 11
	v_pk_fma_f32 v[156:157], v[156:157], v[156:157], v[158:159]
	s_waitcnt vmcnt(58)
	v_lshlrev_b32_e32 v158, 16, v32
	v_pk_add_f32 v[152:153], v[152:153], v[156:157]
	v_lshlrev_b32_e32 v156, 16, v140
	v_pk_add_f32 v[160:161], v[152:153], v[152:153] op_sel:[0,1] op_sel_hi:[1,0]
	v_lshlrev_b32_e32 v152, 16, v148
	v_and_b32_e32 v153, 0xffff0000, v148
	v_and_b32_e32 v157, 0xffff0000, v140
	v_lshlrev_b32_e32 v148, 16, v149
	v_and_b32_e32 v149, 0xffff0000, v149
	v_lshlrev_b32_e32 v140, 16, v141
	v_and_b32_e32 v141, 0xffff0000, v141
	v_pk_add_f32 v[152:153], v[152:153], v[156:157]
	v_pk_add_f32 v[156:157], v[148:149], v[140:141]
	v_mov_b32_e32 v148, v153
	v_mov_b32_e32 v149, v157
	v_mov_b32_e32 v140, v152
	v_mov_b32_e32 v141, v156
	v_pk_mul_f32 v[148:149], v[148:149], v[148:149]
	v_and_b32_e32 v159, 0xffff0000, v32
	v_pk_fma_f32 v[140:141], v[140:141], v[140:141], v[148:149]
	v_lshlrev_b32_e32 v148, 16, v80
	v_pk_add_f32 v[162:163], v[140:141], v[140:141] op_sel:[0,1] op_sel_hi:[1,0]
	v_lshlrev_b32_e32 v140, 16, v90
	v_and_b32_e32 v141, 0xffff0000, v90
	v_and_b32_e32 v149, 0xffff0000, v80
	v_pk_add_f32 v[140:141], v[140:141], v[148:149]
	v_lshlrev_b32_e32 v90, 16, v91
	v_and_b32_e32 v91, 0xffff0000, v91
	v_lshlrev_b32_e32 v80, 16, v81
	v_and_b32_e32 v81, 0xffff0000, v81
	v_pk_add_f32 v[148:149], v[90:91], v[80:81]
	v_mul_f32_e32 v80, v141, v141
	v_pk_fma_f32 v[90:91], v[140:141], v[140:141], v[80:81] op_sel_hi:[1,1,0]
	v_mul_f32_e32 v80, v149, v149
	v_pk_fma_f32 v[164:165], v[148:149], v[148:149], v[80:81] op_sel_hi:[1,1,0]
	v_lshlrev_b32_e32 v80, 16, v34
	v_and_b32_e32 v81, 0xffff0000, v34
	v_lshlrev_b32_e32 v34, 16, v35
	v_and_b32_e32 v35, 0xffff0000, v35
	v_lshlrev_b32_e32 v32, 16, v33
	v_and_b32_e32 v33, 0xffff0000, v33
	v_pk_add_f32 v[80:81], v[80:81], v[158:159]
	v_pk_add_f32 v[158:159], v[34:35], v[32:33]
	v_pk_mul_f32 v[32:33], v[80:81], v[80:81]
	v_pk_mul_f32 v[34:35], v[158:159], v[158:159]
	v_mov_b32_e32 v161, v32
	v_mov_b32_e32 v163, v33
	v_mov_b32_e32 v91, v34
	v_mov_b32_e32 v165, v35
	v_pk_add_f32 v[32:33], v[160:161], v[162:163]
	v_pk_add_f32 v[34:35], v[90:91], v[164:165]
	s_waitcnt vmcnt(55)
	v_lshlrev_b32_e32 v90, 16, v24
	v_pk_add_f32 v[32:33], v[32:33], v[34:35]
	v_and_b32_e32 v91, 0xffff0000, v24
	v_pk_add_f32 v[34:35], v[32:33], v[32:33] op_sel:[0,1] op_sel_hi:[1,0]
	v_lshlrev_b32_e32 v32, 16, v28
	v_and_b32_e32 v33, 0xffff0000, v28
	v_lshlrev_b32_e32 v28, 16, v29
	v_and_b32_e32 v29, 0xffff0000, v29
	v_lshlrev_b32_e32 v24, 16, v25
	v_and_b32_e32 v25, 0xffff0000, v25
	v_pk_add_f32 v[32:33], v[32:33], v[90:91]
	v_pk_add_f32 v[28:29], v[28:29], v[24:25]
	v_mov_b32_e32 v90, v33
	v_mov_b32_e32 v91, v29
	v_mov_b32_e32 v24, v32
	v_mov_b32_e32 v25, v28
	v_pk_mul_f32 v[90:91], v[90:91], v[90:91]
	s_waitcnt vmcnt(52)
	v_lshlrev_b32_e32 v160, 16, v16
	v_pk_fma_f32 v[24:25], v[24:25], v[24:25], v[90:91]
	v_lshlrev_b32_e32 v90, 16, v20
	v_and_b32_e32 v91, 0xffff0000, v20
	v_and_b32_e32 v161, 0xffff0000, v16
	v_lshlrev_b32_e32 v20, 16, v21
	v_and_b32_e32 v21, 0xffff0000, v21
	v_lshlrev_b32_e32 v16, 16, v17
	v_and_b32_e32 v17, 0xffff0000, v17
	v_pk_add_f32 v[160:161], v[90:91], v[160:161]
	v_pk_add_f32 v[164:165], v[20:21], v[16:17]
	s_waitcnt vmcnt(50)
	v_lshlrev_b32_e32 v90, 16, v12
	v_and_b32_e32 v91, 0xffff0000, v12
	s_waitcnt vmcnt(49)
	v_lshlrev_b32_e32 v162, 16, v4
	v_and_b32_e32 v163, 0xffff0000, v4
	v_lshlrev_b32_e32 v12, 16, v13
	v_and_b32_e32 v13, 0xffff0000, v13
	v_lshlrev_b32_e32 v4, 16, v5
	v_and_b32_e32 v5, 0xffff0000, v5
	v_mul_f32_e32 v16, v161, v161
	v_mul_f32_e32 v20, v165, v165
	v_pk_add_f32 v[90:91], v[90:91], v[162:163]
	v_pk_add_f32 v[162:163], v[12:13], v[4:5]
	v_pk_add_f32 v[24:25], v[24:25], v[24:25] op_sel:[0,1] op_sel_hi:[1,0]
	v_pk_fma_f32 v[16:17], v[160:161], v[160:161], v[16:17] op_sel_hi:[1,1,0]
	v_pk_fma_f32 v[20:21], v[164:165], v[164:165], v[20:21] op_sel_hi:[1,1,0]
	v_pk_mul_f32 v[4:5], v[90:91], v[90:91]
	v_pk_mul_f32 v[12:13], v[162:163], v[162:163]
	v_mov_b32_e32 v35, v4
	v_mov_b32_e32 v25, v5
	v_mov_b32_e32 v17, v12
	v_mov_b32_e32 v21, v13
	v_pk_add_f32 v[4:5], v[34:35], v[24:25]
	v_pk_add_f32 v[12:13], v[16:17], v[20:21]
	s_waitcnt vmcnt(47)
	v_lshlrev_b32_e32 v172, 16, v146
	v_pk_add_f32 v[4:5], v[4:5], v[12:13]
	v_and_b32_e32 v173, 0xffff0000, v146
	v_add_f32_e32 v4, v4, v5
	s_waitcnt vmcnt(46)
; template <bool HG>
; __device__ __forceinline__ void readout_phase2(const Args& a, Frame& F, const float* gain, int nrows) {
;     ...
;               asm volatile("s_waitcnt lgkmcnt(0)" ::: "memory"); __builtin_amdgcn_s_barrier(); asm volatile("" ::: "memory"); }
;     RO_FINISH(f0, b0, g0, nw);            RO_LOAD(f0, b0, g0, nw + 3 * 2048);
	v_lshlrev_b32_e32 v176, 16, v144
	v_and_b32_e32 v177, 0xffff0000, v144
	v_add_f32_dpp v4, v4, v4 quad_perm:[1,0,3,2] row_mask:0xf bank_mask:0xf bound_ctrl:1
	v_lshlrev_b32_e32 v146, 16, v147
	v_and_b32_e32 v147, 0xffff0000, v147
	v_add_f32_dpp v4, v4, v4 quad_perm:[2,3,0,1] row_mask:0xf bank_mask:0xf bound_ctrl:1
	v_lshlrev_b32_e32 v144, 16, v145
	v_and_b32_e32 v145, 0xffff0000, v145
	v_add_f32_dpp v4, v4, v4 row_half_mirror row_mask:0xf bank_mask:0xf bound_ctrl:1
	v_pk_add_f32 v[172:173], v[172:173], v[176:177]
	v_pk_add_f32 v[146:147], v[146:147], v[144:145]
	v_add_f32_dpp v4, v4, v4 row_mirror row_mask:0xf bank_mask:0xf bound_ctrl:1
	s_waitcnt vmcnt(44)
	v_lshlrev_b32_e32 v144, 16, v142
	v_readlane_b32 s8, v4, 16
	v_readlane_b32 s9, v4, 48
	v_readlane_b32 s6, v4, 0
	v_readlane_b32 s7, v4, 32
	v_mov_b32_e32 v4, s8
	v_mov_b32_e32 v5, s9
	v_pk_add_f32 v[4:5], s[6:7], v[4:5]
	s_mov_b64 s[6:7], 0x8c00000
	v_add_f32_e32 v4, v4, v5
	v_fmamk_f32 v4, v4, 0x3a000000, v252
	v_mul_f32_e32 v5, 0x4f800000, v4
	v_cmp_gt_f32_e32 vcc, s55, v4
	v_lshl_add_u64 v[34:35], v[2:3], 0, s[6:7]
	v_and_b32_e32 v145, 0xffff0000, v142
	v_cndmask_b32_e32 v4, v4, v5, vcc
	v_sqrt_f32_e32 v5, v4
	s_waitcnt vmcnt(43)
	v_lshlrev_b32_e32 v176, 16, v138
	v_and_b32_e32 v177, 0xffff0000, v138
	v_pk_add_f32 v[144:145], v[144:145], v[176:177]
	v_add_u32_e32 v2, -1, v5
	v_fma_f32 v3, -v2, v5, v4
	v_cmp_ge_f32_e64 s[8:9], 0, v3
	v_add_u32_e32 v3, 1, v5
	v_lshlrev_b32_e32 v142, 16, v143
	v_cndmask_b32_e64 v2, v5, v2, s[8:9]
	v_fma_f32 v5, -v3, v5, v4
	v_cmp_lt_f32_e64 s[8:9], 0, v5
	v_and_b32_e32 v143, 0xffff0000, v143
	v_lshlrev_b32_e32 v138, 16, v139
	v_cndmask_b32_e64 v2, v2, v3, s[8:9]
	v_mul_f32_e32 v3, 0x37800000, v2
	v_cndmask_b32_e32 v2, v2, v3, vcc
	v_cmp_class_f32_e32 vcc, v4, v253
	v_and_b32_e32 v139, 0xffff0000, v139
	v_pk_add_f32 v[138:139], v[142:143], v[138:139]
	v_cndmask_b32_e32 v2, v2, v4, vcc
	v_div_scale_f32 v3, s[6:7], v2, v2, 1.0
	v_rcp_f32_e32 v4, v3
	v_mov_b32_e32 v176, v173
	v_mov_b32_e32 v177, v145
	v_mov_b32_e32 v142, v172
	v_fma_f32 v5, -v3, v4, 1.0
	v_fmac_f32_e32 v4, v5, v4
	v_div_scale_f32 v5, vcc, 1.0, v2, 1.0
	v_mul_f32_e32 v12, v5, v4
	v_fma_f32 v13, -v3, v12, v5
	v_mov_b32_e32 v143, v144
	v_pk_mul_f32 v[176:177], v[176:177], v[176:177]
	v_mov_b32_e32 v178, v147
	v_mov_b32_e32 v179, v139
	v_fmac_f32_e32 v12, v13, v4
	v_pk_fma_f32 v[142:143], v[142:143], v[142:143], v[176:177]
	v_mov_b32_e32 v176, v146
	v_mov_b32_e32 v177, v138
	v_pk_mul_f32 v[178:179], v[178:179], v[178:179]
	v_fma_f32 v3, -v3, v12, v5
	v_pk_fma_f32 v[176:177], v[176:177], v[176:177], v[178:179]
	s_lshl_b64 s[16:17], s[10:11], 11
	v_div_fmas_f32 v3, v3, v4, v12
	v_pk_add_f32 v[142:143], v[142:143], v[176:177]
	s_waitcnt lgkmcnt(0)
	s_barrier
	v_div_fixup_f32 v168, v3, v2, 1.0
	v_lshl_add_u64 v[2:3], s[16:17], 1, v[34:35]
	v_lshl_add_u32 v166, v166, 4, 0
	v_pk_add_f32 v[176:177], v[142:143], v[142:143] op_sel:[0,1] op_sel_hi:[1,0]
	s_waitcnt vmcnt(41)
	v_lshlrev_b32_e32 v142, 16, v128
	v_and_b32_e32 v143, 0xffff0000, v128
	s_waitcnt vmcnt(40)
	v_lshlrev_b32_e32 v178, 16, v126
	v_and_b32_e32 v179, 0xffff0000, v126
	v_lshlrev_b32_e32 v128, 16, v129
	v_and_b32_e32 v129, 0xffff0000, v129
	v_lshlrev_b32_e32 v126, 16, v127
	v_and_b32_e32 v127, 0xffff0000, v127
	v_lshl_add_u64 v[170:171], v[2:3], 0, v[0:1]
	ds_read_b128 v[2:5], v166
	v_pk_add_f32 v[142:143], v[142:143], v[178:179]
	v_pk_add_f32 v[178:179], v[128:129], v[126:127]
	v_mov_b32_e32 v128, v143
	v_mov_b32_e32 v129, v179
	v_mov_b32_e32 v126, v142
	v_mov_b32_e32 v127, v178
	v_pk_mul_f32 v[128:129], v[128:129], v[128:129]
	v_lshlrev_b32_e32 v12, 16, v8
	v_and_b32_e32 v13, 0xffff0000, v8
	v_lshlrev_b32_e32 v16, 16, v9
	v_and_b32_e32 v17, 0xffff0000, v9
	v_pk_mul_f32 v[24:25], v[6:7], v[168:169] op_sel_hi:[1,0]
	ds_read_b128 v[6:9], v166 offset:1024
	v_pk_fma_f32 v[126:127], v[126:127], v[126:127], v[128:129]
	s_waitcnt vmcnt(38)
	v_lshlrev_b32_e32 v128, 16, v120
	v_and_b32_e32 v129, 0xffff0000, v120
	s_waitcnt vmcnt(37)
	v_lshlrev_b32_e32 v180, 16, v118
	v_and_b32_e32 v181, 0xffff0000, v118
	v_lshlrev_b32_e32 v120, 16, v121
	v_and_b32_e32 v121, 0xffff0000, v121
	v_lshlrev_b32_e32 v118, 16, v119
	v_and_b32_e32 v119, 0xffff0000, v119
	v_pk_mul_f32 v[20:21], v[154:155], v[168:169] op_sel_hi:[1,0]
	v_pk_add_f32 v[128:129], v[128:129], v[180:181]
	v_pk_add_f32 v[118:119], v[120:121], v[118:119]
	s_waitcnt vmcnt(35)
	v_lshlrev_b32_e32 v184, 16, v108
	v_and_b32_e32 v185, 0xffff0000, v108
	s_waitcnt vmcnt(34)
	v_lshlrev_b32_e32 v186, 16, v106
	v_and_b32_e32 v187, 0xffff0000, v106
	v_lshlrev_b32_e32 v108, 16, v109
	v_and_b32_e32 v109, 0xffff0000, v109
	v_lshlrev_b32_e32 v106, 16, v107
	v_and_b32_e32 v107, 0xffff0000, v107
	s_waitcnt lgkmcnt(1)
	v_pk_mul_f32 v[24:25], v[2:3], v[24:25]
	v_pk_mul_f32 v[20:21], v[4:5], v[20:21]
	v_mul_f32_e32 v120, v129, v129
	v_mul_f32_e32 v180, v119, v119
	v_pk_add_f32 v[186:187], v[184:185], v[186:187]
	v_pk_add_f32 v[106:107], v[108:109], v[106:107]
	v_pk_mul_f32 v[16:17], v[20:21], v[16:17]
	v_pk_mul_f32 v[12:13], v[24:25], v[12:13]
	v_pk_add_f32 v[126:127], v[126:127], v[126:127] op_sel:[0,1] op_sel_hi:[1,0]
	v_pk_fma_f32 v[120:121], v[128:129], v[128:129], v[120:121] op_sel_hi:[1,1,0]
	v_pk_fma_f32 v[180:181], v[118:119], v[118:119], v[180:181] op_sel_hi:[1,1,0]
	v_pk_mul_f32 v[108:109], v[186:187], v[186:187]
	v_pk_mul_f32 v[184:185], v[106:107], v[106:107]
	v_cvt_pk_bf16_f32 v12, v12, v13
	v_cvt_pk_bf16_f32 v13, v16, v17
	v_pk_mul_f32 v[16:17], v[150:151], v[168:169] op_sel_hi:[1,0]
	v_pk_mul_f32 v[20:21], v[100:101], v[168:169] op_sel_hi:[1,0]
	v_mov_b32_e32 v177, v108
	v_mov_b32_e32 v127, v109
	v_mov_b32_e32 v121, v184
	v_mov_b32_e32 v181, v185
	global_store_dwordx2 v[170:171], v[12:13], off
	v_lshlrev_b32_e32 v12, 16, v10
	v_and_b32_e32 v13, 0xffff0000, v10
	v_lshlrev_b32_e32 v10, 16, v11
	v_and_b32_e32 v11, 0xffff0000, v11
	s_waitcnt lgkmcnt(0)
	v_pk_mul_f32 v[20:21], v[6:7], v[20:21]
	v_pk_mul_f32 v[16:17], v[8:9], v[16:17]
	v_pk_add_f32 v[108:109], v[176:177], v[126:127]
	v_pk_add_f32 v[120:121], v[120:121], v[180:181]
	v_pk_mul_f32 v[10:11], v[16:17], v[10:11]
	v_pk_mul_f32 v[12:13], v[20:21], v[12:13]
	v_pk_add_f32 v[108:109], v[108:109], v[120:121]
	s_waitcnt vmcnt(33)
	v_lshlrev_b32_e32 v120, 16, v98
	v_and_b32_e32 v121, 0xffff0000, v98
	s_waitcnt vmcnt(32)
	v_lshlrev_b32_e32 v126, 16, v96
	v_and_b32_e32 v127, 0xffff0000, v96
	v_lshlrev_b32_e32 v98, 16, v99
	v_and_b32_e32 v99, 0xffff0000, v99
	v_lshlrev_b32_e32 v96, 16, v97
	v_and_b32_e32 v97, 0xffff0000, v97
	v_cvt_pk_bf16_f32 v12, v12, v13
	v_cvt_pk_bf16_f32 v13, v10, v11
	v_pk_add_f32 v[120:121], v[120:121], v[126:127]
	v_pk_add_f32 v[96:97], v[98:99], v[96:97]
	global_store_dwordx2 v[170:171], v[12:13], off offset:512
	ds_read_b128 v[10:13], v166 offset:2048
	v_mov_b32_e32 v126, v121
	v_mov_b32_e32 v127, v97
	v_mov_b32_e32 v98, v120
	v_mov_b32_e32 v99, v96
	v_pk_mul_f32 v[126:127], v[126:127], v[126:127]
	s_waitcnt vmcnt(30)
	v_lshlrev_b32_e32 v176, 16, v82
	v_pk_fma_f32 v[98:99], v[98:99], v[98:99], v[126:127]
	v_lshlrev_b32_e32 v126, 16, v84
	v_and_b32_e32 v127, 0xffff0000, v84
	v_and_b32_e32 v177, 0xffff0000, v82
	v_lshlrev_b32_e32 v84, 16, v85
	v_and_b32_e32 v85, 0xffff0000, v85
	v_lshlrev_b32_e32 v82, 16, v83
	v_and_b32_e32 v83, 0xffff0000, v83
	v_lshlrev_b32_e32 v20, 16, v14
	v_and_b32_e32 v21, 0xffff0000, v14
	v_lshlrev_b32_e32 v24, 16, v15
	v_and_b32_e32 v25, 0xffff0000, v15
	ds_read_b128 v[14:17], v166 offset:3072
	v_pk_add_f32 v[176:177], v[126:127], v[176:177]
	v_pk_add_f32 v[82:83], v[84:85], v[82:83]
	s_waitcnt vmcnt(28)
	v_lshlrev_b32_e32 v180, 16, v78
	v_and_b32_e32 v181, 0xffff0000, v78
	s_waitcnt vmcnt(27)
	v_lshlrev_b32_e32 v184, 16, v74
	v_and_b32_e32 v185, 0xffff0000, v74
	v_lshlrev_b32_e32 v78, 16, v79
	v_and_b32_e32 v79, 0xffff0000, v79
	v_lshlrev_b32_e32 v74, 16, v75
	v_and_b32_e32 v75, 0xffff0000, v75
	v_pk_mul_f32 v[100:101], v[156:157], v[168:169] op_sel_hi:[1,0]
	v_pk_mul_f32 v[150:151], v[152:153], v[168:169] op_sel_hi:[1,0]
	v_mul_f32_e32 v84, v177, v177
	v_mul_f32_e32 v126, v83, v83
	v_pk_add_f32 v[180:181], v[180:181], v[184:185]
	v_pk_add_f32 v[78:79], v[78:79], v[74:75]
	s_waitcnt lgkmcnt(1)
	v_pk_mul_f32 v[150:151], v[10:11], v[150:151]
	v_pk_mul_f32 v[100:101], v[12:13], v[100:101]
	v_pk_add_f32 v[108:109], v[108:109], v[108:109] op_sel:[0,1] op_sel_hi:[1,0]
	v_pk_add_f32 v[98:99], v[98:99], v[98:99] op_sel:[0,1] op_sel_hi:[1,0]
	v_pk_fma_f32 v[84:85], v[176:177], v[176:177], v[84:85] op_sel_hi:[1,1,0]
	v_pk_fma_f32 v[126:127], v[82:83], v[82:83], v[126:127] op_sel_hi:[1,1,0]
	v_pk_mul_f32 v[74:75], v[180:181], v[180:181]
	v_pk_mul_f32 v[184:185], v[78:79], v[78:79]
	v_pk_mul_f32 v[24:25], v[100:101], v[24:25]
	v_pk_mul_f32 v[20:21], v[150:151], v[20:21]
	v_mov_b32_e32 v109, v74
	v_mov_b32_e32 v99, v75
	v_mov_b32_e32 v85, v184
	v_mov_b32_e32 v127, v185
	v_cvt_pk_bf16_f32 v20, v20, v21
	v_cvt_pk_bf16_f32 v21, v24, v25
	v_pk_mul_f32 v[24:25], v[148:149], v[168:169] op_sel_hi:[1,0]
	v_pk_mul_f32 v[100:101], v[140:141], v[168:169] op_sel_hi:[1,0]
	v_pk_add_f32 v[74:75], v[108:109], v[98:99]
	v_pk_add_f32 v[84:85], v[84:85], v[126:127]
	global_store_dwordx2 v[170:171], v[20:21], off offset:1024
	v_lshlrev_b32_e32 v20, 16, v18
	v_and_b32_e32 v21, 0xffff0000, v18
	v_lshlrev_b32_e32 v18, 16, v19
	v_and_b32_e32 v19, 0xffff0000, v19
	s_waitcnt lgkmcnt(0)
	v_pk_mul_f32 v[100:101], v[14:15], v[100:101]
	v_pk_mul_f32 v[24:25], v[16:17], v[24:25]
	v_pk_add_f32 v[74:75], v[74:75], v[84:85]
	v_pk_mul_f32 v[18:19], v[24:25], v[18:19]
	v_pk_mul_f32 v[20:21], v[100:101], v[20:21]
	v_add_f32_e32 v74, v74, v75
	v_cvt_pk_bf16_f32 v20, v20, v21
	v_cvt_pk_bf16_f32 v21, v18, v19
	v_add_f32_dpp v74, v74, v74 quad_perm:[1,0,3,2] row_mask:0xf bank_mask:0xf bound_ctrl:1
	global_store_dwordx2 v[170:171], v[20:21], off offset:1536
	ds_read_b128 v[18:21], v166 offset:4096
	v_add_f32_dpp v74, v74, v74 quad_perm:[2,3,0,1] row_mask:0xf bank_mask:0xf bound_ctrl:1
	v_lshlrev_b32_e32 v100, 16, v22
	v_and_b32_e32 v101, 0xffff0000, v22
	v_add_f32_dpp v74, v74, v74 row_half_mirror row_mask:0xf bank_mask:0xf bound_ctrl:1
	v_lshlrev_b32_e32 v140, 16, v23
	v_and_b32_e32 v141, 0xffff0000, v23
	v_add_f32_dpp v74, v74, v74 row_mirror row_mask:0xf bank_mask:0xf bound_ctrl:1
	ds_read_b128 v[22:25], v166 offset:5120
	v_readlane_b32 s8, v74, 16
	v_readlane_b32 s9, v74, 48
	v_pk_mul_f32 v[148:149], v[158:159], v[168:169] op_sel_hi:[1,0]
	v_pk_mul_f32 v[80:81], v[80:81], v[168:169] op_sel_hi:[1,0]
	v_readlane_b32 s6, v74, 0
	v_readlane_b32 s7, v74, 32
	v_mov_b32_e32 v74, s8
	v_mov_b32_e32 v75, s9
	s_waitcnt lgkmcnt(1)
	v_pk_mul_f32 v[80:81], v[18:19], v[80:81]
	v_pk_mul_f32 v[148:149], v[20:21], v[148:149]
	v_pk_add_f32 v[74:75], s[6:7], v[74:75]
	v_pk_mul_f32 v[140:141], v[148:149], v[140:141]
	v_pk_mul_f32 v[80:81], v[80:81], v[100:101]
	v_add_f32_e32 v74, v74, v75
	v_cvt_pk_bf16_f32 v80, v80, v81
	v_cvt_pk_bf16_f32 v81, v140, v141
	v_pk_mul_f32 v[28:29], v[28:29], v[168:169] op_sel_hi:[1,0]
	v_pk_mul_f32 v[32:33], v[32:33], v[168:169] op_sel_hi:[1,0]
	v_fmamk_f32 v74, v74, 0x3a000000, v252
	global_store_dwordx2 v[170:171], v[80:81], off offset:2048
	v_lshlrev_b32_e32 v80, 16, v26
	v_and_b32_e32 v81, 0xffff0000, v26
	v_lshlrev_b32_e32 v26, 16, v27
	v_and_b32_e32 v27, 0xffff0000, v27
	s_waitcnt lgkmcnt(0)
; template <bool HG>
; __device__ __forceinline__ void readout_phase2(const Args& a, Frame& F, const float* gain, int nrows) {
;     ...
;     RO_FINISH(f0, b0, g0, nw);            RO_LOAD(f0, b0, g0, nw + 3 * 2048);
	v_pk_mul_f32 v[32:33], v[32:33], v[22:23]
	v_pk_mul_f32 v[28:29], v[28:29], v[24:25]
	v_mul_f32_e32 v75, 0x4f800000, v74
	v_cmp_gt_f32_e32 vcc, s55, v74
	v_pk_mul_f32 v[26:27], v[28:29], v[26:27]
	v_pk_mul_f32 v[28:29], v[32:33], v[80:81]
	v_cndmask_b32_e32 v74, v74, v75, vcc
	v_cvt_pk_bf16_f32 v28, v28, v29
	v_cvt_pk_bf16_f32 v29, v26, v27
	v_sqrt_f32_e32 v75, v74
	global_store_dwordx2 v[170:171], v[28:29], off offset:2560
	ds_read_b128 v[26:29], v166 offset:6144
	v_lshlrev_b32_e32 v80, 16, v30
	v_and_b32_e32 v81, 0xffff0000, v30
	v_lshlrev_b32_e32 v100, 16, v31
	v_and_b32_e32 v101, 0xffff0000, v31
	ds_read_b128 v[30:33], v166 offset:7168
	v_add_u32_e32 v84, -1, v75
	v_pk_mul_f32 v[140:141], v[164:165], v[168:169] op_sel_hi:[1,0]
	v_pk_mul_f32 v[148:149], v[160:161], v[168:169] op_sel_hi:[1,0]
	v_fma_f32 v85, -v84, v75, v74
	s_waitcnt lgkmcnt(1)
	v_pk_mul_f32 v[148:149], v[148:149], v[26:27]
	v_pk_mul_f32 v[140:141], v[140:141], v[28:29]
	v_cmp_ge_f32_e64 s[8:9], 0, v85
	v_add_u32_e32 v85, 1, v75
	v_pk_mul_f32 v[100:101], v[140:141], v[100:101]
	v_pk_mul_f32 v[80:81], v[148:149], v[80:81]
	v_cndmask_b32_e64 v84, v75, v84, s[8:9]
	v_fma_f32 v75, -v85, v75, v74
	s_lshl_b64 s[14:15], s[12:13], 11
	v_cvt_pk_bf16_f32 v80, v80, v81
	v_cvt_pk_bf16_f32 v81, v100, v101
	v_pk_mul_f32 v[100:101], v[162:163], v[168:169] op_sel_hi:[1,0]
	v_pk_mul_f32 v[90:91], v[90:91], v[168:169] op_sel_hi:[1,0]
	s_lshl_b64 s[12:13], s[10:11], 12
	v_cmp_lt_f32_e64 s[8:9], 0, v75
	global_store_dwordx2 v[170:171], v[80:81], off offset:3072
	v_lshlrev_b32_e32 v80, 16, v76
	v_and_b32_e32 v81, 0xffff0000, v76
	v_lshlrev_b32_e32 v76, 16, v77
	v_and_b32_e32 v77, 0xffff0000, v77
	s_waitcnt lgkmcnt(0)
	v_pk_mul_f32 v[90:91], v[90:91], v[30:31]
	v_pk_mul_f32 v[100:101], v[100:101], v[32:33]
	s_add_u32 s16, s12, 0x1800000
	v_cndmask_b32_e64 v75, v84, v85, s[8:9]
	v_pk_mul_f32 v[76:77], v[100:101], v[76:77]
	v_pk_mul_f32 v[80:81], v[90:91], v[80:81]
	s_addc_u32 s17, s13, 0
	v_mul_f32_e32 v84, 0x37800000, v75
	v_cvt_pk_bf16_f32 v80, v80, v81
	v_cvt_pk_bf16_f32 v81, v76, v77
	v_lshl_add_u64 v[76:77], v[36:37], 0, s[16:17]
	v_cndmask_b32_e32 v75, v75, v84, vcc
	v_cmp_class_f32_e32 vcc, v74, v253
	v_lshl_add_u64 v[140:141], v[76:77], 0, v[0:1]
	v_lshl_add_u64 v[76:77], v[38:39], 0, s[16:17]
	v_cndmask_b32_e32 v84, v75, v74, vcc
	global_store_dwordx2 v[170:171], v[80:81], off offset:3584
	v_lshl_add_u64 v[170:171], v[76:77], 0, v[0:1]
	v_lshl_add_u64 v[76:77], v[40:41], 0, s[16:17]
	v_div_scale_f32 v85, s[6:7], v84, v84, 1.0
	v_lshl_add_u64 v[166:167], v[76:77], 0, v[0:1]
	global_load_dwordx2 v[168:169], v[140:141], off
	global_load_dwordx2 v[162:163], v[140:141], off offset:512
	global_load_dwordx2 v[158:159], v[140:141], off offset:1024
	global_load_dwordx2 v[154:155], v[140:141], off offset:1536
	global_load_dwordx2 v[174:175], v[170:171], off
	global_load_dwordx2 v[164:165], v[170:171], off offset:512
	global_load_dwordx2 v[160:161], v[170:171], off offset:1024
	global_load_dwordx2 v[156:157], v[170:171], off offset:1536
	global_load_dwordx2 v[100:101], v[166:167], off
	global_load_dwordx2 v[90:91], v[166:167], off offset:512
	global_load_dwordx2 v[80:81], v[166:167], off offset:1024
	global_load_dwordx2 v[76:77], v[166:167], off offset:1536
	global_load_dwordx2 v[152:153], v[140:141], off offset:2048
	global_load_dwordx2 v[150:151], v[140:141], off offset:2560
	global_load_dwordx2 v[148:149], v[140:141], off offset:3072
	s_nop 0
	global_load_dwordx2 v[140:141], v[140:141], off offset:3584
	s_nop 0
	global_load_dwordx2 v[196:197], v[170:171], off offset:2048
	global_load_dwordx2 v[192:193], v[170:171], off offset:2560
	global_load_dwordx2 v[188:189], v[170:171], off offset:3072
	global_load_dwordx2 v[184:185], v[170:171], off offset:3584
	v_rcp_f32_e32 v170, v85
	global_load_dwordx2 v[126:127], v[166:167], off offset:2048
	global_load_dwordx2 v[108:109], v[166:167], off offset:2560
	global_load_dwordx2 v[98:99], v[166:167], off offset:3072
	global_load_dwordx2 v[74:75], v[166:167], off offset:3584
	v_fma_f32 v166, -v85, v170, 1.0
	v_fmac_f32_e32 v170, v166, v170
	v_div_scale_f32 v166, vcc, 1.0, v84, 1.0
	v_mul_f32_e32 v167, v166, v170
	v_fma_f32 v171, -v85, v167, v166
	v_fmac_f32_e32 v167, v171, v170
	v_fma_f32 v85, -v85, v167, v166
	v_div_fmas_f32 v85, v85, v170, v167
	v_div_fixup_f32 v84, v85, v84, 1.0
	v_pk_mul_f32 v[146:147], v[146:147], v[84:85] op_sel_hi:[1,0]
	v_pk_mul_f32 v[172:173], v[172:173], v[84:85] op_sel_hi:[1,0]
	v_lshlrev_b32_e32 v170, 16, v72
	v_and_b32_e32 v171, 0xffff0000, v72
	v_lshlrev_b32_e32 v72, 16, v73
	v_and_b32_e32 v73, 0xffff0000, v73
	v_pk_mul_f32 v[172:173], v[2:3], v[172:173]
	v_pk_mul_f32 v[146:147], v[4:5], v[146:147]
	v_pk_mul_f32 v[138:139], v[138:139], v[84:85] op_sel_hi:[1,0]
	v_pk_mul_f32 v[72:73], v[146:147], v[72:73]
	v_pk_mul_f32 v[146:147], v[172:173], v[170:171]
	v_pk_mul_f32 v[144:145], v[144:145], v[84:85] op_sel_hi:[1,0]
	v_cvt_pk_bf16_f32 v146, v146, v147
	v_cvt_pk_bf16_f32 v147, v72, v73
	v_lshlrev_b32_e32 v72, 16, v70
	v_and_b32_e32 v73, 0xffff0000, v70
	v_lshlrev_b32_e32 v70, 16, v71
	v_and_b32_e32 v71, 0xffff0000, v71
	v_pk_mul_f32 v[144:145], v[6:7], v[144:145]
	v_pk_mul_f32 v[138:139], v[8:9], v[138:139]
	v_lshl_add_u64 v[166:167], s[18:19], 1, v[34:35]
	v_pk_mul_f32 v[70:71], v[138:139], v[70:71]
	v_pk_mul_f32 v[72:73], v[144:145], v[72:73]
	v_lshl_add_u64 v[166:167], v[166:167], 0, v[0:1]
	v_cvt_pk_bf16_f32 v72, v72, v73
	v_cvt_pk_bf16_f32 v73, v70, v71
	global_store_dwordx2 v[166:167], v[72:73], off offset:512
	v_pk_mul_f32 v[72:73], v[178:179], v[84:85] op_sel_hi:[1,0]
	v_pk_mul_f32 v[138:139], v[142:143], v[84:85] op_sel_hi:[1,0]
; template <bool HG>
; __device__ __forceinline__ void readout_phase2(const Args& a, Frame& F, const float* gain, int nrows) {
;     ...
;     RO_FINISH(f1, b1, g1, nw + 2048);     RO_LOAD(f1, b1, g1, nw + 4 * 2048);
	v_lshlrev_b32_e32 v70, 16, v66
	v_and_b32_e32 v71, 0xffff0000, v66
	v_lshlrev_b32_e32 v66, 16, v67
	v_and_b32_e32 v67, 0xffff0000, v67
	v_pk_mul_f32 v[138:139], v[10:11], v[138:139]
	v_pk_mul_f32 v[72:73], v[12:13], v[72:73]
	v_pk_mul_f32 v[70:71], v[138:139], v[70:71]
	v_pk_mul_f32 v[66:67], v[72:73], v[66:67]
	v_cvt_pk_bf16_f32 v70, v70, v71
	v_cvt_pk_bf16_f32 v71, v66, v67
	global_store_dwordx2 v[166:167], v[70:71], off offset:1024
	v_pk_mul_f32 v[70:71], v[118:119], v[84:85] op_sel_hi:[1,0]
	v_pk_mul_f32 v[72:73], v[128:129], v[84:85] op_sel_hi:[1,0]
	v_lshlrev_b32_e32 v66, 16, v60
	v_and_b32_e32 v67, 0xffff0000, v60
	v_lshlrev_b32_e32 v60, 16, v61
	v_and_b32_e32 v61, 0xffff0000, v61
	v_pk_mul_f32 v[72:73], v[14:15], v[72:73]
	v_pk_mul_f32 v[70:71], v[16:17], v[70:71]
	v_pk_mul_f32 v[66:67], v[72:73], v[66:67]
	v_pk_mul_f32 v[60:61], v[70:71], v[60:61]
	v_cvt_pk_bf16_f32 v66, v66, v67
	v_cvt_pk_bf16_f32 v67, v60, v61
	global_store_dwordx2 v[166:167], v[66:67], off offset:1536
	v_pk_mul_f32 v[66:67], v[106:107], v[84:85] op_sel_hi:[1,0]
	v_pk_mul_f32 v[70:71], v[186:187], v[84:85] op_sel_hi:[1,0]
	v_lshlrev_b32_e32 v60, 16, v54
	v_and_b32_e32 v61, 0xffff0000, v54
	v_lshlrev_b32_e32 v54, 16, v55
	v_and_b32_e32 v55, 0xffff0000, v55
	v_pk_mul_f32 v[70:71], v[18:19], v[70:71]
	v_pk_mul_f32 v[66:67], v[20:21], v[66:67]
	v_pk_mul_f32 v[60:61], v[70:71], v[60:61]
	v_pk_mul_f32 v[54:55], v[66:67], v[54:55]
	v_cvt_pk_bf16_f32 v60, v60, v61
	v_cvt_pk_bf16_f32 v61, v54, v55
	global_store_dwordx2 v[166:167], v[60:61], off offset:2048
	v_pk_mul_f32 v[60:61], v[96:97], v[84:85] op_sel_hi:[1,0]
	v_pk_mul_f32 v[66:67], v[120:121], v[84:85] op_sel_hi:[1,0]
	v_lshlrev_b32_e32 v54, 16, v46
	v_and_b32_e32 v55, 0xffff0000, v46
	v_lshlrev_b32_e32 v46, 16, v47
	v_and_b32_e32 v47, 0xffff0000, v47
	v_pk_mul_f32 v[66:67], v[22:23], v[66:67]
	v_pk_mul_f32 v[60:61], v[24:25], v[60:61]
	v_pk_mul_f32 v[54:55], v[66:67], v[54:55]
	v_pk_mul_f32 v[46:47], v[60:61], v[46:47]
	v_cvt_pk_bf16_f32 v54, v54, v55
	v_cvt_pk_bf16_f32 v55, v46, v47
	global_store_dwordx2 v[166:167], v[54:55], off offset:2560
	v_pk_mul_f32 v[54:55], v[82:83], v[84:85] op_sel_hi:[1,0]
	v_pk_mul_f32 v[60:61], v[176:177], v[84:85] op_sel_hi:[1,0]
	v_lshlrev_b32_e32 v46, 16, v44
	v_and_b32_e32 v47, 0xffff0000, v44
	v_lshlrev_b32_e32 v44, 16, v45
	v_and_b32_e32 v45, 0xffff0000, v45
	v_pk_mul_f32 v[60:61], v[26:27], v[60:61]
	v_pk_mul_f32 v[54:55], v[28:29], v[54:55]
	v_pk_mul_f32 v[46:47], v[60:61], v[46:47]
	v_pk_mul_f32 v[44:45], v[54:55], v[44:45]
	v_cvt_pk_bf16_f32 v46, v46, v47
	v_cvt_pk_bf16_f32 v47, v44, v45
	global_store_dwordx2 v[166:167], v[46:47], off offset:3072
	v_pk_mul_f32 v[46:47], v[78:79], v[84:85] op_sel_hi:[1,0]
	v_pk_mul_f32 v[54:55], v[180:181], v[84:85] op_sel_hi:[1,0]
	s_waitcnt vmcnt(62)
	v_lshlrev_b32_e32 v44, 16, v42
	v_and_b32_e32 v45, 0xffff0000, v42
	v_lshlrev_b32_e32 v42, 16, v43
	v_and_b32_e32 v43, 0xffff0000, v43
	v_pk_mul_f32 v[54:55], v[30:31], v[54:55]
	v_pk_mul_f32 v[46:47], v[32:33], v[46:47]
	s_add_u32 s18, s12, 0x2000000
	v_pk_mul_f32 v[42:43], v[46:47], v[42:43]
	v_pk_mul_f32 v[44:45], v[54:55], v[44:45]
	s_addc_u32 s19, s13, 0
	v_cvt_pk_bf16_f32 v44, v44, v45
	v_cvt_pk_bf16_f32 v45, v42, v43
	v_lshl_add_u64 v[42:43], v[36:37], 0, s[18:19]
	v_lshl_add_u64 v[70:71], v[42:43], 0, v[0:1]
	v_lshl_add_u64 v[42:43], v[38:39], 0, s[18:19]
	global_store_dwordx2 v[166:167], v[146:147], off
	global_store_dwordx2 v[166:167], v[44:45], off offset:3584
	v_lshl_add_u64 v[44:45], v[42:43], 0, v[0:1]
	v_lshl_add_u64 v[42:43], v[40:41], 0, s[18:19]
	v_lshl_add_u64 v[42:43], v[42:43], 0, v[0:1]
	global_load_dwordx2 v[170:171], v[70:71], off
	global_load_dwordx2 v[144:145], v[70:71], off offset:512
	global_load_dwordx2 v[138:139], v[70:71], off offset:1024
	global_load_dwordx2 v[118:119], v[70:71], off offset:1536
	global_load_dwordx2 v[176:177], v[44:45], off
	global_load_dwordx2 v[146:147], v[44:45], off offset:512
	global_load_dwordx2 v[142:143], v[44:45], off offset:1024
	global_load_dwordx2 v[120:121], v[44:45], off offset:1536
	global_load_dwordx2 v[66:67], v[42:43], off
	global_load_dwordx2 v[60:61], v[42:43], off offset:512
	global_load_dwordx2 v[54:55], v[42:43], off offset:1024
	global_load_dwordx2 v[46:47], v[42:43], off offset:1536
	global_load_dwordx2 v[106:107], v[70:71], off offset:2048
	global_load_dwordx2 v[96:97], v[70:71], off offset:2560
	global_load_dwordx2 v[82:83], v[70:71], off offset:3072
	global_load_dwordx2 v[72:73], v[70:71], off offset:3584
	s_waitcnt vmcnt(62)
	v_lshlrev_b32_e32 v70, 16, v136
	v_and_b32_e32 v71, 0xffff0000, v136
	v_lshlrev_b32_e32 v78, 16, v134
	v_and_b32_e32 v79, 0xffff0000, v134
	v_pk_add_f32 v[78:79], v[70:71], v[78:79]
	v_lshlrev_b32_e32 v70, 16, v137
	v_and_b32_e32 v71, 0xffff0000, v137
	v_lshlrev_b32_e32 v84, 16, v135
	v_and_b32_e32 v85, 0xffff0000, v135
	v_pk_add_f32 v[128:129], v[70:71], v[84:85]
	v_lshlrev_b32_e32 v70, 16, v132
	v_and_b32_e32 v71, 0xffff0000, v132
	v_lshlrev_b32_e32 v84, 16, v130
	v_and_b32_e32 v85, 0xffff0000, v130
	v_pk_add_f32 v[70:71], v[70:71], v[84:85]
	v_lshlrev_b32_e32 v84, 16, v133
	v_and_b32_e32 v85, 0xffff0000, v133
	v_lshlrev_b32_e32 v130, 16, v131
	v_and_b32_e32 v131, 0xffff0000, v131
	v_pk_add_f32 v[84:85], v[84:85], v[130:131]
	v_mov_b32_e32 v132, v79
	v_mov_b32_e32 v133, v71
	v_mov_b32_e32 v130, v78
	v_mov_b32_e32 v131, v70
	v_pk_mul_f32 v[132:133], v[132:133], v[132:133]
	v_mov_b32_e32 v134, v129
	v_mov_b32_e32 v135, v85
	v_pk_fma_f32 v[130:131], v[130:131], v[130:131], v[132:133]
	v_mov_b32_e32 v132, v128
	v_mov_b32_e32 v133, v84
	v_pk_mul_f32 v[134:135], v[134:135], v[134:135]
	v_lshlrev_b32_e32 v136, 16, v116
	v_pk_fma_f32 v[132:133], v[132:133], v[132:133], v[134:135]
	v_lshlrev_b32_e32 v134, 16, v122
	v_pk_add_f32 v[130:131], v[130:131], v[132:133]
	v_and_b32_e32 v135, 0xffff0000, v122
	v_pk_add_f32 v[132:133], v[130:131], v[130:131] op_sel:[0,1] op_sel_hi:[1,0]
	v_lshlrev_b32_e32 v130, 16, v124
	v_and_b32_e32 v131, 0xffff0000, v124
	v_lshlrev_b32_e32 v124, 16, v125
	v_and_b32_e32 v125, 0xffff0000, v125
	v_lshlrev_b32_e32 v122, 16, v123
	v_and_b32_e32 v123, 0xffff0000, v123
	v_pk_add_f32 v[130:131], v[130:131], v[134:135]
	v_pk_add_f32 v[134:135], v[124:125], v[122:123]
	v_mov_b32_e32 v124, v131
	v_mov_b32_e32 v125, v135
	v_mov_b32_e32 v122, v130
	v_mov_b32_e32 v123, v134
	v_pk_mul_f32 v[124:125], v[124:125], v[124:125]
	v_and_b32_e32 v137, 0xffff0000, v116
	v_pk_fma_f32 v[122:123], v[122:123], v[122:123], v[124:125]
	v_lshlrev_b32_e32 v124, 16, v114
	v_and_b32_e32 v125, 0xffff0000, v114
	v_lshlrev_b32_e32 v114, 16, v115
	v_and_b32_e32 v115, 0xffff0000, v115
	v_lshlrev_b32_e32 v116, 16, v117
	v_and_b32_e32 v117, 0xffff0000, v117
	v_pk_add_f32 v[124:125], v[124:125], v[136:137]
	v_pk_add_f32 v[114:115], v[114:115], v[116:117]
	v_lshlrev_b32_e32 v166, 16, v112
	v_and_b32_e32 v167, 0xffff0000, v112
	v_lshlrev_b32_e32 v172, 16, v110
	v_and_b32_e32 v173, 0xffff0000, v110
	v_lshlrev_b32_e32 v112, 16, v113
	v_and_b32_e32 v113, 0xffff0000, v113
	v_lshlrev_b32_e32 v110, 16, v111
	v_and_b32_e32 v111, 0xffff0000, v111
	v_mul_f32_e32 v116, v125, v125
	v_mul_f32_e32 v136, v115, v115
	v_pk_add_f32 v[166:167], v[166:167], v[172:173]
	v_pk_add_f32 v[112:113], v[112:113], v[110:111]
	v_pk_add_f32 v[122:123], v[122:123], v[122:123] op_sel:[0,1] op_sel_hi:[1,0]
	v_pk_fma_f32 v[116:117], v[124:125], v[124:125], v[116:117] op_sel_hi:[1,1,0]
	v_pk_fma_f32 v[136:137], v[114:115], v[114:115], v[136:137] op_sel_hi:[1,1,0]
	v_pk_mul_f32 v[110:111], v[166:167], v[166:167]
	v_pk_mul_f32 v[172:173], v[112:113], v[112:113]
	v_mov_b32_e32 v133, v110
	v_mov_b32_e32 v123, v111
	v_mov_b32_e32 v117, v172
	v_mov_b32_e32 v137, v173
	v_pk_add_f32 v[110:111], v[132:133], v[122:123]
	v_pk_add_f32 v[116:117], v[116:117], v[136:137]
	v_lshlrev_b32_e32 v122, 16, v102
	v_pk_add_f32 v[110:111], v[110:111], v[116:117]
	v_lshlrev_b32_e32 v116, 16, v104
	v_and_b32_e32 v117, 0xffff0000, v104
	v_and_b32_e32 v123, 0xffff0000, v102
	v_lshlrev_b32_e32 v104, 16, v105
	v_and_b32_e32 v105, 0xffff0000, v105
	v_lshlrev_b32_e32 v102, 16, v103
	v_and_b32_e32 v103, 0xffff0000, v103
	v_pk_add_f32 v[116:117], v[116:117], v[122:123]
	v_pk_add_f32 v[102:103], v[104:105], v[102:103]
	v_mov_b32_e32 v122, v117
	v_mov_b32_e32 v123, v103
	v_mov_b32_e32 v104, v116
	v_mov_b32_e32 v105, v102
	v_pk_mul_f32 v[122:123], v[122:123], v[122:123]
	s_waitcnt vmcnt(60)
	v_lshlrev_b32_e32 v132, 16, v92
	v_pk_fma_f32 v[104:105], v[104:105], v[104:105], v[122:123]
	v_lshlrev_b32_e32 v122, 16, v94
	v_and_b32_e32 v123, 0xffff0000, v94
	v_and_b32_e32 v133, 0xffff0000, v92
	v_lshlrev_b32_e32 v94, 16, v95
	v_and_b32_e32 v95, 0xffff0000, v95
	v_lshlrev_b32_e32 v92, 16, v93
	v_and_b32_e32 v93, 0xffff0000, v93
	v_pk_add_f32 v[132:133], v[122:123], v[132:133]
	v_pk_add_f32 v[92:93], v[94:95], v[92:93]
	s_waitcnt vmcnt(58)
	v_lshlrev_b32_e32 v136, 16, v86
	v_and_b32_e32 v137, 0xffff0000, v86
	s_waitcnt vmcnt(57)
	v_lshlrev_b32_e32 v172, 16, v88
	v_and_b32_e32 v173, 0xffff0000, v88
	v_lshlrev_b32_e32 v86, 16, v87
	v_and_b32_e32 v87, 0xffff0000, v87
	v_lshlrev_b32_e32 v88, 16, v89
	v_and_b32_e32 v89, 0xffff0000, v89
	v_mul_f32_e32 v94, v133, v133
	v_mul_f32_e32 v122, v93, v93
	v_pk_add_f32 v[136:137], v[136:137], v[172:173]
	v_pk_add_f32 v[86:87], v[86:87], v[88:89]
	v_pk_add_f32 v[110:111], v[110:111], v[110:111] op_sel:[0,1] op_sel_hi:[1,0]
	v_pk_add_f32 v[104:105], v[104:105], v[104:105] op_sel:[0,1] op_sel_hi:[1,0]
	v_pk_fma_f32 v[94:95], v[132:133], v[132:133], v[94:95] op_sel_hi:[1,1,0]
	v_pk_fma_f32 v[122:123], v[92:93], v[92:93], v[122:123] op_sel_hi:[1,1,0]
	v_pk_mul_f32 v[88:89], v[136:137], v[136:137]
	v_pk_mul_f32 v[172:173], v[86:87], v[86:87]
	v_mov_b32_e32 v111, v88
	v_mov_b32_e32 v105, v89
	v_mov_b32_e32 v95, v172
	v_mov_b32_e32 v123, v173
	v_pk_add_f32 v[88:89], v[110:111], v[104:105]
	v_pk_add_f32 v[94:95], v[94:95], v[122:123]
	global_load_dwordx2 v[198:199], v[44:45], off offset:2048
	global_load_dwordx2 v[194:195], v[44:45], off offset:2560
	global_load_dwordx2 v[190:191], v[44:45], off offset:3072
	global_load_dwordx2 v[186:187], v[44:45], off offset:3584
	v_pk_add_f32 v[88:89], v[88:89], v[94:95]
	s_nop 0
	v_add_f32_e32 v88, v88, v89
	s_nop 1
	v_add_f32_dpp v88, v88, v88 quad_perm:[1,0,3,2] row_mask:0xf bank_mask:0xf bound_ctrl:1
	s_nop 1
	v_add_f32_dpp v88, v88, v88 quad_perm:[2,3,0,1] row_mask:0xf bank_mask:0xf bound_ctrl:1
	s_nop 1
	v_add_f32_dpp v88, v88, v88 row_half_mirror row_mask:0xf bank_mask:0xf bound_ctrl:1
	s_nop 1
	v_add_f32_dpp v88, v88, v88 row_mirror row_mask:0xf bank_mask:0xf bound_ctrl:1
	s_nop 0
	v_readlane_b32 s8, v88, 16
	v_readlane_b32 s9, v88, 48
	v_readlane_b32 s6, v88, 0
	v_readlane_b32 s7, v88, 32
	v_mov_b32_e32 v88, s8
	v_mov_b32_e32 v89, s9
	v_pk_add_f32 v[88:89], s[6:7], v[88:89]
	s_nop 0
	v_add_f32_e32 v88, v88, v89
	v_fmamk_f32 v88, v88, 0x3a000000, v252
	v_mul_f32_e32 v89, 0x4f800000, v88
	v_cmp_gt_f32_e32 vcc, s55, v88
	s_nop 1
	v_cndmask_b32_e32 v88, v88, v89, vcc
	v_sqrt_f32_e32 v89, v88
	s_nop 0
	v_add_u32_e32 v44, -1, v89
	v_fma_f32 v45, -v44, v89, v88
	v_cmp_ge_f32_e64 s[8:9], 0, v45
	v_add_u32_e32 v45, 1, v89
	s_nop 0
	v_cndmask_b32_e64 v44, v89, v44, s[8:9]
	v_fma_f32 v89, -v45, v89, v88
	v_cmp_lt_f32_e64 s[8:9], 0, v89
	s_nop 1
	v_cndmask_b32_e64 v44, v44, v45, s[8:9]
	v_mul_f32_e32 v45, 0x37800000, v44
	v_cndmask_b32_e32 v44, v44, v45, vcc
	v_cmp_class_f32_e32 vcc, v88, v253
	s_nop 1
	v_cndmask_b32_e32 v44, v44, v88, vcc
	v_div_scale_f32 v45, s[6:7], v44, v44, 1.0
	v_rcp_f32_e32 v104, v45
	global_load_dwordx2 v[122:123], v[42:43], off offset:2048
	global_load_dwordx2 v[110:111], v[42:43], off offset:2560
	global_load_dwordx2 v[94:95], v[42:43], off offset:3072
	global_load_dwordx2 v[88:89], v[42:43], off offset:3584
	v_fma_f32 v42, -v45, v104, 1.0
	v_fmac_f32_e32 v104, v42, v104
	v_div_scale_f32 v42, vcc, 1.0, v44, 1.0
	v_mul_f32_e32 v43, v42, v104
	v_fma_f32 v105, -v45, v43, v42
	v_fmac_f32_e32 v43, v105, v104
	v_fma_f32 v42, -v45, v43, v42
	v_div_fmas_f32 v42, v42, v104, v43
	v_div_fixup_f32 v42, v42, v44, 1.0
	v_pk_mul_f32 v[128:129], v[128:129], v[42:43] op_sel_hi:[1,0]
	v_pk_mul_f32 v[78:79], v[78:79], v[42:43] op_sel_hi:[1,0]
	v_lshlrev_b32_e32 v104, 16, v68
	v_and_b32_e32 v105, 0xffff0000, v68
	v_lshlrev_b32_e32 v68, 16, v69
	v_and_b32_e32 v69, 0xffff0000, v69
	v_pk_mul_f32 v[78:79], v[2:3], v[78:79]
	v_pk_mul_f32 v[128:129], v[4:5], v[128:129]
	v_lshl_add_u64 v[44:45], s[14:15], 1, v[34:35]
	v_pk_mul_f32 v[68:69], v[128:129], v[68:69]
	v_pk_mul_f32 v[78:79], v[78:79], v[104:105]
	v_lshl_add_u64 v[44:45], v[44:45], 0, v[0:1]
	v_cvt_pk_bf16_f32 v78, v78, v79
	v_cvt_pk_bf16_f32 v79, v68, v69
	global_store_dwordx2 v[44:45], v[78:79], off
	v_pk_mul_f32 v[78:79], v[84:85], v[42:43] op_sel_hi:[1,0]
	v_pk_mul_f32 v[70:71], v[70:71], v[42:43] op_sel_hi:[1,0]
	v_lshlrev_b32_e32 v68, 16, v64
	v_and_b32_e32 v69, 0xffff0000, v64
	v_lshlrev_b32_e32 v64, 16, v65
	v_and_b32_e32 v65, 0xffff0000, v65
	v_pk_mul_f32 v[70:71], v[6:7], v[70:71]
	v_pk_mul_f32 v[78:79], v[8:9], v[78:79]
	v_pk_mul_f32 v[68:69], v[70:71], v[68:69]
	v_pk_mul_f32 v[64:65], v[78:79], v[64:65]
	v_cvt_pk_bf16_f32 v68, v68, v69
	v_cvt_pk_bf16_f32 v69, v64, v65
	global_store_dwordx2 v[44:45], v[68:69], off offset:512
	v_pk_mul_f32 v[68:69], v[134:135], v[42:43] op_sel_hi:[1,0]
	v_pk_mul_f32 v[70:71], v[130:131], v[42:43] op_sel_hi:[1,0]
	v_lshlrev_b32_e32 v64, 16, v58
	v_and_b32_e32 v65, 0xffff0000, v58
	v_lshlrev_b32_e32 v58, 16, v59
	v_and_b32_e32 v59, 0xffff0000, v59
	v_pk_mul_f32 v[70:71], v[10:11], v[70:71]
	v_pk_mul_f32 v[68:69], v[12:13], v[68:69]
	v_pk_mul_f32 v[64:65], v[70:71], v[64:65]
	v_pk_mul_f32 v[58:59], v[68:69], v[58:59]
	v_cvt_pk_bf16_f32 v64, v64, v65
	v_cvt_pk_bf16_f32 v65, v58, v59
	global_store_dwordx2 v[44:45], v[64:65], off offset:1024
	v_pk_mul_f32 v[64:65], v[114:115], v[42:43] op_sel_hi:[1,0]
	v_pk_mul_f32 v[68:69], v[124:125], v[42:43] op_sel_hi:[1,0]
	v_lshlrev_b32_e32 v58, 16, v62
	v_and_b32_e32 v59, 0xffff0000, v62
	v_lshlrev_b32_e32 v62, 16, v63
	v_and_b32_e32 v63, 0xffff0000, v63
	v_pk_mul_f32 v[68:69], v[14:15], v[68:69]
	v_pk_mul_f32 v[64:65], v[16:17], v[64:65]
	v_pk_mul_f32 v[58:59], v[68:69], v[58:59]
	v_pk_mul_f32 v[62:63], v[64:65], v[62:63]
	v_cvt_pk_bf16_f32 v58, v58, v59
	v_cvt_pk_bf16_f32 v59, v62, v63
	v_pk_mul_f32 v[62:63], v[112:113], v[42:43] op_sel_hi:[1,0]
	v_pk_mul_f32 v[64:65], v[166:167], v[42:43] op_sel_hi:[1,0]
	global_store_dwordx2 v[44:45], v[58:59], off offset:1536
	v_lshlrev_b32_e32 v58, 16, v56
	v_and_b32_e32 v59, 0xffff0000, v56
	v_lshlrev_b32_e32 v56, 16, v57
; template <bool HG>
; __device__ __forceinline__ void readout_phase2(const Args& a, Frame& F, const float* gain, int nrows) {
;     ...
;     RO_FINISH(f2, b2, g2, nw + 2 * 2048); RO_LOAD(f2, b2, g2, nw + 5 * 2048);
	v_and_b32_e32 v57, 0xffff0000, v57
	v_pk_mul_f32 v[64:65], v[18:19], v[64:65]
	v_pk_mul_f32 v[62:63], v[20:21], v[62:63]
	v_pk_mul_f32 v[58:59], v[64:65], v[58:59]
	v_pk_mul_f32 v[56:57], v[62:63], v[56:57]
	v_cvt_pk_bf16_f32 v58, v58, v59
	v_cvt_pk_bf16_f32 v59, v56, v57
	global_store_dwordx2 v[44:45], v[58:59], off offset:2048
	v_pk_mul_f32 v[58:59], v[102:103], v[42:43] op_sel_hi:[1,0]
	v_pk_mul_f32 v[62:63], v[116:117], v[42:43] op_sel_hi:[1,0]
	v_lshlrev_b32_e32 v56, 16, v52
	v_and_b32_e32 v57, 0xffff0000, v52
	v_lshlrev_b32_e32 v52, 16, v53
	v_and_b32_e32 v53, 0xffff0000, v53
	v_pk_mul_f32 v[62:63], v[22:23], v[62:63]
	v_pk_mul_f32 v[58:59], v[24:25], v[58:59]
	v_pk_mul_f32 v[56:57], v[62:63], v[56:57]
	v_pk_mul_f32 v[52:53], v[58:59], v[52:53]
	v_cvt_pk_bf16_f32 v56, v56, v57
	v_cvt_pk_bf16_f32 v57, v52, v53
	global_store_dwordx2 v[44:45], v[56:57], off offset:2560
	v_pk_mul_f32 v[56:57], v[92:93], v[42:43] op_sel_hi:[1,0]
	v_pk_mul_f32 v[58:59], v[132:133], v[42:43] op_sel_hi:[1,0]
	v_lshlrev_b32_e32 v52, 16, v48
	v_and_b32_e32 v53, 0xffff0000, v48
	v_lshlrev_b32_e32 v48, 16, v49
	v_and_b32_e32 v49, 0xffff0000, v49
	v_pk_mul_f32 v[58:59], v[26:27], v[58:59]
	v_pk_mul_f32 v[56:57], v[28:29], v[56:57]
	v_pk_mul_f32 v[52:53], v[58:59], v[52:53]
	v_pk_mul_f32 v[48:49], v[56:57], v[48:49]
	v_cvt_pk_bf16_f32 v52, v52, v53
	v_cvt_pk_bf16_f32 v53, v48, v49
	global_store_dwordx2 v[44:45], v[52:53], off offset:3072
	v_pk_mul_f32 v[52:53], v[86:87], v[42:43] op_sel_hi:[1,0]
	v_pk_mul_f32 v[42:43], v[136:137], v[42:43] op_sel_hi:[1,0]
	s_waitcnt vmcnt(62)
	v_lshlrev_b32_e32 v48, 16, v50
	v_and_b32_e32 v49, 0xffff0000, v50
	v_lshlrev_b32_e32 v50, 16, v51
	v_and_b32_e32 v51, 0xffff0000, v51
	v_pk_mul_f32 v[42:43], v[30:31], v[42:43]
	v_pk_mul_f32 v[52:53], v[32:33], v[52:53]
	v_pk_mul_f32 v[42:43], v[42:43], v[48:49]
	v_pk_mul_f32 v[50:51], v[52:53], v[50:51]
	s_add_u32 s14, s12, 0x2800000
	v_cvt_pk_bf16_f32 v42, v42, v43
	v_cvt_pk_bf16_f32 v43, v50, v51
	s_addc_u32 s15, s13, 0
	global_store_dwordx2 v[44:45], v[42:43], off offset:3584
	v_lshl_add_u64 v[42:43], v[36:37], 0, s[14:15]
	v_lshl_add_u64 v[52:53], v[42:43], 0, v[0:1]
	v_lshl_add_u64 v[42:43], v[38:39], 0, s[14:15]
	v_lshl_add_u64 v[48:49], v[42:43], 0, v[0:1]
	v_lshl_add_u64 v[42:43], v[40:41], 0, s[14:15]
	v_lshl_add_u64 v[42:43], v[42:43], 0, v[0:1]
	global_load_dwordx2 v[166:167], v[52:53], off
	global_load_dwordx2 v[134:135], v[52:53], off offset:512
	global_load_dwordx2 v[128:129], v[52:53], off offset:1024
	global_load_dwordx2 v[112:113], v[52:53], off offset:1536
	global_load_dwordx2 v[172:173], v[48:49], off
	global_load_dwordx2 v[136:137], v[48:49], off offset:512
	global_load_dwordx2 v[130:131], v[48:49], off offset:1024
	global_load_dwordx2 v[114:115], v[48:49], off offset:1536
	global_load_dwordx2 v[62:63], v[42:43], off
	global_load_dwordx2 v[56:57], v[42:43], off offset:512
	global_load_dwordx2 v[50:51], v[42:43], off offset:1024
	global_load_dwordx2 v[44:45], v[42:43], off offset:1536
	global_load_dwordx2 v[102:103], v[52:53], off offset:2048
	global_load_dwordx2 v[84:85], v[52:53], off offset:2560
	global_load_dwordx2 v[78:79], v[52:53], off offset:3072
	global_load_dwordx2 v[70:71], v[52:53], off offset:3584
	v_lshlrev_b32_e32 v52, 16, v168
	v_and_b32_e32 v53, 0xffff0000, v168
	s_waitcnt vmcnt(62)
	v_lshlrev_b32_e32 v58, 16, v174
	v_and_b32_e32 v59, 0xffff0000, v174
	v_pk_add_f32 v[58:59], v[52:53], v[58:59]
	v_lshlrev_b32_e32 v52, 16, v169
	v_and_b32_e32 v53, 0xffff0000, v169
	v_lshlrev_b32_e32 v64, 16, v175
	v_and_b32_e32 v65, 0xffff0000, v175
	v_pk_add_f32 v[68:69], v[52:53], v[64:65]
	v_lshlrev_b32_e32 v52, 16, v162
	v_and_b32_e32 v53, 0xffff0000, v162
	v_lshlrev_b32_e32 v64, 16, v164
	v_and_b32_e32 v65, 0xffff0000, v164
	v_pk_add_f32 v[52:53], v[52:53], v[64:65]
	v_lshlrev_b32_e32 v64, 16, v163
	v_and_b32_e32 v65, 0xffff0000, v163
	v_lshlrev_b32_e32 v86, 16, v165
	v_and_b32_e32 v87, 0xffff0000, v165
	v_pk_add_f32 v[64:65], v[64:65], v[86:87]
	v_mov_b32_e32 v92, v59
	v_mov_b32_e32 v93, v53
	v_mov_b32_e32 v86, v58
	v_mov_b32_e32 v87, v52
	v_pk_mul_f32 v[92:93], v[92:93], v[92:93]
	v_mov_b32_e32 v104, v69
	v_mov_b32_e32 v105, v65
	v_pk_fma_f32 v[86:87], v[86:87], v[86:87], v[92:93]
	v_mov_b32_e32 v92, v68
	v_mov_b32_e32 v93, v64
	v_pk_mul_f32 v[104:105], v[104:105], v[104:105]
	v_lshlrev_b32_e32 v116, 16, v156
	v_pk_fma_f32 v[92:93], v[92:93], v[92:93], v[104:105]
	v_lshlrev_b32_e32 v104, 16, v160
	v_pk_add_f32 v[86:87], v[86:87], v[92:93]
	v_lshlrev_b32_e32 v92, 16, v158
	v_and_b32_e32 v93, 0xffff0000, v158
	v_and_b32_e32 v105, 0xffff0000, v160
	v_pk_add_f32 v[124:125], v[92:93], v[104:105]
	v_lshlrev_b32_e32 v92, 16, v159
	v_and_b32_e32 v93, 0xffff0000, v159
	v_lshlrev_b32_e32 v104, 16, v161
	v_and_b32_e32 v105, 0xffff0000, v161
	v_pk_add_f32 v[158:159], v[92:93], v[104:105]
	v_mov_b32_e32 v104, v125
	v_mov_b32_e32 v105, v159
	v_mov_b32_e32 v92, v124
	v_mov_b32_e32 v93, v158
	v_pk_mul_f32 v[104:105], v[104:105], v[104:105]
	v_and_b32_e32 v117, 0xffff0000, v156
	v_pk_fma_f32 v[92:93], v[92:93], v[92:93], v[104:105]
	v_lshlrev_b32_e32 v104, 16, v154
	v_and_b32_e32 v105, 0xffff0000, v154
	v_pk_add_f32 v[132:133], v[104:105], v[116:117]
	v_lshlrev_b32_e32 v104, 16, v155
	v_and_b32_e32 v105, 0xffff0000, v155
	v_lshlrev_b32_e32 v116, 16, v157
	v_and_b32_e32 v117, 0xffff0000, v157
	v_lshlrev_b32_e32 v156, 16, v152
	v_and_b32_e32 v157, 0xffff0000, v152
	v_lshlrev_b32_e32 v160, 16, v196
	v_and_b32_e32 v161, 0xffff0000, v196
	v_pk_add_f32 v[154:155], v[104:105], v[116:117]
	v_pk_add_f32 v[162:163], v[156:157], v[160:161]
	v_lshlrev_b32_e32 v152, 16, v153
	v_and_b32_e32 v153, 0xffff0000, v153
	v_lshlrev_b32_e32 v156, 16, v197
	v_and_b32_e32 v157, 0xffff0000, v197
	v_mul_f32_e32 v104, v133, v133
	v_mul_f32_e32 v116, v155, v155
	v_pk_add_f32 v[168:169], v[152:153], v[156:157]
	v_pk_add_f32 v[86:87], v[86:87], v[86:87] op_sel:[0,1] op_sel_hi:[1,0]
	v_pk_add_f32 v[92:93], v[92:93], v[92:93] op_sel:[0,1] op_sel_hi:[1,0]
	v_pk_fma_f32 v[104:105], v[132:133], v[132:133], v[104:105] op_sel_hi:[1,1,0]
	v_pk_fma_f32 v[116:117], v[154:155], v[154:155], v[116:117] op_sel_hi:[1,1,0]
	v_pk_mul_f32 v[152:153], v[162:163], v[162:163]
	v_pk_mul_f32 v[156:157], v[168:169], v[168:169]
	v_mov_b32_e32 v87, v152
	v_mov_b32_e32 v93, v153
	v_mov_b32_e32 v105, v156
	v_mov_b32_e32 v117, v157
	v_pk_add_f32 v[86:87], v[86:87], v[92:93]
	v_pk_add_f32 v[92:93], v[104:105], v[116:117]
	v_lshlrev_b32_e32 v104, 16, v192
	v_pk_add_f32 v[86:87], v[86:87], v[92:93]
	v_lshlrev_b32_e32 v92, 16, v150
	v_and_b32_e32 v93, 0xffff0000, v150
	v_and_b32_e32 v105, 0xffff0000, v192
	v_pk_add_f32 v[174:175], v[92:93], v[104:105]
	v_lshlrev_b32_e32 v92, 16, v151
	v_and_b32_e32 v93, 0xffff0000, v151
	v_lshlrev_b32_e32 v104, 16, v193
	v_and_b32_e32 v105, 0xffff0000, v193
	v_pk_add_f32 v[150:151], v[92:93], v[104:105]
	v_mov_b32_e32 v104, v175
	v_mov_b32_e32 v105, v151
	v_mov_b32_e32 v92, v174
	v_mov_b32_e32 v93, v150
	v_pk_mul_f32 v[104:105], v[104:105], v[104:105]
	s_waitcnt vmcnt(61)
	v_lshlrev_b32_e32 v116, 16, v188
	v_pk_fma_f32 v[92:93], v[92:93], v[92:93], v[104:105]
	v_lshlrev_b32_e32 v104, 16, v148
	v_and_b32_e32 v105, 0xffff0000, v148
	v_and_b32_e32 v117, 0xffff0000, v188
	v_pk_add_f32 v[178:179], v[104:105], v[116:117]
	v_lshlrev_b32_e32 v104, 16, v149
	v_and_b32_e32 v105, 0xffff0000, v149
	v_lshlrev_b32_e32 v116, 16, v189
	v_and_b32_e32 v117, 0xffff0000, v189
	v_lshlrev_b32_e32 v152, 16, v140
	v_and_b32_e32 v153, 0xffff0000, v140
	s_waitcnt vmcnt(60)
	v_lshlrev_b32_e32 v156, 16, v184
	v_and_b32_e32 v157, 0xffff0000, v184
	v_pk_add_f32 v[148:149], v[104:105], v[116:117]
	v_pk_add_f32 v[180:181], v[152:153], v[156:157]
	v_lshlrev_b32_e32 v140, 16, v141
	v_and_b32_e32 v141, 0xffff0000, v141
	v_lshlrev_b32_e32 v152, 16, v185
	v_and_b32_e32 v153, 0xffff0000, v185
	v_mul_f32_e32 v104, v179, v179
	v_mul_f32_e32 v116, v149, v149
	v_pk_add_f32 v[140:141], v[140:141], v[152:153]
	v_pk_add_f32 v[86:87], v[86:87], v[86:87] op_sel:[0,1] op_sel_hi:[1,0]
	v_pk_add_f32 v[92:93], v[92:93], v[92:93] op_sel:[0,1] op_sel_hi:[1,0]
	v_pk_fma_f32 v[104:105], v[178:179], v[178:179], v[104:105] op_sel_hi:[1,1,0]
	v_pk_fma_f32 v[116:117], v[148:149], v[148:149], v[116:117] op_sel_hi:[1,1,0]
	v_pk_mul_f32 v[152:153], v[180:181], v[180:181]
	v_pk_mul_f32 v[156:157], v[140:141], v[140:141]
	v_mov_b32_e32 v87, v152
	v_mov_b32_e32 v93, v153
	v_mov_b32_e32 v105, v156
	v_mov_b32_e32 v117, v157
	v_pk_add_f32 v[86:87], v[86:87], v[92:93]
	v_pk_add_f32 v[92:93], v[104:105], v[116:117]
	global_load_dwordx2 v[164:165], v[48:49], off offset:2048
	global_load_dwordx2 v[160:161], v[48:49], off offset:2560
	global_load_dwordx2 v[156:157], v[48:49], off offset:3072
	global_load_dwordx2 v[152:153], v[48:49], off offset:3584
	v_pk_add_f32 v[86:87], v[86:87], v[92:93]
	s_add_u32 s12, s12, 0x3000000
	v_add_f32_e32 v86, v86, v87
	s_addc_u32 s13, s13, 0
	s_nop 0
	v_add_f32_dpp v86, v86, v86 quad_perm:[1,0,3,2] row_mask:0xf bank_mask:0xf bound_ctrl:1
	s_nop 1
	v_add_f32_dpp v86, v86, v86 quad_perm:[2,3,0,1] row_mask:0xf bank_mask:0xf bound_ctrl:1
	s_nop 1
	v_add_f32_dpp v86, v86, v86 row_half_mirror row_mask:0xf bank_mask:0xf bound_ctrl:1
	s_nop 1
	v_add_f32_dpp v86, v86, v86 row_mirror row_mask:0xf bank_mask:0xf bound_ctrl:1
	s_nop 0
	v_readlane_b32 s8, v86, 16
	v_readlane_b32 s9, v86, 48
	v_readlane_b32 s6, v86, 0
	v_readlane_b32 s7, v86, 32
	v_mov_b32_e32 v86, s8
	v_mov_b32_e32 v87, s9
	v_pk_add_f32 v[86:87], s[6:7], v[86:87]
	s_nop 0
	v_add_f32_e32 v86, v86, v87
	v_fmamk_f32 v86, v86, 0x3a000000, v252
	v_mul_f32_e32 v87, 0x4f800000, v86
	v_cmp_gt_f32_e32 vcc, s55, v86
	s_nop 1
	v_cndmask_b32_e32 v86, v86, v87, vcc
	v_sqrt_f32_e32 v87, v86
	s_nop 0
	v_add_u32_e32 v48, -1, v87
	v_fma_f32 v49, -v48, v87, v86
	v_cmp_ge_f32_e64 s[8:9], 0, v49
	v_add_u32_e32 v49, 1, v87
	s_nop 0
	v_cndmask_b32_e64 v48, v87, v48, s[8:9]
	v_fma_f32 v87, -v49, v87, v86
	v_cmp_lt_f32_e64 s[8:9], 0, v87
	s_nop 1
	v_cndmask_b32_e64 v48, v48, v49, s[8:9]
	v_mul_f32_e32 v49, 0x37800000, v48
	v_cndmask_b32_e32 v48, v48, v49, vcc
	v_cmp_class_f32_e32 vcc, v86, v253
	s_nop 1
	v_cndmask_b32_e32 v48, v48, v86, vcc
	v_div_scale_f32 v49, s[6:7], v48, v48, 1.0
	v_rcp_f32_e32 v184, v49
	global_load_dwordx2 v[116:117], v[42:43], off offset:2048
	global_load_dwordx2 v[104:105], v[42:43], off offset:2560
	global_load_dwordx2 v[92:93], v[42:43], off offset:3072
	global_load_dwordx2 v[86:87], v[42:43], off offset:3584
	v_fma_f32 v42, -v49, v184, 1.0
	v_fmac_f32_e32 v184, v42, v184
	v_div_scale_f32 v42, vcc, 1.0, v48, 1.0
	v_mul_f32_e32 v43, v42, v184
	v_fma_f32 v185, -v49, v43, v42
	v_fmac_f32_e32 v43, v185, v184
	v_fma_f32 v42, -v49, v43, v42
	v_div_fmas_f32 v42, v42, v184, v43
	v_div_fixup_f32 v42, v42, v48, 1.0
	v_pk_mul_f32 v[68:69], v[68:69], v[42:43] op_sel_hi:[1,0]
	v_pk_mul_f32 v[58:59], v[58:59], v[42:43] op_sel_hi:[1,0]
	v_lshlrev_b32_e32 v184, 16, v100
	v_and_b32_e32 v185, 0xffff0000, v100
	v_lshlrev_b32_e32 v100, 16, v101
	v_and_b32_e32 v101, 0xffff0000, v101
	v_pk_mul_f32 v[58:59], v[2:3], v[58:59]
	v_pk_mul_f32 v[68:69], v[4:5], v[68:69]
	v_lshl_add_u64 v[48:49], v[34:35], 0, s[16:17]
	v_pk_mul_f32 v[68:69], v[68:69], v[100:101]
	v_pk_mul_f32 v[58:59], v[58:59], v[184:185]
	v_lshl_add_u64 v[48:49], v[48:49], 0, v[0:1]
	v_cvt_pk_bf16_f32 v58, v58, v59
	v_cvt_pk_bf16_f32 v59, v68, v69
	v_pk_mul_f32 v[64:65], v[64:65], v[42:43] op_sel_hi:[1,0]
	v_pk_mul_f32 v[52:53], v[52:53], v[42:43] op_sel_hi:[1,0]
	global_store_dwordx2 v[48:49], v[58:59], off
	v_lshlrev_b32_e32 v58, 16, v90
	v_and_b32_e32 v59, 0xffff0000, v90
	v_lshlrev_b32_e32 v68, 16, v91
	v_and_b32_e32 v69, 0xffff0000, v91
	v_pk_mul_f32 v[52:53], v[6:7], v[52:53]
	v_pk_mul_f32 v[64:65], v[8:9], v[64:65]
	v_pk_mul_f32 v[52:53], v[52:53], v[58:59]
	v_pk_mul_f32 v[64:65], v[64:65], v[68:69]
	v_cvt_pk_bf16_f32 v52, v52, v53
	v_cvt_pk_bf16_f32 v53, v64, v65
	v_pk_mul_f32 v[64:65], v[158:159], v[42:43] op_sel_hi:[1,0]
	v_pk_mul_f32 v[68:69], v[124:125], v[42:43] op_sel_hi:[1,0]
	global_store_dwordx2 v[48:49], v[52:53], off offset:512
	v_lshlrev_b32_e32 v52, 16, v80
	v_and_b32_e32 v53, 0xffff0000, v80
	v_lshlrev_b32_e32 v58, 16, v81
	v_and_b32_e32 v59, 0xffff0000, v81
	v_pk_mul_f32 v[68:69], v[10:11], v[68:69]
	v_pk_mul_f32 v[64:65], v[12:13], v[64:65]
	v_pk_mul_f32 v[52:53], v[68:69], v[52:53]
	v_pk_mul_f32 v[58:59], v[64:65], v[58:59]
	v_cvt_pk_bf16_f32 v52, v52, v53
	v_cvt_pk_bf16_f32 v53, v58, v59
	v_pk_mul_f32 v[64:65], v[154:155], v[42:43] op_sel_hi:[1,0]
	v_pk_mul_f32 v[68:69], v[132:133], v[42:43] op_sel_hi:[1,0]
	global_store_dwordx2 v[48:49], v[52:53], off offset:1024
	v_lshlrev_b32_e32 v52, 16, v76
	v_and_b32_e32 v53, 0xffff0000, v76
	v_lshlrev_b32_e32 v58, 16, v77
	v_and_b32_e32 v59, 0xffff0000, v77
	v_pk_mul_f32 v[68:69], v[14:15], v[68:69]
	v_pk_mul_f32 v[64:65], v[16:17], v[64:65]
	v_pk_mul_f32 v[52:53], v[68:69], v[52:53]
	v_pk_mul_f32 v[58:59], v[64:65], v[58:59]
	v_pk_mul_f32 v[64:65], v[168:169], v[42:43] op_sel_hi:[1,0]
	v_cvt_pk_bf16_f32 v52, v52, v53
	v_cvt_pk_bf16_f32 v53, v58, v59
	s_waitcnt vmcnt(62)
	v_lshlrev_b32_e32 v58, 16, v127
	v_and_b32_e32 v59, 0xffff0000, v127
	v_pk_mul_f32 v[68:69], v[162:163], v[42:43] op_sel_hi:[1,0]
	v_pk_mul_f32 v[64:65], v[20:21], v[64:65]
	global_store_dwordx2 v[48:49], v[52:53], off offset:1536
	v_lshlrev_b32_e32 v52, 16, v126
	v_and_b32_e32 v53, 0xffff0000, v126
	v_pk_mul_f32 v[68:69], v[18:19], v[68:69]
	v_pk_mul_f32 v[58:59], v[64:65], v[58:59]
	v_pk_mul_f32 v[64:65], v[150:151], v[42:43] op_sel_hi:[1,0]
	s_waitcnt vmcnt(59)
	v_lshlrev_b32_e32 v150, 16, v170
	v_and_b32_e32 v151, 0xffff0000, v170
	s_waitcnt vmcnt(55)
	v_lshlrev_b32_e32 v154, 16, v176
	v_and_b32_e32 v155, 0xffff0000, v176
	v_pk_mul_f32 v[52:53], v[68:69], v[52:53]
	v_pk_mul_f32 v[68:69], v[174:175], v[42:43] op_sel_hi:[1,0]
	v_pk_add_f32 v[174:175], v[150:151], v[154:155]
	v_lshlrev_b32_e32 v150, 16, v171
	v_and_b32_e32 v151, 0xffff0000, v171
	v_lshlrev_b32_e32 v154, 16, v177
	v_and_b32_e32 v155, 0xffff0000, v177
	v_pk_add_f32 v[170:171], v[150:151], v[154:155]
	v_lshlrev_b32_e32 v150, 16, v144
	v_and_b32_e32 v151, 0xffff0000, v144
	s_waitcnt vmcnt(54)
	v_lshlrev_b32_e32 v154, 16, v146
	v_and_b32_e32 v155, 0xffff0000, v146
	v_pk_add_f32 v[168:169], v[150:151], v[154:155]
	v_lshlrev_b32_e32 v144, 16, v145
	v_and_b32_e32 v145, 0xffff0000, v145
	v_lshlrev_b32_e32 v146, 16, v147
	v_and_b32_e32 v147, 0xffff0000, v147
	v_pk_add_f32 v[144:145], v[144:145], v[146:147]
	v_mov_b32_e32 v150, v175
	v_mov_b32_e32 v151, v169
	v_mov_b32_e32 v146, v174
	v_mov_b32_e32 v147, v168
	v_pk_mul_f32 v[150:151], v[150:151], v[150:151]
	v_mov_b32_e32 v154, v171
	v_mov_b32_e32 v155, v145
	v_pk_fma_f32 v[146:147], v[146:147], v[146:147], v[150:151]
	v_mov_b32_e32 v150, v170
	v_mov_b32_e32 v151, v144
	v_pk_mul_f32 v[154:155], v[154:155], v[154:155]
	v_cvt_pk_bf16_f32 v52, v52, v53
	v_pk_fma_f32 v[150:151], v[150:151], v[150:151], v[154:155]
	s_waitcnt vmcnt(53)
	v_lshlrev_b32_e32 v154, 16, v142
	v_pk_add_f32 v[146:147], v[146:147], v[150:151]
	v_and_b32_e32 v155, 0xffff0000, v142
	v_pk_add_f32 v[150:151], v[146:147], v[146:147] op_sel:[0,1] op_sel_hi:[1,0]
	v_lshlrev_b32_e32 v146, 16, v138
	v_and_b32_e32 v147, 0xffff0000, v138
	v_lshlrev_b32_e32 v138, 16, v139
	v_and_b32_e32 v139, 0xffff0000, v139
	v_lshlrev_b32_e32 v142, 16, v143
	v_and_b32_e32 v143, 0xffff0000, v143
	v_pk_add_f32 v[146:147], v[146:147], v[154:155]
	v_pk_add_f32 v[142:143], v[138:139], v[142:143]
	v_mov_b32_e32 v154, v147
	v_mov_b32_e32 v155, v143
	v_mov_b32_e32 v138, v146
	v_mov_b32_e32 v139, v142
	v_pk_mul_f32 v[154:155], v[154:155], v[154:155]
	v_cvt_pk_bf16_f32 v53, v58, v59
	v_pk_fma_f32 v[138:139], v[138:139], v[138:139], v[154:155]
	s_waitcnt vmcnt(52)
	v_lshlrev_b32_e32 v158, 16, v120
	v_pk_add_f32 v[154:155], v[138:139], v[138:139] op_sel:[0,1] op_sel_hi:[1,0]
	v_lshlrev_b32_e32 v138, 16, v118
	v_and_b32_e32 v139, 0xffff0000, v118
	v_and_b32_e32 v159, 0xffff0000, v120
	v_lshlrev_b32_e32 v118, 16, v119
	v_and_b32_e32 v119, 0xffff0000, v119
	v_lshlrev_b32_e32 v120, 16, v121
	v_and_b32_e32 v121, 0xffff0000, v121
	s_waitcnt vmcnt(47)
	v_lshlrev_b32_e32 v162, 16, v106
	v_and_b32_e32 v163, 0xffff0000, v106
	s_waitcnt vmcnt(43)
	v_lshlrev_b32_e32 v176, 16, v198
	v_and_b32_e32 v177, 0xffff0000, v198
	global_store_dwordx2 v[48:49], v[52:53], off offset:2048
	v_lshlrev_b32_e32 v52, 16, v108
	v_and_b32_e32 v53, 0xffff0000, v108
	v_pk_mul_f32 v[68:69], v[22:23], v[68:69]
	v_pk_add_f32 v[138:139], v[138:139], v[158:159]
	v_pk_add_f32 v[118:119], v[118:119], v[120:121]
	v_pk_add_f32 v[176:177], v[162:163], v[176:177]
	v_lshlrev_b32_e32 v106, 16, v107
	v_and_b32_e32 v107, 0xffff0000, v107
	v_lshlrev_b32_e32 v162, 16, v199
	v_and_b32_e32 v163, 0xffff0000, v199
	v_pk_mul_f32 v[52:53], v[68:69], v[52:53]
	v_pk_mul_f32 v[68:69], v[178:179], v[42:43] op_sel_hi:[1,0]
	v_mul_f32_e32 v120, v139, v139
	v_mul_f32_e32 v158, v119, v119
	v_pk_add_f32 v[178:179], v[106:107], v[162:163]
	v_pk_fma_f32 v[120:121], v[138:139], v[138:139], v[120:121] op_sel_hi:[1,1,0]
	v_pk_fma_f32 v[158:159], v[118:119], v[118:119], v[158:159] op_sel_hi:[1,1,0]
	v_pk_mul_f32 v[106:107], v[176:177], v[176:177]
	v_pk_mul_f32 v[162:163], v[178:179], v[178:179]
	v_mov_b32_e32 v151, v106
	v_mov_b32_e32 v155, v107
	v_mov_b32_e32 v121, v162
	v_mov_b32_e32 v159, v163
	v_lshlrev_b32_e32 v58, 16, v109
	v_and_b32_e32 v59, 0xffff0000, v109
	v_pk_mul_f32 v[64:65], v[24:25], v[64:65]
	v_pk_add_f32 v[106:107], v[150:151], v[154:155]
	v_pk_add_f32 v[120:121], v[120:121], v[158:159]
	v_pk_mul_f32 v[58:59], v[64:65], v[58:59]
	v_pk_mul_f32 v[64:65], v[148:149], v[42:43] op_sel_hi:[1,0]
	v_pk_add_f32 v[106:107], v[106:107], v[120:121]
	v_lshlrev_b32_e32 v120, 16, v96
	v_and_b32_e32 v121, 0xffff0000, v96
	s_waitcnt vmcnt(43)
	v_lshlrev_b32_e32 v150, 16, v194
	v_and_b32_e32 v151, 0xffff0000, v194
	v_cvt_pk_bf16_f32 v52, v52, v53
	v_cvt_pk_bf16_f32 v53, v58, v59
	v_lshlrev_b32_e32 v58, 16, v99
	v_and_b32_e32 v59, 0xffff0000, v99
	v_pk_mul_f32 v[64:65], v[28:29], v[64:65]
	v_pk_add_f32 v[120:121], v[120:121], v[150:151]
	v_lshlrev_b32_e32 v96, 16, v97
	v_and_b32_e32 v97, 0xffff0000, v97
	v_lshlrev_b32_e32 v150, 16, v195
	v_and_b32_e32 v151, 0xffff0000, v195
	v_pk_mul_f32 v[58:59], v[64:65], v[58:59]
	v_pk_mul_f32 v[64:65], v[140:141], v[42:43] op_sel_hi:[1,0]
	v_pk_mul_f32 v[42:43], v[180:181], v[42:43] op_sel_hi:[1,0]
	v_pk_add_f32 v[180:181], v[96:97], v[150:151]
	v_mov_b32_e32 v150, v121
	v_mov_b32_e32 v151, v181
	v_mov_b32_e32 v96, v120
	v_mov_b32_e32 v97, v180
	v_pk_mul_f32 v[150:151], v[150:151], v[150:151]
	s_waitcnt vmcnt(42)
; template <bool HG>
; __device__ __forceinline__ void readout_phase2(const Args& a, Frame& F, const float* gain, int nrows) {
;     ...
;     RO_FINISH(f0, b0, g0, nw + 3 * 2048); RO_LOAD(f0, b0, g0, nw + 6 * 2048);
	v_lshlrev_b32_e32 v154, 16, v190
	v_pk_fma_f32 v[96:97], v[96:97], v[96:97], v[150:151]
	v_lshlrev_b32_e32 v150, 16, v82
	v_and_b32_e32 v151, 0xffff0000, v82
	v_and_b32_e32 v155, 0xffff0000, v190
	v_pk_add_f32 v[184:185], v[150:151], v[154:155]
	v_lshlrev_b32_e32 v82, 16, v83
	v_and_b32_e32 v83, 0xffff0000, v83
	v_lshlrev_b32_e32 v150, 16, v191
	v_and_b32_e32 v151, 0xffff0000, v191
	v_lshlrev_b32_e32 v154, 16, v72
	v_and_b32_e32 v155, 0xffff0000, v72
	s_waitcnt vmcnt(41)
	v_lshlrev_b32_e32 v158, 16, v186
	v_and_b32_e32 v159, 0xffff0000, v186
	v_pk_add_f32 v[188:189], v[82:83], v[150:151]
	v_pk_add_f32 v[190:191], v[154:155], v[158:159]
	v_lshlrev_b32_e32 v72, 16, v73
	v_and_b32_e32 v73, 0xffff0000, v73
	v_lshlrev_b32_e32 v154, 16, v187
	v_and_b32_e32 v155, 0xffff0000, v187
	v_mul_f32_e32 v82, v185, v185
	v_mul_f32_e32 v150, v189, v189
	v_pk_add_f32 v[186:187], v[72:73], v[154:155]
	v_pk_add_f32 v[106:107], v[106:107], v[106:107] op_sel:[0,1] op_sel_hi:[1,0]
	v_pk_add_f32 v[96:97], v[96:97], v[96:97] op_sel:[0,1] op_sel_hi:[1,0]
	v_pk_fma_f32 v[82:83], v[184:185], v[184:185], v[82:83] op_sel_hi:[1,1,0]
	v_pk_fma_f32 v[150:151], v[188:189], v[188:189], v[150:151] op_sel_hi:[1,1,0]
	v_pk_mul_f32 v[72:73], v[190:191], v[190:191]
	v_pk_mul_f32 v[154:155], v[186:187], v[186:187]
	v_mov_b32_e32 v107, v72
	v_mov_b32_e32 v97, v73
	v_mov_b32_e32 v83, v154
	v_mov_b32_e32 v151, v155
	v_pk_add_f32 v[72:73], v[106:107], v[96:97]
	v_pk_add_f32 v[82:83], v[82:83], v[150:151]
	global_store_dwordx2 v[48:49], v[52:53], off offset:2560
	v_pk_add_f32 v[72:73], v[72:73], v[82:83]
	v_lshlrev_b32_e32 v52, 16, v98
	v_add_f32_e32 v72, v72, v73
	v_and_b32_e32 v53, 0xffff0000, v98
	v_pk_mul_f32 v[68:69], v[26:27], v[68:69]
	v_add_f32_dpp v72, v72, v72 quad_perm:[1,0,3,2] row_mask:0xf bank_mask:0xf bound_ctrl:1
	v_pk_mul_f32 v[52:53], v[68:69], v[52:53]
	v_pk_mul_f32 v[42:43], v[30:31], v[42:43]
	v_add_f32_dpp v72, v72, v72 quad_perm:[2,3,0,1] row_mask:0xf bank_mask:0xf bound_ctrl:1
	v_cvt_pk_bf16_f32 v52, v52, v53
	v_cvt_pk_bf16_f32 v53, v58, v59
	v_add_f32_dpp v72, v72, v72 row_half_mirror row_mask:0xf bank_mask:0xf bound_ctrl:1
	global_store_dwordx2 v[48:49], v[52:53], off offset:3072
	v_lshlrev_b32_e32 v52, 16, v74
	v_add_f32_dpp v72, v72, v72 row_mirror row_mask:0xf bank_mask:0xf bound_ctrl:1
	v_and_b32_e32 v53, 0xffff0000, v74
	v_readlane_b32 s8, v72, 16
	v_readlane_b32 s9, v72, 48
	v_readlane_b32 s6, v72, 0
	v_readlane_b32 s7, v72, 32
	v_mov_b32_e32 v72, s8
	v_mov_b32_e32 v73, s9
	v_pk_add_f32 v[72:73], s[6:7], v[72:73]
	v_lshlrev_b32_e32 v58, 16, v75
	v_add_f32_e32 v72, v72, v73
	v_fmamk_f32 v72, v72, 0x3a000000, v252
	v_and_b32_e32 v59, 0xffff0000, v75
	v_pk_mul_f32 v[64:65], v[32:33], v[64:65]
	v_mul_f32_e32 v73, 0x4f800000, v72
	v_cmp_gt_f32_e32 vcc, s55, v72
	v_pk_mul_f32 v[58:59], v[64:65], v[58:59]
	v_pk_mul_f32 v[42:43], v[42:43], v[52:53]
	v_cndmask_b32_e32 v72, v72, v73, vcc
	v_cvt_pk_bf16_f32 v42, v42, v43
	v_cvt_pk_bf16_f32 v43, v58, v59
	v_sqrt_f32_e32 v73, v72
	global_store_dwordx2 v[48:49], v[42:43], off offset:3584
	v_lshl_add_u64 v[42:43], v[36:37], 0, s[12:13]
	v_lshl_add_u64 v[68:69], v[42:43], 0, v[0:1]
	v_lshl_add_u64 v[42:43], v[38:39], 0, s[12:13]
	v_lshl_add_u64 v[80:81], v[42:43], 0, v[0:1]
	v_lshl_add_u64 v[42:43], v[40:41], 0, s[12:13]
	v_lshl_add_u64 v[64:65], v[42:43], 0, v[0:1]
	global_load_dwordx2 v[140:141], v[68:69], off
	global_load_dwordx2 v[126:127], v[68:69], off offset:512
	global_load_dwordx2 v[108:109], v[68:69], off offset:1024
	global_load_dwordx2 v[98:99], v[68:69], off offset:1536
	global_load_dwordx2 v[148:149], v[80:81], off
	global_load_dwordx2 v[132:133], v[80:81], off offset:512
	global_load_dwordx2 v[124:125], v[80:81], off offset:1024
	global_load_dwordx2 v[100:101], v[80:81], off offset:1536
	global_load_dwordx2 v[58:59], v[64:65], off
	global_load_dwordx2 v[52:53], v[64:65], off offset:512
	global_load_dwordx2 v[48:49], v[64:65], off offset:1024
	global_load_dwordx2 v[42:43], v[64:65], off offset:1536
	global_load_dwordx2 v[90:91], v[68:69], off offset:2048
	global_load_dwordx2 v[76:77], v[68:69], off offset:2560
	global_load_dwordx2 v[74:75], v[68:69], off offset:3072
	s_nop 0
	global_load_dwordx2 v[68:69], v[68:69], off offset:3584
	s_nop 0
	global_load_dwordx2 v[162:163], v[80:81], off offset:2048
	global_load_dwordx2 v[158:159], v[80:81], off offset:2560
	global_load_dwordx2 v[154:155], v[80:81], off offset:3072
	global_load_dwordx2 v[150:151], v[80:81], off offset:3584
	v_add_u32_e32 v80, -1, v73
	v_fma_f32 v81, -v80, v73, v72
	v_cmp_ge_f32_e64 s[8:9], 0, v81
	v_add_u32_e32 v81, 1, v73
	s_nop 0
	v_cndmask_b32_e64 v80, v73, v80, s[8:9]
	v_fma_f32 v73, -v81, v73, v72
	v_cmp_lt_f32_e64 s[8:9], 0, v73
	s_nop 1
	v_cndmask_b32_e64 v73, v80, v81, s[8:9]
	v_mul_f32_e32 v80, 0x37800000, v73
	v_cndmask_b32_e32 v73, v73, v80, vcc
	v_cmp_class_f32_e32 vcc, v72, v253
	s_nop 1
	v_cndmask_b32_e32 v80, v73, v72, vcc
	v_div_scale_f32 v81, s[6:7], v80, v80, 1.0
	v_rcp_f32_e32 v192, v81
	global_load_dwordx2 v[106:107], v[64:65], off offset:2048
	global_load_dwordx2 v[96:97], v[64:65], off offset:2560
	global_load_dwordx2 v[82:83], v[64:65], off offset:3072
	global_load_dwordx2 v[72:73], v[64:65], off offset:3584
	v_fma_f32 v64, -v81, v192, 1.0
	v_fmac_f32_e32 v192, v64, v192
	v_div_scale_f32 v64, vcc, 1.0, v80, 1.0
	v_mul_f32_e32 v65, v64, v192
	v_fma_f32 v193, -v81, v65, v64
	v_fmac_f32_e32 v65, v193, v192
	v_fma_f32 v64, -v81, v65, v64
	v_div_fmas_f32 v64, v64, v192, v65
	v_div_fixup_f32 v64, v64, v80, 1.0
	v_pk_mul_f32 v[170:171], v[170:171], v[64:65] op_sel_hi:[1,0]
	v_pk_mul_f32 v[174:175], v[174:175], v[64:65] op_sel_hi:[1,0]
	v_lshlrev_b32_e32 v192, 16, v66
	v_and_b32_e32 v193, 0xffff0000, v66
	v_lshlrev_b32_e32 v66, 16, v67
	v_and_b32_e32 v67, 0xffff0000, v67
	v_pk_mul_f32 v[174:175], v[2:3], v[174:175]
	v_pk_mul_f32 v[170:171], v[4:5], v[170:171]
	v_pk_mul_f32 v[144:145], v[144:145], v[64:65] op_sel_hi:[1,0]
	v_pk_mul_f32 v[66:67], v[170:171], v[66:67]
	v_pk_mul_f32 v[170:171], v[174:175], v[192:193]
	v_pk_mul_f32 v[168:169], v[168:169], v[64:65] op_sel_hi:[1,0]
	v_cvt_pk_bf16_f32 v170, v170, v171
	v_cvt_pk_bf16_f32 v171, v66, v67
	v_lshlrev_b32_e32 v66, 16, v60
	v_and_b32_e32 v67, 0xffff0000, v60
	v_lshlrev_b32_e32 v60, 16, v61
	v_and_b32_e32 v61, 0xffff0000, v61
	v_pk_mul_f32 v[168:169], v[6:7], v[168:169]
	v_pk_mul_f32 v[144:145], v[8:9], v[144:145]
	v_lshl_add_u64 v[80:81], v[34:35], 0, s[18:19]
	v_pk_mul_f32 v[60:61], v[144:145], v[60:61]
	v_pk_mul_f32 v[66:67], v[168:169], v[66:67]
	v_lshl_add_u64 v[80:81], v[80:81], 0, v[0:1]
	v_cvt_pk_bf16_f32 v66, v66, v67
	v_cvt_pk_bf16_f32 v67, v60, v61
	global_store_dwordx2 v[80:81], v[66:67], off offset:512
	v_pk_mul_f32 v[66:67], v[142:143], v[64:65] op_sel_hi:[1,0]
	v_pk_mul_f32 v[142:143], v[146:147], v[64:65] op_sel_hi:[1,0]
	v_lshlrev_b32_e32 v60, 16, v54
	v_and_b32_e32 v61, 0xffff0000, v54
	v_lshlrev_b32_e32 v54, 16, v55
	v_and_b32_e32 v55, 0xffff0000, v55
	v_pk_mul_f32 v[142:143], v[10:11], v[142:143]
	v_pk_mul_f32 v[66:67], v[12:13], v[66:67]
	v_pk_mul_f32 v[60:61], v[142:143], v[60:61]
	v_pk_mul_f32 v[54:55], v[66:67], v[54:55]
	v_pk_mul_f32 v[66:67], v[138:139], v[64:65] op_sel_hi:[1,0]
	v_cvt_pk_bf16_f32 v60, v60, v61
	v_cvt_pk_bf16_f32 v61, v54, v55
	v_lshlrev_b32_e32 v54, 16, v46
	v_and_b32_e32 v55, 0xffff0000, v46
	v_pk_mul_f32 v[66:67], v[14:15], v[66:67]
	s_waitcnt vmcnt(56)
	v_lshlrev_b32_e32 v174, 16, v166
	v_pk_mul_f32 v[54:55], v[66:67], v[54:55]
	v_pk_mul_f32 v[66:67], v[176:177], v[64:65] op_sel_hi:[1,0]
	v_and_b32_e32 v175, 0xffff0000, v166
	s_waitcnt vmcnt(52)
	v_lshlrev_b32_e32 v176, 16, v172
	v_and_b32_e32 v177, 0xffff0000, v172
	v_lshlrev_b32_e32 v166, 16, v167
	v_and_b32_e32 v167, 0xffff0000, v167
	v_lshlrev_b32_e32 v172, 16, v173
	v_and_b32_e32 v173, 0xffff0000, v173
	v_pk_add_f32 v[174:175], v[174:175], v[176:177]
	v_pk_add_f32 v[172:173], v[166:167], v[172:173]
	v_lshlrev_b32_e32 v166, 16, v134
	v_and_b32_e32 v167, 0xffff0000, v134
	s_waitcnt vmcnt(51)
	v_lshlrev_b32_e32 v176, 16, v136
	v_and_b32_e32 v177, 0xffff0000, v136
	global_store_dwordx2 v[80:81], v[60:61], off offset:1024
	v_pk_mul_f32 v[60:61], v[118:119], v[64:65] op_sel_hi:[1,0]
	v_pk_add_f32 v[166:167], v[166:167], v[176:177]
	v_lshlrev_b32_e32 v134, 16, v135
	v_and_b32_e32 v135, 0xffff0000, v135
	v_lshlrev_b32_e32 v136, 16, v137
	v_and_b32_e32 v137, 0xffff0000, v137
	v_lshlrev_b32_e32 v46, 16, v47
	v_and_b32_e32 v47, 0xffff0000, v47
	v_pk_mul_f32 v[60:61], v[16:17], v[60:61]
	v_pk_add_f32 v[134:135], v[134:135], v[136:137]
	v_mov_b32_e32 v176, v175
	v_mov_b32_e32 v177, v167
	v_pk_mul_f32 v[46:47], v[60:61], v[46:47]
	v_pk_mul_f32 v[60:61], v[178:179], v[64:65] op_sel_hi:[1,0]
	v_mov_b32_e32 v136, v174
	v_mov_b32_e32 v137, v166
	v_pk_mul_f32 v[176:177], v[176:177], v[176:177]
	v_mov_b32_e32 v178, v173
	v_mov_b32_e32 v179, v135
	v_pk_fma_f32 v[136:137], v[136:137], v[136:137], v[176:177]
	v_mov_b32_e32 v176, v172
	v_mov_b32_e32 v177, v134
	v_pk_mul_f32 v[178:179], v[178:179], v[178:179]
	v_cvt_pk_bf16_f32 v54, v54, v55
	v_cvt_pk_bf16_f32 v55, v46, v47
	v_pk_fma_f32 v[176:177], v[176:177], v[176:177], v[178:179]
	global_store_dwordx2 v[80:81], v[54:55], off offset:1536
	v_lshlrev_b32_e32 v46, 16, v122
	v_and_b32_e32 v47, 0xffff0000, v122
	v_lshlrev_b32_e32 v54, 16, v123
	v_and_b32_e32 v55, 0xffff0000, v123
	v_pk_mul_f32 v[66:67], v[18:19], v[66:67]
	v_pk_mul_f32 v[60:61], v[20:21], v[60:61]
	v_pk_add_f32 v[136:137], v[136:137], v[176:177]
	v_lshlrev_b32_e32 v176, 16, v128
	v_and_b32_e32 v177, 0xffff0000, v128
	s_waitcnt vmcnt(52)
	v_lshlrev_b32_e32 v178, 16, v130
	v_and_b32_e32 v179, 0xffff0000, v130
	v_lshlrev_b32_e32 v128, 16, v129
	v_and_b32_e32 v129, 0xffff0000, v129
	v_lshlrev_b32_e32 v130, 16, v131
	v_and_b32_e32 v131, 0xffff0000, v131
	v_pk_mul_f32 v[54:55], v[60:61], v[54:55]
	v_pk_mul_f32 v[46:47], v[66:67], v[46:47]
	v_pk_add_f32 v[176:177], v[176:177], v[178:179]
	v_pk_add_f32 v[130:131], v[128:129], v[130:131]
	v_cvt_pk_bf16_f32 v46, v46, v47
	v_cvt_pk_bf16_f32 v47, v54, v55
	v_pk_mul_f32 v[60:61], v[180:181], v[64:65] op_sel_hi:[1,0]
	v_pk_mul_f32 v[66:67], v[120:121], v[64:65] op_sel_hi:[1,0]
	v_mov_b32_e32 v178, v177
	v_mov_b32_e32 v179, v131
	global_store_dwordx2 v[80:81], v[46:47], off offset:2048
	v_lshlrev_b32_e32 v46, 16, v110
	v_and_b32_e32 v47, 0xffff0000, v110
	v_lshlrev_b32_e32 v54, 16, v111
	v_and_b32_e32 v55, 0xffff0000, v111
	v_pk_mul_f32 v[66:67], v[22:23], v[66:67]
	v_pk_mul_f32 v[60:61], v[24:25], v[60:61]
	v_mov_b32_e32 v128, v176
	v_mov_b32_e32 v129, v130
	v_pk_mul_f32 v[178:179], v[178:179], v[178:179]
	v_pk_mul_f32 v[54:55], v[60:61], v[54:55]
	v_pk_mul_f32 v[46:47], v[66:67], v[46:47]
	v_pk_mul_f32 v[60:61], v[188:189], v[64:65] op_sel_hi:[1,0]
	v_pk_fma_f32 v[128:129], v[128:129], v[128:129], v[178:179]
	v_cvt_pk_bf16_f32 v46, v46, v47
	v_cvt_pk_bf16_f32 v47, v54, v55
	v_lshlrev_b32_e32 v54, 16, v95
	v_and_b32_e32 v55, 0xffff0000, v95
	v_pk_mul_f32 v[60:61], v[28:29], v[60:61]
	v_pk_add_f32 v[178:179], v[128:129], v[128:129] op_sel:[0,1] op_sel_hi:[1,0]
	v_lshlrev_b32_e32 v128, 16, v112
	v_and_b32_e32 v129, 0xffff0000, v112
	s_waitcnt vmcnt(52)
; template <bool HG>
; __device__ __forceinline__ void readout_phase2(const Args& a, Frame& F, const float* gain, int nrows) {
;     ...
;     RO_FINISH(f1, b1, g1, nw + 4 * 2048); RO_LOAD(f1, b1, g1, nw + 7 * 2048);
	v_lshlrev_b32_e32 v180, 16, v114
	v_and_b32_e32 v181, 0xffff0000, v114
	v_lshlrev_b32_e32 v112, 16, v113
	v_and_b32_e32 v113, 0xffff0000, v113
	v_lshlrev_b32_e32 v114, 16, v115
	v_and_b32_e32 v115, 0xffff0000, v115
	v_pk_mul_f32 v[66:67], v[184:185], v[64:65] op_sel_hi:[1,0]
	v_pk_mul_f32 v[54:55], v[60:61], v[54:55]
	v_pk_mul_f32 v[60:61], v[186:187], v[64:65] op_sel_hi:[1,0]
	v_pk_add_f32 v[128:129], v[128:129], v[180:181]
	v_pk_add_f32 v[112:113], v[112:113], v[114:115]
	s_waitcnt vmcnt(47)
	v_lshlrev_b32_e32 v184, 16, v102
	v_and_b32_e32 v185, 0xffff0000, v102
	s_waitcnt vmcnt(43)
	v_lshlrev_b32_e32 v186, 16, v164
	v_and_b32_e32 v187, 0xffff0000, v164
	v_lshlrev_b32_e32 v102, 16, v103
	v_and_b32_e32 v103, 0xffff0000, v103
	v_lshlrev_b32_e32 v164, 16, v165
	v_and_b32_e32 v165, 0xffff0000, v165
	v_mul_f32_e32 v114, v129, v129
	v_mul_f32_e32 v180, v113, v113
	v_pk_add_f32 v[184:185], v[184:185], v[186:187]
	v_pk_add_f32 v[164:165], v[102:103], v[164:165]
	v_pk_add_f32 v[136:137], v[136:137], v[136:137] op_sel:[0,1] op_sel_hi:[1,0]
	v_pk_fma_f32 v[114:115], v[128:129], v[128:129], v[114:115] op_sel_hi:[1,1,0]
	v_pk_fma_f32 v[180:181], v[112:113], v[112:113], v[180:181] op_sel_hi:[1,1,0]
	v_pk_mul_f32 v[102:103], v[184:185], v[184:185]
	v_pk_mul_f32 v[186:187], v[164:165], v[164:165]
	v_mov_b32_e32 v137, v102
	v_mov_b32_e32 v179, v103
	v_mov_b32_e32 v115, v186
	v_mov_b32_e32 v181, v187
	v_pk_add_f32 v[102:103], v[136:137], v[178:179]
	v_pk_add_f32 v[114:115], v[114:115], v[180:181]
	s_waitcnt vmcnt(42)
	v_lshlrev_b32_e32 v136, 16, v160
	v_pk_add_f32 v[102:103], v[102:103], v[114:115]
	v_lshlrev_b32_e32 v114, 16, v84
	v_and_b32_e32 v115, 0xffff0000, v84
	v_and_b32_e32 v137, 0xffff0000, v160
	v_pk_add_f32 v[114:115], v[114:115], v[136:137]
	v_lshlrev_b32_e32 v84, 16, v85
	v_and_b32_e32 v85, 0xffff0000, v85
	v_lshlrev_b32_e32 v136, 16, v161
	v_and_b32_e32 v137, 0xffff0000, v161
	v_pk_add_f32 v[178:179], v[84:85], v[136:137]
	v_mov_b32_e32 v136, v115
	v_mov_b32_e32 v137, v179
	v_mov_b32_e32 v84, v114
	v_mov_b32_e32 v85, v178
	v_pk_mul_f32 v[136:137], v[136:137], v[136:137]
	s_waitcnt vmcnt(41)
	v_lshlrev_b32_e32 v160, 16, v156
	v_pk_fma_f32 v[84:85], v[84:85], v[84:85], v[136:137]
	v_lshlrev_b32_e32 v136, 16, v78
	v_and_b32_e32 v137, 0xffff0000, v78
	v_and_b32_e32 v161, 0xffff0000, v156
	v_pk_add_f32 v[180:181], v[136:137], v[160:161]
	v_lshlrev_b32_e32 v78, 16, v79
	v_and_b32_e32 v79, 0xffff0000, v79
	v_lshlrev_b32_e32 v136, 16, v157
	v_and_b32_e32 v137, 0xffff0000, v157
	v_pk_add_f32 v[186:187], v[78:79], v[136:137]
	v_lshlrev_b32_e32 v156, 16, v70
	v_and_b32_e32 v157, 0xffff0000, v70
	s_waitcnt vmcnt(40)
	v_lshlrev_b32_e32 v160, 16, v152
	v_and_b32_e32 v161, 0xffff0000, v152
	v_lshlrev_b32_e32 v70, 16, v71
	v_and_b32_e32 v71, 0xffff0000, v71
	v_lshlrev_b32_e32 v152, 16, v153
	v_and_b32_e32 v153, 0xffff0000, v153
	v_pk_mul_f32 v[64:65], v[190:191], v[64:65] op_sel_hi:[1,0]
	v_mul_f32_e32 v78, v181, v181
	v_mul_f32_e32 v136, v187, v187
	v_pk_add_f32 v[188:189], v[156:157], v[160:161]
	v_pk_add_f32 v[190:191], v[70:71], v[152:153]
	v_pk_add_f32 v[102:103], v[102:103], v[102:103] op_sel:[0,1] op_sel_hi:[1,0]
	v_pk_add_f32 v[84:85], v[84:85], v[84:85] op_sel:[0,1] op_sel_hi:[1,0]
	v_pk_fma_f32 v[78:79], v[180:181], v[180:181], v[78:79] op_sel_hi:[1,1,0]
	v_pk_fma_f32 v[136:137], v[186:187], v[186:187], v[136:137] op_sel_hi:[1,1,0]
	v_pk_mul_f32 v[70:71], v[188:189], v[188:189]
	v_pk_mul_f32 v[152:153], v[190:191], v[190:191]
	v_mov_b32_e32 v103, v70
	v_mov_b32_e32 v85, v71
	v_mov_b32_e32 v79, v152
	v_mov_b32_e32 v137, v153
	v_pk_add_f32 v[70:71], v[102:103], v[84:85]
	v_pk_add_f32 v[78:79], v[78:79], v[136:137]
	global_store_dwordx2 v[80:81], v[46:47], off offset:2560
	v_pk_add_f32 v[70:71], v[70:71], v[78:79]
	v_lshlrev_b32_e32 v46, 16, v94
	v_add_f32_e32 v70, v70, v71
	v_and_b32_e32 v47, 0xffff0000, v94
	v_pk_mul_f32 v[66:67], v[26:27], v[66:67]
	v_add_f32_dpp v70, v70, v70 quad_perm:[1,0,3,2] row_mask:0xf bank_mask:0xf bound_ctrl:1
	v_pk_mul_f32 v[46:47], v[66:67], v[46:47]
	v_pk_mul_f32 v[64:65], v[30:31], v[64:65]
	v_add_f32_dpp v70, v70, v70 quad_perm:[2,3,0,1] row_mask:0xf bank_mask:0xf bound_ctrl:1
	v_cvt_pk_bf16_f32 v46, v46, v47
	v_cvt_pk_bf16_f32 v47, v54, v55
	v_add_f32_dpp v70, v70, v70 row_half_mirror row_mask:0xf bank_mask:0xf bound_ctrl:1
	global_store_dwordx2 v[80:81], v[46:47], off offset:3072
	v_lshlrev_b32_e32 v46, 16, v88
	v_add_f32_dpp v70, v70, v70 row_mirror row_mask:0xf bank_mask:0xf bound_ctrl:1
	v_and_b32_e32 v47, 0xffff0000, v88
	v_readlane_b32 s8, v70, 16
	v_readlane_b32 s9, v70, 48
	v_readlane_b32 s6, v70, 0
	v_readlane_b32 s7, v70, 32
	v_mov_b32_e32 v70, s8
	v_mov_b32_e32 v71, s9
	v_pk_add_f32 v[70:71], s[6:7], v[70:71]
	v_lshlrev_b32_e32 v54, 16, v89
	v_add_f32_e32 v70, v70, v71
	v_fmamk_f32 v70, v70, 0x3a000000, v252
	v_mul_f32_e32 v71, 0x4f800000, v70
	v_cmp_gt_f32_e32 vcc, s55, v70
	v_and_b32_e32 v55, 0xffff0000, v89
	v_pk_mul_f32 v[60:61], v[32:33], v[60:61]
	v_cndmask_b32_e32 v70, v70, v71, vcc
	v_sqrt_f32_e32 v71, v70
	s_add_i32 s18, s10, 0x3800
	v_pk_mul_f32 v[54:55], v[60:61], v[54:55]
	v_pk_mul_f32 v[46:47], v[64:65], v[46:47]
	v_add_u32_e32 v78, -1, v71
	v_fma_f32 v79, -v78, v71, v70
	v_cmp_ge_f32_e64 s[8:9], 0, v79
	v_add_u32_e32 v79, 1, v71
	s_ashr_i32 s19, s18, 31
	v_cndmask_b32_e64 v78, v71, v78, s[8:9]
	v_fma_f32 v71, -v79, v71, v70
	v_cvt_pk_bf16_f32 v46, v46, v47
	v_cvt_pk_bf16_f32 v47, v54, v55
	s_lshl_b64 s[16:17], s[18:19], 12
	v_cmp_lt_f32_e64 s[8:9], 0, v71
	global_store_dwordx2 v[80:81], v[46:47], off offset:3584
	v_lshl_add_u64 v[46:47], v[36:37], 0, s[16:17]
	v_cndmask_b32_e64 v71, v78, v79, s[8:9]
; template <bool HG>
; __device__ __forceinline__ void readout_phase2(const Args& a, Frame& F, const float* gain, int nrows) {
;     ...
;     RO_FINISH(f1, b1, g1, nw + 4 * 2048); RO_LOAD(f1, b1, g1, nw + 7 * 2048);
;     RO_FINISH(f2, b2, g2, nw + 5 * 2048);
;     const bool cx = ML + nw < nrows;
;     RO_LOAD(f2, b2, g2, cx ? ML + nw : nw + 7 * 2048);
	v_lshl_add_u64 v[66:67], v[46:47], 0, v[0:1]
	v_lshl_add_u64 v[46:47], v[38:39], 0, s[16:17]
	v_mul_f32_e32 v78, 0x37800000, v71
	global_store_dwordx2 v[80:81], v[170:171], off
	v_lshl_add_u64 v[170:171], v[46:47], 0, v[0:1]
	v_lshl_add_u64 v[46:47], v[40:41], 0, s[16:17]
	v_cndmask_b32_e32 v71, v71, v78, vcc
	v_cmp_class_f32_e32 vcc, v70, v253
	v_lshl_add_u64 v[168:169], v[46:47], 0, v[0:1]
	global_load_dwordx2 v[144:145], v[66:67], off
	global_load_dwordx2 v[138:139], v[66:67], off offset:512
	global_load_dwordx2 v[120:121], v[66:67], off offset:1024
	global_load_dwordx2 v[110:111], v[66:67], off offset:1536
	global_load_dwordx2 v[146:147], v[170:171], off
	global_load_dwordx2 v[142:143], v[170:171], off offset:512
	global_load_dwordx2 v[122:123], v[170:171], off offset:1024
	global_load_dwordx2 v[118:119], v[170:171], off offset:1536
	global_load_dwordx2 v[64:65], v[168:169], off
	global_load_dwordx2 v[60:61], v[168:169], off offset:512
	global_load_dwordx2 v[54:55], v[168:169], off offset:1024
	global_load_dwordx2 v[46:47], v[168:169], off offset:1536
	global_load_dwordx2 v[94:95], v[66:67], off offset:2048
	global_load_dwordx2 v[88:89], v[66:67], off offset:2560
	global_load_dwordx2 v[80:81], v[66:67], off offset:3072
	s_nop 0
	global_load_dwordx2 v[66:67], v[66:67], off offset:3584
	s_nop 0
	global_load_dwordx2 v[160:161], v[170:171], off offset:2048
	global_load_dwordx2 v[156:157], v[170:171], off offset:2560
	global_load_dwordx2 v[152:153], v[170:171], off offset:3072
	global_load_dwordx2 v[136:137], v[170:171], off offset:3584
	v_cndmask_b32_e32 v170, v71, v70, vcc
	v_div_scale_f32 v171, s[6:7], v170, v170, 1.0
	v_rcp_f32_e32 v192, v171
	global_load_dwordx2 v[102:103], v[168:169], off offset:2048
	global_load_dwordx2 v[84:85], v[168:169], off offset:2560
	global_load_dwordx2 v[78:79], v[168:169], off offset:3072
	global_load_dwordx2 v[70:71], v[168:169], off offset:3584
	s_addk_i32 s10, 0x4000
	s_cmp_lt_i32 s10, s47
	v_fma_f32 v168, -v171, v192, 1.0
	v_fmac_f32_e32 v192, v168, v192
	v_div_scale_f32 v168, vcc, 1.0, v170, 1.0
	v_mul_f32_e32 v169, v168, v192
	v_fma_f32 v193, -v171, v169, v168
	v_fmac_f32_e32 v169, v193, v192
	v_fma_f32 v168, -v171, v169, v168
	v_div_fmas_f32 v168, v168, v192, v169
	v_div_fixup_f32 v168, v168, v170, 1.0
	v_pk_mul_f32 v[172:173], v[172:173], v[168:169] op_sel_hi:[1,0]
	v_pk_mul_f32 v[174:175], v[174:175], v[168:169] op_sel_hi:[1,0]
	v_lshlrev_b32_e32 v192, 16, v62
	v_and_b32_e32 v193, 0xffff0000, v62
	v_lshlrev_b32_e32 v62, 16, v63
	v_and_b32_e32 v63, 0xffff0000, v63
	v_pk_mul_f32 v[174:175], v[2:3], v[174:175]
	v_pk_mul_f32 v[172:173], v[4:5], v[172:173]
	v_pk_mul_f32 v[134:135], v[134:135], v[168:169] op_sel_hi:[1,0]
	v_pk_mul_f32 v[62:63], v[172:173], v[62:63]
	v_pk_mul_f32 v[172:173], v[174:175], v[192:193]
	v_pk_mul_f32 v[166:167], v[166:167], v[168:169] op_sel_hi:[1,0]
	v_cvt_pk_bf16_f32 v172, v172, v173
	v_cvt_pk_bf16_f32 v173, v62, v63
	v_lshlrev_b32_e32 v62, 16, v56
	v_and_b32_e32 v63, 0xffff0000, v56
	v_lshlrev_b32_e32 v56, 16, v57
	v_and_b32_e32 v57, 0xffff0000, v57
	v_pk_mul_f32 v[166:167], v[6:7], v[166:167]
	v_pk_mul_f32 v[134:135], v[8:9], v[134:135]
	v_lshl_add_u64 v[170:171], v[34:35], 0, s[14:15]
	v_pk_mul_f32 v[56:57], v[134:135], v[56:57]
	v_pk_mul_f32 v[62:63], v[166:167], v[62:63]
	v_lshl_add_u64 v[170:171], v[170:171], 0, v[0:1]
	v_cvt_pk_bf16_f32 v62, v62, v63
	v_cvt_pk_bf16_f32 v63, v56, v57
	global_store_dwordx2 v[170:171], v[62:63], off offset:512
	v_pk_mul_f32 v[62:63], v[130:131], v[168:169] op_sel_hi:[1,0]
	v_pk_mul_f32 v[130:131], v[176:177], v[168:169] op_sel_hi:[1,0]
	v_lshlrev_b32_e32 v56, 16, v50
	v_and_b32_e32 v57, 0xffff0000, v50
	v_lshlrev_b32_e32 v50, 16, v51
	v_and_b32_e32 v51, 0xffff0000, v51
	v_pk_mul_f32 v[130:131], v[10:11], v[130:131]
	v_pk_mul_f32 v[62:63], v[12:13], v[62:63]
	v_pk_mul_f32 v[56:57], v[130:131], v[56:57]
	v_pk_mul_f32 v[50:51], v[62:63], v[50:51]
	v_cvt_pk_bf16_f32 v56, v56, v57
	v_cvt_pk_bf16_f32 v57, v50, v51
	global_store_dwordx2 v[170:171], v[56:57], off offset:1024
	v_pk_mul_f32 v[56:57], v[112:113], v[168:169] op_sel_hi:[1,0]
	v_pk_mul_f32 v[62:63], v[128:129], v[168:169] op_sel_hi:[1,0]
	v_lshlrev_b32_e32 v50, 16, v44
	v_and_b32_e32 v51, 0xffff0000, v44
	v_lshlrev_b32_e32 v44, 16, v45
	v_and_b32_e32 v45, 0xffff0000, v45
	v_pk_mul_f32 v[62:63], v[14:15], v[62:63]
	v_pk_mul_f32 v[56:57], v[16:17], v[56:57]
	v_pk_mul_f32 v[50:51], v[62:63], v[50:51]
	v_pk_mul_f32 v[44:45], v[56:57], v[44:45]
	v_cvt_pk_bf16_f32 v50, v50, v51
	v_cvt_pk_bf16_f32 v51, v44, v45
	v_pk_mul_f32 v[56:57], v[164:165], v[168:169] op_sel_hi:[1,0]
	v_pk_mul_f32 v[62:63], v[184:185], v[168:169] op_sel_hi:[1,0]
	global_store_dwordx2 v[170:171], v[50:51], off offset:1536
	s_waitcnt vmcnt(62)
	v_lshlrev_b32_e32 v44, 16, v116
	v_and_b32_e32 v45, 0xffff0000, v116
	v_lshlrev_b32_e32 v50, 16, v117
	v_and_b32_e32 v51, 0xffff0000, v117
	v_pk_mul_f32 v[62:63], v[18:19], v[62:63]
	v_pk_mul_f32 v[56:57], v[20:21], v[56:57]
	v_pk_mul_f32 v[44:45], v[62:63], v[44:45]
	v_pk_mul_f32 v[50:51], v[56:57], v[50:51]
	v_cvt_pk_bf16_f32 v44, v44, v45
	v_cvt_pk_bf16_f32 v45, v50, v51
	v_pk_mul_f32 v[56:57], v[178:179], v[168:169] op_sel_hi:[1,0]
	v_pk_mul_f32 v[62:63], v[114:115], v[168:169] op_sel_hi:[1,0]
	global_store_dwordx2 v[170:171], v[44:45], off offset:2048
	v_lshlrev_b32_e32 v44, 16, v104
	v_and_b32_e32 v45, 0xffff0000, v104
	v_lshlrev_b32_e32 v50, 16, v105
	v_and_b32_e32 v51, 0xffff0000, v105
	v_pk_mul_f32 v[62:63], v[22:23], v[62:63]
	v_pk_mul_f32 v[56:57], v[24:25], v[56:57]
	v_pk_mul_f32 v[44:45], v[62:63], v[44:45]
	v_pk_mul_f32 v[50:51], v[56:57], v[50:51]
	v_cvt_pk_bf16_f32 v44, v44, v45
	v_cvt_pk_bf16_f32 v45, v50, v51
	v_pk_mul_f32 v[56:57], v[186:187], v[168:169] op_sel_hi:[1,0]
	v_pk_mul_f32 v[62:63], v[180:181], v[168:169] op_sel_hi:[1,0]
	global_store_dwordx2 v[170:171], v[44:45], off offset:2560
	v_lshlrev_b32_e32 v44, 16, v92
	v_and_b32_e32 v45, 0xffff0000, v92
	v_lshlrev_b32_e32 v50, 16, v93
	v_and_b32_e32 v51, 0xffff0000, v93
	v_pk_mul_f32 v[62:63], v[26:27], v[62:63]
	v_pk_mul_f32 v[56:57], v[28:29], v[56:57]
	v_pk_mul_f32 v[44:45], v[62:63], v[44:45]
	v_pk_mul_f32 v[50:51], v[56:57], v[50:51]
	v_cvt_pk_bf16_f32 v44, v44, v45
	v_cvt_pk_bf16_f32 v45, v50, v51
	v_pk_mul_f32 v[56:57], v[190:191], v[168:169] op_sel_hi:[1,0]
	v_pk_mul_f32 v[62:63], v[188:189], v[168:169] op_sel_hi:[1,0]
	global_store_dwordx2 v[170:171], v[44:45], off offset:3072
	v_lshlrev_b32_e32 v44, 16, v86
	v_and_b32_e32 v45, 0xffff0000, v86
	v_lshlrev_b32_e32 v50, 16, v87
	v_and_b32_e32 v51, 0xffff0000, v87
	v_pk_mul_f32 v[62:63], v[30:31], v[62:63]
	v_pk_mul_f32 v[56:57], v[32:33], v[56:57]
	v_pk_mul_f32 v[44:45], v[62:63], v[44:45]
	v_pk_mul_f32 v[50:51], v[56:57], v[50:51]
	v_cvt_pk_bf16_f32 v44, v44, v45
	v_cvt_pk_bf16_f32 v45, v50, v51
	global_store_dwordx2 v[170:171], v[172:173], off
	global_store_dwordx2 v[170:171], v[44:45], off offset:3584
	s_waitcnt vmcnt(62)
	v_lshlrev_b32_e32 v168, 16, v140
	v_and_b32_e32 v169, 0xffff0000, v140
	s_waitcnt vmcnt(59)
	v_lshlrev_b32_e32 v170, 16, v148
	v_and_b32_e32 v171, 0xffff0000, v148
	v_lshlrev_b32_e32 v140, 16, v141
	v_and_b32_e32 v141, 0xffff0000, v141
	v_lshlrev_b32_e32 v148, 16, v149
	v_and_b32_e32 v149, 0xffff0000, v149
	v_pk_add_f32 v[168:169], v[168:169], v[170:171]
	v_pk_add_f32 v[148:149], v[140:141], v[148:149]
	v_lshlrev_b32_e32 v140, 16, v126
	v_and_b32_e32 v141, 0xffff0000, v126
	s_waitcnt vmcnt(58)
	v_lshlrev_b32_e32 v170, 16, v132
	v_and_b32_e32 v171, 0xffff0000, v132
	v_pk_add_f32 v[140:141], v[140:141], v[170:171]
	v_lshlrev_b32_e32 v126, 16, v127
	v_and_b32_e32 v127, 0xffff0000, v127
	v_lshlrev_b32_e32 v132, 16, v133
	v_and_b32_e32 v133, 0xffff0000, v133
	v_pk_add_f32 v[132:133], v[126:127], v[132:133]
	v_mov_b32_e32 v170, v169
	v_mov_b32_e32 v171, v141
	v_mov_b32_e32 v126, v168
	v_mov_b32_e32 v127, v140
	v_pk_mul_f32 v[170:171], v[170:171], v[170:171]
	v_mov_b32_e32 v172, v149
	v_mov_b32_e32 v173, v133
	v_pk_fma_f32 v[126:127], v[126:127], v[126:127], v[170:171]
	v_mov_b32_e32 v170, v148
	v_mov_b32_e32 v171, v132
	v_pk_mul_f32 v[172:173], v[172:173], v[172:173]
	s_waitcnt vmcnt(47)
	v_lshlrev_b32_e32 v178, 16, v162
	v_pk_fma_f32 v[170:171], v[170:171], v[170:171], v[172:173]
	v_lshlrev_b32_e32 v172, 16, v124
	v_pk_add_f32 v[126:127], v[126:127], v[170:171]
	v_lshlrev_b32_e32 v170, 16, v108
	v_and_b32_e32 v171, 0xffff0000, v108
	v_and_b32_e32 v173, 0xffff0000, v124
	v_lshlrev_b32_e32 v108, 16, v109
	v_and_b32_e32 v109, 0xffff0000, v109
	v_lshlrev_b32_e32 v124, 16, v125
	v_and_b32_e32 v125, 0xffff0000, v125
	v_pk_add_f32 v[170:171], v[170:171], v[172:173]
	v_pk_add_f32 v[174:175], v[108:109], v[124:125]
	v_mov_b32_e32 v124, v171
	v_mov_b32_e32 v125, v175
	v_mov_b32_e32 v108, v170
	v_mov_b32_e32 v109, v174
	v_pk_mul_f32 v[124:125], v[124:125], v[124:125]
	v_lshlrev_b32_e32 v172, 16, v100
	v_pk_fma_f32 v[108:109], v[108:109], v[108:109], v[124:125]
	v_lshlrev_b32_e32 v124, 16, v98
	v_and_b32_e32 v125, 0xffff0000, v98
	v_and_b32_e32 v173, 0xffff0000, v100
	v_pk_add_f32 v[172:173], v[124:125], v[172:173]
	v_lshlrev_b32_e32 v98, 16, v99
	v_and_b32_e32 v99, 0xffff0000, v99
	v_lshlrev_b32_e32 v100, 16, v101
	v_and_b32_e32 v101, 0xffff0000, v101
	v_lshlrev_b32_e32 v124, 16, v90
	v_and_b32_e32 v125, 0xffff0000, v90
	v_and_b32_e32 v179, 0xffff0000, v162
	v_pk_add_f32 v[176:177], v[98:99], v[100:101]
	v_pk_add_f32 v[178:179], v[124:125], v[178:179]
	v_lshlrev_b32_e32 v90, 16, v91
	v_and_b32_e32 v91, 0xffff0000, v91
	v_lshlrev_b32_e32 v124, 16, v163
	v_and_b32_e32 v125, 0xffff0000, v163
	v_mul_f32_e32 v98, v173, v173
	v_mul_f32_e32 v100, v177, v177
	v_pk_add_f32 v[162:163], v[90:91], v[124:125]
	v_pk_add_f32 v[126:127], v[126:127], v[126:127] op_sel:[0,1] op_sel_hi:[1,0]
	v_pk_add_f32 v[108:109], v[108:109], v[108:109] op_sel:[0,1] op_sel_hi:[1,0]
	v_pk_fma_f32 v[98:99], v[172:173], v[172:173], v[98:99] op_sel_hi:[1,1,0]
	v_pk_fma_f32 v[100:101], v[176:177], v[176:177], v[100:101] op_sel_hi:[1,1,0]
	v_pk_mul_f32 v[90:91], v[178:179], v[178:179]
	v_pk_mul_f32 v[124:125], v[162:163], v[162:163]
	v_mov_b32_e32 v127, v90
	v_mov_b32_e32 v109, v91
	v_mov_b32_e32 v99, v124
	v_mov_b32_e32 v101, v125
	v_pk_add_f32 v[90:91], v[126:127], v[108:109]
	v_pk_add_f32 v[98:99], v[98:99], v[100:101]
	s_waitcnt vmcnt(46)
; template <bool HG>
; __device__ __forceinline__ void readout_phase2(const Args& a, Frame& F, const float* gain, int nrows) {
;     ...
;     const bool cx = ML + nw < nrows;
;     RO_LOAD(f2, b2, g2, cx ? ML + nw : nw + 7 * 2048);
	v_lshlrev_b32_e32 v100, 16, v158
	v_pk_add_f32 v[90:91], v[90:91], v[98:99]
	v_lshlrev_b32_e32 v98, 16, v76
	v_and_b32_e32 v99, 0xffff0000, v76
	v_and_b32_e32 v101, 0xffff0000, v158
	v_pk_add_f32 v[180:181], v[98:99], v[100:101]
	v_lshlrev_b32_e32 v76, 16, v77
	v_and_b32_e32 v77, 0xffff0000, v77
	v_lshlrev_b32_e32 v98, 16, v159
	v_and_b32_e32 v99, 0xffff0000, v159
	v_pk_add_f32 v[158:159], v[76:77], v[98:99]
	v_mov_b32_e32 v98, v181
	v_mov_b32_e32 v99, v159
	v_mov_b32_e32 v76, v180
	v_mov_b32_e32 v77, v158
	v_pk_mul_f32 v[98:99], v[98:99], v[98:99]
	s_waitcnt vmcnt(45)
	v_lshlrev_b32_e32 v100, 16, v154
	v_pk_fma_f32 v[76:77], v[76:77], v[76:77], v[98:99]
	v_lshlrev_b32_e32 v98, 16, v74
	v_and_b32_e32 v99, 0xffff0000, v74
	v_and_b32_e32 v101, 0xffff0000, v154
	v_pk_add_f32 v[184:185], v[98:99], v[100:101]
	v_lshlrev_b32_e32 v74, 16, v75
	v_and_b32_e32 v75, 0xffff0000, v75
	v_lshlrev_b32_e32 v98, 16, v155
	v_and_b32_e32 v99, 0xffff0000, v155
	v_lshlrev_b32_e32 v100, 16, v68
	v_and_b32_e32 v101, 0xffff0000, v68
	s_waitcnt vmcnt(44)
	v_lshlrev_b32_e32 v108, 16, v150
	v_and_b32_e32 v109, 0xffff0000, v150
	v_pk_add_f32 v[154:155], v[74:75], v[98:99]
	v_pk_add_f32 v[186:187], v[100:101], v[108:109]
	v_lshlrev_b32_e32 v68, 16, v69
	v_and_b32_e32 v69, 0xffff0000, v69
	v_lshlrev_b32_e32 v100, 16, v151
	v_and_b32_e32 v101, 0xffff0000, v151
	v_mul_f32_e32 v74, v185, v185
	v_mul_f32_e32 v98, v155, v155
	v_pk_add_f32 v[150:151], v[68:69], v[100:101]
	v_pk_add_f32 v[90:91], v[90:91], v[90:91] op_sel:[0,1] op_sel_hi:[1,0]
	v_pk_add_f32 v[76:77], v[76:77], v[76:77] op_sel:[0,1] op_sel_hi:[1,0]
	v_pk_fma_f32 v[74:75], v[184:185], v[184:185], v[74:75] op_sel_hi:[1,1,0]
	v_pk_fma_f32 v[98:99], v[154:155], v[154:155], v[98:99] op_sel_hi:[1,1,0]
	v_pk_mul_f32 v[68:69], v[186:187], v[186:187]
	v_pk_mul_f32 v[100:101], v[150:151], v[150:151]
	v_mov_b32_e32 v91, v68
	v_mov_b32_e32 v77, v69
	v_mov_b32_e32 v75, v100
	v_mov_b32_e32 v99, v101
	v_pk_add_f32 v[68:69], v[90:91], v[76:77]
	v_pk_add_f32 v[74:75], v[74:75], v[98:99]
	s_cselect_b64 s[14:15], -1, 0
	v_pk_add_f32 v[68:69], v[68:69], v[74:75]
	s_and_b64 s[6:7], s[14:15], exec
	v_add_f32_e32 v68, v68, v69
	s_cselect_b32 s6, s10, s18
	s_ashr_i32 s7, s6, 31
	v_add_f32_dpp v68, v68, v68 quad_perm:[1,0,3,2] row_mask:0xf bank_mask:0xf bound_ctrl:1
	s_lshl_b64 s[6:7], s[6:7], 12
	v_lshl_add_u64 v[36:37], v[36:37], 0, s[6:7]
	v_add_f32_dpp v68, v68, v68 quad_perm:[2,3,0,1] row_mask:0xf bank_mask:0xf bound_ctrl:1
	v_lshl_add_u64 v[50:51], v[36:37], 0, v[0:1]
	v_lshl_add_u64 v[36:37], v[38:39], 0, s[6:7]
	v_add_f32_dpp v68, v68, v68 row_half_mirror row_mask:0xf bank_mask:0xf bound_ctrl:1
	v_lshl_add_u64 v[166:167], v[36:37], 0, v[0:1]
	v_lshl_add_u64 v[36:37], v[40:41], 0, s[6:7]
	v_add_f32_dpp v68, v68, v68 row_mirror row_mask:0xf bank_mask:0xf bound_ctrl:1
	v_lshl_add_u64 v[164:165], v[36:37], 0, v[0:1]
	v_readlane_b32 s8, v68, 16
	v_readlane_b32 s9, v68, 48
	v_readlane_b32 s6, v68, 0
	v_readlane_b32 s7, v68, 32
	v_mov_b32_e32 v68, s8
	v_mov_b32_e32 v69, s9
	v_pk_add_f32 v[68:69], s[6:7], v[68:69]
	global_load_dwordx2 v[130:131], v[50:51], off
	global_load_dwordx2 v[116:117], v[50:51], off offset:512
	global_load_dwordx2 v[112:113], v[50:51], off offset:1024
	global_load_dwordx2 v[92:93], v[50:51], off offset:1536
	global_load_dwordx2 v[134:135], v[166:167], off
	global_load_dwordx2 v[128:129], v[166:167], off offset:512
	global_load_dwordx2 v[114:115], v[166:167], off offset:1024
	global_load_dwordx2 v[104:105], v[166:167], off offset:1536
	global_load_dwordx2 v[44:45], v[164:165], off
	global_load_dwordx2 v[40:41], v[164:165], off offset:512
	global_load_dwordx2 v[38:39], v[164:165], off offset:1024
	global_load_dwordx2 v[36:37], v[164:165], off offset:1536
	global_load_dwordx2 v[86:87], v[50:51], off offset:2048
	global_load_dwordx2 v[62:63], v[50:51], off offset:2560
	global_load_dwordx2 v[56:57], v[50:51], off offset:3072
	s_nop 0
	global_load_dwordx2 v[50:51], v[50:51], off offset:3584
	v_add_f32_e32 v68, v68, v69
	v_fmamk_f32 v68, v68, 0x3a000000, v252
	v_mul_f32_e32 v69, 0x4f800000, v68
	v_cmp_gt_f32_e32 vcc, s55, v68
	global_load_dwordx2 v[124:125], v[166:167], off offset:2048
	global_load_dwordx2 v[108:109], v[166:167], off offset:2560
	global_load_dwordx2 v[100:101], v[166:167], off offset:3072
	global_load_dwordx2 v[98:99], v[166:167], off offset:3584
	v_cndmask_b32_e32 v68, v68, v69, vcc
	v_sqrt_f32_e32 v69, v68
	s_nop 0
	v_add_u32_e32 v74, -1, v69
	v_fma_f32 v75, -v74, v69, v68
	v_cmp_ge_f32_e64 s[8:9], 0, v75
	v_add_u32_e32 v75, 1, v69
	s_nop 0
	v_cndmask_b32_e64 v74, v69, v74, s[8:9]
	v_fma_f32 v69, -v75, v69, v68
	v_cmp_lt_f32_e64 s[8:9], 0, v69
	s_nop 1
	v_cndmask_b32_e64 v69, v74, v75, s[8:9]
	v_mul_f32_e32 v74, 0x37800000, v69
	v_cndmask_b32_e32 v69, v69, v74, vcc
	v_cmp_class_f32_e32 vcc, v68, v253
	s_nop 1
	v_cndmask_b32_e32 v126, v69, v68, vcc
	v_div_scale_f32 v127, s[6:7], v126, v126, 1.0
	v_rcp_f32_e32 v166, v127
	global_load_dwordx2 v[90:91], v[164:165], off offset:2048
	global_load_dwordx2 v[76:77], v[164:165], off offset:2560
	global_load_dwordx2 v[74:75], v[164:165], off offset:3072
	global_load_dwordx2 v[68:69], v[164:165], off offset:3584
	v_fma_f32 v164, -v127, v166, 1.0
	v_fmac_f32_e32 v166, v164, v166
	v_div_scale_f32 v164, vcc, 1.0, v126, 1.0
	v_mul_f32_e32 v165, v164, v166
	v_fma_f32 v167, -v127, v165, v164
	v_fmac_f32_e32 v165, v167, v166
	v_fma_f32 v127, -v127, v165, v164
	v_div_fmas_f32 v127, v127, v166, v165
	v_div_fixup_f32 v164, v127, v126, 1.0
	v_pk_mul_f32 v[148:149], v[148:149], v[164:165] op_sel_hi:[1,0]
	v_pk_mul_f32 v[168:169], v[168:169], v[164:165] op_sel_hi:[1,0]
	v_lshlrev_b32_e32 v166, 16, v58
	v_and_b32_e32 v167, 0xffff0000, v58
	v_lshlrev_b32_e32 v58, 16, v59
	v_and_b32_e32 v59, 0xffff0000, v59
	v_pk_mul_f32 v[168:169], v[2:3], v[168:169]
	v_pk_mul_f32 v[148:149], v[4:5], v[148:149]
	v_pk_mul_f32 v[132:133], v[132:133], v[164:165] op_sel_hi:[1,0]
	v_pk_mul_f32 v[58:59], v[148:149], v[58:59]
	v_pk_mul_f32 v[148:149], v[168:169], v[166:167]
	v_pk_mul_f32 v[140:141], v[140:141], v[164:165] op_sel_hi:[1,0]
	v_cvt_pk_bf16_f32 v148, v148, v149
	v_cvt_pk_bf16_f32 v149, v58, v59
	v_lshlrev_b32_e32 v58, 16, v52
	v_and_b32_e32 v59, 0xffff0000, v52
	v_lshlrev_b32_e32 v52, 16, v53
	v_and_b32_e32 v53, 0xffff0000, v53
	v_pk_mul_f32 v[140:141], v[6:7], v[140:141]
	v_pk_mul_f32 v[132:133], v[8:9], v[132:133]
	v_lshl_add_u64 v[126:127], v[34:35], 0, s[12:13]
	v_pk_mul_f32 v[52:53], v[132:133], v[52:53]
	v_pk_mul_f32 v[58:59], v[140:141], v[58:59]
	v_lshl_add_u64 v[126:127], v[126:127], 0, v[0:1]
	v_cvt_pk_bf16_f32 v58, v58, v59
	v_cvt_pk_bf16_f32 v59, v52, v53
	global_store_dwordx2 v[126:127], v[58:59], off offset:512
	v_pk_mul_f32 v[58:59], v[174:175], v[164:165] op_sel_hi:[1,0]
	v_pk_mul_f32 v[132:133], v[170:171], v[164:165] op_sel_hi:[1,0]
	v_lshlrev_b32_e32 v52, 16, v48
	v_and_b32_e32 v53, 0xffff0000, v48
	v_lshlrev_b32_e32 v48, 16, v49
	v_and_b32_e32 v49, 0xffff0000, v49
	v_pk_mul_f32 v[132:133], v[10:11], v[132:133]
	v_pk_mul_f32 v[58:59], v[12:13], v[58:59]
	v_pk_mul_f32 v[52:53], v[132:133], v[52:53]
	v_pk_mul_f32 v[48:49], v[58:59], v[48:49]
	v_cvt_pk_bf16_f32 v52, v52, v53
	v_cvt_pk_bf16_f32 v53, v48, v49
	global_store_dwordx2 v[126:127], v[52:53], off offset:1024
	v_pk_mul_f32 v[52:53], v[176:177], v[164:165] op_sel_hi:[1,0]
	v_pk_mul_f32 v[58:59], v[172:173], v[164:165] op_sel_hi:[1,0]
	v_lshlrev_b32_e32 v48, 16, v42
	v_and_b32_e32 v49, 0xffff0000, v42
	v_lshlrev_b32_e32 v42, 16, v43
	v_and_b32_e32 v43, 0xffff0000, v43
	v_pk_mul_f32 v[58:59], v[14:15], v[58:59]
	v_pk_mul_f32 v[52:53], v[16:17], v[52:53]
	v_pk_mul_f32 v[48:49], v[58:59], v[48:49]
	v_pk_mul_f32 v[42:43], v[52:53], v[42:43]
	v_cvt_pk_bf16_f32 v48, v48, v49
	v_cvt_pk_bf16_f32 v49, v42, v43
	v_pk_mul_f32 v[52:53], v[162:163], v[164:165] op_sel_hi:[1,0]
	v_pk_mul_f32 v[58:59], v[178:179], v[164:165] op_sel_hi:[1,0]
	global_store_dwordx2 v[126:127], v[48:49], off offset:1536
	s_waitcnt vmcnt(62)
	v_lshlrev_b32_e32 v42, 16, v106
	v_and_b32_e32 v43, 0xffff0000, v106
	v_lshlrev_b32_e32 v48, 16, v107
	v_and_b32_e32 v49, 0xffff0000, v107
	v_pk_mul_f32 v[58:59], v[18:19], v[58:59]
	v_pk_mul_f32 v[52:53], v[20:21], v[52:53]
	v_pk_mul_f32 v[42:43], v[58:59], v[42:43]
	v_pk_mul_f32 v[48:49], v[52:53], v[48:49]
	v_cvt_pk_bf16_f32 v42, v42, v43
	v_cvt_pk_bf16_f32 v43, v48, v49
	v_pk_mul_f32 v[52:53], v[158:159], v[164:165] op_sel_hi:[1,0]
	v_pk_mul_f32 v[58:59], v[180:181], v[164:165] op_sel_hi:[1,0]
	global_store_dwordx2 v[126:127], v[42:43], off offset:2048
	v_lshlrev_b32_e32 v42, 16, v96
	v_and_b32_e32 v43, 0xffff0000, v96
	v_lshlrev_b32_e32 v48, 16, v97
	v_and_b32_e32 v49, 0xffff0000, v97
	v_pk_mul_f32 v[58:59], v[22:23], v[58:59]
	v_pk_mul_f32 v[52:53], v[24:25], v[52:53]
	v_pk_mul_f32 v[42:43], v[58:59], v[42:43]
	v_pk_mul_f32 v[48:49], v[52:53], v[48:49]
	v_cvt_pk_bf16_f32 v42, v42, v43
	v_cvt_pk_bf16_f32 v43, v48, v49
	v_pk_mul_f32 v[52:53], v[154:155], v[164:165] op_sel_hi:[1,0]
	v_pk_mul_f32 v[58:59], v[184:185], v[164:165] op_sel_hi:[1,0]
	global_store_dwordx2 v[126:127], v[42:43], off offset:2560
	v_lshlrev_b32_e32 v42, 16, v82
	v_and_b32_e32 v43, 0xffff0000, v82
	v_lshlrev_b32_e32 v48, 16, v83
	v_and_b32_e32 v49, 0xffff0000, v83
	v_pk_mul_f32 v[58:59], v[26:27], v[58:59]
	v_pk_mul_f32 v[52:53], v[28:29], v[52:53]
	v_pk_mul_f32 v[42:43], v[58:59], v[42:43]
	v_pk_mul_f32 v[48:49], v[52:53], v[48:49]
	v_cvt_pk_bf16_f32 v42, v42, v43
	v_cvt_pk_bf16_f32 v43, v48, v49
	global_store_dwordx2 v[126:127], v[42:43], off offset:3072
	v_pk_mul_f32 v[42:43], v[186:187], v[164:165] op_sel_hi:[1,0]
	s_waitcnt vmcnt(57)
	v_lshlrev_b32_e32 v48, 16, v146
	v_pk_mul_f32 v[132:133], v[30:31], v[42:43]
	v_lshlrev_b32_e32 v42, 16, v144
	v_and_b32_e32 v43, 0xffff0000, v144
	v_and_b32_e32 v49, 0xffff0000, v146
	v_pk_add_f32 v[48:49], v[42:43], v[48:49]
	v_lshlrev_b32_e32 v42, 16, v145
	v_and_b32_e32 v43, 0xffff0000, v145
	v_lshlrev_b32_e32 v52, 16, v147
	v_and_b32_e32 v53, 0xffff0000, v147
	v_pk_add_f32 v[58:59], v[42:43], v[52:53]
	v_lshlrev_b32_e32 v42, 16, v138
	v_and_b32_e32 v43, 0xffff0000, v138
	s_waitcnt vmcnt(56)
	v_lshlrev_b32_e32 v52, 16, v142
	v_and_b32_e32 v53, 0xffff0000, v142
	v_pk_add_f32 v[42:43], v[42:43], v[52:53]
	v_lshlrev_b32_e32 v52, 16, v139
	v_and_b32_e32 v53, 0xffff0000, v139
	v_lshlrev_b32_e32 v96, 16, v143
	v_and_b32_e32 v97, 0xffff0000, v143
	v_pk_add_f32 v[52:53], v[52:53], v[96:97]
	v_mov_b32_e32 v138, v49
	v_mov_b32_e32 v139, v43
	v_mov_b32_e32 v96, v48
	v_mov_b32_e32 v97, v42
	v_pk_mul_f32 v[138:139], v[138:139], v[138:139]
	v_mov_b32_e32 v140, v59
	v_mov_b32_e32 v141, v53
	v_pk_fma_f32 v[96:97], v[96:97], v[96:97], v[138:139]
	v_mov_b32_e32 v138, v58
	v_mov_b32_e32 v139, v52
	v_pk_mul_f32 v[140:141], v[140:141], v[140:141]
	s_waitcnt vmcnt(54)
	v_lshlrev_b32_e32 v142, 16, v118
	v_pk_fma_f32 v[138:139], v[138:139], v[138:139], v[140:141]
	v_lshlrev_b32_e32 v140, 16, v122
	v_pk_add_f32 v[96:97], v[96:97], v[138:139]
	v_and_b32_e32 v141, 0xffff0000, v122
	v_pk_add_f32 v[138:139], v[96:97], v[96:97] op_sel:[0,1] op_sel_hi:[1,0]
	v_lshlrev_b32_e32 v96, 16, v120
	v_and_b32_e32 v97, 0xffff0000, v120
	v_lshlrev_b32_e32 v120, 16, v121
	v_and_b32_e32 v121, 0xffff0000, v121
	v_lshlrev_b32_e32 v122, 16, v123
	v_and_b32_e32 v123, 0xffff0000, v123
	v_pk_add_f32 v[96:97], v[96:97], v[140:141]
	v_pk_add_f32 v[120:121], v[120:121], v[122:123]
	v_mov_b32_e32 v140, v97
	v_mov_b32_e32 v141, v121
	v_mov_b32_e32 v122, v96
	v_mov_b32_e32 v123, v120
	v_pk_mul_f32 v[140:141], v[140:141], v[140:141]
	v_and_b32_e32 v143, 0xffff0000, v118
	v_pk_fma_f32 v[122:123], v[122:123], v[122:123], v[140:141]
	v_lshlrev_b32_e32 v140, 16, v110
	v_and_b32_e32 v141, 0xffff0000, v110
	v_lshlrev_b32_e32 v110, 16, v111
	v_and_b32_e32 v111, 0xffff0000, v111
	v_lshlrev_b32_e32 v118, 16, v119
	v_and_b32_e32 v119, 0xffff0000, v119
	s_waitcnt vmcnt(49)
	v_lshlrev_b32_e32 v144, 16, v94
	v_and_b32_e32 v145, 0xffff0000, v94
	s_waitcnt vmcnt(45)
	v_lshlrev_b32_e32 v146, 16, v160
	v_and_b32_e32 v147, 0xffff0000, v160
	v_pk_add_f32 v[140:141], v[140:141], v[142:143]
	v_pk_add_f32 v[110:111], v[110:111], v[118:119]
	v_pk_add_f32 v[144:145], v[144:145], v[146:147]
	v_lshlrev_b32_e32 v94, 16, v95
	v_and_b32_e32 v95, 0xffff0000, v95
	v_lshlrev_b32_e32 v146, 16, v161
	v_and_b32_e32 v147, 0xffff0000, v161
	v_mul_f32_e32 v118, v141, v141
	v_mul_f32_e32 v142, v111, v111
	v_pk_add_f32 v[94:95], v[94:95], v[146:147]
	global_store_dwordx2 v[126:127], v[148:149], off
	v_pk_add_f32 v[122:123], v[122:123], v[122:123] op_sel:[0,1] op_sel_hi:[1,0]
	v_pk_fma_f32 v[118:119], v[140:141], v[140:141], v[118:119] op_sel_hi:[1,1,0]
	v_pk_fma_f32 v[142:143], v[110:111], v[110:111], v[142:143] op_sel_hi:[1,1,0]
	v_pk_mul_f32 v[146:147], v[144:145], v[144:145]
	v_pk_mul_f32 v[148:149], v[94:95], v[94:95]
	v_mov_b32_e32 v139, v146
	v_mov_b32_e32 v123, v147
	v_mov_b32_e32 v119, v148
	v_mov_b32_e32 v143, v149
	v_pk_add_f32 v[122:123], v[138:139], v[122:123]
	v_pk_add_f32 v[118:119], v[118:119], v[142:143]
	s_waitcnt vmcnt(45)
	v_lshlrev_b32_e32 v138, 16, v156
	v_pk_add_f32 v[118:119], v[122:123], v[118:119]
	v_lshlrev_b32_e32 v122, 16, v88
	v_and_b32_e32 v123, 0xffff0000, v88
	v_and_b32_e32 v139, 0xffff0000, v156
	v_pk_add_f32 v[122:123], v[122:123], v[138:139]
	v_lshlrev_b32_e32 v88, 16, v89
	v_and_b32_e32 v89, 0xffff0000, v89
	v_lshlrev_b32_e32 v138, 16, v157
	v_and_b32_e32 v139, 0xffff0000, v157
	v_pk_add_f32 v[88:89], v[88:89], v[138:139]
	v_mov_b32_e32 v142, v123
	v_mov_b32_e32 v143, v89
	v_mov_b32_e32 v138, v122
	v_mov_b32_e32 v139, v88
	v_pk_mul_f32 v[142:143], v[142:143], v[142:143]
	s_waitcnt vmcnt(44)
	v_lshlrev_b32_e32 v146, 16, v152
	v_pk_fma_f32 v[138:139], v[138:139], v[138:139], v[142:143]
	v_lshlrev_b32_e32 v142, 16, v80
	v_and_b32_e32 v143, 0xffff0000, v80
	v_and_b32_e32 v147, 0xffff0000, v152
	v_pk_add_f32 v[142:143], v[142:143], v[146:147]
	v_lshlrev_b32_e32 v80, 16, v81
	v_and_b32_e32 v81, 0xffff0000, v81
	v_lshlrev_b32_e32 v146, 16, v153
	v_and_b32_e32 v147, 0xffff0000, v153
	v_pk_mul_f32 v[106:107], v[150:151], v[164:165] op_sel_hi:[1,0]
	v_pk_add_f32 v[80:81], v[80:81], v[146:147]
	v_lshlrev_b32_e32 v150, 16, v66
	v_and_b32_e32 v151, 0xffff0000, v66
	s_waitcnt vmcnt(43)
	v_lshlrev_b32_e32 v152, 16, v136
	v_and_b32_e32 v153, 0xffff0000, v136
	v_lshlrev_b32_e32 v66, 16, v67
	v_and_b32_e32 v67, 0xffff0000, v67
	v_lshlrev_b32_e32 v136, 16, v137
	v_and_b32_e32 v137, 0xffff0000, v137
	v_mul_f32_e32 v146, v143, v143
	v_mul_f32_e32 v148, v81, v81
	v_pk_add_f32 v[150:151], v[150:151], v[152:153]
	v_pk_add_f32 v[66:67], v[66:67], v[136:137]
	v_pk_add_f32 v[118:119], v[118:119], v[118:119] op_sel:[0,1] op_sel_hi:[1,0]
	v_pk_add_f32 v[138:139], v[138:139], v[138:139] op_sel:[0,1] op_sel_hi:[1,0]
	v_pk_fma_f32 v[146:147], v[142:143], v[142:143], v[146:147] op_sel_hi:[1,1,0]
	v_pk_fma_f32 v[148:149], v[80:81], v[80:81], v[148:149] op_sel_hi:[1,1,0]
	v_pk_mul_f32 v[136:137], v[150:151], v[150:151]
	v_pk_mul_f32 v[152:153], v[66:67], v[66:67]
	v_mov_b32_e32 v119, v136
	v_mov_b32_e32 v139, v137
	v_mov_b32_e32 v147, v152
	v_mov_b32_e32 v149, v153
	v_pk_add_f32 v[118:119], v[118:119], v[138:139]
	v_pk_add_f32 v[136:137], v[146:147], v[148:149]
	v_lshlrev_b32_e32 v82, 16, v72
	v_pk_add_f32 v[118:119], v[118:119], v[136:137]
	v_and_b32_e32 v83, 0xffff0000, v72
	v_add_f32_e32 v118, v118, v119
	v_lshlrev_b32_e32 v72, 16, v73
	v_and_b32_e32 v73, 0xffff0000, v73
	v_add_f32_dpp v118, v118, v118 quad_perm:[1,0,3,2] row_mask:0xf bank_mask:0xf bound_ctrl:1
	v_pk_mul_f32 v[106:107], v[32:33], v[106:107]
	v_pk_mul_f32 v[82:83], v[132:133], v[82:83]
	v_add_f32_dpp v118, v118, v118 quad_perm:[2,3,0,1] row_mask:0xf bank_mask:0xf bound_ctrl:1
	v_pk_mul_f32 v[72:73], v[106:107], v[72:73]
	v_cvt_pk_bf16_f32 v82, v82, v83
	v_add_f32_dpp v118, v118, v118 row_half_mirror row_mask:0xf bank_mask:0xf bound_ctrl:1
	v_cvt_pk_bf16_f32 v83, v72, v73
	global_store_dwordx2 v[126:127], v[82:83], off offset:3584
	v_add_f32_dpp v118, v118, v118 row_mirror row_mask:0xf bank_mask:0xf bound_ctrl:1
	s_nop 0
	v_readlane_b32 s8, v118, 16
	v_readlane_b32 s9, v118, 48
	v_readlane_b32 s6, v118, 0
	v_readlane_b32 s7, v118, 32
	v_mov_b32_e32 v118, s8
	v_mov_b32_e32 v119, s9
	v_pk_add_f32 v[118:119], s[6:7], v[118:119]
	s_nop 0
	v_add_f32_e32 v118, v118, v119
	v_fmamk_f32 v118, v118, 0x3a000000, v252
	v_mul_f32_e32 v119, 0x4f800000, v118
	v_cmp_gt_f32_e32 vcc, s55, v118
	s_nop 1
; template <bool HG>
; __device__ __forceinline__ void readout_phase2(const Args& a, Frame& F, const float* gain, int nrows) {
;     ...
;     if (cx) RO_FINISH(f2, b2, g2, ML + nw);
	v_cndmask_b32_e32 v118, v118, v119, vcc
	v_sqrt_f32_e32 v119, v118
	s_nop 0
	v_add_u32_e32 v106, -1, v119
	v_fma_f32 v107, -v106, v119, v118
	v_cmp_ge_f32_e64 s[8:9], 0, v107
	v_add_u32_e32 v107, 1, v119
	s_nop 0
	v_cndmask_b32_e64 v106, v119, v106, s[8:9]
	v_fma_f32 v119, -v107, v119, v118
	v_cmp_lt_f32_e64 s[8:9], 0, v119
	s_nop 1
	v_cndmask_b32_e64 v106, v106, v107, s[8:9]
	v_mul_f32_e32 v107, 0x37800000, v106
	v_cndmask_b32_e32 v106, v106, v107, vcc
	v_cmp_class_f32_e32 vcc, v118, v253
	s_nop 1
	v_cndmask_b32_e32 v106, v106, v118, vcc
	v_div_scale_f32 v107, s[6:7], v106, v106, 1.0
	v_rcp_f32_e32 v118, v107
	s_nop 0
	v_fma_f32 v72, -v107, v118, 1.0
	v_fmac_f32_e32 v118, v72, v118
	v_div_scale_f32 v72, vcc, 1.0, v106, 1.0
	v_mul_f32_e32 v73, v72, v118
	v_fma_f32 v82, -v107, v73, v72
	v_fmac_f32_e32 v73, v82, v118
	v_fma_f32 v72, -v107, v73, v72
	v_div_fmas_f32 v72, v72, v118, v73
	v_div_fixup_f32 v72, v72, v106, 1.0
	v_pk_mul_f32 v[58:59], v[58:59], v[72:73] op_sel_hi:[1,0]
	v_pk_mul_f32 v[48:49], v[48:49], v[72:73] op_sel_hi:[1,0]
	v_lshlrev_b32_e32 v106, 16, v64
	v_and_b32_e32 v107, 0xffff0000, v64
	v_lshlrev_b32_e32 v64, 16, v65
	v_and_b32_e32 v65, 0xffff0000, v65
	v_pk_mul_f32 v[48:49], v[2:3], v[48:49]
	v_pk_mul_f32 v[58:59], v[4:5], v[58:59]
	v_lshl_add_u64 v[82:83], v[34:35], 0, s[16:17]
	v_pk_mul_f32 v[58:59], v[58:59], v[64:65]
	v_pk_mul_f32 v[48:49], v[48:49], v[106:107]
	v_lshl_add_u64 v[82:83], v[82:83], 0, v[0:1]
	v_cvt_pk_bf16_f32 v48, v48, v49
	v_cvt_pk_bf16_f32 v49, v58, v59
	v_pk_mul_f32 v[52:53], v[52:53], v[72:73] op_sel_hi:[1,0]
	v_pk_mul_f32 v[42:43], v[42:43], v[72:73] op_sel_hi:[1,0]
	global_store_dwordx2 v[82:83], v[48:49], off
	v_lshlrev_b32_e32 v48, 16, v60
	v_and_b32_e32 v49, 0xffff0000, v60
	v_lshlrev_b32_e32 v58, 16, v61
	v_and_b32_e32 v59, 0xffff0000, v61
	v_pk_mul_f32 v[42:43], v[6:7], v[42:43]
	v_pk_mul_f32 v[52:53], v[8:9], v[52:53]
	v_pk_mul_f32 v[42:43], v[42:43], v[48:49]
	v_pk_mul_f32 v[52:53], v[52:53], v[58:59]
	v_cvt_pk_bf16_f32 v42, v42, v43
	v_cvt_pk_bf16_f32 v43, v52, v53
	global_store_dwordx2 v[82:83], v[42:43], off offset:512
	v_lshlrev_b32_e32 v42, 16, v54
	v_and_b32_e32 v43, 0xffff0000, v54
	v_lshlrev_b32_e32 v48, 16, v55
	v_and_b32_e32 v49, 0xffff0000, v55
	v_pk_mul_f32 v[52:53], v[120:121], v[72:73] op_sel_hi:[1,0]
	v_pk_mul_f32 v[54:55], v[96:97], v[72:73] op_sel_hi:[1,0]
	v_pk_mul_f32 v[52:53], v[12:13], v[52:53]
	v_pk_mul_f32 v[54:55], v[10:11], v[54:55]
	v_pk_mul_f32 v[48:49], v[52:53], v[48:49]
	v_pk_mul_f32 v[42:43], v[54:55], v[42:43]
	v_pk_mul_f32 v[52:53], v[140:141], v[72:73] op_sel_hi:[1,0]
	v_cvt_pk_bf16_f32 v42, v42, v43
	v_cvt_pk_bf16_f32 v43, v48, v49
	v_pk_mul_f32 v[48:49], v[110:111], v[72:73] op_sel_hi:[1,0]
	global_store_dwordx2 v[82:83], v[42:43], off offset:1024
	v_lshlrev_b32_e32 v42, 16, v46
	v_and_b32_e32 v43, 0xffff0000, v46
	v_lshlrev_b32_e32 v46, 16, v47
	v_and_b32_e32 v47, 0xffff0000, v47
	v_pk_mul_f32 v[52:53], v[14:15], v[52:53]
	v_pk_mul_f32 v[48:49], v[16:17], v[48:49]
	v_pk_mul_f32 v[42:43], v[52:53], v[42:43]
	v_pk_mul_f32 v[46:47], v[48:49], v[46:47]
	v_cvt_pk_bf16_f32 v42, v42, v43
	v_cvt_pk_bf16_f32 v43, v46, v47
	v_pk_mul_f32 v[48:49], v[94:95], v[72:73] op_sel_hi:[1,0]
	v_pk_mul_f32 v[52:53], v[144:145], v[72:73] op_sel_hi:[1,0]
	global_store_dwordx2 v[82:83], v[42:43], off offset:1536
	s_waitcnt vmcnt(47)
	v_lshlrev_b32_e32 v42, 16, v102
	v_and_b32_e32 v43, 0xffff0000, v102
	v_lshlrev_b32_e32 v46, 16, v103
	v_and_b32_e32 v47, 0xffff0000, v103
	v_pk_mul_f32 v[52:53], v[18:19], v[52:53]
	v_pk_mul_f32 v[48:49], v[20:21], v[48:49]
	v_pk_mul_f32 v[42:43], v[52:53], v[42:43]
	v_pk_mul_f32 v[46:47], v[48:49], v[46:47]
	v_cvt_pk_bf16_f32 v42, v42, v43
	v_cvt_pk_bf16_f32 v43, v46, v47
	v_pk_mul_f32 v[48:49], v[88:89], v[72:73] op_sel_hi:[1,0]
	v_pk_mul_f32 v[52:53], v[122:123], v[72:73] op_sel_hi:[1,0]
	global_store_dwordx2 v[82:83], v[42:43], off offset:2048
	s_waitcnt vmcnt(47)
	v_lshlrev_b32_e32 v42, 16, v84
	v_and_b32_e32 v43, 0xffff0000, v84
	v_lshlrev_b32_e32 v46, 16, v85
	v_and_b32_e32 v47, 0xffff0000, v85
	v_pk_mul_f32 v[52:53], v[22:23], v[52:53]
	v_pk_mul_f32 v[48:49], v[24:25], v[48:49]
	v_pk_mul_f32 v[42:43], v[52:53], v[42:43]
	v_pk_mul_f32 v[46:47], v[48:49], v[46:47]
	v_cvt_pk_bf16_f32 v42, v42, v43
	v_cvt_pk_bf16_f32 v43, v46, v47
	v_pk_mul_f32 v[48:49], v[80:81], v[72:73] op_sel_hi:[1,0]
	v_pk_mul_f32 v[52:53], v[142:143], v[72:73] op_sel_hi:[1,0]
	global_store_dwordx2 v[82:83], v[42:43], off offset:2560
	s_waitcnt vmcnt(47)
	v_lshlrev_b32_e32 v42, 16, v78
	v_and_b32_e32 v43, 0xffff0000, v78
	v_lshlrev_b32_e32 v46, 16, v79
	v_and_b32_e32 v47, 0xffff0000, v79
	v_pk_mul_f32 v[52:53], v[26:27], v[52:53]
	v_pk_mul_f32 v[48:49], v[28:29], v[48:49]
	v_pk_mul_f32 v[42:43], v[52:53], v[42:43]
	v_pk_mul_f32 v[46:47], v[48:49], v[46:47]
	v_cvt_pk_bf16_f32 v42, v42, v43
	v_cvt_pk_bf16_f32 v43, v46, v47
	v_pk_mul_f32 v[48:49], v[66:67], v[72:73] op_sel_hi:[1,0]
	v_pk_mul_f32 v[52:53], v[150:151], v[72:73] op_sel_hi:[1,0]
	global_store_dwordx2 v[82:83], v[42:43], off offset:3072
	s_waitcnt vmcnt(47)
	v_lshlrev_b32_e32 v42, 16, v70
	v_and_b32_e32 v43, 0xffff0000, v70
	v_lshlrev_b32_e32 v46, 16, v71
	v_and_b32_e32 v47, 0xffff0000, v71
	v_pk_mul_f32 v[52:53], v[30:31], v[52:53]
	v_pk_mul_f32 v[48:49], v[32:33], v[48:49]
	v_pk_mul_f32 v[42:43], v[52:53], v[42:43]
	v_pk_mul_f32 v[46:47], v[48:49], v[46:47]
	v_cvt_pk_bf16_f32 v42, v42, v43
	v_cvt_pk_bf16_f32 v43, v46, v47
	s_and_b64 vcc, exec, s[14:15]
	global_store_dwordx2 v[82:83], v[42:43], off offset:3584
	s_cbranch_vccz .LBB0_582
	s_waitcnt vmcnt(39)
	v_lshlrev_b32_e32 v42, 16, v130
	v_and_b32_e32 v43, 0xffff0000, v130
	s_waitcnt vmcnt(35)
	v_lshlrev_b32_e32 v46, 16, v134
	v_and_b32_e32 v47, 0xffff0000, v134
	v_pk_add_f32 v[46:47], v[42:43], v[46:47]
	v_lshlrev_b32_e32 v42, 16, v131
	v_and_b32_e32 v43, 0xffff0000, v131
	v_lshlrev_b32_e32 v48, 16, v135
	v_and_b32_e32 v49, 0xffff0000, v135
	v_pk_add_f32 v[52:53], v[42:43], v[48:49]
	v_lshlrev_b32_e32 v42, 16, v116
	v_and_b32_e32 v43, 0xffff0000, v116
	s_waitcnt vmcnt(34)
	v_lshlrev_b32_e32 v48, 16, v128
	v_and_b32_e32 v49, 0xffff0000, v128
	v_pk_add_f32 v[42:43], v[42:43], v[48:49]
	v_lshlrev_b32_e32 v48, 16, v117
	v_and_b32_e32 v49, 0xffff0000, v117
	v_lshlrev_b32_e32 v54, 16, v129
	v_and_b32_e32 v55, 0xffff0000, v129
	v_pk_add_f32 v[48:49], v[48:49], v[54:55]
	v_mov_b32_e32 v58, v47
	v_mov_b32_e32 v59, v43
	v_mov_b32_e32 v54, v46
	v_mov_b32_e32 v55, v42
	v_pk_mul_f32 v[58:59], v[58:59], v[58:59]
	v_mov_b32_e32 v60, v53
	v_mov_b32_e32 v61, v49
	v_pk_fma_f32 v[54:55], v[54:55], v[54:55], v[58:59]
	v_mov_b32_e32 v58, v52
	v_mov_b32_e32 v59, v48
	v_pk_mul_f32 v[60:61], v[60:61], v[60:61]
	s_waitcnt vmcnt(33)
	v_lshlrev_b32_e32 v64, 16, v115
	v_pk_fma_f32 v[58:59], v[58:59], v[58:59], v[60:61]
	v_lshlrev_b32_e32 v60, 16, v114
	v_pk_add_f32 v[54:55], v[54:55], v[58:59]
	v_and_b32_e32 v61, 0xffff0000, v114
	v_pk_add_f32 v[58:59], v[54:55], v[54:55] op_sel:[0,1] op_sel_hi:[1,0]
	v_lshlrev_b32_e32 v54, 16, v112
	v_and_b32_e32 v55, 0xffff0000, v112
	v_pk_add_f32 v[54:55], v[54:55], v[60:61]
	v_lshlrev_b32_e32 v60, 16, v113
	v_and_b32_e32 v61, 0xffff0000, v113
	v_and_b32_e32 v65, 0xffff0000, v115
	v_pk_add_f32 v[60:61], v[60:61], v[64:65]
	v_mov_b32_e32 v66, v55
	v_mov_b32_e32 v67, v61
	v_mov_b32_e32 v64, v54
	v_mov_b32_e32 v65, v60
	v_pk_mul_f32 v[66:67], v[66:67], v[66:67]
	s_waitcnt vmcnt(32)
	v_lshlrev_b32_e32 v70, 16, v104
	v_pk_fma_f32 v[64:65], v[64:65], v[64:65], v[66:67]
	v_lshlrev_b32_e32 v66, 16, v92
	v_and_b32_e32 v67, 0xffff0000, v92
	v_and_b32_e32 v71, 0xffff0000, v104
	v_pk_add_f32 v[66:67], v[66:67], v[70:71]
	v_lshlrev_b32_e32 v70, 16, v93
	v_and_b32_e32 v71, 0xffff0000, v93
	v_lshlrev_b32_e32 v72, 16, v105
	v_and_b32_e32 v73, 0xffff0000, v105
	s_waitcnt vmcnt(27)
	v_lshlrev_b32_e32 v80, 16, v86
	v_and_b32_e32 v81, 0xffff0000, v86
	s_waitcnt vmcnt(23)
	v_lshlrev_b32_e32 v82, 16, v124
	v_and_b32_e32 v83, 0xffff0000, v124
	v_pk_add_f32 v[70:71], v[70:71], v[72:73]
	v_pk_add_f32 v[80:81], v[80:81], v[82:83]
	v_lshlrev_b32_e32 v82, 16, v87
	v_and_b32_e32 v83, 0xffff0000, v87
	v_lshlrev_b32_e32 v84, 16, v125
	v_and_b32_e32 v85, 0xffff0000, v125
	v_mul_f32_e32 v72, v67, v67
	v_mul_f32_e32 v78, v71, v71
	v_pk_add_f32 v[82:83], v[82:83], v[84:85]
	v_pk_add_f32 v[64:65], v[64:65], v[64:65] op_sel:[0,1] op_sel_hi:[1,0]
	v_pk_fma_f32 v[72:73], v[66:67], v[66:67], v[72:73] op_sel_hi:[1,1,0]
	v_pk_fma_f32 v[78:79], v[70:71], v[70:71], v[78:79] op_sel_hi:[1,1,0]
	v_pk_mul_f32 v[84:85], v[80:81], v[80:81]
	v_pk_mul_f32 v[86:87], v[82:83], v[82:83]
	v_mov_b32_e32 v59, v84
	v_mov_b32_e32 v65, v85
	v_mov_b32_e32 v73, v86
	v_mov_b32_e32 v79, v87
	v_pk_add_f32 v[58:59], v[58:59], v[64:65]
	v_pk_add_f32 v[64:65], v[72:73], v[78:79]
	s_waitcnt vmcnt(22)
	v_lshlrev_b32_e32 v72, 16, v108
	v_pk_add_f32 v[58:59], v[58:59], v[64:65]
	v_lshlrev_b32_e32 v64, 16, v62
	v_and_b32_e32 v65, 0xffff0000, v62
	v_and_b32_e32 v73, 0xffff0000, v108
	v_pk_add_f32 v[64:65], v[64:65], v[72:73]
	v_lshlrev_b32_e32 v62, 16, v63
	v_and_b32_e32 v63, 0xffff0000, v63
	v_lshlrev_b32_e32 v72, 16, v109
	v_and_b32_e32 v73, 0xffff0000, v109
	v_pk_add_f32 v[62:63], v[62:63], v[72:73]
	v_mov_b32_e32 v78, v65
	v_mov_b32_e32 v79, v63
	v_mov_b32_e32 v72, v64
	v_mov_b32_e32 v73, v62
	v_pk_mul_f32 v[78:79], v[78:79], v[78:79]
	s_waitcnt vmcnt(21)
	v_lshlrev_b32_e32 v84, 16, v100
	v_pk_fma_f32 v[72:73], v[72:73], v[72:73], v[78:79]
	v_lshlrev_b32_e32 v78, 16, v56
	v_and_b32_e32 v79, 0xffff0000, v56
	v_and_b32_e32 v85, 0xffff0000, v100
	v_pk_add_f32 v[78:79], v[78:79], v[84:85]
	v_lshlrev_b32_e32 v56, 16, v57
	v_and_b32_e32 v57, 0xffff0000, v57
	v_lshlrev_b32_e32 v84, 16, v101
	v_and_b32_e32 v85, 0xffff0000, v101
	v_lshlrev_b32_e32 v88, 16, v50
	v_and_b32_e32 v89, 0xffff0000, v50
	s_waitcnt vmcnt(20)
; template <bool HG>
; __device__ __forceinline__ void readout_phase2(const Args& a, Frame& F, const float* gain, int nrows) {
;     ...
;     if (cx) RO_FINISH(f2, b2, g2, ML + nw);
	v_lshlrev_b32_e32 v92, 16, v98
	v_and_b32_e32 v93, 0xffff0000, v98
	v_pk_add_f32 v[56:57], v[56:57], v[84:85]
	v_pk_add_f32 v[88:89], v[88:89], v[92:93]
	v_lshlrev_b32_e32 v50, 16, v51
	v_and_b32_e32 v51, 0xffff0000, v51
	v_lshlrev_b32_e32 v92, 16, v99
	v_and_b32_e32 v93, 0xffff0000, v99
	v_mul_f32_e32 v84, v79, v79
	v_mul_f32_e32 v86, v57, v57
	v_pk_add_f32 v[50:51], v[50:51], v[92:93]
	v_pk_add_f32 v[58:59], v[58:59], v[58:59] op_sel:[0,1] op_sel_hi:[1,0]
	v_pk_add_f32 v[72:73], v[72:73], v[72:73] op_sel:[0,1] op_sel_hi:[1,0]
	v_pk_fma_f32 v[84:85], v[78:79], v[78:79], v[84:85] op_sel_hi:[1,1,0]
	v_pk_fma_f32 v[86:87], v[56:57], v[56:57], v[86:87] op_sel_hi:[1,1,0]
	v_pk_mul_f32 v[92:93], v[88:89], v[88:89]
	v_pk_mul_f32 v[94:95], v[50:51], v[50:51]
	v_mov_b32_e32 v59, v92
	v_mov_b32_e32 v73, v93
	v_mov_b32_e32 v85, v94
	v_mov_b32_e32 v87, v95
	v_pk_add_f32 v[58:59], v[58:59], v[72:73]
	v_pk_add_f32 v[72:73], v[84:85], v[86:87]
	s_ashr_i32 s11, s10, 31
	v_pk_add_f32 v[58:59], v[58:59], v[72:73]
	s_nop 0
	v_add_f32_e32 v58, v58, v59
	s_nop 1
	v_add_f32_dpp v58, v58, v58 quad_perm:[1,0,3,2] row_mask:0xf bank_mask:0xf bound_ctrl:1
	s_nop 1
	v_add_f32_dpp v58, v58, v58 quad_perm:[2,3,0,1] row_mask:0xf bank_mask:0xf bound_ctrl:1
	s_nop 1
	v_add_f32_dpp v58, v58, v58 row_half_mirror row_mask:0xf bank_mask:0xf bound_ctrl:1
	s_nop 1
	v_add_f32_dpp v58, v58, v58 row_mirror row_mask:0xf bank_mask:0xf bound_ctrl:1
	s_nop 0
	v_readlane_b32 s8, v58, 16
	v_readlane_b32 s9, v58, 48
	v_readlane_b32 s6, v58, 0
	v_readlane_b32 s7, v58, 32
	v_mov_b32_e32 v58, s8
	v_mov_b32_e32 v59, s9
	v_pk_add_f32 v[58:59], s[6:7], v[58:59]
	s_nop 0
	v_add_f32_e32 v58, v58, v59
	v_fmamk_f32 v58, v58, 0x3a000000, v252
	v_mul_f32_e32 v59, 0x4f800000, v58
	v_cmp_gt_f32_e32 vcc, s55, v58
	s_nop 1
	v_cndmask_b32_e32 v58, v58, v59, vcc
	v_sqrt_f32_e32 v59, v58
	s_nop 0
	v_add_u32_e32 v72, -1, v59
	v_fma_f32 v73, -v72, v59, v58
	v_cmp_ge_f32_e64 s[8:9], 0, v73
	v_add_u32_e32 v73, 1, v59
	s_nop 0
	v_cndmask_b32_e64 v72, v59, v72, s[8:9]
	v_fma_f32 v59, -v73, v59, v58
	v_cmp_lt_f32_e64 s[8:9], 0, v59
	s_nop 1
	v_cndmask_b32_e64 v59, v72, v73, s[8:9]
	v_mul_f32_e32 v72, 0x37800000, v59
	v_cndmask_b32_e32 v59, v59, v72, vcc
	v_cmp_class_f32_e32 vcc, v58, v253
	s_nop 1
	v_cndmask_b32_e32 v58, v59, v58, vcc
	v_div_scale_f32 v59, s[6:7], v58, v58, 1.0
	v_rcp_f32_e32 v72, v59
	s_lshl_b64 s[6:7], s[10:11], 12
	v_lshl_add_u64 v[34:35], v[34:35], 0, s[6:7]
	v_lshl_add_u64 v[34:35], v[34:35], 0, v[0:1]
	v_fma_f32 v73, -v59, v72, 1.0
	v_fmac_f32_e32 v72, v73, v72
	v_div_scale_f32 v73, vcc, 1.0, v58, 1.0
	v_mul_f32_e32 v84, v73, v72
	v_fma_f32 v85, -v59, v84, v73
	v_fmac_f32_e32 v84, v85, v72
	v_fma_f32 v59, -v59, v84, v73
	v_div_fmas_f32 v59, v59, v72, v84
	v_div_fixup_f32 v58, v59, v58, 1.0
	v_pk_mul_f32 v[52:53], v[52:53], v[58:59] op_sel_hi:[1,0]
	v_pk_mul_f32 v[46:47], v[46:47], v[58:59] op_sel_hi:[1,0]
	v_lshlrev_b32_e32 v72, 16, v44
	v_and_b32_e32 v73, 0xffff0000, v44
	v_lshlrev_b32_e32 v44, 16, v45
	v_and_b32_e32 v45, 0xffff0000, v45
	v_pk_mul_f32 v[2:3], v[2:3], v[46:47]
	v_pk_mul_f32 v[4:5], v[4:5], v[52:53]
	v_pk_mul_f32 v[2:3], v[2:3], v[72:73]
	v_pk_mul_f32 v[4:5], v[4:5], v[44:45]
	v_cvt_pk_bf16_f32 v2, v2, v3
	v_cvt_pk_bf16_f32 v3, v4, v5
	global_store_dwordx2 v[34:35], v[2:3], off
	v_lshlrev_b32_e32 v2, 16, v40
	v_and_b32_e32 v3, 0xffff0000, v40
	v_lshlrev_b32_e32 v4, 16, v41
	v_and_b32_e32 v5, 0xffff0000, v41
	v_pk_mul_f32 v[40:41], v[48:49], v[58:59] op_sel_hi:[1,0]
	v_pk_mul_f32 v[42:43], v[42:43], v[58:59] op_sel_hi:[1,0]
	v_pk_mul_f32 v[8:9], v[8:9], v[40:41]
	v_pk_mul_f32 v[6:7], v[6:7], v[42:43]
	v_pk_mul_f32 v[4:5], v[8:9], v[4:5]
	v_pk_mul_f32 v[2:3], v[6:7], v[2:3]
	v_pk_mul_f32 v[6:7], v[60:61], v[58:59] op_sel_hi:[1,0]
	v_cvt_pk_bf16_f32 v2, v2, v3
	v_cvt_pk_bf16_f32 v3, v4, v5
	v_pk_mul_f32 v[8:9], v[54:55], v[58:59] op_sel_hi:[1,0]
	global_store_dwordx2 v[34:35], v[2:3], off offset:512
	v_lshlrev_b32_e32 v2, 16, v38
	v_and_b32_e32 v3, 0xffff0000, v38
	v_lshlrev_b32_e32 v4, 16, v39
	v_and_b32_e32 v5, 0xffff0000, v39
	v_pk_mul_f32 v[8:9], v[10:11], v[8:9]
	v_pk_mul_f32 v[6:7], v[12:13], v[6:7]
	v_pk_mul_f32 v[2:3], v[8:9], v[2:3]
	v_pk_mul_f32 v[4:5], v[6:7], v[4:5]
	v_cvt_pk_bf16_f32 v2, v2, v3
	v_cvt_pk_bf16_f32 v3, v4, v5
	v_pk_mul_f32 v[6:7], v[70:71], v[58:59] op_sel_hi:[1,0]
	v_pk_mul_f32 v[8:9], v[66:67], v[58:59] op_sel_hi:[1,0]
	global_store_dwordx2 v[34:35], v[2:3], off offset:1024
	v_lshlrev_b32_e32 v2, 16, v36
	v_and_b32_e32 v3, 0xffff0000, v36
	v_lshlrev_b32_e32 v4, 16, v37
	v_and_b32_e32 v5, 0xffff0000, v37
	v_pk_mul_f32 v[8:9], v[14:15], v[8:9]
	v_pk_mul_f32 v[6:7], v[16:17], v[6:7]
	v_pk_mul_f32 v[2:3], v[8:9], v[2:3]
	v_pk_mul_f32 v[4:5], v[6:7], v[4:5]
	v_cvt_pk_bf16_f32 v2, v2, v3
	v_cvt_pk_bf16_f32 v3, v4, v5
	v_pk_mul_f32 v[6:7], v[82:83], v[58:59] op_sel_hi:[1,0]
	v_pk_mul_f32 v[8:9], v[80:81], v[58:59] op_sel_hi:[1,0]
	global_store_dwordx2 v[34:35], v[2:3], off offset:1536
	s_waitcnt vmcnt(23)
	v_lshlrev_b32_e32 v2, 16, v90
	v_and_b32_e32 v3, 0xffff0000, v90
	v_lshlrev_b32_e32 v4, 16, v91
	v_and_b32_e32 v5, 0xffff0000, v91
	v_pk_mul_f32 v[8:9], v[18:19], v[8:9]
	v_pk_mul_f32 v[6:7], v[20:21], v[6:7]
	v_pk_mul_f32 v[2:3], v[8:9], v[2:3]
	v_pk_mul_f32 v[4:5], v[6:7], v[4:5]
	v_cvt_pk_bf16_f32 v2, v2, v3
	v_cvt_pk_bf16_f32 v3, v4, v5
	v_pk_mul_f32 v[6:7], v[62:63], v[58:59] op_sel_hi:[1,0]
	v_pk_mul_f32 v[8:9], v[64:65], v[58:59] op_sel_hi:[1,0]
	global_store_dwordx2 v[34:35], v[2:3], off offset:2048
	s_waitcnt vmcnt(23)
	v_lshlrev_b32_e32 v2, 16, v76
	v_and_b32_e32 v3, 0xffff0000, v76
	v_lshlrev_b32_e32 v4, 16, v77
	v_and_b32_e32 v5, 0xffff0000, v77
	v_pk_mul_f32 v[8:9], v[22:23], v[8:9]
	v_pk_mul_f32 v[6:7], v[24:25], v[6:7]
	v_pk_mul_f32 v[2:3], v[8:9], v[2:3]
	v_pk_mul_f32 v[4:5], v[6:7], v[4:5]
	v_cvt_pk_bf16_f32 v2, v2, v3
	v_cvt_pk_bf16_f32 v3, v4, v5
	v_pk_mul_f32 v[6:7], v[56:57], v[58:59] op_sel_hi:[1,0]
	v_pk_mul_f32 v[8:9], v[78:79], v[58:59] op_sel_hi:[1,0]
	global_store_dwordx2 v[34:35], v[2:3], off offset:2560
	s_waitcnt vmcnt(23)
	v_lshlrev_b32_e32 v2, 16, v74
	v_and_b32_e32 v3, 0xffff0000, v74
	v_lshlrev_b32_e32 v4, 16, v75
	v_and_b32_e32 v5, 0xffff0000, v75
	v_pk_mul_f32 v[8:9], v[26:27], v[8:9]
	v_pk_mul_f32 v[6:7], v[28:29], v[6:7]
	v_pk_mul_f32 v[2:3], v[8:9], v[2:3]
	v_pk_mul_f32 v[4:5], v[6:7], v[4:5]
	v_cvt_pk_bf16_f32 v2, v2, v3
	v_cvt_pk_bf16_f32 v3, v4, v5
	v_pk_mul_f32 v[6:7], v[50:51], v[58:59] op_sel_hi:[1,0]
	v_pk_mul_f32 v[8:9], v[88:89], v[58:59] op_sel_hi:[1,0]
	global_store_dwordx2 v[34:35], v[2:3], off offset:3072
	s_waitcnt vmcnt(23)
	v_lshlrev_b32_e32 v2, 16, v68
	v_and_b32_e32 v3, 0xffff0000, v68
	v_lshlrev_b32_e32 v4, 16, v69
	v_and_b32_e32 v5, 0xffff0000, v69
	v_pk_mul_f32 v[8:9], v[30:31], v[8:9]
	v_pk_mul_f32 v[6:7], v[32:33], v[6:7]
	v_pk_mul_f32 v[2:3], v[8:9], v[2:3]
	v_pk_mul_f32 v[4:5], v[6:7], v[4:5]
	v_cvt_pk_bf16_f32 v2, v2, v3
	v_cvt_pk_bf16_f32 v3, v4, v5
	global_store_dwordx2 v[34:35], v[2:3], off offset:3584

; #define GAS __attribute__((address_space(1)))
; template <bool HG>
; __device__ __forceinline__ void readout_phase(const Args& a, Frame& F, const float* gain, int nrows) {
;     ...
;     for (int r = gw; r < nrows; r += NGW) {
;         const GAS v2u* f = (const GAS v2u*)(OF + (size_t)r * D) + F.lane; const GAS v2u* bk = (const GAS v2u*)(OB + (size_t)r * D) + F.lane;
;         const GAS v2u* g8 = (const GAS v2u*)(G + (size_t)r * D) + F.lane;
;         f32x4 v[8]; float ssj[8]; float tot = 0.f;
; #pragma unroll
;         for (int j = 0; j < 8; ++j) { const v2u fa = EW_NT ? __builtin_nontemporal_load(f + 64 * j) : f[64 * j], fb = EW_NT ? __builtin_nontemporal_load(bk + 64 * j) : bk[64 * j]; v[j] = (f32x4){bflo(fa.x) + bflo(fb.x), bfhi(fa.x) + bfhi(fb.x), bflo(fa.y) + bflo(fb.y), bfhi(fa.y) + bfhi(fb.y)}; ssj[j] = (v[j][0] * v[j][0] + v[j][1] * v[j][1]) + (v[j][2] * v[j][2] + v[j][3] * v[j][3]); tot += ssj[j]; }
.LBB0_859:
	v_lshl_add_u64 v[36:37], v[2:3], 0, v[0:1]
	v_add_co_u32_e32 v6, vcc, 0xf7800000, v36
	v_lshl_add_u64 v[4:5], v[36:37], 0, s[52:53]
	s_nop 0
	v_addc_co_u32_e32 v7, vcc, -1, v37, vcc
	global_load_dwordx2 v[6:7], v[6:7], off
	s_nop 0
	global_load_dwordx2 v[8:9], v[36:37], off
	s_mov_b32 s6, 0xe6800000
	s_mov_b32 s7, -1
	s_add_i32 s8, s8, s42
	v_lshl_add_u64 v[2:3], v[2:3], 0, s[74:75]
	s_cmp_lt_i32 s8, s47
	s_waitcnt vmcnt(1)
	v_lshlrev_b32_e32 v10, 16, v6
	v_and_b32_e32 v11, 0xffff0000, v6
	s_waitcnt vmcnt(0)
	v_lshlrev_b32_e32 v12, 16, v8
	v_and_b32_e32 v13, 0xffff0000, v8
	v_lshlrev_b32_e32 v6, 16, v7
	v_and_b32_e32 v7, 0xffff0000, v7
	v_lshlrev_b32_e32 v8, 16, v9
	v_and_b32_e32 v9, 0xffff0000, v9
	v_pk_add_f32 v[38:39], v[10:11], v[12:13]
	v_pk_add_f32 v[40:41], v[6:7], v[8:9]
	v_mov_b32_e32 v8, v39
	v_mov_b32_e32 v9, v41
	v_mov_b32_e32 v6, v38
	v_mov_b32_e32 v7, v40
	v_pk_mul_f32 v[8:9], v[8:9], v[8:9]
	s_nop 0
	v_pk_fma_f32 v[6:7], v[6:7], v[6:7], v[8:9]
	s_nop 0
	v_add_f32_e32 v45, v6, v7
	global_load_dwordx2 v[6:7], v[4:5], off offset:512
	global_load_dwordx2 v[8:9], v[36:37], off offset:512
	v_add_f32_dpp v45, v45, v45 quad_perm:[1,0,3,2] row_mask:0xf bank_mask:0xf bound_ctrl:1
	s_waitcnt vmcnt(1)
	v_lshlrev_b32_e32 v10, 16, v6
	v_and_b32_e32 v11, 0xffff0000, v6
	s_waitcnt vmcnt(0)
	v_lshlrev_b32_e32 v12, 16, v8
	v_and_b32_e32 v13, 0xffff0000, v8
	v_lshlrev_b32_e32 v6, 16, v7
	v_and_b32_e32 v7, 0xffff0000, v7
	v_lshlrev_b32_e32 v8, 16, v9
	v_and_b32_e32 v9, 0xffff0000, v9
	v_pk_add_f32 v[32:33], v[10:11], v[12:13]
	v_pk_add_f32 v[34:35], v[6:7], v[8:9]
	v_mov_b32_e32 v8, v33
	v_mov_b32_e32 v9, v35
	v_mov_b32_e32 v6, v32
	v_mov_b32_e32 v7, v34
	v_pk_mul_f32 v[8:9], v[8:9], v[8:9]
	v_add_f32_dpp v45, v45, v45 quad_perm:[2,3,0,1] row_mask:0xf bank_mask:0xf bound_ctrl:1
	v_pk_fma_f32 v[6:7], v[6:7], v[6:7], v[8:9]
	s_nop 0
	v_add_f32_e32 v52, v6, v7
	global_load_dwordx2 v[6:7], v[4:5], off offset:1024
	global_load_dwordx2 v[8:9], v[36:37], off offset:1024
	v_add_f32_dpp v45, v45, v45 row_half_mirror row_mask:0xf bank_mask:0xf bound_ctrl:1
	s_waitcnt vmcnt(1)
	v_lshlrev_b32_e32 v10, 16, v6
	v_and_b32_e32 v11, 0xffff0000, v6
	s_waitcnt vmcnt(0)
	v_lshlrev_b32_e32 v12, 16, v8
	v_and_b32_e32 v13, 0xffff0000, v8
	v_lshlrev_b32_e32 v6, 16, v7
	v_and_b32_e32 v7, 0xffff0000, v7
	v_lshlrev_b32_e32 v8, 16, v9
	v_and_b32_e32 v9, 0xffff0000, v9
	v_pk_add_f32 v[26:27], v[10:11], v[12:13]
	v_pk_add_f32 v[28:29], v[6:7], v[8:9]
	v_mov_b32_e32 v8, v27
	v_mov_b32_e32 v9, v29
	v_mov_b32_e32 v6, v26
	v_mov_b32_e32 v7, v28
	v_pk_mul_f32 v[8:9], v[8:9], v[8:9]
	v_add_f32_dpp v45, v45, v45 row_mirror row_mask:0xf bank_mask:0xf bound_ctrl:1
	v_pk_fma_f32 v[6:7], v[6:7], v[6:7], v[8:9]
	v_readlane_b32 s9, v45, 16
	v_add_f32_e32 v53, v6, v7
	global_load_dwordx2 v[6:7], v[4:5], off offset:1536
	global_load_dwordx2 v[8:9], v[36:37], off offset:1536
	v_readlane_b32 s10, v45, 48
	v_mov_b32_e32 v46, s9
	s_waitcnt vmcnt(1)
	v_lshlrev_b32_e32 v10, 16, v6
	v_and_b32_e32 v11, 0xffff0000, v6
	s_waitcnt vmcnt(0)
	v_lshlrev_b32_e32 v12, 16, v8
	v_and_b32_e32 v13, 0xffff0000, v8
	v_lshlrev_b32_e32 v6, 16, v7
	v_and_b32_e32 v7, 0xffff0000, v7
	v_lshlrev_b32_e32 v8, 16, v9
	v_and_b32_e32 v9, 0xffff0000, v9
	v_pk_add_f32 v[20:21], v[10:11], v[12:13]
	v_pk_add_f32 v[22:23], v[6:7], v[8:9]
	v_mov_b32_e32 v8, v21
	v_mov_b32_e32 v9, v23
	v_mov_b32_e32 v6, v20
	v_mov_b32_e32 v7, v22
	v_pk_mul_f32 v[8:9], v[8:9], v[8:9]
	v_mov_b32_e32 v47, s10
	v_pk_fma_f32 v[6:7], v[6:7], v[6:7], v[8:9]
	s_nop 0
	v_add_f32_e32 v54, v6, v7
	global_load_dwordx2 v[6:7], v[4:5], off offset:2048
	global_load_dwordx2 v[8:9], v[36:37], off offset:2048
	s_waitcnt vmcnt(1)
	v_lshlrev_b32_e32 v10, 16, v6
	v_and_b32_e32 v11, 0xffff0000, v6
	s_waitcnt vmcnt(0)
	v_lshlrev_b32_e32 v12, 16, v8
	v_and_b32_e32 v13, 0xffff0000, v8
	v_lshlrev_b32_e32 v6, 16, v7
	v_and_b32_e32 v7, 0xffff0000, v7
	v_lshlrev_b32_e32 v8, 16, v9
	v_and_b32_e32 v9, 0xffff0000, v9
	v_pk_add_f32 v[16:17], v[10:11], v[12:13]
	v_pk_add_f32 v[18:19], v[6:7], v[8:9]
	v_mov_b32_e32 v8, v17
	v_mov_b32_e32 v9, v19
	v_mov_b32_e32 v6, v16
	v_mov_b32_e32 v7, v18
	v_pk_mul_f32 v[8:9], v[8:9], v[8:9]
	s_nop 0
	v_pk_fma_f32 v[6:7], v[6:7], v[6:7], v[8:9]
	s_nop 0
	v_add_f32_e32 v55, v6, v7
	global_load_dwordx2 v[6:7], v[4:5], off offset:2560
	global_load_dwordx2 v[8:9], v[36:37], off offset:2560
	s_waitcnt vmcnt(1)
	v_lshlrev_b32_e32 v10, 16, v6
	v_and_b32_e32 v11, 0xffff0000, v6
	s_waitcnt vmcnt(0)
	v_lshlrev_b32_e32 v12, 16, v8
	v_and_b32_e32 v13, 0xffff0000, v8
	v_lshlrev_b32_e32 v6, 16, v7
	v_and_b32_e32 v7, 0xffff0000, v7
	v_lshlrev_b32_e32 v8, 16, v9
	v_and_b32_e32 v9, 0xffff0000, v9
	v_pk_add_f32 v[12:13], v[10:11], v[12:13]
	v_pk_add_f32 v[14:15], v[6:7], v[8:9]
	v_mov_b32_e32 v8, v13
	v_mov_b32_e32 v9, v15
	v_mov_b32_e32 v6, v12
	v_mov_b32_e32 v7, v14
	v_pk_mul_f32 v[8:9], v[8:9], v[8:9]
	s_nop 0
	v_pk_fma_f32 v[6:7], v[6:7], v[6:7], v[8:9]
	s_nop 0
	v_add_f32_e32 v44, v6, v7
	global_load_dwordx2 v[6:7], v[4:5], off offset:3072
	global_load_dwordx2 v[10:11], v[36:37], off offset:3072
	s_waitcnt vmcnt(1)
	v_lshlrev_b32_e32 v8, 16, v6
	v_and_b32_e32 v9, 0xffff0000, v6
	s_waitcnt vmcnt(0)
	v_lshlrev_b32_e32 v24, 16, v10
	v_and_b32_e32 v25, 0xffff0000, v10
	v_lshlrev_b32_e32 v6, 16, v7
	v_and_b32_e32 v7, 0xffff0000, v7
	v_lshlrev_b32_e32 v10, 16, v11
	v_and_b32_e32 v11, 0xffff0000, v11
	v_pk_add_f32 v[8:9], v[8:9], v[24:25]
	v_pk_add_f32 v[10:11], v[6:7], v[10:11]
	v_mov_b32_e32 v24, v9
	v_mov_b32_e32 v25, v11
	v_mov_b32_e32 v6, v8
	v_mov_b32_e32 v7, v10
	v_pk_mul_f32 v[24:25], v[24:25], v[24:25]
	s_nop 0
	v_pk_fma_f32 v[6:7], v[6:7], v[6:7], v[24:25]
	s_nop 0
	v_add_f32_e32 v43, v6, v7
	global_load_dwordx2 v[6:7], v[4:5], off offset:3584
	global_load_dwordx2 v[24:25], v[36:37], off offset:3584
	s_waitcnt vmcnt(1)
; #define GAS __attribute__((address_space(1)))
; __device__ __forceinline__ unsigned pk2(float lo, float hi) { const f32x2_t v = {lo, hi}; const bf16x2_t b = __builtin_convertvector(v, bf16x2_t); return __builtin_bit_cast(unsigned, b); }
; template <bool HG>
; __device__ __forceinline__ void readout_phase(const Args& a, Frame& F, const float* gain, int nrows) {
;     ...
;         for (int j = 0; j < 8; ++j) { const v2u fa = EW_NT ? __builtin_nontemporal_load(f + 64 * j) : f[64 * j], fb = EW_NT ? __builtin_nontemporal_load(bk + 64 * j) : bk[64 * j]; v[j] = (f32x4){bflo(fa.x) + bflo(fb.x), bfhi(fa.x) + bfhi(fb.x), bflo(fa.y) + bflo(fb.y), bfhi(fa.y) + bfhi(fb.y)}; ssj[j] = (v[j][0] * v[j][0] + v[j][1] * v[j][1]) + (v[j][2] * v[j][2] + v[j][3] * v[j][3]); tot += ssj[j]; }
;         float rs_all = 0.f;
;         if (HG) rs_all = 1.0f / sqrtf(wave_sum(tot) * (1.0f / D) + EPS);
;         GAS v2u* o8 = (GAS v2u*)(HN + (size_t)r * D) + F.lane;
; #pragma unroll
;         for (int j = 0; j < 8; ++j) {
;             float rs = rs_all; f32x4 gn = {1.f, 1.f, 1.f, 1.f};
;             if (!HG) rs = 1.0f / sqrtf(wave_sum(ssj[j]) * (1.0f / 256.0f) + EPS);
;             else gn = *(const GAS f32x4*)(gain + 256 * j + 4 * F.lane);
;             const v2u gw2 = EW_NT ? __builtin_nontemporal_load(g8 + 64 * j) : g8[64 * j];
;             const f32x4 gt = {bflo(gw2.x), bfhi(gw2.x), bflo(gw2.y), bfhi(gw2.y)};
;             const f32x4 y = (v[j] * rs) * gn * gt;
;             v2u w; w.x = pk2(y[0], y[1]); w.y = pk2(y[2], y[3]); o8[64 * j] = w; }
	v_lshlrev_b32_e32 v4, 16, v6
	v_and_b32_e32 v5, 0xffff0000, v6
	s_waitcnt vmcnt(0)
	v_lshlrev_b32_e32 v30, 16, v24
	v_and_b32_e32 v31, 0xffff0000, v24
	v_lshlrev_b32_e32 v6, 16, v7
	v_and_b32_e32 v7, 0xffff0000, v7
	v_lshlrev_b32_e32 v24, 16, v25
	v_and_b32_e32 v25, 0xffff0000, v25
	v_pk_add_f32 v[4:5], v[4:5], v[30:31]
	v_pk_add_f32 v[6:7], v[6:7], v[24:25]
	v_mov_b32_e32 v30, v5
	v_mov_b32_e32 v31, v7
	v_mov_b32_e32 v24, v4
	v_mov_b32_e32 v25, v6
	v_pk_mul_f32 v[30:31], v[30:31], v[30:31]
	s_nop 0
	v_pk_fma_f32 v[24:25], v[24:25], v[24:25], v[30:31]
	v_lshl_add_u64 v[30:31], v[36:37], 0, s[6:7]
	v_readlane_b32 s6, v45, 0
	v_readlane_b32 s7, v45, 32
	v_add_f32_e32 v42, v24, v25
	v_lshl_add_u64 v[24:25], v[36:37], 0, s[12:13]
	v_pk_add_f32 v[46:47], s[6:7], v[46:47]
	s_nop 0
	v_add_f32_e32 v45, v46, v47
	v_fmamk_f32 v45, v45, 0x3b800000, v252
	v_cmp_gt_f32_e32 vcc, s55, v45
	v_mul_f32_e32 v46, 0x4f800000, v45
	s_nop 0
	v_cndmask_b32_e32 v45, v45, v46, vcc
	v_sqrt_f32_e32 v46, v45
	s_nop 0
	v_add_u32_e32 v47, -1, v46
	v_fma_f32 v48, -v47, v46, v45
	v_cmp_ge_f32_e64 s[6:7], 0, v48
	v_add_u32_e32 v48, 1, v46
	s_nop 0
	v_cndmask_b32_e64 v47, v46, v47, s[6:7]
	v_fma_f32 v46, -v48, v46, v45
	v_cmp_lt_f32_e64 s[6:7], 0, v46
	s_nop 1
	v_cndmask_b32_e64 v46, v47, v48, s[6:7]
	v_mul_f32_e32 v47, 0x37800000, v46
	v_cndmask_b32_e32 v46, v46, v47, vcc
	v_cmp_class_f32_e32 vcc, v45, v253
	s_nop 1
	v_cndmask_b32_e32 v45, v46, v45, vcc
	v_div_scale_f32 v46, s[6:7], v45, v45, 1.0
	v_rcp_f32_e32 v47, v46
	s_mov_b32 s6, 0xe6800000
	v_fma_f32 v48, -v46, v47, 1.0
	v_fmac_f32_e32 v47, v48, v47
	v_div_scale_f32 v48, vcc, 1.0, v45, 1.0
	v_mul_f32_e32 v49, v48, v47
	v_fma_f32 v50, -v46, v49, v48
	v_fmac_f32_e32 v49, v50, v47
	v_fma_f32 v46, -v46, v49, v48
	v_div_fmas_f32 v46, v46, v47, v49
	v_add_co_u32_e32 v48, vcc, s6, v36
	v_div_fixup_f32 v46, v46, v45, 1.0
	s_nop 0
	v_addc_co_u32_e32 v49, vcc, -1, v37, vcc
	global_load_dwordx2 v[48:49], v[48:49], off
	v_pk_mul_f32 v[38:39], v[38:39], v[46:47] op_sel_hi:[1,0]
	v_pk_mul_f32 v[40:41], v[40:41], v[46:47] op_sel_hi:[1,0]
	v_add_co_u32_e32 v36, vcc, s67, v36
	s_waitcnt vmcnt(0)
	v_lshlrev_b32_e32 v50, 16, v48
	v_and_b32_e32 v51, 0xffff0000, v48
	v_lshlrev_b32_e32 v48, 16, v49
	v_and_b32_e32 v49, 0xffff0000, v49
	v_pk_mul_f32 v[40:41], v[40:41], v[48:49]
	v_pk_mul_f32 v[38:39], v[38:39], v[50:51]
	v_addc_co_u32_e32 v37, vcc, -1, v37, vcc
	v_cvt_pk_bf16_f32 v38, v38, v39
	v_cvt_pk_bf16_f32 v39, v40, v41
	global_store_dwordx2 v[36:37], v[38:39], off
	v_add_f32_dpp v36, v52, v52 quad_perm:[1,0,3,2] row_mask:0xf bank_mask:0xf bound_ctrl:1
	s_nop 1
	v_add_f32_dpp v36, v36, v36 quad_perm:[2,3,0,1] row_mask:0xf bank_mask:0xf bound_ctrl:1
	s_nop 1
	v_add_f32_dpp v36, v36, v36 row_half_mirror row_mask:0xf bank_mask:0xf bound_ctrl:1
	s_nop 1
	v_add_f32_dpp v36, v36, v36 row_mirror row_mask:0xf bank_mask:0xf bound_ctrl:1
	s_nop 0
	v_readlane_b32 s9, v36, 16
	v_readlane_b32 s10, v36, 48
	v_readlane_b32 s6, v36, 0
	v_readlane_b32 s7, v36, 32
	v_mov_b32_e32 v36, s9
	v_mov_b32_e32 v37, s10
	v_pk_add_f32 v[36:37], s[6:7], v[36:37]
	s_nop 0
	v_add_f32_e32 v36, v36, v37
	v_fmamk_f32 v36, v36, 0x3b800000, v252
	v_cmp_gt_f32_e32 vcc, s55, v36
	v_mul_f32_e32 v37, 0x4f800000, v36
	s_nop 0
	v_cndmask_b32_e32 v36, v36, v37, vcc
	v_sqrt_f32_e32 v37, v36
	s_nop 0
	v_add_u32_e32 v38, -1, v37
	v_fma_f32 v39, -v38, v37, v36
	v_cmp_ge_f32_e64 s[6:7], 0, v39
	v_add_u32_e32 v39, 1, v37
	s_nop 0
	v_cndmask_b32_e64 v38, v37, v38, s[6:7]
	v_fma_f32 v37, -v39, v37, v36
	v_cmp_lt_f32_e64 s[6:7], 0, v37
	s_nop 1
	v_cndmask_b32_e64 v37, v38, v39, s[6:7]
	v_mul_f32_e32 v38, 0x37800000, v37
	v_cndmask_b32_e32 v37, v37, v38, vcc
	v_cmp_class_f32_e32 vcc, v36, v253
	s_nop 1
	v_cndmask_b32_e32 v36, v37, v36, vcc
	v_div_scale_f32 v37, s[6:7], v36, v36, 1.0
	v_rcp_f32_e32 v38, v37
	s_nop 0
	v_fma_f32 v39, -v37, v38, 1.0
	v_fmac_f32_e32 v38, v39, v38
	v_div_scale_f32 v39, vcc, 1.0, v36, 1.0
	v_mul_f32_e32 v40, v39, v38
	v_fma_f32 v41, -v37, v40, v39
	v_fmac_f32_e32 v40, v41, v38
	v_fma_f32 v37, -v37, v40, v39
	v_div_fmas_f32 v37, v37, v38, v40
	global_load_dwordx2 v[38:39], v[30:31], off offset:512
	v_div_fixup_f32 v36, v37, v36, 1.0
	v_pk_mul_f32 v[32:33], v[32:33], v[36:37] op_sel_hi:[1,0]
	v_pk_mul_f32 v[34:35], v[34:35], v[36:37] op_sel_hi:[1,0]
	s_waitcnt vmcnt(0)
	v_lshlrev_b32_e32 v40, 16, v38
	v_and_b32_e32 v41, 0xffff0000, v38
	v_lshlrev_b32_e32 v38, 16, v39
	v_and_b32_e32 v39, 0xffff0000, v39
	v_pk_mul_f32 v[34:35], v[34:35], v[38:39]
	v_pk_mul_f32 v[32:33], v[32:33], v[40:41]
	s_nop 0
	v_cvt_pk_bf16_f32 v32, v32, v33
	v_cvt_pk_bf16_f32 v33, v34, v35
	global_store_dwordx2 v[24:25], v[32:33], off offset:512
	v_add_f32_dpp v32, v53, v53 quad_perm:[1,0,3,2] row_mask:0xf bank_mask:0xf bound_ctrl:1
	s_nop 1
	v_add_f32_dpp v32, v32, v32 quad_perm:[2,3,0,1] row_mask:0xf bank_mask:0xf bound_ctrl:1
	s_nop 1
	v_add_f32_dpp v32, v32, v32 row_half_mirror row_mask:0xf bank_mask:0xf bound_ctrl:1
	s_nop 1
	v_add_f32_dpp v32, v32, v32 row_mirror row_mask:0xf bank_mask:0xf bound_ctrl:1
	s_nop 0
	v_readlane_b32 s9, v32, 16
	v_readlane_b32 s10, v32, 48
	v_readlane_b32 s6, v32, 0
	v_readlane_b32 s7, v32, 32
	v_mov_b32_e32 v32, s9
	v_mov_b32_e32 v33, s10
	v_pk_add_f32 v[32:33], s[6:7], v[32:33]
	s_nop 0
	v_add_f32_e32 v32, v32, v33
	v_fmamk_f32 v32, v32, 0x3b800000, v252
	v_cmp_gt_f32_e32 vcc, s55, v32
	v_mul_f32_e32 v33, 0x4f800000, v32
	s_nop 0
	v_cndmask_b32_e32 v32, v32, v33, vcc
	v_sqrt_f32_e32 v33, v32
	s_nop 0
	v_add_u32_e32 v34, -1, v33
	v_fma_f32 v35, -v34, v33, v32
	v_cmp_ge_f32_e64 s[6:7], 0, v35
	v_add_u32_e32 v35, 1, v33
	s_nop 0
	v_cndmask_b32_e64 v34, v33, v34, s[6:7]
	v_fma_f32 v33, -v35, v33, v32
	v_cmp_lt_f32_e64 s[6:7], 0, v33
	s_nop 1
	v_cndmask_b32_e64 v33, v34, v35, s[6:7]
	v_mul_f32_e32 v34, 0x37800000, v33
	v_cndmask_b32_e32 v33, v33, v34, vcc
	v_cmp_class_f32_e32 vcc, v32, v253
	s_nop 1
	v_cndmask_b32_e32 v32, v33, v32, vcc
	v_div_scale_f32 v33, s[6:7], v32, v32, 1.0
	v_rcp_f32_e32 v34, v33
	s_nop 0
	v_fma_f32 v35, -v33, v34, 1.0
	v_fmac_f32_e32 v34, v35, v34
	v_div_scale_f32 v35, vcc, 1.0, v32, 1.0
	v_mul_f32_e32 v36, v35, v34
	v_fma_f32 v37, -v33, v36, v35
	v_fmac_f32_e32 v36, v37, v34
	v_fma_f32 v33, -v33, v36, v35
	v_div_fmas_f32 v33, v33, v34, v36
	global_load_dwordx2 v[34:35], v[30:31], off offset:1024
	v_div_fixup_f32 v32, v33, v32, 1.0
	v_pk_mul_f32 v[26:27], v[26:27], v[32:33] op_sel_hi:[1,0]
	v_pk_mul_f32 v[28:29], v[28:29], v[32:33] op_sel_hi:[1,0]
	s_waitcnt vmcnt(0)
; #define GAS __attribute__((address_space(1)))
; __device__ __forceinline__ unsigned pk2(float lo, float hi) { const f32x2_t v = {lo, hi}; const bf16x2_t b = __builtin_convertvector(v, bf16x2_t); return __builtin_bit_cast(unsigned, b); }
; template <bool HG>
; __device__ __forceinline__ void readout_phase(const Args& a, Frame& F, const float* gain, int nrows) {
;     ...
;             if (!HG) rs = 1.0f / sqrtf(wave_sum(ssj[j]) * (1.0f / 256.0f) + EPS);
;             else gn = *(const GAS f32x4*)(gain + 256 * j + 4 * F.lane);
;             const v2u gw2 = EW_NT ? __builtin_nontemporal_load(g8 + 64 * j) : g8[64 * j];
;             const f32x4 gt = {bflo(gw2.x), bfhi(gw2.x), bflo(gw2.y), bfhi(gw2.y)};
;             const f32x4 y = (v[j] * rs) * gn * gt;
;             v2u w; w.x = pk2(y[0], y[1]); w.y = pk2(y[2], y[3]); o8[64 * j] = w; }
	v_lshlrev_b32_e32 v36, 16, v34
	v_and_b32_e32 v37, 0xffff0000, v34
	v_lshlrev_b32_e32 v34, 16, v35
	v_and_b32_e32 v35, 0xffff0000, v35
	v_pk_mul_f32 v[28:29], v[28:29], v[34:35]
	v_pk_mul_f32 v[26:27], v[26:27], v[36:37]
	s_nop 0
	v_cvt_pk_bf16_f32 v26, v26, v27
	v_cvt_pk_bf16_f32 v27, v28, v29
	global_store_dwordx2 v[24:25], v[26:27], off offset:1024
	v_add_f32_dpp v26, v54, v54 quad_perm:[1,0,3,2] row_mask:0xf bank_mask:0xf bound_ctrl:1
	s_nop 1
	v_add_f32_dpp v26, v26, v26 quad_perm:[2,3,0,1] row_mask:0xf bank_mask:0xf bound_ctrl:1
	s_nop 1
	v_add_f32_dpp v26, v26, v26 row_half_mirror row_mask:0xf bank_mask:0xf bound_ctrl:1
	s_nop 1
	v_add_f32_dpp v26, v26, v26 row_mirror row_mask:0xf bank_mask:0xf bound_ctrl:1
	s_nop 0
	v_readlane_b32 s9, v26, 16
	v_readlane_b32 s10, v26, 48
	v_readlane_b32 s6, v26, 0
	v_readlane_b32 s7, v26, 32
	v_mov_b32_e32 v26, s9
	v_mov_b32_e32 v27, s10
	v_pk_add_f32 v[26:27], s[6:7], v[26:27]
	s_nop 0
	v_add_f32_e32 v26, v26, v27
	v_fmamk_f32 v26, v26, 0x3b800000, v252
	v_cmp_gt_f32_e32 vcc, s55, v26
	v_mul_f32_e32 v27, 0x4f800000, v26
	s_nop 0
	v_cndmask_b32_e32 v26, v26, v27, vcc
	v_sqrt_f32_e32 v27, v26
	s_nop 0
	v_add_u32_e32 v28, -1, v27
	v_fma_f32 v29, -v28, v27, v26
	v_cmp_ge_f32_e64 s[6:7], 0, v29
	v_add_u32_e32 v29, 1, v27
	s_nop 0
	v_cndmask_b32_e64 v28, v27, v28, s[6:7]
	v_fma_f32 v27, -v29, v27, v26
	v_cmp_lt_f32_e64 s[6:7], 0, v27
	s_nop 1
	v_cndmask_b32_e64 v27, v28, v29, s[6:7]
	v_mul_f32_e32 v28, 0x37800000, v27
	v_cndmask_b32_e32 v27, v27, v28, vcc
	v_cmp_class_f32_e32 vcc, v26, v253
	s_nop 1
	v_cndmask_b32_e32 v26, v27, v26, vcc
	v_div_scale_f32 v27, s[6:7], v26, v26, 1.0
	v_rcp_f32_e32 v28, v27
	s_nop 0
	v_fma_f32 v29, -v27, v28, 1.0
	v_fmac_f32_e32 v28, v29, v28
	v_div_scale_f32 v29, vcc, 1.0, v26, 1.0
	v_mul_f32_e32 v32, v29, v28
	v_fma_f32 v33, -v27, v32, v29
	v_fmac_f32_e32 v32, v33, v28
	v_fma_f32 v27, -v27, v32, v29
	v_div_fmas_f32 v27, v27, v28, v32
	global_load_dwordx2 v[28:29], v[30:31], off offset:1536
	v_div_fixup_f32 v26, v27, v26, 1.0
	v_pk_mul_f32 v[20:21], v[20:21], v[26:27] op_sel_hi:[1,0]
	v_pk_mul_f32 v[22:23], v[22:23], v[26:27] op_sel_hi:[1,0]
	s_waitcnt vmcnt(0)
	v_lshlrev_b32_e32 v32, 16, v28
	v_and_b32_e32 v33, 0xffff0000, v28
	v_lshlrev_b32_e32 v28, 16, v29
	v_and_b32_e32 v29, 0xffff0000, v29
	v_pk_mul_f32 v[22:23], v[22:23], v[28:29]
	v_pk_mul_f32 v[20:21], v[20:21], v[32:33]
	s_nop 0
	v_cvt_pk_bf16_f32 v20, v20, v21
	v_cvt_pk_bf16_f32 v21, v22, v23
	global_store_dwordx2 v[24:25], v[20:21], off offset:1536
	v_add_f32_dpp v20, v55, v55 quad_perm:[1,0,3,2] row_mask:0xf bank_mask:0xf bound_ctrl:1
	s_nop 1
	v_add_f32_dpp v20, v20, v20 quad_perm:[2,3,0,1] row_mask:0xf bank_mask:0xf bound_ctrl:1
	s_nop 1
	v_add_f32_dpp v20, v20, v20 row_half_mirror row_mask:0xf bank_mask:0xf bound_ctrl:1
	s_nop 1
	v_add_f32_dpp v20, v20, v20 row_mirror row_mask:0xf bank_mask:0xf bound_ctrl:1
	s_nop 0
	v_readlane_b32 s9, v20, 16
	v_readlane_b32 s10, v20, 48
	v_readlane_b32 s6, v20, 0
	v_readlane_b32 s7, v20, 32
	v_mov_b32_e32 v20, s9
	v_mov_b32_e32 v21, s10
	v_pk_add_f32 v[20:21], s[6:7], v[20:21]
	s_nop 0
	v_add_f32_e32 v20, v20, v21
	v_fmamk_f32 v20, v20, 0x3b800000, v252
	v_cmp_gt_f32_e32 vcc, s55, v20
	v_mul_f32_e32 v21, 0x4f800000, v20
	s_nop 0
	v_cndmask_b32_e32 v20, v20, v21, vcc
	v_sqrt_f32_e32 v21, v20
	s_nop 0
	v_add_u32_e32 v22, -1, v21
	v_fma_f32 v23, -v22, v21, v20
	v_cmp_ge_f32_e64 s[6:7], 0, v23
	v_add_u32_e32 v23, 1, v21
	s_nop 0
	v_cndmask_b32_e64 v22, v21, v22, s[6:7]
	v_fma_f32 v21, -v23, v21, v20
	v_cmp_lt_f32_e64 s[6:7], 0, v21
	s_nop 1
	v_cndmask_b32_e64 v21, v22, v23, s[6:7]
	v_mul_f32_e32 v22, 0x37800000, v21
	v_cndmask_b32_e32 v21, v21, v22, vcc
	v_cmp_class_f32_e32 vcc, v20, v253
	s_nop 1
	v_cndmask_b32_e32 v20, v21, v20, vcc
	v_div_scale_f32 v21, s[6:7], v20, v20, 1.0
	v_rcp_f32_e32 v22, v21
	s_nop 0
	v_fma_f32 v23, -v21, v22, 1.0
	v_fmac_f32_e32 v22, v23, v22
	v_div_scale_f32 v23, vcc, 1.0, v20, 1.0
	v_mul_f32_e32 v26, v23, v22
	v_fma_f32 v27, -v21, v26, v23
	v_fmac_f32_e32 v26, v27, v22
	v_fma_f32 v21, -v21, v26, v23
	v_div_fmas_f32 v21, v21, v22, v26
	global_load_dwordx2 v[22:23], v[30:31], off offset:2048
	v_div_fixup_f32 v20, v21, v20, 1.0
	v_pk_mul_f32 v[16:17], v[16:17], v[20:21] op_sel_hi:[1,0]
	v_pk_mul_f32 v[18:19], v[18:19], v[20:21] op_sel_hi:[1,0]
	s_waitcnt vmcnt(0)
	v_lshlrev_b32_e32 v26, 16, v22
	v_and_b32_e32 v27, 0xffff0000, v22
	v_lshlrev_b32_e32 v22, 16, v23
	v_and_b32_e32 v23, 0xffff0000, v23
	v_pk_mul_f32 v[18:19], v[18:19], v[22:23]
	v_pk_mul_f32 v[16:17], v[16:17], v[26:27]
	s_nop 0
	v_cvt_pk_bf16_f32 v16, v16, v17
	v_cvt_pk_bf16_f32 v17, v18, v19
	global_store_dwordx2 v[24:25], v[16:17], off offset:2048
	v_add_f32_dpp v16, v44, v44 quad_perm:[1,0,3,2] row_mask:0xf bank_mask:0xf bound_ctrl:1
	s_nop 1
	v_add_f32_dpp v16, v16, v16 quad_perm:[2,3,0,1] row_mask:0xf bank_mask:0xf bound_ctrl:1
	s_nop 1
	v_add_f32_dpp v16, v16, v16 row_half_mirror row_mask:0xf bank_mask:0xf bound_ctrl:1
	s_nop 1
	v_add_f32_dpp v16, v16, v16 row_mirror row_mask:0xf bank_mask:0xf bound_ctrl:1
	s_nop 0
	v_readlane_b32 s9, v16, 16
	v_readlane_b32 s10, v16, 48
	v_readlane_b32 s6, v16, 0
	v_readlane_b32 s7, v16, 32
	v_mov_b32_e32 v16, s9
	v_mov_b32_e32 v17, s10
	v_pk_add_f32 v[16:17], s[6:7], v[16:17]
	s_nop 0
	v_add_f32_e32 v16, v16, v17
	v_fmamk_f32 v16, v16, 0x3b800000, v252
	v_cmp_gt_f32_e32 vcc, s55, v16
	v_mul_f32_e32 v17, 0x4f800000, v16
	s_nop 0
	v_cndmask_b32_e32 v16, v16, v17, vcc
	v_sqrt_f32_e32 v17, v16
	s_nop 0
	v_add_u32_e32 v18, -1, v17
	v_fma_f32 v19, -v18, v17, v16
	v_cmp_ge_f32_e64 s[6:7], 0, v19
	v_add_u32_e32 v19, 1, v17
	s_nop 0
	v_cndmask_b32_e64 v18, v17, v18, s[6:7]
	v_fma_f32 v17, -v19, v17, v16
	v_cmp_lt_f32_e64 s[6:7], 0, v17
	s_nop 1
	v_cndmask_b32_e64 v17, v18, v19, s[6:7]
	v_mul_f32_e32 v18, 0x37800000, v17
	v_cndmask_b32_e32 v17, v17, v18, vcc
	v_cmp_class_f32_e32 vcc, v16, v253
	s_nop 1
	v_cndmask_b32_e32 v16, v17, v16, vcc
	v_div_scale_f32 v17, s[6:7], v16, v16, 1.0
	v_rcp_f32_e32 v18, v17
	s_nop 0
	v_fma_f32 v19, -v17, v18, 1.0
	v_fmac_f32_e32 v18, v19, v18
	v_div_scale_f32 v19, vcc, 1.0, v16, 1.0
	v_mul_f32_e32 v20, v19, v18
	v_fma_f32 v21, -v17, v20, v19
	v_fmac_f32_e32 v20, v21, v18
	v_fma_f32 v17, -v17, v20, v19
	v_div_fmas_f32 v17, v17, v18, v20
	global_load_dwordx2 v[18:19], v[30:31], off offset:2560
	v_div_fixup_f32 v16, v17, v16, 1.0
	v_pk_mul_f32 v[12:13], v[12:13], v[16:17] op_sel_hi:[1,0]
	v_pk_mul_f32 v[14:15], v[14:15], v[16:17] op_sel_hi:[1,0]
	s_waitcnt vmcnt(0)
; #define GAS __attribute__((address_space(1)))
; __device__ __forceinline__ unsigned pk2(float lo, float hi) { const f32x2_t v = {lo, hi}; const bf16x2_t b = __builtin_convertvector(v, bf16x2_t); return __builtin_bit_cast(unsigned, b); }
; template <bool HG>
; __device__ __forceinline__ void readout_phase(const Args& a, Frame& F, const float* gain, int nrows) {
;     ...
;             if (!HG) rs = 1.0f / sqrtf(wave_sum(ssj[j]) * (1.0f / 256.0f) + EPS);
;             else gn = *(const GAS f32x4*)(gain + 256 * j + 4 * F.lane);
;             const v2u gw2 = EW_NT ? __builtin_nontemporal_load(g8 + 64 * j) : g8[64 * j];
;             const f32x4 gt = {bflo(gw2.x), bfhi(gw2.x), bflo(gw2.y), bfhi(gw2.y)};
;             const f32x4 y = (v[j] * rs) * gn * gt;
;             v2u w; w.x = pk2(y[0], y[1]); w.y = pk2(y[2], y[3]); o8[64 * j] = w; }
;     }
	v_lshlrev_b32_e32 v20, 16, v18
	v_and_b32_e32 v21, 0xffff0000, v18
	v_lshlrev_b32_e32 v18, 16, v19
	v_and_b32_e32 v19, 0xffff0000, v19
	v_pk_mul_f32 v[14:15], v[14:15], v[18:19]
	v_pk_mul_f32 v[12:13], v[12:13], v[20:21]
	s_nop 0
	v_cvt_pk_bf16_f32 v12, v12, v13
	v_cvt_pk_bf16_f32 v13, v14, v15
	global_store_dwordx2 v[24:25], v[12:13], off offset:2560
	v_add_f32_dpp v12, v43, v43 quad_perm:[1,0,3,2] row_mask:0xf bank_mask:0xf bound_ctrl:1
	s_nop 1
	v_add_f32_dpp v12, v12, v12 quad_perm:[2,3,0,1] row_mask:0xf bank_mask:0xf bound_ctrl:1
	s_nop 1
	v_add_f32_dpp v12, v12, v12 row_half_mirror row_mask:0xf bank_mask:0xf bound_ctrl:1
	s_nop 1
	v_add_f32_dpp v12, v12, v12 row_mirror row_mask:0xf bank_mask:0xf bound_ctrl:1
	s_nop 0
	v_readlane_b32 s9, v12, 16
	v_readlane_b32 s10, v12, 48
	v_readlane_b32 s6, v12, 0
	v_readlane_b32 s7, v12, 32
	v_mov_b32_e32 v12, s9
	v_mov_b32_e32 v13, s10
	v_pk_add_f32 v[12:13], s[6:7], v[12:13]
	s_nop 0
	v_add_f32_e32 v12, v12, v13
	v_fmamk_f32 v12, v12, 0x3b800000, v252
	v_cmp_gt_f32_e32 vcc, s55, v12
	v_mul_f32_e32 v13, 0x4f800000, v12
	s_nop 0
	v_cndmask_b32_e32 v12, v12, v13, vcc
	v_sqrt_f32_e32 v13, v12
	s_nop 0
	v_add_u32_e32 v14, -1, v13
	v_fma_f32 v15, -v14, v13, v12
	v_cmp_ge_f32_e64 s[6:7], 0, v15
	v_add_u32_e32 v15, 1, v13
	s_nop 0
	v_cndmask_b32_e64 v14, v13, v14, s[6:7]
	v_fma_f32 v13, -v15, v13, v12
	v_cmp_lt_f32_e64 s[6:7], 0, v13
	s_nop 1
	v_cndmask_b32_e64 v13, v14, v15, s[6:7]
	v_mul_f32_e32 v14, 0x37800000, v13
	v_cndmask_b32_e32 v13, v13, v14, vcc
	v_cmp_class_f32_e32 vcc, v12, v253
	s_nop 1
	v_cndmask_b32_e32 v12, v13, v12, vcc
	v_div_scale_f32 v13, s[6:7], v12, v12, 1.0
	v_rcp_f32_e32 v14, v13
	s_nop 0
	v_fma_f32 v15, -v13, v14, 1.0
	v_fmac_f32_e32 v14, v15, v14
	v_div_scale_f32 v15, vcc, 1.0, v12, 1.0
	v_mul_f32_e32 v16, v15, v14
	v_fma_f32 v17, -v13, v16, v15
	v_fmac_f32_e32 v16, v17, v14
	v_fma_f32 v13, -v13, v16, v15
	v_div_fmas_f32 v13, v13, v14, v16
	global_load_dwordx2 v[14:15], v[30:31], off offset:3072
	v_div_fixup_f32 v12, v13, v12, 1.0
	v_pk_mul_f32 v[8:9], v[8:9], v[12:13] op_sel_hi:[1,0]
	v_pk_mul_f32 v[10:11], v[10:11], v[12:13] op_sel_hi:[1,0]
	s_waitcnt vmcnt(0)
	v_lshlrev_b32_e32 v16, 16, v14
	v_and_b32_e32 v17, 0xffff0000, v14
	v_lshlrev_b32_e32 v14, 16, v15
	v_and_b32_e32 v15, 0xffff0000, v15
	v_pk_mul_f32 v[10:11], v[10:11], v[14:15]
	v_pk_mul_f32 v[8:9], v[8:9], v[16:17]
	s_nop 0
	v_cvt_pk_bf16_f32 v8, v8, v9
	v_cvt_pk_bf16_f32 v9, v10, v11
	global_store_dwordx2 v[24:25], v[8:9], off offset:3072
	v_add_f32_dpp v8, v42, v42 quad_perm:[1,0,3,2] row_mask:0xf bank_mask:0xf bound_ctrl:1
	s_nop 1
	v_add_f32_dpp v8, v8, v8 quad_perm:[2,3,0,1] row_mask:0xf bank_mask:0xf bound_ctrl:1
	s_nop 1
	v_add_f32_dpp v8, v8, v8 row_half_mirror row_mask:0xf bank_mask:0xf bound_ctrl:1
	s_nop 1
	v_add_f32_dpp v8, v8, v8 row_mirror row_mask:0xf bank_mask:0xf bound_ctrl:1
	s_nop 0
	v_readlane_b32 s9, v8, 16
	v_readlane_b32 s10, v8, 48
	v_readlane_b32 s6, v8, 0
	v_readlane_b32 s7, v8, 32
	v_mov_b32_e32 v8, s9
	v_mov_b32_e32 v9, s10
	v_pk_add_f32 v[8:9], s[6:7], v[8:9]
	s_nop 0
	v_add_f32_e32 v8, v8, v9
	v_fmamk_f32 v8, v8, 0x3b800000, v252
	v_cmp_gt_f32_e32 vcc, s55, v8
	v_mul_f32_e32 v9, 0x4f800000, v8
	s_nop 0
	v_cndmask_b32_e32 v8, v8, v9, vcc
	v_sqrt_f32_e32 v9, v8
	s_nop 0
	v_add_u32_e32 v10, -1, v9
	v_fma_f32 v11, -v10, v9, v8
	v_cmp_ge_f32_e64 s[6:7], 0, v11
	v_add_u32_e32 v11, 1, v9
	s_nop 0
	v_cndmask_b32_e64 v10, v9, v10, s[6:7]
	v_fma_f32 v9, -v11, v9, v8
	v_cmp_lt_f32_e64 s[6:7], 0, v9
	s_nop 1
	v_cndmask_b32_e64 v9, v10, v11, s[6:7]
	v_mul_f32_e32 v10, 0x37800000, v9
	v_cndmask_b32_e32 v9, v9, v10, vcc
	v_cmp_class_f32_e32 vcc, v8, v253
	s_nop 1
	v_cndmask_b32_e32 v8, v9, v8, vcc
	v_div_scale_f32 v9, s[6:7], v8, v8, 1.0
	v_rcp_f32_e32 v10, v9
	s_nop 0
	v_fma_f32 v11, -v9, v10, 1.0
	v_fmac_f32_e32 v10, v11, v10
	v_div_scale_f32 v11, vcc, 1.0, v8, 1.0
	v_mul_f32_e32 v12, v11, v10
	v_fma_f32 v13, -v9, v12, v11
	v_fmac_f32_e32 v12, v13, v10
	v_fma_f32 v9, -v9, v12, v11
	v_div_fmas_f32 v9, v9, v10, v12
	global_load_dwordx2 v[10:11], v[30:31], off offset:3584
	v_div_fixup_f32 v8, v9, v8, 1.0
	v_pk_mul_f32 v[4:5], v[4:5], v[8:9] op_sel_hi:[1,0]
	v_pk_mul_f32 v[6:7], v[6:7], v[8:9] op_sel_hi:[1,0]
	s_waitcnt vmcnt(0)
	v_lshlrev_b32_e32 v12, 16, v10
	v_and_b32_e32 v13, 0xffff0000, v10
	v_lshlrev_b32_e32 v10, 16, v11
	v_and_b32_e32 v11, 0xffff0000, v11
	v_pk_mul_f32 v[6:7], v[6:7], v[10:11]
	v_pk_mul_f32 v[4:5], v[4:5], v[12:13]
	s_nop 0
	v_cvt_pk_bf16_f32 v4, v4, v5
	v_cvt_pk_bf16_f32 v5, v6, v7
	global_store_dwordx2 v[24:25], v[4:5], off offset:3584
	s_cbranch_scc1 .LBB0_859

; #define LAS __attribute__((address_space(3)))
; __device__ __forceinline__ void relaunder(Frame& F) { int t = mk_tid(); asm volatile("" : "+v"(t)); F.tid = t; F.lane = t & 63; F.wave = __builtin_amdgcn_readfirstlane(t >> 6); }
; template <bool HG>
; __device__ __forceinline__ void readout_phase2(const Args& a, Frame& F, const float* gain, int nrows) {
;     relaunder(F);
;     const int nw = F.vcu * NWAVES + F.wave;
;     const bf16* OF = (const bf16*)(a.ws + WS_OF); const bf16* OB = (const bf16*)(a.ws + WS_OB);
;     const bf16* G = (const bf16*)(a.ws + WS_ACT) + (size_t)(HG ? 6 : 3) * ACT_STRIDE; bf16* HN = (bf16*)(a.ws + WS_HN);
;     LAS float* GL = (LAS float*)F.lds;
;     v2u f0[8], b0[8], g0[8], f1[8], b1[8], g1[8], f2[8], b2[8], g2[8];
;     ...
;     RO_LOAD(f0, b0, g0, nw); RO_LOAD(f1, b1, g1, nw + 2048); RO_LOAD(f2, b2, g2, nw + 2 * 2048);
.LBB0_861:
	s_andn2_b64 vcc, exec, s[6:7]
	s_cbranch_vccnz .LBB0_864
	s_getreg_b32 s6, hwreg(HW_REG_HW_ID, 0, 6)
	s_lshl_b32 s6, s6, 2
	s_add_i32 s6, s6, 0
	s_add_i32 s6, s6, 0x20540
	v_mov_b32_e32 v0, s6
	ds_read_b32 v0, v0
	v_mov_b64_e32 v[2:3], s[0:1]
	s_waitcnt lgkmcnt(0)
	v_readfirstlane_b32 s6, v0
	v_mbcnt_lo_u32_b32 v0, -1, 0
	v_mbcnt_hi_u32_b32 v0, -1, v0
	s_nop 1
	v_lshl_add_u32 v0, s6, 6, v0
	v_mov_b32_e32 v2, s72
	v_mov_b32_e32 v3, s73
	v_readfirstlane_b32 s6, v0
	s_ashr_i32 s6, s6, 6
	s_add_i32 s8, s6, s91
	s_mov_b64 s[6:7], 0x2ac00000
	s_ashr_i32 s9, s8, 31
	v_and_b32_e32 v12, 63, v0
	s_lshl_b64 s[10:11], s[8:9], 12
	v_lshlrev_b32_e32 v0, 3, v12
	s_add_u32 s16, s10, 0x800000
	s_addc_u32 s17, s11, 0
	s_add_u32 s12, s10, 0x1000000
	s_addc_u32 s13, s11, 0
	s_waitcnt vmcnt(0) lgkmcnt(0)
	v_lshl_add_u64 v[4:5], v[2:3], 0, s[6:7]
	s_mov_b64 s[6:7], 0x33400000
	v_lshl_add_u64 v[6:7], v[2:3], 0, s[6:7]
	s_mov_b64 s[6:7], 0x19c00000
	v_lshl_add_u64 v[8:9], v[2:3], 0, s[6:7]
	v_lshl_add_u64 v[10:11], v[4:5], 0, s[10:11]
	v_lshl_add_u64 v[10:11], v[10:11], 0, v[0:1]
	v_lshl_add_u64 v[12:13], v[6:7], 0, s[10:11]
	v_lshl_add_u64 v[14:15], v[8:9], 0, s[10:11]
	v_lshl_add_u64 v[12:13], v[12:13], 0, v[0:1]
	v_lshl_add_u64 v[14:15], v[14:15], 0, v[0:1]
	global_load_dwordx2 v[152:153], v[10:11], off
	global_load_dwordx2 v[150:151], v[12:13], off
	global_load_dwordx2 v[64:65], v[14:15], off
	global_load_dwordx2 v[148:149], v[10:11], off offset:512
	global_load_dwordx2 v[142:143], v[12:13], off offset:512
	global_load_dwordx2 v[58:59], v[14:15], off offset:512
	global_load_dwordx2 v[136:137], v[10:11], off offset:1024
	global_load_dwordx2 v[130:131], v[12:13], off offset:1024
	global_load_dwordx2 v[52:53], v[14:15], off offset:1024
	global_load_dwordx2 v[126:127], v[10:11], off offset:1536
	global_load_dwordx2 v[122:123], v[12:13], off offset:1536
	global_load_dwordx2 v[46:47], v[14:15], off offset:1536
	global_load_dwordx2 v[118:119], v[10:11], off offset:2048
	global_load_dwordx2 v[114:115], v[12:13], off offset:2048
	global_load_dwordx2 v[40:41], v[14:15], off offset:2048
	global_load_dwordx2 v[110:111], v[10:11], off offset:2560
	global_load_dwordx2 v[106:107], v[12:13], off offset:2560
	global_load_dwordx2 v[24:25], v[14:15], off offset:2560
	global_load_dwordx2 v[102:103], v[10:11], off offset:3072
	global_load_dwordx2 v[98:99], v[12:13], off offset:3072
	global_load_dwordx2 v[20:21], v[14:15], off offset:3072
	global_load_dwordx2 v[94:95], v[10:11], off offset:3584
	global_load_dwordx2 v[90:91], v[12:13], off offset:3584
	global_load_dwordx2 v[16:17], v[14:15], off offset:3584
	v_lshl_add_u64 v[10:11], v[4:5], 0, s[16:17]
	v_lshl_add_u64 v[10:11], v[10:11], 0, v[0:1]
	v_lshl_add_u64 v[12:13], v[6:7], 0, s[16:17]
	v_lshl_add_u64 v[14:15], v[8:9], 0, s[16:17]
	v_lshl_add_u64 v[12:13], v[12:13], 0, v[0:1]
	v_lshl_add_u64 v[14:15], v[14:15], 0, v[0:1]
	global_load_dwordx2 v[146:147], v[10:11], off
	global_load_dwordx2 v[144:145], v[12:13], off
	global_load_dwordx2 v[66:67], v[14:15], off
	global_load_dwordx2 v[140:141], v[10:11], off offset:512
	global_load_dwordx2 v[138:139], v[12:13], off offset:512
	global_load_dwordx2 v[60:61], v[14:15], off offset:512
	global_load_dwordx2 v[134:135], v[10:11], off offset:1024
	global_load_dwordx2 v[132:133], v[12:13], off offset:1024
	global_load_dwordx2 v[54:55], v[14:15], off offset:1024
	global_load_dwordx2 v[128:129], v[10:11], off offset:1536
	global_load_dwordx2 v[124:125], v[12:13], off offset:1536
	global_load_dwordx2 v[48:49], v[14:15], off offset:1536
	global_load_dwordx2 v[120:121], v[10:11], off offset:2048
	global_load_dwordx2 v[116:117], v[12:13], off offset:2048
	global_load_dwordx2 v[42:43], v[14:15], off offset:2048
	global_load_dwordx2 v[112:113], v[10:11], off offset:2560
	global_load_dwordx2 v[108:109], v[12:13], off offset:2560
	global_load_dwordx2 v[36:37], v[14:15], off offset:2560
	global_load_dwordx2 v[104:105], v[10:11], off offset:3072
	global_load_dwordx2 v[100:101], v[12:13], off offset:3072
	global_load_dwordx2 v[32:33], v[14:15], off offset:3072
	global_load_dwordx2 v[96:97], v[10:11], off offset:3584
	global_load_dwordx2 v[92:93], v[12:13], off offset:3584
	global_load_dwordx2 v[28:29], v[14:15], off offset:3584
	v_lshl_add_u64 v[10:11], v[4:5], 0, s[12:13]
	v_lshl_add_u64 v[38:39], v[10:11], 0, v[0:1]
	v_lshl_add_u64 v[10:11], v[6:7], 0, s[12:13]
	v_lshl_add_u64 v[12:13], v[8:9], 0, s[12:13]
	v_lshl_add_u64 v[10:11], v[10:11], 0, v[0:1]
	v_lshl_add_u64 v[154:155], v[12:13], 0, v[0:1]
	global_load_dwordx2 v[88:89], v[38:39], off
	global_load_dwordx2 v[86:87], v[10:11], off
	global_load_dwordx2 v[34:35], v[154:155], off
	global_load_dwordx2 v[84:85], v[38:39], off offset:512
	global_load_dwordx2 v[82:83], v[10:11], off offset:512
	global_load_dwordx2 v[30:31], v[154:155], off offset:512
	global_load_dwordx2 v[80:81], v[38:39], off offset:1024
	global_load_dwordx2 v[78:79], v[10:11], off offset:1024
	global_load_dwordx2 v[26:27], v[154:155], off offset:1024
	global_load_dwordx2 v[74:75], v[38:39], off offset:1536
	global_load_dwordx2 v[76:77], v[10:11], off offset:1536
	global_load_dwordx2 v[22:23], v[154:155], off offset:1536
	global_load_dwordx2 v[72:73], v[38:39], off offset:2048
	global_load_dwordx2 v[70:71], v[10:11], off offset:2048
	global_load_dwordx2 v[18:19], v[154:155], off offset:2048
	global_load_dwordx2 v[68:69], v[38:39], off offset:2560
	global_load_dwordx2 v[62:63], v[10:11], off offset:2560
	global_load_dwordx2 v[14:15], v[154:155], off offset:2560
	global_load_dwordx2 v[56:57], v[38:39], off offset:3072
	global_load_dwordx2 v[50:51], v[10:11], off offset:3072
	global_load_dwordx2 v[12:13], v[154:155], off offset:3072
	s_nop 0
	global_load_dwordx2 v[38:39], v[38:39], off offset:3584
	s_nop 0
	global_load_dwordx2 v[44:45], v[10:11], off offset:3584
	s_nop 0
	global_load_dwordx2 v[10:11], v[154:155], off offset:3584
	s_mov_b64 s[6:7], 0x8c00000
	v_lshl_add_u64 v[2:3], v[2:3], 0, s[6:7]
	s_waitcnt vmcnt(62)
	v_lshlrev_b32_e32 v154, 16, v152
	v_and_b32_e32 v155, 0xffff0000, v152
	v_lshlrev_b32_e32 v156, 16, v150
	v_and_b32_e32 v157, 0xffff0000, v150
	v_lshlrev_b32_e32 v152, 16, v153
	v_and_b32_e32 v153, 0xffff0000, v153
	v_lshlrev_b32_e32 v150, 16, v151
	v_and_b32_e32 v151, 0xffff0000, v151
	v_pk_add_f32 v[154:155], v[154:155], v[156:157]
	v_pk_add_f32 v[152:153], v[152:153], v[150:151]
	v_mov_b32_e32 v156, v155
	v_mov_b32_e32 v157, v153
	v_mov_b32_e32 v150, v154
	v_mov_b32_e32 v151, v152
	v_pk_mul_f32 v[156:157], v[156:157], v[156:157]
	s_waitcnt vmcnt(49)
	v_lshlrev_b32_e32 v162, 16, v90
	v_pk_fma_f32 v[150:151], v[150:151], v[150:151], v[156:157]
	v_lshlrev_b32_e32 v156, 16, v142
	v_add_f32_e32 v161, v150, v151
	v_lshlrev_b32_e32 v150, 16, v148
	v_and_b32_e32 v151, 0xffff0000, v148
	v_and_b32_e32 v157, 0xffff0000, v142
	v_lshlrev_b32_e32 v148, 16, v149
	v_and_b32_e32 v149, 0xffff0000, v149
	v_lshlrev_b32_e32 v142, 16, v143
	v_and_b32_e32 v143, 0xffff0000, v143
	v_pk_add_f32 v[150:151], v[150:151], v[156:157]
	v_pk_add_f32 v[148:149], v[148:149], v[142:143]
	v_mov_b32_e32 v156, v151
	v_mov_b32_e32 v157, v149
	v_mov_b32_e32 v142, v150
	v_mov_b32_e32 v143, v148
	v_pk_mul_f32 v[156:157], v[156:157], v[156:157]
	v_add_f32_dpp v161, v161, v161 quad_perm:[1,0,3,2] row_mask:0xf bank_mask:0xf bound_ctrl:1
	v_pk_fma_f32 v[142:143], v[142:143], v[142:143], v[156:157]
	v_lshlrev_b32_e32 v156, 16, v130
	v_add_f32_e32 v166, v142, v143
	v_lshlrev_b32_e32 v142, 16, v136
	v_and_b32_e32 v143, 0xffff0000, v136
	v_and_b32_e32 v157, 0xffff0000, v130
	v_lshlrev_b32_e32 v136, 16, v137
	v_and_b32_e32 v137, 0xffff0000, v137
	v_lshlrev_b32_e32 v130, 16, v131
	v_and_b32_e32 v131, 0xffff0000, v131
	v_pk_add_f32 v[142:143], v[142:143], v[156:157]
	v_pk_add_f32 v[136:137], v[136:137], v[130:131]
	v_mov_b32_e32 v156, v143
	v_mov_b32_e32 v157, v137
	v_mov_b32_e32 v130, v142
	v_mov_b32_e32 v131, v136
	v_pk_mul_f32 v[156:157], v[156:157], v[156:157]
	v_and_b32_e32 v163, 0xffff0000, v90
	v_pk_fma_f32 v[130:131], v[130:131], v[130:131], v[156:157]
	v_lshlrev_b32_e32 v156, 16, v122
	v_add_f32_e32 v160, v130, v131
	v_lshlrev_b32_e32 v130, 16, v126
	v_and_b32_e32 v131, 0xffff0000, v126
	v_and_b32_e32 v157, 0xffff0000, v122
	v_lshlrev_b32_e32 v126, 16, v127
	v_and_b32_e32 v127, 0xffff0000, v127
	v_lshlrev_b32_e32 v122, 16, v123
	v_and_b32_e32 v123, 0xffff0000, v123
	v_pk_add_f32 v[130:131], v[130:131], v[156:157]
	v_pk_add_f32 v[126:127], v[126:127], v[122:123]
	v_mov_b32_e32 v156, v131
	v_mov_b32_e32 v157, v127
	v_mov_b32_e32 v122, v130
	v_mov_b32_e32 v123, v126
	v_pk_mul_f32 v[156:157], v[156:157], v[156:157]
	v_lshlrev_b32_e32 v90, 16, v91
	v_pk_fma_f32 v[122:123], v[122:123], v[122:123], v[156:157]
	v_lshlrev_b32_e32 v156, 16, v114
	v_add_f32_e32 v167, v122, v123
	v_lshlrev_b32_e32 v122, 16, v118
	v_and_b32_e32 v123, 0xffff0000, v118
	v_and_b32_e32 v157, 0xffff0000, v114
	v_lshlrev_b32_e32 v118, 16, v119
	v_and_b32_e32 v119, 0xffff0000, v119
	v_lshlrev_b32_e32 v114, 16, v115
	v_and_b32_e32 v115, 0xffff0000, v115
	v_pk_add_f32 v[122:123], v[122:123], v[156:157]
	v_pk_add_f32 v[118:119], v[118:119], v[114:115]
	v_mov_b32_e32 v156, v123
	v_mov_b32_e32 v157, v119
	v_mov_b32_e32 v114, v122
	v_mov_b32_e32 v115, v118
	v_pk_mul_f32 v[156:157], v[156:157], v[156:157]
	v_and_b32_e32 v91, 0xffff0000, v91
	v_pk_fma_f32 v[114:115], v[114:115], v[114:115], v[156:157]
	v_lshlrev_b32_e32 v156, 16, v106
	v_add_f32_e32 v159, v114, v115
	v_lshlrev_b32_e32 v114, 16, v110
	v_and_b32_e32 v115, 0xffff0000, v110
	v_and_b32_e32 v157, 0xffff0000, v106
	v_lshlrev_b32_e32 v110, 16, v111
	v_and_b32_e32 v111, 0xffff0000, v111
	v_lshlrev_b32_e32 v106, 16, v107
	v_and_b32_e32 v107, 0xffff0000, v107
	v_pk_add_f32 v[114:115], v[114:115], v[156:157]
	v_pk_add_f32 v[110:111], v[110:111], v[106:107]
	v_mov_b32_e32 v156, v115
	v_mov_b32_e32 v157, v111
	v_mov_b32_e32 v106, v114
	v_mov_b32_e32 v107, v110
	v_pk_mul_f32 v[156:157], v[156:157], v[156:157]
	v_add_f32_dpp v161, v161, v161 quad_perm:[2,3,0,1] row_mask:0xf bank_mask:0xf bound_ctrl:1
	v_pk_fma_f32 v[106:107], v[106:107], v[106:107], v[156:157]
	v_lshlrev_b32_e32 v156, 16, v98
	v_add_f32_e32 v158, v106, v107
	v_lshlrev_b32_e32 v106, 16, v102
	v_and_b32_e32 v107, 0xffff0000, v102
	v_and_b32_e32 v157, 0xffff0000, v98
	v_lshlrev_b32_e32 v102, 16, v103
	v_and_b32_e32 v103, 0xffff0000, v103
	v_lshlrev_b32_e32 v98, 16, v99
	v_and_b32_e32 v99, 0xffff0000, v99
	v_pk_add_f32 v[106:107], v[106:107], v[156:157]
	v_pk_add_f32 v[102:103], v[102:103], v[98:99]
	v_mov_b32_e32 v156, v107
	v_mov_b32_e32 v157, v103
	v_mov_b32_e32 v98, v106
	v_mov_b32_e32 v99, v102
	v_pk_mul_f32 v[156:157], v[156:157], v[156:157]
	v_add_f32_dpp v161, v161, v161 row_half_mirror row_mask:0xf bank_mask:0xf bound_ctrl:1
	v_pk_fma_f32 v[98:99], v[98:99], v[98:99], v[156:157]
	s_nop 0
	v_add_f32_e32 v157, v98, v99
	v_lshlrev_b32_e32 v98, 16, v94
	v_and_b32_e32 v99, 0xffff0000, v94
	v_lshlrev_b32_e32 v94, 16, v95
	v_and_b32_e32 v95, 0xffff0000, v95
	v_pk_add_f32 v[98:99], v[98:99], v[162:163]
	v_pk_add_f32 v[90:91], v[94:95], v[90:91]
	v_mov_b32_e32 v162, v99
	v_mov_b32_e32 v163, v91
	v_add_f32_dpp v161, v161, v161 row_mirror row_mask:0xf bank_mask:0xf bound_ctrl:1
	v_mov_b32_e32 v94, v98
	v_mov_b32_e32 v95, v90
	v_pk_mul_f32 v[162:163], v[162:163], v[162:163]
	v_readlane_b32 s9, v161, 16
	v_readlane_b32 s14, v161, 48
	v_pk_fma_f32 v[94:95], v[94:95], v[94:95], v[162:163]
	v_readlane_b32 s6, v161, 0
	v_readlane_b32 s7, v161, 32
	v_mov_b32_e32 v162, s9
	v_mov_b32_e32 v163, s14
	v_pk_add_f32 v[162:163], s[6:7], v[162:163]
	v_add_f32_e32 v156, v94, v95
	v_add_f32_e32 v161, v162, v163
	v_fmamk_f32 v161, v161, 0x3b800000, v252
	v_cmp_gt_f32_e32 vcc, s55, v161
	v_mul_f32_e32 v162, 0x4f800000, v161
	v_lshl_add_u64 v[94:95], v[2:3], 0, s[10:11]
	v_cndmask_b32_e32 v161, v161, v162, vcc
	v_sqrt_f32_e32 v162, v161
	v_lshl_add_u64 v[94:95], v[94:95], 0, v[0:1]
	v_add_u32_e32 v163, -1, v162
	v_fma_f32 v164, -v163, v162, v161
	v_cmp_ge_f32_e64 s[6:7], 0, v164
	v_add_u32_e32 v164, 1, v162
	s_nop 0
	v_cndmask_b32_e64 v163, v162, v163, s[6:7]
	v_fma_f32 v162, -v164, v162, v161
	v_cmp_lt_f32_e64 s[6:7], 0, v162
	s_nop 1
	v_cndmask_b32_e64 v162, v163, v164, s[6:7]
	v_mul_f32_e32 v163, 0x37800000, v162
	v_cndmask_b32_e32 v162, v162, v163, vcc
	v_cmp_class_f32_e32 vcc, v161, v253
	s_nop 1
	v_cndmask_b32_e32 v161, v162, v161, vcc
	v_div_scale_f32 v162, s[6:7], v161, v161, 1.0
	v_rcp_f32_e32 v163, v162
	s_nop 0
	v_fma_f32 v164, -v162, v163, 1.0
	v_fmac_f32_e32 v163, v164, v163
	v_div_scale_f32 v164, vcc, 1.0, v161, 1.0
	v_mul_f32_e32 v165, v164, v163
	v_fma_f32 v168, -v162, v165, v164
	v_fmac_f32_e32 v165, v168, v163
	v_fma_f32 v162, -v162, v165, v164
	v_div_fmas_f32 v162, v162, v163, v165
	v_div_fixup_f32 v162, v162, v161, 1.0
	v_lshlrev_b32_e32 v164, 16, v64
	v_and_b32_e32 v165, 0xffff0000, v64
	v_lshlrev_b32_e32 v64, 16, v65
	v_and_b32_e32 v65, 0xffff0000, v65
	v_pk_mul_f32 v[154:155], v[154:155], v[162:163] op_sel_hi:[1,0]
	v_pk_mul_f32 v[152:153], v[152:153], v[162:163] op_sel_hi:[1,0]
	s_nop 0
	v_pk_mul_f32 v[64:65], v[152:153], v[64:65]
	v_pk_mul_f32 v[152:153], v[154:155], v[164:165]
	s_nop 0
	v_cvt_pk_bf16_f32 v152, v152, v153
	v_cvt_pk_bf16_f32 v153, v64, v65
	v_add_f32_dpp v64, v166, v166 quad_perm:[1,0,3,2] row_mask:0xf bank_mask:0xf bound_ctrl:1
	global_store_dwordx2 v[94:95], v[152:153], off
	s_nop 0
	v_add_f32_dpp v64, v64, v64 quad_perm:[2,3,0,1] row_mask:0xf bank_mask:0xf bound_ctrl:1
	s_nop 1
	v_add_f32_dpp v64, v64, v64 row_half_mirror row_mask:0xf bank_mask:0xf bound_ctrl:1
	s_nop 1
	v_add_f32_dpp v64, v64, v64 row_mirror row_mask:0xf bank_mask:0xf bound_ctrl:1
	s_nop 0
	v_readlane_b32 s9, v64, 16
	v_readlane_b32 s14, v64, 48
	v_readlane_b32 s6, v64, 0
	v_readlane_b32 s7, v64, 32
	v_mov_b32_e32 v64, s9
	v_mov_b32_e32 v65, s14
	v_pk_add_f32 v[64:65], s[6:7], v[64:65]
	s_nop 0
	v_add_f32_e32 v64, v64, v65
	v_fmamk_f32 v64, v64, 0x3b800000, v252
	v_cmp_gt_f32_e32 vcc, s55, v64
	v_mul_f32_e32 v65, 0x4f800000, v64
	s_nop 0
	v_cndmask_b32_e32 v64, v64, v65, vcc
	v_sqrt_f32_e32 v65, v64
	s_nop 0
	v_add_u32_e32 v152, -1, v65
	v_fma_f32 v153, -v152, v65, v64
	v_cmp_ge_f32_e64 s[6:7], 0, v153
	v_add_u32_e32 v153, 1, v65
	s_nop 0
	v_cndmask_b32_e64 v152, v65, v152, s[6:7]
	v_fma_f32 v65, -v153, v65, v64
	v_cmp_lt_f32_e64 s[6:7], 0, v65
	s_nop 1
	v_cndmask_b32_e64 v65, v152, v153, s[6:7]
	v_mul_f32_e32 v152, 0x37800000, v65
	v_cndmask_b32_e32 v65, v65, v152, vcc
	v_cmp_class_f32_e32 vcc, v64, v253
	s_nop 1
	v_cndmask_b32_e32 v64, v65, v64, vcc
	v_div_scale_f32 v65, s[6:7], v64, v64, 1.0
	v_rcp_f32_e32 v152, v65
	s_nop 0
	v_fma_f32 v153, -v65, v152, 1.0
	v_fmac_f32_e32 v152, v153, v152
	v_div_scale_f32 v153, vcc, 1.0, v64, 1.0
	v_mul_f32_e32 v154, v153, v152
	v_fma_f32 v155, -v65, v154, v153
	v_fmac_f32_e32 v154, v155, v152
	v_fma_f32 v65, -v65, v154, v153
	v_div_fmas_f32 v65, v65, v152, v154
	v_div_fixup_f32 v64, v65, v64, 1.0
	v_lshlrev_b32_e32 v152, 16, v58
	v_and_b32_e32 v153, 0xffff0000, v58
	v_lshlrev_b32_e32 v58, 16, v59
	v_and_b32_e32 v59, 0xffff0000, v59
	v_pk_mul_f32 v[150:151], v[150:151], v[64:65] op_sel_hi:[1,0]
	v_pk_mul_f32 v[64:65], v[148:149], v[64:65] op_sel_hi:[1,0]
	s_nop 0
	v_pk_mul_f32 v[58:59], v[64:65], v[58:59]
	v_pk_mul_f32 v[64:65], v[150:151], v[152:153]
	s_waitcnt vmcnt(47)
	v_lshlrev_b32_e32 v152, 16, v144
	v_cvt_pk_bf16_f32 v64, v64, v65
	v_cvt_pk_bf16_f32 v65, v58, v59
	v_add_f32_dpp v58, v160, v160 quad_perm:[1,0,3,2] row_mask:0xf bank_mask:0xf bound_ctrl:1
	global_store_dwordx2 v[94:95], v[64:65], off offset:512
	v_and_b32_e32 v153, 0xffff0000, v144
	v_add_f32_dpp v58, v58, v58 quad_perm:[2,3,0,1] row_mask:0xf bank_mask:0xf bound_ctrl:1
	v_lshlrev_b32_e32 v144, 16, v145
	v_and_b32_e32 v145, 0xffff0000, v145
	v_add_f32_dpp v58, v58, v58 row_half_mirror row_mask:0xf bank_mask:0xf bound_ctrl:1
	s_nop 1
	v_add_f32_dpp v58, v58, v58 row_mirror row_mask:0xf bank_mask:0xf bound_ctrl:1
	s_nop 0
	v_readlane_b32 s9, v58, 16
	v_readlane_b32 s14, v58, 48
	v_readlane_b32 s6, v58, 0
	v_readlane_b32 s7, v58, 32
	v_mov_b32_e32 v58, s9
	v_mov_b32_e32 v59, s14
	v_pk_add_f32 v[58:59], s[6:7], v[58:59]
	s_nop 0
	v_add_f32_e32 v58, v58, v59
	v_fmamk_f32 v58, v58, 0x3b800000, v252
	v_cmp_gt_f32_e32 vcc, s55, v58
	v_mul_f32_e32 v59, 0x4f800000, v58
	s_nop 0
	v_cndmask_b32_e32 v58, v58, v59, vcc
	v_sqrt_f32_e32 v59, v58
	s_nop 0
	v_add_u32_e32 v64, -1, v59
	v_fma_f32 v65, -v64, v59, v58
	v_cmp_ge_f32_e64 s[6:7], 0, v65
	v_add_u32_e32 v65, 1, v59
	s_nop 0
	v_cndmask_b32_e64 v64, v59, v64, s[6:7]
	v_fma_f32 v59, -v65, v59, v58
	v_cmp_lt_f32_e64 s[6:7], 0, v59
	s_nop 1
	v_cndmask_b32_e64 v59, v64, v65, s[6:7]
	v_mul_f32_e32 v64, 0x37800000, v59
	v_cndmask_b32_e32 v59, v59, v64, vcc
	v_cmp_class_f32_e32 vcc, v58, v253
	s_nop 1
	v_cndmask_b32_e32 v58, v59, v58, vcc
	v_div_scale_f32 v59, s[6:7], v58, v58, 1.0
	v_rcp_f32_e32 v64, v59
	s_nop 0
	v_fma_f32 v65, -v59, v64, 1.0
	v_fmac_f32_e32 v64, v65, v64
	v_div_scale_f32 v65, vcc, 1.0, v58, 1.0
	v_mul_f32_e32 v148, v65, v64
	v_fma_f32 v149, -v59, v148, v65
	v_fmac_f32_e32 v148, v149, v64
	v_fma_f32 v59, -v59, v148, v65
	v_div_fmas_f32 v59, v59, v64, v148
	v_div_fixup_f32 v58, v59, v58, 1.0
	v_lshlrev_b32_e32 v64, 16, v52
	v_and_b32_e32 v65, 0xffff0000, v52
	v_lshlrev_b32_e32 v52, 16, v53
	v_and_b32_e32 v53, 0xffff0000, v53
	v_pk_mul_f32 v[142:143], v[142:143], v[58:59] op_sel_hi:[1,0]
	v_pk_mul_f32 v[58:59], v[136:137], v[58:59] op_sel_hi:[1,0]
	s_nop 0
	v_pk_mul_f32 v[52:53], v[58:59], v[52:53]
	v_pk_mul_f32 v[58:59], v[142:143], v[64:65]
	s_nop 0
	v_cvt_pk_bf16_f32 v58, v58, v59
	v_cvt_pk_bf16_f32 v59, v52, v53
	v_add_f32_dpp v52, v167, v167 quad_perm:[1,0,3,2] row_mask:0xf bank_mask:0xf bound_ctrl:1
	global_store_dwordx2 v[94:95], v[58:59], off offset:1024
	s_nop 0
	v_add_f32_dpp v52, v52, v52 quad_perm:[2,3,0,1] row_mask:0xf bank_mask:0xf bound_ctrl:1
	s_nop 1
	v_add_f32_dpp v52, v52, v52 row_half_mirror row_mask:0xf bank_mask:0xf bound_ctrl:1
	s_nop 1
	v_add_f32_dpp v52, v52, v52 row_mirror row_mask:0xf bank_mask:0xf bound_ctrl:1
	s_nop 0
	v_readlane_b32 s9, v52, 16
	v_readlane_b32 s14, v52, 48
	v_readlane_b32 s6, v52, 0
	v_readlane_b32 s7, v52, 32
	v_mov_b32_e32 v52, s9
	v_mov_b32_e32 v53, s14
	v_pk_add_f32 v[52:53], s[6:7], v[52:53]
	s_nop 0
	v_add_f32_e32 v52, v52, v53
	v_fmamk_f32 v52, v52, 0x3b800000, v252
	v_cmp_gt_f32_e32 vcc, s55, v52
	v_mul_f32_e32 v53, 0x4f800000, v52
	s_nop 0
	v_cndmask_b32_e32 v52, v52, v53, vcc
	v_sqrt_f32_e32 v53, v52
	s_nop 0
	v_add_u32_e32 v58, -1, v53
	v_fma_f32 v59, -v58, v53, v52
	v_cmp_ge_f32_e64 s[6:7], 0, v59
	v_add_u32_e32 v59, 1, v53
	s_nop 0
	v_cndmask_b32_e64 v58, v53, v58, s[6:7]
	v_fma_f32 v53, -v59, v53, v52
	v_cmp_lt_f32_e64 s[6:7], 0, v53
	s_nop 1
	v_cndmask_b32_e64 v53, v58, v59, s[6:7]
	v_mul_f32_e32 v58, 0x37800000, v53
	v_cndmask_b32_e32 v53, v53, v58, vcc
	v_cmp_class_f32_e32 vcc, v52, v253
	s_nop 1
	v_cndmask_b32_e32 v52, v53, v52, vcc
	v_div_scale_f32 v53, s[6:7], v52, v52, 1.0
	v_rcp_f32_e32 v58, v53
	s_nop 0
	v_fma_f32 v59, -v53, v58, 1.0
	v_fmac_f32_e32 v58, v59, v58
	v_div_scale_f32 v59, vcc, 1.0, v52, 1.0
	v_mul_f32_e32 v64, v59, v58
	v_fma_f32 v65, -v53, v64, v59
	v_fmac_f32_e32 v64, v65, v58
	v_fma_f32 v53, -v53, v64, v59
	v_div_fmas_f32 v53, v53, v58, v64
	v_div_fixup_f32 v52, v53, v52, 1.0
	v_lshlrev_b32_e32 v58, 16, v46
	v_and_b32_e32 v59, 0xffff0000, v46
	v_lshlrev_b32_e32 v46, 16, v47
	v_and_b32_e32 v47, 0xffff0000, v47
	v_pk_mul_f32 v[64:65], v[130:131], v[52:53] op_sel_hi:[1,0]
	v_pk_mul_f32 v[52:53], v[126:127], v[52:53] op_sel_hi:[1,0]
	s_nop 0
	v_pk_mul_f32 v[46:47], v[52:53], v[46:47]
	v_pk_mul_f32 v[52:53], v[64:65], v[58:59]
	s_nop 0
	v_cvt_pk_bf16_f32 v52, v52, v53
	v_cvt_pk_bf16_f32 v53, v46, v47
	v_add_f32_dpp v46, v159, v159 quad_perm:[1,0,3,2] row_mask:0xf bank_mask:0xf bound_ctrl:1
	global_store_dwordx2 v[94:95], v[52:53], off offset:1536
	s_waitcnt vmcnt(29)
	v_and_b32_e32 v159, 0xffff0000, v92
	v_add_f32_dpp v46, v46, v46 quad_perm:[2,3,0,1] row_mask:0xf bank_mask:0xf bound_ctrl:1
	s_nop 1
	v_add_f32_dpp v46, v46, v46 row_half_mirror row_mask:0xf bank_mask:0xf bound_ctrl:1
	s_nop 1
	v_add_f32_dpp v46, v46, v46 row_mirror row_mask:0xf bank_mask:0xf bound_ctrl:1
	s_nop 0
	v_readlane_b32 s9, v46, 16
	v_readlane_b32 s14, v46, 48
	v_readlane_b32 s6, v46, 0
	v_readlane_b32 s7, v46, 32
	v_mov_b32_e32 v46, s9
	v_mov_b32_e32 v47, s14
	v_pk_add_f32 v[46:47], s[6:7], v[46:47]
	s_nop 0
	v_add_f32_e32 v46, v46, v47
	v_fmamk_f32 v46, v46, 0x3b800000, v252
	v_cmp_gt_f32_e32 vcc, s55, v46
	v_mul_f32_e32 v47, 0x4f800000, v46
	s_nop 0
	v_cndmask_b32_e32 v46, v46, v47, vcc
	v_sqrt_f32_e32 v47, v46
	s_nop 0
	v_add_u32_e32 v52, -1, v47
	v_fma_f32 v53, -v52, v47, v46
	v_cmp_ge_f32_e64 s[6:7], 0, v53
	v_add_u32_e32 v53, 1, v47
	s_nop 0
	v_cndmask_b32_e64 v52, v47, v52, s[6:7]
	v_fma_f32 v47, -v53, v47, v46
	v_cmp_lt_f32_e64 s[6:7], 0, v47
	s_nop 1
	v_cndmask_b32_e64 v47, v52, v53, s[6:7]
	v_mul_f32_e32 v52, 0x37800000, v47
	v_cndmask_b32_e32 v47, v47, v52, vcc
	v_cmp_class_f32_e32 vcc, v46, v253
	s_nop 1
	v_cndmask_b32_e32 v46, v47, v46, vcc
	v_div_scale_f32 v47, s[6:7], v46, v46, 1.0
	v_rcp_f32_e32 v52, v47
	s_nop 0
	v_fma_f32 v53, -v47, v52, 1.0
	v_fmac_f32_e32 v52, v53, v52
	v_div_scale_f32 v53, vcc, 1.0, v46, 1.0
	v_mul_f32_e32 v58, v53, v52
	v_fma_f32 v59, -v47, v58, v53
	v_fmac_f32_e32 v58, v59, v52
	v_fma_f32 v47, -v47, v58, v53
	v_div_fmas_f32 v47, v47, v52, v58
	v_div_fixup_f32 v46, v47, v46, 1.0
	v_lshlrev_b32_e32 v52, 16, v40
	v_and_b32_e32 v53, 0xffff0000, v40
	v_lshlrev_b32_e32 v40, 16, v41
	v_and_b32_e32 v41, 0xffff0000, v41
	v_pk_mul_f32 v[58:59], v[122:123], v[46:47] op_sel_hi:[1,0]
	v_pk_mul_f32 v[46:47], v[118:119], v[46:47] op_sel_hi:[1,0]
	s_nop 0
	v_pk_mul_f32 v[40:41], v[46:47], v[40:41]
	v_pk_mul_f32 v[46:47], v[58:59], v[52:53]
	s_nop 0
	v_cvt_pk_bf16_f32 v46, v46, v47
	v_cvt_pk_bf16_f32 v47, v40, v41
	v_add_f32_dpp v40, v158, v158 quad_perm:[1,0,3,2] row_mask:0xf bank_mask:0xf bound_ctrl:1
	global_store_dwordx2 v[94:95], v[46:47], off offset:2048
	v_lshlrev_b32_e32 v158, 16, v92
	v_add_f32_dpp v40, v40, v40 quad_perm:[2,3,0,1] row_mask:0xf bank_mask:0xf bound_ctrl:1
	v_lshlrev_b32_e32 v92, 16, v93
	v_and_b32_e32 v93, 0xffff0000, v93
	v_add_f32_dpp v40, v40, v40 row_half_mirror row_mask:0xf bank_mask:0xf bound_ctrl:1
	s_nop 1
	v_add_f32_dpp v40, v40, v40 row_mirror row_mask:0xf bank_mask:0xf bound_ctrl:1
	s_nop 0
	v_readlane_b32 s9, v40, 16
	v_readlane_b32 s14, v40, 48
	v_readlane_b32 s6, v40, 0
	v_readlane_b32 s7, v40, 32
	v_mov_b32_e32 v40, s9
	v_mov_b32_e32 v41, s14
	v_pk_add_f32 v[40:41], s[6:7], v[40:41]
	s_nop 0
	v_add_f32_e32 v40, v40, v41
	v_fmamk_f32 v40, v40, 0x3b800000, v252
	v_cmp_gt_f32_e32 vcc, s55, v40
	v_mul_f32_e32 v41, 0x4f800000, v40
	s_nop 0
	v_cndmask_b32_e32 v40, v40, v41, vcc
	v_sqrt_f32_e32 v41, v40
	s_nop 0
	v_add_u32_e32 v46, -1, v41
	v_fma_f32 v47, -v46, v41, v40
	v_cmp_ge_f32_e64 s[6:7], 0, v47
; template <bool HG>
; __device__ __forceinline__ void readout_phase2(const Args& a, Frame& F, const float* gain, int nrows) {
;     ...
;     RO_FINISH(f0, b0, g0, nw);            RO_LOAD(f0, b0, g0, nw + 3 * 2048);
	v_add_u32_e32 v47, 1, v41
	s_nop 0
	v_cndmask_b32_e64 v46, v41, v46, s[6:7]
	v_fma_f32 v41, -v47, v41, v40
	v_cmp_lt_f32_e64 s[6:7], 0, v41
	s_nop 1
	v_cndmask_b32_e64 v41, v46, v47, s[6:7]
	v_mul_f32_e32 v46, 0x37800000, v41
	v_cndmask_b32_e32 v41, v41, v46, vcc
	v_cmp_class_f32_e32 vcc, v40, v253
	s_nop 1
	v_cndmask_b32_e32 v40, v41, v40, vcc
	v_div_scale_f32 v41, s[6:7], v40, v40, 1.0
	v_rcp_f32_e32 v46, v41
	s_nop 0
	v_fma_f32 v47, -v41, v46, 1.0
	v_fmac_f32_e32 v46, v47, v46
	v_div_scale_f32 v47, vcc, 1.0, v40, 1.0
	v_mul_f32_e32 v52, v47, v46
	v_fma_f32 v53, -v41, v52, v47
	v_fmac_f32_e32 v52, v53, v46
	v_fma_f32 v41, -v41, v52, v47
	v_div_fmas_f32 v41, v41, v46, v52
	v_div_fixup_f32 v40, v41, v40, 1.0
	v_lshlrev_b32_e32 v46, 16, v24
	v_and_b32_e32 v47, 0xffff0000, v24
	v_lshlrev_b32_e32 v24, 16, v25
	v_and_b32_e32 v25, 0xffff0000, v25
	v_pk_mul_f32 v[52:53], v[114:115], v[40:41] op_sel_hi:[1,0]
	v_pk_mul_f32 v[40:41], v[110:111], v[40:41] op_sel_hi:[1,0]
	s_nop 0
	v_pk_mul_f32 v[24:25], v[40:41], v[24:25]
	v_pk_mul_f32 v[40:41], v[52:53], v[46:47]
	s_nop 0
	v_cvt_pk_bf16_f32 v40, v40, v41
	v_cvt_pk_bf16_f32 v41, v24, v25
	v_add_f32_dpp v24, v157, v157 quad_perm:[1,0,3,2] row_mask:0xf bank_mask:0xf bound_ctrl:1
	global_store_dwordx2 v[94:95], v[40:41], off offset:2560
	s_nop 0
	v_add_f32_dpp v24, v24, v24 quad_perm:[2,3,0,1] row_mask:0xf bank_mask:0xf bound_ctrl:1
	s_nop 1
	v_add_f32_dpp v24, v24, v24 row_half_mirror row_mask:0xf bank_mask:0xf bound_ctrl:1
	s_nop 1
	v_add_f32_dpp v24, v24, v24 row_mirror row_mask:0xf bank_mask:0xf bound_ctrl:1
	s_nop 0
	v_readlane_b32 s9, v24, 16
	v_readlane_b32 s14, v24, 48
	v_readlane_b32 s6, v24, 0
	v_readlane_b32 s7, v24, 32
	v_mov_b32_e32 v24, s9
	v_mov_b32_e32 v25, s14
	v_pk_add_f32 v[24:25], s[6:7], v[24:25]
	s_nop 0
	v_add_f32_e32 v24, v24, v25
	v_fmamk_f32 v24, v24, 0x3b800000, v252
	v_cmp_gt_f32_e32 vcc, s55, v24
	v_mul_f32_e32 v25, 0x4f800000, v24
	s_nop 0
	v_cndmask_b32_e32 v24, v24, v25, vcc
	v_sqrt_f32_e32 v25, v24
	s_nop 0
	v_add_u32_e32 v40, -1, v25
	v_fma_f32 v41, -v40, v25, v24
	v_cmp_ge_f32_e64 s[6:7], 0, v41
	v_add_u32_e32 v41, 1, v25
	s_nop 0
	v_cndmask_b32_e64 v40, v25, v40, s[6:7]
	v_fma_f32 v25, -v41, v25, v24
	v_cmp_lt_f32_e64 s[6:7], 0, v25
	s_nop 1
	v_cndmask_b32_e64 v25, v40, v41, s[6:7]
	v_mul_f32_e32 v40, 0x37800000, v25
	v_cndmask_b32_e32 v25, v25, v40, vcc
	v_cmp_class_f32_e32 vcc, v24, v253
	s_nop 1
	v_cndmask_b32_e32 v24, v25, v24, vcc
	v_div_scale_f32 v25, s[6:7], v24, v24, 1.0
	v_rcp_f32_e32 v40, v25
	s_nop 0
	v_fma_f32 v41, -v25, v40, 1.0
	v_fmac_f32_e32 v40, v41, v40
	v_div_scale_f32 v41, vcc, 1.0, v24, 1.0
	v_mul_f32_e32 v46, v41, v40
	v_fma_f32 v47, -v25, v46, v41
	v_fmac_f32_e32 v46, v47, v40
	v_fma_f32 v25, -v25, v46, v41
	v_div_fmas_f32 v25, v25, v40, v46
	v_div_fixup_f32 v24, v25, v24, 1.0
	v_lshlrev_b32_e32 v40, 16, v20
	v_and_b32_e32 v41, 0xffff0000, v20
	v_lshlrev_b32_e32 v20, 16, v21
	v_and_b32_e32 v21, 0xffff0000, v21
	v_pk_mul_f32 v[46:47], v[106:107], v[24:25] op_sel_hi:[1,0]
	v_pk_mul_f32 v[24:25], v[102:103], v[24:25] op_sel_hi:[1,0]
	s_nop 0
	v_pk_mul_f32 v[20:21], v[24:25], v[20:21]
	v_pk_mul_f32 v[24:25], v[46:47], v[40:41]
	s_nop 0
	v_cvt_pk_bf16_f32 v24, v24, v25
	v_cvt_pk_bf16_f32 v25, v20, v21
	v_add_f32_dpp v20, v156, v156 quad_perm:[1,0,3,2] row_mask:0xf bank_mask:0xf bound_ctrl:1
	global_store_dwordx2 v[94:95], v[24:25], off offset:3072
	s_nop 0
	v_add_f32_dpp v20, v20, v20 quad_perm:[2,3,0,1] row_mask:0xf bank_mask:0xf bound_ctrl:1
	s_nop 1
	v_add_f32_dpp v20, v20, v20 row_half_mirror row_mask:0xf bank_mask:0xf bound_ctrl:1
	s_nop 1
	v_add_f32_dpp v20, v20, v20 row_mirror row_mask:0xf bank_mask:0xf bound_ctrl:1
	s_nop 0
	v_readlane_b32 s9, v20, 16
	v_readlane_b32 s14, v20, 48
	v_readlane_b32 s6, v20, 0
	v_readlane_b32 s7, v20, 32
	v_mov_b32_e32 v20, s9
	v_mov_b32_e32 v21, s14
	v_pk_add_f32 v[20:21], s[6:7], v[20:21]
	s_add_u32 s14, s10, 0x1800000
	v_add_f32_e32 v20, v20, v21
	v_fmamk_f32 v20, v20, 0x3b800000, v252
	v_cmp_gt_f32_e32 vcc, s55, v20
	v_mul_f32_e32 v21, 0x4f800000, v20
	s_addc_u32 s15, s11, 0
	v_cndmask_b32_e32 v20, v20, v21, vcc
	v_sqrt_f32_e32 v21, v20
	s_nop 0
	v_add_u32_e32 v24, -1, v21
	v_fma_f32 v25, -v24, v21, v20
	v_cmp_ge_f32_e64 s[6:7], 0, v25
	v_add_u32_e32 v25, 1, v21
	s_nop 0
	v_cndmask_b32_e64 v24, v21, v24, s[6:7]
	v_fma_f32 v21, -v25, v21, v20
	v_cmp_lt_f32_e64 s[6:7], 0, v21
	s_nop 1
	v_cndmask_b32_e64 v21, v24, v25, s[6:7]
	v_mul_f32_e32 v24, 0x37800000, v21
	v_cndmask_b32_e32 v21, v21, v24, vcc
	v_cmp_class_f32_e32 vcc, v20, v253
	s_nop 1
	v_cndmask_b32_e32 v20, v21, v20, vcc
	v_div_scale_f32 v21, s[6:7], v20, v20, 1.0
	v_rcp_f32_e32 v24, v21
	s_nop 0
	v_fma_f32 v25, -v21, v24, 1.0
	v_fmac_f32_e32 v24, v25, v24
	v_div_scale_f32 v25, vcc, 1.0, v20, 1.0
	v_mul_f32_e32 v40, v25, v24
	v_fma_f32 v41, -v21, v40, v25
	v_fmac_f32_e32 v40, v41, v24
	v_fma_f32 v21, -v21, v40, v25
	v_div_fmas_f32 v21, v21, v24, v40
	v_div_fixup_f32 v20, v21, v20, 1.0
	v_lshlrev_b32_e32 v24, 16, v16
	v_and_b32_e32 v25, 0xffff0000, v16
	v_lshlrev_b32_e32 v16, 16, v17
	v_and_b32_e32 v17, 0xffff0000, v17
	v_pk_mul_f32 v[40:41], v[98:99], v[20:21] op_sel_hi:[1,0]
	v_pk_mul_f32 v[20:21], v[90:91], v[20:21] op_sel_hi:[1,0]
	s_nop 0
	v_pk_mul_f32 v[16:17], v[20:21], v[16:17]
	v_pk_mul_f32 v[20:21], v[40:41], v[24:25]
	s_nop 0
	v_cvt_pk_bf16_f32 v20, v20, v21
	v_cvt_pk_bf16_f32 v21, v16, v17
	global_store_dwordx2 v[94:95], v[20:21], off offset:3584
	v_lshl_add_u64 v[20:21], v[6:7], 0, s[14:15]
	v_lshl_add_u64 v[16:17], v[4:5], 0, s[14:15]
	v_lshl_add_u64 v[94:95], v[20:21], 0, v[0:1]
	v_lshl_add_u64 v[20:21], v[8:9], 0, s[14:15]
	v_lshl_add_u64 v[16:17], v[16:17], 0, v[0:1]
	v_lshl_add_u64 v[150:151], v[20:21], 0, v[0:1]
	global_load_dwordx2 v[160:161], v[16:17], off
	global_load_dwordx2 v[154:155], v[94:95], off
	global_load_dwordx2 v[64:65], v[150:151], off
	global_load_dwordx2 v[148:149], v[16:17], off offset:512
	global_load_dwordx2 v[142:143], v[94:95], off offset:512
	global_load_dwordx2 v[58:59], v[150:151], off offset:512
	global_load_dwordx2 v[136:137], v[16:17], off offset:1024
	global_load_dwordx2 v[130:131], v[94:95], off offset:1024
	global_load_dwordx2 v[52:53], v[150:151], off offset:1024
	global_load_dwordx2 v[122:123], v[16:17], off offset:1536
	global_load_dwordx2 v[126:127], v[94:95], off offset:1536
	global_load_dwordx2 v[46:47], v[150:151], off offset:1536
	global_load_dwordx2 v[118:119], v[16:17], off offset:2048
	global_load_dwordx2 v[114:115], v[94:95], off offset:2048
	global_load_dwordx2 v[40:41], v[150:151], off offset:2048
	global_load_dwordx2 v[110:111], v[16:17], off offset:2560
	global_load_dwordx2 v[106:107], v[94:95], off offset:2560
	global_load_dwordx2 v[24:25], v[150:151], off offset:2560
	global_load_dwordx2 v[102:103], v[16:17], off offset:3072
	global_load_dwordx2 v[98:99], v[94:95], off offset:3072
	global_load_dwordx2 v[20:21], v[150:151], off offset:3072
	global_load_dwordx2 v[90:91], v[16:17], off offset:3584
	s_nop 0
	global_load_dwordx2 v[94:95], v[94:95], off offset:3584
	s_nop 0
	global_load_dwordx2 v[16:17], v[150:151], off offset:3584
	v_lshlrev_b32_e32 v150, 16, v146
	v_and_b32_e32 v151, 0xffff0000, v146
	v_lshlrev_b32_e32 v146, 16, v147
	v_and_b32_e32 v147, 0xffff0000, v147
	v_pk_add_f32 v[150:151], v[150:151], v[152:153]
	v_pk_add_f32 v[146:147], v[146:147], v[144:145]
	v_mov_b32_e32 v152, v151
	v_mov_b32_e32 v153, v147
	v_mov_b32_e32 v144, v150
	v_mov_b32_e32 v145, v146
	v_pk_mul_f32 v[152:153], v[152:153], v[152:153]
	s_nop 0
	v_pk_fma_f32 v[144:145], v[144:145], v[144:145], v[152:153]
	v_lshlrev_b32_e32 v152, 16, v138
	v_add_f32_e32 v162, v144, v145
	v_lshlrev_b32_e32 v144, 16, v140
	v_and_b32_e32 v145, 0xffff0000, v140
	v_and_b32_e32 v153, 0xffff0000, v138
	v_lshlrev_b32_e32 v140, 16, v141
	v_and_b32_e32 v141, 0xffff0000, v141
	v_lshlrev_b32_e32 v138, 16, v139
	v_and_b32_e32 v139, 0xffff0000, v139
	v_pk_add_f32 v[144:145], v[144:145], v[152:153]
	v_pk_add_f32 v[140:141], v[140:141], v[138:139]
	v_mov_b32_e32 v152, v145
	v_mov_b32_e32 v153, v141
	v_mov_b32_e32 v138, v144
	v_mov_b32_e32 v139, v140
	v_pk_mul_f32 v[152:153], v[152:153], v[152:153]
	s_nop 0
	v_pk_fma_f32 v[138:139], v[138:139], v[138:139], v[152:153]
	v_lshlrev_b32_e32 v152, 16, v132
	v_add_f32_e32 v164, v138, v139
	v_lshlrev_b32_e32 v138, 16, v134
	v_and_b32_e32 v139, 0xffff0000, v134
	v_and_b32_e32 v153, 0xffff0000, v132
	v_lshlrev_b32_e32 v134, 16, v135
	v_and_b32_e32 v135, 0xffff0000, v135
	v_lshlrev_b32_e32 v132, 16, v133
	v_and_b32_e32 v133, 0xffff0000, v133
	v_pk_add_f32 v[138:139], v[138:139], v[152:153]
	v_pk_add_f32 v[134:135], v[134:135], v[132:133]
	v_mov_b32_e32 v152, v139
	v_mov_b32_e32 v153, v135
	v_mov_b32_e32 v132, v138
	v_mov_b32_e32 v133, v134
	v_pk_mul_f32 v[152:153], v[152:153], v[152:153]
	s_nop 0
	v_pk_fma_f32 v[132:133], v[132:133], v[132:133], v[152:153]
	v_lshlrev_b32_e32 v152, 16, v124
	v_add_f32_e32 v165, v132, v133
	v_lshlrev_b32_e32 v132, 16, v128
	v_and_b32_e32 v133, 0xffff0000, v128
	v_and_b32_e32 v153, 0xffff0000, v124
	v_lshlrev_b32_e32 v128, 16, v129
	v_and_b32_e32 v129, 0xffff0000, v129
	v_lshlrev_b32_e32 v124, 16, v125
	v_and_b32_e32 v125, 0xffff0000, v125
	v_pk_add_f32 v[132:133], v[132:133], v[152:153]
	v_pk_add_f32 v[128:129], v[128:129], v[124:125]
	v_mov_b32_e32 v152, v133
	v_mov_b32_e32 v153, v129
	v_mov_b32_e32 v124, v132
	v_mov_b32_e32 v125, v128
	v_pk_mul_f32 v[152:153], v[152:153], v[152:153]
	s_nop 0
	v_pk_fma_f32 v[124:125], v[124:125], v[124:125], v[152:153]
	v_lshlrev_b32_e32 v152, 16, v116
	v_add_f32_e32 v166, v124, v125
	v_lshlrev_b32_e32 v124, 16, v120
	v_and_b32_e32 v125, 0xffff0000, v120
	v_and_b32_e32 v153, 0xffff0000, v116
	v_lshlrev_b32_e32 v120, 16, v121
	v_and_b32_e32 v121, 0xffff0000, v121
	v_lshlrev_b32_e32 v116, 16, v117
	v_and_b32_e32 v117, 0xffff0000, v117
	v_pk_add_f32 v[124:125], v[124:125], v[152:153]
	v_pk_add_f32 v[120:121], v[120:121], v[116:117]
	v_mov_b32_e32 v152, v125
	v_mov_b32_e32 v153, v121
	v_mov_b32_e32 v116, v124
	v_mov_b32_e32 v117, v120
	v_pk_mul_f32 v[152:153], v[152:153], v[152:153]
	s_nop 0
	v_pk_fma_f32 v[116:117], v[116:117], v[116:117], v[152:153]
	v_lshlrev_b32_e32 v152, 16, v108
	v_add_f32_e32 v157, v116, v117
	v_lshlrev_b32_e32 v116, 16, v112
	v_and_b32_e32 v117, 0xffff0000, v112
	v_and_b32_e32 v153, 0xffff0000, v108
	v_lshlrev_b32_e32 v112, 16, v113
	v_and_b32_e32 v113, 0xffff0000, v113
	v_lshlrev_b32_e32 v108, 16, v109
	v_and_b32_e32 v109, 0xffff0000, v109
	v_pk_add_f32 v[116:117], v[116:117], v[152:153]
	v_pk_add_f32 v[112:113], v[112:113], v[108:109]
	v_mov_b32_e32 v152, v117
	v_mov_b32_e32 v153, v113
	v_mov_b32_e32 v108, v116
	v_mov_b32_e32 v109, v112
	v_pk_mul_f32 v[152:153], v[152:153], v[152:153]
	s_nop 0
	v_pk_fma_f32 v[108:109], v[108:109], v[108:109], v[152:153]
	v_lshlrev_b32_e32 v152, 16, v100
	v_add_f32_e32 v156, v108, v109
	v_lshlrev_b32_e32 v108, 16, v104
	v_and_b32_e32 v109, 0xffff0000, v104
	v_and_b32_e32 v153, 0xffff0000, v100
	v_lshlrev_b32_e32 v104, 16, v105
	v_and_b32_e32 v105, 0xffff0000, v105
	v_lshlrev_b32_e32 v100, 16, v101
	v_and_b32_e32 v101, 0xffff0000, v101
	v_pk_add_f32 v[108:109], v[108:109], v[152:153]
	v_pk_add_f32 v[104:105], v[104:105], v[100:101]
	v_mov_b32_e32 v152, v109
	v_mov_b32_e32 v153, v105
	v_mov_b32_e32 v100, v108
	v_mov_b32_e32 v101, v104
	v_pk_mul_f32 v[152:153], v[152:153], v[152:153]
	s_nop 0
	v_pk_fma_f32 v[100:101], v[100:101], v[100:101], v[152:153]
	s_nop 0
	v_add_f32_e32 v153, v100, v101
	v_lshlrev_b32_e32 v100, 16, v96
	v_and_b32_e32 v101, 0xffff0000, v96
	v_lshlrev_b32_e32 v96, 16, v97
	v_and_b32_e32 v97, 0xffff0000, v97
	v_pk_add_f32 v[100:101], v[100:101], v[158:159]
	v_pk_add_f32 v[92:93], v[96:97], v[92:93]
	v_mov_b32_e32 v158, v101
	v_mov_b32_e32 v159, v93
	v_mov_b32_e32 v96, v100
	v_mov_b32_e32 v97, v92
	v_pk_mul_f32 v[158:159], v[158:159], v[158:159]
	s_nop 0
	v_pk_fma_f32 v[96:97], v[96:97], v[96:97], v[158:159]
	v_add_f32_dpp v158, v162, v162 quad_perm:[1,0,3,2] row_mask:0xf bank_mask:0xf bound_ctrl:1
	v_add_f32_e32 v152, v96, v97
	v_lshl_add_u64 v[96:97], v[2:3], 0, s[16:17]
	v_add_f32_dpp v158, v158, v158 quad_perm:[2,3,0,1] row_mask:0xf bank_mask:0xf bound_ctrl:1
	v_lshl_add_u64 v[96:97], v[96:97], 0, v[0:1]
	s_nop 0
	v_add_f32_dpp v158, v158, v158 row_half_mirror row_mask:0xf bank_mask:0xf bound_ctrl:1
	s_nop 1
	v_add_f32_dpp v158, v158, v158 row_mirror row_mask:0xf bank_mask:0xf bound_ctrl:1
	s_nop 0
	v_readlane_b32 s9, v158, 16
	v_readlane_b32 s16, v158, 48
	v_readlane_b32 s6, v158, 0
	v_readlane_b32 s7, v158, 32
	v_mov_b32_e32 v158, s9
	v_mov_b32_e32 v159, s16
	v_pk_add_f32 v[158:159], s[6:7], v[158:159]
	s_nop 0
	v_add_f32_e32 v158, v158, v159
	v_fmamk_f32 v158, v158, 0x3b800000, v252
	v_cmp_gt_f32_e32 vcc, s55, v158
	v_mul_f32_e32 v159, 0x4f800000, v158
	s_nop 0
	v_cndmask_b32_e32 v158, v158, v159, vcc
	v_sqrt_f32_e32 v159, v158
	s_nop 0
	v_add_u32_e32 v162, -1, v159
	v_fma_f32 v163, -v162, v159, v158
	v_cmp_ge_f32_e64 s[6:7], 0, v163
	v_add_u32_e32 v163, 1, v159
	s_nop 0
	v_cndmask_b32_e64 v162, v159, v162, s[6:7]
	v_fma_f32 v159, -v163, v159, v158
	v_cmp_lt_f32_e64 s[6:7], 0, v159
	s_nop 1
	v_cndmask_b32_e64 v159, v162, v163, s[6:7]
	v_mul_f32_e32 v162, 0x37800000, v159
	v_cndmask_b32_e32 v159, v159, v162, vcc
	v_cmp_class_f32_e32 vcc, v158, v253
	s_nop 1
	v_cndmask_b32_e32 v158, v159, v158, vcc
	v_div_scale_f32 v159, s[6:7], v158, v158, 1.0
	v_rcp_f32_e32 v162, v159
	s_nop 0
	v_fma_f32 v163, -v159, v162, 1.0
	v_fmac_f32_e32 v162, v163, v162
	v_div_scale_f32 v163, vcc, 1.0, v158, 1.0
	v_mul_f32_e32 v167, v163, v162
	v_fma_f32 v168, -v159, v167, v163
	v_fmac_f32_e32 v167, v168, v162
	v_fma_f32 v159, -v159, v167, v163
	v_div_fmas_f32 v159, v159, v162, v167
	v_div_fixup_f32 v158, v159, v158, 1.0
	v_lshlrev_b32_e32 v162, 16, v66
	v_and_b32_e32 v163, 0xffff0000, v66
	v_lshlrev_b32_e32 v66, 16, v67
	v_and_b32_e32 v67, 0xffff0000, v67
	v_pk_mul_f32 v[150:151], v[150:151], v[158:159] op_sel_hi:[1,0]
	v_pk_mul_f32 v[146:147], v[146:147], v[158:159] op_sel_hi:[1,0]
	s_nop 0
	v_pk_mul_f32 v[66:67], v[146:147], v[66:67]
	v_pk_mul_f32 v[146:147], v[150:151], v[162:163]
	s_nop 0
	v_cvt_pk_bf16_f32 v146, v146, v147
	v_cvt_pk_bf16_f32 v147, v66, v67
	v_add_f32_dpp v66, v164, v164 quad_perm:[1,0,3,2] row_mask:0xf bank_mask:0xf bound_ctrl:1
	global_store_dwordx2 v[96:97], v[146:147], off
	s_nop 0
	v_add_f32_dpp v66, v66, v66 quad_perm:[2,3,0,1] row_mask:0xf bank_mask:0xf bound_ctrl:1
	s_nop 1
	v_add_f32_dpp v66, v66, v66 row_half_mirror row_mask:0xf bank_mask:0xf bound_ctrl:1
	s_nop 1
	v_add_f32_dpp v66, v66, v66 row_mirror row_mask:0xf bank_mask:0xf bound_ctrl:1
	s_nop 0
	v_readlane_b32 s9, v66, 16
	v_readlane_b32 s16, v66, 48
	v_readlane_b32 s6, v66, 0
	v_readlane_b32 s7, v66, 32
	v_mov_b32_e32 v66, s9
	v_mov_b32_e32 v67, s16
	v_pk_add_f32 v[66:67], s[6:7], v[66:67]
	s_nop 0
	v_add_f32_e32 v66, v66, v67
	v_fmamk_f32 v66, v66, 0x3b800000, v252
	v_cmp_gt_f32_e32 vcc, s55, v66
	v_mul_f32_e32 v67, 0x4f800000, v66
	s_nop 0
	v_cndmask_b32_e32 v66, v66, v67, vcc
	v_sqrt_f32_e32 v67, v66
	s_nop 0
	v_add_u32_e32 v146, -1, v67
	v_fma_f32 v147, -v146, v67, v66
	v_cmp_ge_f32_e64 s[6:7], 0, v147
	v_add_u32_e32 v147, 1, v67
	s_nop 0
	v_cndmask_b32_e64 v146, v67, v146, s[6:7]
	v_fma_f32 v67, -v147, v67, v66
	v_cmp_lt_f32_e64 s[6:7], 0, v67
	s_nop 1
	v_cndmask_b32_e64 v67, v146, v147, s[6:7]
	v_mul_f32_e32 v146, 0x37800000, v67
	v_cndmask_b32_e32 v67, v67, v146, vcc
	v_cmp_class_f32_e32 vcc, v66, v253
	s_nop 1
	v_cndmask_b32_e32 v66, v67, v66, vcc
	v_div_scale_f32 v67, s[6:7], v66, v66, 1.0
	v_rcp_f32_e32 v146, v67
	s_nop 0
	v_fma_f32 v147, -v67, v146, 1.0
	v_fmac_f32_e32 v146, v147, v146
	v_div_scale_f32 v147, vcc, 1.0, v66, 1.0
	v_mul_f32_e32 v150, v147, v146
	v_fma_f32 v151, -v67, v150, v147
	v_fmac_f32_e32 v150, v151, v146
	v_fma_f32 v67, -v67, v150, v147
	v_div_fmas_f32 v67, v67, v146, v150
	v_div_fixup_f32 v66, v67, v66, 1.0
	v_lshlrev_b32_e32 v146, 16, v60
	v_and_b32_e32 v147, 0xffff0000, v60
	v_lshlrev_b32_e32 v60, 16, v61
	v_and_b32_e32 v61, 0xffff0000, v61
	v_pk_mul_f32 v[144:145], v[144:145], v[66:67] op_sel_hi:[1,0]
	v_pk_mul_f32 v[66:67], v[140:141], v[66:67] op_sel_hi:[1,0]
	s_nop 0
	v_pk_mul_f32 v[60:61], v[66:67], v[60:61]
	v_pk_mul_f32 v[66:67], v[144:145], v[146:147]
	s_nop 0
	v_cvt_pk_bf16_f32 v66, v66, v67
	v_cvt_pk_bf16_f32 v67, v60, v61
	v_add_f32_dpp v60, v165, v165 quad_perm:[1,0,3,2] row_mask:0xf bank_mask:0xf bound_ctrl:1
	global_store_dwordx2 v[96:97], v[66:67], off offset:512
	s_nop 0
	v_add_f32_dpp v60, v60, v60 quad_perm:[2,3,0,1] row_mask:0xf bank_mask:0xf bound_ctrl:1
	s_nop 1
	v_add_f32_dpp v60, v60, v60 row_half_mirror row_mask:0xf bank_mask:0xf bound_ctrl:1
	s_nop 1
	v_add_f32_dpp v60, v60, v60 row_mirror row_mask:0xf bank_mask:0xf bound_ctrl:1
	s_nop 0
	v_readlane_b32 s9, v60, 16
	v_readlane_b32 s16, v60, 48
	v_readlane_b32 s6, v60, 0
	v_readlane_b32 s7, v60, 32
	v_mov_b32_e32 v60, s9
	v_mov_b32_e32 v61, s16
	v_pk_add_f32 v[60:61], s[6:7], v[60:61]
	s_nop 0
	v_add_f32_e32 v60, v60, v61
	v_fmamk_f32 v60, v60, 0x3b800000, v252
	v_cmp_gt_f32_e32 vcc, s55, v60
	v_mul_f32_e32 v61, 0x4f800000, v60
	s_nop 0
	v_cndmask_b32_e32 v60, v60, v61, vcc
	v_sqrt_f32_e32 v61, v60
	s_nop 0
	v_add_u32_e32 v66, -1, v61
	v_fma_f32 v67, -v66, v61, v60
	v_cmp_ge_f32_e64 s[6:7], 0, v67
	v_add_u32_e32 v67, 1, v61
	s_nop 0
	v_cndmask_b32_e64 v66, v61, v66, s[6:7]
	v_fma_f32 v61, -v67, v61, v60
	v_cmp_lt_f32_e64 s[6:7], 0, v61
	s_nop 1
	v_cndmask_b32_e64 v61, v66, v67, s[6:7]
	v_mul_f32_e32 v66, 0x37800000, v61
	v_cndmask_b32_e32 v61, v61, v66, vcc
	v_cmp_class_f32_e32 vcc, v60, v253
	s_nop 1
	v_cndmask_b32_e32 v60, v61, v60, vcc
	v_div_scale_f32 v61, s[6:7], v60, v60, 1.0
	v_rcp_f32_e32 v66, v61
	s_nop 0
	v_fma_f32 v67, -v61, v66, 1.0
	v_fmac_f32_e32 v66, v67, v66
	v_div_scale_f32 v67, vcc, 1.0, v60, 1.0
	v_mul_f32_e32 v140, v67, v66
	v_fma_f32 v141, -v61, v140, v67
	v_fmac_f32_e32 v140, v141, v66
	v_fma_f32 v61, -v61, v140, v67
	v_div_fmas_f32 v61, v61, v66, v140
	v_div_fixup_f32 v60, v61, v60, 1.0
	v_lshlrev_b32_e32 v66, 16, v54
	v_and_b32_e32 v67, 0xffff0000, v54
	v_lshlrev_b32_e32 v54, 16, v55
	v_and_b32_e32 v55, 0xffff0000, v55
	v_pk_mul_f32 v[138:139], v[138:139], v[60:61] op_sel_hi:[1,0]
	v_pk_mul_f32 v[60:61], v[134:135], v[60:61] op_sel_hi:[1,0]
	s_waitcnt vmcnt(56)
	v_lshlrev_b32_e32 v140, 16, v86
	v_pk_mul_f32 v[54:55], v[60:61], v[54:55]
	v_pk_mul_f32 v[60:61], v[138:139], v[66:67]
	v_and_b32_e32 v141, 0xffff0000, v86
	v_cvt_pk_bf16_f32 v60, v60, v61
	v_cvt_pk_bf16_f32 v61, v54, v55
	v_add_f32_dpp v54, v166, v166 quad_perm:[1,0,3,2] row_mask:0xf bank_mask:0xf bound_ctrl:1
	global_store_dwordx2 v[96:97], v[60:61], off offset:1024
	v_lshlrev_b32_e32 v86, 16, v87
	v_add_f32_dpp v54, v54, v54 quad_perm:[2,3,0,1] row_mask:0xf bank_mask:0xf bound_ctrl:1
	v_and_b32_e32 v87, 0xffff0000, v87
	s_nop 0
	v_add_f32_dpp v54, v54, v54 row_half_mirror row_mask:0xf bank_mask:0xf bound_ctrl:1
	s_nop 1
	v_add_f32_dpp v54, v54, v54 row_mirror row_mask:0xf bank_mask:0xf bound_ctrl:1
	s_nop 0
	v_readlane_b32 s9, v54, 16
	v_readlane_b32 s16, v54, 48
	v_readlane_b32 s6, v54, 0
	v_readlane_b32 s7, v54, 32
	v_mov_b32_e32 v54, s9
	v_mov_b32_e32 v55, s16
	v_pk_add_f32 v[54:55], s[6:7], v[54:55]
	s_nop 0
	v_add_f32_e32 v54, v54, v55
	v_fmamk_f32 v54, v54, 0x3b800000, v252
	v_cmp_gt_f32_e32 vcc, s55, v54
	v_mul_f32_e32 v55, 0x4f800000, v54
	s_nop 0
	v_cndmask_b32_e32 v54, v54, v55, vcc
	v_sqrt_f32_e32 v55, v54
	s_nop 0
	v_add_u32_e32 v60, -1, v55
	v_fma_f32 v61, -v60, v55, v54
	v_cmp_ge_f32_e64 s[6:7], 0, v61
	v_add_u32_e32 v61, 1, v55
	s_nop 0
	v_cndmask_b32_e64 v60, v55, v60, s[6:7]
	v_fma_f32 v55, -v61, v55, v54
	v_cmp_lt_f32_e64 s[6:7], 0, v55
	s_nop 1
	v_cndmask_b32_e64 v55, v60, v61, s[6:7]
	v_mul_f32_e32 v60, 0x37800000, v55
	v_cndmask_b32_e32 v55, v55, v60, vcc
	v_cmp_class_f32_e32 vcc, v54, v253
	s_nop 1
	v_cndmask_b32_e32 v54, v55, v54, vcc
	v_div_scale_f32 v55, s[6:7], v54, v54, 1.0
	v_rcp_f32_e32 v60, v55
	s_nop 0
	v_fma_f32 v61, -v55, v60, 1.0
	v_fmac_f32_e32 v60, v61, v60
	v_div_scale_f32 v61, vcc, 1.0, v54, 1.0
	v_mul_f32_e32 v66, v61, v60
	v_fma_f32 v67, -v55, v66, v61
	v_fmac_f32_e32 v66, v67, v60
	v_fma_f32 v55, -v55, v66, v61
	v_div_fmas_f32 v55, v55, v60, v66
	v_div_fixup_f32 v54, v55, v54, 1.0
	v_lshlrev_b32_e32 v60, 16, v48
	v_and_b32_e32 v61, 0xffff0000, v48
	v_lshlrev_b32_e32 v48, 16, v49
	v_and_b32_e32 v49, 0xffff0000, v49
	v_pk_mul_f32 v[66:67], v[132:133], v[54:55] op_sel_hi:[1,0]
	v_pk_mul_f32 v[54:55], v[128:129], v[54:55] op_sel_hi:[1,0]
	s_nop 0
	v_pk_mul_f32 v[48:49], v[54:55], v[48:49]
	v_pk_mul_f32 v[54:55], v[66:67], v[60:61]
	s_nop 0
	v_cvt_pk_bf16_f32 v54, v54, v55
	v_cvt_pk_bf16_f32 v55, v48, v49
	v_add_f32_dpp v48, v157, v157 quad_perm:[1,0,3,2] row_mask:0xf bank_mask:0xf bound_ctrl:1
	global_store_dwordx2 v[96:97], v[54:55], off offset:1536
	s_nop 0
	v_add_f32_dpp v48, v48, v48 quad_perm:[2,3,0,1] row_mask:0xf bank_mask:0xf bound_ctrl:1
	s_nop 1
	v_add_f32_dpp v48, v48, v48 row_half_mirror row_mask:0xf bank_mask:0xf bound_ctrl:1
	s_nop 1
	v_add_f32_dpp v48, v48, v48 row_mirror row_mask:0xf bank_mask:0xf bound_ctrl:1
	s_nop 0
	v_readlane_b32 s9, v48, 16
	v_readlane_b32 s16, v48, 48
	v_readlane_b32 s6, v48, 0
	v_readlane_b32 s7, v48, 32
	v_mov_b32_e32 v48, s9
	v_mov_b32_e32 v49, s16
	v_pk_add_f32 v[48:49], s[6:7], v[48:49]
	s_nop 0
	v_add_f32_e32 v48, v48, v49
	v_fmamk_f32 v48, v48, 0x3b800000, v252
	v_cmp_gt_f32_e32 vcc, s55, v48
	v_mul_f32_e32 v49, 0x4f800000, v48
	s_nop 0
	v_cndmask_b32_e32 v48, v48, v49, vcc
	v_sqrt_f32_e32 v49, v48
	s_nop 0
	v_add_u32_e32 v54, -1, v49
	v_fma_f32 v55, -v54, v49, v48
	v_cmp_ge_f32_e64 s[6:7], 0, v55
	v_add_u32_e32 v55, 1, v49
	s_nop 0
	v_cndmask_b32_e64 v54, v49, v54, s[6:7]
	v_fma_f32 v49, -v55, v49, v48
	v_cmp_lt_f32_e64 s[6:7], 0, v49
	s_nop 1
	v_cndmask_b32_e64 v49, v54, v55, s[6:7]
	v_mul_f32_e32 v54, 0x37800000, v49
	v_cndmask_b32_e32 v49, v49, v54, vcc
	v_cmp_class_f32_e32 vcc, v48, v253
	s_nop 1
	v_cndmask_b32_e32 v48, v49, v48, vcc
	v_div_scale_f32 v49, s[6:7], v48, v48, 1.0
	v_rcp_f32_e32 v54, v49
	s_nop 0
	v_fma_f32 v55, -v49, v54, 1.0
	v_fmac_f32_e32 v54, v55, v54
	v_div_scale_f32 v55, vcc, 1.0, v48, 1.0
	v_mul_f32_e32 v60, v55, v54
	v_fma_f32 v61, -v49, v60, v55
	v_fmac_f32_e32 v60, v61, v54
	v_fma_f32 v49, -v49, v60, v55
	v_div_fmas_f32 v49, v49, v54, v60
	v_div_fixup_f32 v48, v49, v48, 1.0
	v_lshlrev_b32_e32 v54, 16, v42
	v_and_b32_e32 v55, 0xffff0000, v42
	v_lshlrev_b32_e32 v42, 16, v43
	v_and_b32_e32 v43, 0xffff0000, v43
	v_pk_mul_f32 v[60:61], v[124:125], v[48:49] op_sel_hi:[1,0]
	v_pk_mul_f32 v[48:49], v[120:121], v[48:49] op_sel_hi:[1,0]
	s_nop 0
	v_pk_mul_f32 v[42:43], v[48:49], v[42:43]
	v_pk_mul_f32 v[48:49], v[60:61], v[54:55]
	s_nop 0
	v_cvt_pk_bf16_f32 v48, v48, v49
	v_cvt_pk_bf16_f32 v49, v42, v43
	v_add_f32_dpp v42, v156, v156 quad_perm:[1,0,3,2] row_mask:0xf bank_mask:0xf bound_ctrl:1
	global_store_dwordx2 v[96:97], v[48:49], off offset:2048
	s_nop 0
	v_add_f32_dpp v42, v42, v42 quad_perm:[2,3,0,1] row_mask:0xf bank_mask:0xf bound_ctrl:1
	s_nop 1
	v_add_f32_dpp v42, v42, v42 row_half_mirror row_mask:0xf bank_mask:0xf bound_ctrl:1
	s_nop 1
	v_add_f32_dpp v42, v42, v42 row_mirror row_mask:0xf bank_mask:0xf bound_ctrl:1
	s_nop 0
	v_readlane_b32 s9, v42, 16
	v_readlane_b32 s16, v42, 48
	v_readlane_b32 s6, v42, 0
	v_readlane_b32 s7, v42, 32
	v_mov_b32_e32 v42, s9
	v_mov_b32_e32 v43, s16
	v_pk_add_f32 v[42:43], s[6:7], v[42:43]
	s_nop 0
	v_add_f32_e32 v42, v42, v43
	v_fmamk_f32 v42, v42, 0x3b800000, v252
	v_cmp_gt_f32_e32 vcc, s55, v42
	v_mul_f32_e32 v43, 0x4f800000, v42
	s_nop 0
	v_cndmask_b32_e32 v42, v42, v43, vcc
	v_sqrt_f32_e32 v43, v42
	s_nop 0
	v_add_u32_e32 v48, -1, v43
	v_fma_f32 v49, -v48, v43, v42
	v_cmp_ge_f32_e64 s[6:7], 0, v49
	v_add_u32_e32 v49, 1, v43
	s_nop 0
	v_cndmask_b32_e64 v48, v43, v48, s[6:7]
	v_fma_f32 v43, -v49, v43, v42
	v_cmp_lt_f32_e64 s[6:7], 0, v43
	s_nop 1
	v_cndmask_b32_e64 v43, v48, v49, s[6:7]
	v_mul_f32_e32 v48, 0x37800000, v43
	v_cndmask_b32_e32 v43, v43, v48, vcc
	v_cmp_class_f32_e32 vcc, v42, v253
	s_nop 1
	v_cndmask_b32_e32 v42, v43, v42, vcc
	v_div_scale_f32 v43, s[6:7], v42, v42, 1.0
	v_rcp_f32_e32 v48, v43
	s_nop 0
	v_fma_f32 v49, -v43, v48, 1.0
	v_fmac_f32_e32 v48, v49, v48
	v_div_scale_f32 v49, vcc, 1.0, v42, 1.0
	v_mul_f32_e32 v54, v49, v48
	v_fma_f32 v55, -v43, v54, v49
	v_fmac_f32_e32 v54, v55, v48
	v_fma_f32 v43, -v43, v54, v49
	v_div_fmas_f32 v43, v43, v48, v54
	v_div_fixup_f32 v42, v43, v42, 1.0
	v_lshlrev_b32_e32 v48, 16, v36
	v_and_b32_e32 v49, 0xffff0000, v36
	v_lshlrev_b32_e32 v36, 16, v37
	v_and_b32_e32 v37, 0xffff0000, v37
	v_pk_mul_f32 v[54:55], v[116:117], v[42:43] op_sel_hi:[1,0]
	v_pk_mul_f32 v[42:43], v[112:113], v[42:43] op_sel_hi:[1,0]
	s_nop 0
	v_pk_mul_f32 v[36:37], v[42:43], v[36:37]
	v_pk_mul_f32 v[42:43], v[54:55], v[48:49]
	s_nop 0
	v_cvt_pk_bf16_f32 v42, v42, v43
	v_cvt_pk_bf16_f32 v43, v36, v37
	v_add_f32_dpp v36, v153, v153 quad_perm:[1,0,3,2] row_mask:0xf bank_mask:0xf bound_ctrl:1
	global_store_dwordx2 v[96:97], v[42:43], off offset:2560
	s_waitcnt vmcnt(39)
	v_and_b32_e32 v153, 0xffff0000, v44
	v_add_f32_dpp v36, v36, v36 quad_perm:[2,3,0,1] row_mask:0xf bank_mask:0xf bound_ctrl:1
	s_nop 1
	v_add_f32_dpp v36, v36, v36 row_half_mirror row_mask:0xf bank_mask:0xf bound_ctrl:1
	s_nop 1
	v_add_f32_dpp v36, v36, v36 row_mirror row_mask:0xf bank_mask:0xf bound_ctrl:1
	s_nop 0
	v_readlane_b32 s9, v36, 16
	v_readlane_b32 s16, v36, 48
	v_readlane_b32 s6, v36, 0
	v_readlane_b32 s7, v36, 32
	v_mov_b32_e32 v36, s9
	v_mov_b32_e32 v37, s16
	v_pk_add_f32 v[36:37], s[6:7], v[36:37]
	s_nop 0
	v_add_f32_e32 v36, v36, v37
	v_fmamk_f32 v36, v36, 0x3b800000, v252
	v_cmp_gt_f32_e32 vcc, s55, v36
	v_mul_f32_e32 v37, 0x4f800000, v36
	s_nop 0
	v_cndmask_b32_e32 v36, v36, v37, vcc
	v_sqrt_f32_e32 v37, v36
	s_nop 0
	v_add_u32_e32 v42, -1, v37
	v_fma_f32 v43, -v42, v37, v36
	v_cmp_ge_f32_e64 s[6:7], 0, v43
	v_add_u32_e32 v43, 1, v37
	s_nop 0
	v_cndmask_b32_e64 v42, v37, v42, s[6:7]
	v_fma_f32 v37, -v43, v37, v36
	v_cmp_lt_f32_e64 s[6:7], 0, v37
	s_nop 1
	v_cndmask_b32_e64 v37, v42, v43, s[6:7]
	v_mul_f32_e32 v42, 0x37800000, v37
	v_cndmask_b32_e32 v37, v37, v42, vcc
	v_cmp_class_f32_e32 vcc, v36, v253
	s_nop 1
	v_cndmask_b32_e32 v36, v37, v36, vcc
	v_div_scale_f32 v37, s[6:7], v36, v36, 1.0
	v_rcp_f32_e32 v42, v37
	s_nop 0
	v_fma_f32 v43, -v37, v42, 1.0
	v_fmac_f32_e32 v42, v43, v42
	v_div_scale_f32 v43, vcc, 1.0, v36, 1.0
	v_mul_f32_e32 v48, v43, v42
	v_fma_f32 v49, -v37, v48, v43
	v_fmac_f32_e32 v48, v49, v42
	v_fma_f32 v37, -v37, v48, v43
	v_div_fmas_f32 v37, v37, v42, v48
	v_div_fixup_f32 v36, v37, v36, 1.0
	v_lshlrev_b32_e32 v42, 16, v32
	v_and_b32_e32 v43, 0xffff0000, v32
	v_lshlrev_b32_e32 v32, 16, v33
	v_and_b32_e32 v33, 0xffff0000, v33
	v_pk_mul_f32 v[48:49], v[108:109], v[36:37] op_sel_hi:[1,0]
	v_pk_mul_f32 v[36:37], v[104:105], v[36:37] op_sel_hi:[1,0]
	s_nop 0
	v_pk_mul_f32 v[32:33], v[36:37], v[32:33]
	v_pk_mul_f32 v[36:37], v[48:49], v[42:43]
	s_nop 0
	v_cvt_pk_bf16_f32 v36, v36, v37
	v_cvt_pk_bf16_f32 v37, v32, v33
	v_add_f32_dpp v32, v152, v152 quad_perm:[1,0,3,2] row_mask:0xf bank_mask:0xf bound_ctrl:1
	global_store_dwordx2 v[96:97], v[36:37], off offset:3072
	v_lshlrev_b32_e32 v152, 16, v44
	v_add_f32_dpp v32, v32, v32 quad_perm:[2,3,0,1] row_mask:0xf bank_mask:0xf bound_ctrl:1
	v_lshlrev_b32_e32 v44, 16, v45
	v_and_b32_e32 v45, 0xffff0000, v45
	v_add_f32_dpp v32, v32, v32 row_half_mirror row_mask:0xf bank_mask:0xf bound_ctrl:1
	s_nop 1
	v_add_f32_dpp v32, v32, v32 row_mirror row_mask:0xf bank_mask:0xf bound_ctrl:1
	s_nop 0
	v_readlane_b32 s9, v32, 16
	v_readlane_b32 s16, v32, 48
	v_readlane_b32 s6, v32, 0
	v_readlane_b32 s7, v32, 32
	v_mov_b32_e32 v32, s9
	v_mov_b32_e32 v33, s16
	v_pk_add_f32 v[32:33], s[6:7], v[32:33]
	s_add_u32 s16, s10, 0x2000000
	v_add_f32_e32 v32, v32, v33
	v_fmamk_f32 v32, v32, 0x3b800000, v252
	v_cmp_gt_f32_e32 vcc, s55, v32
	v_mul_f32_e32 v33, 0x4f800000, v32
	s_addc_u32 s17, s11, 0
	v_cndmask_b32_e32 v32, v32, v33, vcc
	v_sqrt_f32_e32 v33, v32
	s_nop 0
	v_add_u32_e32 v36, -1, v33
	v_fma_f32 v37, -v36, v33, v32
	v_cmp_ge_f32_e64 s[6:7], 0, v37
	v_add_u32_e32 v37, 1, v33
	s_nop 0
	v_cndmask_b32_e64 v36, v33, v36, s[6:7]
	v_fma_f32 v33, -v37, v33, v32
	v_cmp_lt_f32_e64 s[6:7], 0, v33
	s_nop 1
	v_cndmask_b32_e64 v33, v36, v37, s[6:7]
	v_mul_f32_e32 v36, 0x37800000, v33
	v_cndmask_b32_e32 v33, v33, v36, vcc
	v_cmp_class_f32_e32 vcc, v32, v253
	s_nop 1
	v_cndmask_b32_e32 v32, v33, v32, vcc
	v_div_scale_f32 v33, s[6:7], v32, v32, 1.0
	v_rcp_f32_e32 v36, v33
	s_nop 0
	v_fma_f32 v37, -v33, v36, 1.0
	v_fmac_f32_e32 v36, v37, v36
	v_div_scale_f32 v37, vcc, 1.0, v32, 1.0
	v_mul_f32_e32 v42, v37, v36
	v_fma_f32 v43, -v33, v42, v37
	v_fmac_f32_e32 v42, v43, v36
	v_fma_f32 v33, -v33, v42, v37
	v_div_fmas_f32 v33, v33, v36, v42
	v_div_fixup_f32 v32, v33, v32, 1.0
	v_lshlrev_b32_e32 v36, 16, v28
	v_and_b32_e32 v37, 0xffff0000, v28
	v_lshlrev_b32_e32 v28, 16, v29
	v_and_b32_e32 v29, 0xffff0000, v29
	v_pk_mul_f32 v[42:43], v[100:101], v[32:33] op_sel_hi:[1,0]
	v_pk_mul_f32 v[32:33], v[92:93], v[32:33] op_sel_hi:[1,0]
	s_nop 0
	v_pk_mul_f32 v[28:29], v[32:33], v[28:29]
	v_pk_mul_f32 v[32:33], v[42:43], v[36:37]
	s_nop 0
	v_cvt_pk_bf16_f32 v32, v32, v33
	v_cvt_pk_bf16_f32 v33, v28, v29
	global_store_dwordx2 v[96:97], v[32:33], off offset:3584
	v_lshl_add_u64 v[32:33], v[6:7], 0, s[16:17]
	v_lshl_add_u64 v[28:29], v[4:5], 0, s[16:17]
	v_lshl_add_u64 v[96:97], v[32:33], 0, v[0:1]
	v_lshl_add_u64 v[32:33], v[8:9], 0, s[16:17]
	v_lshl_add_u64 v[28:29], v[28:29], 0, v[0:1]
	v_lshl_add_u64 v[134:135], v[32:33], 0, v[0:1]
	global_load_dwordx2 v[162:163], v[28:29], off
	global_load_dwordx2 v[156:157], v[96:97], off
	global_load_dwordx2 v[66:67], v[134:135], off
	global_load_dwordx2 v[150:151], v[28:29], off offset:512
	global_load_dwordx2 v[144:145], v[96:97], off offset:512
	global_load_dwordx2 v[60:61], v[134:135], off offset:512
	global_load_dwordx2 v[138:139], v[28:29], off offset:1024
	global_load_dwordx2 v[132:133], v[96:97], off offset:1024
	global_load_dwordx2 v[54:55], v[134:135], off offset:1024
	global_load_dwordx2 v[124:125], v[28:29], off offset:1536
	global_load_dwordx2 v[128:129], v[96:97], off offset:1536
	global_load_dwordx2 v[48:49], v[134:135], off offset:1536
	global_load_dwordx2 v[120:121], v[28:29], off offset:2048
	global_load_dwordx2 v[116:117], v[96:97], off offset:2048
	global_load_dwordx2 v[42:43], v[134:135], off offset:2048
	global_load_dwordx2 v[112:113], v[28:29], off offset:2560
	global_load_dwordx2 v[108:109], v[96:97], off offset:2560
	global_load_dwordx2 v[36:37], v[134:135], off offset:2560
	global_load_dwordx2 v[104:105], v[28:29], off offset:3072
	global_load_dwordx2 v[100:101], v[96:97], off offset:3072
	global_load_dwordx2 v[32:33], v[134:135], off offset:3072
	global_load_dwordx2 v[92:93], v[28:29], off offset:3584
	s_nop 0
	global_load_dwordx2 v[96:97], v[96:97], off offset:3584
	s_nop 0
	global_load_dwordx2 v[28:29], v[134:135], off offset:3584
	v_lshlrev_b32_e32 v134, 16, v88
	v_and_b32_e32 v135, 0xffff0000, v88
	v_lshlrev_b32_e32 v88, 16, v89
	v_and_b32_e32 v89, 0xffff0000, v89
	v_pk_add_f32 v[134:135], v[134:135], v[140:141]
	v_pk_add_f32 v[88:89], v[88:89], v[86:87]
	v_mov_b32_e32 v140, v135
	v_mov_b32_e32 v141, v89
	v_mov_b32_e32 v86, v134
	v_mov_b32_e32 v87, v88
	v_pk_mul_f32 v[140:141], v[140:141], v[140:141]
	s_nop 0
	v_pk_fma_f32 v[86:87], v[86:87], v[86:87], v[140:141]
	v_lshlrev_b32_e32 v140, 16, v82
	v_add_f32_e32 v158, v86, v87
	v_lshlrev_b32_e32 v86, 16, v84
	v_and_b32_e32 v87, 0xffff0000, v84
	v_and_b32_e32 v141, 0xffff0000, v82
	v_lshlrev_b32_e32 v84, 16, v85
	v_and_b32_e32 v85, 0xffff0000, v85
	v_lshlrev_b32_e32 v82, 16, v83
	v_and_b32_e32 v83, 0xffff0000, v83
	v_pk_add_f32 v[86:87], v[86:87], v[140:141]
	v_pk_add_f32 v[84:85], v[84:85], v[82:83]
	v_mov_b32_e32 v140, v87
	v_mov_b32_e32 v141, v85
	v_mov_b32_e32 v82, v86
	v_mov_b32_e32 v83, v84
	v_pk_mul_f32 v[140:141], v[140:141], v[140:141]
	s_nop 0
	v_pk_fma_f32 v[82:83], v[82:83], v[82:83], v[140:141]
	v_lshlrev_b32_e32 v140, 16, v78
	v_add_f32_e32 v164, v82, v83
	v_lshlrev_b32_e32 v82, 16, v80
	v_and_b32_e32 v83, 0xffff0000, v80
	v_and_b32_e32 v141, 0xffff0000, v78
	v_lshlrev_b32_e32 v80, 16, v81
	v_and_b32_e32 v81, 0xffff0000, v81
	v_lshlrev_b32_e32 v78, 16, v79
	v_and_b32_e32 v79, 0xffff0000, v79
	v_pk_add_f32 v[82:83], v[82:83], v[140:141]
	v_pk_add_f32 v[80:81], v[80:81], v[78:79]
	v_mov_b32_e32 v140, v83
	v_mov_b32_e32 v141, v81
	v_mov_b32_e32 v78, v82
	v_mov_b32_e32 v79, v80
	v_pk_mul_f32 v[140:141], v[140:141], v[140:141]
	s_nop 0
	v_pk_fma_f32 v[78:79], v[78:79], v[78:79], v[140:141]
	v_lshlrev_b32_e32 v140, 16, v76
	v_add_f32_e32 v165, v78, v79
	v_lshlrev_b32_e32 v78, 16, v74
	v_and_b32_e32 v79, 0xffff0000, v74
	v_and_b32_e32 v141, 0xffff0000, v76
	v_lshlrev_b32_e32 v74, 16, v75
	v_and_b32_e32 v75, 0xffff0000, v75
	v_lshlrev_b32_e32 v76, 16, v77
	v_and_b32_e32 v77, 0xffff0000, v77
	v_pk_add_f32 v[78:79], v[78:79], v[140:141]
	v_pk_add_f32 v[76:77], v[74:75], v[76:77]
	v_mov_b32_e32 v140, v79
	v_mov_b32_e32 v141, v77
	v_mov_b32_e32 v74, v78
	v_mov_b32_e32 v75, v76
	v_pk_mul_f32 v[140:141], v[140:141], v[140:141]
	s_nop 0
	v_pk_fma_f32 v[74:75], v[74:75], v[74:75], v[140:141]
	v_lshlrev_b32_e32 v140, 16, v70
	v_add_f32_e32 v166, v74, v75
	v_lshlrev_b32_e32 v74, 16, v72
	v_and_b32_e32 v75, 0xffff0000, v72
	v_and_b32_e32 v141, 0xffff0000, v70
	v_lshlrev_b32_e32 v72, 16, v73
	v_and_b32_e32 v73, 0xffff0000, v73
	v_lshlrev_b32_e32 v70, 16, v71
	v_and_b32_e32 v71, 0xffff0000, v71
	v_pk_add_f32 v[74:75], v[74:75], v[140:141]
	v_pk_add_f32 v[72:73], v[72:73], v[70:71]
	v_mov_b32_e32 v140, v75
	v_mov_b32_e32 v141, v73
	v_mov_b32_e32 v70, v74
	v_mov_b32_e32 v71, v72
	v_pk_mul_f32 v[140:141], v[140:141], v[140:141]
	s_nop 0
	v_pk_fma_f32 v[70:71], v[70:71], v[70:71], v[140:141]
	v_lshlrev_b32_e32 v140, 16, v62
	v_add_f32_e32 v147, v70, v71
	v_lshlrev_b32_e32 v70, 16, v68
	v_and_b32_e32 v71, 0xffff0000, v68
	v_and_b32_e32 v141, 0xffff0000, v62
	v_lshlrev_b32_e32 v68, 16, v69
	v_and_b32_e32 v69, 0xffff0000, v69
	v_lshlrev_b32_e32 v62, 16, v63
	v_and_b32_e32 v63, 0xffff0000, v63
	v_pk_add_f32 v[70:71], v[70:71], v[140:141]
	v_pk_add_f32 v[68:69], v[68:69], v[62:63]
	v_mov_b32_e32 v140, v71
	v_mov_b32_e32 v141, v69
	v_mov_b32_e32 v62, v70
	v_mov_b32_e32 v63, v68
	v_pk_mul_f32 v[140:141], v[140:141], v[140:141]
	s_nop 0
	v_pk_fma_f32 v[62:63], v[62:63], v[62:63], v[140:141]
	v_lshlrev_b32_e32 v140, 16, v50
	v_add_f32_e32 v146, v62, v63
	v_lshlrev_b32_e32 v62, 16, v56
	v_and_b32_e32 v63, 0xffff0000, v56
	v_and_b32_e32 v141, 0xffff0000, v50
	v_lshlrev_b32_e32 v56, 16, v57
	v_and_b32_e32 v57, 0xffff0000, v57
	v_lshlrev_b32_e32 v50, 16, v51
	v_and_b32_e32 v51, 0xffff0000, v51
	v_pk_add_f32 v[62:63], v[62:63], v[140:141]
	v_pk_add_f32 v[56:57], v[56:57], v[50:51]
	v_mov_b32_e32 v140, v63
	v_mov_b32_e32 v141, v57
	v_mov_b32_e32 v50, v62
	v_mov_b32_e32 v51, v56
	v_pk_mul_f32 v[140:141], v[140:141], v[140:141]
	s_nop 0
	v_pk_fma_f32 v[50:51], v[50:51], v[50:51], v[140:141]
	s_nop 0
	v_add_f32_e32 v141, v50, v51
	v_lshlrev_b32_e32 v50, 16, v38
	v_and_b32_e32 v51, 0xffff0000, v38
	v_lshlrev_b32_e32 v38, 16, v39
	v_and_b32_e32 v39, 0xffff0000, v39
	v_pk_add_f32 v[50:51], v[50:51], v[152:153]
	v_pk_add_f32 v[38:39], v[38:39], v[44:45]
	v_mov_b32_e32 v152, v51
	v_mov_b32_e32 v153, v39
	v_mov_b32_e32 v44, v50
	v_mov_b32_e32 v45, v38
	v_pk_mul_f32 v[152:153], v[152:153], v[152:153]
	s_nop 0
	v_pk_fma_f32 v[44:45], v[44:45], v[44:45], v[152:153]
	v_add_f32_dpp v152, v158, v158 quad_perm:[1,0,3,2] row_mask:0xf bank_mask:0xf bound_ctrl:1
	v_add_f32_e32 v140, v44, v45
	v_lshl_add_u64 v[44:45], v[2:3], 0, s[12:13]
	v_add_f32_dpp v152, v152, v152 quad_perm:[2,3,0,1] row_mask:0xf bank_mask:0xf bound_ctrl:1
	v_lshl_add_u64 v[44:45], v[44:45], 0, v[0:1]
	s_nop 0
	v_add_f32_dpp v152, v152, v152 row_half_mirror row_mask:0xf bank_mask:0xf bound_ctrl:1
	s_nop 1
	v_add_f32_dpp v152, v152, v152 row_mirror row_mask:0xf bank_mask:0xf bound_ctrl:1
	s_nop 0
	v_readlane_b32 s9, v152, 16
	v_readlane_b32 s12, v152, 48
	v_readlane_b32 s6, v152, 0
	v_readlane_b32 s7, v152, 32
	v_mov_b32_e32 v152, s9
	v_mov_b32_e32 v153, s12
	v_pk_add_f32 v[152:153], s[6:7], v[152:153]
	s_nop 0
	v_add_f32_e32 v152, v152, v153
	v_fmamk_f32 v152, v152, 0x3b800000, v252
	v_cmp_gt_f32_e32 vcc, s55, v152
	v_mul_f32_e32 v153, 0x4f800000, v152
	s_nop 0
	v_cndmask_b32_e32 v152, v152, v153, vcc
	v_sqrt_f32_e32 v153, v152
	s_nop 0
	v_add_u32_e32 v158, -1, v153
	v_fma_f32 v159, -v158, v153, v152
	v_cmp_ge_f32_e64 s[6:7], 0, v159
	v_add_u32_e32 v159, 1, v153
	s_nop 0
	v_cndmask_b32_e64 v158, v153, v158, s[6:7]
	v_fma_f32 v153, -v159, v153, v152
	v_cmp_lt_f32_e64 s[6:7], 0, v153
	s_nop 1
	v_cndmask_b32_e64 v153, v158, v159, s[6:7]
	v_mul_f32_e32 v158, 0x37800000, v153
	v_cndmask_b32_e32 v153, v153, v158, vcc
	v_cmp_class_f32_e32 vcc, v152, v253
	s_nop 1
	v_cndmask_b32_e32 v152, v153, v152, vcc
	v_div_scale_f32 v153, s[6:7], v152, v152, 1.0
	v_rcp_f32_e32 v158, v153
	s_nop 0
	v_fma_f32 v159, -v153, v158, 1.0
	v_fmac_f32_e32 v158, v159, v158
	v_div_scale_f32 v159, vcc, 1.0, v152, 1.0
	v_mul_f32_e32 v167, v159, v158
	v_fma_f32 v168, -v153, v167, v159
	v_fmac_f32_e32 v167, v168, v158
	v_fma_f32 v153, -v153, v167, v159
	v_div_fmas_f32 v153, v153, v158, v167
	v_div_fixup_f32 v152, v153, v152, 1.0
	v_lshlrev_b32_e32 v158, 16, v34
	v_and_b32_e32 v159, 0xffff0000, v34
	v_lshlrev_b32_e32 v34, 16, v35
	v_and_b32_e32 v35, 0xffff0000, v35
	v_pk_mul_f32 v[134:135], v[134:135], v[152:153] op_sel_hi:[1,0]
	v_pk_mul_f32 v[88:89], v[88:89], v[152:153] op_sel_hi:[1,0]
	s_nop 0
	v_pk_mul_f32 v[34:35], v[88:89], v[34:35]
	v_pk_mul_f32 v[88:89], v[134:135], v[158:159]
	s_nop 0
	v_cvt_pk_bf16_f32 v88, v88, v89
	v_cvt_pk_bf16_f32 v89, v34, v35
	v_add_f32_dpp v34, v164, v164 quad_perm:[1,0,3,2] row_mask:0xf bank_mask:0xf bound_ctrl:1
	global_store_dwordx2 v[44:45], v[88:89], off
	s_nop 0
	v_add_f32_dpp v34, v34, v34 quad_perm:[2,3,0,1] row_mask:0xf bank_mask:0xf bound_ctrl:1
	s_nop 1
	v_add_f32_dpp v34, v34, v34 row_half_mirror row_mask:0xf bank_mask:0xf bound_ctrl:1
	s_nop 1
	v_add_f32_dpp v34, v34, v34 row_mirror row_mask:0xf bank_mask:0xf bound_ctrl:1
	s_nop 0
	v_readlane_b32 s9, v34, 16
	v_readlane_b32 s12, v34, 48
	v_readlane_b32 s6, v34, 0
	v_readlane_b32 s7, v34, 32
	v_mov_b32_e32 v34, s9
	v_mov_b32_e32 v35, s12
	v_pk_add_f32 v[34:35], s[6:7], v[34:35]
	s_nop 0
	v_add_f32_e32 v34, v34, v35
	v_fmamk_f32 v34, v34, 0x3b800000, v252
	v_cmp_gt_f32_e32 vcc, s55, v34
	v_mul_f32_e32 v35, 0x4f800000, v34
	s_nop 0
	v_cndmask_b32_e32 v34, v34, v35, vcc
	v_sqrt_f32_e32 v35, v34
	s_nop 0
	v_add_u32_e32 v88, -1, v35
	v_fma_f32 v89, -v88, v35, v34
	v_cmp_ge_f32_e64 s[6:7], 0, v89
	v_add_u32_e32 v89, 1, v35
	s_nop 0
	v_cndmask_b32_e64 v88, v35, v88, s[6:7]
	v_fma_f32 v35, -v89, v35, v34
	v_cmp_lt_f32_e64 s[6:7], 0, v35
	s_nop 1
	v_cndmask_b32_e64 v35, v88, v89, s[6:7]
	v_mul_f32_e32 v88, 0x37800000, v35
	v_cndmask_b32_e32 v35, v35, v88, vcc
	v_cmp_class_f32_e32 vcc, v34, v253
	s_nop 1
	v_cndmask_b32_e32 v34, v35, v34, vcc
	v_div_scale_f32 v35, s[6:7], v34, v34, 1.0
	v_rcp_f32_e32 v88, v35
	s_nop 0
	v_fma_f32 v89, -v35, v88, 1.0
	v_fmac_f32_e32 v88, v89, v88
	v_div_scale_f32 v89, vcc, 1.0, v34, 1.0
	v_mul_f32_e32 v134, v89, v88
	v_fma_f32 v135, -v35, v134, v89
	v_fmac_f32_e32 v134, v135, v88
	v_fma_f32 v35, -v35, v134, v89
	v_div_fmas_f32 v35, v35, v88, v134
	v_div_fixup_f32 v34, v35, v34, 1.0
	v_lshlrev_b32_e32 v88, 16, v30
	v_and_b32_e32 v89, 0xffff0000, v30
	v_lshlrev_b32_e32 v30, 16, v31
	v_and_b32_e32 v31, 0xffff0000, v31
	v_pk_mul_f32 v[86:87], v[86:87], v[34:35] op_sel_hi:[1,0]
	v_pk_mul_f32 v[34:35], v[84:85], v[34:35] op_sel_hi:[1,0]
	s_nop 0
	v_pk_mul_f32 v[30:31], v[34:35], v[30:31]
	v_pk_mul_f32 v[34:35], v[86:87], v[88:89]
	s_nop 0
	v_cvt_pk_bf16_f32 v34, v34, v35
	v_cvt_pk_bf16_f32 v35, v30, v31
	v_add_f32_dpp v30, v165, v165 quad_perm:[1,0,3,2] row_mask:0xf bank_mask:0xf bound_ctrl:1
	global_store_dwordx2 v[44:45], v[34:35], off offset:512
	s_nop 0
	v_add_f32_dpp v30, v30, v30 quad_perm:[2,3,0,1] row_mask:0xf bank_mask:0xf bound_ctrl:1
	s_nop 1
	v_add_f32_dpp v30, v30, v30 row_half_mirror row_mask:0xf bank_mask:0xf bound_ctrl:1
	s_nop 1
	v_add_f32_dpp v30, v30, v30 row_mirror row_mask:0xf bank_mask:0xf bound_ctrl:1
	s_nop 0
	v_readlane_b32 s9, v30, 16
	v_readlane_b32 s12, v30, 48
	v_readlane_b32 s6, v30, 0
	v_readlane_b32 s7, v30, 32
	v_mov_b32_e32 v30, s9
	v_mov_b32_e32 v31, s12
	v_pk_add_f32 v[30:31], s[6:7], v[30:31]
	s_nop 0
	v_add_f32_e32 v30, v30, v31
	v_fmamk_f32 v30, v30, 0x3b800000, v252
	v_cmp_gt_f32_e32 vcc, s55, v30
	v_mul_f32_e32 v31, 0x4f800000, v30
	s_nop 0
	v_cndmask_b32_e32 v30, v30, v31, vcc
	v_sqrt_f32_e32 v31, v30
	s_nop 0
	v_add_u32_e32 v34, -1, v31
	v_fma_f32 v35, -v34, v31, v30
	v_cmp_ge_f32_e64 s[6:7], 0, v35
	v_add_u32_e32 v35, 1, v31
	s_nop 0
	v_cndmask_b32_e64 v34, v31, v34, s[6:7]
	v_fma_f32 v31, -v35, v31, v30
	v_cmp_lt_f32_e64 s[6:7], 0, v31
	s_nop 1
	v_cndmask_b32_e64 v31, v34, v35, s[6:7]
	v_mul_f32_e32 v34, 0x37800000, v31
	v_cndmask_b32_e32 v31, v31, v34, vcc
	v_cmp_class_f32_e32 vcc, v30, v253
	s_nop 1
	v_cndmask_b32_e32 v30, v31, v30, vcc
	v_div_scale_f32 v31, s[6:7], v30, v30, 1.0
	v_rcp_f32_e32 v34, v31
	s_nop 0
	v_fma_f32 v35, -v31, v34, 1.0
	v_fmac_f32_e32 v34, v35, v34
	v_div_scale_f32 v35, vcc, 1.0, v30, 1.0
	v_mul_f32_e32 v84, v35, v34
	v_fma_f32 v85, -v31, v84, v35
	v_fmac_f32_e32 v84, v85, v34
	v_fma_f32 v31, -v31, v84, v35
	v_div_fmas_f32 v31, v31, v34, v84
	v_div_fixup_f32 v30, v31, v30, 1.0
	v_lshlrev_b32_e32 v34, 16, v26
	v_and_b32_e32 v35, 0xffff0000, v26
	v_lshlrev_b32_e32 v26, 16, v27
	v_and_b32_e32 v27, 0xffff0000, v27
	v_pk_mul_f32 v[82:83], v[82:83], v[30:31] op_sel_hi:[1,0]
	v_pk_mul_f32 v[30:31], v[80:81], v[30:31] op_sel_hi:[1,0]
	s_nop 0
	v_pk_mul_f32 v[26:27], v[30:31], v[26:27]
	v_pk_mul_f32 v[30:31], v[82:83], v[34:35]
	s_nop 0
	v_cvt_pk_bf16_f32 v30, v30, v31
	v_cvt_pk_bf16_f32 v31, v26, v27
	v_add_f32_dpp v26, v166, v166 quad_perm:[1,0,3,2] row_mask:0xf bank_mask:0xf bound_ctrl:1
	global_store_dwordx2 v[44:45], v[30:31], off offset:1024
	s_nop 0
	v_add_f32_dpp v26, v26, v26 quad_perm:[2,3,0,1] row_mask:0xf bank_mask:0xf bound_ctrl:1
	s_nop 1
	v_add_f32_dpp v26, v26, v26 row_half_mirror row_mask:0xf bank_mask:0xf bound_ctrl:1
	s_nop 1
	v_add_f32_dpp v26, v26, v26 row_mirror row_mask:0xf bank_mask:0xf bound_ctrl:1
	s_nop 0
	v_readlane_b32 s9, v26, 16
	v_readlane_b32 s12, v26, 48
	v_readlane_b32 s6, v26, 0
	v_readlane_b32 s7, v26, 32
	v_mov_b32_e32 v26, s9
	v_mov_b32_e32 v27, s12
	v_pk_add_f32 v[26:27], s[6:7], v[26:27]
	s_nop 0
	v_add_f32_e32 v26, v26, v27
	v_fmamk_f32 v26, v26, 0x3b800000, v252
	v_cmp_gt_f32_e32 vcc, s55, v26
	v_mul_f32_e32 v27, 0x4f800000, v26
	s_nop 0
	v_cndmask_b32_e32 v26, v26, v27, vcc
	v_sqrt_f32_e32 v27, v26
	s_nop 0
	v_add_u32_e32 v30, -1, v27
	v_fma_f32 v31, -v30, v27, v26
	v_cmp_ge_f32_e64 s[6:7], 0, v31
	v_add_u32_e32 v31, 1, v27
	s_nop 0
	v_cndmask_b32_e64 v30, v27, v30, s[6:7]
	v_fma_f32 v27, -v31, v27, v26
	v_cmp_lt_f32_e64 s[6:7], 0, v27
	s_nop 1
	v_cndmask_b32_e64 v27, v30, v31, s[6:7]
	v_mul_f32_e32 v30, 0x37800000, v27
	v_cndmask_b32_e32 v27, v27, v30, vcc
	v_cmp_class_f32_e32 vcc, v26, v253
	s_nop 1
	v_cndmask_b32_e32 v26, v27, v26, vcc
	v_div_scale_f32 v27, s[6:7], v26, v26, 1.0
	v_rcp_f32_e32 v30, v27
	s_nop 0
	v_fma_f32 v31, -v27, v30, 1.0
	v_fmac_f32_e32 v30, v31, v30
	v_div_scale_f32 v31, vcc, 1.0, v26, 1.0
	v_mul_f32_e32 v34, v31, v30
	v_fma_f32 v35, -v27, v34, v31
	v_fmac_f32_e32 v34, v35, v30
	v_fma_f32 v27, -v27, v34, v31
	v_div_fmas_f32 v27, v27, v30, v34
	v_div_fixup_f32 v26, v27, v26, 1.0
	v_lshlrev_b32_e32 v30, 16, v22
	v_and_b32_e32 v31, 0xffff0000, v22
	v_lshlrev_b32_e32 v22, 16, v23
	v_and_b32_e32 v23, 0xffff0000, v23
	v_pk_mul_f32 v[34:35], v[78:79], v[26:27] op_sel_hi:[1,0]
	v_pk_mul_f32 v[26:27], v[76:77], v[26:27] op_sel_hi:[1,0]
	s_nop 0
	v_pk_mul_f32 v[22:23], v[26:27], v[22:23]
	v_pk_mul_f32 v[26:27], v[34:35], v[30:31]
	s_nop 0
	v_cvt_pk_bf16_f32 v26, v26, v27
	v_cvt_pk_bf16_f32 v27, v22, v23
	v_add_f32_dpp v22, v147, v147 quad_perm:[1,0,3,2] row_mask:0xf bank_mask:0xf bound_ctrl:1
	global_store_dwordx2 v[44:45], v[26:27], off offset:1536
	s_nop 0
	v_add_f32_dpp v22, v22, v22 quad_perm:[2,3,0,1] row_mask:0xf bank_mask:0xf bound_ctrl:1
	s_nop 1
	v_add_f32_dpp v22, v22, v22 row_half_mirror row_mask:0xf bank_mask:0xf bound_ctrl:1
	s_nop 1
	v_add_f32_dpp v22, v22, v22 row_mirror row_mask:0xf bank_mask:0xf bound_ctrl:1
	s_nop 0
	v_readlane_b32 s9, v22, 16
	v_readlane_b32 s12, v22, 48
	v_readlane_b32 s6, v22, 0
	v_readlane_b32 s7, v22, 32
	v_mov_b32_e32 v22, s9
	v_mov_b32_e32 v23, s12
	v_pk_add_f32 v[22:23], s[6:7], v[22:23]
	s_nop 0
	v_add_f32_e32 v22, v22, v23
	v_fmamk_f32 v22, v22, 0x3b800000, v252
	v_cmp_gt_f32_e32 vcc, s55, v22
	v_mul_f32_e32 v23, 0x4f800000, v22
	s_nop 0
	v_cndmask_b32_e32 v22, v22, v23, vcc
	v_sqrt_f32_e32 v23, v22
	s_nop 0
	v_add_u32_e32 v26, -1, v23
	v_fma_f32 v27, -v26, v23, v22
	v_cmp_ge_f32_e64 s[6:7], 0, v27
	v_add_u32_e32 v27, 1, v23
	s_nop 0
	v_cndmask_b32_e64 v26, v23, v26, s[6:7]
	v_fma_f32 v23, -v27, v23, v22
	v_cmp_lt_f32_e64 s[6:7], 0, v23
	s_nop 1
	v_cndmask_b32_e64 v23, v26, v27, s[6:7]
	v_mul_f32_e32 v26, 0x37800000, v23
	v_cndmask_b32_e32 v23, v23, v26, vcc
	v_cmp_class_f32_e32 vcc, v22, v253
	s_nop 1
	v_cndmask_b32_e32 v22, v23, v22, vcc
	v_div_scale_f32 v23, s[6:7], v22, v22, 1.0
	v_rcp_f32_e32 v26, v23
	s_nop 0
	v_fma_f32 v27, -v23, v26, 1.0
	v_fmac_f32_e32 v26, v27, v26
	v_div_scale_f32 v27, vcc, 1.0, v22, 1.0
	v_mul_f32_e32 v30, v27, v26
	v_fma_f32 v31, -v23, v30, v27
	v_fmac_f32_e32 v30, v31, v26
	v_fma_f32 v23, -v23, v30, v27
	v_div_fmas_f32 v23, v23, v26, v30
	v_div_fixup_f32 v22, v23, v22, 1.0
	v_lshlrev_b32_e32 v26, 16, v18
	v_and_b32_e32 v27, 0xffff0000, v18
	v_lshlrev_b32_e32 v18, 16, v19
	v_and_b32_e32 v19, 0xffff0000, v19
	v_pk_mul_f32 v[30:31], v[74:75], v[22:23] op_sel_hi:[1,0]
	v_pk_mul_f32 v[22:23], v[72:73], v[22:23] op_sel_hi:[1,0]
	s_nop 0
	v_pk_mul_f32 v[18:19], v[22:23], v[18:19]
	v_pk_mul_f32 v[22:23], v[30:31], v[26:27]
	s_nop 0
	v_cvt_pk_bf16_f32 v22, v22, v23
	v_cvt_pk_bf16_f32 v23, v18, v19
	v_add_f32_dpp v18, v146, v146 quad_perm:[1,0,3,2] row_mask:0xf bank_mask:0xf bound_ctrl:1
	global_store_dwordx2 v[44:45], v[22:23], off offset:2048
	s_nop 0
	v_add_f32_dpp v18, v18, v18 quad_perm:[2,3,0,1] row_mask:0xf bank_mask:0xf bound_ctrl:1
	s_nop 1
	v_add_f32_dpp v18, v18, v18 row_half_mirror row_mask:0xf bank_mask:0xf bound_ctrl:1
	s_nop 1
	v_add_f32_dpp v18, v18, v18 row_mirror row_mask:0xf bank_mask:0xf bound_ctrl:1
	s_nop 0
	v_readlane_b32 s9, v18, 16
	v_readlane_b32 s12, v18, 48
	v_readlane_b32 s6, v18, 0
	v_readlane_b32 s7, v18, 32
	v_mov_b32_e32 v18, s9
	v_mov_b32_e32 v19, s12
	v_pk_add_f32 v[18:19], s[6:7], v[18:19]
	s_nop 0
	v_add_f32_e32 v18, v18, v19
	v_fmamk_f32 v18, v18, 0x3b800000, v252
	v_cmp_gt_f32_e32 vcc, s55, v18
	v_mul_f32_e32 v19, 0x4f800000, v18
	s_nop 0
	v_cndmask_b32_e32 v18, v18, v19, vcc
	v_sqrt_f32_e32 v19, v18
	s_nop 0
	v_add_u32_e32 v22, -1, v19
	v_fma_f32 v23, -v22, v19, v18
	v_cmp_ge_f32_e64 s[6:7], 0, v23
	v_add_u32_e32 v23, 1, v19
	s_nop 0
	v_cndmask_b32_e64 v22, v19, v22, s[6:7]
	v_fma_f32 v19, -v23, v19, v18
	v_cmp_lt_f32_e64 s[6:7], 0, v19
	s_nop 1
	v_cndmask_b32_e64 v19, v22, v23, s[6:7]
	v_mul_f32_e32 v22, 0x37800000, v19
	v_cndmask_b32_e32 v19, v19, v22, vcc
	v_cmp_class_f32_e32 vcc, v18, v253
	s_nop 1
	v_cndmask_b32_e32 v18, v19, v18, vcc
	v_div_scale_f32 v19, s[6:7], v18, v18, 1.0
	v_rcp_f32_e32 v22, v19
	s_nop 0
	v_fma_f32 v23, -v19, v22, 1.0
; template <bool HG>
; __device__ __forceinline__ void readout_phase2(const Args& a, Frame& F, const float* gain, int nrows) {
;     ...
;     RO_FINISH(f1, b1, g1, nw + 2048);     RO_LOAD(f1, b1, g1, nw + 4 * 2048);
;     RO_FINISH(f2, b2, g2, nw + 2 * 2048); RO_LOAD(f2, b2, g2, nw + 5 * 2048);
	v_fmac_f32_e32 v22, v23, v22
	v_div_scale_f32 v23, vcc, 1.0, v18, 1.0
	v_mul_f32_e32 v26, v23, v22
	v_fma_f32 v27, -v19, v26, v23
	v_fmac_f32_e32 v26, v27, v22
	v_fma_f32 v19, -v19, v26, v23
	v_div_fmas_f32 v19, v19, v22, v26
	v_div_fixup_f32 v18, v19, v18, 1.0
	v_lshlrev_b32_e32 v22, 16, v14
	v_and_b32_e32 v23, 0xffff0000, v14
	v_lshlrev_b32_e32 v14, 16, v15
	v_and_b32_e32 v15, 0xffff0000, v15
	v_pk_mul_f32 v[26:27], v[70:71], v[18:19] op_sel_hi:[1,0]
	v_pk_mul_f32 v[18:19], v[68:69], v[18:19] op_sel_hi:[1,0]
	s_nop 0
	v_pk_mul_f32 v[14:15], v[18:19], v[14:15]
	v_pk_mul_f32 v[18:19], v[26:27], v[22:23]
	s_nop 0
	v_cvt_pk_bf16_f32 v18, v18, v19
	v_cvt_pk_bf16_f32 v19, v14, v15
	v_add_f32_dpp v14, v141, v141 quad_perm:[1,0,3,2] row_mask:0xf bank_mask:0xf bound_ctrl:1
	global_store_dwordx2 v[44:45], v[18:19], off offset:2560
	s_nop 0
	v_add_f32_dpp v14, v14, v14 quad_perm:[2,3,0,1] row_mask:0xf bank_mask:0xf bound_ctrl:1
	s_nop 1
	v_add_f32_dpp v14, v14, v14 row_half_mirror row_mask:0xf bank_mask:0xf bound_ctrl:1
	s_nop 1
	v_add_f32_dpp v14, v14, v14 row_mirror row_mask:0xf bank_mask:0xf bound_ctrl:1
	s_nop 0
	v_readlane_b32 s9, v14, 16
	v_readlane_b32 s12, v14, 48
	v_readlane_b32 s6, v14, 0
	v_readlane_b32 s7, v14, 32
	v_mov_b32_e32 v14, s9
	v_mov_b32_e32 v15, s12
	v_pk_add_f32 v[14:15], s[6:7], v[14:15]
	s_nop 0
	v_add_f32_e32 v14, v14, v15
	v_fmamk_f32 v14, v14, 0x3b800000, v252
	v_cmp_gt_f32_e32 vcc, s55, v14
	v_mul_f32_e32 v15, 0x4f800000, v14
	s_nop 0
	v_cndmask_b32_e32 v14, v14, v15, vcc
	v_sqrt_f32_e32 v15, v14
	s_nop 0
	v_add_u32_e32 v18, -1, v15
	v_fma_f32 v19, -v18, v15, v14
	v_cmp_ge_f32_e64 s[6:7], 0, v19
	v_add_u32_e32 v19, 1, v15
	s_nop 0
	v_cndmask_b32_e64 v18, v15, v18, s[6:7]
	v_fma_f32 v15, -v19, v15, v14
	v_cmp_lt_f32_e64 s[6:7], 0, v15
	s_nop 1
	v_cndmask_b32_e64 v15, v18, v19, s[6:7]
	v_mul_f32_e32 v18, 0x37800000, v15
	v_cndmask_b32_e32 v15, v15, v18, vcc
	v_cmp_class_f32_e32 vcc, v14, v253
	s_nop 1
	v_cndmask_b32_e32 v14, v15, v14, vcc
	v_div_scale_f32 v15, s[6:7], v14, v14, 1.0
	v_rcp_f32_e32 v18, v15
	s_nop 0
	v_fma_f32 v19, -v15, v18, 1.0
	v_fmac_f32_e32 v18, v19, v18
	v_div_scale_f32 v19, vcc, 1.0, v14, 1.0
	v_mul_f32_e32 v22, v19, v18
	v_fma_f32 v23, -v15, v22, v19
	v_fmac_f32_e32 v22, v23, v18
	v_fma_f32 v15, -v15, v22, v19
	v_div_fmas_f32 v15, v15, v18, v22
	v_div_fixup_f32 v14, v15, v14, 1.0
	v_lshlrev_b32_e32 v18, 16, v12
	v_and_b32_e32 v19, 0xffff0000, v12
	v_lshlrev_b32_e32 v12, 16, v13
	v_and_b32_e32 v13, 0xffff0000, v13
	v_pk_mul_f32 v[22:23], v[62:63], v[14:15] op_sel_hi:[1,0]
	v_pk_mul_f32 v[14:15], v[56:57], v[14:15] op_sel_hi:[1,0]
	s_nop 0
	v_pk_mul_f32 v[12:13], v[14:15], v[12:13]
	v_pk_mul_f32 v[14:15], v[22:23], v[18:19]
	s_nop 0
	v_cvt_pk_bf16_f32 v14, v14, v15
	v_cvt_pk_bf16_f32 v15, v12, v13
	v_add_f32_dpp v12, v140, v140 quad_perm:[1,0,3,2] row_mask:0xf bank_mask:0xf bound_ctrl:1
	global_store_dwordx2 v[44:45], v[14:15], off offset:3072
	s_nop 0
	v_add_f32_dpp v12, v12, v12 quad_perm:[2,3,0,1] row_mask:0xf bank_mask:0xf bound_ctrl:1
	s_nop 1
	v_add_f32_dpp v12, v12, v12 row_half_mirror row_mask:0xf bank_mask:0xf bound_ctrl:1
	s_nop 1
	v_add_f32_dpp v12, v12, v12 row_mirror row_mask:0xf bank_mask:0xf bound_ctrl:1
	s_nop 0
	v_readlane_b32 s9, v12, 16
	v_readlane_b32 s12, v12, 48
	v_readlane_b32 s6, v12, 0
	v_readlane_b32 s7, v12, 32
	v_mov_b32_e32 v12, s9
	v_mov_b32_e32 v13, s12
	v_pk_add_f32 v[12:13], s[6:7], v[12:13]
	s_add_u32 s12, s10, 0x2800000
	v_add_f32_e32 v12, v12, v13
	v_fmamk_f32 v12, v12, 0x3b800000, v252
	v_cmp_gt_f32_e32 vcc, s55, v12
	v_mul_f32_e32 v13, 0x4f800000, v12
	s_addc_u32 s13, s11, 0
	v_cndmask_b32_e32 v12, v12, v13, vcc
	v_sqrt_f32_e32 v13, v12
	s_add_u32 s40, s10, 0x3000000
	s_addc_u32 s41, s11, 0
	s_add_i32 s82, s8, 0x4000
	v_add_u32_e32 v14, -1, v13
	v_fma_f32 v15, -v14, v13, v12
	v_cmp_ge_f32_e64 s[6:7], 0, v15
	v_add_u32_e32 v15, 1, v13
	s_nop 0
	v_cndmask_b32_e64 v14, v13, v14, s[6:7]
	v_fma_f32 v13, -v15, v13, v12
	v_cmp_lt_f32_e64 s[6:7], 0, v13
	s_nop 1
	v_cndmask_b32_e64 v13, v14, v15, s[6:7]
	v_mul_f32_e32 v14, 0x37800000, v13
	v_cndmask_b32_e32 v13, v13, v14, vcc
	v_cmp_class_f32_e32 vcc, v12, v253
	s_nop 1
	v_cndmask_b32_e32 v12, v13, v12, vcc
	v_div_scale_f32 v13, s[6:7], v12, v12, 1.0
	v_rcp_f32_e32 v14, v13
	s_nop 0
	v_fma_f32 v15, -v13, v14, 1.0
	v_fmac_f32_e32 v14, v15, v14
	v_div_scale_f32 v15, vcc, 1.0, v12, 1.0
	v_mul_f32_e32 v18, v15, v14
	v_fma_f32 v19, -v13, v18, v15
	v_fmac_f32_e32 v18, v19, v14
	v_fma_f32 v13, -v13, v18, v15
	v_div_fmas_f32 v13, v13, v14, v18
	v_div_fixup_f32 v12, v13, v12, 1.0
	s_waitcnt vmcnt(62)
; template <bool HG>
; __device__ __forceinline__ void readout_phase2(const Args& a, Frame& F, const float* gain, int nrows) {
;     ...
;     RO_FINISH(f2, b2, g2, nw + 2 * 2048); RO_LOAD(f2, b2, g2, nw + 5 * 2048);
;     RO_FINISH(f0, b0, g0, nw + 3 * 2048); RO_LOAD(f0, b0, g0, nw + 6 * 2048);
	v_lshlrev_b32_e32 v14, 16, v10
	v_and_b32_e32 v15, 0xffff0000, v10
	v_lshlrev_b32_e32 v10, 16, v11
	v_and_b32_e32 v11, 0xffff0000, v11
	v_pk_mul_f32 v[18:19], v[50:51], v[12:13] op_sel_hi:[1,0]
	v_pk_mul_f32 v[12:13], v[38:39], v[12:13] op_sel_hi:[1,0]
	s_nop 0
	v_pk_mul_f32 v[10:11], v[12:13], v[10:11]
	v_pk_mul_f32 v[12:13], v[18:19], v[14:15]
	v_lshl_add_u64 v[14:15], v[8:9], 0, s[12:13]
	v_cvt_pk_bf16_f32 v12, v12, v13
	v_cvt_pk_bf16_f32 v13, v10, v11
	global_store_dwordx2 v[44:45], v[12:13], off offset:3584
	v_lshl_add_u64 v[10:11], v[4:5], 0, s[12:13]
	v_lshl_add_u64 v[12:13], v[6:7], 0, s[12:13]
	v_lshl_add_u64 v[10:11], v[10:11], 0, v[0:1]
	v_lshl_add_u64 v[12:13], v[12:13], 0, v[0:1]
	v_lshl_add_u64 v[14:15], v[14:15], 0, v[0:1]
	global_load_dwordx2 v[158:159], v[10:11], off
	global_load_dwordx2 v[152:153], v[12:13], off
	global_load_dwordx2 v[62:63], v[14:15], off
	global_load_dwordx2 v[146:147], v[10:11], off offset:512
	global_load_dwordx2 v[140:141], v[12:13], off offset:512
	global_load_dwordx2 v[56:57], v[14:15], off offset:512
	global_load_dwordx2 v[134:135], v[10:11], off offset:1024
	global_load_dwordx2 v[88:89], v[12:13], off offset:1024
	global_load_dwordx2 v[50:51], v[14:15], off offset:1024
	global_load_dwordx2 v[84:85], v[10:11], off offset:1536
	global_load_dwordx2 v[86:87], v[12:13], off offset:1536
	global_load_dwordx2 v[44:45], v[14:15], off offset:1536
	global_load_dwordx2 v[82:83], v[10:11], off offset:2048
	global_load_dwordx2 v[80:81], v[12:13], off offset:2048
	global_load_dwordx2 v[38:39], v[14:15], off offset:2048
	global_load_dwordx2 v[78:79], v[10:11], off offset:2560
	global_load_dwordx2 v[76:77], v[12:13], off offset:2560
	global_load_dwordx2 v[34:35], v[14:15], off offset:2560
	global_load_dwordx2 v[74:75], v[10:11], off offset:3072
	global_load_dwordx2 v[72:73], v[12:13], off offset:3072
	global_load_dwordx2 v[30:31], v[14:15], off offset:3072
	global_load_dwordx2 v[68:69], v[10:11], off offset:3584
	global_load_dwordx2 v[70:71], v[12:13], off offset:3584
	global_load_dwordx2 v[26:27], v[14:15], off offset:3584
	v_lshlrev_b32_e32 v10, 16, v160
	v_and_b32_e32 v11, 0xffff0000, v160
	s_waitcnt vmcnt(62)
	v_lshlrev_b32_e32 v12, 16, v154
	v_and_b32_e32 v13, 0xffff0000, v154
	v_pk_add_f32 v[164:165], v[10:11], v[12:13]
	v_lshlrev_b32_e32 v10, 16, v161
	v_and_b32_e32 v11, 0xffff0000, v161
	v_lshlrev_b32_e32 v12, 16, v155
	v_and_b32_e32 v13, 0xffff0000, v155
	v_pk_add_f32 v[160:161], v[10:11], v[12:13]
	v_mov_b32_e32 v12, v165
	v_mov_b32_e32 v13, v161
	v_mov_b32_e32 v10, v164
	v_mov_b32_e32 v11, v160
	v_pk_mul_f32 v[12:13], v[12:13], v[12:13]
	v_lshlrev_b32_e32 v14, 16, v95
	v_pk_fma_f32 v[10:11], v[10:11], v[10:11], v[12:13]
	v_lshlrev_b32_e32 v12, 16, v142
	v_add_f32_e32 v167, v10, v11
	v_lshlrev_b32_e32 v10, 16, v148
	v_and_b32_e32 v11, 0xffff0000, v148
	v_and_b32_e32 v13, 0xffff0000, v142
	v_pk_add_f32 v[154:155], v[10:11], v[12:13]
	v_lshlrev_b32_e32 v10, 16, v149
	v_and_b32_e32 v11, 0xffff0000, v149
	v_lshlrev_b32_e32 v12, 16, v143
	v_and_b32_e32 v13, 0xffff0000, v143
	v_pk_add_f32 v[148:149], v[10:11], v[12:13]
	v_mov_b32_e32 v12, v155
	v_mov_b32_e32 v13, v149
	v_mov_b32_e32 v10, v154
	v_mov_b32_e32 v11, v148
	v_pk_mul_f32 v[12:13], v[12:13], v[12:13]
	v_and_b32_e32 v15, 0xffff0000, v95
	v_pk_fma_f32 v[10:11], v[10:11], v[10:11], v[12:13]
	v_lshlrev_b32_e32 v12, 16, v130
	v_add_f32_e32 v168, v10, v11
	v_lshlrev_b32_e32 v10, 16, v136
	v_and_b32_e32 v11, 0xffff0000, v136
	v_and_b32_e32 v13, 0xffff0000, v130
	v_pk_add_f32 v[142:143], v[10:11], v[12:13]
	v_lshlrev_b32_e32 v10, 16, v137
	v_and_b32_e32 v11, 0xffff0000, v137
	v_lshlrev_b32_e32 v12, 16, v131
	v_and_b32_e32 v13, 0xffff0000, v131
	v_pk_add_f32 v[136:137], v[10:11], v[12:13]
	v_mov_b32_e32 v12, v143
	v_mov_b32_e32 v13, v137
	v_mov_b32_e32 v10, v142
	v_mov_b32_e32 v11, v136
	v_pk_mul_f32 v[12:13], v[12:13], v[12:13]
	s_nop 0
	v_pk_fma_f32 v[10:11], v[10:11], v[10:11], v[12:13]
	v_lshlrev_b32_e32 v12, 16, v126
	v_add_f32_e32 v169, v10, v11
	v_lshlrev_b32_e32 v10, 16, v122
	v_and_b32_e32 v11, 0xffff0000, v122
	v_and_b32_e32 v13, 0xffff0000, v126
	v_pk_add_f32 v[130:131], v[10:11], v[12:13]
	v_lshlrev_b32_e32 v10, 16, v123
	v_and_b32_e32 v11, 0xffff0000, v123
	v_lshlrev_b32_e32 v12, 16, v127
	v_and_b32_e32 v13, 0xffff0000, v127
	v_pk_add_f32 v[126:127], v[10:11], v[12:13]
	v_mov_b32_e32 v12, v131
	v_mov_b32_e32 v13, v127
	v_mov_b32_e32 v10, v130
	v_mov_b32_e32 v11, v126
	v_pk_mul_f32 v[12:13], v[12:13], v[12:13]
	s_nop 0
	v_pk_fma_f32 v[10:11], v[10:11], v[10:11], v[12:13]
	v_lshlrev_b32_e32 v12, 16, v114
	v_add_f32_e32 v170, v10, v11
	v_lshlrev_b32_e32 v10, 16, v118
	v_and_b32_e32 v11, 0xffff0000, v118
	v_and_b32_e32 v13, 0xffff0000, v114
	v_pk_add_f32 v[122:123], v[10:11], v[12:13]
	v_lshlrev_b32_e32 v10, 16, v119
	v_and_b32_e32 v11, 0xffff0000, v119
	v_lshlrev_b32_e32 v12, 16, v115
	v_and_b32_e32 v13, 0xffff0000, v115
	v_pk_add_f32 v[118:119], v[10:11], v[12:13]
	v_mov_b32_e32 v12, v123
	v_mov_b32_e32 v13, v119
	v_mov_b32_e32 v10, v122
	v_mov_b32_e32 v11, v118
	v_pk_mul_f32 v[12:13], v[12:13], v[12:13]
	s_nop 0
	v_pk_fma_f32 v[10:11], v[10:11], v[10:11], v[12:13]
	v_lshlrev_b32_e32 v12, 16, v106
	v_add_f32_e32 v166, v10, v11
	v_lshlrev_b32_e32 v10, 16, v110
	v_and_b32_e32 v11, 0xffff0000, v110
	v_and_b32_e32 v13, 0xffff0000, v106
	v_pk_add_f32 v[114:115], v[10:11], v[12:13]
	v_lshlrev_b32_e32 v10, 16, v111
	v_and_b32_e32 v11, 0xffff0000, v111
	v_lshlrev_b32_e32 v12, 16, v107
	v_and_b32_e32 v13, 0xffff0000, v107
	v_pk_add_f32 v[106:107], v[10:11], v[12:13]
	v_mov_b32_e32 v12, v115
	v_mov_b32_e32 v13, v107
	v_mov_b32_e32 v10, v114
	v_mov_b32_e32 v11, v106
	v_pk_mul_f32 v[12:13], v[12:13], v[12:13]
	s_nop 0
	v_pk_fma_f32 v[10:11], v[10:11], v[10:11], v[12:13]
	v_lshlrev_b32_e32 v12, 16, v98
	v_add_f32_e32 v110, v10, v11
	v_lshlrev_b32_e32 v10, 16, v102
	v_and_b32_e32 v11, 0xffff0000, v102
	v_and_b32_e32 v13, 0xffff0000, v98
	v_pk_add_f32 v[18:19], v[10:11], v[12:13]
	v_lshlrev_b32_e32 v10, 16, v103
	v_and_b32_e32 v11, 0xffff0000, v103
	v_lshlrev_b32_e32 v12, 16, v99
	v_and_b32_e32 v13, 0xffff0000, v99
	v_pk_add_f32 v[22:23], v[10:11], v[12:13]
	v_mov_b32_e32 v12, v19
	v_mov_b32_e32 v13, v23
	v_mov_b32_e32 v10, v18
	v_mov_b32_e32 v11, v22
	v_pk_mul_f32 v[12:13], v[12:13], v[12:13]
	s_nop 0
	v_pk_fma_f32 v[10:11], v[10:11], v[10:11], v[12:13]
	v_lshlrev_b32_e32 v12, 16, v94
	v_add_f32_e32 v98, v10, v11
	v_lshlrev_b32_e32 v10, 16, v90
	v_and_b32_e32 v11, 0xffff0000, v90
	v_and_b32_e32 v13, 0xffff0000, v94
	v_pk_add_f32 v[10:11], v[10:11], v[12:13]
	v_lshlrev_b32_e32 v12, 16, v91
	v_and_b32_e32 v13, 0xffff0000, v91
	v_pk_add_f32 v[12:13], v[12:13], v[14:15]
	v_mov_b32_e32 v90, v11
	v_mov_b32_e32 v91, v13
	v_mov_b32_e32 v14, v10
	v_mov_b32_e32 v15, v12
	v_pk_mul_f32 v[90:91], v[90:91], v[90:91]
	s_nop 0
	v_pk_fma_f32 v[14:15], v[14:15], v[14:15], v[90:91]
	v_add_f32_dpp v91, v167, v167 quad_perm:[1,0,3,2] row_mask:0xf bank_mask:0xf bound_ctrl:1
	v_add_f32_e32 v90, v14, v15
	v_lshl_add_u64 v[14:15], v[2:3], 0, s[14:15]
	v_add_f32_dpp v91, v91, v91 quad_perm:[2,3,0,1] row_mask:0xf bank_mask:0xf bound_ctrl:1
	v_lshl_add_u64 v[14:15], v[14:15], 0, v[0:1]
	s_nop 0
	v_add_f32_dpp v91, v91, v91 row_half_mirror row_mask:0xf bank_mask:0xf bound_ctrl:1
	s_nop 1
	v_add_f32_dpp v91, v91, v91 row_mirror row_mask:0xf bank_mask:0xf bound_ctrl:1
	s_nop 0
	v_readlane_b32 s9, v91, 16
	v_readlane_b32 s14, v91, 48
	v_readlane_b32 s6, v91, 0
	v_readlane_b32 s7, v91, 32
	v_mov_b32_e32 v94, s9
	v_mov_b32_e32 v95, s14
	v_pk_add_f32 v[94:95], s[6:7], v[94:95]
	s_nop 0
	v_add_f32_e32 v91, v94, v95
	v_fmamk_f32 v91, v91, 0x3b800000, v252
	v_cmp_gt_f32_e32 vcc, s55, v91
	v_mul_f32_e32 v94, 0x4f800000, v91
	s_nop 0
	v_cndmask_b32_e32 v91, v91, v94, vcc
	v_sqrt_f32_e32 v94, v91
	s_nop 0
	v_add_u32_e32 v95, -1, v94
	v_fma_f32 v99, -v95, v94, v91
	v_cmp_ge_f32_e64 s[6:7], 0, v99
	v_add_u32_e32 v99, 1, v94
	s_nop 0
	v_cndmask_b32_e64 v95, v94, v95, s[6:7]
	v_fma_f32 v94, -v99, v94, v91
	v_cmp_lt_f32_e64 s[6:7], 0, v94
	s_nop 1
	v_cndmask_b32_e64 v94, v95, v99, s[6:7]
	v_mul_f32_e32 v95, 0x37800000, v94
	v_cndmask_b32_e32 v94, v94, v95, vcc
	v_cmp_class_f32_e32 vcc, v91, v253
	s_nop 1
	v_cndmask_b32_e32 v91, v94, v91, vcc
	v_div_scale_f32 v94, s[6:7], v91, v91, 1.0
	v_rcp_f32_e32 v95, v94
	s_nop 0
	v_fma_f32 v99, -v94, v95, 1.0
	v_fmac_f32_e32 v95, v99, v95
	v_div_scale_f32 v99, vcc, 1.0, v91, 1.0
	v_mul_f32_e32 v102, v99, v95
	v_fma_f32 v103, -v94, v102, v99
	v_fmac_f32_e32 v102, v103, v95
	v_fma_f32 v94, -v94, v102, v99
	v_div_fmas_f32 v94, v94, v95, v102
	v_div_fixup_f32 v94, v94, v91, 1.0
	v_lshlrev_b32_e32 v102, 16, v64
	v_and_b32_e32 v103, 0xffff0000, v64
	v_lshlrev_b32_e32 v64, 16, v65
	v_and_b32_e32 v65, 0xffff0000, v65
	v_pk_mul_f32 v[164:165], v[164:165], v[94:95] op_sel_hi:[1,0]
	v_pk_mul_f32 v[94:95], v[160:161], v[94:95] op_sel_hi:[1,0]
	s_nop 0
	v_pk_mul_f32 v[64:65], v[94:95], v[64:65]
	v_pk_mul_f32 v[94:95], v[164:165], v[102:103]
	s_nop 0
	v_cvt_pk_bf16_f32 v94, v94, v95
	v_cvt_pk_bf16_f32 v95, v64, v65
	v_add_f32_dpp v64, v168, v168 quad_perm:[1,0,3,2] row_mask:0xf bank_mask:0xf bound_ctrl:1
	global_store_dwordx2 v[14:15], v[94:95], off
	s_nop 0
	v_add_f32_dpp v64, v64, v64 quad_perm:[2,3,0,1] row_mask:0xf bank_mask:0xf bound_ctrl:1
	s_nop 1
	v_add_f32_dpp v64, v64, v64 row_half_mirror row_mask:0xf bank_mask:0xf bound_ctrl:1
	s_nop 1
	v_add_f32_dpp v64, v64, v64 row_mirror row_mask:0xf bank_mask:0xf bound_ctrl:1
	s_nop 0
	v_readlane_b32 s9, v64, 16
	v_readlane_b32 s14, v64, 48
	v_readlane_b32 s6, v64, 0
	v_readlane_b32 s7, v64, 32
	v_mov_b32_e32 v64, s9
	v_mov_b32_e32 v65, s14
	v_pk_add_f32 v[64:65], s[6:7], v[64:65]
	s_nop 0
	v_add_f32_e32 v64, v64, v65
	v_fmamk_f32 v64, v64, 0x3b800000, v252
	v_cmp_gt_f32_e32 vcc, s55, v64
	v_mul_f32_e32 v65, 0x4f800000, v64
	s_nop 0
	v_cndmask_b32_e32 v64, v64, v65, vcc
	v_sqrt_f32_e32 v65, v64
	s_nop 0
	v_add_u32_e32 v91, -1, v65
	v_fma_f32 v94, -v91, v65, v64
	v_cmp_ge_f32_e64 s[6:7], 0, v94
	v_add_u32_e32 v94, 1, v65
	s_nop 0
	v_cndmask_b32_e64 v91, v65, v91, s[6:7]
	v_fma_f32 v65, -v94, v65, v64
	v_cmp_lt_f32_e64 s[6:7], 0, v65
	s_nop 1
	v_cndmask_b32_e64 v65, v91, v94, s[6:7]
	v_mul_f32_e32 v91, 0x37800000, v65
	v_cndmask_b32_e32 v65, v65, v91, vcc
	v_cmp_class_f32_e32 vcc, v64, v253
	s_nop 1
	v_cndmask_b32_e32 v64, v65, v64, vcc
	v_div_scale_f32 v65, s[6:7], v64, v64, 1.0
	v_rcp_f32_e32 v91, v65
	s_nop 0
	v_fma_f32 v94, -v65, v91, 1.0
	v_fmac_f32_e32 v91, v94, v91
	v_div_scale_f32 v94, vcc, 1.0, v64, 1.0
	v_mul_f32_e32 v95, v94, v91
	v_fma_f32 v99, -v65, v95, v94
	v_fmac_f32_e32 v95, v99, v91
	v_fma_f32 v65, -v65, v95, v94
	v_div_fmas_f32 v65, v65, v91, v95
	v_div_fixup_f32 v64, v65, v64, 1.0
	v_lshlrev_b32_e32 v94, 16, v58
	v_and_b32_e32 v95, 0xffff0000, v58
	v_lshlrev_b32_e32 v58, 16, v59
	v_and_b32_e32 v59, 0xffff0000, v59
	v_pk_mul_f32 v[102:103], v[154:155], v[64:65] op_sel_hi:[1,0]
	v_pk_mul_f32 v[64:65], v[148:149], v[64:65] op_sel_hi:[1,0]
	s_nop 0
	v_pk_mul_f32 v[58:59], v[64:65], v[58:59]
	v_pk_mul_f32 v[64:65], v[102:103], v[94:95]
	s_nop 0
	v_cvt_pk_bf16_f32 v64, v64, v65
	v_cvt_pk_bf16_f32 v65, v58, v59
	v_add_f32_dpp v58, v169, v169 quad_perm:[1,0,3,2] row_mask:0xf bank_mask:0xf bound_ctrl:1
	global_store_dwordx2 v[14:15], v[64:65], off offset:512
	s_nop 0
	v_add_f32_dpp v58, v58, v58 quad_perm:[2,3,0,1] row_mask:0xf bank_mask:0xf bound_ctrl:1
	s_nop 1
	v_add_f32_dpp v58, v58, v58 row_half_mirror row_mask:0xf bank_mask:0xf bound_ctrl:1
	s_nop 1
	v_add_f32_dpp v58, v58, v58 row_mirror row_mask:0xf bank_mask:0xf bound_ctrl:1
	s_nop 0
	v_readlane_b32 s9, v58, 16
	v_readlane_b32 s14, v58, 48
	v_readlane_b32 s6, v58, 0
	v_readlane_b32 s7, v58, 32
	v_mov_b32_e32 v58, s9
	v_mov_b32_e32 v59, s14
	v_pk_add_f32 v[58:59], s[6:7], v[58:59]
	s_nop 0
	v_add_f32_e32 v58, v58, v59
	v_fmamk_f32 v58, v58, 0x3b800000, v252
	v_cmp_gt_f32_e32 vcc, s55, v58
	v_mul_f32_e32 v59, 0x4f800000, v58
	s_nop 0
	v_cndmask_b32_e32 v58, v58, v59, vcc
	v_sqrt_f32_e32 v59, v58
	s_nop 0
	v_add_u32_e32 v64, -1, v59
	v_fma_f32 v65, -v64, v59, v58
	v_cmp_ge_f32_e64 s[6:7], 0, v65
	v_add_u32_e32 v65, 1, v59
	s_nop 0
	v_cndmask_b32_e64 v64, v59, v64, s[6:7]
	v_fma_f32 v59, -v65, v59, v58
	v_cmp_lt_f32_e64 s[6:7], 0, v59
	s_nop 1
	v_cndmask_b32_e64 v59, v64, v65, s[6:7]
	v_mul_f32_e32 v64, 0x37800000, v59
	v_cndmask_b32_e32 v59, v59, v64, vcc
	v_cmp_class_f32_e32 vcc, v58, v253
	s_nop 1
	v_cndmask_b32_e32 v58, v59, v58, vcc
	v_div_scale_f32 v59, s[6:7], v58, v58, 1.0
	v_rcp_f32_e32 v64, v59
	s_nop 0
	v_fma_f32 v65, -v59, v64, 1.0
	v_fmac_f32_e32 v64, v65, v64
	v_div_scale_f32 v65, vcc, 1.0, v58, 1.0
	v_mul_f32_e32 v91, v65, v64
	v_fma_f32 v94, -v59, v91, v65
	v_fmac_f32_e32 v91, v94, v64
	v_fma_f32 v59, -v59, v91, v65
	v_div_fmas_f32 v59, v59, v64, v91
	v_div_fixup_f32 v58, v59, v58, 1.0
	v_lshlrev_b32_e32 v64, 16, v52
	v_and_b32_e32 v65, 0xffff0000, v52
	v_lshlrev_b32_e32 v52, 16, v53
	v_and_b32_e32 v53, 0xffff0000, v53
	v_pk_mul_f32 v[94:95], v[142:143], v[58:59] op_sel_hi:[1,0]
	v_pk_mul_f32 v[58:59], v[136:137], v[58:59] op_sel_hi:[1,0]
	s_nop 0
	v_pk_mul_f32 v[52:53], v[58:59], v[52:53]
	v_pk_mul_f32 v[58:59], v[94:95], v[64:65]
	s_nop 0
	v_cvt_pk_bf16_f32 v58, v58, v59
	v_cvt_pk_bf16_f32 v59, v52, v53
	v_add_f32_dpp v52, v170, v170 quad_perm:[1,0,3,2] row_mask:0xf bank_mask:0xf bound_ctrl:1
	global_store_dwordx2 v[14:15], v[58:59], off offset:1024
	s_nop 0
	v_add_f32_dpp v52, v52, v52 quad_perm:[2,3,0,1] row_mask:0xf bank_mask:0xf bound_ctrl:1
	s_nop 1
	v_add_f32_dpp v52, v52, v52 row_half_mirror row_mask:0xf bank_mask:0xf bound_ctrl:1
	s_nop 1
	v_add_f32_dpp v52, v52, v52 row_mirror row_mask:0xf bank_mask:0xf bound_ctrl:1
	s_nop 0
	v_readlane_b32 s9, v52, 16
	v_readlane_b32 s14, v52, 48
	v_readlane_b32 s6, v52, 0
	v_readlane_b32 s7, v52, 32
	v_mov_b32_e32 v52, s9
	v_mov_b32_e32 v53, s14
	v_pk_add_f32 v[52:53], s[6:7], v[52:53]
	s_nop 0
	v_add_f32_e32 v52, v52, v53
	v_fmamk_f32 v52, v52, 0x3b800000, v252
	v_cmp_gt_f32_e32 vcc, s55, v52
	v_mul_f32_e32 v53, 0x4f800000, v52
	s_nop 0
	v_cndmask_b32_e32 v52, v52, v53, vcc
	v_sqrt_f32_e32 v53, v52
	s_nop 0
	v_add_u32_e32 v58, -1, v53
	v_fma_f32 v59, -v58, v53, v52
	v_cmp_ge_f32_e64 s[6:7], 0, v59
	v_add_u32_e32 v59, 1, v53
	s_nop 0
	v_cndmask_b32_e64 v58, v53, v58, s[6:7]
	v_fma_f32 v53, -v59, v53, v52
	v_cmp_lt_f32_e64 s[6:7], 0, v53
	s_nop 1
	v_cndmask_b32_e64 v53, v58, v59, s[6:7]
	v_mul_f32_e32 v58, 0x37800000, v53
	v_cndmask_b32_e32 v53, v53, v58, vcc
	v_cmp_class_f32_e32 vcc, v52, v253
	s_nop 1
	v_cndmask_b32_e32 v52, v53, v52, vcc
	v_div_scale_f32 v53, s[6:7], v52, v52, 1.0
	v_rcp_f32_e32 v58, v53
	s_nop 0
	v_fma_f32 v59, -v53, v58, 1.0
	v_fmac_f32_e32 v58, v59, v58
	v_div_scale_f32 v59, vcc, 1.0, v52, 1.0
	v_mul_f32_e32 v64, v59, v58
	v_fma_f32 v65, -v53, v64, v59
	v_fmac_f32_e32 v64, v65, v58
	v_fma_f32 v53, -v53, v64, v59
	v_div_fmas_f32 v53, v53, v58, v64
	v_div_fixup_f32 v52, v53, v52, 1.0
	v_lshlrev_b32_e32 v58, 16, v46
	v_and_b32_e32 v59, 0xffff0000, v46
	v_lshlrev_b32_e32 v46, 16, v47
	v_and_b32_e32 v47, 0xffff0000, v47
	v_pk_mul_f32 v[64:65], v[130:131], v[52:53] op_sel_hi:[1,0]
	v_pk_mul_f32 v[52:53], v[126:127], v[52:53] op_sel_hi:[1,0]
	s_nop 0
	v_pk_mul_f32 v[46:47], v[52:53], v[46:47]
	v_pk_mul_f32 v[52:53], v[64:65], v[58:59]
	s_nop 0
	v_cvt_pk_bf16_f32 v52, v52, v53
	v_cvt_pk_bf16_f32 v53, v46, v47
	v_add_f32_dpp v46, v166, v166 quad_perm:[1,0,3,2] row_mask:0xf bank_mask:0xf bound_ctrl:1
	global_store_dwordx2 v[14:15], v[52:53], off offset:1536
	s_nop 0
	v_add_f32_dpp v46, v46, v46 quad_perm:[2,3,0,1] row_mask:0xf bank_mask:0xf bound_ctrl:1
	s_nop 1
	v_add_f32_dpp v46, v46, v46 row_half_mirror row_mask:0xf bank_mask:0xf bound_ctrl:1
	s_nop 1
	v_add_f32_dpp v46, v46, v46 row_mirror row_mask:0xf bank_mask:0xf bound_ctrl:1
	s_nop 0
	v_readlane_b32 s9, v46, 16
	v_readlane_b32 s14, v46, 48
	v_readlane_b32 s6, v46, 0
	v_readlane_b32 s7, v46, 32
	v_mov_b32_e32 v46, s9
	v_mov_b32_e32 v47, s14
	v_pk_add_f32 v[46:47], s[6:7], v[46:47]
	s_nop 0
	v_add_f32_e32 v46, v46, v47
	v_fmamk_f32 v46, v46, 0x3b800000, v252
	v_cmp_gt_f32_e32 vcc, s55, v46
	v_mul_f32_e32 v47, 0x4f800000, v46
	s_nop 0
	v_cndmask_b32_e32 v46, v46, v47, vcc
	v_sqrt_f32_e32 v47, v46
	s_nop 0
	v_add_u32_e32 v52, -1, v47
	v_fma_f32 v53, -v52, v47, v46
	v_cmp_ge_f32_e64 s[6:7], 0, v53
	v_add_u32_e32 v53, 1, v47
	s_nop 0
	v_cndmask_b32_e64 v52, v47, v52, s[6:7]
	v_fma_f32 v47, -v53, v47, v46
	v_cmp_lt_f32_e64 s[6:7], 0, v47
	s_nop 1
	v_cndmask_b32_e64 v47, v52, v53, s[6:7]
	v_mul_f32_e32 v52, 0x37800000, v47
	v_cndmask_b32_e32 v47, v47, v52, vcc
	v_cmp_class_f32_e32 vcc, v46, v253
	s_nop 1
	v_cndmask_b32_e32 v46, v47, v46, vcc
	v_div_scale_f32 v47, s[6:7], v46, v46, 1.0
	v_rcp_f32_e32 v52, v47
	s_nop 0
	v_fma_f32 v53, -v47, v52, 1.0
	v_fmac_f32_e32 v52, v53, v52
	v_div_scale_f32 v53, vcc, 1.0, v46, 1.0
	v_mul_f32_e32 v58, v53, v52
	v_fma_f32 v59, -v47, v58, v53
	v_fmac_f32_e32 v58, v59, v52
	v_fma_f32 v47, -v47, v58, v53
	v_div_fmas_f32 v47, v47, v52, v58
	v_div_fixup_f32 v46, v47, v46, 1.0
	v_lshlrev_b32_e32 v52, 16, v40
	v_and_b32_e32 v53, 0xffff0000, v40
	v_lshlrev_b32_e32 v40, 16, v41
	v_and_b32_e32 v41, 0xffff0000, v41
	v_pk_mul_f32 v[58:59], v[122:123], v[46:47] op_sel_hi:[1,0]
	v_pk_mul_f32 v[46:47], v[118:119], v[46:47] op_sel_hi:[1,0]
	s_nop 0
	v_pk_mul_f32 v[40:41], v[46:47], v[40:41]
	v_pk_mul_f32 v[46:47], v[58:59], v[52:53]
	s_nop 0
	v_cvt_pk_bf16_f32 v46, v46, v47
	v_cvt_pk_bf16_f32 v47, v40, v41
	v_add_f32_dpp v40, v110, v110 quad_perm:[1,0,3,2] row_mask:0xf bank_mask:0xf bound_ctrl:1
	global_store_dwordx2 v[14:15], v[46:47], off offset:2048
	s_nop 0
	v_add_f32_dpp v40, v40, v40 quad_perm:[2,3,0,1] row_mask:0xf bank_mask:0xf bound_ctrl:1
	s_nop 1
	v_add_f32_dpp v40, v40, v40 row_half_mirror row_mask:0xf bank_mask:0xf bound_ctrl:1
	s_nop 1
	v_add_f32_dpp v40, v40, v40 row_mirror row_mask:0xf bank_mask:0xf bound_ctrl:1
	s_nop 0
	v_readlane_b32 s9, v40, 16
	v_readlane_b32 s14, v40, 48
	v_readlane_b32 s6, v40, 0
	v_readlane_b32 s7, v40, 32
	v_mov_b32_e32 v40, s9
	v_mov_b32_e32 v41, s14
	v_pk_add_f32 v[40:41], s[6:7], v[40:41]
	s_nop 0
	v_add_f32_e32 v40, v40, v41
	v_fmamk_f32 v40, v40, 0x3b800000, v252
	v_cmp_gt_f32_e32 vcc, s55, v40
	v_mul_f32_e32 v41, 0x4f800000, v40
	s_nop 0
	v_cndmask_b32_e32 v40, v40, v41, vcc
	v_sqrt_f32_e32 v41, v40
	s_nop 0
	v_add_u32_e32 v46, -1, v41
	v_fma_f32 v47, -v46, v41, v40
	v_cmp_ge_f32_e64 s[6:7], 0, v47
	v_add_u32_e32 v47, 1, v41
	s_nop 0
	v_cndmask_b32_e64 v46, v41, v46, s[6:7]
	v_fma_f32 v41, -v47, v41, v40
	v_cmp_lt_f32_e64 s[6:7], 0, v41
	s_nop 1
	v_cndmask_b32_e64 v41, v46, v47, s[6:7]
	v_mul_f32_e32 v46, 0x37800000, v41
	v_cndmask_b32_e32 v41, v41, v46, vcc
	v_cmp_class_f32_e32 vcc, v40, v253
	s_nop 1
	v_cndmask_b32_e32 v40, v41, v40, vcc
	v_div_scale_f32 v41, s[6:7], v40, v40, 1.0
	v_rcp_f32_e32 v46, v41
	s_nop 0
	v_fma_f32 v47, -v41, v46, 1.0
	v_fmac_f32_e32 v46, v47, v46
	v_div_scale_f32 v47, vcc, 1.0, v40, 1.0
	v_mul_f32_e32 v52, v47, v46
	v_fma_f32 v53, -v41, v52, v47
	v_fmac_f32_e32 v52, v53, v46
	v_fma_f32 v41, -v41, v52, v47
	v_div_fmas_f32 v41, v41, v46, v52
	v_div_fixup_f32 v40, v41, v40, 1.0
	v_lshlrev_b32_e32 v46, 16, v24
	v_and_b32_e32 v47, 0xffff0000, v24
	v_lshlrev_b32_e32 v24, 16, v25
	v_and_b32_e32 v25, 0xffff0000, v25
	v_pk_mul_f32 v[52:53], v[114:115], v[40:41] op_sel_hi:[1,0]
	v_pk_mul_f32 v[40:41], v[106:107], v[40:41] op_sel_hi:[1,0]
	s_nop 0
	v_pk_mul_f32 v[24:25], v[40:41], v[24:25]
	v_pk_mul_f32 v[40:41], v[52:53], v[46:47]
	s_waitcnt vmcnt(38)
	v_lshlrev_b32_e32 v52, 16, v97
	v_cvt_pk_bf16_f32 v40, v40, v41
	v_cvt_pk_bf16_f32 v41, v24, v25
	v_add_f32_dpp v24, v98, v98 quad_perm:[1,0,3,2] row_mask:0xf bank_mask:0xf bound_ctrl:1
	global_store_dwordx2 v[14:15], v[40:41], off offset:2560
	v_and_b32_e32 v53, 0xffff0000, v97
	v_add_f32_dpp v24, v24, v24 quad_perm:[2,3,0,1] row_mask:0xf bank_mask:0xf bound_ctrl:1
	s_nop 1
	v_add_f32_dpp v24, v24, v24 row_half_mirror row_mask:0xf bank_mask:0xf bound_ctrl:1
	s_nop 1
	v_add_f32_dpp v24, v24, v24 row_mirror row_mask:0xf bank_mask:0xf bound_ctrl:1
	s_nop 0
	v_readlane_b32 s9, v24, 16
	v_readlane_b32 s14, v24, 48
	v_readlane_b32 s6, v24, 0
	v_readlane_b32 s7, v24, 32
	v_mov_b32_e32 v24, s9
	v_mov_b32_e32 v25, s14
	v_pk_add_f32 v[24:25], s[6:7], v[24:25]
	s_nop 0
	v_add_f32_e32 v24, v24, v25
	v_fmamk_f32 v24, v24, 0x3b800000, v252
	v_cmp_gt_f32_e32 vcc, s55, v24
	v_mul_f32_e32 v25, 0x4f800000, v24
	s_nop 0
	v_cndmask_b32_e32 v24, v24, v25, vcc
	v_sqrt_f32_e32 v25, v24
	s_nop 0
	v_add_u32_e32 v40, -1, v25
	v_fma_f32 v41, -v40, v25, v24
	v_cmp_ge_f32_e64 s[6:7], 0, v41
	v_add_u32_e32 v41, 1, v25
	s_nop 0
	v_cndmask_b32_e64 v40, v25, v40, s[6:7]
	v_fma_f32 v25, -v41, v25, v24
	v_cmp_lt_f32_e64 s[6:7], 0, v25
	s_nop 1
	v_cndmask_b32_e64 v25, v40, v41, s[6:7]
	v_mul_f32_e32 v40, 0x37800000, v25
	v_cndmask_b32_e32 v25, v25, v40, vcc
	v_cmp_class_f32_e32 vcc, v24, v253
	s_nop 1
	v_cndmask_b32_e32 v24, v25, v24, vcc
	v_div_scale_f32 v25, s[6:7], v24, v24, 1.0
	v_rcp_f32_e32 v40, v25
	s_nop 0
	v_fma_f32 v41, -v25, v40, 1.0
	v_fmac_f32_e32 v40, v41, v40
	v_div_scale_f32 v41, vcc, 1.0, v24, 1.0
	v_mul_f32_e32 v46, v41, v40
	v_fma_f32 v47, -v25, v46, v41
	v_fmac_f32_e32 v46, v47, v40
	v_fma_f32 v25, -v25, v46, v41
	v_div_fmas_f32 v25, v25, v40, v46
	v_div_fixup_f32 v24, v25, v24, 1.0
	v_lshlrev_b32_e32 v40, 16, v20
	v_and_b32_e32 v41, 0xffff0000, v20
	v_lshlrev_b32_e32 v20, 16, v21
	v_and_b32_e32 v21, 0xffff0000, v21
	v_pk_mul_f32 v[18:19], v[18:19], v[24:25] op_sel_hi:[1,0]
	v_pk_mul_f32 v[22:23], v[22:23], v[24:25] op_sel_hi:[1,0]
	v_pk_mul_f32 v[18:19], v[18:19], v[40:41]
	v_pk_mul_f32 v[20:21], v[22:23], v[20:21]
	v_cvt_pk_bf16_f32 v18, v18, v19
	v_cvt_pk_bf16_f32 v19, v20, v21
	global_store_dwordx2 v[14:15], v[18:19], off offset:3072
	v_add_f32_dpp v18, v90, v90 quad_perm:[1,0,3,2] row_mask:0xf bank_mask:0xf bound_ctrl:1
	s_nop 1
	v_add_f32_dpp v18, v18, v18 quad_perm:[2,3,0,1] row_mask:0xf bank_mask:0xf bound_ctrl:1
	s_nop 1
	v_add_f32_dpp v18, v18, v18 row_half_mirror row_mask:0xf bank_mask:0xf bound_ctrl:1
	s_nop 1
	v_add_f32_dpp v18, v18, v18 row_mirror row_mask:0xf bank_mask:0xf bound_ctrl:1
	s_nop 0
	v_readlane_b32 s9, v18, 16
	v_readlane_b32 s14, v18, 48
	v_readlane_b32 s6, v18, 0
	v_readlane_b32 s7, v18, 32
	v_mov_b32_e32 v18, s9
	v_mov_b32_e32 v19, s14
	v_pk_add_f32 v[18:19], s[6:7], v[18:19]
	s_nop 0
	v_add_f32_e32 v18, v18, v19
	v_fmamk_f32 v18, v18, 0x3b800000, v252
	v_cmp_gt_f32_e32 vcc, s55, v18
	v_mul_f32_e32 v19, 0x4f800000, v18
	s_nop 0
	v_cndmask_b32_e32 v18, v18, v19, vcc
	v_sqrt_f32_e32 v19, v18
; template <bool HG>
; __device__ __forceinline__ void readout_phase2(const Args& a, Frame& F, const float* gain, int nrows) {
;     ...
;     RO_FINISH(f0, b0, g0, nw + 3 * 2048); RO_LOAD(f0, b0, g0, nw + 6 * 2048);
;     RO_FINISH(f1, b1, g1, nw + 4 * 2048); RO_LOAD(f1, b1, g1, nw + 7 * 2048);
	s_nop 0
	v_add_u32_e32 v20, -1, v19
	v_fma_f32 v21, -v20, v19, v18
	v_cmp_ge_f32_e64 s[6:7], 0, v21
	v_add_u32_e32 v21, 1, v19
	s_nop 0
	v_cndmask_b32_e64 v20, v19, v20, s[6:7]
	v_fma_f32 v19, -v21, v19, v18
	v_cmp_lt_f32_e64 s[6:7], 0, v19
	s_nop 1
	v_cndmask_b32_e64 v19, v20, v21, s[6:7]
	v_mul_f32_e32 v20, 0x37800000, v19
	v_cndmask_b32_e32 v19, v19, v20, vcc
	v_cmp_class_f32_e32 vcc, v18, v253
	s_nop 1
	v_cndmask_b32_e32 v18, v19, v18, vcc
	v_div_scale_f32 v19, s[6:7], v18, v18, 1.0
	v_rcp_f32_e32 v20, v19
	s_nop 0
	v_fma_f32 v21, -v19, v20, 1.0
	v_fmac_f32_e32 v20, v21, v20
	v_div_scale_f32 v21, vcc, 1.0, v18, 1.0
	v_mul_f32_e32 v22, v21, v20
	v_fma_f32 v23, -v19, v22, v21
	v_fmac_f32_e32 v22, v23, v20
	v_fma_f32 v19, -v19, v22, v21
	v_div_fmas_f32 v19, v19, v20, v22
	v_div_fixup_f32 v18, v19, v18, 1.0
	v_lshlrev_b32_e32 v20, 16, v16
	v_and_b32_e32 v21, 0xffff0000, v16
	v_lshlrev_b32_e32 v16, 16, v17
	v_and_b32_e32 v17, 0xffff0000, v17
	v_pk_mul_f32 v[10:11], v[10:11], v[18:19] op_sel_hi:[1,0]
	v_pk_mul_f32 v[12:13], v[12:13], v[18:19] op_sel_hi:[1,0]
	v_pk_mul_f32 v[10:11], v[10:11], v[20:21]
	v_pk_mul_f32 v[12:13], v[12:13], v[16:17]
	v_cvt_pk_bf16_f32 v10, v10, v11
	v_cvt_pk_bf16_f32 v11, v12, v13
	v_lshl_add_u64 v[12:13], v[6:7], 0, s[40:41]
	global_store_dwordx2 v[14:15], v[10:11], off offset:3584
	v_lshl_add_u64 v[10:11], v[4:5], 0, s[40:41]
	v_lshl_add_u64 v[40:41], v[12:13], 0, v[0:1]
	v_lshl_add_u64 v[12:13], v[8:9], 0, s[40:41]
	v_lshl_add_u64 v[10:11], v[10:11], 0, v[0:1]
	v_lshl_add_u64 v[46:47], v[12:13], 0, v[0:1]
	global_load_dwordx2 v[148:149], v[10:11], off
	global_load_dwordx2 v[142:143], v[40:41], off
	global_load_dwordx2 v[24:25], v[46:47], off
	global_load_dwordx2 v[136:137], v[10:11], off offset:512
	global_load_dwordx2 v[130:131], v[40:41], off offset:512
	global_load_dwordx2 v[22:23], v[46:47], off offset:512
	global_load_dwordx2 v[126:127], v[10:11], off offset:1024
	global_load_dwordx2 v[122:123], v[40:41], off offset:1024
	global_load_dwordx2 v[20:21], v[46:47], off offset:1024
	global_load_dwordx2 v[114:115], v[10:11], off offset:1536
	global_load_dwordx2 v[118:119], v[40:41], off offset:1536
	global_load_dwordx2 v[18:19], v[46:47], off offset:1536
	global_load_dwordx2 v[110:111], v[10:11], off offset:2048
	global_load_dwordx2 v[106:107], v[40:41], off offset:2048
	global_load_dwordx2 v[16:17], v[46:47], off offset:2048
	global_load_dwordx2 v[102:103], v[10:11], off offset:2560
	global_load_dwordx2 v[98:99], v[40:41], off offset:2560
	global_load_dwordx2 v[14:15], v[46:47], off offset:2560
	global_load_dwordx2 v[94:95], v[10:11], off offset:3072
	global_load_dwordx2 v[90:91], v[40:41], off offset:3072
	global_load_dwordx2 v[12:13], v[46:47], off offset:3072
	global_load_dwordx2 v[58:59], v[10:11], off offset:3584
	global_load_dwordx2 v[64:65], v[40:41], off offset:3584
	s_nop 0
	global_load_dwordx2 v[10:11], v[46:47], off offset:3584
	v_lshlrev_b32_e32 v40, 16, v162
	v_and_b32_e32 v41, 0xffff0000, v162
	v_lshlrev_b32_e32 v46, 16, v156
	v_and_b32_e32 v47, 0xffff0000, v156
	v_pk_add_f32 v[160:161], v[40:41], v[46:47]
	v_lshlrev_b32_e32 v40, 16, v163
	v_and_b32_e32 v41, 0xffff0000, v163
	v_lshlrev_b32_e32 v46, 16, v157
	v_and_b32_e32 v47, 0xffff0000, v157
	v_pk_add_f32 v[156:157], v[40:41], v[46:47]
	v_mov_b32_e32 v46, v161
	v_mov_b32_e32 v47, v157
	v_mov_b32_e32 v40, v160
	v_mov_b32_e32 v41, v156
	v_pk_mul_f32 v[46:47], v[46:47], v[46:47]
	s_nop 0
	v_pk_fma_f32 v[40:41], v[40:41], v[40:41], v[46:47]
	v_lshlrev_b32_e32 v46, 16, v144
	v_add_f32_e32 v164, v40, v41
	v_lshlrev_b32_e32 v40, 16, v150
	v_and_b32_e32 v41, 0xffff0000, v150
	v_and_b32_e32 v47, 0xffff0000, v144
	v_pk_add_f32 v[154:155], v[40:41], v[46:47]
	v_lshlrev_b32_e32 v40, 16, v151
	v_and_b32_e32 v41, 0xffff0000, v151
	v_lshlrev_b32_e32 v46, 16, v145
	v_and_b32_e32 v47, 0xffff0000, v145
	v_pk_add_f32 v[150:151], v[40:41], v[46:47]
	v_mov_b32_e32 v46, v155
	v_mov_b32_e32 v47, v151
	v_mov_b32_e32 v40, v154
	v_mov_b32_e32 v41, v150
	v_pk_mul_f32 v[46:47], v[46:47], v[46:47]
	s_nop 0
	v_pk_fma_f32 v[40:41], v[40:41], v[40:41], v[46:47]
	v_lshlrev_b32_e32 v46, 16, v132
	v_add_f32_e32 v166, v40, v41
	v_lshlrev_b32_e32 v40, 16, v138
	v_and_b32_e32 v41, 0xffff0000, v138
	v_and_b32_e32 v47, 0xffff0000, v132
	v_pk_add_f32 v[144:145], v[40:41], v[46:47]
	v_lshlrev_b32_e32 v40, 16, v139
	v_and_b32_e32 v41, 0xffff0000, v139
	v_lshlrev_b32_e32 v46, 16, v133
	v_and_b32_e32 v47, 0xffff0000, v133
	v_pk_add_f32 v[138:139], v[40:41], v[46:47]
	v_mov_b32_e32 v46, v145
	v_mov_b32_e32 v47, v139
	v_mov_b32_e32 v40, v144
	v_mov_b32_e32 v41, v138
	v_pk_mul_f32 v[46:47], v[46:47], v[46:47]
	s_nop 0
	v_pk_fma_f32 v[40:41], v[40:41], v[40:41], v[46:47]
	v_lshlrev_b32_e32 v46, 16, v128
	v_add_f32_e32 v167, v40, v41
	v_lshlrev_b32_e32 v40, 16, v124
	v_and_b32_e32 v41, 0xffff0000, v124
	v_and_b32_e32 v47, 0xffff0000, v128
	v_pk_add_f32 v[132:133], v[40:41], v[46:47]
	v_lshlrev_b32_e32 v40, 16, v125
	v_and_b32_e32 v41, 0xffff0000, v125
	v_lshlrev_b32_e32 v46, 16, v129
	v_and_b32_e32 v47, 0xffff0000, v129
	v_pk_add_f32 v[128:129], v[40:41], v[46:47]
	v_mov_b32_e32 v46, v133
	v_mov_b32_e32 v47, v129
	v_mov_b32_e32 v40, v132
	v_mov_b32_e32 v41, v128
	v_pk_mul_f32 v[46:47], v[46:47], v[46:47]
	s_nop 0
	v_pk_fma_f32 v[40:41], v[40:41], v[40:41], v[46:47]
	v_lshlrev_b32_e32 v46, 16, v116
	v_add_f32_e32 v168, v40, v41
	v_lshlrev_b32_e32 v40, 16, v120
	v_and_b32_e32 v41, 0xffff0000, v120
	v_and_b32_e32 v47, 0xffff0000, v116
	v_pk_add_f32 v[124:125], v[40:41], v[46:47]
	v_lshlrev_b32_e32 v40, 16, v121
	v_and_b32_e32 v41, 0xffff0000, v121
	v_lshlrev_b32_e32 v46, 16, v117
	v_and_b32_e32 v47, 0xffff0000, v117
	v_pk_add_f32 v[120:121], v[40:41], v[46:47]
	v_mov_b32_e32 v46, v125
	v_mov_b32_e32 v47, v121
	v_mov_b32_e32 v40, v124
	v_mov_b32_e32 v41, v120
	v_pk_mul_f32 v[46:47], v[46:47], v[46:47]
	s_nop 0
	v_pk_fma_f32 v[40:41], v[40:41], v[40:41], v[46:47]
	v_lshlrev_b32_e32 v46, 16, v108
	v_add_f32_e32 v163, v40, v41
	v_lshlrev_b32_e32 v40, 16, v112
	v_and_b32_e32 v41, 0xffff0000, v112
	v_and_b32_e32 v47, 0xffff0000, v108
	v_pk_add_f32 v[116:117], v[40:41], v[46:47]
	v_lshlrev_b32_e32 v40, 16, v113
	v_and_b32_e32 v41, 0xffff0000, v113
	v_lshlrev_b32_e32 v46, 16, v109
	v_and_b32_e32 v47, 0xffff0000, v109
	v_pk_add_f32 v[112:113], v[40:41], v[46:47]
	v_mov_b32_e32 v46, v117
	v_mov_b32_e32 v47, v113
	v_mov_b32_e32 v40, v116
	v_mov_b32_e32 v41, v112
	v_pk_mul_f32 v[46:47], v[46:47], v[46:47]
	s_nop 0
	v_pk_fma_f32 v[40:41], v[40:41], v[40:41], v[46:47]
	v_lshlrev_b32_e32 v46, 16, v100
	v_add_f32_e32 v162, v40, v41
	v_lshlrev_b32_e32 v40, 16, v104
	v_and_b32_e32 v41, 0xffff0000, v104
	v_and_b32_e32 v47, 0xffff0000, v100
	v_pk_add_f32 v[108:109], v[40:41], v[46:47]
	v_lshlrev_b32_e32 v40, 16, v105
	v_and_b32_e32 v41, 0xffff0000, v105
	v_lshlrev_b32_e32 v46, 16, v101
	v_and_b32_e32 v47, 0xffff0000, v101
	v_pk_add_f32 v[100:101], v[40:41], v[46:47]
	v_mov_b32_e32 v46, v109
	v_mov_b32_e32 v47, v101
	v_mov_b32_e32 v40, v108
	v_mov_b32_e32 v41, v100
	v_pk_mul_f32 v[46:47], v[46:47], v[46:47]
	s_nop 0
	v_pk_fma_f32 v[40:41], v[40:41], v[40:41], v[46:47]
	v_lshlrev_b32_e32 v46, 16, v96
	v_add_f32_e32 v104, v40, v41
	v_lshlrev_b32_e32 v40, 16, v92
	v_and_b32_e32 v41, 0xffff0000, v92
	v_and_b32_e32 v47, 0xffff0000, v96
	v_pk_add_f32 v[40:41], v[40:41], v[46:47]
	v_lshlrev_b32_e32 v46, 16, v93
	v_and_b32_e32 v47, 0xffff0000, v93
	v_pk_add_f32 v[46:47], v[46:47], v[52:53]
	v_mov_b32_e32 v92, v41
	v_mov_b32_e32 v93, v47
	v_mov_b32_e32 v52, v40
	v_mov_b32_e32 v53, v46
	v_pk_mul_f32 v[92:93], v[92:93], v[92:93]
	s_nop 0
	v_pk_fma_f32 v[52:53], v[52:53], v[52:53], v[92:93]
	v_add_f32_dpp v93, v164, v164 quad_perm:[1,0,3,2] row_mask:0xf bank_mask:0xf bound_ctrl:1
	v_add_f32_e32 v92, v52, v53
	v_lshl_add_u64 v[52:53], v[2:3], 0, s[16:17]
	v_add_f32_dpp v93, v93, v93 quad_perm:[2,3,0,1] row_mask:0xf bank_mask:0xf bound_ctrl:1
	v_lshl_add_u64 v[52:53], v[52:53], 0, v[0:1]
	s_nop 0
	v_add_f32_dpp v93, v93, v93 row_half_mirror row_mask:0xf bank_mask:0xf bound_ctrl:1
	s_nop 1
	v_add_f32_dpp v93, v93, v93 row_mirror row_mask:0xf bank_mask:0xf bound_ctrl:1
	s_nop 0
	v_readlane_b32 s9, v93, 16
	v_readlane_b32 s10, v93, 48
	v_readlane_b32 s6, v93, 0
	v_readlane_b32 s7, v93, 32
	v_mov_b32_e32 v96, s9
	v_mov_b32_e32 v97, s10
	v_pk_add_f32 v[96:97], s[6:7], v[96:97]
	s_nop 0
	v_add_f32_e32 v93, v96, v97
	v_fmamk_f32 v93, v93, 0x3b800000, v252
	v_cmp_gt_f32_e32 vcc, s55, v93
	v_mul_f32_e32 v96, 0x4f800000, v93
	s_nop 0
	v_cndmask_b32_e32 v93, v93, v96, vcc
	v_sqrt_f32_e32 v96, v93
	s_nop 0
	v_add_u32_e32 v97, -1, v96
	v_fma_f32 v105, -v97, v96, v93
	v_cmp_ge_f32_e64 s[6:7], 0, v105
	v_add_u32_e32 v105, 1, v96
	s_nop 0
	v_cndmask_b32_e64 v97, v96, v97, s[6:7]
	v_fma_f32 v96, -v105, v96, v93
	v_cmp_lt_f32_e64 s[6:7], 0, v96
	s_nop 1
	v_cndmask_b32_e64 v96, v97, v105, s[6:7]
	v_mul_f32_e32 v97, 0x37800000, v96
	v_cndmask_b32_e32 v96, v96, v97, vcc
	v_cmp_class_f32_e32 vcc, v93, v253
	s_nop 1
	v_cndmask_b32_e32 v93, v96, v93, vcc
	v_div_scale_f32 v96, s[6:7], v93, v93, 1.0
	v_rcp_f32_e32 v97, v96
	s_nop 0
	v_fma_f32 v105, -v96, v97, 1.0
	v_fmac_f32_e32 v97, v105, v97
	v_div_scale_f32 v105, vcc, 1.0, v93, 1.0
	v_mul_f32_e32 v164, v105, v97
	v_fma_f32 v165, -v96, v164, v105
	v_fmac_f32_e32 v164, v165, v97
	v_fma_f32 v96, -v96, v164, v105
	v_div_fmas_f32 v96, v96, v97, v164
	v_div_fixup_f32 v96, v96, v93, 1.0
	v_lshlrev_b32_e32 v164, 16, v66
	v_and_b32_e32 v165, 0xffff0000, v66
	v_lshlrev_b32_e32 v66, 16, v67
	v_and_b32_e32 v67, 0xffff0000, v67
	v_pk_mul_f32 v[160:161], v[160:161], v[96:97] op_sel_hi:[1,0]
	v_pk_mul_f32 v[96:97], v[156:157], v[96:97] op_sel_hi:[1,0]
	s_nop 0
	v_pk_mul_f32 v[66:67], v[96:97], v[66:67]
	v_pk_mul_f32 v[96:97], v[160:161], v[164:165]
	s_waitcnt vmcnt(33)
	v_lshlrev_b32_e32 v160, 16, v70
	v_cvt_pk_bf16_f32 v96, v96, v97
	v_cvt_pk_bf16_f32 v97, v66, v67
	v_add_f32_dpp v66, v166, v166 quad_perm:[1,0,3,2] row_mask:0xf bank_mask:0xf bound_ctrl:1
	global_store_dwordx2 v[52:53], v[96:97], off
	v_and_b32_e32 v161, 0xffff0000, v70
	v_add_f32_dpp v66, v66, v66 quad_perm:[2,3,0,1] row_mask:0xf bank_mask:0xf bound_ctrl:1
	v_lshlrev_b32_e32 v70, 16, v71
	v_and_b32_e32 v71, 0xffff0000, v71
	v_add_f32_dpp v66, v66, v66 row_half_mirror row_mask:0xf bank_mask:0xf bound_ctrl:1
	s_nop 1
	v_add_f32_dpp v66, v66, v66 row_mirror row_mask:0xf bank_mask:0xf bound_ctrl:1
	s_nop 0
	v_readlane_b32 s9, v66, 16
	v_readlane_b32 s10, v66, 48
	v_readlane_b32 s6, v66, 0
	v_readlane_b32 s7, v66, 32
	v_mov_b32_e32 v66, s9
	v_mov_b32_e32 v67, s10
	v_pk_add_f32 v[66:67], s[6:7], v[66:67]
	s_nop 0
	v_add_f32_e32 v66, v66, v67
	v_fmamk_f32 v66, v66, 0x3b800000, v252
	v_cmp_gt_f32_e32 vcc, s55, v66
	v_mul_f32_e32 v67, 0x4f800000, v66
	s_nop 0
	v_cndmask_b32_e32 v66, v66, v67, vcc
	v_sqrt_f32_e32 v67, v66
	s_nop 0
	v_add_u32_e32 v93, -1, v67
	v_fma_f32 v96, -v93, v67, v66
	v_cmp_ge_f32_e64 s[6:7], 0, v96
	v_add_u32_e32 v96, 1, v67
	s_nop 0
	v_cndmask_b32_e64 v93, v67, v93, s[6:7]
	v_fma_f32 v67, -v96, v67, v66
	v_cmp_lt_f32_e64 s[6:7], 0, v67
	s_nop 1
	v_cndmask_b32_e64 v67, v93, v96, s[6:7]
	v_mul_f32_e32 v93, 0x37800000, v67
	v_cndmask_b32_e32 v67, v67, v93, vcc
	v_cmp_class_f32_e32 vcc, v66, v253
	s_nop 1
	v_cndmask_b32_e32 v66, v67, v66, vcc
	v_div_scale_f32 v67, s[6:7], v66, v66, 1.0
	v_rcp_f32_e32 v93, v67
	s_nop 0
	v_fma_f32 v96, -v67, v93, 1.0
	v_fmac_f32_e32 v93, v96, v93
	v_div_scale_f32 v96, vcc, 1.0, v66, 1.0
	v_mul_f32_e32 v97, v96, v93
	v_fma_f32 v105, -v67, v97, v96
	v_fmac_f32_e32 v97, v105, v93
	v_fma_f32 v67, -v67, v97, v96
	v_div_fmas_f32 v67, v67, v93, v97
	v_div_fixup_f32 v66, v67, v66, 1.0
	v_lshlrev_b32_e32 v96, 16, v60
	v_and_b32_e32 v97, 0xffff0000, v60
	v_lshlrev_b32_e32 v60, 16, v61
	v_and_b32_e32 v61, 0xffff0000, v61
	v_pk_mul_f32 v[154:155], v[154:155], v[66:67] op_sel_hi:[1,0]
	v_pk_mul_f32 v[66:67], v[150:151], v[66:67] op_sel_hi:[1,0]
	s_nop 0
	v_pk_mul_f32 v[60:61], v[66:67], v[60:61]
	v_pk_mul_f32 v[66:67], v[154:155], v[96:97]
	v_lshlrev_b32_e32 v154, 16, v152
	v_cvt_pk_bf16_f32 v66, v66, v67
	v_cvt_pk_bf16_f32 v67, v60, v61
	v_add_f32_dpp v60, v167, v167 quad_perm:[1,0,3,2] row_mask:0xf bank_mask:0xf bound_ctrl:1
	global_store_dwordx2 v[52:53], v[66:67], off offset:512
	v_and_b32_e32 v155, 0xffff0000, v152
	v_add_f32_dpp v60, v60, v60 quad_perm:[2,3,0,1] row_mask:0xf bank_mask:0xf bound_ctrl:1
	v_lshlrev_b32_e32 v152, 16, v153
	v_and_b32_e32 v153, 0xffff0000, v153
	v_add_f32_dpp v60, v60, v60 row_half_mirror row_mask:0xf bank_mask:0xf bound_ctrl:1
	s_nop 1
	v_add_f32_dpp v60, v60, v60 row_mirror row_mask:0xf bank_mask:0xf bound_ctrl:1
	s_nop 0
	v_readlane_b32 s9, v60, 16
	v_readlane_b32 s10, v60, 48
	v_readlane_b32 s6, v60, 0
	v_readlane_b32 s7, v60, 32
	v_mov_b32_e32 v60, s9
	v_mov_b32_e32 v61, s10
	v_pk_add_f32 v[60:61], s[6:7], v[60:61]
	s_nop 0
	v_add_f32_e32 v60, v60, v61
	v_fmamk_f32 v60, v60, 0x3b800000, v252
	v_cmp_gt_f32_e32 vcc, s55, v60
	v_mul_f32_e32 v61, 0x4f800000, v60
	s_nop 0
	v_cndmask_b32_e32 v60, v60, v61, vcc
	v_sqrt_f32_e32 v61, v60
	s_nop 0
	v_add_u32_e32 v66, -1, v61
	v_fma_f32 v67, -v66, v61, v60
	v_cmp_ge_f32_e64 s[6:7], 0, v67
	v_add_u32_e32 v67, 1, v61
	s_nop 0
	v_cndmask_b32_e64 v66, v61, v66, s[6:7]
	v_fma_f32 v61, -v67, v61, v60
	v_cmp_lt_f32_e64 s[6:7], 0, v61
	s_nop 1
	v_cndmask_b32_e64 v61, v66, v67, s[6:7]
	v_mul_f32_e32 v66, 0x37800000, v61
	v_cndmask_b32_e32 v61, v61, v66, vcc
	v_cmp_class_f32_e32 vcc, v60, v253
	s_nop 1
	v_cndmask_b32_e32 v60, v61, v60, vcc
	v_div_scale_f32 v61, s[6:7], v60, v60, 1.0
	v_rcp_f32_e32 v66, v61
	s_nop 0
	v_fma_f32 v67, -v61, v66, 1.0
	v_fmac_f32_e32 v66, v67, v66
	v_div_scale_f32 v67, vcc, 1.0, v60, 1.0
	v_mul_f32_e32 v93, v67, v66
	v_fma_f32 v96, -v61, v93, v67
	v_fmac_f32_e32 v93, v96, v66
	v_fma_f32 v61, -v61, v93, v67
	v_div_fmas_f32 v61, v61, v66, v93
	v_div_fixup_f32 v60, v61, v60, 1.0
	v_lshlrev_b32_e32 v66, 16, v54
	v_and_b32_e32 v67, 0xffff0000, v54
	v_lshlrev_b32_e32 v54, 16, v55
	v_and_b32_e32 v55, 0xffff0000, v55
	v_pk_mul_f32 v[96:97], v[144:145], v[60:61] op_sel_hi:[1,0]
	v_pk_mul_f32 v[60:61], v[138:139], v[60:61] op_sel_hi:[1,0]
	s_nop 0
	v_pk_mul_f32 v[54:55], v[60:61], v[54:55]
	v_pk_mul_f32 v[60:61], v[96:97], v[66:67]
	s_nop 0
	v_cvt_pk_bf16_f32 v60, v60, v61
	v_cvt_pk_bf16_f32 v61, v54, v55
	v_add_f32_dpp v54, v168, v168 quad_perm:[1,0,3,2] row_mask:0xf bank_mask:0xf bound_ctrl:1
	global_store_dwordx2 v[52:53], v[60:61], off offset:1024
	s_nop 0
	v_add_f32_dpp v54, v54, v54 quad_perm:[2,3,0,1] row_mask:0xf bank_mask:0xf bound_ctrl:1
	s_nop 1
	v_add_f32_dpp v54, v54, v54 row_half_mirror row_mask:0xf bank_mask:0xf bound_ctrl:1
	s_nop 1
	v_add_f32_dpp v54, v54, v54 row_mirror row_mask:0xf bank_mask:0xf bound_ctrl:1
	s_nop 0
	v_readlane_b32 s9, v54, 16
	v_readlane_b32 s10, v54, 48
	v_readlane_b32 s6, v54, 0
	v_readlane_b32 s7, v54, 32
	v_mov_b32_e32 v54, s9
	v_mov_b32_e32 v55, s10
	v_pk_add_f32 v[54:55], s[6:7], v[54:55]
	s_nop 0
	v_add_f32_e32 v54, v54, v55
	v_fmamk_f32 v54, v54, 0x3b800000, v252
	v_cmp_gt_f32_e32 vcc, s55, v54
	v_mul_f32_e32 v55, 0x4f800000, v54
	s_nop 0
	v_cndmask_b32_e32 v54, v54, v55, vcc
	v_sqrt_f32_e32 v55, v54
	s_nop 0
	v_add_u32_e32 v60, -1, v55
	v_fma_f32 v61, -v60, v55, v54
	v_cmp_ge_f32_e64 s[6:7], 0, v61
	v_add_u32_e32 v61, 1, v55
	s_nop 0
	v_cndmask_b32_e64 v60, v55, v60, s[6:7]
	v_fma_f32 v55, -v61, v55, v54
	v_cmp_lt_f32_e64 s[6:7], 0, v55
	s_nop 1
	v_cndmask_b32_e64 v55, v60, v61, s[6:7]
	v_mul_f32_e32 v60, 0x37800000, v55
	v_cndmask_b32_e32 v55, v55, v60, vcc
	v_cmp_class_f32_e32 vcc, v54, v253
	s_nop 1
	v_cndmask_b32_e32 v54, v55, v54, vcc
	v_div_scale_f32 v55, s[6:7], v54, v54, 1.0
	v_rcp_f32_e32 v60, v55
	s_nop 0
	v_fma_f32 v61, -v55, v60, 1.0
	v_fmac_f32_e32 v60, v61, v60
	v_div_scale_f32 v61, vcc, 1.0, v54, 1.0
	v_mul_f32_e32 v66, v61, v60
	v_fma_f32 v67, -v55, v66, v61
	v_fmac_f32_e32 v66, v67, v60
	v_fma_f32 v55, -v55, v66, v61
	v_div_fmas_f32 v55, v55, v60, v66
	v_div_fixup_f32 v54, v55, v54, 1.0
	v_lshlrev_b32_e32 v60, 16, v48
	v_and_b32_e32 v61, 0xffff0000, v48
	v_lshlrev_b32_e32 v48, 16, v49
	v_and_b32_e32 v49, 0xffff0000, v49
	v_pk_mul_f32 v[66:67], v[132:133], v[54:55] op_sel_hi:[1,0]
	v_pk_mul_f32 v[54:55], v[128:129], v[54:55] op_sel_hi:[1,0]
	s_nop 0
	v_pk_mul_f32 v[48:49], v[54:55], v[48:49]
	v_pk_mul_f32 v[54:55], v[66:67], v[60:61]
	s_nop 0
	v_cvt_pk_bf16_f32 v54, v54, v55
	v_cvt_pk_bf16_f32 v55, v48, v49
	v_add_f32_dpp v48, v163, v163 quad_perm:[1,0,3,2] row_mask:0xf bank_mask:0xf bound_ctrl:1
	global_store_dwordx2 v[52:53], v[54:55], off offset:1536
	s_nop 0
	v_add_f32_dpp v48, v48, v48 quad_perm:[2,3,0,1] row_mask:0xf bank_mask:0xf bound_ctrl:1
	s_nop 1
	v_add_f32_dpp v48, v48, v48 row_half_mirror row_mask:0xf bank_mask:0xf bound_ctrl:1
	s_nop 1
	v_add_f32_dpp v48, v48, v48 row_mirror row_mask:0xf bank_mask:0xf bound_ctrl:1
	s_nop 0
	v_readlane_b32 s9, v48, 16
	v_readlane_b32 s10, v48, 48
	v_readlane_b32 s6, v48, 0
	v_readlane_b32 s7, v48, 32
	v_mov_b32_e32 v48, s9
	v_mov_b32_e32 v49, s10
	v_pk_add_f32 v[48:49], s[6:7], v[48:49]
	s_nop 0
	v_add_f32_e32 v48, v48, v49
	v_fmamk_f32 v48, v48, 0x3b800000, v252
	v_cmp_gt_f32_e32 vcc, s55, v48
	v_mul_f32_e32 v49, 0x4f800000, v48
	s_nop 0
	v_cndmask_b32_e32 v48, v48, v49, vcc
	v_sqrt_f32_e32 v49, v48
	s_nop 0
	v_add_u32_e32 v54, -1, v49
	v_fma_f32 v55, -v54, v49, v48
	v_cmp_ge_f32_e64 s[6:7], 0, v55
	v_add_u32_e32 v55, 1, v49
	s_nop 0
	v_cndmask_b32_e64 v54, v49, v54, s[6:7]
	v_fma_f32 v49, -v55, v49, v48
	v_cmp_lt_f32_e64 s[6:7], 0, v49
	s_nop 1
	v_cndmask_b32_e64 v49, v54, v55, s[6:7]
	v_mul_f32_e32 v54, 0x37800000, v49
	v_cndmask_b32_e32 v49, v49, v54, vcc
	v_cmp_class_f32_e32 vcc, v48, v253
	s_nop 1
	v_cndmask_b32_e32 v48, v49, v48, vcc
	v_div_scale_f32 v49, s[6:7], v48, v48, 1.0
	v_rcp_f32_e32 v54, v49
	s_nop 0
	v_fma_f32 v55, -v49, v54, 1.0
	v_fmac_f32_e32 v54, v55, v54
	v_div_scale_f32 v55, vcc, 1.0, v48, 1.0
	v_mul_f32_e32 v60, v55, v54
	v_fma_f32 v61, -v49, v60, v55
	v_fmac_f32_e32 v60, v61, v54
	v_fma_f32 v49, -v49, v60, v55
	v_div_fmas_f32 v49, v49, v54, v60
	v_div_fixup_f32 v48, v49, v48, 1.0
	v_lshlrev_b32_e32 v54, 16, v42
	v_and_b32_e32 v55, 0xffff0000, v42
	v_lshlrev_b32_e32 v42, 16, v43
	v_and_b32_e32 v43, 0xffff0000, v43
	v_pk_mul_f32 v[60:61], v[124:125], v[48:49] op_sel_hi:[1,0]
	v_pk_mul_f32 v[48:49], v[120:121], v[48:49] op_sel_hi:[1,0]
	s_nop 0
	v_pk_mul_f32 v[42:43], v[48:49], v[42:43]
	v_pk_mul_f32 v[48:49], v[60:61], v[54:55]
	s_nop 0
	v_cvt_pk_bf16_f32 v48, v48, v49
	v_cvt_pk_bf16_f32 v49, v42, v43
	v_add_f32_dpp v42, v162, v162 quad_perm:[1,0,3,2] row_mask:0xf bank_mask:0xf bound_ctrl:1
	global_store_dwordx2 v[52:53], v[48:49], off offset:2048
	s_nop 0
	v_add_f32_dpp v42, v42, v42 quad_perm:[2,3,0,1] row_mask:0xf bank_mask:0xf bound_ctrl:1
	s_nop 1
	v_add_f32_dpp v42, v42, v42 row_half_mirror row_mask:0xf bank_mask:0xf bound_ctrl:1
	s_nop 1
	v_add_f32_dpp v42, v42, v42 row_mirror row_mask:0xf bank_mask:0xf bound_ctrl:1
	s_nop 0
	v_readlane_b32 s9, v42, 16
	v_readlane_b32 s10, v42, 48
	v_readlane_b32 s6, v42, 0
	v_readlane_b32 s7, v42, 32
	v_mov_b32_e32 v42, s9
	v_mov_b32_e32 v43, s10
	v_pk_add_f32 v[42:43], s[6:7], v[42:43]
	s_nop 0
	v_add_f32_e32 v42, v42, v43
	v_fmamk_f32 v42, v42, 0x3b800000, v252
	v_cmp_gt_f32_e32 vcc, s55, v42
	v_mul_f32_e32 v43, 0x4f800000, v42
	s_nop 0
	v_cndmask_b32_e32 v42, v42, v43, vcc
	v_sqrt_f32_e32 v43, v42
	s_nop 0
	v_add_u32_e32 v48, -1, v43
	v_fma_f32 v49, -v48, v43, v42
	v_cmp_ge_f32_e64 s[6:7], 0, v49
	v_add_u32_e32 v49, 1, v43
	s_nop 0
	v_cndmask_b32_e64 v48, v43, v48, s[6:7]
	v_fma_f32 v43, -v49, v43, v42
	v_cmp_lt_f32_e64 s[6:7], 0, v43
	s_nop 1
	v_cndmask_b32_e64 v43, v48, v49, s[6:7]
	v_mul_f32_e32 v48, 0x37800000, v43
	v_cndmask_b32_e32 v43, v43, v48, vcc
	v_cmp_class_f32_e32 vcc, v42, v253
	s_nop 1
	v_cndmask_b32_e32 v42, v43, v42, vcc
	v_div_scale_f32 v43, s[6:7], v42, v42, 1.0
	v_rcp_f32_e32 v48, v43
	s_nop 0
	v_fma_f32 v49, -v43, v48, 1.0
	v_fmac_f32_e32 v48, v49, v48
	v_div_scale_f32 v49, vcc, 1.0, v42, 1.0
	v_mul_f32_e32 v54, v49, v48
	v_fma_f32 v55, -v43, v54, v49
	v_fmac_f32_e32 v54, v55, v48
	v_fma_f32 v43, -v43, v54, v49
	v_div_fmas_f32 v43, v43, v48, v54
	v_div_fixup_f32 v42, v43, v42, 1.0
	v_lshlrev_b32_e32 v48, 16, v36
	v_and_b32_e32 v49, 0xffff0000, v36
	v_lshlrev_b32_e32 v36, 16, v37
	v_and_b32_e32 v37, 0xffff0000, v37
	v_pk_mul_f32 v[54:55], v[116:117], v[42:43] op_sel_hi:[1,0]
	v_pk_mul_f32 v[42:43], v[112:113], v[42:43] op_sel_hi:[1,0]
	s_nop 0
	v_pk_mul_f32 v[36:37], v[42:43], v[36:37]
	v_pk_mul_f32 v[42:43], v[54:55], v[48:49]
	s_nop 0
	v_cvt_pk_bf16_f32 v42, v42, v43
	v_cvt_pk_bf16_f32 v43, v36, v37
	v_add_f32_dpp v36, v104, v104 quad_perm:[1,0,3,2] row_mask:0xf bank_mask:0xf bound_ctrl:1
	global_store_dwordx2 v[52:53], v[42:43], off offset:2560
	s_nop 0
	v_add_f32_dpp v36, v36, v36 quad_perm:[2,3,0,1] row_mask:0xf bank_mask:0xf bound_ctrl:1
	s_nop 1
	v_add_f32_dpp v36, v36, v36 row_half_mirror row_mask:0xf bank_mask:0xf bound_ctrl:1
	s_nop 1
	v_add_f32_dpp v36, v36, v36 row_mirror row_mask:0xf bank_mask:0xf bound_ctrl:1
	s_nop 0
	v_readlane_b32 s9, v36, 16
	v_readlane_b32 s10, v36, 48
	v_readlane_b32 s6, v36, 0
	v_readlane_b32 s7, v36, 32
	v_mov_b32_e32 v36, s9
	v_mov_b32_e32 v37, s10
	v_pk_add_f32 v[36:37], s[6:7], v[36:37]
	s_nop 0
	v_add_f32_e32 v36, v36, v37
	v_fmamk_f32 v36, v36, 0x3b800000, v252
	v_cmp_gt_f32_e32 vcc, s55, v36
	v_mul_f32_e32 v37, 0x4f800000, v36
	s_nop 0
	v_cndmask_b32_e32 v36, v36, v37, vcc
	v_sqrt_f32_e32 v37, v36
	s_nop 0
	v_add_u32_e32 v42, -1, v37
	v_fma_f32 v43, -v42, v37, v36
	v_cmp_ge_f32_e64 s[6:7], 0, v43
	v_add_u32_e32 v43, 1, v37
	s_nop 0
	v_cndmask_b32_e64 v42, v37, v42, s[6:7]
	v_fma_f32 v37, -v43, v37, v36
	v_cmp_lt_f32_e64 s[6:7], 0, v37
	s_nop 1
	v_cndmask_b32_e64 v37, v42, v43, s[6:7]
	v_mul_f32_e32 v42, 0x37800000, v37
	v_cndmask_b32_e32 v37, v37, v42, vcc
	v_cmp_class_f32_e32 vcc, v36, v253
	s_nop 1
	v_cndmask_b32_e32 v36, v37, v36, vcc
	v_div_scale_f32 v37, s[6:7], v36, v36, 1.0
	v_rcp_f32_e32 v42, v37
	s_nop 0
	v_fma_f32 v43, -v37, v42, 1.0
	v_fmac_f32_e32 v42, v43, v42
	v_div_scale_f32 v43, vcc, 1.0, v36, 1.0
	v_mul_f32_e32 v48, v43, v42
	v_fma_f32 v49, -v37, v48, v43
	v_fmac_f32_e32 v48, v49, v42
	v_fma_f32 v37, -v37, v48, v43
	v_div_fmas_f32 v37, v37, v42, v48
	v_div_fixup_f32 v36, v37, v36, 1.0
	v_lshlrev_b32_e32 v42, 16, v32
	v_and_b32_e32 v43, 0xffff0000, v32
	v_lshlrev_b32_e32 v32, 16, v33
	v_and_b32_e32 v33, 0xffff0000, v33
	v_pk_mul_f32 v[48:49], v[108:109], v[36:37] op_sel_hi:[1,0]
	v_pk_mul_f32 v[36:37], v[100:101], v[36:37] op_sel_hi:[1,0]
; template <bool HG>
; __device__ __forceinline__ void readout_phase2(const Args& a, Frame& F, const float* gain, int nrows) {
;     ...
;     RO_FINISH(f1, b1, g1, nw + 4 * 2048); RO_LOAD(f1, b1, g1, nw + 7 * 2048);
;     RO_FINISH(f2, b2, g2, nw + 5 * 2048);
	s_nop 0
	v_pk_mul_f32 v[32:33], v[36:37], v[32:33]
	v_pk_mul_f32 v[36:37], v[48:49], v[42:43]
	s_nop 0
	v_cvt_pk_bf16_f32 v36, v36, v37
	v_cvt_pk_bf16_f32 v37, v32, v33
	v_add_f32_dpp v32, v92, v92 quad_perm:[1,0,3,2] row_mask:0xf bank_mask:0xf bound_ctrl:1
	global_store_dwordx2 v[52:53], v[36:37], off offset:3072
	s_nop 0
	v_add_f32_dpp v32, v32, v32 quad_perm:[2,3,0,1] row_mask:0xf bank_mask:0xf bound_ctrl:1
	s_nop 1
	v_add_f32_dpp v32, v32, v32 row_half_mirror row_mask:0xf bank_mask:0xf bound_ctrl:1
	s_nop 1
	v_add_f32_dpp v32, v32, v32 row_mirror row_mask:0xf bank_mask:0xf bound_ctrl:1
	s_nop 0
	v_readlane_b32 s9, v32, 16
	v_readlane_b32 s10, v32, 48
	v_readlane_b32 s6, v32, 0
	v_readlane_b32 s7, v32, 32
	v_mov_b32_e32 v32, s9
	v_mov_b32_e32 v33, s10
	v_pk_add_f32 v[32:33], s[6:7], v[32:33]
	s_add_i32 s10, s8, 0x3800
	v_add_f32_e32 v32, v32, v33
	v_fmamk_f32 v32, v32, 0x3b800000, v252
	v_cmp_gt_f32_e32 vcc, s55, v32
	v_mul_f32_e32 v33, 0x4f800000, v32
	s_ashr_i32 s11, s10, 31
	v_cndmask_b32_e32 v32, v32, v33, vcc
	v_sqrt_f32_e32 v33, v32
	s_lshl_b64 s[78:79], s[10:11], 12
	s_cmp_lt_i32 s82, s47
	v_add_u32_e32 v36, -1, v33
	v_fma_f32 v37, -v36, v33, v32
	v_cmp_ge_f32_e64 s[6:7], 0, v37
	v_add_u32_e32 v37, 1, v33
	s_nop 0
	v_cndmask_b32_e64 v36, v33, v36, s[6:7]
	v_fma_f32 v33, -v37, v33, v32
	v_cmp_lt_f32_e64 s[6:7], 0, v33
	s_nop 1
	v_cndmask_b32_e64 v33, v36, v37, s[6:7]
	v_mul_f32_e32 v36, 0x37800000, v33
	v_cndmask_b32_e32 v33, v33, v36, vcc
	v_cmp_class_f32_e32 vcc, v32, v253
	s_nop 1
	v_cndmask_b32_e32 v32, v33, v32, vcc
	v_div_scale_f32 v33, s[6:7], v32, v32, 1.0
	v_rcp_f32_e32 v36, v33
	s_nop 0
	v_fma_f32 v37, -v33, v36, 1.0
	v_fmac_f32_e32 v36, v37, v36
	v_div_scale_f32 v37, vcc, 1.0, v32, 1.0
	v_mul_f32_e32 v42, v37, v36
	v_fma_f32 v43, -v33, v42, v37
	v_fmac_f32_e32 v42, v43, v36
	v_fma_f32 v33, -v33, v42, v37
	v_div_fmas_f32 v33, v33, v36, v42
	v_div_fixup_f32 v32, v33, v32, 1.0
	v_lshlrev_b32_e32 v36, 16, v28
	v_and_b32_e32 v37, 0xffff0000, v28
	v_lshlrev_b32_e32 v28, 16, v29
	v_and_b32_e32 v29, 0xffff0000, v29
	v_pk_mul_f32 v[40:41], v[40:41], v[32:33] op_sel_hi:[1,0]
	v_pk_mul_f32 v[32:33], v[46:47], v[32:33] op_sel_hi:[1,0]
	s_nop 0
	v_pk_mul_f32 v[28:29], v[32:33], v[28:29]
	v_pk_mul_f32 v[32:33], v[40:41], v[36:37]
	s_nop 0
	v_cvt_pk_bf16_f32 v32, v32, v33
	v_cvt_pk_bf16_f32 v33, v28, v29
	global_store_dwordx2 v[52:53], v[32:33], off offset:3584
	v_lshl_add_u64 v[32:33], v[6:7], 0, s[78:79]
	v_lshl_add_u64 v[28:29], v[4:5], 0, s[78:79]
	v_lshl_add_u64 v[60:61], v[32:33], 0, v[0:1]
	v_lshl_add_u64 v[32:33], v[8:9], 0, s[78:79]
	v_lshl_add_u64 v[28:29], v[28:29], 0, v[0:1]
	v_lshl_add_u64 v[150:151], v[32:33], 0, v[0:1]
	global_load_dwordx2 v[144:145], v[28:29], off
	global_load_dwordx2 v[138:139], v[60:61], off
	global_load_dwordx2 v[52:53], v[150:151], off
	global_load_dwordx2 v[132:133], v[28:29], off offset:512
	global_load_dwordx2 v[128:129], v[60:61], off offset:512
	global_load_dwordx2 v[48:49], v[150:151], off offset:512
	global_load_dwordx2 v[124:125], v[28:29], off offset:1024
	global_load_dwordx2 v[120:121], v[60:61], off offset:1024
	global_load_dwordx2 v[46:47], v[150:151], off offset:1024
	global_load_dwordx2 v[112:113], v[28:29], off offset:1536
	global_load_dwordx2 v[116:117], v[60:61], off offset:1536
	global_load_dwordx2 v[42:43], v[150:151], off offset:1536
	global_load_dwordx2 v[108:109], v[28:29], off offset:2048
	global_load_dwordx2 v[104:105], v[60:61], off offset:2048
	global_load_dwordx2 v[40:41], v[150:151], off offset:2048
	global_load_dwordx2 v[100:101], v[28:29], off offset:2560
	global_load_dwordx2 v[96:97], v[60:61], off offset:2560
	global_load_dwordx2 v[36:37], v[150:151], off offset:2560
	global_load_dwordx2 v[92:93], v[28:29], off offset:3072
	global_load_dwordx2 v[66:67], v[60:61], off offset:3072
	global_load_dwordx2 v[32:33], v[150:151], off offset:3072
	global_load_dwordx2 v[54:55], v[28:29], off offset:3584
	s_nop 0
	global_load_dwordx2 v[60:61], v[60:61], off offset:3584
	s_nop 0
	global_load_dwordx2 v[28:29], v[150:151], off offset:3584
	v_lshlrev_b32_e32 v150, 16, v158
	v_and_b32_e32 v151, 0xffff0000, v158
	v_pk_add_f32 v[154:155], v[150:151], v[154:155]
	v_lshlrev_b32_e32 v150, 16, v159
	v_and_b32_e32 v151, 0xffff0000, v159
	v_pk_add_f32 v[152:153], v[150:151], v[152:153]
	v_mov_b32_e32 v156, v155
	v_mov_b32_e32 v157, v153
	v_mov_b32_e32 v150, v154
	v_mov_b32_e32 v151, v152
	v_pk_mul_f32 v[156:157], v[156:157], v[156:157]
	s_nop 0
	v_pk_fma_f32 v[150:151], v[150:151], v[150:151], v[156:157]
	v_lshlrev_b32_e32 v156, 16, v140
	v_add_f32_e32 v162, v150, v151
	v_lshlrev_b32_e32 v150, 16, v146
	v_and_b32_e32 v151, 0xffff0000, v146
	v_and_b32_e32 v157, 0xffff0000, v140
	v_lshlrev_b32_e32 v146, 16, v147
	v_and_b32_e32 v147, 0xffff0000, v147
	v_lshlrev_b32_e32 v140, 16, v141
	v_and_b32_e32 v141, 0xffff0000, v141
	v_pk_add_f32 v[150:151], v[150:151], v[156:157]
	v_pk_add_f32 v[146:147], v[146:147], v[140:141]
	v_mov_b32_e32 v156, v151
	v_mov_b32_e32 v157, v147
	v_mov_b32_e32 v140, v150
	v_mov_b32_e32 v141, v146
	v_pk_mul_f32 v[156:157], v[156:157], v[156:157]
	s_nop 0
	v_pk_fma_f32 v[140:141], v[140:141], v[140:141], v[156:157]
	v_lshlrev_b32_e32 v156, 16, v88
	v_add_f32_e32 v164, v140, v141
	v_lshlrev_b32_e32 v140, 16, v134
	v_and_b32_e32 v141, 0xffff0000, v134
	v_and_b32_e32 v157, 0xffff0000, v88
	v_lshlrev_b32_e32 v134, 16, v135
	v_and_b32_e32 v135, 0xffff0000, v135
	v_lshlrev_b32_e32 v88, 16, v89
	v_and_b32_e32 v89, 0xffff0000, v89
	v_pk_add_f32 v[140:141], v[140:141], v[156:157]
	v_pk_add_f32 v[134:135], v[134:135], v[88:89]
	v_mov_b32_e32 v156, v141
	v_mov_b32_e32 v157, v135
	v_mov_b32_e32 v88, v140
	v_mov_b32_e32 v89, v134
	v_pk_mul_f32 v[156:157], v[156:157], v[156:157]
	s_nop 0
	v_pk_fma_f32 v[88:89], v[88:89], v[88:89], v[156:157]
	v_lshlrev_b32_e32 v156, 16, v86
	v_add_f32_e32 v165, v88, v89
	v_lshlrev_b32_e32 v88, 16, v84
	v_and_b32_e32 v89, 0xffff0000, v84
	v_and_b32_e32 v157, 0xffff0000, v86
	v_lshlrev_b32_e32 v84, 16, v85
	v_and_b32_e32 v85, 0xffff0000, v85
	v_lshlrev_b32_e32 v86, 16, v87
	v_and_b32_e32 v87, 0xffff0000, v87
	v_pk_add_f32 v[88:89], v[88:89], v[156:157]
	v_pk_add_f32 v[86:87], v[84:85], v[86:87]
	v_mov_b32_e32 v156, v89
	v_mov_b32_e32 v157, v87
	v_mov_b32_e32 v84, v88
	v_mov_b32_e32 v85, v86
	v_pk_mul_f32 v[156:157], v[156:157], v[156:157]
	s_nop 0
	v_pk_fma_f32 v[84:85], v[84:85], v[84:85], v[156:157]
	v_lshlrev_b32_e32 v156, 16, v80
	v_add_f32_e32 v166, v84, v85
	v_lshlrev_b32_e32 v84, 16, v82
	v_and_b32_e32 v85, 0xffff0000, v82
	v_and_b32_e32 v157, 0xffff0000, v80
	v_lshlrev_b32_e32 v82, 16, v83
	v_and_b32_e32 v83, 0xffff0000, v83
	v_lshlrev_b32_e32 v80, 16, v81
	v_and_b32_e32 v81, 0xffff0000, v81
	v_pk_add_f32 v[84:85], v[84:85], v[156:157]
	v_pk_add_f32 v[82:83], v[82:83], v[80:81]
	v_mov_b32_e32 v156, v85
	v_mov_b32_e32 v157, v83
	v_mov_b32_e32 v80, v84
	v_mov_b32_e32 v81, v82
	v_pk_mul_f32 v[156:157], v[156:157], v[156:157]
	s_nop 0
	v_pk_fma_f32 v[80:81], v[80:81], v[80:81], v[156:157]
	v_lshlrev_b32_e32 v156, 16, v76
	v_add_f32_e32 v159, v80, v81
	v_lshlrev_b32_e32 v80, 16, v78
	v_and_b32_e32 v81, 0xffff0000, v78
	v_and_b32_e32 v157, 0xffff0000, v76
	v_lshlrev_b32_e32 v78, 16, v79
	v_and_b32_e32 v79, 0xffff0000, v79
	v_lshlrev_b32_e32 v76, 16, v77
	v_and_b32_e32 v77, 0xffff0000, v77
	v_pk_add_f32 v[80:81], v[80:81], v[156:157]
	v_pk_add_f32 v[78:79], v[78:79], v[76:77]
	v_mov_b32_e32 v156, v81
	v_mov_b32_e32 v157, v79
	v_mov_b32_e32 v76, v80
	v_mov_b32_e32 v77, v78
	v_pk_mul_f32 v[156:157], v[156:157], v[156:157]
	s_nop 0
	v_pk_fma_f32 v[76:77], v[76:77], v[76:77], v[156:157]
	v_lshlrev_b32_e32 v156, 16, v72
	v_add_f32_e32 v158, v76, v77
	v_lshlrev_b32_e32 v76, 16, v74
	v_and_b32_e32 v77, 0xffff0000, v74
	v_and_b32_e32 v157, 0xffff0000, v72
	v_lshlrev_b32_e32 v74, 16, v75
	v_and_b32_e32 v75, 0xffff0000, v75
	v_lshlrev_b32_e32 v72, 16, v73
	v_and_b32_e32 v73, 0xffff0000, v73
	v_pk_add_f32 v[76:77], v[76:77], v[156:157]
	v_pk_add_f32 v[74:75], v[74:75], v[72:73]
	v_mov_b32_e32 v156, v77
	v_mov_b32_e32 v157, v75
	v_mov_b32_e32 v72, v76
	v_mov_b32_e32 v73, v74
	v_pk_mul_f32 v[156:157], v[156:157], v[156:157]
	s_nop 0
	v_pk_fma_f32 v[72:73], v[72:73], v[72:73], v[156:157]
	s_nop 0
	v_add_f32_e32 v157, v72, v73
	v_lshlrev_b32_e32 v72, 16, v68
	v_and_b32_e32 v73, 0xffff0000, v68
	v_lshlrev_b32_e32 v68, 16, v69
	v_and_b32_e32 v69, 0xffff0000, v69
	v_pk_add_f32 v[72:73], v[72:73], v[160:161]
	v_pk_add_f32 v[68:69], v[68:69], v[70:71]
	v_mov_b32_e32 v160, v73
	v_mov_b32_e32 v161, v69
	v_mov_b32_e32 v70, v72
	v_mov_b32_e32 v71, v68
	v_pk_mul_f32 v[160:161], v[160:161], v[160:161]
	s_nop 0
	v_pk_fma_f32 v[70:71], v[70:71], v[70:71], v[160:161]
	v_add_f32_dpp v160, v162, v162 quad_perm:[1,0,3,2] row_mask:0xf bank_mask:0xf bound_ctrl:1
	v_add_f32_e32 v156, v70, v71
	v_lshl_add_u64 v[70:71], v[2:3], 0, s[12:13]
	v_add_f32_dpp v160, v160, v160 quad_perm:[2,3,0,1] row_mask:0xf bank_mask:0xf bound_ctrl:1
	v_lshl_add_u64 v[70:71], v[70:71], 0, v[0:1]
	s_nop 0
	v_add_f32_dpp v160, v160, v160 row_half_mirror row_mask:0xf bank_mask:0xf bound_ctrl:1
	s_nop 1
	v_add_f32_dpp v160, v160, v160 row_mirror row_mask:0xf bank_mask:0xf bound_ctrl:1
	s_nop 0
	v_readlane_b32 s9, v160, 16
	v_readlane_b32 s11, v160, 48
	v_readlane_b32 s6, v160, 0
	v_readlane_b32 s7, v160, 32
	v_mov_b32_e32 v160, s9
	v_mov_b32_e32 v161, s11
	v_pk_add_f32 v[160:161], s[6:7], v[160:161]
	s_nop 0
	v_add_f32_e32 v160, v160, v161
	v_fmamk_f32 v160, v160, 0x3b800000, v252
	v_cmp_gt_f32_e32 vcc, s55, v160
	v_mul_f32_e32 v161, 0x4f800000, v160
	s_nop 0
	v_cndmask_b32_e32 v160, v160, v161, vcc
	v_sqrt_f32_e32 v161, v160
	s_nop 0
	v_add_u32_e32 v162, -1, v161
	v_fma_f32 v163, -v162, v161, v160
	v_cmp_ge_f32_e64 s[6:7], 0, v163
	v_add_u32_e32 v163, 1, v161
	s_nop 0
	v_cndmask_b32_e64 v162, v161, v162, s[6:7]
	v_fma_f32 v161, -v163, v161, v160
	v_cmp_lt_f32_e64 s[6:7], 0, v161
	s_nop 1
	v_cndmask_b32_e64 v161, v162, v163, s[6:7]
	v_mul_f32_e32 v162, 0x37800000, v161
	v_cndmask_b32_e32 v161, v161, v162, vcc
	v_cmp_class_f32_e32 vcc, v160, v253
	s_nop 1
	v_cndmask_b32_e32 v160, v161, v160, vcc
	v_div_scale_f32 v161, s[6:7], v160, v160, 1.0
	v_rcp_f32_e32 v162, v161
	s_nop 0
	v_fma_f32 v163, -v161, v162, 1.0
	v_fmac_f32_e32 v162, v163, v162
	v_div_scale_f32 v163, vcc, 1.0, v160, 1.0
	v_mul_f32_e32 v167, v163, v162
	v_fma_f32 v168, -v161, v167, v163
	v_fmac_f32_e32 v167, v168, v162
	v_fma_f32 v161, -v161, v167, v163
	v_div_fmas_f32 v161, v161, v162, v167
	v_div_fixup_f32 v160, v161, v160, 1.0
	v_lshlrev_b32_e32 v162, 16, v62
	v_and_b32_e32 v163, 0xffff0000, v62
	v_lshlrev_b32_e32 v62, 16, v63
	v_and_b32_e32 v63, 0xffff0000, v63
	v_pk_mul_f32 v[154:155], v[154:155], v[160:161] op_sel_hi:[1,0]
	v_pk_mul_f32 v[152:153], v[152:153], v[160:161] op_sel_hi:[1,0]
	s_nop 0
	v_pk_mul_f32 v[62:63], v[152:153], v[62:63]
	v_pk_mul_f32 v[152:153], v[154:155], v[162:163]
	s_nop 0
	v_cvt_pk_bf16_f32 v152, v152, v153
	v_cvt_pk_bf16_f32 v153, v62, v63
	v_add_f32_dpp v62, v164, v164 quad_perm:[1,0,3,2] row_mask:0xf bank_mask:0xf bound_ctrl:1
	global_store_dwordx2 v[70:71], v[152:153], off
	s_nop 0
	v_add_f32_dpp v62, v62, v62 quad_perm:[2,3,0,1] row_mask:0xf bank_mask:0xf bound_ctrl:1
	s_nop 1
	v_add_f32_dpp v62, v62, v62 row_half_mirror row_mask:0xf bank_mask:0xf bound_ctrl:1
	s_nop 1
	v_add_f32_dpp v62, v62, v62 row_mirror row_mask:0xf bank_mask:0xf bound_ctrl:1
	s_nop 0
	v_readlane_b32 s9, v62, 16
	v_readlane_b32 s11, v62, 48
	v_readlane_b32 s6, v62, 0
	v_readlane_b32 s7, v62, 32
	v_mov_b32_e32 v62, s9
	v_mov_b32_e32 v63, s11
	v_pk_add_f32 v[62:63], s[6:7], v[62:63]
	s_nop 0
	v_add_f32_e32 v62, v62, v63
	v_fmamk_f32 v62, v62, 0x3b800000, v252
	v_cmp_gt_f32_e32 vcc, s55, v62
	v_mul_f32_e32 v63, 0x4f800000, v62
	s_nop 0
	v_cndmask_b32_e32 v62, v62, v63, vcc
	v_sqrt_f32_e32 v63, v62
	s_nop 0
	v_add_u32_e32 v152, -1, v63
	v_fma_f32 v153, -v152, v63, v62
	v_cmp_ge_f32_e64 s[6:7], 0, v153
	v_add_u32_e32 v153, 1, v63
	s_nop 0
	v_cndmask_b32_e64 v152, v63, v152, s[6:7]
	v_fma_f32 v63, -v153, v63, v62
	v_cmp_lt_f32_e64 s[6:7], 0, v63
	s_nop 1
	v_cndmask_b32_e64 v63, v152, v153, s[6:7]
	v_mul_f32_e32 v152, 0x37800000, v63
	v_cndmask_b32_e32 v63, v63, v152, vcc
	v_cmp_class_f32_e32 vcc, v62, v253
	s_nop 1
	v_cndmask_b32_e32 v62, v63, v62, vcc
	v_div_scale_f32 v63, s[6:7], v62, v62, 1.0
	v_rcp_f32_e32 v152, v63
	s_nop 0
	v_fma_f32 v153, -v63, v152, 1.0
	v_fmac_f32_e32 v152, v153, v152
	v_div_scale_f32 v153, vcc, 1.0, v62, 1.0
	v_mul_f32_e32 v154, v153, v152
	v_fma_f32 v155, -v63, v154, v153
	v_fmac_f32_e32 v154, v155, v152
	v_fma_f32 v63, -v63, v154, v153
	v_div_fmas_f32 v63, v63, v152, v154
	v_div_fixup_f32 v62, v63, v62, 1.0
	v_lshlrev_b32_e32 v152, 16, v56
	v_and_b32_e32 v153, 0xffff0000, v56
	v_lshlrev_b32_e32 v56, 16, v57
	v_and_b32_e32 v57, 0xffff0000, v57
	v_pk_mul_f32 v[150:151], v[150:151], v[62:63] op_sel_hi:[1,0]
	v_pk_mul_f32 v[62:63], v[146:147], v[62:63] op_sel_hi:[1,0]
	s_nop 0
	v_pk_mul_f32 v[56:57], v[62:63], v[56:57]
	v_pk_mul_f32 v[62:63], v[150:151], v[152:153]
	s_nop 0
	v_cvt_pk_bf16_f32 v62, v62, v63
	v_cvt_pk_bf16_f32 v63, v56, v57
	v_add_f32_dpp v56, v165, v165 quad_perm:[1,0,3,2] row_mask:0xf bank_mask:0xf bound_ctrl:1
	global_store_dwordx2 v[70:71], v[62:63], off offset:512
	s_nop 0
	v_add_f32_dpp v56, v56, v56 quad_perm:[2,3,0,1] row_mask:0xf bank_mask:0xf bound_ctrl:1
	s_nop 1
	v_add_f32_dpp v56, v56, v56 row_half_mirror row_mask:0xf bank_mask:0xf bound_ctrl:1
	s_nop 1
	v_add_f32_dpp v56, v56, v56 row_mirror row_mask:0xf bank_mask:0xf bound_ctrl:1
	s_nop 0
	v_readlane_b32 s9, v56, 16
	v_readlane_b32 s11, v56, 48
	v_readlane_b32 s6, v56, 0
	v_readlane_b32 s7, v56, 32
	v_mov_b32_e32 v56, s9
	v_mov_b32_e32 v57, s11
	v_pk_add_f32 v[56:57], s[6:7], v[56:57]
	s_nop 0
	v_add_f32_e32 v56, v56, v57
	v_fmamk_f32 v56, v56, 0x3b800000, v252
	v_cmp_gt_f32_e32 vcc, s55, v56
	v_mul_f32_e32 v57, 0x4f800000, v56
	s_nop 0
	v_cndmask_b32_e32 v56, v56, v57, vcc
	v_sqrt_f32_e32 v57, v56
	s_nop 0
	v_add_u32_e32 v62, -1, v57
	v_fma_f32 v63, -v62, v57, v56
	v_cmp_ge_f32_e64 s[6:7], 0, v63
	v_add_u32_e32 v63, 1, v57
	s_nop 0
	v_cndmask_b32_e64 v62, v57, v62, s[6:7]
	v_fma_f32 v57, -v63, v57, v56
	v_cmp_lt_f32_e64 s[6:7], 0, v57
	s_nop 1
	v_cndmask_b32_e64 v57, v62, v63, s[6:7]
	v_mul_f32_e32 v62, 0x37800000, v57
	v_cndmask_b32_e32 v57, v57, v62, vcc
	v_cmp_class_f32_e32 vcc, v56, v253
	s_nop 1
	v_cndmask_b32_e32 v56, v57, v56, vcc
	v_div_scale_f32 v57, s[6:7], v56, v56, 1.0
	v_rcp_f32_e32 v62, v57
	s_nop 0
	v_fma_f32 v63, -v57, v62, 1.0
	v_fmac_f32_e32 v62, v63, v62
	v_div_scale_f32 v63, vcc, 1.0, v56, 1.0
	v_mul_f32_e32 v146, v63, v62
	v_fma_f32 v147, -v57, v146, v63
	v_fmac_f32_e32 v146, v147, v62
	v_fma_f32 v57, -v57, v146, v63
	v_div_fmas_f32 v57, v57, v62, v146
	v_div_fixup_f32 v56, v57, v56, 1.0
	v_lshlrev_b32_e32 v62, 16, v50
	v_and_b32_e32 v63, 0xffff0000, v50
	v_lshlrev_b32_e32 v50, 16, v51
	v_and_b32_e32 v51, 0xffff0000, v51
	v_pk_mul_f32 v[140:141], v[140:141], v[56:57] op_sel_hi:[1,0]
	v_pk_mul_f32 v[56:57], v[134:135], v[56:57] op_sel_hi:[1,0]
	s_nop 0
	v_pk_mul_f32 v[50:51], v[56:57], v[50:51]
	v_pk_mul_f32 v[56:57], v[140:141], v[62:63]
	s_nop 0
	v_cvt_pk_bf16_f32 v56, v56, v57
	v_cvt_pk_bf16_f32 v57, v50, v51
	v_add_f32_dpp v50, v166, v166 quad_perm:[1,0,3,2] row_mask:0xf bank_mask:0xf bound_ctrl:1
	global_store_dwordx2 v[70:71], v[56:57], off offset:1024
	s_nop 0
	v_add_f32_dpp v50, v50, v50 quad_perm:[2,3,0,1] row_mask:0xf bank_mask:0xf bound_ctrl:1
	s_nop 1
	v_add_f32_dpp v50, v50, v50 row_half_mirror row_mask:0xf bank_mask:0xf bound_ctrl:1
	s_nop 1
	v_add_f32_dpp v50, v50, v50 row_mirror row_mask:0xf bank_mask:0xf bound_ctrl:1
	s_nop 0
	v_readlane_b32 s9, v50, 16
	v_readlane_b32 s11, v50, 48
	v_readlane_b32 s6, v50, 0
	v_readlane_b32 s7, v50, 32
	v_mov_b32_e32 v50, s9
	v_mov_b32_e32 v51, s11
	v_pk_add_f32 v[50:51], s[6:7], v[50:51]
	s_nop 0
	v_add_f32_e32 v50, v50, v51
	v_fmamk_f32 v50, v50, 0x3b800000, v252
	v_cmp_gt_f32_e32 vcc, s55, v50
	v_mul_f32_e32 v51, 0x4f800000, v50
	s_nop 0
	v_cndmask_b32_e32 v50, v50, v51, vcc
	v_sqrt_f32_e32 v51, v50
	s_nop 0
	v_add_u32_e32 v56, -1, v51
	v_fma_f32 v57, -v56, v51, v50
	v_cmp_ge_f32_e64 s[6:7], 0, v57
	v_add_u32_e32 v57, 1, v51
	s_nop 0
	v_cndmask_b32_e64 v56, v51, v56, s[6:7]
	v_fma_f32 v51, -v57, v51, v50
	v_cmp_lt_f32_e64 s[6:7], 0, v51
	s_nop 1
	v_cndmask_b32_e64 v51, v56, v57, s[6:7]
	v_mul_f32_e32 v56, 0x37800000, v51
	v_cndmask_b32_e32 v51, v51, v56, vcc
	v_cmp_class_f32_e32 vcc, v50, v253
	s_nop 1
	v_cndmask_b32_e32 v50, v51, v50, vcc
	v_div_scale_f32 v51, s[6:7], v50, v50, 1.0
	v_rcp_f32_e32 v56, v51
	s_nop 0
	v_fma_f32 v57, -v51, v56, 1.0
	v_fmac_f32_e32 v56, v57, v56
	v_div_scale_f32 v57, vcc, 1.0, v50, 1.0
	v_mul_f32_e32 v62, v57, v56
	v_fma_f32 v63, -v51, v62, v57
	v_fmac_f32_e32 v62, v63, v56
	v_fma_f32 v51, -v51, v62, v57
	v_div_fmas_f32 v51, v51, v56, v62
	v_div_fixup_f32 v50, v51, v50, 1.0
	v_lshlrev_b32_e32 v56, 16, v44
	v_and_b32_e32 v57, 0xffff0000, v44
	v_lshlrev_b32_e32 v44, 16, v45
	v_and_b32_e32 v45, 0xffff0000, v45
	v_pk_mul_f32 v[62:63], v[88:89], v[50:51] op_sel_hi:[1,0]
	v_pk_mul_f32 v[50:51], v[86:87], v[50:51] op_sel_hi:[1,0]
	s_nop 0
	v_pk_mul_f32 v[44:45], v[50:51], v[44:45]
	v_pk_mul_f32 v[50:51], v[62:63], v[56:57]
	s_nop 0
	v_cvt_pk_bf16_f32 v50, v50, v51
	v_cvt_pk_bf16_f32 v51, v44, v45
	v_add_f32_dpp v44, v159, v159 quad_perm:[1,0,3,2] row_mask:0xf bank_mask:0xf bound_ctrl:1
	global_store_dwordx2 v[70:71], v[50:51], off offset:1536
	s_nop 0
	v_add_f32_dpp v44, v44, v44 quad_perm:[2,3,0,1] row_mask:0xf bank_mask:0xf bound_ctrl:1
	s_nop 1
	v_add_f32_dpp v44, v44, v44 row_half_mirror row_mask:0xf bank_mask:0xf bound_ctrl:1
	s_nop 1
	v_add_f32_dpp v44, v44, v44 row_mirror row_mask:0xf bank_mask:0xf bound_ctrl:1
	s_nop 0
	v_readlane_b32 s9, v44, 16
	v_readlane_b32 s11, v44, 48
	v_readlane_b32 s6, v44, 0
	v_readlane_b32 s7, v44, 32
	v_mov_b32_e32 v44, s9
	v_mov_b32_e32 v45, s11
	v_pk_add_f32 v[44:45], s[6:7], v[44:45]
	s_nop 0
	v_add_f32_e32 v44, v44, v45
	v_fmamk_f32 v44, v44, 0x3b800000, v252
	v_cmp_gt_f32_e32 vcc, s55, v44
	v_mul_f32_e32 v45, 0x4f800000, v44
	s_nop 0
	v_cndmask_b32_e32 v44, v44, v45, vcc
	v_sqrt_f32_e32 v45, v44
	s_nop 0
	v_add_u32_e32 v50, -1, v45
	v_fma_f32 v51, -v50, v45, v44
	v_cmp_ge_f32_e64 s[6:7], 0, v51
	v_add_u32_e32 v51, 1, v45
	s_nop 0
	v_cndmask_b32_e64 v50, v45, v50, s[6:7]
	v_fma_f32 v45, -v51, v45, v44
	v_cmp_lt_f32_e64 s[6:7], 0, v45
	s_nop 1
	v_cndmask_b32_e64 v45, v50, v51, s[6:7]
	v_mul_f32_e32 v50, 0x37800000, v45
	v_cndmask_b32_e32 v45, v45, v50, vcc
	v_cmp_class_f32_e32 vcc, v44, v253
	s_nop 1
	v_cndmask_b32_e32 v44, v45, v44, vcc
	v_div_scale_f32 v45, s[6:7], v44, v44, 1.0
	v_rcp_f32_e32 v50, v45
	s_nop 0
	v_fma_f32 v51, -v45, v50, 1.0
	v_fmac_f32_e32 v50, v51, v50
	v_div_scale_f32 v51, vcc, 1.0, v44, 1.0
	v_mul_f32_e32 v56, v51, v50
	v_fma_f32 v57, -v45, v56, v51
	v_fmac_f32_e32 v56, v57, v50
	v_fma_f32 v45, -v45, v56, v51
	v_div_fmas_f32 v45, v45, v50, v56
	v_div_fixup_f32 v44, v45, v44, 1.0
	v_lshlrev_b32_e32 v50, 16, v38
	v_and_b32_e32 v51, 0xffff0000, v38
	v_lshlrev_b32_e32 v38, 16, v39
	v_and_b32_e32 v39, 0xffff0000, v39
	v_pk_mul_f32 v[56:57], v[84:85], v[44:45] op_sel_hi:[1,0]
	v_pk_mul_f32 v[44:45], v[82:83], v[44:45] op_sel_hi:[1,0]
	s_nop 0
	v_pk_mul_f32 v[38:39], v[44:45], v[38:39]
	v_pk_mul_f32 v[44:45], v[56:57], v[50:51]
	s_nop 0
	v_cvt_pk_bf16_f32 v44, v44, v45
	v_cvt_pk_bf16_f32 v45, v38, v39
	v_add_f32_dpp v38, v158, v158 quad_perm:[1,0,3,2] row_mask:0xf bank_mask:0xf bound_ctrl:1
	global_store_dwordx2 v[70:71], v[44:45], off offset:2048
	s_nop 0
	v_add_f32_dpp v38, v38, v38 quad_perm:[2,3,0,1] row_mask:0xf bank_mask:0xf bound_ctrl:1
	s_nop 1
	v_add_f32_dpp v38, v38, v38 row_half_mirror row_mask:0xf bank_mask:0xf bound_ctrl:1
	s_nop 1
	v_add_f32_dpp v38, v38, v38 row_mirror row_mask:0xf bank_mask:0xf bound_ctrl:1
	s_nop 0
	v_readlane_b32 s9, v38, 16
	v_readlane_b32 s11, v38, 48
	v_readlane_b32 s6, v38, 0
	v_readlane_b32 s7, v38, 32
	v_mov_b32_e32 v38, s9
	v_mov_b32_e32 v39, s11
	v_pk_add_f32 v[38:39], s[6:7], v[38:39]
	s_nop 0
	v_add_f32_e32 v38, v38, v39
	v_fmamk_f32 v38, v38, 0x3b800000, v252
	v_cmp_gt_f32_e32 vcc, s55, v38
	v_mul_f32_e32 v39, 0x4f800000, v38
	s_nop 0
	v_cndmask_b32_e32 v38, v38, v39, vcc
	v_sqrt_f32_e32 v39, v38
	s_nop 0
	v_add_u32_e32 v44, -1, v39
	v_fma_f32 v45, -v44, v39, v38
	v_cmp_ge_f32_e64 s[6:7], 0, v45
	v_add_u32_e32 v45, 1, v39
	s_nop 0
	v_cndmask_b32_e64 v44, v39, v44, s[6:7]
	v_fma_f32 v39, -v45, v39, v38
	v_cmp_lt_f32_e64 s[6:7], 0, v39
	s_nop 1
	v_cndmask_b32_e64 v39, v44, v45, s[6:7]
	v_mul_f32_e32 v44, 0x37800000, v39
	v_cndmask_b32_e32 v39, v39, v44, vcc
	v_cmp_class_f32_e32 vcc, v38, v253
	s_nop 1
	v_cndmask_b32_e32 v38, v39, v38, vcc
	v_div_scale_f32 v39, s[6:7], v38, v38, 1.0
	v_rcp_f32_e32 v44, v39
	s_nop 0
	v_fma_f32 v45, -v39, v44, 1.0
	v_fmac_f32_e32 v44, v45, v44
	v_div_scale_f32 v45, vcc, 1.0, v38, 1.0
	v_mul_f32_e32 v50, v45, v44
	v_fma_f32 v51, -v39, v50, v45
	v_fmac_f32_e32 v50, v51, v44
	v_fma_f32 v39, -v39, v50, v45
	v_div_fmas_f32 v39, v39, v44, v50
	v_div_fixup_f32 v38, v39, v38, 1.0
	v_lshlrev_b32_e32 v44, 16, v34
	v_and_b32_e32 v45, 0xffff0000, v34
	v_lshlrev_b32_e32 v34, 16, v35
	v_and_b32_e32 v35, 0xffff0000, v35
	v_pk_mul_f32 v[50:51], v[80:81], v[38:39] op_sel_hi:[1,0]
	v_pk_mul_f32 v[38:39], v[78:79], v[38:39] op_sel_hi:[1,0]
	s_nop 0
	v_pk_mul_f32 v[34:35], v[38:39], v[34:35]
	v_pk_mul_f32 v[38:39], v[50:51], v[44:45]
	s_nop 0
	v_cvt_pk_bf16_f32 v38, v38, v39
	v_cvt_pk_bf16_f32 v39, v34, v35
	v_add_f32_dpp v34, v157, v157 quad_perm:[1,0,3,2] row_mask:0xf bank_mask:0xf bound_ctrl:1
	global_store_dwordx2 v[70:71], v[38:39], off offset:2560
	s_nop 0
	v_add_f32_dpp v34, v34, v34 quad_perm:[2,3,0,1] row_mask:0xf bank_mask:0xf bound_ctrl:1
	s_nop 1
	v_add_f32_dpp v34, v34, v34 row_half_mirror row_mask:0xf bank_mask:0xf bound_ctrl:1
	s_nop 1
	v_add_f32_dpp v34, v34, v34 row_mirror row_mask:0xf bank_mask:0xf bound_ctrl:1
	s_nop 0
	v_readlane_b32 s9, v34, 16
	v_readlane_b32 s11, v34, 48
	v_readlane_b32 s6, v34, 0
	v_readlane_b32 s7, v34, 32
	v_mov_b32_e32 v34, s9
	v_mov_b32_e32 v35, s11
	v_pk_add_f32 v[34:35], s[6:7], v[34:35]
	s_nop 0
	v_add_f32_e32 v34, v34, v35
	v_fmamk_f32 v34, v34, 0x3b800000, v252
	v_cmp_gt_f32_e32 vcc, s55, v34
	v_mul_f32_e32 v35, 0x4f800000, v34
	s_nop 0
	v_cndmask_b32_e32 v34, v34, v35, vcc
	v_sqrt_f32_e32 v35, v34
	s_nop 0
	v_add_u32_e32 v38, -1, v35
	v_fma_f32 v39, -v38, v35, v34
	v_cmp_ge_f32_e64 s[6:7], 0, v39
	v_add_u32_e32 v39, 1, v35
	s_nop 0
	v_cndmask_b32_e64 v38, v35, v38, s[6:7]
; template <bool HG>
; __device__ __forceinline__ void readout_phase2(const Args& a, Frame& F, const float* gain, int nrows) {
;     ...
;     const bool cx = ML + nw < nrows;
;     RO_LOAD(f2, b2, g2, cx ? ML + nw : nw + 7 * 2048);
;     RO_FINISH(f0, b0, g0, nw + 6 * 2048);
	v_fma_f32 v35, -v39, v35, v34
	v_cmp_lt_f32_e64 s[6:7], 0, v35
	s_nop 1
	v_cndmask_b32_e64 v35, v38, v39, s[6:7]
	v_mul_f32_e32 v38, 0x37800000, v35
	v_cndmask_b32_e32 v35, v35, v38, vcc
	v_cmp_class_f32_e32 vcc, v34, v253
	s_nop 1
	v_cndmask_b32_e32 v34, v35, v34, vcc
	v_div_scale_f32 v35, s[6:7], v34, v34, 1.0
	v_rcp_f32_e32 v38, v35
	s_nop 0
	v_fma_f32 v39, -v35, v38, 1.0
	v_fmac_f32_e32 v38, v39, v38
	v_div_scale_f32 v39, vcc, 1.0, v34, 1.0
	v_mul_f32_e32 v44, v39, v38
	v_fma_f32 v45, -v35, v44, v39
	v_fmac_f32_e32 v44, v45, v38
	v_fma_f32 v35, -v35, v44, v39
	v_div_fmas_f32 v35, v35, v38, v44
	v_div_fixup_f32 v34, v35, v34, 1.0
	v_lshlrev_b32_e32 v38, 16, v30
	v_and_b32_e32 v39, 0xffff0000, v30
	v_lshlrev_b32_e32 v30, 16, v31
	v_and_b32_e32 v31, 0xffff0000, v31
	v_pk_mul_f32 v[44:45], v[76:77], v[34:35] op_sel_hi:[1,0]
	v_pk_mul_f32 v[34:35], v[74:75], v[34:35] op_sel_hi:[1,0]
	s_nop 0
	v_pk_mul_f32 v[30:31], v[34:35], v[30:31]
	v_pk_mul_f32 v[34:35], v[44:45], v[38:39]
	s_nop 0
	v_cvt_pk_bf16_f32 v34, v34, v35
	v_cvt_pk_bf16_f32 v35, v30, v31
	v_add_f32_dpp v30, v156, v156 quad_perm:[1,0,3,2] row_mask:0xf bank_mask:0xf bound_ctrl:1
	global_store_dwordx2 v[70:71], v[34:35], off offset:3072
	s_nop 0
	v_add_f32_dpp v30, v30, v30 quad_perm:[2,3,0,1] row_mask:0xf bank_mask:0xf bound_ctrl:1
	s_nop 1
	v_add_f32_dpp v30, v30, v30 row_half_mirror row_mask:0xf bank_mask:0xf bound_ctrl:1
	s_nop 1
	v_add_f32_dpp v30, v30, v30 row_mirror row_mask:0xf bank_mask:0xf bound_ctrl:1
	s_nop 0
	v_readlane_b32 s9, v30, 16
	v_readlane_b32 s11, v30, 48
	v_readlane_b32 s6, v30, 0
	v_readlane_b32 s7, v30, 32
	v_mov_b32_e32 v30, s9
	v_mov_b32_e32 v31, s11
	v_pk_add_f32 v[30:31], s[6:7], v[30:31]
	s_nop 0
	v_add_f32_e32 v30, v30, v31
	v_fmamk_f32 v30, v30, 0x3b800000, v252
	v_cmp_gt_f32_e32 vcc, s55, v30
	v_mul_f32_e32 v31, 0x4f800000, v30
	s_nop 0
	v_cndmask_b32_e32 v30, v30, v31, vcc
	v_sqrt_f32_e32 v31, v30
	s_nop 0
	v_add_u32_e32 v34, -1, v31
	v_fma_f32 v35, -v34, v31, v30
	v_cmp_ge_f32_e64 s[6:7], 0, v35
	v_add_u32_e32 v35, 1, v31
	s_nop 0
	v_cndmask_b32_e64 v34, v31, v34, s[6:7]
	v_fma_f32 v31, -v35, v31, v30
	v_cmp_lt_f32_e64 s[6:7], 0, v31
	s_nop 1
	v_cndmask_b32_e64 v31, v34, v35, s[6:7]
	v_mul_f32_e32 v34, 0x37800000, v31
	v_cndmask_b32_e32 v31, v31, v34, vcc
	v_cmp_class_f32_e32 vcc, v30, v253
	s_nop 1
	v_cndmask_b32_e32 v30, v31, v30, vcc
	v_div_scale_f32 v31, s[6:7], v30, v30, 1.0
	v_rcp_f32_e32 v34, v31
	s_cselect_b32 s6, s82, s10
	s_ashr_i32 s7, s6, 31
	s_lshl_b64 s[48:49], s[6:7], 12
	v_fma_f32 v35, -v31, v34, 1.0
	v_fmac_f32_e32 v34, v35, v34
	v_div_scale_f32 v35, vcc, 1.0, v30, 1.0
	v_mul_f32_e32 v38, v35, v34
	v_fma_f32 v39, -v31, v38, v35
	v_fmac_f32_e32 v38, v39, v34
	v_fma_f32 v31, -v31, v38, v35
	v_div_fmas_f32 v31, v31, v34, v38
	v_div_fixup_f32 v30, v31, v30, 1.0
	s_waitcnt vmcnt(62)
	v_lshlrev_b32_e32 v34, 16, v26
	v_and_b32_e32 v35, 0xffff0000, v26
	v_lshlrev_b32_e32 v26, 16, v27
	v_and_b32_e32 v27, 0xffff0000, v27
	v_pk_mul_f32 v[38:39], v[72:73], v[30:31] op_sel_hi:[1,0]
	v_pk_mul_f32 v[30:31], v[68:69], v[30:31] op_sel_hi:[1,0]
	v_lshl_add_u64 v[6:7], v[6:7], 0, s[48:49]
	v_pk_mul_f32 v[26:27], v[30:31], v[26:27]
	v_pk_mul_f32 v[30:31], v[38:39], v[34:35]
	v_lshl_add_u64 v[4:5], v[4:5], 0, s[48:49]
	v_cvt_pk_bf16_f32 v30, v30, v31
	v_cvt_pk_bf16_f32 v31, v26, v27
	global_store_dwordx2 v[70:71], v[30:31], off offset:3584
	v_lshlrev_b32_e32 v26, 16, v148
	v_and_b32_e32 v27, 0xffff0000, v148
	s_waitcnt vmcnt(62)
	v_lshlrev_b32_e32 v30, 16, v142
	v_and_b32_e32 v31, 0xffff0000, v142
	v_pk_add_f32 v[140:141], v[26:27], v[30:31]
	v_lshlrev_b32_e32 v26, 16, v149
	v_and_b32_e32 v27, 0xffff0000, v149
	v_lshlrev_b32_e32 v30, 16, v143
	v_and_b32_e32 v31, 0xffff0000, v143
	v_pk_add_f32 v[142:143], v[26:27], v[30:31]
	v_mov_b32_e32 v30, v141
	v_mov_b32_e32 v31, v143
	v_mov_b32_e32 v26, v140
	v_mov_b32_e32 v27, v142
	v_pk_mul_f32 v[30:31], v[30:31], v[30:31]
	v_lshl_add_u64 v[4:5], v[4:5], 0, v[0:1]
	v_pk_fma_f32 v[26:27], v[26:27], v[26:27], v[30:31]
	s_waitcnt vmcnt(59)
	v_lshlrev_b32_e32 v30, 16, v130
	v_add_f32_e32 v34, v26, v27
	v_lshlrev_b32_e32 v26, 16, v136
	v_and_b32_e32 v27, 0xffff0000, v136
	v_and_b32_e32 v31, 0xffff0000, v130
	v_pk_add_f32 v[134:135], v[26:27], v[30:31]
	v_lshlrev_b32_e32 v26, 16, v137
	v_and_b32_e32 v27, 0xffff0000, v137
	v_lshlrev_b32_e32 v30, 16, v131
	v_and_b32_e32 v31, 0xffff0000, v131
	v_pk_add_f32 v[136:137], v[26:27], v[30:31]
	v_mov_b32_e32 v30, v135
	v_mov_b32_e32 v31, v137
	v_mov_b32_e32 v26, v134
	v_mov_b32_e32 v27, v136
	v_pk_mul_f32 v[30:31], v[30:31], v[30:31]
	s_cmp_ge_i32 s82, s47
	v_pk_fma_f32 v[26:27], v[26:27], v[26:27], v[30:31]
	s_waitcnt vmcnt(56)
	v_lshlrev_b32_e32 v30, 16, v122
	v_add_f32_e32 v35, v26, v27
	v_lshlrev_b32_e32 v26, 16, v126
	v_and_b32_e32 v27, 0xffff0000, v126
	v_and_b32_e32 v31, 0xffff0000, v122
	v_pk_add_f32 v[130:131], v[26:27], v[30:31]
	v_lshlrev_b32_e32 v26, 16, v127
	v_and_b32_e32 v27, 0xffff0000, v127
	v_lshlrev_b32_e32 v30, 16, v123
	v_and_b32_e32 v31, 0xffff0000, v123
	v_pk_add_f32 v[122:123], v[26:27], v[30:31]
	v_mov_b32_e32 v30, v131
	v_mov_b32_e32 v31, v123
	v_mov_b32_e32 v26, v130
	v_mov_b32_e32 v27, v122
	v_pk_mul_f32 v[30:31], v[30:31], v[30:31]
	s_nop 0
	v_pk_fma_f32 v[26:27], v[26:27], v[26:27], v[30:31]
	s_waitcnt vmcnt(53)
	v_lshlrev_b32_e32 v30, 16, v118
	v_add_f32_e32 v38, v26, v27
	v_lshlrev_b32_e32 v26, 16, v114
	v_and_b32_e32 v27, 0xffff0000, v114
	v_and_b32_e32 v31, 0xffff0000, v118
	v_pk_add_f32 v[86:87], v[26:27], v[30:31]
	v_lshlrev_b32_e32 v26, 16, v115
	v_and_b32_e32 v27, 0xffff0000, v115
	v_lshlrev_b32_e32 v30, 16, v119
	v_and_b32_e32 v31, 0xffff0000, v119
	v_pk_add_f32 v[88:89], v[26:27], v[30:31]
	v_mov_b32_e32 v30, v87
	v_mov_b32_e32 v31, v89
	v_mov_b32_e32 v26, v86
	v_mov_b32_e32 v27, v88
	v_pk_mul_f32 v[30:31], v[30:31], v[30:31]
	s_nop 0
	v_pk_fma_f32 v[26:27], v[26:27], v[26:27], v[30:31]
	s_waitcnt vmcnt(50)
	v_lshlrev_b32_e32 v30, 16, v106
	v_add_f32_e32 v39, v26, v27
	v_lshlrev_b32_e32 v26, 16, v110
	v_and_b32_e32 v27, 0xffff0000, v110
	v_and_b32_e32 v31, 0xffff0000, v106
	v_pk_add_f32 v[78:79], v[26:27], v[30:31]
	v_lshlrev_b32_e32 v26, 16, v111
	v_and_b32_e32 v27, 0xffff0000, v111
	v_lshlrev_b32_e32 v30, 16, v107
	v_and_b32_e32 v31, 0xffff0000, v107
	v_pk_add_f32 v[80:81], v[26:27], v[30:31]
	v_mov_b32_e32 v30, v79
	v_mov_b32_e32 v31, v81
	v_mov_b32_e32 v26, v78
	v_mov_b32_e32 v27, v80
	v_pk_mul_f32 v[30:31], v[30:31], v[30:31]
	s_nop 0
	v_pk_fma_f32 v[26:27], v[26:27], v[26:27], v[30:31]
	s_waitcnt vmcnt(47)
	v_lshlrev_b32_e32 v30, 16, v98
	v_add_f32_e32 v56, v26, v27
	v_lshlrev_b32_e32 v26, 16, v102
	v_and_b32_e32 v27, 0xffff0000, v102
	v_and_b32_e32 v31, 0xffff0000, v98
	v_pk_add_f32 v[70:71], v[26:27], v[30:31]
	v_lshlrev_b32_e32 v26, 16, v103
	v_and_b32_e32 v27, 0xffff0000, v103
	v_lshlrev_b32_e32 v30, 16, v99
	v_and_b32_e32 v31, 0xffff0000, v99
	v_pk_add_f32 v[72:73], v[26:27], v[30:31]
	v_mov_b32_e32 v30, v71
	v_mov_b32_e32 v31, v73
	v_mov_b32_e32 v26, v70
	v_mov_b32_e32 v27, v72
	v_pk_mul_f32 v[30:31], v[30:31], v[30:31]
	s_nop 0
	v_pk_fma_f32 v[26:27], v[26:27], v[26:27], v[30:31]
	s_waitcnt vmcnt(44)
	v_lshlrev_b32_e32 v30, 16, v90
	v_add_f32_e32 v57, v26, v27
	v_lshlrev_b32_e32 v26, 16, v94
	v_and_b32_e32 v27, 0xffff0000, v94
	v_and_b32_e32 v31, 0xffff0000, v90
	v_pk_add_f32 v[62:63], v[26:27], v[30:31]
	v_lshlrev_b32_e32 v26, 16, v95
	v_and_b32_e32 v27, 0xffff0000, v95
	v_lshlrev_b32_e32 v30, 16, v91
	v_and_b32_e32 v31, 0xffff0000, v91
	v_pk_add_f32 v[68:69], v[26:27], v[30:31]
	v_mov_b32_e32 v30, v63
	v_mov_b32_e32 v31, v69
	v_mov_b32_e32 v26, v62
	v_mov_b32_e32 v27, v68
	v_pk_mul_f32 v[30:31], v[30:31], v[30:31]
	s_nop 0
	v_pk_fma_f32 v[26:27], v[26:27], v[26:27], v[30:31]
	s_waitcnt vmcnt(41)
	v_lshlrev_b32_e32 v30, 16, v64
	v_add_f32_e32 v74, v26, v27
	v_lshlrev_b32_e32 v26, 16, v58
	v_and_b32_e32 v27, 0xffff0000, v58
	v_and_b32_e32 v31, 0xffff0000, v64
	v_pk_add_f32 v[44:45], v[26:27], v[30:31]
	v_lshlrev_b32_e32 v26, 16, v59
	v_and_b32_e32 v27, 0xffff0000, v59
	v_lshlrev_b32_e32 v30, 16, v65
	v_and_b32_e32 v31, 0xffff0000, v65
	v_pk_add_f32 v[50:51], v[26:27], v[30:31]
	v_mov_b32_e32 v30, v45
	v_mov_b32_e32 v31, v51
	v_mov_b32_e32 v26, v44
	v_mov_b32_e32 v27, v50
	v_pk_mul_f32 v[30:31], v[30:31], v[30:31]
	s_nop 0
	v_pk_fma_f32 v[26:27], v[26:27], v[26:27], v[30:31]
	s_waitcnt vmcnt(30)
	v_and_b32_e32 v31, 0xffff0000, v138
	v_add_f32_e32 v30, v26, v27
	v_add_f32_dpp v26, v34, v34 quad_perm:[1,0,3,2] row_mask:0xf bank_mask:0xf bound_ctrl:1
	s_nop 1
	v_add_f32_dpp v26, v26, v26 quad_perm:[2,3,0,1] row_mask:0xf bank_mask:0xf bound_ctrl:1
	s_nop 1
	v_add_f32_dpp v26, v26, v26 row_half_mirror row_mask:0xf bank_mask:0xf bound_ctrl:1
	s_nop 1
	v_add_f32_dpp v26, v26, v26 row_mirror row_mask:0xf bank_mask:0xf bound_ctrl:1
	s_nop 0
	v_readlane_b32 s8, v26, 16
	v_readlane_b32 s9, v26, 48
	v_readlane_b32 s6, v26, 0
	v_readlane_b32 s7, v26, 32
	v_mov_b32_e32 v26, s8
	v_mov_b32_e32 v27, s9
	v_pk_add_f32 v[26:27], s[6:7], v[26:27]
	s_nop 0
	v_add_f32_e32 v26, v26, v27
	v_fmamk_f32 v26, v26, 0x3b800000, v252
	v_cmp_gt_f32_e32 vcc, s55, v26
	v_mul_f32_e32 v27, 0x4f800000, v26
	s_nop 0
	v_cndmask_b32_e32 v211, v26, v27, vcc
	v_add_f32_dpp v26, v35, v35 quad_perm:[1,0,3,2] row_mask:0xf bank_mask:0xf bound_ctrl:1
	v_sqrt_f32_e32 v214, v211
	s_nop 0
	v_add_f32_dpp v26, v26, v26 quad_perm:[2,3,0,1] row_mask:0xf bank_mask:0xf bound_ctrl:1
	v_add_u32_e32 v216, -1, v214
	s_nop 0
	v_add_f32_dpp v26, v26, v26 row_half_mirror row_mask:0xf bank_mask:0xf bound_ctrl:1
	v_add_u32_e32 v213, 1, v214
	v_fma_f32 v178, -v216, v214, v211
	v_add_f32_dpp v26, v26, v26 row_mirror row_mask:0xf bank_mask:0xf bound_ctrl:1
	v_fma_f32 v179, -v213, v214, v211
	v_readlane_b32 s8, v26, 16
	v_readlane_b32 s9, v26, 48
	v_readlane_b32 s6, v26, 0
	v_readlane_b32 s7, v26, 32
	v_mov_b32_e32 v26, s8
	v_mov_b32_e32 v27, s9
	v_pk_add_f32 v[26:27], s[6:7], v[26:27]
	s_nop 0
	v_add_f32_e32 v26, v26, v27
	v_fmamk_f32 v26, v26, 0x3b800000, v252
	v_cmp_gt_f32_e64 s[30:31], s55, v26
	v_mul_f32_e32 v27, 0x4f800000, v26
	s_nop 0
	v_cndmask_b32_e64 v202, v26, v27, s[30:31]
	v_add_f32_dpp v26, v38, v38 quad_perm:[1,0,3,2] row_mask:0xf bank_mask:0xf bound_ctrl:1
	v_sqrt_f32_e32 v205, v202
	s_nop 0
	v_add_f32_dpp v26, v26, v26 quad_perm:[2,3,0,1] row_mask:0xf bank_mask:0xf bound_ctrl:1
	v_add_u32_e32 v209, -1, v205
	s_nop 0
	v_add_f32_dpp v26, v26, v26 row_half_mirror row_mask:0xf bank_mask:0xf bound_ctrl:1
	v_add_u32_e32 v207, 1, v205
	s_nop 0
	v_add_f32_dpp v26, v26, v26 row_mirror row_mask:0xf bank_mask:0xf bound_ctrl:1
	s_nop 0
	v_readlane_b32 s8, v26, 16
	v_readlane_b32 s9, v26, 48
	v_readlane_b32 s6, v26, 0
	v_readlane_b32 s7, v26, 32
	v_mov_b32_e32 v26, s8
	v_mov_b32_e32 v27, s9
	v_pk_add_f32 v[26:27], s[6:7], v[26:27]
	s_nop 0
	v_add_f32_e32 v26, v26, v27
	v_fmamk_f32 v26, v26, 0x3b800000, v252
	v_cmp_gt_f32_e64 s[26:27], s55, v26
	v_mul_f32_e32 v27, 0x4f800000, v26
	s_nop 0
	v_cndmask_b32_e64 v194, v26, v27, s[26:27]
	v_add_f32_dpp v26, v39, v39 quad_perm:[1,0,3,2] row_mask:0xf bank_mask:0xf bound_ctrl:1
	v_sqrt_f32_e32 v197, v194
	s_nop 0
	v_add_f32_dpp v26, v26, v26 quad_perm:[2,3,0,1] row_mask:0xf bank_mask:0xf bound_ctrl:1
	v_add_u32_e32 v199, -1, v197
	s_nop 0
	v_add_f32_dpp v26, v26, v26 row_half_mirror row_mask:0xf bank_mask:0xf bound_ctrl:1
	v_add_u32_e32 v196, 1, v197
	s_nop 0
	v_add_f32_dpp v26, v26, v26 row_mirror row_mask:0xf bank_mask:0xf bound_ctrl:1
	s_nop 0
	v_readlane_b32 s8, v26, 16
	v_readlane_b32 s9, v26, 48
	v_readlane_b32 s6, v26, 0
	v_readlane_b32 s7, v26, 32
	v_mov_b32_e32 v26, s8
	v_mov_b32_e32 v27, s9
	v_pk_add_f32 v[26:27], s[6:7], v[26:27]
	s_nop 0
	v_add_f32_e32 v26, v26, v27
	v_fmamk_f32 v26, v26, 0x3b800000, v252
	v_cmp_gt_f32_e64 s[22:23], s55, v26
	v_mul_f32_e32 v27, 0x4f800000, v26
	s_nop 0
	v_cndmask_b32_e64 v186, v26, v27, s[22:23]
	v_add_f32_dpp v26, v56, v56 quad_perm:[1,0,3,2] row_mask:0xf bank_mask:0xf bound_ctrl:1
	v_sqrt_f32_e32 v189, v186
	s_nop 0
	v_add_f32_dpp v26, v26, v26 quad_perm:[2,3,0,1] row_mask:0xf bank_mask:0xf bound_ctrl:1
	v_add_u32_e32 v193, -1, v189
	s_nop 0
	v_add_f32_dpp v26, v26, v26 row_half_mirror row_mask:0xf bank_mask:0xf bound_ctrl:1
	v_add_u32_e32 v191, 1, v189
	s_nop 0
	v_add_f32_dpp v26, v26, v26 row_mirror row_mask:0xf bank_mask:0xf bound_ctrl:1
	s_nop 0
	v_readlane_b32 s8, v26, 16
	v_readlane_b32 s9, v26, 48
	v_readlane_b32 s6, v26, 0
	v_readlane_b32 s7, v26, 32
	v_mov_b32_e32 v26, s8
	v_mov_b32_e32 v27, s9
	v_pk_add_f32 v[26:27], s[6:7], v[26:27]
	s_nop 0
	v_add_f32_e32 v26, v26, v27
	v_fmamk_f32 v26, v26, 0x3b800000, v252
	v_cmp_gt_f32_e64 s[18:19], s55, v26
	v_mul_f32_e32 v27, 0x4f800000, v26
	s_nop 0
	v_cndmask_b32_e64 v172, v26, v27, s[18:19]
	v_add_f32_dpp v26, v57, v57 quad_perm:[1,0,3,2] row_mask:0xf bank_mask:0xf bound_ctrl:1
	v_sqrt_f32_e32 v175, v172
	s_nop 0
	v_add_f32_dpp v26, v26, v26 quad_perm:[2,3,0,1] row_mask:0xf bank_mask:0xf bound_ctrl:1
	v_add_u32_e32 v177, -1, v175
	s_nop 0
	v_add_f32_dpp v26, v26, v26 row_half_mirror row_mask:0xf bank_mask:0xf bound_ctrl:1
	v_add_u32_e32 v174, 1, v175
	s_nop 0
	v_add_f32_dpp v26, v26, v26 row_mirror row_mask:0xf bank_mask:0xf bound_ctrl:1
	s_nop 0
	v_readlane_b32 s8, v26, 16
	v_readlane_b32 s9, v26, 48
	v_readlane_b32 s6, v26, 0
	v_readlane_b32 s7, v26, 32
	v_mov_b32_e32 v26, s8
	v_mov_b32_e32 v27, s9
	v_pk_add_f32 v[26:27], s[6:7], v[26:27]
	s_nop 0
	v_add_f32_e32 v26, v26, v27
	v_fmamk_f32 v26, v26, 0x3b800000, v252
	v_cmp_gt_f32_e64 s[14:15], s55, v26
	v_mul_f32_e32 v27, 0x4f800000, v26
	s_nop 0
	v_cndmask_b32_e64 v164, v26, v27, s[14:15]
	v_add_f32_dpp v26, v74, v74 quad_perm:[1,0,3,2] row_mask:0xf bank_mask:0xf bound_ctrl:1
	v_sqrt_f32_e32 v167, v164
	s_nop 0
	v_add_f32_dpp v26, v26, v26 quad_perm:[2,3,0,1] row_mask:0xf bank_mask:0xf bound_ctrl:1
	v_add_u32_e32 v171, -1, v167
	s_nop 0
	v_add_f32_dpp v26, v26, v26 row_half_mirror row_mask:0xf bank_mask:0xf bound_ctrl:1
	v_add_u32_e32 v169, 1, v167
	s_nop 0
	v_add_f32_dpp v26, v26, v26 row_mirror row_mask:0xf bank_mask:0xf bound_ctrl:1
	s_nop 0
	v_readlane_b32 s8, v26, 16
	v_readlane_b32 s9, v26, 48
	v_readlane_b32 s6, v26, 0
	v_readlane_b32 s7, v26, 32
	v_mov_b32_e32 v26, s8
	v_mov_b32_e32 v27, s9
	v_pk_add_f32 v[26:27], s[6:7], v[26:27]
	s_nop 0
	v_add_f32_e32 v26, v26, v27
	v_fmamk_f32 v26, v26, 0x3b800000, v252
	v_cmp_gt_f32_e64 s[10:11], s55, v26
	v_mul_f32_e32 v27, 0x4f800000, v26
	s_nop 0
	v_cndmask_b32_e64 v156, v26, v27, s[10:11]
	v_add_f32_dpp v26, v30, v30 quad_perm:[1,0,3,2] row_mask:0xf bank_mask:0xf bound_ctrl:1
	v_lshlrev_b32_e32 v30, 16, v138
	v_sqrt_f32_e32 v159, v156
	v_add_f32_dpp v26, v26, v26 quad_perm:[2,3,0,1] row_mask:0xf bank_mask:0xf bound_ctrl:1
	v_add_u32_e32 v161, -1, v159
	s_nop 0
	v_add_f32_dpp v26, v26, v26 row_half_mirror row_mask:0xf bank_mask:0xf bound_ctrl:1
	v_add_u32_e32 v158, 1, v159
	s_nop 0
	v_add_f32_dpp v26, v26, v26 row_mirror row_mask:0xf bank_mask:0xf bound_ctrl:1
	s_nop 0
	v_readlane_b32 s8, v26, 16
	v_readlane_b32 s9, v26, 48
	v_readlane_b32 s6, v26, 0
	v_readlane_b32 s7, v26, 32
	v_mov_b32_e32 v26, s8
	v_mov_b32_e32 v27, s9
	v_pk_add_f32 v[26:27], s[6:7], v[26:27]
	s_nop 0
	v_add_f32_e32 v26, v26, v27
	v_fmamk_f32 v26, v26, 0x3b800000, v252
	v_cmp_gt_f32_e64 s[6:7], s55, v26
	v_mul_f32_e32 v27, 0x4f800000, v26
	s_nop 0
	v_cndmask_b32_e64 v150, v26, v27, s[6:7]
	v_lshlrev_b32_e32 v26, 16, v144
	v_and_b32_e32 v27, 0xffff0000, v144
	v_pk_add_f32 v[126:127], v[26:27], v[30:31]
	v_lshlrev_b32_e32 v26, 16, v145
	v_and_b32_e32 v27, 0xffff0000, v145
	v_lshlrev_b32_e32 v30, 16, v139
	v_and_b32_e32 v31, 0xffff0000, v139
	v_pk_add_f32 v[138:139], v[26:27], v[30:31]
	v_mov_b32_e32 v30, v127
	v_mov_b32_e32 v31, v139
	v_mov_b32_e32 v26, v126
	v_mov_b32_e32 v27, v138
	v_pk_mul_f32 v[30:31], v[30:31], v[30:31]
	v_sqrt_f32_e32 v151, v150
	v_pk_fma_f32 v[26:27], v[26:27], v[26:27], v[30:31]
	s_waitcnt vmcnt(27)
	v_lshlrev_b32_e32 v30, 16, v128
	v_add_f32_e32 v34, v26, v27
	v_lshlrev_b32_e32 v26, 16, v132
	v_and_b32_e32 v27, 0xffff0000, v132
	v_and_b32_e32 v31, 0xffff0000, v128
	v_pk_add_f32 v[114:115], v[26:27], v[30:31]
	v_lshlrev_b32_e32 v26, 16, v133
	v_and_b32_e32 v27, 0xffff0000, v133
	v_lshlrev_b32_e32 v30, 16, v129
	v_and_b32_e32 v31, 0xffff0000, v129
	v_pk_add_f32 v[118:119], v[26:27], v[30:31]
	v_mov_b32_e32 v30, v115
	v_mov_b32_e32 v31, v119
	v_mov_b32_e32 v26, v114
	v_mov_b32_e32 v27, v118
	v_pk_mul_f32 v[30:31], v[30:31], v[30:31]
	v_add_u32_e32 v155, -1, v151
	v_pk_fma_f32 v[26:27], v[26:27], v[26:27], v[30:31]
	s_waitcnt vmcnt(24)
	v_lshlrev_b32_e32 v30, 16, v120
	v_add_f32_e32 v35, v26, v27
	v_lshlrev_b32_e32 v26, 16, v124
	v_and_b32_e32 v27, 0xffff0000, v124
	v_and_b32_e32 v31, 0xffff0000, v120
	v_pk_add_f32 v[102:103], v[26:27], v[30:31]
	v_lshlrev_b32_e32 v26, 16, v125
	v_and_b32_e32 v27, 0xffff0000, v125
	v_lshlrev_b32_e32 v30, 16, v121
	v_and_b32_e32 v31, 0xffff0000, v121
	v_pk_add_f32 v[106:107], v[26:27], v[30:31]
	v_mov_b32_e32 v30, v103
	v_mov_b32_e32 v31, v107
	v_mov_b32_e32 v26, v102
	v_mov_b32_e32 v27, v106
	v_pk_mul_f32 v[30:31], v[30:31], v[30:31]
	v_add_u32_e32 v153, 1, v151
	v_pk_fma_f32 v[26:27], v[26:27], v[26:27], v[30:31]
	s_waitcnt vmcnt(21)
	v_lshlrev_b32_e32 v30, 16, v116
	v_add_f32_e32 v38, v26, v27
	v_lshlrev_b32_e32 v26, 16, v112
	v_and_b32_e32 v27, 0xffff0000, v112
	v_and_b32_e32 v31, 0xffff0000, v116
	v_pk_add_f32 v[90:91], v[26:27], v[30:31]
	v_lshlrev_b32_e32 v26, 16, v113
	v_and_b32_e32 v27, 0xffff0000, v113
	v_lshlrev_b32_e32 v30, 16, v117
	v_and_b32_e32 v31, 0xffff0000, v117
	v_pk_add_f32 v[94:95], v[26:27], v[30:31]
	v_mov_b32_e32 v30, v91
	v_mov_b32_e32 v31, v95
	v_mov_b32_e32 v26, v90
	v_mov_b32_e32 v27, v94
	v_pk_mul_f32 v[30:31], v[30:31], v[30:31]
	s_nop 0
	v_pk_fma_f32 v[26:27], v[26:27], v[26:27], v[30:31]
	s_waitcnt vmcnt(18)
	v_lshlrev_b32_e32 v30, 16, v104
	v_add_f32_e32 v39, v26, v27
	v_lshlrev_b32_e32 v26, 16, v108
	v_and_b32_e32 v27, 0xffff0000, v108
	v_and_b32_e32 v31, 0xffff0000, v104
	v_pk_add_f32 v[82:83], v[26:27], v[30:31]
	v_lshlrev_b32_e32 v26, 16, v109
	v_and_b32_e32 v27, 0xffff0000, v109
	v_lshlrev_b32_e32 v30, 16, v105
	v_and_b32_e32 v31, 0xffff0000, v105
	v_pk_add_f32 v[84:85], v[26:27], v[30:31]
	v_mov_b32_e32 v30, v83
	v_mov_b32_e32 v31, v85
	v_mov_b32_e32 v26, v82
	v_mov_b32_e32 v27, v84
	v_pk_mul_f32 v[30:31], v[30:31], v[30:31]
	s_nop 0
	v_pk_fma_f32 v[26:27], v[26:27], v[26:27], v[30:31]
	s_waitcnt vmcnt(15)
	v_lshlrev_b32_e32 v30, 16, v96
	v_add_f32_e32 v58, v26, v27
	v_lshlrev_b32_e32 v26, 16, v100
	v_and_b32_e32 v27, 0xffff0000, v100
	v_and_b32_e32 v31, 0xffff0000, v96
	v_pk_add_f32 v[74:75], v[26:27], v[30:31]
	v_lshlrev_b32_e32 v26, 16, v101
	v_and_b32_e32 v27, 0xffff0000, v101
	v_lshlrev_b32_e32 v30, 16, v97
	v_and_b32_e32 v31, 0xffff0000, v97
	v_pk_add_f32 v[76:77], v[26:27], v[30:31]
	v_mov_b32_e32 v30, v75
	v_mov_b32_e32 v31, v77
	v_mov_b32_e32 v26, v74
	v_mov_b32_e32 v27, v76
	v_pk_mul_f32 v[30:31], v[30:31], v[30:31]
	s_nop 0
	v_pk_fma_f32 v[26:27], v[26:27], v[26:27], v[30:31]
	s_waitcnt vmcnt(12)
	v_lshlrev_b32_e32 v30, 16, v66
	v_add_f32_e32 v59, v26, v27
	v_lshlrev_b32_e32 v26, 16, v92
	v_and_b32_e32 v27, 0xffff0000, v92
	v_and_b32_e32 v31, 0xffff0000, v66
	v_pk_add_f32 v[64:65], v[26:27], v[30:31]
	v_lshlrev_b32_e32 v26, 16, v93
	v_and_b32_e32 v27, 0xffff0000, v93
	v_lshlrev_b32_e32 v30, 16, v67
	v_and_b32_e32 v31, 0xffff0000, v67
	v_pk_add_f32 v[66:67], v[26:27], v[30:31]
	v_mov_b32_e32 v30, v65
	v_mov_b32_e32 v31, v67
	v_mov_b32_e32 v26, v64
	v_mov_b32_e32 v27, v66
	v_pk_mul_f32 v[30:31], v[30:31], v[30:31]
	s_nop 0
	v_pk_fma_f32 v[26:27], v[26:27], v[26:27], v[30:31]
	s_waitcnt vmcnt(9)
	v_lshlrev_b32_e32 v30, 16, v60
	v_add_f32_e32 v92, v26, v27
	v_lshlrev_b32_e32 v26, 16, v54
	v_and_b32_e32 v27, 0xffff0000, v54
	v_and_b32_e32 v31, 0xffff0000, v60
	v_pk_add_f32 v[56:57], v[26:27], v[30:31]
	v_lshlrev_b32_e32 v26, 16, v55
	v_and_b32_e32 v27, 0xffff0000, v55
	v_lshlrev_b32_e32 v30, 16, v61
	v_and_b32_e32 v31, 0xffff0000, v61
	v_pk_add_f32 v[54:55], v[26:27], v[30:31]
	v_mov_b32_e32 v30, v57
	v_mov_b32_e32 v31, v55
	v_mov_b32_e32 v26, v56
	v_mov_b32_e32 v27, v54
	v_pk_mul_f32 v[30:31], v[30:31], v[30:31]
	v_lshl_add_u64 v[60:61], v[6:7], 0, v[0:1]
	v_pk_fma_f32 v[26:27], v[26:27], v[26:27], v[30:31]
	v_lshl_add_u64 v[6:7], v[8:9], 0, s[48:49]
	v_add_f32_e32 v30, v26, v27
	v_add_f32_dpp v26, v34, v34 quad_perm:[1,0,3,2] row_mask:0xf bank_mask:0xf bound_ctrl:1
	v_lshl_add_u64 v[148:149], v[6:7], 0, v[0:1]
	s_nop 0
	v_add_f32_dpp v26, v26, v26 quad_perm:[2,3,0,1] row_mask:0xf bank_mask:0xf bound_ctrl:1
	s_nop 1
	v_add_f32_dpp v26, v26, v26 row_half_mirror row_mask:0xf bank_mask:0xf bound_ctrl:1
	s_nop 1
	v_add_f32_dpp v26, v26, v26 row_mirror row_mask:0xf bank_mask:0xf bound_ctrl:1
	s_nop 0
	v_readlane_b32 s12, v26, 16
	v_readlane_b32 s13, v26, 48
	v_readlane_b32 s8, v26, 0
	v_readlane_b32 s9, v26, 32
	v_mov_b32_e32 v26, s12
	v_mov_b32_e32 v27, s13
	v_pk_add_f32 v[26:27], s[8:9], v[26:27]
	s_nop 0
	v_add_f32_e32 v26, v26, v27
	v_fmamk_f32 v26, v26, 0x3b800000, v252
	v_cmp_gt_f32_e64 s[36:37], s55, v26
	v_mul_f32_e32 v27, 0x4f800000, v26
	s_nop 0
	v_cndmask_b32_e64 v215, v26, v27, s[36:37]
	v_add_f32_dpp v26, v35, v35 quad_perm:[1,0,3,2] row_mask:0xf bank_mask:0xf bound_ctrl:1
	v_sqrt_f32_e32 v218, v215
	s_nop 0
	v_add_f32_dpp v26, v26, v26 quad_perm:[2,3,0,1] row_mask:0xf bank_mask:0xf bound_ctrl:1
	v_add_u32_e32 v219, -1, v218
	s_nop 0
	v_add_f32_dpp v26, v26, v26 row_half_mirror row_mask:0xf bank_mask:0xf bound_ctrl:1
	v_add_u32_e32 v217, 1, v218
	s_nop 0
	v_add_f32_dpp v26, v26, v26 row_mirror row_mask:0xf bank_mask:0xf bound_ctrl:1
	s_nop 0
	v_readlane_b32 s12, v26, 16
	v_readlane_b32 s13, v26, 48
	v_readlane_b32 s8, v26, 0
	v_readlane_b32 s9, v26, 32
	v_mov_b32_e32 v26, s12
	v_mov_b32_e32 v27, s13
	v_pk_add_f32 v[26:27], s[8:9], v[26:27]
	s_nop 0
	v_add_f32_e32 v26, v26, v27
	v_fmamk_f32 v26, v26, 0x3b800000, v252
	v_cmp_gt_f32_e64 s[34:35], s55, v26
	v_mul_f32_e32 v27, 0x4f800000, v26
	s_nop 0
	v_cndmask_b32_e64 v206, v26, v27, s[34:35]
	v_add_f32_dpp v26, v38, v38 quad_perm:[1,0,3,2] row_mask:0xf bank_mask:0xf bound_ctrl:1
	v_sqrt_f32_e32 v208, v206
	s_nop 0
	v_add_f32_dpp v26, v26, v26 quad_perm:[2,3,0,1] row_mask:0xf bank_mask:0xf bound_ctrl:1
	v_add_u32_e32 v212, -1, v208
	s_nop 0
	v_add_f32_dpp v26, v26, v26 row_half_mirror row_mask:0xf bank_mask:0xf bound_ctrl:1
	v_add_u32_e32 v210, 1, v208
	s_nop 0
	v_add_f32_dpp v26, v26, v26 row_mirror row_mask:0xf bank_mask:0xf bound_ctrl:1
	s_nop 0
	v_readlane_b32 s12, v26, 16
	v_readlane_b32 s13, v26, 48
	v_readlane_b32 s8, v26, 0
	v_readlane_b32 s9, v26, 32
	v_mov_b32_e32 v26, s12
	v_mov_b32_e32 v27, s13
	v_pk_add_f32 v[26:27], s[8:9], v[26:27]
	s_nop 0
	v_add_f32_e32 v26, v26, v27
	v_fmamk_f32 v26, v26, 0x3b800000, v252
	v_cmp_gt_f32_e64 s[28:29], s55, v26
; template <bool HG>
; __device__ __forceinline__ void readout_phase2(const Args& a, Frame& F, const float* gain, int nrows) {
;     ...
;     RO_LOAD(f2, b2, g2, cx ? ML + nw : nw + 7 * 2048);
	v_mul_f32_e32 v27, 0x4f800000, v26
	s_nop 0
	v_cndmask_b32_e64 v200, v26, v27, s[28:29]
	v_add_f32_dpp v26, v39, v39 quad_perm:[1,0,3,2] row_mask:0xf bank_mask:0xf bound_ctrl:1
	v_sqrt_f32_e32 v203, v200
	s_nop 0
	v_add_f32_dpp v26, v26, v26 quad_perm:[2,3,0,1] row_mask:0xf bank_mask:0xf bound_ctrl:1
	v_add_u32_e32 v204, -1, v203
	s_nop 0
	v_add_f32_dpp v26, v26, v26 row_half_mirror row_mask:0xf bank_mask:0xf bound_ctrl:1
	v_add_u32_e32 v201, 1, v203
	s_nop 0
	v_add_f32_dpp v26, v26, v26 row_mirror row_mask:0xf bank_mask:0xf bound_ctrl:1
	s_nop 0
	v_readlane_b32 s12, v26, 16
	v_readlane_b32 s13, v26, 48
	v_readlane_b32 s8, v26, 0
	v_readlane_b32 s9, v26, 32
	v_mov_b32_e32 v26, s12
	v_mov_b32_e32 v27, s13
	v_pk_add_f32 v[26:27], s[8:9], v[26:27]
	s_nop 0
	v_add_f32_e32 v26, v26, v27
	v_fmamk_f32 v26, v26, 0x3b800000, v252
	v_cmp_gt_f32_e64 s[24:25], s55, v26
	v_mul_f32_e32 v27, 0x4f800000, v26
	s_nop 0
	v_cndmask_b32_e64 v190, v26, v27, s[24:25]
	v_add_f32_dpp v26, v58, v58 quad_perm:[1,0,3,2] row_mask:0xf bank_mask:0xf bound_ctrl:1
	v_sqrt_f32_e32 v192, v190
	s_nop 0
	v_add_f32_dpp v26, v26, v26 quad_perm:[2,3,0,1] row_mask:0xf bank_mask:0xf bound_ctrl:1
	v_add_u32_e32 v198, -1, v192
	s_nop 0
	v_add_f32_dpp v26, v26, v26 row_half_mirror row_mask:0xf bank_mask:0xf bound_ctrl:1
	v_add_u32_e32 v195, 1, v192
	s_nop 0
	v_add_f32_dpp v26, v26, v26 row_mirror row_mask:0xf bank_mask:0xf bound_ctrl:1
	s_nop 0
	v_readlane_b32 s12, v26, 16
	v_readlane_b32 s13, v26, 48
	v_readlane_b32 s8, v26, 0
	v_readlane_b32 s9, v26, 32
	v_mov_b32_e32 v26, s12
	v_mov_b32_e32 v27, s13
	v_pk_add_f32 v[26:27], s[8:9], v[26:27]
	s_nop 0
	v_add_f32_e32 v26, v26, v27
	v_fmamk_f32 v26, v26, 0x3b800000, v252
	v_cmp_gt_f32_e64 s[20:21], s55, v26
	v_mul_f32_e32 v27, 0x4f800000, v26
	s_nop 0
	v_cndmask_b32_e64 v184, v26, v27, s[20:21]
	v_add_f32_dpp v26, v59, v59 quad_perm:[1,0,3,2] row_mask:0xf bank_mask:0xf bound_ctrl:1
	v_sqrt_f32_e32 v187, v184
	s_nop 0
	v_add_f32_dpp v26, v26, v26 quad_perm:[2,3,0,1] row_mask:0xf bank_mask:0xf bound_ctrl:1
	v_add_u32_e32 v188, -1, v187
	s_nop 0
	v_add_f32_dpp v26, v26, v26 row_half_mirror row_mask:0xf bank_mask:0xf bound_ctrl:1
	v_add_u32_e32 v185, 1, v187
	s_nop 0
	v_add_f32_dpp v26, v26, v26 row_mirror row_mask:0xf bank_mask:0xf bound_ctrl:1
	s_nop 0
	v_readlane_b32 s12, v26, 16
	v_readlane_b32 s13, v26, 48
	v_readlane_b32 s8, v26, 0
	v_readlane_b32 s9, v26, 32
	v_mov_b32_e32 v26, s12
	v_mov_b32_e32 v27, s13
	v_pk_add_f32 v[26:27], s[8:9], v[26:27]
	s_nop 0
	v_add_f32_e32 v26, v26, v27
	v_fmamk_f32 v26, v26, 0x3b800000, v252
	v_cmp_gt_f32_e64 s[16:17], s55, v26
	v_mul_f32_e32 v27, 0x4f800000, v26
	s_nop 0
	v_cndmask_b32_e64 v168, v26, v27, s[16:17]
	v_add_f32_dpp v26, v92, v92 quad_perm:[1,0,3,2] row_mask:0xf bank_mask:0xf bound_ctrl:1
	v_sqrt_f32_e32 v170, v168
	s_nop 0
	v_add_f32_dpp v26, v26, v26 quad_perm:[2,3,0,1] row_mask:0xf bank_mask:0xf bound_ctrl:1
	v_add_u32_e32 v176, -1, v170
	s_nop 0
	v_add_f32_dpp v26, v26, v26 row_half_mirror row_mask:0xf bank_mask:0xf bound_ctrl:1
	v_add_u32_e32 v173, 1, v170
	s_nop 0
	v_add_f32_dpp v26, v26, v26 row_mirror row_mask:0xf bank_mask:0xf bound_ctrl:1
	s_nop 0
	v_readlane_b32 s12, v26, 16
	v_readlane_b32 s13, v26, 48
	v_readlane_b32 s8, v26, 0
	v_readlane_b32 s9, v26, 32
	v_mov_b32_e32 v26, s12
	v_mov_b32_e32 v27, s13
	v_pk_add_f32 v[26:27], s[8:9], v[26:27]
	s_nop 0
	v_add_f32_e32 v26, v26, v27
	v_fmamk_f32 v26, v26, 0x3b800000, v252
	v_cmp_gt_f32_e64 s[12:13], s55, v26
	v_mul_f32_e32 v27, 0x4f800000, v26
	s_nop 0
	v_cndmask_b32_e64 v162, v26, v27, s[12:13]
	v_add_f32_dpp v26, v30, v30 quad_perm:[1,0,3,2] row_mask:0xf bank_mask:0xf bound_ctrl:1
	v_sqrt_f32_e32 v165, v162
	s_nop 0
	v_add_f32_dpp v26, v26, v26 quad_perm:[2,3,0,1] row_mask:0xf bank_mask:0xf bound_ctrl:1
	v_add_u32_e32 v166, -1, v165
	s_nop 0
	v_add_f32_dpp v26, v26, v26 row_half_mirror row_mask:0xf bank_mask:0xf bound_ctrl:1
	v_add_u32_e32 v163, 1, v165
	s_nop 0
	v_add_f32_dpp v26, v26, v26 row_mirror row_mask:0xf bank_mask:0xf bound_ctrl:1
	s_nop 0
	v_readlane_b32 s33, v26, 16
	v_readlane_b32 s44, v26, 48
	v_readlane_b32 s8, v26, 0
	v_readlane_b32 s9, v26, 32
	v_mov_b32_e32 v26, s33
	v_mov_b32_e32 v27, s44
	v_pk_add_f32 v[26:27], s[8:9], v[26:27]
	s_nop 0
	v_add_f32_e32 v26, v26, v27
	v_fmamk_f32 v26, v26, 0x3b800000, v252
	v_cmp_gt_f32_e64 s[8:9], s55, v26
	v_mul_f32_e32 v27, 0x4f800000, v26
	s_nop 0
	v_cndmask_b32_e64 v152, v26, v27, s[8:9]
	global_load_dwordx2 v[146:147], v[4:5], off
	global_load_dwordx2 v[144:145], v[60:61], off
	global_load_dwordx2 v[58:59], v[148:149], off
	global_load_dwordx2 v[132:133], v[4:5], off offset:512
	global_load_dwordx2 v[128:129], v[60:61], off offset:512
	global_load_dwordx2 v[38:39], v[148:149], off offset:512
	global_load_dwordx2 v[124:125], v[4:5], off offset:1024
	global_load_dwordx2 v[120:121], v[60:61], off offset:1024
	global_load_dwordx2 v[34:35], v[148:149], off offset:1024
	global_load_dwordx2 v[116:117], v[4:5], off offset:1536
	global_load_dwordx2 v[112:113], v[60:61], off offset:1536
	global_load_dwordx2 v[30:31], v[148:149], off offset:1536
	global_load_dwordx2 v[110:111], v[4:5], off offset:2048
	global_load_dwordx2 v[108:109], v[60:61], off offset:2048
	global_load_dwordx2 v[26:27], v[148:149], off offset:2048
	global_load_dwordx2 v[104:105], v[4:5], off offset:2560
	global_load_dwordx2 v[100:101], v[60:61], off offset:2560
	global_load_dwordx2 v[8:9], v[148:149], off offset:2560
	global_load_dwordx2 v[98:99], v[4:5], off offset:3072
	global_load_dwordx2 v[96:97], v[60:61], off offset:3072
	global_load_dwordx2 v[6:7], v[148:149], off offset:3072
; template <bool HG>
; __device__ __forceinline__ void readout_phase2(const Args& a, Frame& F, const float* gain, int nrows) {
;     ...
;     RO_FINISH(f0, b0, g0, nw + 6 * 2048);
	global_load_dwordx2 v[92:93], v[4:5], off offset:3584
	s_nop 0
	global_load_dwordx2 v[60:61], v[60:61], off offset:3584
	s_nop 0
	global_load_dwordx2 v[4:5], v[148:149], off offset:3584
	v_lshl_add_u64 v[148:149], v[2:3], 0, s[40:41]
	v_cmp_ge_f32_e64 s[40:41], 0, v178
	v_lshl_add_u64 v[148:149], v[148:149], 0, v[0:1]
	v_sqrt_f32_e32 v154, v152
	v_cndmask_b32_e64 v178, v214, v216, s[40:41]
	v_cmp_lt_f32_e64 s[40:41], 0, v179
	v_add_u32_e32 v160, -1, v154
	s_nop 0
	v_cndmask_b32_e64 v178, v178, v213, s[40:41]
	v_mul_f32_e32 v179, 0x37800000, v178
	v_cndmask_b32_e32 v178, v178, v179, vcc
	v_cmp_class_f32_e32 vcc, v211, v253
	v_add_u32_e32 v157, 1, v154
	s_nop 0
	v_cndmask_b32_e32 v178, v178, v211, vcc
	v_div_scale_f32 v179, s[40:41], v178, v178, 1.0
	v_rcp_f32_e32 v180, v179
	s_nop 0
	v_fma_f32 v181, -v179, v180, 1.0
	v_fmac_f32_e32 v180, v181, v180
	v_div_scale_f32 v181, vcc, 1.0, v178, 1.0
	v_mul_f32_e32 v211, v181, v180
	v_fma_f32 v213, -v179, v211, v181
	v_fmac_f32_e32 v211, v213, v180
	v_fma_f32 v179, -v179, v211, v181
	v_div_fmas_f32 v179, v179, v180, v211
	v_div_fixup_f32 v178, v179, v178, 1.0
	v_lshlrev_b32_e32 v180, 16, v24
	v_and_b32_e32 v181, 0xffff0000, v24
	v_lshlrev_b32_e32 v24, 16, v25
	v_and_b32_e32 v25, 0xffff0000, v25
	v_pk_mul_f32 v[140:141], v[140:141], v[178:179] op_sel_hi:[1,0]
	v_pk_mul_f32 v[142:143], v[142:143], v[178:179] op_sel_hi:[1,0]
	v_pk_mul_f32 v[140:141], v[140:141], v[180:181]
	v_pk_mul_f32 v[24:25], v[142:143], v[24:25]
	v_cvt_pk_bf16_f32 v140, v140, v141
	v_cvt_pk_bf16_f32 v141, v24, v25
	v_fma_f32 v24, -v209, v205, v202
	v_cmp_ge_f32_e32 vcc, 0, v24
	v_fma_f32 v25, -v207, v205, v202
	global_store_dwordx2 v[148:149], v[140:141], off
	v_cndmask_b32_e32 v24, v205, v209, vcc
	v_cmp_lt_f32_e32 vcc, 0, v25
	s_nop 1
	v_cndmask_b32_e32 v24, v24, v207, vcc
	v_mul_f32_e32 v25, 0x37800000, v24
	v_cndmask_b32_e64 v24, v24, v25, s[30:31]
	v_cmp_class_f32_e32 vcc, v202, v253
	s_nop 1
	v_cndmask_b32_e32 v24, v24, v202, vcc
	v_div_scale_f32 v25, s[30:31], v24, v24, 1.0
	v_rcp_f32_e32 v140, v25
	s_nop 0
	v_fma_f32 v141, -v25, v140, 1.0
	v_fmac_f32_e32 v140, v141, v140
	v_div_scale_f32 v141, vcc, 1.0, v24, 1.0
	v_mul_f32_e32 v142, v141, v140
	v_fma_f32 v143, -v25, v142, v141
	v_fmac_f32_e32 v142, v143, v140
	v_fma_f32 v25, -v25, v142, v141
	v_div_fmas_f32 v25, v25, v140, v142
	v_div_fixup_f32 v24, v25, v24, 1.0
	v_lshlrev_b32_e32 v140, 16, v22
	v_and_b32_e32 v141, 0xffff0000, v22
	v_lshlrev_b32_e32 v22, 16, v23
	v_and_b32_e32 v23, 0xffff0000, v23
	v_pk_mul_f32 v[134:135], v[134:135], v[24:25] op_sel_hi:[1,0]
	v_pk_mul_f32 v[24:25], v[136:137], v[24:25] op_sel_hi:[1,0]
	s_nop 0
	v_pk_mul_f32 v[22:23], v[24:25], v[22:23]
	v_pk_mul_f32 v[24:25], v[134:135], v[140:141]
	s_nop 0
	v_cvt_pk_bf16_f32 v24, v24, v25
	v_cvt_pk_bf16_f32 v25, v22, v23
	v_fma_f32 v22, -v199, v197, v194
	v_cmp_ge_f32_e32 vcc, 0, v22
	v_fma_f32 v23, -v196, v197, v194
	global_store_dwordx2 v[148:149], v[24:25], off offset:512
	v_cndmask_b32_e32 v22, v197, v199, vcc
	v_cmp_lt_f32_e32 vcc, 0, v23
	s_nop 1
	v_cndmask_b32_e32 v22, v22, v196, vcc
	v_mul_f32_e32 v23, 0x37800000, v22
	v_cndmask_b32_e64 v22, v22, v23, s[26:27]
	v_cmp_class_f32_e32 vcc, v194, v253
	s_nop 1
	v_cndmask_b32_e32 v22, v22, v194, vcc
	v_div_scale_f32 v23, s[26:27], v22, v22, 1.0
	v_rcp_f32_e32 v24, v23
	s_nop 0
	v_fma_f32 v25, -v23, v24, 1.0
	v_fmac_f32_e32 v24, v25, v24
	v_div_scale_f32 v25, vcc, 1.0, v22, 1.0
	v_mul_f32_e32 v134, v25, v24
	v_fma_f32 v135, -v23, v134, v25
	v_fmac_f32_e32 v134, v135, v24
	v_fma_f32 v23, -v23, v134, v25
	v_div_fmas_f32 v23, v23, v24, v134
	v_div_fixup_f32 v22, v23, v22, 1.0
	v_lshlrev_b32_e32 v24, 16, v20
	v_and_b32_e32 v25, 0xffff0000, v20
	v_lshlrev_b32_e32 v20, 16, v21
	v_and_b32_e32 v21, 0xffff0000, v21
	v_pk_mul_f32 v[130:131], v[130:131], v[22:23] op_sel_hi:[1,0]
	v_pk_mul_f32 v[22:23], v[122:123], v[22:23] op_sel_hi:[1,0]
	s_nop 0
	v_pk_mul_f32 v[20:21], v[22:23], v[20:21]
	v_pk_mul_f32 v[22:23], v[130:131], v[24:25]
	s_nop 0
	v_cvt_pk_bf16_f32 v22, v22, v23
	v_cvt_pk_bf16_f32 v23, v20, v21
	v_fma_f32 v20, -v193, v189, v186
	v_cmp_ge_f32_e32 vcc, 0, v20
	v_fma_f32 v21, -v191, v189, v186
	global_store_dwordx2 v[148:149], v[22:23], off offset:1024
	v_cndmask_b32_e32 v20, v189, v193, vcc
	v_cmp_lt_f32_e32 vcc, 0, v21
	s_nop 1
	v_cndmask_b32_e32 v20, v20, v191, vcc
	v_mul_f32_e32 v21, 0x37800000, v20
	v_cndmask_b32_e64 v20, v20, v21, s[22:23]
	v_cmp_class_f32_e32 vcc, v186, v253
	s_nop 1
	v_cndmask_b32_e32 v20, v20, v186, vcc
	v_div_scale_f32 v21, s[22:23], v20, v20, 1.0
	v_rcp_f32_e32 v22, v21
	s_nop 0
	v_fma_f32 v23, -v21, v22, 1.0
	v_fmac_f32_e32 v22, v23, v22
	v_div_scale_f32 v23, vcc, 1.0, v20, 1.0
	v_mul_f32_e32 v24, v23, v22
	v_fma_f32 v25, -v21, v24, v23
	v_fmac_f32_e32 v24, v25, v22
	v_fma_f32 v21, -v21, v24, v23
	v_div_fmas_f32 v21, v21, v22, v24
	v_div_fixup_f32 v20, v21, v20, 1.0
	v_lshlrev_b32_e32 v22, 16, v18
	v_and_b32_e32 v23, 0xffff0000, v18
	v_lshlrev_b32_e32 v18, 16, v19
	v_and_b32_e32 v19, 0xffff0000, v19
	v_pk_mul_f32 v[24:25], v[86:87], v[20:21] op_sel_hi:[1,0]
	v_pk_mul_f32 v[20:21], v[88:89], v[20:21] op_sel_hi:[1,0]
	s_nop 0
	v_pk_mul_f32 v[18:19], v[20:21], v[18:19]
	v_pk_mul_f32 v[20:21], v[24:25], v[22:23]
	s_nop 0
	v_cvt_pk_bf16_f32 v20, v20, v21
	v_cvt_pk_bf16_f32 v21, v18, v19
	v_fma_f32 v18, -v177, v175, v172
	v_cmp_ge_f32_e32 vcc, 0, v18
	v_fma_f32 v19, -v174, v175, v172
	global_store_dwordx2 v[148:149], v[20:21], off offset:1536
	v_cndmask_b32_e32 v18, v175, v177, vcc
	v_cmp_lt_f32_e32 vcc, 0, v19
	s_nop 1
	v_cndmask_b32_e32 v18, v18, v174, vcc
	v_mul_f32_e32 v19, 0x37800000, v18
	v_cndmask_b32_e64 v18, v18, v19, s[18:19]
; template <bool HG>
; __device__ __forceinline__ void readout_phase2(const Args& a, Frame& F, const float* gain, int nrows) {
;     ...
;     RO_FINISH(f0, b0, g0, nw + 6 * 2048);
;     RO_FINISH(f1, b1, g1, nw + 7 * 2048);
	v_cmp_class_f32_e32 vcc, v172, v253
	s_nop 1
	v_cndmask_b32_e32 v18, v18, v172, vcc
	v_div_scale_f32 v19, s[18:19], v18, v18, 1.0
	v_rcp_f32_e32 v20, v19
	s_nop 0
	v_fma_f32 v21, -v19, v20, 1.0
	v_fmac_f32_e32 v20, v21, v20
	v_div_scale_f32 v21, vcc, 1.0, v18, 1.0
	v_mul_f32_e32 v22, v21, v20
	v_fma_f32 v23, -v19, v22, v21
	v_fmac_f32_e32 v22, v23, v20
	v_fma_f32 v19, -v19, v22, v21
	v_div_fmas_f32 v19, v19, v20, v22
	v_div_fixup_f32 v18, v19, v18, 1.0
	v_lshlrev_b32_e32 v20, 16, v16
	v_and_b32_e32 v21, 0xffff0000, v16
	v_lshlrev_b32_e32 v16, 16, v17
	v_and_b32_e32 v17, 0xffff0000, v17
	v_pk_mul_f32 v[22:23], v[78:79], v[18:19] op_sel_hi:[1,0]
	v_pk_mul_f32 v[18:19], v[80:81], v[18:19] op_sel_hi:[1,0]
	s_nop 0
	v_pk_mul_f32 v[16:17], v[18:19], v[16:17]
	v_pk_mul_f32 v[18:19], v[22:23], v[20:21]
	s_nop 0
	v_cvt_pk_bf16_f32 v18, v18, v19
	v_cvt_pk_bf16_f32 v19, v16, v17
	v_fma_f32 v16, -v171, v167, v164
	v_cmp_ge_f32_e32 vcc, 0, v16
	v_fma_f32 v17, -v169, v167, v164
	global_store_dwordx2 v[148:149], v[18:19], off offset:2048
	v_cndmask_b32_e32 v16, v167, v171, vcc
	v_cmp_lt_f32_e32 vcc, 0, v17
	s_nop 1
	v_cndmask_b32_e32 v16, v16, v169, vcc
	v_mul_f32_e32 v17, 0x37800000, v16
	v_cndmask_b32_e64 v16, v16, v17, s[14:15]
	v_cmp_class_f32_e32 vcc, v164, v253
	s_nop 1
	v_cndmask_b32_e32 v16, v16, v164, vcc
	v_div_scale_f32 v17, s[14:15], v16, v16, 1.0
	v_rcp_f32_e32 v18, v17
	s_nop 0
	v_fma_f32 v19, -v17, v18, 1.0
	v_fmac_f32_e32 v18, v19, v18
	v_div_scale_f32 v19, vcc, 1.0, v16, 1.0
	v_mul_f32_e32 v20, v19, v18
	v_fma_f32 v21, -v17, v20, v19
	v_fmac_f32_e32 v20, v21, v18
	v_fma_f32 v17, -v17, v20, v19
	v_div_fmas_f32 v17, v17, v18, v20
	v_div_fixup_f32 v16, v17, v16, 1.0
	v_lshlrev_b32_e32 v18, 16, v14
	v_and_b32_e32 v19, 0xffff0000, v14
	v_lshlrev_b32_e32 v14, 16, v15
	v_and_b32_e32 v15, 0xffff0000, v15
	v_pk_mul_f32 v[20:21], v[70:71], v[16:17] op_sel_hi:[1,0]
	v_pk_mul_f32 v[16:17], v[72:73], v[16:17] op_sel_hi:[1,0]
	s_nop 0
	v_pk_mul_f32 v[14:15], v[16:17], v[14:15]
	v_pk_mul_f32 v[16:17], v[20:21], v[18:19]
	s_nop 0
	v_cvt_pk_bf16_f32 v16, v16, v17
	v_cvt_pk_bf16_f32 v17, v14, v15
	v_fma_f32 v14, -v161, v159, v156
	v_cmp_ge_f32_e32 vcc, 0, v14
	v_fma_f32 v15, -v158, v159, v156
	global_store_dwordx2 v[148:149], v[16:17], off offset:2560
	v_cndmask_b32_e32 v14, v159, v161, vcc
	v_cmp_lt_f32_e32 vcc, 0, v15
	s_nop 1
	v_cndmask_b32_e32 v14, v14, v158, vcc
	v_mul_f32_e32 v15, 0x37800000, v14
	v_cndmask_b32_e64 v14, v14, v15, s[10:11]
	v_cmp_class_f32_e32 vcc, v156, v253
	s_nop 1
	v_cndmask_b32_e32 v14, v14, v156, vcc
	v_div_scale_f32 v15, s[10:11], v14, v14, 1.0
	v_rcp_f32_e32 v16, v15
	s_nop 0
	v_fma_f32 v17, -v15, v16, 1.0
	v_fmac_f32_e32 v16, v17, v16
	v_div_scale_f32 v17, vcc, 1.0, v14, 1.0
	v_mul_f32_e32 v18, v17, v16
	v_fma_f32 v19, -v15, v18, v17
	v_fmac_f32_e32 v18, v19, v16
	v_fma_f32 v15, -v15, v18, v17
	v_div_fmas_f32 v15, v15, v16, v18
	v_div_fixup_f32 v14, v15, v14, 1.0
	v_lshlrev_b32_e32 v16, 16, v12
	v_and_b32_e32 v17, 0xffff0000, v12
	v_lshlrev_b32_e32 v12, 16, v13
	v_and_b32_e32 v13, 0xffff0000, v13
	v_pk_mul_f32 v[18:19], v[62:63], v[14:15] op_sel_hi:[1,0]
	v_pk_mul_f32 v[14:15], v[68:69], v[14:15] op_sel_hi:[1,0]
	s_nop 0
	v_pk_mul_f32 v[12:13], v[14:15], v[12:13]
	v_pk_mul_f32 v[14:15], v[18:19], v[16:17]
	s_nop 0
	v_cvt_pk_bf16_f32 v14, v14, v15
	v_cvt_pk_bf16_f32 v15, v12, v13
	v_fma_f32 v12, -v155, v151, v150
	v_cmp_ge_f32_e32 vcc, 0, v12
	v_fma_f32 v13, -v153, v151, v150
	global_store_dwordx2 v[148:149], v[14:15], off offset:3072
	v_cndmask_b32_e32 v12, v151, v155, vcc
	v_cmp_lt_f32_e32 vcc, 0, v13
	s_nop 1
	v_cndmask_b32_e32 v12, v12, v153, vcc
	v_mul_f32_e32 v13, 0x37800000, v12
	v_cndmask_b32_e64 v12, v12, v13, s[6:7]
	v_cmp_class_f32_e32 vcc, v150, v253
	s_nop 1
	v_cndmask_b32_e32 v12, v12, v150, vcc
	v_div_scale_f32 v13, s[6:7], v12, v12, 1.0
	v_rcp_f32_e32 v14, v13
	s_nop 0
	v_fma_f32 v15, -v13, v14, 1.0
	v_fmac_f32_e32 v14, v15, v14
	v_div_scale_f32 v15, vcc, 1.0, v12, 1.0
	v_mul_f32_e32 v16, v15, v14
	v_fma_f32 v17, -v13, v16, v15
	v_fmac_f32_e32 v16, v17, v14
	v_fma_f32 v13, -v13, v16, v15
	v_div_fmas_f32 v13, v13, v14, v16
	v_div_fixup_f32 v12, v13, v12, 1.0
	v_lshlrev_b32_e32 v14, 16, v10
	v_and_b32_e32 v15, 0xffff0000, v10
	v_lshlrev_b32_e32 v10, 16, v11
	v_and_b32_e32 v11, 0xffff0000, v11
	v_pk_mul_f32 v[16:17], v[44:45], v[12:13] op_sel_hi:[1,0]
	v_pk_mul_f32 v[12:13], v[50:51], v[12:13] op_sel_hi:[1,0]
	s_nop 0
	v_pk_mul_f32 v[10:11], v[12:13], v[10:11]
	v_pk_mul_f32 v[12:13], v[16:17], v[14:15]
	s_nop 0
	v_cvt_pk_bf16_f32 v12, v12, v13
	v_cvt_pk_bf16_f32 v13, v10, v11
	global_store_dwordx2 v[148:149], v[12:13], off offset:3584
	v_fma_f32 v12, -v219, v218, v215
	v_cmp_ge_f32_e32 vcc, 0, v12
	v_fma_f32 v13, -v217, v218, v215
	v_lshl_add_u64 v[10:11], v[2:3], 0, s[78:79]
	v_cndmask_b32_e32 v12, v218, v219, vcc
	v_cmp_lt_f32_e32 vcc, 0, v13
	v_lshl_add_u64 v[10:11], v[10:11], 0, v[0:1]
	s_nop 0
	v_cndmask_b32_e32 v12, v12, v217, vcc
	v_mul_f32_e32 v13, 0x37800000, v12
	v_cndmask_b32_e64 v12, v12, v13, s[36:37]
	v_cmp_class_f32_e32 vcc, v215, v253
	s_nop 1
	v_cndmask_b32_e32 v12, v12, v215, vcc
	v_div_scale_f32 v13, s[6:7], v12, v12, 1.0
	v_rcp_f32_e32 v14, v13
	s_nop 0
	v_fma_f32 v15, -v13, v14, 1.0
	v_fmac_f32_e32 v14, v15, v14
	v_div_scale_f32 v15, vcc, 1.0, v12, 1.0
	v_mul_f32_e32 v16, v15, v14
	v_fma_f32 v17, -v13, v16, v15
	v_fmac_f32_e32 v16, v17, v14
	v_fma_f32 v13, -v13, v16, v15
	v_div_fmas_f32 v13, v13, v14, v16
	v_div_fixup_f32 v12, v13, v12, 1.0
	v_lshlrev_b32_e32 v14, 16, v52
	v_and_b32_e32 v15, 0xffff0000, v52
	v_lshlrev_b32_e32 v16, 16, v53
	v_and_b32_e32 v17, 0xffff0000, v53
; template <bool HG>
; __device__ __forceinline__ void readout_phase2(const Args& a, Frame& F, const float* gain, int nrows) {
;     ...
;     RO_FINISH(f1, b1, g1, nw + 7 * 2048);
	v_pk_mul_f32 v[18:19], v[126:127], v[12:13] op_sel_hi:[1,0]
	v_pk_mul_f32 v[12:13], v[138:139], v[12:13] op_sel_hi:[1,0]
	v_pk_mul_f32 v[14:15], v[18:19], v[14:15]
	v_pk_mul_f32 v[12:13], v[12:13], v[16:17]
	v_cvt_pk_bf16_f32 v14, v14, v15
	v_cvt_pk_bf16_f32 v15, v12, v13
	v_fma_f32 v12, -v212, v208, v206
	v_cmp_ge_f32_e32 vcc, 0, v12
	v_fma_f32 v13, -v210, v208, v206
	global_store_dwordx2 v[10:11], v[14:15], off
	v_cndmask_b32_e32 v12, v208, v212, vcc
	v_cmp_lt_f32_e32 vcc, 0, v13
	s_nop 1
	v_cndmask_b32_e32 v12, v12, v210, vcc
	v_mul_f32_e32 v13, 0x37800000, v12
	v_cndmask_b32_e64 v12, v12, v13, s[34:35]
	v_cmp_class_f32_e32 vcc, v206, v253
	s_nop 1
	v_cndmask_b32_e32 v12, v12, v206, vcc
	v_div_scale_f32 v13, s[6:7], v12, v12, 1.0
	v_rcp_f32_e32 v14, v13
	s_nop 0
	v_fma_f32 v15, -v13, v14, 1.0
	v_fmac_f32_e32 v14, v15, v14
	v_div_scale_f32 v15, vcc, 1.0, v12, 1.0
	v_mul_f32_e32 v16, v15, v14
	v_fma_f32 v17, -v13, v16, v15
	v_fmac_f32_e32 v16, v17, v14
	v_fma_f32 v13, -v13, v16, v15
	v_div_fmas_f32 v13, v13, v14, v16
	v_div_fixup_f32 v12, v13, v12, 1.0
	v_lshlrev_b32_e32 v14, 16, v48
	v_and_b32_e32 v15, 0xffff0000, v48
	v_lshlrev_b32_e32 v16, 16, v49
	v_and_b32_e32 v17, 0xffff0000, v49
	v_pk_mul_f32 v[18:19], v[114:115], v[12:13] op_sel_hi:[1,0]
	v_pk_mul_f32 v[12:13], v[118:119], v[12:13] op_sel_hi:[1,0]
	v_pk_mul_f32 v[14:15], v[18:19], v[14:15]
	v_pk_mul_f32 v[12:13], v[12:13], v[16:17]
	v_cvt_pk_bf16_f32 v14, v14, v15
	v_cvt_pk_bf16_f32 v15, v12, v13
	v_fma_f32 v12, -v204, v203, v200
	v_cmp_ge_f32_e32 vcc, 0, v12
	v_fma_f32 v13, -v201, v203, v200
	global_store_dwordx2 v[10:11], v[14:15], off offset:512
	v_cndmask_b32_e32 v12, v203, v204, vcc
	v_cmp_lt_f32_e32 vcc, 0, v13
	s_nop 1
	v_cndmask_b32_e32 v12, v12, v201, vcc
	v_mul_f32_e32 v13, 0x37800000, v12
	v_cndmask_b32_e64 v12, v12, v13, s[28:29]
	v_cmp_class_f32_e32 vcc, v200, v253
	s_nop 1
	v_cndmask_b32_e32 v12, v12, v200, vcc
	v_div_scale_f32 v13, s[6:7], v12, v12, 1.0
	v_rcp_f32_e32 v14, v13
	s_nop 0
	v_fma_f32 v15, -v13, v14, 1.0
	v_fmac_f32_e32 v14, v15, v14
	v_div_scale_f32 v15, vcc, 1.0, v12, 1.0
	v_mul_f32_e32 v16, v15, v14
	v_fma_f32 v17, -v13, v16, v15
	v_fmac_f32_e32 v16, v17, v14
	v_fma_f32 v13, -v13, v16, v15
	v_div_fmas_f32 v13, v13, v14, v16
	v_div_fixup_f32 v12, v13, v12, 1.0
	v_lshlrev_b32_e32 v14, 16, v46
	v_and_b32_e32 v15, 0xffff0000, v46
	v_lshlrev_b32_e32 v16, 16, v47
	v_and_b32_e32 v17, 0xffff0000, v47
	v_pk_mul_f32 v[18:19], v[102:103], v[12:13] op_sel_hi:[1,0]
	v_pk_mul_f32 v[12:13], v[106:107], v[12:13] op_sel_hi:[1,0]
	v_pk_mul_f32 v[14:15], v[18:19], v[14:15]
	v_pk_mul_f32 v[12:13], v[12:13], v[16:17]
	v_cvt_pk_bf16_f32 v14, v14, v15
	v_cvt_pk_bf16_f32 v15, v12, v13
	v_fma_f32 v12, -v198, v192, v190
	v_cmp_ge_f32_e32 vcc, 0, v12
	v_fma_f32 v13, -v195, v192, v190
	global_store_dwordx2 v[10:11], v[14:15], off offset:1024
	v_cndmask_b32_e32 v12, v192, v198, vcc
	v_cmp_lt_f32_e32 vcc, 0, v13
	s_nop 1
	v_cndmask_b32_e32 v12, v12, v195, vcc
	v_mul_f32_e32 v13, 0x37800000, v12
	v_cndmask_b32_e64 v12, v12, v13, s[24:25]
	v_cmp_class_f32_e32 vcc, v190, v253
	s_nop 1
	v_cndmask_b32_e32 v12, v12, v190, vcc
	v_div_scale_f32 v13, s[6:7], v12, v12, 1.0
	v_rcp_f32_e32 v14, v13
	s_nop 0
	v_fma_f32 v15, -v13, v14, 1.0
	v_fmac_f32_e32 v14, v15, v14
	v_div_scale_f32 v15, vcc, 1.0, v12, 1.0
	v_mul_f32_e32 v16, v15, v14
	v_fma_f32 v17, -v13, v16, v15
	v_fmac_f32_e32 v16, v17, v14
	v_fma_f32 v13, -v13, v16, v15
	v_div_fmas_f32 v13, v13, v14, v16
	v_div_fixup_f32 v12, v13, v12, 1.0
	v_lshlrev_b32_e32 v14, 16, v42
	v_and_b32_e32 v15, 0xffff0000, v42
	v_lshlrev_b32_e32 v16, 16, v43
	v_and_b32_e32 v17, 0xffff0000, v43
	v_pk_mul_f32 v[18:19], v[90:91], v[12:13] op_sel_hi:[1,0]
	v_pk_mul_f32 v[12:13], v[94:95], v[12:13] op_sel_hi:[1,0]
	v_pk_mul_f32 v[14:15], v[18:19], v[14:15]
	v_pk_mul_f32 v[12:13], v[12:13], v[16:17]
	v_cvt_pk_bf16_f32 v14, v14, v15
	v_cvt_pk_bf16_f32 v15, v12, v13
	v_fma_f32 v12, -v188, v187, v184
	v_cmp_ge_f32_e32 vcc, 0, v12
	v_fma_f32 v13, -v185, v187, v184
	global_store_dwordx2 v[10:11], v[14:15], off offset:1536
	v_cndmask_b32_e32 v12, v187, v188, vcc
	v_cmp_lt_f32_e32 vcc, 0, v13
	s_nop 1
	v_cndmask_b32_e32 v12, v12, v185, vcc
	v_mul_f32_e32 v13, 0x37800000, v12
	v_cndmask_b32_e64 v12, v12, v13, s[20:21]
	v_cmp_class_f32_e32 vcc, v184, v253
	s_nop 1
	v_cndmask_b32_e32 v12, v12, v184, vcc
	v_div_scale_f32 v13, s[6:7], v12, v12, 1.0
	v_rcp_f32_e32 v14, v13
	s_nop 0
	v_fma_f32 v15, -v13, v14, 1.0
	v_fmac_f32_e32 v14, v15, v14
	v_div_scale_f32 v15, vcc, 1.0, v12, 1.0
	v_mul_f32_e32 v16, v15, v14
	v_fma_f32 v17, -v13, v16, v15
	v_fmac_f32_e32 v16, v17, v14
	v_fma_f32 v13, -v13, v16, v15
	v_div_fmas_f32 v13, v13, v14, v16
	v_div_fixup_f32 v12, v13, v12, 1.0
	v_lshlrev_b32_e32 v14, 16, v40
	v_and_b32_e32 v15, 0xffff0000, v40
	v_lshlrev_b32_e32 v16, 16, v41
	v_and_b32_e32 v17, 0xffff0000, v41
	v_pk_mul_f32 v[18:19], v[82:83], v[12:13] op_sel_hi:[1,0]
	v_pk_mul_f32 v[12:13], v[84:85], v[12:13] op_sel_hi:[1,0]
	v_pk_mul_f32 v[14:15], v[18:19], v[14:15]
	v_pk_mul_f32 v[12:13], v[12:13], v[16:17]
	v_cvt_pk_bf16_f32 v14, v14, v15
	v_cvt_pk_bf16_f32 v15, v12, v13
	v_fma_f32 v12, -v176, v170, v168
	v_cmp_ge_f32_e32 vcc, 0, v12
	v_fma_f32 v13, -v173, v170, v168
	global_store_dwordx2 v[10:11], v[14:15], off offset:2048
	v_cndmask_b32_e32 v12, v170, v176, vcc
	v_cmp_lt_f32_e32 vcc, 0, v13
	s_nop 1
	v_cndmask_b32_e32 v12, v12, v173, vcc
	v_mul_f32_e32 v13, 0x37800000, v12
	v_cndmask_b32_e64 v12, v12, v13, s[16:17]
	v_cmp_class_f32_e32 vcc, v168, v253
	s_nop 1
	v_cndmask_b32_e32 v12, v12, v168, vcc
	v_div_scale_f32 v13, s[6:7], v12, v12, 1.0
	v_rcp_f32_e32 v14, v13
	s_nop 0
; template <bool HG>
; __device__ __forceinline__ void readout_phase2(const Args& a, Frame& F, const float* gain, int nrows) {
;     ...
;     RO_FINISH(f1, b1, g1, nw + 7 * 2048);
;     if (cx) RO_FINISH(f2, b2, g2, ML + nw);
	v_fma_f32 v15, -v13, v14, 1.0
	v_fmac_f32_e32 v14, v15, v14
	v_div_scale_f32 v15, vcc, 1.0, v12, 1.0
	v_mul_f32_e32 v16, v15, v14
	v_fma_f32 v17, -v13, v16, v15
	v_fmac_f32_e32 v16, v17, v14
	v_fma_f32 v13, -v13, v16, v15
	v_div_fmas_f32 v13, v13, v14, v16
	v_div_fixup_f32 v12, v13, v12, 1.0
	v_lshlrev_b32_e32 v14, 16, v36
	v_and_b32_e32 v15, 0xffff0000, v36
	v_lshlrev_b32_e32 v16, 16, v37
	v_and_b32_e32 v17, 0xffff0000, v37
	v_pk_mul_f32 v[18:19], v[74:75], v[12:13] op_sel_hi:[1,0]
	v_pk_mul_f32 v[12:13], v[76:77], v[12:13] op_sel_hi:[1,0]
	v_pk_mul_f32 v[14:15], v[18:19], v[14:15]
	v_pk_mul_f32 v[12:13], v[12:13], v[16:17]
	v_cvt_pk_bf16_f32 v14, v14, v15
	v_cvt_pk_bf16_f32 v15, v12, v13
	v_fma_f32 v12, -v166, v165, v162
	v_cmp_ge_f32_e32 vcc, 0, v12
	v_fma_f32 v13, -v163, v165, v162
	global_store_dwordx2 v[10:11], v[14:15], off offset:2560
	v_cndmask_b32_e32 v12, v165, v166, vcc
	v_cmp_lt_f32_e32 vcc, 0, v13
	s_nop 1
	v_cndmask_b32_e32 v12, v12, v163, vcc
	v_mul_f32_e32 v13, 0x37800000, v12
	v_cndmask_b32_e64 v12, v12, v13, s[12:13]
	v_cmp_class_f32_e32 vcc, v162, v253
	s_nop 1
	v_cndmask_b32_e32 v12, v12, v162, vcc
	v_div_scale_f32 v13, s[6:7], v12, v12, 1.0
	v_rcp_f32_e32 v14, v13
	s_nop 0
	v_fma_f32 v15, -v13, v14, 1.0
	v_fmac_f32_e32 v14, v15, v14
	v_div_scale_f32 v15, vcc, 1.0, v12, 1.0
	v_mul_f32_e32 v16, v15, v14
	v_fma_f32 v17, -v13, v16, v15
	v_fmac_f32_e32 v16, v17, v14
	v_fma_f32 v13, -v13, v16, v15
	v_div_fmas_f32 v13, v13, v14, v16
	v_div_fixup_f32 v12, v13, v12, 1.0
	v_lshlrev_b32_e32 v14, 16, v32
	v_and_b32_e32 v15, 0xffff0000, v32
	v_lshlrev_b32_e32 v16, 16, v33
	v_and_b32_e32 v17, 0xffff0000, v33
	v_pk_mul_f32 v[18:19], v[64:65], v[12:13] op_sel_hi:[1,0]
	v_pk_mul_f32 v[12:13], v[66:67], v[12:13] op_sel_hi:[1,0]
	v_pk_mul_f32 v[14:15], v[18:19], v[14:15]
	v_pk_mul_f32 v[12:13], v[12:13], v[16:17]
	v_cvt_pk_bf16_f32 v14, v14, v15
	v_cvt_pk_bf16_f32 v15, v12, v13
	v_fma_f32 v12, -v160, v154, v152
	v_cmp_ge_f32_e32 vcc, 0, v12
	v_fma_f32 v13, -v157, v154, v152
	global_store_dwordx2 v[10:11], v[14:15], off offset:3072
	v_cndmask_b32_e32 v12, v154, v160, vcc
	v_cmp_lt_f32_e32 vcc, 0, v13
	s_nop 1
	v_cndmask_b32_e32 v12, v12, v157, vcc
	v_mul_f32_e32 v13, 0x37800000, v12
	v_cndmask_b32_e64 v12, v12, v13, s[8:9]
	v_cmp_class_f32_e32 vcc, v152, v253
	s_nop 1
	v_cndmask_b32_e32 v12, v12, v152, vcc
	v_div_scale_f32 v13, s[6:7], v12, v12, 1.0
	v_rcp_f32_e32 v14, v13
	s_nop 0
	v_fma_f32 v15, -v13, v14, 1.0
	v_fmac_f32_e32 v14, v15, v14
	v_div_scale_f32 v15, vcc, 1.0, v12, 1.0
	v_mul_f32_e32 v16, v15, v14
	v_fma_f32 v17, -v13, v16, v15
	v_fmac_f32_e32 v16, v17, v14
	v_fma_f32 v13, -v13, v16, v15
	v_div_fmas_f32 v13, v13, v14, v16
	v_div_fixup_f32 v12, v13, v12, 1.0
	s_waitcnt vmcnt(47)
	v_lshlrev_b32_e32 v14, 16, v28
	v_and_b32_e32 v15, 0xffff0000, v28
	v_lshlrev_b32_e32 v16, 16, v29
	v_and_b32_e32 v17, 0xffff0000, v29
	v_pk_mul_f32 v[18:19], v[56:57], v[12:13] op_sel_hi:[1,0]
	v_pk_mul_f32 v[12:13], v[54:55], v[12:13] op_sel_hi:[1,0]
	v_pk_mul_f32 v[14:15], v[18:19], v[14:15]
	v_pk_mul_f32 v[12:13], v[12:13], v[16:17]
	v_cvt_pk_bf16_f32 v14, v14, v15
	v_cvt_pk_bf16_f32 v15, v12, v13
	global_store_dwordx2 v[10:11], v[14:15], off offset:3584
	s_cbranch_scc1 .LBB0_864
	s_waitcnt vmcnt(39)
	v_lshlrev_b32_e32 v10, 16, v146
	v_and_b32_e32 v11, 0xffff0000, v146
	s_waitcnt vmcnt(38)
	v_lshlrev_b32_e32 v12, 16, v144
	v_and_b32_e32 v13, 0xffff0000, v144
	v_pk_add_f32 v[46:47], v[10:11], v[12:13]
	v_lshlrev_b32_e32 v10, 16, v147
	v_and_b32_e32 v11, 0xffff0000, v147
	v_lshlrev_b32_e32 v12, 16, v145
	v_and_b32_e32 v13, 0xffff0000, v145
	v_pk_add_f32 v[48:49], v[10:11], v[12:13]
	v_mov_b32_e32 v12, v47
	v_mov_b32_e32 v13, v49
	v_mov_b32_e32 v10, v46
	v_mov_b32_e32 v11, v48
	v_pk_mul_f32 v[12:13], v[12:13], v[12:13]
	s_ashr_i32 s83, s82, 31
	v_pk_fma_f32 v[10:11], v[10:11], v[10:11], v[12:13]
	s_waitcnt vmcnt(35)
	v_lshlrev_b32_e32 v12, 16, v128
	v_add_f32_e32 v62, v10, v11
	v_lshlrev_b32_e32 v10, 16, v132
	v_and_b32_e32 v11, 0xffff0000, v132
	v_and_b32_e32 v13, 0xffff0000, v128
	v_pk_add_f32 v[42:43], v[10:11], v[12:13]
	v_lshlrev_b32_e32 v10, 16, v133
	v_and_b32_e32 v11, 0xffff0000, v133
	v_lshlrev_b32_e32 v12, 16, v129
	v_and_b32_e32 v13, 0xffff0000, v129
	v_pk_add_f32 v[44:45], v[10:11], v[12:13]
	v_mov_b32_e32 v12, v43
	v_mov_b32_e32 v13, v45
	v_mov_b32_e32 v10, v42
	v_mov_b32_e32 v11, v44
	v_pk_mul_f32 v[12:13], v[12:13], v[12:13]
	s_lshl_b64 s[6:7], s[82:83], 12
	v_pk_fma_f32 v[10:11], v[10:11], v[10:11], v[12:13]
	s_waitcnt vmcnt(32)
	v_lshlrev_b32_e32 v12, 16, v120
	v_add_f32_e32 v63, v10, v11
	v_lshlrev_b32_e32 v10, 16, v124
	v_and_b32_e32 v11, 0xffff0000, v124
	v_and_b32_e32 v13, 0xffff0000, v120
	v_pk_add_f32 v[36:37], v[10:11], v[12:13]
	v_lshlrev_b32_e32 v10, 16, v125
	v_and_b32_e32 v11, 0xffff0000, v125
	v_lshlrev_b32_e32 v12, 16, v121
	v_and_b32_e32 v13, 0xffff0000, v121
	v_pk_add_f32 v[40:41], v[10:11], v[12:13]
	v_mov_b32_e32 v12, v37
	v_mov_b32_e32 v13, v41
	v_mov_b32_e32 v10, v36
	v_mov_b32_e32 v11, v40
	v_pk_mul_f32 v[12:13], v[12:13], v[12:13]
	v_lshl_add_u64 v[2:3], v[2:3], 0, s[6:7]
	v_pk_fma_f32 v[10:11], v[10:11], v[10:11], v[12:13]
	s_waitcnt vmcnt(29)
	v_lshlrev_b32_e32 v12, 16, v112
	v_add_f32_e32 v64, v10, v11
	v_lshlrev_b32_e32 v10, 16, v116
	v_and_b32_e32 v11, 0xffff0000, v116
	v_and_b32_e32 v13, 0xffff0000, v112
	v_pk_add_f32 v[28:29], v[10:11], v[12:13]
	v_lshlrev_b32_e32 v10, 16, v117
	v_and_b32_e32 v11, 0xffff0000, v117
	v_lshlrev_b32_e32 v12, 16, v113
	v_and_b32_e32 v13, 0xffff0000, v113
	v_pk_add_f32 v[32:33], v[10:11], v[12:13]
	v_mov_b32_e32 v12, v29
	v_mov_b32_e32 v13, v33
	v_mov_b32_e32 v10, v28
	v_mov_b32_e32 v11, v32
	v_pk_mul_f32 v[12:13], v[12:13], v[12:13]
	s_waitcnt vmcnt(17)
	v_lshlrev_b32_e32 v54, 16, v61
	v_pk_fma_f32 v[10:11], v[10:11], v[10:11], v[12:13]
	v_lshlrev_b32_e32 v12, 16, v108
	v_add_f32_e32 v65, v10, v11
	v_lshlrev_b32_e32 v10, 16, v110
	v_and_b32_e32 v11, 0xffff0000, v110
	v_and_b32_e32 v13, 0xffff0000, v108
	v_pk_add_f32 v[22:23], v[10:11], v[12:13]
	v_lshlrev_b32_e32 v10, 16, v111
	v_and_b32_e32 v11, 0xffff0000, v111
	v_lshlrev_b32_e32 v12, 16, v109
	v_and_b32_e32 v13, 0xffff0000, v109
	v_pk_add_f32 v[24:25], v[10:11], v[12:13]
	v_mov_b32_e32 v12, v23
	v_mov_b32_e32 v13, v25
	v_mov_b32_e32 v10, v22
	v_mov_b32_e32 v11, v24
	v_pk_mul_f32 v[12:13], v[12:13], v[12:13]
	v_and_b32_e32 v55, 0xffff0000, v61
	v_pk_fma_f32 v[10:11], v[10:11], v[10:11], v[12:13]
	v_lshlrev_b32_e32 v12, 16, v100
	v_add_f32_e32 v53, v10, v11
	v_lshlrev_b32_e32 v10, 16, v104
	v_and_b32_e32 v11, 0xffff0000, v104
	v_and_b32_e32 v13, 0xffff0000, v100
	v_pk_add_f32 v[18:19], v[10:11], v[12:13]
	v_lshlrev_b32_e32 v10, 16, v105
	v_and_b32_e32 v11, 0xffff0000, v105
	v_lshlrev_b32_e32 v12, 16, v101
	v_and_b32_e32 v13, 0xffff0000, v101
	v_pk_add_f32 v[20:21], v[10:11], v[12:13]
	v_mov_b32_e32 v12, v19
	v_mov_b32_e32 v13, v21
	v_mov_b32_e32 v10, v18
	v_mov_b32_e32 v11, v20
	v_pk_mul_f32 v[12:13], v[12:13], v[12:13]
	v_lshl_add_u64 v[2:3], v[2:3], 0, v[0:1]
	v_pk_fma_f32 v[10:11], v[10:11], v[10:11], v[12:13]
	v_lshlrev_b32_e32 v12, 16, v96
	v_add_f32_e32 v52, v10, v11
	v_lshlrev_b32_e32 v10, 16, v98
	v_and_b32_e32 v11, 0xffff0000, v98
	v_and_b32_e32 v13, 0xffff0000, v96
	v_pk_add_f32 v[14:15], v[10:11], v[12:13]
	v_lshlrev_b32_e32 v10, 16, v99
	v_and_b32_e32 v11, 0xffff0000, v99
	v_lshlrev_b32_e32 v12, 16, v97
	v_and_b32_e32 v13, 0xffff0000, v97
	v_pk_add_f32 v[16:17], v[10:11], v[12:13]
	v_mov_b32_e32 v12, v15
	v_mov_b32_e32 v13, v17
	v_mov_b32_e32 v10, v14
	v_mov_b32_e32 v11, v16
	v_pk_mul_f32 v[12:13], v[12:13], v[12:13]
	v_add_f32_dpp v0, v62, v62 quad_perm:[1,0,3,2] row_mask:0xf bank_mask:0xf bound_ctrl:1
	v_pk_fma_f32 v[10:11], v[10:11], v[10:11], v[12:13]
	v_lshlrev_b32_e32 v12, 16, v60
	v_add_f32_e32 v51, v10, v11
	v_lshlrev_b32_e32 v10, 16, v92
	v_and_b32_e32 v11, 0xffff0000, v92
	v_and_b32_e32 v13, 0xffff0000, v60
	v_pk_add_f32 v[10:11], v[10:11], v[12:13]
	v_lshlrev_b32_e32 v12, 16, v93
	v_and_b32_e32 v13, 0xffff0000, v93
	v_pk_add_f32 v[12:13], v[12:13], v[54:55]
	v_add_f32_dpp v0, v0, v0 quad_perm:[2,3,0,1] row_mask:0xf bank_mask:0xf bound_ctrl:1
	v_mov_b32_e32 v56, v11
	v_mov_b32_e32 v57, v13
	v_add_f32_dpp v0, v0, v0 row_half_mirror row_mask:0xf bank_mask:0xf bound_ctrl:1
	v_mov_b32_e32 v54, v10
	v_mov_b32_e32 v55, v12
	v_pk_mul_f32 v[56:57], v[56:57], v[56:57]
	v_add_f32_dpp v0, v0, v0 row_mirror row_mask:0xf bank_mask:0xf bound_ctrl:1
	v_pk_fma_f32 v[54:55], v[54:55], v[54:55], v[56:57]
	v_readlane_b32 s8, v0, 16
	v_readlane_b32 s9, v0, 48
	v_add_f32_e32 v50, v54, v55
	v_readlane_b32 s6, v0, 0
	v_readlane_b32 s7, v0, 32
	v_mov_b32_e32 v54, s8
	v_mov_b32_e32 v55, s9
	v_pk_add_f32 v[54:55], s[6:7], v[54:55]
	s_mov_b32 s83, 0x80000
	v_add_f32_e32 v0, v54, v55
	v_fmamk_f32 v0, v0, 0x3b800000, v252
	v_cmp_gt_f32_e32 vcc, s55, v0
	v_mul_f32_e32 v54, 0x4f800000, v0
	s_nop 0
	v_cndmask_b32_e32 v0, v0, v54, vcc
	v_sqrt_f32_e32 v54, v0
	s_nop 0
	v_add_u32_e32 v55, -1, v54
	v_fma_f32 v56, -v55, v54, v0
	v_cmp_ge_f32_e64 s[6:7], 0, v56
	v_add_u32_e32 v56, 1, v54
	s_nop 0
	v_cndmask_b32_e64 v55, v54, v55, s[6:7]
	v_fma_f32 v54, -v56, v54, v0
	v_cmp_lt_f32_e64 s[6:7], 0, v54
	s_nop 1
	v_cndmask_b32_e64 v54, v55, v56, s[6:7]
	v_mul_f32_e32 v55, 0x37800000, v54
	v_cndmask_b32_e32 v54, v54, v55, vcc
	v_cmp_class_f32_e32 vcc, v0, v253
	s_nop 1
	v_cndmask_b32_e32 v0, v54, v0, vcc
	v_div_scale_f32 v54, s[6:7], v0, v0, 1.0
	v_rcp_f32_e32 v55, v54
	s_nop 0
	v_fma_f32 v56, -v54, v55, 1.0
	v_fmac_f32_e32 v55, v56, v55
	v_div_scale_f32 v56, vcc, 1.0, v0, 1.0
	v_mul_f32_e32 v57, v56, v55
	v_fma_f32 v60, -v54, v57, v56
	v_fmac_f32_e32 v57, v60, v55
	v_fma_f32 v54, -v54, v57, v56
	v_div_fmas_f32 v54, v54, v55, v57
	v_div_fixup_f32 v0, v54, v0, 1.0
	v_pk_mul_f32 v[46:47], v[46:47], v[0:1] op_sel_hi:[1,0]
	v_pk_mul_f32 v[48:49], v[48:49], v[0:1] op_sel_hi:[1,0]
	v_add_f32_dpp v0, v63, v63 quad_perm:[1,0,3,2] row_mask:0xf bank_mask:0xf bound_ctrl:1
	v_lshlrev_b32_e32 v54, 16, v58
	v_and_b32_e32 v55, 0xffff0000, v58
	v_add_f32_dpp v0, v0, v0 quad_perm:[2,3,0,1] row_mask:0xf bank_mask:0xf bound_ctrl:1
	v_lshlrev_b32_e32 v56, 16, v59
	v_and_b32_e32 v57, 0xffff0000, v59
	v_add_f32_dpp v0, v0, v0 row_half_mirror row_mask:0xf bank_mask:0xf bound_ctrl:1
	v_pk_mul_f32 v[48:49], v[48:49], v[56:57]
	v_pk_mul_f32 v[46:47], v[46:47], v[54:55]
	v_add_f32_dpp v0, v0, v0 row_mirror row_mask:0xf bank_mask:0xf bound_ctrl:1
	v_cvt_pk_bf16_f32 v46, v46, v47
	v_cvt_pk_bf16_f32 v47, v48, v49
	v_readlane_b32 s8, v0, 16
	v_readlane_b32 s9, v0, 48
	global_store_dwordx2 v[2:3], v[46:47], off
	v_readlane_b32 s6, v0, 0
	v_readlane_b32 s7, v0, 32
	v_mov_b32_e32 v46, s8
	v_mov_b32_e32 v47, s9
	v_pk_add_f32 v[46:47], s[6:7], v[46:47]
	s_nop 0
	v_add_f32_e32 v0, v46, v47
	v_fmamk_f32 v0, v0, 0x3b800000, v252
	v_cmp_gt_f32_e32 vcc, s55, v0
	v_mul_f32_e32 v46, 0x4f800000, v0
	s_nop 0
	v_cndmask_b32_e32 v0, v0, v46, vcc
	v_sqrt_f32_e32 v46, v0
	s_nop 0
	v_add_u32_e32 v47, -1, v46
	v_fma_f32 v48, -v47, v46, v0
	v_cmp_ge_f32_e64 s[6:7], 0, v48
	v_add_u32_e32 v48, 1, v46
	s_nop 0
	v_cndmask_b32_e64 v47, v46, v47, s[6:7]
	v_fma_f32 v46, -v48, v46, v0
	v_cmp_lt_f32_e64 s[6:7], 0, v46
	s_nop 1
	v_cndmask_b32_e64 v46, v47, v48, s[6:7]
	v_mul_f32_e32 v47, 0x37800000, v46
	v_cndmask_b32_e32 v46, v46, v47, vcc
	v_cmp_class_f32_e32 vcc, v0, v253
	s_nop 1
	v_cndmask_b32_e32 v0, v46, v0, vcc
	v_div_scale_f32 v46, s[6:7], v0, v0, 1.0
	v_rcp_f32_e32 v47, v46
	s_nop 0
	v_fma_f32 v48, -v46, v47, 1.0
	v_fmac_f32_e32 v47, v48, v47
	v_div_scale_f32 v48, vcc, 1.0, v0, 1.0
	v_mul_f32_e32 v49, v48, v47
	v_fma_f32 v54, -v46, v49, v48
	v_fmac_f32_e32 v49, v54, v47
	v_fma_f32 v46, -v46, v49, v48
	v_div_fmas_f32 v46, v46, v47, v49
	v_div_fixup_f32 v0, v46, v0, 1.0
	v_pk_mul_f32 v[42:43], v[42:43], v[0:1] op_sel_hi:[1,0]
	v_pk_mul_f32 v[44:45], v[44:45], v[0:1] op_sel_hi:[1,0]
	v_add_f32_dpp v0, v64, v64 quad_perm:[1,0,3,2] row_mask:0xf bank_mask:0xf bound_ctrl:1
	v_lshlrev_b32_e32 v46, 16, v38
	v_and_b32_e32 v47, 0xffff0000, v38
	v_add_f32_dpp v0, v0, v0 quad_perm:[2,3,0,1] row_mask:0xf bank_mask:0xf bound_ctrl:1
	v_lshlrev_b32_e32 v38, 16, v39
	v_and_b32_e32 v39, 0xffff0000, v39
	v_add_f32_dpp v0, v0, v0 row_half_mirror row_mask:0xf bank_mask:0xf bound_ctrl:1
	v_pk_mul_f32 v[38:39], v[44:45], v[38:39]
	v_pk_mul_f32 v[42:43], v[42:43], v[46:47]
	v_add_f32_dpp v0, v0, v0 row_mirror row_mask:0xf bank_mask:0xf bound_ctrl:1
	v_cvt_pk_bf16_f32 v42, v42, v43
	v_readlane_b32 s8, v0, 16
	v_readlane_b32 s9, v0, 48
	v_cvt_pk_bf16_f32 v43, v38, v39
	v_readlane_b32 s6, v0, 0
	v_readlane_b32 s7, v0, 32
	v_mov_b32_e32 v38, s8
	v_mov_b32_e32 v39, s9
	v_pk_add_f32 v[38:39], s[6:7], v[38:39]
	global_store_dwordx2 v[2:3], v[42:43], off offset:512
	v_add_f32_e32 v0, v38, v39
	v_fmamk_f32 v0, v0, 0x3b800000, v252
	v_cmp_gt_f32_e32 vcc, s55, v0
	v_mul_f32_e32 v38, 0x4f800000, v0
	s_nop 0
	v_cndmask_b32_e32 v0, v0, v38, vcc
	v_sqrt_f32_e32 v38, v0
	s_nop 0
	v_add_u32_e32 v39, -1, v38
	v_fma_f32 v42, -v39, v38, v0
	v_cmp_ge_f32_e64 s[6:7], 0, v42
	v_add_u32_e32 v42, 1, v38
	s_nop 0
	v_cndmask_b32_e64 v39, v38, v39, s[6:7]
	v_fma_f32 v38, -v42, v38, v0
	v_cmp_lt_f32_e64 s[6:7], 0, v38
	s_nop 1
	v_cndmask_b32_e64 v38, v39, v42, s[6:7]
	v_mul_f32_e32 v39, 0x37800000, v38
	v_cndmask_b32_e32 v38, v38, v39, vcc
	v_cmp_class_f32_e32 vcc, v0, v253
	s_nop 1
	v_cndmask_b32_e32 v0, v38, v0, vcc
	v_div_scale_f32 v38, s[6:7], v0, v0, 1.0
	v_rcp_f32_e32 v39, v38
	s_nop 0
	v_fma_f32 v42, -v38, v39, 1.0
	v_fmac_f32_e32 v39, v42, v39
	v_div_scale_f32 v42, vcc, 1.0, v0, 1.0
	v_mul_f32_e32 v43, v42, v39
	v_fma_f32 v44, -v38, v43, v42
	v_fmac_f32_e32 v43, v44, v39
	v_fma_f32 v38, -v38, v43, v42
	v_div_fmas_f32 v38, v38, v39, v43
	v_div_fixup_f32 v0, v38, v0, 1.0
	v_pk_mul_f32 v[36:37], v[36:37], v[0:1] op_sel_hi:[1,0]
	v_pk_mul_f32 v[40:41], v[40:41], v[0:1] op_sel_hi:[1,0]
	v_add_f32_dpp v0, v65, v65 quad_perm:[1,0,3,2] row_mask:0xf bank_mask:0xf bound_ctrl:1
	v_lshlrev_b32_e32 v38, 16, v34
	v_and_b32_e32 v39, 0xffff0000, v34
	v_add_f32_dpp v0, v0, v0 quad_perm:[2,3,0,1] row_mask:0xf bank_mask:0xf bound_ctrl:1
	v_lshlrev_b32_e32 v34, 16, v35
	v_and_b32_e32 v35, 0xffff0000, v35
	v_add_f32_dpp v0, v0, v0 row_half_mirror row_mask:0xf bank_mask:0xf bound_ctrl:1
	v_pk_mul_f32 v[34:35], v[40:41], v[34:35]
	v_pk_mul_f32 v[36:37], v[36:37], v[38:39]
	v_add_f32_dpp v0, v0, v0 row_mirror row_mask:0xf bank_mask:0xf bound_ctrl:1
	v_cvt_pk_bf16_f32 v36, v36, v37
	v_readlane_b32 s8, v0, 16
	v_readlane_b32 s9, v0, 48
	v_cvt_pk_bf16_f32 v37, v34, v35
	v_readlane_b32 s6, v0, 0
	v_readlane_b32 s7, v0, 32
	v_mov_b32_e32 v34, s8
	v_mov_b32_e32 v35, s9
	v_pk_add_f32 v[34:35], s[6:7], v[34:35]
	global_store_dwordx2 v[2:3], v[36:37], off offset:1024
	v_add_f32_e32 v0, v34, v35
	v_fmamk_f32 v0, v0, 0x3b800000, v252
	v_cmp_gt_f32_e32 vcc, s55, v0
	v_mul_f32_e32 v34, 0x4f800000, v0
	s_nop 0
	v_cndmask_b32_e32 v0, v0, v34, vcc
	v_sqrt_f32_e32 v34, v0
	s_nop 0
	v_add_u32_e32 v35, -1, v34
	v_fma_f32 v36, -v35, v34, v0
	v_cmp_ge_f32_e64 s[6:7], 0, v36
	v_add_u32_e32 v36, 1, v34
	s_nop 0
	v_cndmask_b32_e64 v35, v34, v35, s[6:7]
	v_fma_f32 v34, -v36, v34, v0
	v_cmp_lt_f32_e64 s[6:7], 0, v34
	s_nop 1
	v_cndmask_b32_e64 v34, v35, v36, s[6:7]
	v_mul_f32_e32 v35, 0x37800000, v34
	v_cndmask_b32_e32 v34, v34, v35, vcc
	v_cmp_class_f32_e32 vcc, v0, v253
	s_nop 1
	v_cndmask_b32_e32 v0, v34, v0, vcc
	v_div_scale_f32 v34, s[6:7], v0, v0, 1.0
	v_rcp_f32_e32 v35, v34
	s_nop 0
	v_fma_f32 v36, -v34, v35, 1.0
	v_fmac_f32_e32 v35, v36, v35
	v_div_scale_f32 v36, vcc, 1.0, v0, 1.0
	v_mul_f32_e32 v37, v36, v35
	v_fma_f32 v38, -v34, v37, v36
	v_fmac_f32_e32 v37, v38, v35
	v_fma_f32 v34, -v34, v37, v36
	v_div_fmas_f32 v34, v34, v35, v37
	v_div_fixup_f32 v0, v34, v0, 1.0
	v_pk_mul_f32 v[28:29], v[28:29], v[0:1] op_sel_hi:[1,0]
	v_pk_mul_f32 v[32:33], v[32:33], v[0:1] op_sel_hi:[1,0]
	v_add_f32_dpp v0, v53, v53 quad_perm:[1,0,3,2] row_mask:0xf bank_mask:0xf bound_ctrl:1
	v_lshlrev_b32_e32 v34, 16, v30
	v_and_b32_e32 v35, 0xffff0000, v30
	v_add_f32_dpp v0, v0, v0 quad_perm:[2,3,0,1] row_mask:0xf bank_mask:0xf bound_ctrl:1
	v_lshlrev_b32_e32 v30, 16, v31
	v_and_b32_e32 v31, 0xffff0000, v31
	v_add_f32_dpp v0, v0, v0 row_half_mirror row_mask:0xf bank_mask:0xf bound_ctrl:1
	v_pk_mul_f32 v[30:31], v[32:33], v[30:31]
	v_pk_mul_f32 v[28:29], v[28:29], v[34:35]
	v_add_f32_dpp v0, v0, v0 row_mirror row_mask:0xf bank_mask:0xf bound_ctrl:1
	v_cvt_pk_bf16_f32 v28, v28, v29
	v_cvt_pk_bf16_f32 v29, v30, v31
	v_readlane_b32 s8, v0, 16
	v_readlane_b32 s9, v0, 48
	global_store_dwordx2 v[2:3], v[28:29], off offset:1536
	v_readlane_b32 s6, v0, 0
	v_readlane_b32 s7, v0, 32
	v_mov_b32_e32 v28, s8
	v_mov_b32_e32 v29, s9
	v_pk_add_f32 v[28:29], s[6:7], v[28:29]
	s_nop 0
	v_add_f32_e32 v0, v28, v29
	v_fmamk_f32 v0, v0, 0x3b800000, v252
	v_cmp_gt_f32_e32 vcc, s55, v0
	v_mul_f32_e32 v28, 0x4f800000, v0
	s_nop 0
	v_cndmask_b32_e32 v0, v0, v28, vcc
	v_sqrt_f32_e32 v28, v0
	s_nop 0
	v_add_u32_e32 v29, -1, v28
	v_fma_f32 v30, -v29, v28, v0
	v_cmp_ge_f32_e64 s[6:7], 0, v30
	v_add_u32_e32 v30, 1, v28
	s_nop 0
	v_cndmask_b32_e64 v29, v28, v29, s[6:7]
	v_fma_f32 v28, -v30, v28, v0
	v_cmp_lt_f32_e64 s[6:7], 0, v28
	s_nop 1
	v_cndmask_b32_e64 v28, v29, v30, s[6:7]
	v_mul_f32_e32 v29, 0x37800000, v28
	v_cndmask_b32_e32 v28, v28, v29, vcc
	v_cmp_class_f32_e32 vcc, v0, v253
	s_nop 1
	v_cndmask_b32_e32 v0, v28, v0, vcc
	v_div_scale_f32 v28, s[6:7], v0, v0, 1.0
	v_rcp_f32_e32 v29, v28
	s_nop 0
	v_fma_f32 v30, -v28, v29, 1.0
	v_fmac_f32_e32 v29, v30, v29
	v_div_scale_f32 v30, vcc, 1.0, v0, 1.0
	v_mul_f32_e32 v31, v30, v29
	v_fma_f32 v32, -v28, v31, v30
	v_fmac_f32_e32 v31, v32, v29
	v_fma_f32 v28, -v28, v31, v30
	v_div_fmas_f32 v28, v28, v29, v31
	v_div_fixup_f32 v0, v28, v0, 1.0
	v_pk_mul_f32 v[22:23], v[22:23], v[0:1] op_sel_hi:[1,0]
	v_pk_mul_f32 v[24:25], v[24:25], v[0:1] op_sel_hi:[1,0]
	v_add_f32_dpp v0, v52, v52 quad_perm:[1,0,3,2] row_mask:0xf bank_mask:0xf bound_ctrl:1
	v_lshlrev_b32_e32 v28, 16, v26
	v_and_b32_e32 v29, 0xffff0000, v26
	v_add_f32_dpp v0, v0, v0 quad_perm:[2,3,0,1] row_mask:0xf bank_mask:0xf bound_ctrl:1
	v_lshlrev_b32_e32 v26, 16, v27
	v_and_b32_e32 v27, 0xffff0000, v27
	v_add_f32_dpp v0, v0, v0 row_half_mirror row_mask:0xf bank_mask:0xf bound_ctrl:1
	v_pk_mul_f32 v[24:25], v[24:25], v[26:27]
	v_pk_mul_f32 v[22:23], v[22:23], v[28:29]
	v_add_f32_dpp v0, v0, v0 row_mirror row_mask:0xf bank_mask:0xf bound_ctrl:1
	v_cvt_pk_bf16_f32 v22, v22, v23
	v_cvt_pk_bf16_f32 v23, v24, v25
	v_readlane_b32 s8, v0, 16
	v_readlane_b32 s9, v0, 48
	global_store_dwordx2 v[2:3], v[22:23], off offset:2048
	v_readlane_b32 s6, v0, 0
	v_readlane_b32 s7, v0, 32
	v_mov_b32_e32 v22, s8
	v_mov_b32_e32 v23, s9
	v_pk_add_f32 v[22:23], s[6:7], v[22:23]
	s_nop 0
	v_add_f32_e32 v0, v22, v23
	v_fmamk_f32 v0, v0, 0x3b800000, v252
	v_cmp_gt_f32_e32 vcc, s55, v0
	v_mul_f32_e32 v22, 0x4f800000, v0
	s_nop 0
	v_cndmask_b32_e32 v0, v0, v22, vcc
	v_sqrt_f32_e32 v22, v0
	s_nop 0
	v_add_u32_e32 v23, -1, v22
	v_fma_f32 v24, -v23, v22, v0
	v_cmp_ge_f32_e64 s[6:7], 0, v24
	v_add_u32_e32 v24, 1, v22
	s_nop 0
	v_cndmask_b32_e64 v23, v22, v23, s[6:7]
	v_fma_f32 v22, -v24, v22, v0
	v_cmp_lt_f32_e64 s[6:7], 0, v22
	s_nop 1
	v_cndmask_b32_e64 v22, v23, v24, s[6:7]
	v_mul_f32_e32 v23, 0x37800000, v22
	v_cndmask_b32_e32 v22, v22, v23, vcc
	v_cmp_class_f32_e32 vcc, v0, v253
	s_nop 1
	v_cndmask_b32_e32 v0, v22, v0, vcc
	v_div_scale_f32 v22, s[6:7], v0, v0, 1.0
	v_rcp_f32_e32 v23, v22
	s_nop 0
	v_fma_f32 v24, -v22, v23, 1.0
	v_fmac_f32_e32 v23, v24, v23
	v_div_scale_f32 v24, vcc, 1.0, v0, 1.0
	v_mul_f32_e32 v25, v24, v23
	v_fma_f32 v26, -v22, v25, v24
	v_fmac_f32_e32 v25, v26, v23
	v_fma_f32 v22, -v22, v25, v24
	v_div_fmas_f32 v22, v22, v23, v25
	v_div_fixup_f32 v0, v22, v0, 1.0
	v_pk_mul_f32 v[18:19], v[18:19], v[0:1] op_sel_hi:[1,0]
	v_pk_mul_f32 v[20:21], v[20:21], v[0:1] op_sel_hi:[1,0]
	v_add_f32_dpp v0, v51, v51 quad_perm:[1,0,3,2] row_mask:0xf bank_mask:0xf bound_ctrl:1
	v_lshlrev_b32_e32 v22, 16, v8
	v_and_b32_e32 v23, 0xffff0000, v8
	v_add_f32_dpp v0, v0, v0 quad_perm:[2,3,0,1] row_mask:0xf bank_mask:0xf bound_ctrl:1
	v_lshlrev_b32_e32 v8, 16, v9
	v_and_b32_e32 v9, 0xffff0000, v9
	v_add_f32_dpp v0, v0, v0 row_half_mirror row_mask:0xf bank_mask:0xf bound_ctrl:1
	v_pk_mul_f32 v[8:9], v[20:21], v[8:9]
	v_pk_mul_f32 v[18:19], v[18:19], v[22:23]
	v_add_f32_dpp v0, v0, v0 row_mirror row_mask:0xf bank_mask:0xf bound_ctrl:1
	v_cvt_pk_bf16_f32 v18, v18, v19
	v_readlane_b32 s8, v0, 16
	v_readlane_b32 s9, v0, 48
	v_cvt_pk_bf16_f32 v19, v8, v9
	v_readlane_b32 s6, v0, 0
	v_readlane_b32 s7, v0, 32
	v_mov_b32_e32 v8, s8
	v_mov_b32_e32 v9, s9
	v_pk_add_f32 v[8:9], s[6:7], v[8:9]
	global_store_dwordx2 v[2:3], v[18:19], off offset:2560
	v_add_f32_e32 v0, v8, v9
	v_fmamk_f32 v0, v0, 0x3b800000, v252
	v_cmp_gt_f32_e32 vcc, s55, v0
	v_mul_f32_e32 v8, 0x4f800000, v0
	s_nop 0
	v_cndmask_b32_e32 v0, v0, v8, vcc
	v_sqrt_f32_e32 v8, v0
	s_nop 0
	v_add_u32_e32 v9, -1, v8
	v_fma_f32 v18, -v9, v8, v0
	v_cmp_ge_f32_e64 s[6:7], 0, v18
	v_add_u32_e32 v18, 1, v8
	s_nop 0
	v_cndmask_b32_e64 v9, v8, v9, s[6:7]
	v_fma_f32 v8, -v18, v8, v0
	v_cmp_lt_f32_e64 s[6:7], 0, v8
	s_nop 1
	v_cndmask_b32_e64 v8, v9, v18, s[6:7]
	v_mul_f32_e32 v9, 0x37800000, v8
	v_cndmask_b32_e32 v8, v8, v9, vcc
	v_cmp_class_f32_e32 vcc, v0, v253
	s_nop 1
	v_cndmask_b32_e32 v0, v8, v0, vcc
	v_div_scale_f32 v8, s[6:7], v0, v0, 1.0
	v_rcp_f32_e32 v9, v8
	s_nop 0
	v_fma_f32 v18, -v8, v9, 1.0
	v_fmac_f32_e32 v9, v18, v9
	v_div_scale_f32 v18, vcc, 1.0, v0, 1.0
	v_mul_f32_e32 v19, v18, v9
	v_fma_f32 v20, -v8, v19, v18
	v_fmac_f32_e32 v19, v20, v9
	v_fma_f32 v8, -v8, v19, v18
	v_div_fmas_f32 v8, v8, v9, v19
	v_div_fixup_f32 v0, v8, v0, 1.0
	v_pk_mul_f32 v[14:15], v[14:15], v[0:1] op_sel_hi:[1,0]
	v_pk_mul_f32 v[16:17], v[16:17], v[0:1] op_sel_hi:[1,0]
	v_add_f32_dpp v0, v50, v50 quad_perm:[1,0,3,2] row_mask:0xf bank_mask:0xf bound_ctrl:1
	v_lshlrev_b32_e32 v8, 16, v6
	v_and_b32_e32 v9, 0xffff0000, v6
	v_add_f32_dpp v0, v0, v0 quad_perm:[2,3,0,1] row_mask:0xf bank_mask:0xf bound_ctrl:1
	v_lshlrev_b32_e32 v6, 16, v7
	v_and_b32_e32 v7, 0xffff0000, v7
	v_add_f32_dpp v0, v0, v0 row_half_mirror row_mask:0xf bank_mask:0xf bound_ctrl:1
	v_pk_mul_f32 v[6:7], v[16:17], v[6:7]
	v_pk_mul_f32 v[8:9], v[14:15], v[8:9]
	v_add_f32_dpp v0, v0, v0 row_mirror row_mask:0xf bank_mask:0xf bound_ctrl:1
	v_cvt_pk_bf16_f32 v8, v8, v9
	v_readlane_b32 s8, v0, 16
	v_readlane_b32 s9, v0, 48
	v_cvt_pk_bf16_f32 v9, v6, v7
	v_readlane_b32 s6, v0, 0
	v_readlane_b32 s7, v0, 32
	v_mov_b32_e32 v6, s8
	v_mov_b32_e32 v7, s9
	v_pk_add_f32 v[6:7], s[6:7], v[6:7]
	global_store_dwordx2 v[2:3], v[8:9], off offset:3072
	v_add_f32_e32 v0, v6, v7
	v_fmamk_f32 v0, v0, 0x3b800000, v252
	v_cmp_gt_f32_e32 vcc, s55, v0
	v_mul_f32_e32 v6, 0x4f800000, v0
	s_nop 0
	v_cndmask_b32_e32 v0, v0, v6, vcc
	v_sqrt_f32_e32 v6, v0
	s_nop 0
	v_add_u32_e32 v7, -1, v6
	v_fma_f32 v8, -v7, v6, v0
	v_cmp_ge_f32_e64 s[6:7], 0, v8
	v_add_u32_e32 v8, 1, v6
	s_nop 0
	v_cndmask_b32_e64 v7, v6, v7, s[6:7]
	v_fma_f32 v6, -v8, v6, v0
	v_cmp_lt_f32_e64 s[6:7], 0, v6
	s_nop 1
	v_cndmask_b32_e64 v6, v7, v8, s[6:7]
	v_mul_f32_e32 v7, 0x37800000, v6
	v_cndmask_b32_e32 v6, v6, v7, vcc
	v_cmp_class_f32_e32 vcc, v0, v253
	s_nop 1
	v_cndmask_b32_e32 v0, v6, v0, vcc
	v_div_scale_f32 v6, s[6:7], v0, v0, 1.0
	v_rcp_f32_e32 v7, v6
	s_nop 0
	v_fma_f32 v8, -v6, v7, 1.0
	v_fmac_f32_e32 v7, v8, v7
	v_div_scale_f32 v8, vcc, 1.0, v0, 1.0
	v_mul_f32_e32 v9, v8, v7
	v_fma_f32 v14, -v6, v9, v8
	v_fmac_f32_e32 v9, v14, v7
	v_fma_f32 v6, -v6, v9, v8
	v_div_fmas_f32 v6, v6, v7, v9
	v_div_fixup_f32 v0, v6, v0, 1.0
	s_waitcnt vmcnt(23)
	v_lshlrev_b32_e32 v6, 16, v4
	v_and_b32_e32 v7, 0xffff0000, v4
	v_lshlrev_b32_e32 v4, 16, v5
	v_and_b32_e32 v5, 0xffff0000, v5
	v_pk_mul_f32 v[8:9], v[10:11], v[0:1] op_sel_hi:[1,0]
	v_pk_mul_f32 v[10:11], v[12:13], v[0:1] op_sel_hi:[1,0]
	v_pk_mul_f32 v[6:7], v[8:9], v[6:7]
	v_pk_mul_f32 v[4:5], v[10:11], v[4:5]
	v_cvt_pk_bf16_f32 v6, v6, v7
	v_cvt_pk_bf16_f32 v7, v4, v5
	global_store_dwordx2 v[2:3], v[6:7], off offset:3584

; #define GAS __attribute__((address_space(1)))
; #define LAS __attribute__((address_space(3)))
; #define NR_LOAD(dst, k_) do { const GAS v2u* xr_ = (const GAS v2u*)(X + (size_t)(nw + 2048 * (k_)) * D) + F.lane; \
;         _Pragma("unroll") for (int j = 0; j < 8; ++j) dst[j] = __builtin_nontemporal_load(xr_ + 64 * j); } while (0)
; __device__ __forceinline__ void norm_mod_phase2(const Args& a, Frame& F, const float* gain, const float* modl, int sh_off, int sc_off, int nrows, const float* slab_gate) {
;     ...
;     const int nw = F.vcu * NWAVES + F.wave;
;     bf16* X = (bf16*)(a.ws + WS_X); bf16* HN = (bf16*)(a.ws + WS_HN);
;     LAS float* CA = (LAS float*)F.lds; LAS float* CB = CA + 5 * D;
;     v2u r0[8], r1[8], r2[8], r3[8], r4[8], r5[8], r6[8], r7[8];
;     ...
;     NR_LOAD(r0, 0); NR_LOAD(r1, 1); NR_LOAD(r2, 2); NR_LOAD(r3, 3); NR_LOAD(r4, 4); NR_LOAD(r5, 5); NR_LOAD(r6, 6); NR_LOAD(r7, 7);
;     { const GAS f32x4* g4 = (const GAS f32x4*)gain;
;       for (int q = F.tid; q < 5 * D / 4; q += NWAVES * 64) { const int bq = q >> 9, cq = q & 511; const GAS f32x4* mb4 = (const GAS f32x4*)(modl + (size_t)bq * MOD_LD);
;           ((LAS f32x4*)CA)[q] = g4[cq] * (mb4[sc_off / 4 + cq] + 1.0f); ((LAS f32x4*)CB)[q] = mb4[sh_off / 4 + cq]; } }
.LBB0_1042:
	s_andn2_b64 vcc, exec, s[8:9]
	s_cbranch_vccnz .LBB0_1051
	s_getreg_b32 s6, hwreg(HW_REG_HW_ID, 0, 6)
	s_lshl_b32 s6, s6, 2
	s_add_i32 s6, s6, 0
	s_add_i32 s6, s6, 0x20540
	v_mov_b32_e32 v0, s6
	ds_read_b32 v0, v0
	v_mov_b64_e32 v[2:3], s[0:1]
	v_mov_b32_e32 v7, v1
	s_waitcnt lgkmcnt(0)
	v_readfirstlane_b32 s6, v0
	v_mbcnt_lo_u32_b32 v0, -1, 0
	v_mbcnt_hi_u32_b32 v0, -1, v0
	s_nop 1
	v_lshl_add_u32 v142, s6, 6, v0
	v_mov_b32_e32 v136, s72
	v_mov_b32_e32 v137, s73
	v_readfirstlane_b32 s6, v142
	s_ashr_i32 s6, s6, 6
	s_add_i32 s10, s6, s91
	s_mov_b64 s[6:7], 0x400000
	s_ashr_i32 s11, s10, 31
	v_and_b32_e32 v147, 63, v142
	s_add_i32 s78, s10, 0x800
	v_lshlrev_b32_e32 v6, 3, v147
	s_ashr_i32 s79, s78, 31
	s_add_i32 s36, s10, 0x1000
	s_ashr_i32 s37, s36, 31
	s_add_i32 s30, s10, 0x1800
	s_ashr_i32 s31, s30, 31
	s_add_i32 s26, s10, 0x2000
	s_ashr_i32 s27, s26, 31
	s_add_i32 s22, s10, 0x2800
	s_ashr_i32 s23, s22, 31
	s_add_i32 s18, s10, 0x3000
	s_ashr_i32 s19, s18, 31
	s_add_i32 s14, s10, 0x3800
	s_ashr_i32 s15, s14, 31
	s_waitcnt vmcnt(0) lgkmcnt(0)
	v_lshl_add_u64 v[8:9], v[136:137], 0, s[6:7]
	s_lshl_b64 s[6:7], s[10:11], 12
	v_lshl_add_u64 v[2:3], v[8:9], 0, s[6:7]
	v_lshl_add_u64 v[2:3], v[2:3], 0, v[6:7]
	s_lshl_b64 s[6:7], s[78:79], 12
	v_and_b32_e32 v184, 0x1ff, v142
	v_lshlrev_b32_e32 v184, 4, v184
	v_mov_b32_e32 v185, 0
	v_mov_b32_e32 v186, s76
	v_lshlrev_b32_e32 v186, 13, v186
	v_mov_b32_e32 v187, 0
	v_lshl_add_u64 v[188:189], v[74:75], 0, v[186:187]
	v_lshl_add_u64 v[188:189], v[188:189], 0, v[184:185]
	global_load_dwordx4 v[192:195], v[188:189], off
	v_add_u32_e32 v196, 0x8000, v184
	v_add_u32_e32 v201, 0x6000, v184
	v_add_u32_e32 v197, 0x14000, v184
	v_add_u32_e32 v202, 0x12000, v184
	v_add_u32_e32 v198, 0x20000, v184
	v_add_u32_e32 v203, 0x1e000, v184
	v_add_u32_e32 v199, 0x2c000, v184
	v_add_u32_e32 v204, 0x2a000, v184
	v_add_u32_e32 v200, 0x38000, v184
	v_add_u32_e32 v205, 0x36000, v184
	global_load_dwordx4 v[208:211], v196, s[86:87]
	global_load_dwordx4 v[228:231], v201, s[86:87]
	global_load_dwordx4 v[212:215], v197, s[86:87]
	global_load_dwordx4 v[232:235], v202, s[86:87]
	global_load_dwordx4 v[216:219], v198, s[86:87]
	global_load_dwordx4 v[236:239], v203, s[86:87]
	global_load_dwordx4 v[220:223], v199, s[86:87]
	global_load_dwordx4 v[240:243], v204, s[86:87]
	global_load_dwordx4 v[224:227], v200, s[86:87]
	global_load_dwordx4 v[244:247], v205, s[86:87]
	global_load_dwordx2 v[140:141], v[2:3], off
	global_load_dwordx2 v[138:139], v[2:3], off offset:512
	global_load_dwordx2 v[134:135], v[2:3], off offset:1024
	global_load_dwordx2 v[132:133], v[2:3], off offset:1536
	global_load_dwordx2 v[130:131], v[2:3], off offset:2048
	global_load_dwordx2 v[128:129], v[2:3], off offset:2560
	global_load_dwordx2 v[126:127], v[2:3], off offset:3072
	global_load_dwordx2 v[124:125], v[2:3], off offset:3584
	v_lshl_add_u64 v[2:3], v[8:9], 0, s[6:7]
	v_lshl_add_u64 v[2:3], v[2:3], 0, v[6:7]
	s_lshl_b64 s[6:7], s[36:37], 12
	global_load_dwordx2 v[122:123], v[2:3], off
	global_load_dwordx2 v[120:121], v[2:3], off offset:512
	global_load_dwordx2 v[118:119], v[2:3], off offset:1024
	global_load_dwordx2 v[116:117], v[2:3], off offset:1536
	global_load_dwordx2 v[114:115], v[2:3], off offset:2048
	global_load_dwordx2 v[112:113], v[2:3], off offset:2560
	global_load_dwordx2 v[110:111], v[2:3], off offset:3072
	global_load_dwordx2 v[108:109], v[2:3], off offset:3584
	v_lshl_add_u64 v[2:3], v[8:9], 0, s[6:7]
	v_lshl_add_u64 v[2:3], v[2:3], 0, v[6:7]
	s_lshl_b64 s[6:7], s[30:31], 12
	global_load_dwordx2 v[106:107], v[2:3], off
	global_load_dwordx2 v[104:105], v[2:3], off offset:512
	global_load_dwordx2 v[102:103], v[2:3], off offset:1024
	global_load_dwordx2 v[100:101], v[2:3], off offset:1536
	global_load_dwordx2 v[98:99], v[2:3], off offset:2048
	global_load_dwordx2 v[96:97], v[2:3], off offset:2560
	global_load_dwordx2 v[94:95], v[2:3], off offset:3072
	global_load_dwordx2 v[92:93], v[2:3], off offset:3584
	v_lshl_add_u64 v[2:3], v[8:9], 0, s[6:7]
	v_lshl_add_u64 v[2:3], v[2:3], 0, v[6:7]
	s_lshl_b64 s[6:7], s[26:27], 12
	global_load_dwordx2 v[90:91], v[2:3], off
	global_load_dwordx2 v[88:89], v[2:3], off offset:512
	global_load_dwordx2 v[86:87], v[2:3], off offset:1024
	global_load_dwordx2 v[84:85], v[2:3], off offset:1536
	global_load_dwordx2 v[82:83], v[2:3], off offset:2048
	global_load_dwordx2 v[80:81], v[2:3], off offset:2560
	global_load_dwordx2 v[78:79], v[2:3], off offset:3072
	global_load_dwordx2 v[76:77], v[2:3], off offset:3584
	v_lshl_add_u64 v[2:3], v[8:9], 0, s[6:7]
	v_lshl_add_u64 v[2:3], v[2:3], 0, v[6:7]
	s_lshl_b64 s[6:7], s[22:23], 12
	global_load_dwordx2 v[72:73], v[2:3], off
	global_load_dwordx2 v[70:71], v[2:3], off offset:512
	global_load_dwordx2 v[68:69], v[2:3], off offset:1024
	global_load_dwordx2 v[66:67], v[2:3], off offset:1536
	global_load_dwordx2 v[64:65], v[2:3], off offset:2048
	global_load_dwordx2 v[62:63], v[2:3], off offset:2560
	global_load_dwordx2 v[60:61], v[2:3], off offset:3072
	global_load_dwordx2 v[58:59], v[2:3], off offset:3584
	v_lshl_add_u64 v[2:3], v[8:9], 0, s[6:7]
	v_lshl_add_u64 v[2:3], v[2:3], 0, v[6:7]
	s_lshl_b64 s[6:7], s[18:19], 12
	global_load_dwordx2 v[56:57], v[2:3], off
	global_load_dwordx2 v[54:55], v[2:3], off offset:512
	global_load_dwordx2 v[52:53], v[2:3], off offset:1024
	global_load_dwordx2 v[50:51], v[2:3], off offset:1536
	global_load_dwordx2 v[48:49], v[2:3], off offset:2048
	global_load_dwordx2 v[46:47], v[2:3], off offset:2560
	global_load_dwordx2 v[44:45], v[2:3], off offset:3072
	global_load_dwordx2 v[42:43], v[2:3], off offset:3584
	v_lshl_add_u64 v[2:3], v[8:9], 0, s[6:7]
	v_lshl_add_u64 v[2:3], v[2:3], 0, v[6:7]
	s_lshl_b64 s[6:7], s[14:15], 12
	global_load_dwordx2 v[40:41], v[2:3], off
	global_load_dwordx2 v[38:39], v[2:3], off offset:512
	global_load_dwordx2 v[36:37], v[2:3], off offset:1024
	global_load_dwordx2 v[34:35], v[2:3], off offset:1536
	global_load_dwordx2 v[32:33], v[2:3], off offset:2048
	global_load_dwordx2 v[30:31], v[2:3], off offset:2560
	global_load_dwordx2 v[28:29], v[2:3], off offset:3072
	global_load_dwordx2 v[26:27], v[2:3], off offset:3584
	v_lshl_add_u64 v[2:3], v[8:9], 0, s[6:7]
	v_lshl_add_u64 v[2:3], v[2:3], 0, v[6:7]
	global_load_dwordx2 v[24:25], v[2:3], off
	global_load_dwordx2 v[22:23], v[2:3], off offset:512
	global_load_dwordx2 v[20:21], v[2:3], off offset:1024
	global_load_dwordx2 v[18:19], v[2:3], off offset:1536
	global_load_dwordx2 v[16:17], v[2:3], off offset:2048
	global_load_dwordx2 v[14:15], v[2:3], off offset:2560
	global_load_dwordx2 v[12:13], v[2:3], off offset:3072
	global_load_dwordx2 v[10:11], v[2:3], off offset:3584
	s_waitcnt vmcnt(62)
; #define GAS __attribute__((address_space(1)))
; #define LAS __attribute__((address_space(3)))
; #define NR_LOAD(dst, k_) do { const GAS v2u* xr_ = (const GAS v2u*)(X + (size_t)(nw + 2048 * (k_)) * D) + F.lane; \
;         _Pragma("unroll") for (int j = 0; j < 8; ++j) dst[j] = __builtin_nontemporal_load(xr_ + 64 * j); } while (0)
; __device__ __forceinline__ void norm_mod_phase2(const Args& a, Frame& F, const float* gain, const float* modl, int sh_off, int sc_off, int nrows, const float* slab_gate) {
;     ...
;     NR_LOAD(r0, 0); NR_LOAD(r1, 1); NR_LOAD(r2, 2); NR_LOAD(r3, 3); NR_LOAD(r4, 4); NR_LOAD(r5, 5); NR_LOAD(r6, 6); NR_LOAD(r7, 7);
;     { const GAS f32x4* g4 = (const GAS f32x4*)gain;
;       for (int q = F.tid; q < 5 * D / 4; q += NWAVES * 64) { const int bq = q >> 9, cq = q & 511; const GAS f32x4* mb4 = (const GAS f32x4*)(modl + (size_t)bq * MOD_LD);
;           ((LAS f32x4*)CA)[q] = g4[cq] * (mb4[sc_off / 4 + cq] + 1.0f); ((LAS f32x4*)CB)[q] = mb4[sh_off / 4 + cq]; } }
;     asm volatile("s_waitcnt lgkmcnt(0)" ::: "memory"); __builtin_amdgcn_s_barrier(); asm volatile("" ::: "memory");
	v_lshl_add_u32 v184, v142, 4, 0
	v_add_u32_e32 v185, 0xa000, v184
	v_pk_add_f32 v[210:211], v[210:211], 1.0 op_sel_hi:[1,0]
	v_pk_add_f32 v[208:209], v[208:209], 1.0 op_sel_hi:[1,0]
	v_pk_mul_f32 v[210:211], v[194:195], v[210:211]
	v_pk_mul_f32 v[208:209], v[192:193], v[208:209]
	ds_write_b128 v184, v[208:211]
	ds_write_b128 v185, v[228:231]
	v_pk_add_f32 v[214:215], v[214:215], 1.0 op_sel_hi:[1,0]
	v_pk_add_f32 v[212:213], v[212:213], 1.0 op_sel_hi:[1,0]
	v_pk_mul_f32 v[214:215], v[194:195], v[214:215]
	v_pk_mul_f32 v[212:213], v[192:193], v[212:213]
	ds_write_b128 v184, v[212:215] offset:8192
	ds_write_b128 v185, v[232:235] offset:8192
	v_pk_add_f32 v[218:219], v[218:219], 1.0 op_sel_hi:[1,0]
	v_pk_add_f32 v[216:217], v[216:217], 1.0 op_sel_hi:[1,0]
	v_pk_mul_f32 v[218:219], v[194:195], v[218:219]
	v_pk_mul_f32 v[216:217], v[192:193], v[216:217]
	ds_write_b128 v184, v[216:219] offset:16384
	ds_write_b128 v185, v[236:239] offset:16384
	v_pk_add_f32 v[222:223], v[222:223], 1.0 op_sel_hi:[1,0]
	v_pk_add_f32 v[220:221], v[220:221], 1.0 op_sel_hi:[1,0]
	v_pk_mul_f32 v[222:223], v[194:195], v[222:223]
	v_pk_mul_f32 v[220:221], v[192:193], v[220:221]
	ds_write_b128 v184, v[220:223] offset:24576
	ds_write_b128 v185, v[240:243] offset:24576
	v_pk_add_f32 v[226:227], v[226:227], 1.0 op_sel_hi:[1,0]
	v_pk_add_f32 v[224:225], v[224:225], 1.0 op_sel_hi:[1,0]
	v_pk_mul_f32 v[226:227], v[194:195], v[226:227]
	v_pk_mul_f32 v[224:225], v[192:193], v[224:225]
	ds_write_b128 v184, v[224:227] offset:32768
	ds_write_b128 v185, v[244:247] offset:32768
	s_waitcnt vmcnt(62)
	v_cvt_f32_f16_sdwa v153, v140 dst_sel:DWORD dst_unused:UNUSED_PAD src0_sel:WORD_1
	v_cvt_f32_f16_sdwa v149, v138 dst_sel:DWORD dst_unused:UNUSED_PAD src0_sel:WORD_1
	v_cvt_f32_f16_e32 v152, v140
	v_cvt_f32_f16_sdwa v155, v141 dst_sel:DWORD dst_unused:UNUSED_PAD src0_sel:WORD_1
	v_cvt_f32_f16_e32 v148, v138
	v_cvt_f32_f16_sdwa v151, v139 dst_sel:DWORD dst_unused:UNUSED_PAD src0_sel:WORD_1
	v_cvt_f32_f16_e32 v154, v141
	v_cvt_f32_f16_e32 v150, v139
	s_waitcnt vmcnt(61)
	v_cvt_f32_f16_sdwa v139, v134 dst_sel:DWORD dst_unused:UNUSED_PAD src0_sel:WORD_1
	v_cvt_f32_f16_sdwa v141, v135 dst_sel:DWORD dst_unused:UNUSED_PAD src0_sel:WORD_1
	s_mov_b64 s[6:7], 0x8c00000
	v_mov_b32_e32 v74, v153
	v_mov_b32_e32 v75, v149
	v_cvt_f32_f16_e32 v138, v134
	v_cvt_f32_f16_e32 v140, v135
	v_lshl_add_u64 v[2:3], v[136:137], 0, s[6:7]
	v_mov_b32_e32 v4, v152
	v_mov_b32_e32 v5, v148
	v_pk_mul_f32 v[74:75], v[74:75], v[74:75]
	v_mov_b32_e32 v136, v155
	v_mov_b32_e32 v137, v151
	v_pk_fma_f32 v[4:5], v[4:5], v[4:5], v[74:75]
	v_mov_b32_e32 v74, v154
	v_mov_b32_e32 v75, v150
	v_pk_mul_f32 v[136:137], v[136:137], v[136:137]
	v_mov_b32_e32 v134, v139
	v_pk_fma_f32 v[74:75], v[74:75], v[74:75], v[136:137]
	v_mov_b32_e32 v135, v141
	s_waitcnt vmcnt(60)
	v_cvt_f32_f16_sdwa v143, v132 dst_sel:DWORD dst_unused:UNUSED_PAD src0_sel:WORD_1
	v_pk_add_f32 v[4:5], v[4:5], v[74:75]
	v_mov_b32_e32 v74, v138
	v_mov_b32_e32 v75, v140
	v_pk_mul_f32 v[134:135], v[134:135], v[134:135]
	v_cvt_f32_f16_e32 v142, v132
	v_cvt_f32_f16_sdwa v145, v133 dst_sel:DWORD dst_unused:UNUSED_PAD src0_sel:WORD_1
	v_pk_fma_f32 v[74:75], v[74:75], v[74:75], v[134:135]
	v_cvt_f32_f16_e32 v144, v133
	s_waitcnt vmcnt(59)
	v_cvt_f32_f16_sdwa v133, v130 dst_sel:DWORD dst_unused:UNUSED_PAD src0_sel:WORD_1
	v_cvt_f32_f16_e32 v132, v130
	v_cvt_f32_f16_sdwa v135, v131 dst_sel:DWORD dst_unused:UNUSED_PAD src0_sel:WORD_1
	v_cvt_f32_f16_e32 v134, v131
	v_mul_f32_e32 v0, v143, v143
	v_pk_fma_f32 v[136:137], v[142:143], v[142:143], v[0:1] op_sel_hi:[1,1,0]
	v_mul_f32_e32 v0, v145, v145
	v_pk_add_f32 v[4:5], v[4:5], v[4:5] op_sel:[0,1] op_sel_hi:[1,0]
	v_pk_add_f32 v[74:75], v[74:75], v[74:75] op_sel:[0,1] op_sel_hi:[1,0]
	v_pk_fma_f32 v[156:157], v[144:145], v[144:145], v[0:1] op_sel_hi:[1,1,0]
	v_pk_mul_f32 v[130:131], v[132:133], v[132:133]
	v_pk_mul_f32 v[158:159], v[134:135], v[134:135]
	v_mov_b32_e32 v5, v130
	v_mov_b32_e32 v75, v131
	v_mov_b32_e32 v137, v158
	v_mov_b32_e32 v157, v159
	v_pk_add_f32 v[4:5], v[4:5], v[74:75]
	v_pk_add_f32 v[74:75], v[136:137], v[156:157]
	s_waitcnt vmcnt(58)
	v_cvt_f32_f16_sdwa v131, v128 dst_sel:DWORD dst_unused:UNUSED_PAD src0_sel:WORD_1
	v_cvt_f32_f16_sdwa v137, v129 dst_sel:DWORD dst_unused:UNUSED_PAD src0_sel:WORD_1
	v_cvt_f32_f16_e32 v130, v128
	v_cvt_f32_f16_e32 v136, v129
	v_pk_add_f32 v[4:5], v[4:5], v[74:75]
	v_mov_b32_e32 v74, v131
	v_mov_b32_e32 v75, v137
	v_pk_add_f32 v[156:157], v[4:5], v[4:5] op_sel:[0,1] op_sel_hi:[1,0]
	v_mov_b32_e32 v4, v130
	v_mov_b32_e32 v5, v136
	v_pk_mul_f32 v[74:75], v[74:75], v[74:75]
	s_waitcnt vmcnt(57)
	v_cvt_f32_f16_sdwa v129, v127 dst_sel:DWORD dst_unused:UNUSED_PAD src0_sel:WORD_1
	v_pk_fma_f32 v[4:5], v[4:5], v[4:5], v[74:75]
	v_cvt_f32_f16_e32 v128, v127
	v_pk_add_f32 v[158:159], v[4:5], v[4:5] op_sel:[0,1] op_sel_hi:[1,0]
	v_cvt_f32_f16_sdwa v5, v126 dst_sel:DWORD dst_unused:UNUSED_PAD src0_sel:WORD_1
	v_cvt_f32_f16_e32 v4, v126
	s_waitcnt vmcnt(56)
	v_cvt_f32_f16_sdwa v75, v124 dst_sel:DWORD dst_unused:UNUSED_PAD src0_sel:WORD_1
	v_cvt_f32_f16_e32 v74, v124
	v_cvt_f32_f16_sdwa v127, v125 dst_sel:DWORD dst_unused:UNUSED_PAD src0_sel:WORD_1
	v_cvt_f32_f16_e32 v126, v125
	v_mul_f32_e32 v0, v5, v5
	v_pk_fma_f32 v[160:161], v[4:5], v[4:5], v[0:1] op_sel_hi:[1,1,0]
	v_mul_f32_e32 v0, v129, v129
	v_pk_fma_f32 v[162:163], v[128:129], v[128:129], v[0:1] op_sel_hi:[1,1,0]
	v_pk_mul_f32 v[124:125], v[74:75], v[74:75]
	v_pk_mul_f32 v[164:165], v[126:127], v[126:127]
	v_mov_b32_e32 v157, v124
	v_mov_b32_e32 v159, v125
	v_mov_b32_e32 v161, v164
	v_mov_b32_e32 v163, v165
	v_pk_add_f32 v[124:125], v[156:157], v[158:159]
	v_pk_add_f32 v[156:157], v[160:161], v[162:163]
	s_waitcnt lgkmcnt(0)
	s_barrier
; #define GAS __attribute__((address_space(1)))
; #define LAS __attribute__((address_space(3)))
; #define NR_LOAD(dst, k_) do { const GAS v2u* xr_ = (const GAS v2u*)(X + (size_t)(nw + 2048 * (k_)) * D) + F.lane; \
;         _Pragma("unroll") for (int j = 0; j < 8; ++j) dst[j] = __builtin_nontemporal_load(xr_ + 64 * j); } while (0)
; __device__ __forceinline__ void norm_mod_phase2(const Args& a, Frame& F, const float* gain, const float* modl, int sh_off, int sc_off, int nrows, const float* slab_gate) {
;     ...
;     NR_LOAD(r0, 0); NR_LOAD(r1, 1); NR_LOAD(r2, 2); NR_LOAD(r3, 3); NR_LOAD(r4, 4); NR_LOAD(r5, 5); NR_LOAD(r6, 6); NR_LOAD(r7, 7);
;     { const GAS f32x4* g4 = (const GAS f32x4*)gain;
;       for (int q = F.tid; q < 5 * D / 4; q += NWAVES * 64) { const int bq = q >> 9, cq = q & 511; const GAS f32x4* mb4 = (const GAS f32x4*)(modl + (size_t)bq * MOD_LD);
;           ((LAS f32x4*)CA)[q] = g4[cq] * (mb4[sc_off / 4 + cq] + 1.0f); ((LAS f32x4*)CB)[q] = mb4[sh_off / 4 + cq]; } }
;     asm volatile("s_waitcnt lgkmcnt(0)" ::: "memory"); __builtin_amdgcn_s_barrier(); asm volatile("" ::: "memory");
;     NR_FINISH(r0, nw,            (nw) >> 12);
;     NR_FINISH(r1, nw + 2048,     (nw + 2048) >> 12);
;     NR_FINISH(r2, nw + 2 * 2048, (nw + 2 * 2048) >> 12);
	v_pk_add_f32 v[124:125], v[124:125], v[156:157]
	s_lshl_b64 s[12:13], s[10:11], 11
	v_add_f32_e32 v0, v124, v125
	s_lshl_b64 s[48:49], s[78:79], 11
	s_lshl_b64 s[40:41], s[36:37], 11
	v_add_f32_dpp v0, v0, v0 quad_perm:[1,0,3,2] row_mask:0xf bank_mask:0xf bound_ctrl:1
	s_lshl_b64 s[34:35], s[30:31], 11
	s_lshl_b64 s[28:29], s[26:27], 11
	v_add_f32_dpp v0, v0, v0 quad_perm:[2,3,0,1] row_mask:0xf bank_mask:0xf bound_ctrl:1
	s_lshl_b64 s[24:25], s[22:23], 11
	s_lshl_b64 s[20:21], s[18:19], 11
	v_add_f32_dpp v0, v0, v0 row_half_mirror row_mask:0xf bank_mask:0xf bound_ctrl:1
	s_lshl_b64 s[16:17], s[14:15], 11
	s_nop 0
	v_add_f32_dpp v0, v0, v0 row_mirror row_mask:0xf bank_mask:0xf bound_ctrl:1
	s_nop 0
	v_readlane_b32 s8, v0, 16
	v_readlane_b32 s9, v0, 48
	v_readlane_b32 s6, v0, 0
	v_readlane_b32 s7, v0, 32
	v_mov_b32_e32 v124, s8
	v_mov_b32_e32 v125, s9
	v_pk_add_f32 v[124:125], s[6:7], v[124:125]
	s_nop 0
	v_add_f32_e32 v0, v124, v125
	v_fmamk_f32 v0, v0, 0x3a000000, v252
	v_cmp_gt_f32_e32 vcc, s55, v0
	v_mul_f32_e32 v7, 0x4f800000, v0
	s_nop 0
	v_cndmask_b32_e32 v0, v0, v7, vcc
	v_sqrt_f32_e32 v7, v0
	s_nop 0
	v_add_u32_e32 v124, -1, v7
	v_fma_f32 v125, -v124, v7, v0
	v_cmp_ge_f32_e64 s[8:9], 0, v125
	v_add_u32_e32 v125, 1, v7
	s_nop 0
	v_cndmask_b32_e64 v124, v7, v124, s[8:9]
	v_fma_f32 v7, -v125, v7, v0
	v_cmp_lt_f32_e64 s[8:9], 0, v7
	s_nop 1
	v_cndmask_b32_e64 v7, v124, v125, s[8:9]
	v_mul_f32_e32 v124, 0x37800000, v7
	v_cndmask_b32_e32 v7, v7, v124, vcc
	v_cmp_class_f32_e32 vcc, v0, v253
	s_nop 1
	v_cndmask_b32_e32 v0, v7, v0, vcc
	v_div_scale_f32 v7, s[6:7], v0, v0, 1.0
	v_rcp_f32_e32 v124, v7
	s_lshl_b32 s6, s10, 1
	s_and_b32 s6, s6, 0xffffe000
	s_add_i32 s6, s6, 0
	v_fma_f32 v125, -v7, v124, 1.0
	v_fmac_f32_e32 v124, v125, v124
	v_div_scale_f32 v125, vcc, 1.0, v0, 1.0
	v_mul_f32_e32 v146, v125, v124
	v_fma_f32 v156, -v7, v146, v125
	v_fmac_f32_e32 v146, v156, v124
	v_fma_f32 v7, -v7, v146, v125
	v_div_fmas_f32 v7, v7, v124, v146
	v_div_fixup_f32 v146, v7, v0, 1.0
	v_lshlrev_b32_e32 v0, 4, v147
	v_add_u32_e32 v164, s6, v0
	v_pk_mul_f32 v[160:161], v[152:153], v[146:147] op_sel_hi:[1,0]
	v_pk_mul_f32 v[162:163], v[154:155], v[146:147] op_sel_hi:[1,0]
	ds_read_b128 v[152:155], v164
	ds_read_b128 v[156:159], v164 offset:40960
	v_lshl_add_u64 v[124:125], s[12:13], 1, v[2:3]
	v_mov_b32_e32 v7, v1
	v_lshl_add_u64 v[124:125], v[124:125], 0, v[6:7]
	v_pk_mul_f32 v[4:5], v[4:5], v[146:147] op_sel_hi:[1,0]
	s_waitcnt lgkmcnt(0)
	v_pk_fma_f32 v[154:155], v[154:155], v[162:163], v[158:159]
	v_pk_fma_f32 v[152:153], v[152:153], v[160:161], v[156:157]
	v_pk_mul_f32 v[156:157], v[148:149], v[146:147] op_sel_hi:[1,0]
	v_cvt_pk_bf16_f32 v152, v152, v153
	v_cvt_pk_bf16_f32 v153, v154, v155
	global_store_dwordx2 v[124:125], v[152:153], off
	v_pk_mul_f32 v[158:159], v[150:151], v[146:147] op_sel_hi:[1,0]
	ds_read_b128 v[148:151], v164 offset:1024
	ds_read_b128 v[152:155], v164 offset:41984
	s_waitcnt lgkmcnt(0)
	v_pk_fma_f32 v[150:151], v[150:151], v[158:159], v[154:155]
	v_pk_fma_f32 v[148:149], v[148:149], v[156:157], v[152:153]
	v_pk_mul_f32 v[152:153], v[138:139], v[146:147] op_sel_hi:[1,0]
	v_cvt_pk_bf16_f32 v148, v148, v149
	v_cvt_pk_bf16_f32 v149, v150, v151
	global_store_dwordx2 v[124:125], v[148:149], off offset:512
	v_pk_mul_f32 v[154:155], v[140:141], v[146:147] op_sel_hi:[1,0]
	ds_read_b128 v[138:141], v164 offset:2048
	ds_read_b128 v[148:151], v164 offset:43008
	s_waitcnt lgkmcnt(0)
	v_pk_fma_f32 v[140:141], v[140:141], v[154:155], v[150:151]
	v_pk_fma_f32 v[138:139], v[138:139], v[152:153], v[148:149]
	v_pk_mul_f32 v[148:149], v[142:143], v[146:147] op_sel_hi:[1,0]
	v_cvt_pk_bf16_f32 v138, v138, v139
	v_cvt_pk_bf16_f32 v139, v140, v141
	global_store_dwordx2 v[124:125], v[138:139], off offset:1024
	v_pk_mul_f32 v[150:151], v[144:145], v[146:147] op_sel_hi:[1,0]
	ds_read_b128 v[138:141], v164 offset:3072
	ds_read_b128 v[142:145], v164 offset:44032
	s_waitcnt lgkmcnt(0)
	v_pk_fma_f32 v[140:141], v[150:151], v[140:141], v[144:145]
	v_pk_fma_f32 v[138:139], v[148:149], v[138:139], v[142:143]
	v_pk_mul_f32 v[142:143], v[132:133], v[146:147] op_sel_hi:[1,0]
	v_cvt_pk_bf16_f32 v138, v138, v139
	v_cvt_pk_bf16_f32 v139, v140, v141
	global_store_dwordx2 v[124:125], v[138:139], off offset:1536
	v_pk_mul_f32 v[144:145], v[134:135], v[146:147] op_sel_hi:[1,0]
	ds_read_b128 v[132:135], v164 offset:4096
	ds_read_b128 v[138:141], v164 offset:45056
	s_waitcnt lgkmcnt(0)
	v_pk_fma_f32 v[134:135], v[144:145], v[134:135], v[140:141]
	v_pk_fma_f32 v[132:133], v[142:143], v[132:133], v[138:139]
	v_pk_mul_f32 v[138:139], v[130:131], v[146:147] op_sel_hi:[1,0]
	v_cvt_pk_bf16_f32 v132, v132, v133
	v_cvt_pk_bf16_f32 v133, v134, v135
	global_store_dwordx2 v[124:125], v[132:133], off offset:2048
	v_pk_mul_f32 v[140:141], v[136:137], v[146:147] op_sel_hi:[1,0]
	ds_read_b128 v[130:133], v164 offset:5120
	ds_read_b128 v[134:137], v164 offset:46080
	s_waitcnt lgkmcnt(0)
	v_pk_fma_f32 v[132:133], v[140:141], v[132:133], v[136:137]
	v_pk_fma_f32 v[130:131], v[138:139], v[130:131], v[134:135]
	v_pk_mul_f32 v[136:137], v[128:129], v[146:147] op_sel_hi:[1,0]
	v_cvt_pk_bf16_f32 v130, v130, v131
	v_cvt_pk_bf16_f32 v131, v132, v133
	global_store_dwordx2 v[124:125], v[130:131], off offset:2560
	ds_read_b128 v[128:131], v164 offset:6144
	ds_read_b128 v[132:135], v164 offset:47104
	s_waitcnt vmcnt(61)
	v_cvt_f32_f16_sdwa v139, v123 dst_sel:DWORD dst_unused:UNUSED_PAD src0_sel:WORD_1
	v_cvt_f32_f16_e32 v138, v123
	s_waitcnt vmcnt(59)
	v_cvt_f32_f16_sdwa v123, v118 dst_sel:DWORD dst_unused:UNUSED_PAD src0_sel:WORD_1
	s_waitcnt lgkmcnt(0)
; __device__ __forceinline__ void norm_mod_phase2(const Args& a, Frame& F, const float* gain, const float* modl, int sh_off, int sc_off, int nrows, const float* slab_gate) {
;     ...
;     NR_FINISH(r0, nw,            (nw) >> 12);
;     NR_FINISH(r1, nw + 2048,     (nw + 2048) >> 12);
;     NR_FINISH(r2, nw + 2 * 2048, (nw + 2 * 2048) >> 12);
;     NR_FINISH(r3, nw + 3 * 2048, (nw + 3 * 2048) >> 12);
	v_pk_fma_f32 v[130:131], v[136:137], v[130:131], v[134:135]
	v_pk_fma_f32 v[4:5], v[4:5], v[128:129], v[132:133]
	v_cvt_f32_f16_sdwa v137, v122 dst_sel:DWORD dst_unused:UNUSED_PAD src0_sel:WORD_1
	v_cvt_pk_bf16_f32 v4, v4, v5
	v_cvt_pk_bf16_f32 v5, v130, v131
	global_store_dwordx2 v[124:125], v[4:5], off offset:3072
	v_pk_mul_f32 v[4:5], v[74:75], v[146:147] op_sel_hi:[1,0]
	v_pk_mul_f32 v[74:75], v[126:127], v[146:147] op_sel_hi:[1,0]
	ds_read_b128 v[126:129], v164 offset:7168
	ds_read_b128 v[130:133], v164 offset:48128
	v_cvt_f32_f16_e32 v136, v122
	v_cvt_f32_f16_sdwa v135, v121 dst_sel:DWORD dst_unused:UNUSED_PAD src0_sel:WORD_1
	v_cvt_f32_f16_e32 v134, v121
	v_cvt_f32_f16_e32 v122, v118
	s_waitcnt lgkmcnt(0)
	v_pk_fma_f32 v[74:75], v[74:75], v[128:129], v[132:133]
	v_cvt_f32_f16_sdwa v133, v120 dst_sel:DWORD dst_unused:UNUSED_PAD src0_sel:WORD_1
	v_pk_fma_f32 v[4:5], v[4:5], v[126:127], v[130:131]
	v_cvt_f32_f16_e32 v132, v120
	v_cvt_pk_bf16_f32 v4, v4, v5
	v_cvt_pk_bf16_f32 v5, v74, v75
	global_store_dwordx2 v[124:125], v[4:5], off offset:3584
	v_cvt_f32_f16_sdwa v125, v119 dst_sel:DWORD dst_unused:UNUSED_PAD src0_sel:WORD_1
	s_waitcnt vmcnt(60)
	v_cvt_f32_f16_sdwa v127, v116 dst_sel:DWORD dst_unused:UNUSED_PAD src0_sel:WORD_1
	v_mov_b32_e32 v74, v137
	v_mov_b32_e32 v75, v133
	v_cvt_f32_f16_e32 v124, v119
	v_cvt_f32_f16_e32 v126, v116
	v_cvt_f32_f16_sdwa v129, v117 dst_sel:DWORD dst_unused:UNUSED_PAD src0_sel:WORD_1
	v_mov_b32_e32 v4, v136
	v_mov_b32_e32 v5, v132
	v_pk_mul_f32 v[74:75], v[74:75], v[74:75]
	v_mov_b32_e32 v120, v139
	v_mov_b32_e32 v121, v135
	v_cvt_f32_f16_e32 v128, v117
	v_pk_fma_f32 v[4:5], v[4:5], v[4:5], v[74:75]
	v_mov_b32_e32 v74, v138
	v_mov_b32_e32 v75, v134
	v_pk_mul_f32 v[120:121], v[120:121], v[120:121]
	v_mov_b32_e32 v118, v123
	v_pk_fma_f32 v[74:75], v[74:75], v[74:75], v[120:121]
	v_mov_b32_e32 v119, v125
	v_mul_f32_e32 v116, v127, v127
	v_pk_add_f32 v[4:5], v[4:5], v[74:75]
	v_mov_b32_e32 v74, v122
	v_mov_b32_e32 v75, v124
	v_pk_mul_f32 v[118:119], v[118:119], v[118:119]
	v_pk_fma_f32 v[120:121], v[126:127], v[126:127], v[116:117] op_sel_hi:[1,1,0]
	v_mul_f32_e32 v116, v129, v129
	v_pk_fma_f32 v[74:75], v[74:75], v[74:75], v[118:119]
	v_pk_fma_f32 v[130:131], v[128:129], v[128:129], v[116:117] op_sel_hi:[1,1,0]
	s_waitcnt vmcnt(59)
	v_cvt_f32_f16_sdwa v117, v114 dst_sel:DWORD dst_unused:UNUSED_PAD src0_sel:WORD_1
	v_cvt_f32_f16_e32 v116, v114
	v_cvt_f32_f16_sdwa v119, v115 dst_sel:DWORD dst_unused:UNUSED_PAD src0_sel:WORD_1
	v_cvt_f32_f16_e32 v118, v115
	v_pk_add_f32 v[4:5], v[4:5], v[4:5] op_sel:[0,1] op_sel_hi:[1,0]
	v_pk_add_f32 v[74:75], v[74:75], v[74:75] op_sel:[0,1] op_sel_hi:[1,0]
	v_pk_mul_f32 v[114:115], v[116:117], v[116:117]
	v_pk_mul_f32 v[140:141], v[118:119], v[118:119]
	v_mov_b32_e32 v5, v114
	v_mov_b32_e32 v75, v115
	v_mov_b32_e32 v121, v140
	v_mov_b32_e32 v131, v141
	v_pk_add_f32 v[4:5], v[4:5], v[74:75]
	v_pk_add_f32 v[74:75], v[120:121], v[130:131]
	s_waitcnt vmcnt(58)
	v_cvt_f32_f16_sdwa v115, v112 dst_sel:DWORD dst_unused:UNUSED_PAD src0_sel:WORD_1
	v_cvt_f32_f16_sdwa v121, v113 dst_sel:DWORD dst_unused:UNUSED_PAD src0_sel:WORD_1
	v_cvt_f32_f16_e32 v114, v112
	v_cvt_f32_f16_e32 v120, v113
	v_pk_add_f32 v[4:5], v[4:5], v[74:75]
	v_mov_b32_e32 v74, v115
	v_mov_b32_e32 v75, v121
	v_pk_add_f32 v[130:131], v[4:5], v[4:5] op_sel:[0,1] op_sel_hi:[1,0]
	v_mov_b32_e32 v4, v114
	v_mov_b32_e32 v5, v120
	v_pk_mul_f32 v[74:75], v[74:75], v[74:75]
	s_waitcnt vmcnt(57)
	v_cvt_f32_f16_sdwa v113, v111 dst_sel:DWORD dst_unused:UNUSED_PAD src0_sel:WORD_1
	v_pk_fma_f32 v[4:5], v[4:5], v[4:5], v[74:75]
	v_cvt_f32_f16_e32 v112, v111
	v_pk_add_f32 v[140:141], v[4:5], v[4:5] op_sel:[0,1] op_sel_hi:[1,0]
	v_cvt_f32_f16_sdwa v5, v110 dst_sel:DWORD dst_unused:UNUSED_PAD src0_sel:WORD_1
	v_cvt_f32_f16_e32 v4, v110
	s_waitcnt vmcnt(56)
	v_cvt_f32_f16_sdwa v111, v109 dst_sel:DWORD dst_unused:UNUSED_PAD src0_sel:WORD_1
	v_cvt_f32_f16_e32 v110, v109
	v_mul_f32_e32 v74, v5, v5
	v_pk_fma_f32 v[142:143], v[4:5], v[4:5], v[74:75] op_sel_hi:[1,1,0]
	v_mul_f32_e32 v74, v113, v113
	v_pk_fma_f32 v[144:145], v[112:113], v[112:113], v[74:75] op_sel_hi:[1,1,0]
	v_cvt_f32_f16_sdwa v75, v108 dst_sel:DWORD dst_unused:UNUSED_PAD src0_sel:WORD_1
	v_cvt_f32_f16_e32 v74, v108
	v_pk_mul_f32 v[148:149], v[110:111], v[110:111]
	v_pk_mul_f32 v[108:109], v[74:75], v[74:75]
	s_nop 0
	v_mov_b32_e32 v131, v108
	v_mov_b32_e32 v141, v109
	v_mov_b32_e32 v143, v148
	v_mov_b32_e32 v145, v149
	v_pk_add_f32 v[108:109], v[130:131], v[140:141]
	v_pk_add_f32 v[130:131], v[142:143], v[144:145]
	s_nop 0
	v_pk_add_f32 v[108:109], v[108:109], v[130:131]
	s_nop 0
	v_add_f32_e32 v108, v108, v109
	s_nop 1
	v_add_f32_dpp v108, v108, v108 quad_perm:[1,0,3,2] row_mask:0xf bank_mask:0xf bound_ctrl:1
	s_nop 1
	v_add_f32_dpp v108, v108, v108 quad_perm:[2,3,0,1] row_mask:0xf bank_mask:0xf bound_ctrl:1
	s_nop 1
	v_add_f32_dpp v108, v108, v108 row_half_mirror row_mask:0xf bank_mask:0xf bound_ctrl:1
	s_nop 1
	v_add_f32_dpp v108, v108, v108 row_mirror row_mask:0xf bank_mask:0xf bound_ctrl:1
	s_nop 0
	v_readlane_b32 s8, v108, 16
	v_readlane_b32 s9, v108, 48
	v_readlane_b32 s6, v108, 0
	v_readlane_b32 s7, v108, 32
	v_mov_b32_e32 v108, s8
	v_mov_b32_e32 v109, s9
	v_pk_add_f32 v[108:109], s[6:7], v[108:109]
	s_nop 0
	v_add_f32_e32 v108, v108, v109
	v_fmamk_f32 v108, v108, 0x3a000000, v252
	v_cmp_gt_f32_e32 vcc, s55, v108
	v_mul_f32_e32 v109, 0x4f800000, v108
	s_nop 0
	v_cndmask_b32_e32 v108, v108, v109, vcc
	v_sqrt_f32_e32 v109, v108
	s_nop 0
	v_add_u32_e32 v130, -1, v109
	v_fma_f32 v131, -v130, v109, v108
	v_cmp_ge_f32_e64 s[8:9], 0, v131
	v_add_u32_e32 v131, 1, v109
	s_nop 0
	v_cndmask_b32_e64 v130, v109, v130, s[8:9]
	v_fma_f32 v109, -v131, v109, v108
	v_cmp_lt_f32_e64 s[8:9], 0, v109
	s_nop 1
	v_cndmask_b32_e64 v109, v130, v131, s[8:9]
	v_mul_f32_e32 v130, 0x37800000, v109
	v_cndmask_b32_e32 v109, v109, v130, vcc
	v_cmp_class_f32_e32 vcc, v108, v253
	s_nop 1
	v_cndmask_b32_e32 v108, v109, v108, vcc
	v_div_scale_f32 v109, s[6:7], v108, v108, 1.0
	v_rcp_f32_e32 v130, v109
	s_lshl_b32 s6, s78, 1
	s_and_b32 s6, s6, 0xffffe000
	s_add_i32 s6, s6, 0
	v_fma_f32 v131, -v109, v130, 1.0
	v_fmac_f32_e32 v130, v131, v130
	v_div_scale_f32 v131, vcc, 1.0, v108, 1.0
	v_mul_f32_e32 v140, v131, v130
	v_fma_f32 v141, -v109, v140, v131
	v_fmac_f32_e32 v140, v141, v130
	v_fma_f32 v109, -v109, v140, v131
	v_div_fmas_f32 v109, v109, v130, v140
	v_div_fixup_f32 v130, v109, v108, 1.0
	v_pk_mul_f32 v[144:145], v[136:137], v[130:131] op_sel_hi:[1,0]
	v_pk_mul_f32 v[148:149], v[138:139], v[130:131] op_sel_hi:[1,0]
	v_add_u32_e32 v131, s6, v0
	ds_read_b128 v[136:139], v131
	ds_read_b128 v[140:143], v131 offset:40960
	v_lshl_add_u64 v[108:109], s[48:49], 1, v[2:3]
	v_lshl_add_u64 v[108:109], v[108:109], 0, v[6:7]
	v_pk_mul_f32 v[4:5], v[4:5], v[130:131] op_sel_hi:[1,0]
	s_waitcnt lgkmcnt(0)
; __device__ __forceinline__ void norm_mod_phase2(const Args& a, Frame& F, const float* gain, const float* modl, int sh_off, int sc_off, int nrows, const float* slab_gate) {
;     ...
;     NR_FINISH(r0, nw,            (nw) >> 12);
;     NR_FINISH(r1, nw + 2048,     (nw + 2048) >> 12);
;     NR_FINISH(r2, nw + 2 * 2048, (nw + 2 * 2048) >> 12);
;     NR_FINISH(r3, nw + 3 * 2048, (nw + 3 * 2048) >> 12);
;     NR_FINISH(r4, nw + 4 * 2048, (nw + 4 * 2048) >> 12);
	v_pk_fma_f32 v[138:139], v[138:139], v[148:149], v[142:143]
	v_pk_fma_f32 v[136:137], v[136:137], v[144:145], v[140:141]
	v_pk_mul_f32 v[140:141], v[132:133], v[130:131] op_sel_hi:[1,0]
	v_cvt_pk_bf16_f32 v136, v136, v137
	v_cvt_pk_bf16_f32 v137, v138, v139
	global_store_dwordx2 v[108:109], v[136:137], off
	v_pk_mul_f32 v[142:143], v[134:135], v[130:131] op_sel_hi:[1,0]
	ds_read_b128 v[132:135], v131 offset:1024
	ds_read_b128 v[136:139], v131 offset:41984
	s_waitcnt lgkmcnt(0)
	v_pk_fma_f32 v[134:135], v[134:135], v[142:143], v[138:139]
	v_pk_fma_f32 v[132:133], v[132:133], v[140:141], v[136:137]
	v_pk_mul_f32 v[136:137], v[122:123], v[130:131] op_sel_hi:[1,0]
	v_cvt_pk_bf16_f32 v132, v132, v133
	v_cvt_pk_bf16_f32 v133, v134, v135
	global_store_dwordx2 v[108:109], v[132:133], off offset:512
	v_pk_mul_f32 v[138:139], v[124:125], v[130:131] op_sel_hi:[1,0]
	ds_read_b128 v[122:125], v131 offset:2048
	ds_read_b128 v[132:135], v131 offset:43008
	s_waitcnt lgkmcnt(0)
	v_pk_fma_f32 v[124:125], v[124:125], v[138:139], v[134:135]
	v_pk_fma_f32 v[122:123], v[122:123], v[136:137], v[132:133]
	v_pk_mul_f32 v[132:133], v[126:127], v[130:131] op_sel_hi:[1,0]
	v_cvt_pk_bf16_f32 v122, v122, v123
	v_cvt_pk_bf16_f32 v123, v124, v125
	global_store_dwordx2 v[108:109], v[122:123], off offset:1024
	v_pk_mul_f32 v[134:135], v[128:129], v[130:131] op_sel_hi:[1,0]
	ds_read_b128 v[122:125], v131 offset:3072
	ds_read_b128 v[126:129], v131 offset:44032
	s_waitcnt lgkmcnt(0)
	v_pk_fma_f32 v[124:125], v[134:135], v[124:125], v[128:129]
	v_pk_fma_f32 v[122:123], v[132:133], v[122:123], v[126:127]
	v_pk_mul_f32 v[126:127], v[116:117], v[130:131] op_sel_hi:[1,0]
	v_cvt_pk_bf16_f32 v122, v122, v123
	v_cvt_pk_bf16_f32 v123, v124, v125
	global_store_dwordx2 v[108:109], v[122:123], off offset:1536
	v_pk_mul_f32 v[128:129], v[118:119], v[130:131] op_sel_hi:[1,0]
	ds_read_b128 v[116:119], v131 offset:4096
	ds_read_b128 v[122:125], v131 offset:45056
	s_waitcnt lgkmcnt(0)
	v_pk_fma_f32 v[118:119], v[128:129], v[118:119], v[124:125]
	v_pk_fma_f32 v[116:117], v[126:127], v[116:117], v[122:123]
	v_pk_mul_f32 v[122:123], v[114:115], v[130:131] op_sel_hi:[1,0]
	v_cvt_pk_bf16_f32 v116, v116, v117
	v_cvt_pk_bf16_f32 v117, v118, v119
	global_store_dwordx2 v[108:109], v[116:117], off offset:2048
	v_pk_mul_f32 v[124:125], v[120:121], v[130:131] op_sel_hi:[1,0]
	ds_read_b128 v[114:117], v131 offset:5120
	ds_read_b128 v[118:121], v131 offset:46080
	s_waitcnt lgkmcnt(0)
	v_pk_fma_f32 v[116:117], v[124:125], v[116:117], v[120:121]
	v_pk_fma_f32 v[114:115], v[122:123], v[114:115], v[118:119]
	v_pk_mul_f32 v[120:121], v[112:113], v[130:131] op_sel_hi:[1,0]
	v_cvt_pk_bf16_f32 v114, v114, v115
	v_cvt_pk_bf16_f32 v115, v116, v117
	global_store_dwordx2 v[108:109], v[114:115], off offset:2560
	ds_read_b128 v[112:115], v131 offset:6144
	ds_read_b128 v[116:119], v131 offset:47104
	s_waitcnt vmcnt(61)
	v_cvt_f32_f16_sdwa v123, v107 dst_sel:DWORD dst_unused:UNUSED_PAD src0_sel:WORD_1
	v_cvt_f32_f16_e32 v122, v107
	s_waitcnt vmcnt(59)
	v_cvt_f32_f16_sdwa v107, v102 dst_sel:DWORD dst_unused:UNUSED_PAD src0_sel:WORD_1
	s_waitcnt lgkmcnt(0)
	v_pk_fma_f32 v[114:115], v[120:121], v[114:115], v[118:119]
	v_pk_fma_f32 v[4:5], v[4:5], v[112:113], v[116:117]
	v_cvt_f32_f16_sdwa v121, v106 dst_sel:DWORD dst_unused:UNUSED_PAD src0_sel:WORD_1
	v_cvt_pk_bf16_f32 v4, v4, v5
	v_cvt_pk_bf16_f32 v5, v114, v115
	global_store_dwordx2 v[108:109], v[4:5], off offset:3072
	v_pk_mul_f32 v[4:5], v[74:75], v[130:131] op_sel_hi:[1,0]
	v_pk_mul_f32 v[74:75], v[110:111], v[130:131] op_sel_hi:[1,0]
	ds_read_b128 v[110:113], v131 offset:7168
	ds_read_b128 v[114:117], v131 offset:48128
	v_cvt_f32_f16_e32 v120, v106
	v_cvt_f32_f16_sdwa v119, v105 dst_sel:DWORD dst_unused:UNUSED_PAD src0_sel:WORD_1
	v_cvt_f32_f16_e32 v118, v105
	v_cvt_f32_f16_e32 v106, v102
	s_waitcnt lgkmcnt(0)
	v_pk_fma_f32 v[74:75], v[74:75], v[112:113], v[116:117]
	v_cvt_f32_f16_sdwa v117, v104 dst_sel:DWORD dst_unused:UNUSED_PAD src0_sel:WORD_1
	v_pk_fma_f32 v[4:5], v[4:5], v[110:111], v[114:115]
	v_cvt_f32_f16_e32 v116, v104
	v_cvt_pk_bf16_f32 v4, v4, v5
	v_cvt_pk_bf16_f32 v5, v74, v75
	global_store_dwordx2 v[108:109], v[4:5], off offset:3584
	v_cvt_f32_f16_sdwa v109, v103 dst_sel:DWORD dst_unused:UNUSED_PAD src0_sel:WORD_1
	s_waitcnt vmcnt(60)
	v_cvt_f32_f16_sdwa v111, v100 dst_sel:DWORD dst_unused:UNUSED_PAD src0_sel:WORD_1
	v_mov_b32_e32 v74, v121
	v_mov_b32_e32 v75, v117
	v_cvt_f32_f16_e32 v108, v103
	v_cvt_f32_f16_e32 v110, v100
	v_cvt_f32_f16_sdwa v113, v101 dst_sel:DWORD dst_unused:UNUSED_PAD src0_sel:WORD_1
	v_mov_b32_e32 v4, v120
	v_mov_b32_e32 v5, v116
	v_pk_mul_f32 v[74:75], v[74:75], v[74:75]
	v_mov_b32_e32 v104, v123
	v_mov_b32_e32 v105, v119
	v_cvt_f32_f16_e32 v112, v101
	v_pk_fma_f32 v[4:5], v[4:5], v[4:5], v[74:75]
	v_mov_b32_e32 v74, v122
	v_mov_b32_e32 v75, v118
	v_pk_mul_f32 v[104:105], v[104:105], v[104:105]
	v_mov_b32_e32 v102, v107
	v_pk_fma_f32 v[74:75], v[74:75], v[74:75], v[104:105]
	v_mov_b32_e32 v103, v109
	v_mul_f32_e32 v100, v111, v111
	v_pk_add_f32 v[4:5], v[4:5], v[74:75]
	v_mov_b32_e32 v74, v106
	v_mov_b32_e32 v75, v108
	v_pk_mul_f32 v[102:103], v[102:103], v[102:103]
	v_pk_fma_f32 v[104:105], v[110:111], v[110:111], v[100:101] op_sel_hi:[1,1,0]
	v_mul_f32_e32 v100, v113, v113
	v_pk_fma_f32 v[74:75], v[74:75], v[74:75], v[102:103]
	v_pk_fma_f32 v[114:115], v[112:113], v[112:113], v[100:101] op_sel_hi:[1,1,0]
	s_waitcnt vmcnt(59)
; __device__ __forceinline__ void norm_mod_phase2(const Args& a, Frame& F, const float* gain, const float* modl, int sh_off, int sc_off, int nrows, const float* slab_gate) {
;     ...
;     NR_FINISH(r2, nw + 2 * 2048, (nw + 2 * 2048) >> 12);
;     NR_FINISH(r3, nw + 3 * 2048, (nw + 3 * 2048) >> 12);
;     NR_FINISH(r4, nw + 4 * 2048, (nw + 4 * 2048) >> 12);
	v_cvt_f32_f16_sdwa v101, v98 dst_sel:DWORD dst_unused:UNUSED_PAD src0_sel:WORD_1
	v_cvt_f32_f16_e32 v100, v98
	v_cvt_f32_f16_sdwa v103, v99 dst_sel:DWORD dst_unused:UNUSED_PAD src0_sel:WORD_1
	v_cvt_f32_f16_e32 v102, v99
	v_pk_add_f32 v[4:5], v[4:5], v[4:5] op_sel:[0,1] op_sel_hi:[1,0]
	v_pk_add_f32 v[74:75], v[74:75], v[74:75] op_sel:[0,1] op_sel_hi:[1,0]
	v_pk_mul_f32 v[98:99], v[100:101], v[100:101]
	v_pk_mul_f32 v[124:125], v[102:103], v[102:103]
	v_mov_b32_e32 v5, v98
	v_mov_b32_e32 v75, v99
	v_mov_b32_e32 v105, v124
	v_mov_b32_e32 v115, v125
	v_pk_add_f32 v[4:5], v[4:5], v[74:75]
	v_pk_add_f32 v[74:75], v[104:105], v[114:115]
	s_waitcnt vmcnt(58)
	v_cvt_f32_f16_sdwa v99, v96 dst_sel:DWORD dst_unused:UNUSED_PAD src0_sel:WORD_1
	v_cvt_f32_f16_sdwa v105, v97 dst_sel:DWORD dst_unused:UNUSED_PAD src0_sel:WORD_1
	v_cvt_f32_f16_e32 v98, v96
	v_cvt_f32_f16_e32 v104, v97
	v_pk_add_f32 v[4:5], v[4:5], v[74:75]
	v_mov_b32_e32 v74, v99
	v_mov_b32_e32 v75, v105
	v_pk_add_f32 v[114:115], v[4:5], v[4:5] op_sel:[0,1] op_sel_hi:[1,0]
	v_mov_b32_e32 v4, v98
	v_mov_b32_e32 v5, v104
	v_pk_mul_f32 v[74:75], v[74:75], v[74:75]
	s_waitcnt vmcnt(57)
	v_cvt_f32_f16_sdwa v97, v95 dst_sel:DWORD dst_unused:UNUSED_PAD src0_sel:WORD_1
	v_pk_fma_f32 v[4:5], v[4:5], v[4:5], v[74:75]
	v_cvt_f32_f16_e32 v96, v95
	v_pk_add_f32 v[124:125], v[4:5], v[4:5] op_sel:[0,1] op_sel_hi:[1,0]
	v_cvt_f32_f16_sdwa v5, v94 dst_sel:DWORD dst_unused:UNUSED_PAD src0_sel:WORD_1
	v_cvt_f32_f16_e32 v4, v94
	s_waitcnt vmcnt(56)
	v_cvt_f32_f16_sdwa v95, v93 dst_sel:DWORD dst_unused:UNUSED_PAD src0_sel:WORD_1
	v_cvt_f32_f16_e32 v94, v93
	v_mul_f32_e32 v74, v5, v5
	v_pk_fma_f32 v[126:127], v[4:5], v[4:5], v[74:75] op_sel_hi:[1,1,0]
	v_mul_f32_e32 v74, v97, v97
	v_pk_fma_f32 v[128:129], v[96:97], v[96:97], v[74:75] op_sel_hi:[1,1,0]
	v_cvt_f32_f16_sdwa v75, v92 dst_sel:DWORD dst_unused:UNUSED_PAD src0_sel:WORD_1
	v_cvt_f32_f16_e32 v74, v92
	v_pk_mul_f32 v[130:131], v[94:95], v[94:95]
	v_pk_mul_f32 v[92:93], v[74:75], v[74:75]
	s_nop 0
	v_mov_b32_e32 v115, v92
	v_mov_b32_e32 v125, v93
	v_mov_b32_e32 v127, v130
	v_mov_b32_e32 v129, v131
	v_pk_add_f32 v[92:93], v[114:115], v[124:125]
	v_pk_add_f32 v[114:115], v[126:127], v[128:129]
	s_nop 0
	v_pk_add_f32 v[92:93], v[92:93], v[114:115]
	s_nop 0
	v_add_f32_e32 v92, v92, v93
	s_nop 1
	v_add_f32_dpp v92, v92, v92 quad_perm:[1,0,3,2] row_mask:0xf bank_mask:0xf bound_ctrl:1
	s_nop 1
	v_add_f32_dpp v92, v92, v92 quad_perm:[2,3,0,1] row_mask:0xf bank_mask:0xf bound_ctrl:1
	s_nop 1
	v_add_f32_dpp v92, v92, v92 row_half_mirror row_mask:0xf bank_mask:0xf bound_ctrl:1
	s_nop 1
	v_add_f32_dpp v92, v92, v92 row_mirror row_mask:0xf bank_mask:0xf bound_ctrl:1
	s_nop 0
	v_readlane_b32 s8, v92, 16
	v_readlane_b32 s9, v92, 48
	v_readlane_b32 s6, v92, 0
	v_readlane_b32 s7, v92, 32
	v_mov_b32_e32 v92, s8
	v_mov_b32_e32 v93, s9
	v_pk_add_f32 v[92:93], s[6:7], v[92:93]
	s_nop 0
	v_add_f32_e32 v92, v92, v93
	v_fmamk_f32 v92, v92, 0x3a000000, v252
	v_cmp_gt_f32_e32 vcc, s55, v92
	v_mul_f32_e32 v93, 0x4f800000, v92
	s_nop 0
	v_cndmask_b32_e32 v92, v92, v93, vcc
	v_sqrt_f32_e32 v93, v92
	s_nop 0
	v_add_u32_e32 v114, -1, v93
	v_fma_f32 v115, -v114, v93, v92
	v_cmp_ge_f32_e64 s[8:9], 0, v115
	v_add_u32_e32 v115, 1, v93
	s_nop 0
	v_cndmask_b32_e64 v114, v93, v114, s[8:9]
	v_fma_f32 v93, -v115, v93, v92
	v_cmp_lt_f32_e64 s[8:9], 0, v93
	s_nop 1
	v_cndmask_b32_e64 v93, v114, v115, s[8:9]
	v_mul_f32_e32 v114, 0x37800000, v93
	v_cndmask_b32_e32 v93, v93, v114, vcc
	v_cmp_class_f32_e32 vcc, v92, v253
	s_nop 1
	v_cndmask_b32_e32 v92, v93, v92, vcc
	v_div_scale_f32 v93, s[6:7], v92, v92, 1.0
	v_rcp_f32_e32 v114, v93
	s_lshl_b32 s6, s36, 1
	s_and_b32 s6, s6, 0xffffe000
	s_add_i32 s6, s6, 0
	v_fma_f32 v115, -v93, v114, 1.0
	v_fmac_f32_e32 v114, v115, v114
	v_div_scale_f32 v115, vcc, 1.0, v92, 1.0
	v_mul_f32_e32 v124, v115, v114
	v_fma_f32 v125, -v93, v124, v115
	v_fmac_f32_e32 v124, v125, v114
	v_fma_f32 v93, -v93, v124, v115
	v_div_fmas_f32 v93, v93, v114, v124
	v_div_fixup_f32 v114, v93, v92, 1.0
	v_pk_mul_f32 v[128:129], v[120:121], v[114:115] op_sel_hi:[1,0]
	v_pk_mul_f32 v[130:131], v[122:123], v[114:115] op_sel_hi:[1,0]
	v_add_u32_e32 v115, s6, v0
	ds_read_b128 v[120:123], v115
	ds_read_b128 v[124:127], v115 offset:40960
	v_lshl_add_u64 v[92:93], s[40:41], 1, v[2:3]
	v_lshl_add_u64 v[92:93], v[92:93], 0, v[6:7]
	v_pk_mul_f32 v[4:5], v[4:5], v[114:115] op_sel_hi:[1,0]
	s_waitcnt lgkmcnt(0)
	v_pk_fma_f32 v[122:123], v[122:123], v[130:131], v[126:127]
	v_pk_fma_f32 v[120:121], v[120:121], v[128:129], v[124:125]
	v_pk_mul_f32 v[124:125], v[116:117], v[114:115] op_sel_hi:[1,0]
	v_cvt_pk_bf16_f32 v120, v120, v121
	v_cvt_pk_bf16_f32 v121, v122, v123
	global_store_dwordx2 v[92:93], v[120:121], off
	v_pk_mul_f32 v[126:127], v[118:119], v[114:115] op_sel_hi:[1,0]
	ds_read_b128 v[116:119], v115 offset:1024
	ds_read_b128 v[120:123], v115 offset:41984
	s_waitcnt lgkmcnt(0)
	v_pk_fma_f32 v[118:119], v[118:119], v[126:127], v[122:123]
	v_pk_fma_f32 v[116:117], v[116:117], v[124:125], v[120:121]
	v_pk_mul_f32 v[120:121], v[106:107], v[114:115] op_sel_hi:[1,0]
	v_cvt_pk_bf16_f32 v116, v116, v117
	v_cvt_pk_bf16_f32 v117, v118, v119
	global_store_dwordx2 v[92:93], v[116:117], off offset:512
	v_pk_mul_f32 v[122:123], v[108:109], v[114:115] op_sel_hi:[1,0]
	ds_read_b128 v[106:109], v115 offset:2048
	ds_read_b128 v[116:119], v115 offset:43008
	s_waitcnt lgkmcnt(0)
; __device__ __forceinline__ void norm_mod_phase2(const Args& a, Frame& F, const float* gain, const float* modl, int sh_off, int sc_off, int nrows, const float* slab_gate) {
;     ...
;     NR_FINISH(r2, nw + 2 * 2048, (nw + 2 * 2048) >> 12);
;     NR_FINISH(r3, nw + 3 * 2048, (nw + 3 * 2048) >> 12);
;     NR_FINISH(r4, nw + 4 * 2048, (nw + 4 * 2048) >> 12);
;     NR_FINISH(r5, nw + 5 * 2048, (nw + 5 * 2048) >> 12);
	v_pk_fma_f32 v[108:109], v[108:109], v[122:123], v[118:119]
	v_pk_fma_f32 v[106:107], v[106:107], v[120:121], v[116:117]
	v_pk_mul_f32 v[116:117], v[110:111], v[114:115] op_sel_hi:[1,0]
	v_cvt_pk_bf16_f32 v106, v106, v107
	v_cvt_pk_bf16_f32 v107, v108, v109
	global_store_dwordx2 v[92:93], v[106:107], off offset:1024
	v_pk_mul_f32 v[118:119], v[112:113], v[114:115] op_sel_hi:[1,0]
	ds_read_b128 v[106:109], v115 offset:3072
	ds_read_b128 v[110:113], v115 offset:44032
	s_waitcnt lgkmcnt(0)
	v_pk_fma_f32 v[108:109], v[118:119], v[108:109], v[112:113]
	v_pk_fma_f32 v[106:107], v[116:117], v[106:107], v[110:111]
	v_pk_mul_f32 v[110:111], v[100:101], v[114:115] op_sel_hi:[1,0]
	v_cvt_pk_bf16_f32 v106, v106, v107
	v_cvt_pk_bf16_f32 v107, v108, v109
	global_store_dwordx2 v[92:93], v[106:107], off offset:1536
	v_pk_mul_f32 v[112:113], v[102:103], v[114:115] op_sel_hi:[1,0]
	ds_read_b128 v[100:103], v115 offset:4096
	ds_read_b128 v[106:109], v115 offset:45056
	s_waitcnt lgkmcnt(0)
	v_pk_fma_f32 v[102:103], v[112:113], v[102:103], v[108:109]
	v_pk_fma_f32 v[100:101], v[110:111], v[100:101], v[106:107]
	v_pk_mul_f32 v[106:107], v[98:99], v[114:115] op_sel_hi:[1,0]
	v_cvt_pk_bf16_f32 v100, v100, v101
	v_cvt_pk_bf16_f32 v101, v102, v103
	global_store_dwordx2 v[92:93], v[100:101], off offset:2048
	v_pk_mul_f32 v[108:109], v[104:105], v[114:115] op_sel_hi:[1,0]
	ds_read_b128 v[98:101], v115 offset:5120
	ds_read_b128 v[102:105], v115 offset:46080
	s_waitcnt lgkmcnt(0)
	v_pk_fma_f32 v[100:101], v[108:109], v[100:101], v[104:105]
	v_pk_fma_f32 v[98:99], v[106:107], v[98:99], v[102:103]
	v_pk_mul_f32 v[104:105], v[96:97], v[114:115] op_sel_hi:[1,0]
	v_cvt_pk_bf16_f32 v98, v98, v99
	v_cvt_pk_bf16_f32 v99, v100, v101
	global_store_dwordx2 v[92:93], v[98:99], off offset:2560
	ds_read_b128 v[96:99], v115 offset:6144
	ds_read_b128 v[100:103], v115 offset:47104
	s_waitcnt vmcnt(61)
	v_cvt_f32_f16_sdwa v107, v91 dst_sel:DWORD dst_unused:UNUSED_PAD src0_sel:WORD_1
	v_cvt_f32_f16_e32 v106, v91
	s_waitcnt vmcnt(59)
	v_cvt_f32_f16_sdwa v91, v86 dst_sel:DWORD dst_unused:UNUSED_PAD src0_sel:WORD_1
	s_waitcnt lgkmcnt(0)
	v_pk_fma_f32 v[98:99], v[104:105], v[98:99], v[102:103]
	v_pk_fma_f32 v[4:5], v[4:5], v[96:97], v[100:101]
	v_cvt_f32_f16_sdwa v105, v90 dst_sel:DWORD dst_unused:UNUSED_PAD src0_sel:WORD_1
	v_cvt_pk_bf16_f32 v4, v4, v5
	v_cvt_pk_bf16_f32 v5, v98, v99
	global_store_dwordx2 v[92:93], v[4:5], off offset:3072
	v_pk_mul_f32 v[4:5], v[74:75], v[114:115] op_sel_hi:[1,0]
	v_pk_mul_f32 v[74:75], v[94:95], v[114:115] op_sel_hi:[1,0]
	ds_read_b128 v[94:97], v115 offset:7168
	ds_read_b128 v[98:101], v115 offset:48128
	v_cvt_f32_f16_e32 v104, v90
	v_cvt_f32_f16_sdwa v103, v89 dst_sel:DWORD dst_unused:UNUSED_PAD src0_sel:WORD_1
	v_cvt_f32_f16_e32 v102, v89
	v_cvt_f32_f16_e32 v90, v86
	s_waitcnt lgkmcnt(0)
	v_pk_fma_f32 v[74:75], v[74:75], v[96:97], v[100:101]
	v_cvt_f32_f16_sdwa v101, v88 dst_sel:DWORD dst_unused:UNUSED_PAD src0_sel:WORD_1
	v_pk_fma_f32 v[4:5], v[4:5], v[94:95], v[98:99]
	v_cvt_f32_f16_e32 v100, v88
	v_cvt_pk_bf16_f32 v4, v4, v5
	v_cvt_pk_bf16_f32 v5, v74, v75
	global_store_dwordx2 v[92:93], v[4:5], off offset:3584
	v_cvt_f32_f16_sdwa v93, v87 dst_sel:DWORD dst_unused:UNUSED_PAD src0_sel:WORD_1
	s_waitcnt vmcnt(60)
	v_cvt_f32_f16_sdwa v95, v84 dst_sel:DWORD dst_unused:UNUSED_PAD src0_sel:WORD_1
	v_mov_b32_e32 v74, v105
	v_mov_b32_e32 v75, v101
	v_cvt_f32_f16_e32 v92, v87
	v_cvt_f32_f16_e32 v94, v84
	v_cvt_f32_f16_sdwa v97, v85 dst_sel:DWORD dst_unused:UNUSED_PAD src0_sel:WORD_1
	v_mov_b32_e32 v4, v104
	v_mov_b32_e32 v5, v100
	v_pk_mul_f32 v[74:75], v[74:75], v[74:75]
	v_mov_b32_e32 v88, v107
	v_mov_b32_e32 v89, v103
	v_cvt_f32_f16_e32 v96, v85
	v_pk_fma_f32 v[4:5], v[4:5], v[4:5], v[74:75]
	v_mov_b32_e32 v74, v106
	v_mov_b32_e32 v75, v102
	v_pk_mul_f32 v[88:89], v[88:89], v[88:89]
	v_mov_b32_e32 v86, v91
	v_pk_fma_f32 v[74:75], v[74:75], v[74:75], v[88:89]
	v_mov_b32_e32 v87, v93
	v_mul_f32_e32 v84, v95, v95
	v_pk_add_f32 v[4:5], v[4:5], v[74:75]
	v_mov_b32_e32 v74, v90
	v_mov_b32_e32 v75, v92
	v_pk_mul_f32 v[86:87], v[86:87], v[86:87]
	v_pk_fma_f32 v[88:89], v[94:95], v[94:95], v[84:85] op_sel_hi:[1,1,0]
	v_mul_f32_e32 v84, v97, v97
	v_pk_fma_f32 v[74:75], v[74:75], v[74:75], v[86:87]
	v_pk_fma_f32 v[98:99], v[96:97], v[96:97], v[84:85] op_sel_hi:[1,1,0]
	s_waitcnt vmcnt(59)
	v_cvt_f32_f16_sdwa v85, v82 dst_sel:DWORD dst_unused:UNUSED_PAD src0_sel:WORD_1
	v_cvt_f32_f16_e32 v84, v82
	v_cvt_f32_f16_sdwa v87, v83 dst_sel:DWORD dst_unused:UNUSED_PAD src0_sel:WORD_1
	v_cvt_f32_f16_e32 v86, v83
	v_pk_add_f32 v[4:5], v[4:5], v[4:5] op_sel:[0,1] op_sel_hi:[1,0]
	v_pk_add_f32 v[74:75], v[74:75], v[74:75] op_sel:[0,1] op_sel_hi:[1,0]
	v_pk_mul_f32 v[82:83], v[84:85], v[84:85]
	v_pk_mul_f32 v[108:109], v[86:87], v[86:87]
	v_mov_b32_e32 v5, v82
	v_mov_b32_e32 v75, v83
	v_mov_b32_e32 v89, v108
	v_mov_b32_e32 v99, v109
	v_pk_add_f32 v[4:5], v[4:5], v[74:75]
	v_pk_add_f32 v[74:75], v[88:89], v[98:99]
	s_waitcnt vmcnt(58)
	v_cvt_f32_f16_sdwa v83, v80 dst_sel:DWORD dst_unused:UNUSED_PAD src0_sel:WORD_1
	v_cvt_f32_f16_sdwa v89, v81 dst_sel:DWORD dst_unused:UNUSED_PAD src0_sel:WORD_1
	v_cvt_f32_f16_e32 v82, v80
	v_cvt_f32_f16_e32 v88, v81
	v_pk_add_f32 v[4:5], v[4:5], v[74:75]
	v_mov_b32_e32 v74, v83
	v_mov_b32_e32 v75, v89
	v_pk_add_f32 v[98:99], v[4:5], v[4:5] op_sel:[0,1] op_sel_hi:[1,0]
	v_mov_b32_e32 v4, v82
	v_mov_b32_e32 v5, v88
	v_pk_mul_f32 v[74:75], v[74:75], v[74:75]
	s_waitcnt vmcnt(57)
; __device__ __forceinline__ void norm_mod_phase2(const Args& a, Frame& F, const float* gain, const float* modl, int sh_off, int sc_off, int nrows, const float* slab_gate) {
;     ...
;     NR_FINISH(r4, nw + 4 * 2048, (nw + 4 * 2048) >> 12);
;     NR_FINISH(r5, nw + 5 * 2048, (nw + 5 * 2048) >> 12);
	v_cvt_f32_f16_sdwa v81, v79 dst_sel:DWORD dst_unused:UNUSED_PAD src0_sel:WORD_1
	v_pk_fma_f32 v[4:5], v[4:5], v[4:5], v[74:75]
	v_cvt_f32_f16_e32 v80, v79
	v_pk_add_f32 v[108:109], v[4:5], v[4:5] op_sel:[0,1] op_sel_hi:[1,0]
	v_cvt_f32_f16_sdwa v5, v78 dst_sel:DWORD dst_unused:UNUSED_PAD src0_sel:WORD_1
	v_cvt_f32_f16_e32 v4, v78
	s_waitcnt vmcnt(56)
	v_cvt_f32_f16_sdwa v79, v77 dst_sel:DWORD dst_unused:UNUSED_PAD src0_sel:WORD_1
	v_cvt_f32_f16_e32 v78, v77
	v_mul_f32_e32 v74, v5, v5
	v_pk_fma_f32 v[110:111], v[4:5], v[4:5], v[74:75] op_sel_hi:[1,1,0]
	v_mul_f32_e32 v74, v81, v81
	v_pk_fma_f32 v[112:113], v[80:81], v[80:81], v[74:75] op_sel_hi:[1,1,0]
	v_cvt_f32_f16_sdwa v75, v76 dst_sel:DWORD dst_unused:UNUSED_PAD src0_sel:WORD_1
	v_cvt_f32_f16_e32 v74, v76
	v_pk_mul_f32 v[114:115], v[78:79], v[78:79]
	v_pk_mul_f32 v[76:77], v[74:75], v[74:75]
	s_nop 0
	v_mov_b32_e32 v99, v76
	v_mov_b32_e32 v109, v77
	v_mov_b32_e32 v111, v114
	v_mov_b32_e32 v113, v115
	v_pk_add_f32 v[76:77], v[98:99], v[108:109]
	v_pk_add_f32 v[98:99], v[110:111], v[112:113]
	s_nop 0
	v_pk_add_f32 v[76:77], v[76:77], v[98:99]
	s_nop 0
	v_add_f32_e32 v76, v76, v77
	s_nop 1
	v_add_f32_dpp v76, v76, v76 quad_perm:[1,0,3,2] row_mask:0xf bank_mask:0xf bound_ctrl:1
	s_nop 1
	v_add_f32_dpp v76, v76, v76 quad_perm:[2,3,0,1] row_mask:0xf bank_mask:0xf bound_ctrl:1
	s_nop 1
	v_add_f32_dpp v76, v76, v76 row_half_mirror row_mask:0xf bank_mask:0xf bound_ctrl:1
	s_nop 1
	v_add_f32_dpp v76, v76, v76 row_mirror row_mask:0xf bank_mask:0xf bound_ctrl:1
	s_nop 0
	v_readlane_b32 s8, v76, 16
	v_readlane_b32 s9, v76, 48
	v_readlane_b32 s6, v76, 0
	v_readlane_b32 s7, v76, 32
	v_mov_b32_e32 v76, s8
	v_mov_b32_e32 v77, s9
	v_pk_add_f32 v[76:77], s[6:7], v[76:77]
	s_nop 0
	v_add_f32_e32 v76, v76, v77
	v_fmamk_f32 v76, v76, 0x3a000000, v252
	v_cmp_gt_f32_e32 vcc, s55, v76
	v_mul_f32_e32 v77, 0x4f800000, v76
	s_nop 0
	v_cndmask_b32_e32 v76, v76, v77, vcc
	v_sqrt_f32_e32 v77, v76
	s_nop 0
	v_add_u32_e32 v98, -1, v77
	v_fma_f32 v99, -v98, v77, v76
	v_cmp_ge_f32_e64 s[8:9], 0, v99
	v_add_u32_e32 v99, 1, v77
	s_nop 0
	v_cndmask_b32_e64 v98, v77, v98, s[8:9]
	v_fma_f32 v77, -v99, v77, v76
	v_cmp_lt_f32_e64 s[8:9], 0, v77
	s_nop 1
	v_cndmask_b32_e64 v77, v98, v99, s[8:9]
	v_mul_f32_e32 v98, 0x37800000, v77
	v_cndmask_b32_e32 v77, v77, v98, vcc
	v_cmp_class_f32_e32 vcc, v76, v253
	s_nop 1
	v_cndmask_b32_e32 v76, v77, v76, vcc
	v_div_scale_f32 v77, s[6:7], v76, v76, 1.0
	v_rcp_f32_e32 v98, v77
	s_lshl_b32 s6, s30, 1
	s_and_b32 s6, s6, 0xffffe000
	s_add_i32 s6, s6, 0
	v_fma_f32 v99, -v77, v98, 1.0
	v_fmac_f32_e32 v98, v99, v98
	v_div_scale_f32 v99, vcc, 1.0, v76, 1.0
	v_mul_f32_e32 v108, v99, v98
	v_fma_f32 v109, -v77, v108, v99
	v_fmac_f32_e32 v108, v109, v98
	v_fma_f32 v77, -v77, v108, v99
	v_div_fmas_f32 v77, v77, v98, v108
	v_div_fixup_f32 v98, v77, v76, 1.0
	v_pk_mul_f32 v[112:113], v[104:105], v[98:99] op_sel_hi:[1,0]
	v_pk_mul_f32 v[114:115], v[106:107], v[98:99] op_sel_hi:[1,0]
	v_add_u32_e32 v99, s6, v0
	ds_read_b128 v[104:107], v99
	ds_read_b128 v[108:111], v99 offset:40960
	v_lshl_add_u64 v[76:77], s[34:35], 1, v[2:3]
	v_lshl_add_u64 v[76:77], v[76:77], 0, v[6:7]
	v_pk_mul_f32 v[4:5], v[4:5], v[98:99] op_sel_hi:[1,0]
	s_waitcnt lgkmcnt(0)
	v_pk_fma_f32 v[106:107], v[106:107], v[114:115], v[110:111]
	v_pk_fma_f32 v[104:105], v[104:105], v[112:113], v[108:109]
	v_pk_mul_f32 v[108:109], v[100:101], v[98:99] op_sel_hi:[1,0]
	v_cvt_pk_bf16_f32 v104, v104, v105
	v_cvt_pk_bf16_f32 v105, v106, v107
	global_store_dwordx2 v[76:77], v[104:105], off
	v_pk_mul_f32 v[110:111], v[102:103], v[98:99] op_sel_hi:[1,0]
	ds_read_b128 v[100:103], v99 offset:1024
	ds_read_b128 v[104:107], v99 offset:41984
	s_waitcnt lgkmcnt(0)
	v_pk_fma_f32 v[102:103], v[102:103], v[110:111], v[106:107]
	v_pk_fma_f32 v[100:101], v[100:101], v[108:109], v[104:105]
	v_pk_mul_f32 v[104:105], v[90:91], v[98:99] op_sel_hi:[1,0]
	v_cvt_pk_bf16_f32 v100, v100, v101
	v_cvt_pk_bf16_f32 v101, v102, v103
	global_store_dwordx2 v[76:77], v[100:101], off offset:512
	v_pk_mul_f32 v[106:107], v[92:93], v[98:99] op_sel_hi:[1,0]
	ds_read_b128 v[90:93], v99 offset:2048
	ds_read_b128 v[100:103], v99 offset:43008
	s_waitcnt lgkmcnt(0)
	v_pk_fma_f32 v[92:93], v[92:93], v[106:107], v[102:103]
	v_pk_fma_f32 v[90:91], v[90:91], v[104:105], v[100:101]
	v_pk_mul_f32 v[100:101], v[94:95], v[98:99] op_sel_hi:[1,0]
	v_cvt_pk_bf16_f32 v90, v90, v91
	v_cvt_pk_bf16_f32 v91, v92, v93
	global_store_dwordx2 v[76:77], v[90:91], off offset:1024
	v_pk_mul_f32 v[102:103], v[96:97], v[98:99] op_sel_hi:[1,0]
	ds_read_b128 v[90:93], v99 offset:3072
	ds_read_b128 v[94:97], v99 offset:44032
	s_waitcnt lgkmcnt(0)
	v_pk_fma_f32 v[92:93], v[102:103], v[92:93], v[96:97]
	v_pk_fma_f32 v[90:91], v[100:101], v[90:91], v[94:95]
	v_pk_mul_f32 v[94:95], v[84:85], v[98:99] op_sel_hi:[1,0]
	v_cvt_pk_bf16_f32 v90, v90, v91
	v_cvt_pk_bf16_f32 v91, v92, v93
	global_store_dwordx2 v[76:77], v[90:91], off offset:1536
	v_pk_mul_f32 v[96:97], v[86:87], v[98:99] op_sel_hi:[1,0]
	ds_read_b128 v[84:87], v99 offset:4096
	ds_read_b128 v[90:93], v99 offset:45056
	s_waitcnt lgkmcnt(0)
	v_pk_fma_f32 v[86:87], v[96:97], v[86:87], v[92:93]
	v_pk_fma_f32 v[84:85], v[94:95], v[84:85], v[90:91]
	v_pk_mul_f32 v[90:91], v[82:83], v[98:99] op_sel_hi:[1,0]
	v_cvt_pk_bf16_f32 v84, v84, v85
	v_cvt_pk_bf16_f32 v85, v86, v87
	global_store_dwordx2 v[76:77], v[84:85], off offset:2048
	v_pk_mul_f32 v[92:93], v[88:89], v[98:99] op_sel_hi:[1,0]
	ds_read_b128 v[82:85], v99 offset:5120
	ds_read_b128 v[86:89], v99 offset:46080
	s_waitcnt lgkmcnt(0)
; __device__ __forceinline__ void norm_mod_phase2(const Args& a, Frame& F, const float* gain, const float* modl, int sh_off, int sc_off, int nrows, const float* slab_gate) {
;     ...
;     NR_FINISH(r5, nw + 5 * 2048, (nw + 5 * 2048) >> 12);
;     NR_FINISH(r6, nw + 6 * 2048, (nw + 6 * 2048) >> 12);
	v_pk_fma_f32 v[84:85], v[92:93], v[84:85], v[88:89]
	v_pk_fma_f32 v[82:83], v[90:91], v[82:83], v[86:87]
	v_pk_mul_f32 v[88:89], v[80:81], v[98:99] op_sel_hi:[1,0]
	v_cvt_pk_bf16_f32 v82, v82, v83
	v_cvt_pk_bf16_f32 v83, v84, v85
	global_store_dwordx2 v[76:77], v[82:83], off offset:2560
	ds_read_b128 v[80:83], v99 offset:6144
	ds_read_b128 v[84:87], v99 offset:47104
	s_waitcnt vmcnt(61)
	v_cvt_f32_f16_sdwa v91, v73 dst_sel:DWORD dst_unused:UNUSED_PAD src0_sel:WORD_1
	v_cvt_f32_f16_e32 v90, v73
	s_waitcnt lgkmcnt(0)
	v_pk_fma_f32 v[82:83], v[88:89], v[82:83], v[86:87]
	v_pk_fma_f32 v[4:5], v[4:5], v[80:81], v[84:85]
	v_cvt_f32_f16_sdwa v89, v72 dst_sel:DWORD dst_unused:UNUSED_PAD src0_sel:WORD_1
	v_cvt_pk_bf16_f32 v4, v4, v5
	v_cvt_pk_bf16_f32 v5, v82, v83
	global_store_dwordx2 v[76:77], v[4:5], off offset:3072
	v_pk_mul_f32 v[4:5], v[74:75], v[98:99] op_sel_hi:[1,0]
	v_pk_mul_f32 v[74:75], v[78:79], v[98:99] op_sel_hi:[1,0]
	ds_read_b128 v[78:81], v99 offset:7168
	ds_read_b128 v[82:85], v99 offset:48128
	v_cvt_f32_f16_e32 v88, v72
	s_waitcnt vmcnt(61)
	v_cvt_f32_f16_sdwa v87, v71 dst_sel:DWORD dst_unused:UNUSED_PAD src0_sel:WORD_1
	v_cvt_f32_f16_e32 v86, v71
	v_mov_b32_e32 v72, v91
	s_waitcnt lgkmcnt(0)
	v_pk_fma_f32 v[74:75], v[74:75], v[80:81], v[84:85]
	v_cvt_f32_f16_sdwa v85, v70 dst_sel:DWORD dst_unused:UNUSED_PAD src0_sel:WORD_1
	v_cvt_f32_f16_e32 v84, v70
	v_pk_fma_f32 v[4:5], v[4:5], v[78:79], v[82:83]
	v_mov_b32_e32 v70, v89
	v_cvt_pk_bf16_f32 v4, v4, v5
	v_cvt_pk_bf16_f32 v5, v74, v75
	global_store_dwordx2 v[76:77], v[4:5], off offset:3584
	v_mov_b32_e32 v71, v85
	s_waitcnt vmcnt(61)
	v_cvt_f32_f16_sdwa v75, v68 dst_sel:DWORD dst_unused:UNUSED_PAD src0_sel:WORD_1
	v_cvt_f32_f16_sdwa v77, v69 dst_sel:DWORD dst_unused:UNUSED_PAD src0_sel:WORD_1
	v_mov_b32_e32 v4, v88
	v_mov_b32_e32 v5, v84
	v_pk_mul_f32 v[70:71], v[70:71], v[70:71]
	v_mov_b32_e32 v73, v87
	v_cvt_f32_f16_e32 v74, v68
	v_cvt_f32_f16_e32 v76, v69
	s_waitcnt vmcnt(60)
	v_cvt_f32_f16_sdwa v79, v66 dst_sel:DWORD dst_unused:UNUSED_PAD src0_sel:WORD_1
	v_pk_fma_f32 v[4:5], v[4:5], v[4:5], v[70:71]
	v_mov_b32_e32 v70, v90
	v_mov_b32_e32 v71, v86
	v_pk_mul_f32 v[72:73], v[72:73], v[72:73]
	v_cvt_f32_f16_e32 v78, v66
	v_cvt_f32_f16_sdwa v81, v67 dst_sel:DWORD dst_unused:UNUSED_PAD src0_sel:WORD_1
	v_pk_fma_f32 v[70:71], v[70:71], v[70:71], v[72:73]
	v_cvt_f32_f16_e32 v80, v67
	v_pk_add_f32 v[4:5], v[4:5], v[70:71]
	v_mov_b32_e32 v70, v75
	v_mov_b32_e32 v71, v77
	v_mov_b32_e32 v68, v74
	v_mov_b32_e32 v69, v76
	v_pk_mul_f32 v[70:71], v[70:71], v[70:71]
	v_mul_f32_e32 v66, v79, v79
	v_pk_fma_f32 v[68:69], v[68:69], v[68:69], v[70:71]
	v_pk_fma_f32 v[72:73], v[78:79], v[78:79], v[66:67] op_sel_hi:[1,1,0]
	v_mul_f32_e32 v66, v81, v81
	v_pk_add_f32 v[70:71], v[68:69], v[68:69] op_sel:[0,1] op_sel_hi:[1,0]
	v_pk_fma_f32 v[82:83], v[80:81], v[80:81], v[66:67] op_sel_hi:[1,1,0]
	s_waitcnt vmcnt(59)
	v_cvt_f32_f16_sdwa v67, v64 dst_sel:DWORD dst_unused:UNUSED_PAD src0_sel:WORD_1
	v_cvt_f32_f16_e32 v66, v64
	v_cvt_f32_f16_sdwa v69, v65 dst_sel:DWORD dst_unused:UNUSED_PAD src0_sel:WORD_1
	v_cvt_f32_f16_e32 v68, v65
	v_pk_add_f32 v[4:5], v[4:5], v[4:5] op_sel:[0,1] op_sel_hi:[1,0]
	v_pk_mul_f32 v[64:65], v[66:67], v[66:67]
	v_pk_mul_f32 v[92:93], v[68:69], v[68:69]
	v_mov_b32_e32 v5, v64
	v_mov_b32_e32 v71, v65
	v_mov_b32_e32 v73, v92
	v_mov_b32_e32 v83, v93
	v_pk_add_f32 v[4:5], v[4:5], v[70:71]
	v_pk_add_f32 v[64:65], v[72:73], v[82:83]
	s_waitcnt vmcnt(58)
	v_cvt_f32_f16_sdwa v71, v62 dst_sel:DWORD dst_unused:UNUSED_PAD src0_sel:WORD_1
	v_cvt_f32_f16_sdwa v73, v63 dst_sel:DWORD dst_unused:UNUSED_PAD src0_sel:WORD_1
	v_cvt_f32_f16_e32 v70, v62
	v_cvt_f32_f16_e32 v72, v63
	v_pk_add_f32 v[4:5], v[4:5], v[64:65]
	v_mov_b32_e32 v62, v71
	v_mov_b32_e32 v63, v73
	v_pk_add_f32 v[82:83], v[4:5], v[4:5] op_sel:[0,1] op_sel_hi:[1,0]
	v_mov_b32_e32 v4, v70
	v_mov_b32_e32 v5, v72
	v_pk_mul_f32 v[62:63], v[62:63], v[62:63]
	s_waitcnt vmcnt(56)
	v_cvt_f32_f16_sdwa v65, v59 dst_sel:DWORD dst_unused:UNUSED_PAD src0_sel:WORD_1
	v_pk_fma_f32 v[4:5], v[4:5], v[4:5], v[62:63]
	v_cvt_f32_f16_sdwa v63, v61 dst_sel:DWORD dst_unused:UNUSED_PAD src0_sel:WORD_1
	v_pk_add_f32 v[92:93], v[4:5], v[4:5] op_sel:[0,1] op_sel_hi:[1,0]
	v_cvt_f32_f16_sdwa v5, v60 dst_sel:DWORD dst_unused:UNUSED_PAD src0_sel:WORD_1
	v_cvt_f32_f16_e32 v4, v60
	v_cvt_f32_f16_e32 v62, v61
	v_cvt_f32_f16_e32 v64, v59
	v_mul_f32_e32 v60, v5, v5
	v_pk_fma_f32 v[94:95], v[4:5], v[4:5], v[60:61] op_sel_hi:[1,1,0]
	v_mul_f32_e32 v60, v63, v63
	v_pk_fma_f32 v[96:97], v[62:63], v[62:63], v[60:61] op_sel_hi:[1,1,0]
	v_cvt_f32_f16_sdwa v61, v58 dst_sel:DWORD dst_unused:UNUSED_PAD src0_sel:WORD_1
	v_cvt_f32_f16_e32 v60, v58
	v_pk_mul_f32 v[98:99], v[64:65], v[64:65]
	v_pk_mul_f32 v[58:59], v[60:61], v[60:61]
	s_nop 0
	v_mov_b32_e32 v83, v58
	v_mov_b32_e32 v93, v59
	v_mov_b32_e32 v95, v98
	v_mov_b32_e32 v97, v99
	v_pk_add_f32 v[58:59], v[82:83], v[92:93]
	v_pk_add_f32 v[82:83], v[94:95], v[96:97]
	s_nop 0
	v_pk_add_f32 v[58:59], v[58:59], v[82:83]
	s_nop 0
	v_add_f32_e32 v58, v58, v59
	s_nop 1
	v_add_f32_dpp v58, v58, v58 quad_perm:[1,0,3,2] row_mask:0xf bank_mask:0xf bound_ctrl:1
	s_nop 1
	v_add_f32_dpp v58, v58, v58 quad_perm:[2,3,0,1] row_mask:0xf bank_mask:0xf bound_ctrl:1
	s_nop 1
	v_add_f32_dpp v58, v58, v58 row_half_mirror row_mask:0xf bank_mask:0xf bound_ctrl:1
	s_nop 1
	v_add_f32_dpp v58, v58, v58 row_mirror row_mask:0xf bank_mask:0xf bound_ctrl:1
	s_nop 0
	v_readlane_b32 s8, v58, 16
	v_readlane_b32 s9, v58, 48
	v_readlane_b32 s6, v58, 0
	v_readlane_b32 s7, v58, 32
	v_mov_b32_e32 v58, s8
	v_mov_b32_e32 v59, s9
	v_pk_add_f32 v[58:59], s[6:7], v[58:59]
; __device__ __forceinline__ void norm_mod_phase2(const Args& a, Frame& F, const float* gain, const float* modl, int sh_off, int sc_off, int nrows, const float* slab_gate) {
;     ...
;     NR_FINISH(r5, nw + 5 * 2048, (nw + 5 * 2048) >> 12);
;     NR_FINISH(r6, nw + 6 * 2048, (nw + 6 * 2048) >> 12);
	s_nop 0
	v_add_f32_e32 v58, v58, v59
	v_fmamk_f32 v58, v58, 0x3a000000, v252
	v_cmp_gt_f32_e32 vcc, s55, v58
	v_mul_f32_e32 v59, 0x4f800000, v58
	s_nop 0
	v_cndmask_b32_e32 v58, v58, v59, vcc
	v_sqrt_f32_e32 v59, v58
	s_nop 0
	v_add_u32_e32 v82, -1, v59
	v_fma_f32 v83, -v82, v59, v58
	v_cmp_ge_f32_e64 s[8:9], 0, v83
	v_add_u32_e32 v83, 1, v59
	s_nop 0
	v_cndmask_b32_e64 v82, v59, v82, s[8:9]
	v_fma_f32 v59, -v83, v59, v58
	v_cmp_lt_f32_e64 s[8:9], 0, v59
	s_nop 1
	v_cndmask_b32_e64 v59, v82, v83, s[8:9]
	v_mul_f32_e32 v82, 0x37800000, v59
	v_cndmask_b32_e32 v59, v59, v82, vcc
	v_cmp_class_f32_e32 vcc, v58, v253
	s_nop 1
	v_cndmask_b32_e32 v58, v59, v58, vcc
	v_div_scale_f32 v59, s[6:7], v58, v58, 1.0
	v_rcp_f32_e32 v82, v59
	s_lshl_b32 s6, s26, 1
	s_and_b32 s6, s6, 0xffffe000
	s_add_i32 s6, s6, 0
	v_fma_f32 v83, -v59, v82, 1.0
	v_fmac_f32_e32 v82, v83, v82
	v_div_scale_f32 v83, vcc, 1.0, v58, 1.0
	v_mul_f32_e32 v92, v83, v82
	v_fma_f32 v93, -v59, v92, v83
	v_fmac_f32_e32 v92, v93, v82
	v_fma_f32 v59, -v59, v92, v83
	v_div_fmas_f32 v59, v59, v82, v92
	v_div_fixup_f32 v82, v59, v58, 1.0
	v_pk_mul_f32 v[96:97], v[88:89], v[82:83] op_sel_hi:[1,0]
	v_pk_mul_f32 v[98:99], v[90:91], v[82:83] op_sel_hi:[1,0]
	v_add_u32_e32 v83, s6, v0
	ds_read_b128 v[88:91], v83
	ds_read_b128 v[92:95], v83 offset:40960
	v_lshl_add_u64 v[58:59], s[28:29], 1, v[2:3]
	v_lshl_add_u64 v[58:59], v[58:59], 0, v[6:7]
	v_pk_mul_f32 v[4:5], v[4:5], v[82:83] op_sel_hi:[1,0]
	v_pk_mul_f32 v[62:63], v[62:63], v[82:83] op_sel_hi:[1,0]
	s_waitcnt lgkmcnt(0)
	v_pk_fma_f32 v[90:91], v[90:91], v[98:99], v[94:95]
	v_pk_fma_f32 v[88:89], v[88:89], v[96:97], v[92:93]
	v_pk_mul_f32 v[92:93], v[84:85], v[82:83] op_sel_hi:[1,0]
	v_cvt_pk_bf16_f32 v88, v88, v89
	v_cvt_pk_bf16_f32 v89, v90, v91
	global_store_dwordx2 v[58:59], v[88:89], off
	v_pk_mul_f32 v[94:95], v[86:87], v[82:83] op_sel_hi:[1,0]
	ds_read_b128 v[84:87], v83 offset:1024
	ds_read_b128 v[88:91], v83 offset:41984
	s_waitcnt lgkmcnt(0)
	v_pk_fma_f32 v[86:87], v[86:87], v[94:95], v[90:91]
	v_pk_fma_f32 v[84:85], v[84:85], v[92:93], v[88:89]
	v_pk_mul_f32 v[88:89], v[74:75], v[82:83] op_sel_hi:[1,0]
	v_cvt_pk_bf16_f32 v84, v84, v85
	v_cvt_pk_bf16_f32 v85, v86, v87
	global_store_dwordx2 v[58:59], v[84:85], off offset:512
	v_pk_mul_f32 v[90:91], v[76:77], v[82:83] op_sel_hi:[1,0]
	ds_read_b128 v[74:77], v83 offset:2048
	ds_read_b128 v[84:87], v83 offset:43008
	s_waitcnt lgkmcnt(0)
	v_pk_fma_f32 v[76:77], v[76:77], v[90:91], v[86:87]
	v_pk_fma_f32 v[74:75], v[74:75], v[88:89], v[84:85]
	v_pk_mul_f32 v[84:85], v[78:79], v[82:83] op_sel_hi:[1,0]
	v_cvt_pk_bf16_f32 v74, v74, v75
	v_cvt_pk_bf16_f32 v75, v76, v77
	global_store_dwordx2 v[58:59], v[74:75], off offset:1024
	v_pk_mul_f32 v[86:87], v[80:81], v[82:83] op_sel_hi:[1,0]
	ds_read_b128 v[74:77], v83 offset:3072
	ds_read_b128 v[78:81], v83 offset:44032
	s_waitcnt lgkmcnt(0)
	v_pk_fma_f32 v[76:77], v[86:87], v[76:77], v[80:81]
	v_pk_fma_f32 v[74:75], v[84:85], v[74:75], v[78:79]
	v_pk_mul_f32 v[78:79], v[66:67], v[82:83] op_sel_hi:[1,0]
	v_cvt_pk_bf16_f32 v74, v74, v75
	v_cvt_pk_bf16_f32 v75, v76, v77
	global_store_dwordx2 v[58:59], v[74:75], off offset:1536
	v_pk_mul_f32 v[80:81], v[68:69], v[82:83] op_sel_hi:[1,0]
	ds_read_b128 v[66:69], v83 offset:4096
	ds_read_b128 v[74:77], v83 offset:45056
	s_waitcnt lgkmcnt(0)
	v_pk_fma_f32 v[68:69], v[80:81], v[68:69], v[76:77]
	v_pk_fma_f32 v[66:67], v[78:79], v[66:67], v[74:75]
	v_pk_mul_f32 v[74:75], v[70:71], v[82:83] op_sel_hi:[1,0]
	v_cvt_pk_bf16_f32 v66, v66, v67
	v_cvt_pk_bf16_f32 v67, v68, v69
	global_store_dwordx2 v[58:59], v[66:67], off offset:2048
	v_pk_mul_f32 v[76:77], v[72:73], v[82:83] op_sel_hi:[1,0]
	ds_read_b128 v[66:69], v83 offset:5120
	ds_read_b128 v[70:73], v83 offset:46080
	s_waitcnt lgkmcnt(0)
	v_pk_fma_f32 v[68:69], v[76:77], v[68:69], v[72:73]
	v_pk_fma_f32 v[66:67], v[74:75], v[66:67], v[70:71]
	s_waitcnt vmcnt(60)
	v_cvt_f32_f16_sdwa v75, v57 dst_sel:DWORD dst_unused:UNUSED_PAD src0_sel:WORD_1
	v_cvt_pk_bf16_f32 v66, v66, v67
	v_cvt_pk_bf16_f32 v67, v68, v69
	global_store_dwordx2 v[58:59], v[66:67], off offset:2560
	ds_read_b128 v[66:69], v83 offset:6144
	ds_read_b128 v[70:73], v83 offset:47104
	v_cvt_f32_f16_e32 v74, v57
	s_waitcnt lgkmcnt(0)
	v_pk_fma_f32 v[62:63], v[62:63], v[68:69], v[72:73]
	v_pk_fma_f32 v[4:5], v[4:5], v[66:67], v[70:71]
	v_pk_mul_f32 v[68:69], v[64:65], v[82:83] op_sel_hi:[1,0]
	v_cvt_pk_bf16_f32 v4, v4, v5
	v_cvt_pk_bf16_f32 v5, v62, v63
	global_store_dwordx2 v[58:59], v[4:5], off offset:3072
	v_pk_mul_f32 v[4:5], v[60:61], v[82:83] op_sel_hi:[1,0]
	ds_read_b128 v[60:63], v83 offset:7168
	ds_read_b128 v[64:67], v83 offset:48128
	v_cvt_f32_f16_sdwa v73, v56 dst_sel:DWORD dst_unused:UNUSED_PAD src0_sel:WORD_1
	v_cvt_f32_f16_e32 v72, v56
	s_waitcnt vmcnt(61)
	v_cvt_f32_f16_sdwa v71, v55 dst_sel:DWORD dst_unused:UNUSED_PAD src0_sel:WORD_1
	v_cvt_f32_f16_e32 v70, v55
	s_waitcnt lgkmcnt(0)
	v_pk_fma_f32 v[62:63], v[68:69], v[62:63], v[66:67]
	v_cvt_f32_f16_sdwa v69, v54 dst_sel:DWORD dst_unused:UNUSED_PAD src0_sel:WORD_1
	v_cvt_f32_f16_e32 v68, v54
	v_pk_fma_f32 v[4:5], v[4:5], v[60:61], v[64:65]
	v_mov_b32_e32 v54, v73
	v_cvt_pk_bf16_f32 v4, v4, v5
	v_cvt_pk_bf16_f32 v5, v62, v63
	global_store_dwordx2 v[58:59], v[4:5], off offset:3584
	v_mov_b32_e32 v55, v69
	s_waitcnt vmcnt(61)
	v_cvt_f32_f16_sdwa v59, v52 dst_sel:DWORD dst_unused:UNUSED_PAD src0_sel:WORD_1
	v_cvt_f32_f16_sdwa v61, v53 dst_sel:DWORD dst_unused:UNUSED_PAD src0_sel:WORD_1
	v_mov_b32_e32 v4, v72
	v_mov_b32_e32 v5, v68
	v_pk_mul_f32 v[54:55], v[54:55], v[54:55]
	v_mov_b32_e32 v56, v75
	v_mov_b32_e32 v57, v71
	v_cvt_f32_f16_e32 v58, v52
	v_cvt_f32_f16_e32 v60, v53
	s_waitcnt vmcnt(60)
; __device__ __forceinline__ void norm_mod_phase2(const Args& a, Frame& F, const float* gain, const float* modl, int sh_off, int sc_off, int nrows, const float* slab_gate) {
;     ...
;     NR_FINISH(r6, nw + 6 * 2048, (nw + 6 * 2048) >> 12);
;     NR_FINISH(r7, nw + 7 * 2048, (nw + 7 * 2048) >> 12);
	v_cvt_f32_f16_sdwa v63, v50 dst_sel:DWORD dst_unused:UNUSED_PAD src0_sel:WORD_1
	v_pk_fma_f32 v[4:5], v[4:5], v[4:5], v[54:55]
	v_mov_b32_e32 v54, v74
	v_mov_b32_e32 v55, v70
	v_pk_mul_f32 v[56:57], v[56:57], v[56:57]
	v_cvt_f32_f16_e32 v62, v50
	v_cvt_f32_f16_sdwa v65, v51 dst_sel:DWORD dst_unused:UNUSED_PAD src0_sel:WORD_1
	v_pk_fma_f32 v[54:55], v[54:55], v[54:55], v[56:57]
	v_cvt_f32_f16_e32 v64, v51
	v_pk_add_f32 v[4:5], v[4:5], v[54:55]
	v_mov_b32_e32 v54, v59
	v_mov_b32_e32 v55, v61
	v_mov_b32_e32 v52, v58
	v_mov_b32_e32 v53, v60
	v_pk_mul_f32 v[54:55], v[54:55], v[54:55]
	v_mul_f32_e32 v50, v63, v63
	v_pk_fma_f32 v[52:53], v[52:53], v[52:53], v[54:55]
	v_pk_fma_f32 v[56:57], v[62:63], v[62:63], v[50:51] op_sel_hi:[1,1,0]
	v_mul_f32_e32 v50, v65, v65
	v_pk_add_f32 v[54:55], v[52:53], v[52:53] op_sel:[0,1] op_sel_hi:[1,0]
	v_pk_fma_f32 v[66:67], v[64:65], v[64:65], v[50:51] op_sel_hi:[1,1,0]
	s_waitcnt vmcnt(59)
	v_cvt_f32_f16_sdwa v51, v48 dst_sel:DWORD dst_unused:UNUSED_PAD src0_sel:WORD_1
	v_cvt_f32_f16_e32 v50, v48
	v_cvt_f32_f16_sdwa v53, v49 dst_sel:DWORD dst_unused:UNUSED_PAD src0_sel:WORD_1
	v_cvt_f32_f16_e32 v52, v49
	v_pk_add_f32 v[4:5], v[4:5], v[4:5] op_sel:[0,1] op_sel_hi:[1,0]
	v_pk_mul_f32 v[48:49], v[50:51], v[50:51]
	v_pk_mul_f32 v[76:77], v[52:53], v[52:53]
	v_mov_b32_e32 v5, v48
	v_mov_b32_e32 v55, v49
	v_mov_b32_e32 v57, v76
	v_mov_b32_e32 v67, v77
	v_pk_add_f32 v[4:5], v[4:5], v[54:55]
	v_pk_add_f32 v[48:49], v[56:57], v[66:67]
	s_waitcnt vmcnt(58)
	v_cvt_f32_f16_sdwa v55, v46 dst_sel:DWORD dst_unused:UNUSED_PAD src0_sel:WORD_1
	v_cvt_f32_f16_sdwa v57, v47 dst_sel:DWORD dst_unused:UNUSED_PAD src0_sel:WORD_1
	v_cvt_f32_f16_e32 v54, v46
	v_cvt_f32_f16_e32 v56, v47
	v_pk_add_f32 v[4:5], v[4:5], v[48:49]
	v_mov_b32_e32 v46, v55
	v_mov_b32_e32 v47, v57
	v_pk_add_f32 v[66:67], v[4:5], v[4:5] op_sel:[0,1] op_sel_hi:[1,0]
	v_mov_b32_e32 v4, v54
	v_mov_b32_e32 v5, v56
	v_pk_mul_f32 v[46:47], v[46:47], v[46:47]
	s_waitcnt vmcnt(56)
	v_cvt_f32_f16_sdwa v49, v43 dst_sel:DWORD dst_unused:UNUSED_PAD src0_sel:WORD_1
	v_pk_fma_f32 v[4:5], v[4:5], v[4:5], v[46:47]
	v_cvt_f32_f16_sdwa v47, v45 dst_sel:DWORD dst_unused:UNUSED_PAD src0_sel:WORD_1
	v_pk_add_f32 v[76:77], v[4:5], v[4:5] op_sel:[0,1] op_sel_hi:[1,0]
	v_cvt_f32_f16_sdwa v5, v44 dst_sel:DWORD dst_unused:UNUSED_PAD src0_sel:WORD_1
	v_cvt_f32_f16_e32 v4, v44
	v_cvt_f32_f16_e32 v46, v45
	v_cvt_f32_f16_e32 v48, v43
	v_mul_f32_e32 v44, v5, v5
	v_pk_fma_f32 v[78:79], v[4:5], v[4:5], v[44:45] op_sel_hi:[1,1,0]
	v_mul_f32_e32 v44, v47, v47
	v_pk_fma_f32 v[80:81], v[46:47], v[46:47], v[44:45] op_sel_hi:[1,1,0]
	v_cvt_f32_f16_sdwa v45, v42 dst_sel:DWORD dst_unused:UNUSED_PAD src0_sel:WORD_1
	v_cvt_f32_f16_e32 v44, v42
	v_pk_mul_f32 v[82:83], v[48:49], v[48:49]
	v_pk_mul_f32 v[42:43], v[44:45], v[44:45]
	s_nop 0
	v_mov_b32_e32 v67, v42
	v_mov_b32_e32 v77, v43
	v_mov_b32_e32 v79, v82
	v_mov_b32_e32 v81, v83
	v_pk_add_f32 v[42:43], v[66:67], v[76:77]
	v_pk_add_f32 v[66:67], v[78:79], v[80:81]
	s_nop 0
	v_pk_add_f32 v[42:43], v[42:43], v[66:67]
	s_nop 0
	v_add_f32_e32 v42, v42, v43
	s_nop 1
	v_add_f32_dpp v42, v42, v42 quad_perm:[1,0,3,2] row_mask:0xf bank_mask:0xf bound_ctrl:1
	s_nop 1
	v_add_f32_dpp v42, v42, v42 quad_perm:[2,3,0,1] row_mask:0xf bank_mask:0xf bound_ctrl:1
	s_nop 1
	v_add_f32_dpp v42, v42, v42 row_half_mirror row_mask:0xf bank_mask:0xf bound_ctrl:1
	s_nop 1
	v_add_f32_dpp v42, v42, v42 row_mirror row_mask:0xf bank_mask:0xf bound_ctrl:1
	s_nop 0
	v_readlane_b32 s8, v42, 16
	v_readlane_b32 s9, v42, 48
	v_readlane_b32 s6, v42, 0
	v_readlane_b32 s7, v42, 32
	v_mov_b32_e32 v42, s8
	v_mov_b32_e32 v43, s9
	v_pk_add_f32 v[42:43], s[6:7], v[42:43]
	s_nop 0
	v_add_f32_e32 v42, v42, v43
	v_fmamk_f32 v42, v42, 0x3a000000, v252
	v_cmp_gt_f32_e32 vcc, s55, v42
	v_mul_f32_e32 v43, 0x4f800000, v42
	s_nop 0
	v_cndmask_b32_e32 v42, v42, v43, vcc
	v_sqrt_f32_e32 v43, v42
	s_nop 0
	v_add_u32_e32 v66, -1, v43
	v_fma_f32 v67, -v66, v43, v42
	v_cmp_ge_f32_e64 s[8:9], 0, v67
	v_add_u32_e32 v67, 1, v43
	s_nop 0
	v_cndmask_b32_e64 v66, v43, v66, s[8:9]
	v_fma_f32 v43, -v67, v43, v42
	v_cmp_lt_f32_e64 s[8:9], 0, v43
	s_nop 1
	v_cndmask_b32_e64 v43, v66, v67, s[8:9]
	v_mul_f32_e32 v66, 0x37800000, v43
	v_cndmask_b32_e32 v43, v43, v66, vcc
	v_cmp_class_f32_e32 vcc, v42, v253
	s_nop 1
	v_cndmask_b32_e32 v42, v43, v42, vcc
	v_div_scale_f32 v43, s[6:7], v42, v42, 1.0
	v_rcp_f32_e32 v66, v43
	s_lshl_b32 s6, s22, 1
	s_and_b32 s6, s6, 0xffffe000
	s_add_i32 s6, s6, 0
	v_fma_f32 v67, -v43, v66, 1.0
	v_fmac_f32_e32 v66, v67, v66
	v_div_scale_f32 v67, vcc, 1.0, v42, 1.0
	v_mul_f32_e32 v76, v67, v66
	v_fma_f32 v77, -v43, v76, v67
	v_fmac_f32_e32 v76, v77, v66
	v_fma_f32 v43, -v43, v76, v67
	v_div_fmas_f32 v43, v43, v66, v76
	v_div_fixup_f32 v66, v43, v42, 1.0
	v_pk_mul_f32 v[80:81], v[72:73], v[66:67] op_sel_hi:[1,0]
	v_pk_mul_f32 v[82:83], v[74:75], v[66:67] op_sel_hi:[1,0]
	v_add_u32_e32 v67, s6, v0
	ds_read_b128 v[72:75], v67
	ds_read_b128 v[76:79], v67 offset:40960
	v_lshl_add_u64 v[42:43], s[24:25], 1, v[2:3]
	v_lshl_add_u64 v[42:43], v[42:43], 0, v[6:7]
	v_pk_mul_f32 v[4:5], v[4:5], v[66:67] op_sel_hi:[1,0]
	v_pk_mul_f32 v[46:47], v[46:47], v[66:67] op_sel_hi:[1,0]
	s_waitcnt lgkmcnt(0)
	v_pk_fma_f32 v[74:75], v[74:75], v[82:83], v[78:79]
	v_pk_fma_f32 v[72:73], v[72:73], v[80:81], v[76:77]
	v_pk_mul_f32 v[76:77], v[68:69], v[66:67] op_sel_hi:[1,0]
	v_cvt_pk_bf16_f32 v72, v72, v73
	v_cvt_pk_bf16_f32 v73, v74, v75
	global_store_dwordx2 v[42:43], v[72:73], off
	v_pk_mul_f32 v[78:79], v[70:71], v[66:67] op_sel_hi:[1,0]
	ds_read_b128 v[68:71], v67 offset:1024
	ds_read_b128 v[72:75], v67 offset:41984
	s_waitcnt lgkmcnt(0)
; __device__ __forceinline__ void norm_mod_phase2(const Args& a, Frame& F, const float* gain, const float* modl, int sh_off, int sc_off, int nrows, const float* slab_gate) {
;     ...
;     NR_FINISH(r6, nw + 6 * 2048, (nw + 6 * 2048) >> 12);
;     NR_FINISH(r7, nw + 7 * 2048, (nw + 7 * 2048) >> 12);
	v_pk_fma_f32 v[70:71], v[70:71], v[78:79], v[74:75]
	v_pk_fma_f32 v[68:69], v[68:69], v[76:77], v[72:73]
	v_pk_mul_f32 v[72:73], v[58:59], v[66:67] op_sel_hi:[1,0]
	v_cvt_pk_bf16_f32 v68, v68, v69
	v_cvt_pk_bf16_f32 v69, v70, v71
	global_store_dwordx2 v[42:43], v[68:69], off offset:512
	v_pk_mul_f32 v[74:75], v[60:61], v[66:67] op_sel_hi:[1,0]
	ds_read_b128 v[58:61], v67 offset:2048
	ds_read_b128 v[68:71], v67 offset:43008
	s_waitcnt lgkmcnt(0)
	v_pk_fma_f32 v[60:61], v[60:61], v[74:75], v[70:71]
	v_pk_fma_f32 v[58:59], v[58:59], v[72:73], v[68:69]
	v_pk_mul_f32 v[68:69], v[62:63], v[66:67] op_sel_hi:[1,0]
	v_cvt_pk_bf16_f32 v58, v58, v59
	v_cvt_pk_bf16_f32 v59, v60, v61
	global_store_dwordx2 v[42:43], v[58:59], off offset:1024
	v_pk_mul_f32 v[70:71], v[64:65], v[66:67] op_sel_hi:[1,0]
	ds_read_b128 v[58:61], v67 offset:3072
	ds_read_b128 v[62:65], v67 offset:44032
	s_waitcnt lgkmcnt(0)
	v_pk_fma_f32 v[60:61], v[70:71], v[60:61], v[64:65]
	v_pk_fma_f32 v[58:59], v[68:69], v[58:59], v[62:63]
	v_pk_mul_f32 v[62:63], v[50:51], v[66:67] op_sel_hi:[1,0]
	v_cvt_pk_bf16_f32 v58, v58, v59
	v_cvt_pk_bf16_f32 v59, v60, v61
	global_store_dwordx2 v[42:43], v[58:59], off offset:1536
	v_pk_mul_f32 v[64:65], v[52:53], v[66:67] op_sel_hi:[1,0]
	ds_read_b128 v[50:53], v67 offset:4096
	ds_read_b128 v[58:61], v67 offset:45056
	s_waitcnt lgkmcnt(0)
	v_pk_fma_f32 v[52:53], v[64:65], v[52:53], v[60:61]
	v_pk_fma_f32 v[50:51], v[62:63], v[50:51], v[58:59]
	v_pk_mul_f32 v[58:59], v[54:55], v[66:67] op_sel_hi:[1,0]
	v_cvt_pk_bf16_f32 v50, v50, v51
	v_cvt_pk_bf16_f32 v51, v52, v53
	global_store_dwordx2 v[42:43], v[50:51], off offset:2048
	v_pk_mul_f32 v[60:61], v[56:57], v[66:67] op_sel_hi:[1,0]
	ds_read_b128 v[50:53], v67 offset:5120
	ds_read_b128 v[54:57], v67 offset:46080
	s_waitcnt lgkmcnt(0)
	v_pk_fma_f32 v[52:53], v[60:61], v[52:53], v[56:57]
	v_pk_fma_f32 v[50:51], v[58:59], v[50:51], v[54:55]
	s_waitcnt vmcnt(60)
	v_cvt_f32_f16_sdwa v59, v41 dst_sel:DWORD dst_unused:UNUSED_PAD src0_sel:WORD_1
	v_cvt_pk_bf16_f32 v50, v50, v51
	v_cvt_pk_bf16_f32 v51, v52, v53
	global_store_dwordx2 v[42:43], v[50:51], off offset:2560
	ds_read_b128 v[50:53], v67 offset:6144
	ds_read_b128 v[54:57], v67 offset:47104
	v_cvt_f32_f16_e32 v58, v41
	s_waitcnt lgkmcnt(0)
	v_pk_fma_f32 v[46:47], v[46:47], v[52:53], v[56:57]
	v_pk_fma_f32 v[4:5], v[4:5], v[50:51], v[54:55]
	v_pk_mul_f32 v[52:53], v[48:49], v[66:67] op_sel_hi:[1,0]
	v_cvt_pk_bf16_f32 v4, v4, v5
	v_cvt_pk_bf16_f32 v5, v46, v47
	global_store_dwordx2 v[42:43], v[4:5], off offset:3072
	v_pk_mul_f32 v[4:5], v[44:45], v[66:67] op_sel_hi:[1,0]
	ds_read_b128 v[44:47], v67 offset:7168
	ds_read_b128 v[48:51], v67 offset:48128
	v_cvt_f32_f16_sdwa v57, v40 dst_sel:DWORD dst_unused:UNUSED_PAD src0_sel:WORD_1
	v_cvt_f32_f16_e32 v56, v40
	s_waitcnt vmcnt(61)
	v_cvt_f32_f16_sdwa v55, v39 dst_sel:DWORD dst_unused:UNUSED_PAD src0_sel:WORD_1
	v_cvt_f32_f16_e32 v54, v39
	s_waitcnt lgkmcnt(0)
	v_pk_fma_f32 v[46:47], v[52:53], v[46:47], v[50:51]
	v_cvt_f32_f16_sdwa v53, v38 dst_sel:DWORD dst_unused:UNUSED_PAD src0_sel:WORD_1
	v_cvt_f32_f16_e32 v52, v38
	v_pk_fma_f32 v[4:5], v[4:5], v[44:45], v[48:49]
	v_mov_b32_e32 v38, v57
	v_cvt_pk_bf16_f32 v4, v4, v5
	v_cvt_pk_bf16_f32 v5, v46, v47
	global_store_dwordx2 v[42:43], v[4:5], off offset:3584
	v_mov_b32_e32 v39, v53
	s_waitcnt vmcnt(61)
	v_cvt_f32_f16_sdwa v43, v36 dst_sel:DWORD dst_unused:UNUSED_PAD src0_sel:WORD_1
	v_cvt_f32_f16_sdwa v45, v37 dst_sel:DWORD dst_unused:UNUSED_PAD src0_sel:WORD_1
	v_mov_b32_e32 v4, v56
	v_mov_b32_e32 v5, v52
	v_pk_mul_f32 v[38:39], v[38:39], v[38:39]
	v_mov_b32_e32 v40, v59
	v_mov_b32_e32 v41, v55
	v_cvt_f32_f16_e32 v42, v36
	v_cvt_f32_f16_e32 v44, v37
	s_waitcnt vmcnt(60)
	v_cvt_f32_f16_sdwa v47, v34 dst_sel:DWORD dst_unused:UNUSED_PAD src0_sel:WORD_1
	v_pk_fma_f32 v[4:5], v[4:5], v[4:5], v[38:39]
	v_mov_b32_e32 v38, v58
	v_mov_b32_e32 v39, v54
	v_pk_mul_f32 v[40:41], v[40:41], v[40:41]
	v_cvt_f32_f16_e32 v46, v34
	v_cvt_f32_f16_sdwa v49, v35 dst_sel:DWORD dst_unused:UNUSED_PAD src0_sel:WORD_1
	v_pk_fma_f32 v[38:39], v[38:39], v[38:39], v[40:41]
	v_cvt_f32_f16_e32 v48, v35
	v_pk_add_f32 v[4:5], v[4:5], v[38:39]
	v_mov_b32_e32 v38, v43
	v_mov_b32_e32 v39, v45
	v_mov_b32_e32 v36, v42
	v_mov_b32_e32 v37, v44
	v_pk_mul_f32 v[38:39], v[38:39], v[38:39]
	v_mul_f32_e32 v34, v47, v47
	v_pk_fma_f32 v[36:37], v[36:37], v[36:37], v[38:39]
	v_pk_fma_f32 v[40:41], v[46:47], v[46:47], v[34:35] op_sel_hi:[1,1,0]
	v_mul_f32_e32 v34, v49, v49
	v_pk_add_f32 v[38:39], v[36:37], v[36:37] op_sel:[0,1] op_sel_hi:[1,0]
	v_pk_fma_f32 v[50:51], v[48:49], v[48:49], v[34:35] op_sel_hi:[1,1,0]
	s_waitcnt vmcnt(59)
	v_cvt_f32_f16_sdwa v35, v32 dst_sel:DWORD dst_unused:UNUSED_PAD src0_sel:WORD_1
	v_cvt_f32_f16_e32 v34, v32
	v_cvt_f32_f16_sdwa v37, v33 dst_sel:DWORD dst_unused:UNUSED_PAD src0_sel:WORD_1
	v_cvt_f32_f16_e32 v36, v33
	v_pk_add_f32 v[4:5], v[4:5], v[4:5] op_sel:[0,1] op_sel_hi:[1,0]
	v_pk_mul_f32 v[32:33], v[34:35], v[34:35]
	v_pk_mul_f32 v[60:61], v[36:37], v[36:37]
	v_mov_b32_e32 v5, v32
	v_mov_b32_e32 v39, v33
	v_mov_b32_e32 v41, v60
	v_mov_b32_e32 v51, v61
	v_pk_add_f32 v[4:5], v[4:5], v[38:39]
	v_pk_add_f32 v[32:33], v[40:41], v[50:51]
	s_waitcnt vmcnt(58)
	v_cvt_f32_f16_sdwa v39, v30 dst_sel:DWORD dst_unused:UNUSED_PAD src0_sel:WORD_1
	v_cvt_f32_f16_sdwa v41, v31 dst_sel:DWORD dst_unused:UNUSED_PAD src0_sel:WORD_1
	v_cvt_f32_f16_e32 v38, v30
	v_cvt_f32_f16_e32 v40, v31
	v_pk_add_f32 v[4:5], v[4:5], v[32:33]
	v_mov_b32_e32 v30, v39
	v_mov_b32_e32 v31, v41
	v_pk_add_f32 v[50:51], v[4:5], v[4:5] op_sel:[0,1] op_sel_hi:[1,0]
	v_mov_b32_e32 v4, v38
	v_mov_b32_e32 v5, v40
	v_pk_mul_f32 v[30:31], v[30:31], v[30:31]
	s_waitcnt vmcnt(56)
; __device__ __forceinline__ void norm_mod_phase2(const Args& a, Frame& F, const float* gain, const float* modl, int sh_off, int sc_off, int nrows, const float* slab_gate) {
;     ...
;     NR_FINISH(r6, nw + 6 * 2048, (nw + 6 * 2048) >> 12);
;     NR_FINISH(r7, nw + 7 * 2048, (nw + 7 * 2048) >> 12);
	v_cvt_f32_f16_sdwa v33, v27 dst_sel:DWORD dst_unused:UNUSED_PAD src0_sel:WORD_1
	v_pk_fma_f32 v[4:5], v[4:5], v[4:5], v[30:31]
	v_cvt_f32_f16_sdwa v31, v29 dst_sel:DWORD dst_unused:UNUSED_PAD src0_sel:WORD_1
	v_pk_add_f32 v[60:61], v[4:5], v[4:5] op_sel:[0,1] op_sel_hi:[1,0]
	v_cvt_f32_f16_sdwa v5, v28 dst_sel:DWORD dst_unused:UNUSED_PAD src0_sel:WORD_1
	v_cvt_f32_f16_e32 v4, v28
	v_cvt_f32_f16_e32 v30, v29
	v_cvt_f32_f16_e32 v32, v27
	v_mul_f32_e32 v28, v5, v5
	v_pk_fma_f32 v[62:63], v[4:5], v[4:5], v[28:29] op_sel_hi:[1,1,0]
	v_mul_f32_e32 v28, v31, v31
	v_pk_fma_f32 v[64:65], v[30:31], v[30:31], v[28:29] op_sel_hi:[1,1,0]
	v_cvt_f32_f16_sdwa v29, v26 dst_sel:DWORD dst_unused:UNUSED_PAD src0_sel:WORD_1
	v_cvt_f32_f16_e32 v28, v26
	v_pk_mul_f32 v[66:67], v[32:33], v[32:33]
	v_pk_mul_f32 v[26:27], v[28:29], v[28:29]
	s_nop 0
	v_mov_b32_e32 v51, v26
	v_mov_b32_e32 v61, v27
	v_mov_b32_e32 v63, v66
	v_mov_b32_e32 v65, v67
	v_pk_add_f32 v[26:27], v[50:51], v[60:61]
	v_pk_add_f32 v[50:51], v[62:63], v[64:65]
	s_nop 0
	v_pk_add_f32 v[26:27], v[26:27], v[50:51]
	s_nop 0
	v_add_f32_e32 v26, v26, v27
	s_nop 1
	v_add_f32_dpp v26, v26, v26 quad_perm:[1,0,3,2] row_mask:0xf bank_mask:0xf bound_ctrl:1
	s_nop 1
	v_add_f32_dpp v26, v26, v26 quad_perm:[2,3,0,1] row_mask:0xf bank_mask:0xf bound_ctrl:1
	s_nop 1
	v_add_f32_dpp v26, v26, v26 row_half_mirror row_mask:0xf bank_mask:0xf bound_ctrl:1
	s_nop 1
	v_add_f32_dpp v26, v26, v26 row_mirror row_mask:0xf bank_mask:0xf bound_ctrl:1
	s_nop 0
	v_readlane_b32 s8, v26, 16
	v_readlane_b32 s9, v26, 48
	v_readlane_b32 s6, v26, 0
	v_readlane_b32 s7, v26, 32
	v_mov_b32_e32 v26, s8
	v_mov_b32_e32 v27, s9
	v_pk_add_f32 v[26:27], s[6:7], v[26:27]
	s_nop 0
	v_add_f32_e32 v26, v26, v27
	v_fmamk_f32 v26, v26, 0x3a000000, v252
	v_cmp_gt_f32_e32 vcc, s55, v26
	v_mul_f32_e32 v27, 0x4f800000, v26
	s_nop 0
	v_cndmask_b32_e32 v26, v26, v27, vcc
	v_sqrt_f32_e32 v27, v26
	s_nop 0
	v_add_u32_e32 v50, -1, v27
	v_fma_f32 v51, -v50, v27, v26
	v_cmp_ge_f32_e64 s[8:9], 0, v51
	v_add_u32_e32 v51, 1, v27
	s_nop 0
	v_cndmask_b32_e64 v50, v27, v50, s[8:9]
	v_fma_f32 v27, -v51, v27, v26
	v_cmp_lt_f32_e64 s[8:9], 0, v27
	s_nop 1
	v_cndmask_b32_e64 v27, v50, v51, s[8:9]
	v_mul_f32_e32 v50, 0x37800000, v27
	v_cndmask_b32_e32 v27, v27, v50, vcc
	v_cmp_class_f32_e32 vcc, v26, v253
	s_nop 1
	v_cndmask_b32_e32 v26, v27, v26, vcc
	v_div_scale_f32 v27, s[6:7], v26, v26, 1.0
	v_rcp_f32_e32 v50, v27
	s_lshl_b32 s6, s18, 1
	s_and_b32 s6, s6, 0xffffe000
	s_add_i32 s6, s6, 0
	v_fma_f32 v51, -v27, v50, 1.0
	v_fmac_f32_e32 v50, v51, v50
	v_div_scale_f32 v51, vcc, 1.0, v26, 1.0
	v_mul_f32_e32 v60, v51, v50
	v_fma_f32 v61, -v27, v60, v51
	v_fmac_f32_e32 v60, v61, v50
	v_fma_f32 v27, -v27, v60, v51
	v_div_fmas_f32 v27, v27, v50, v60
	v_div_fixup_f32 v50, v27, v26, 1.0
	v_pk_mul_f32 v[64:65], v[56:57], v[50:51] op_sel_hi:[1,0]
	v_pk_mul_f32 v[66:67], v[58:59], v[50:51] op_sel_hi:[1,0]
	v_add_u32_e32 v51, s6, v0
	ds_read_b128 v[56:59], v51
	ds_read_b128 v[60:63], v51 offset:40960
	v_lshl_add_u64 v[26:27], s[20:21], 1, v[2:3]
	v_lshl_add_u64 v[26:27], v[26:27], 0, v[6:7]
	v_pk_mul_f32 v[4:5], v[4:5], v[50:51] op_sel_hi:[1,0]
	v_pk_mul_f32 v[30:31], v[30:31], v[50:51] op_sel_hi:[1,0]
	s_waitcnt lgkmcnt(0)
	v_pk_fma_f32 v[58:59], v[58:59], v[66:67], v[62:63]
	v_pk_fma_f32 v[56:57], v[56:57], v[64:65], v[60:61]
	v_pk_mul_f32 v[60:61], v[52:53], v[50:51] op_sel_hi:[1,0]
	v_cvt_pk_bf16_f32 v56, v56, v57
	v_cvt_pk_bf16_f32 v57, v58, v59
	global_store_dwordx2 v[26:27], v[56:57], off
	v_pk_mul_f32 v[62:63], v[54:55], v[50:51] op_sel_hi:[1,0]
	ds_read_b128 v[52:55], v51 offset:1024
	ds_read_b128 v[56:59], v51 offset:41984
	s_waitcnt lgkmcnt(0)
	v_pk_fma_f32 v[54:55], v[54:55], v[62:63], v[58:59]
	v_pk_fma_f32 v[52:53], v[52:53], v[60:61], v[56:57]
	v_pk_mul_f32 v[56:57], v[42:43], v[50:51] op_sel_hi:[1,0]
	v_cvt_pk_bf16_f32 v52, v52, v53
	v_cvt_pk_bf16_f32 v53, v54, v55
	global_store_dwordx2 v[26:27], v[52:53], off offset:512
	v_pk_mul_f32 v[58:59], v[44:45], v[50:51] op_sel_hi:[1,0]
	ds_read_b128 v[42:45], v51 offset:2048
	ds_read_b128 v[52:55], v51 offset:43008
	s_waitcnt lgkmcnt(0)
	v_pk_fma_f32 v[44:45], v[44:45], v[58:59], v[54:55]
	v_pk_fma_f32 v[42:43], v[42:43], v[56:57], v[52:53]
	v_pk_mul_f32 v[52:53], v[46:47], v[50:51] op_sel_hi:[1,0]
	v_cvt_pk_bf16_f32 v42, v42, v43
	v_cvt_pk_bf16_f32 v43, v44, v45
	global_store_dwordx2 v[26:27], v[42:43], off offset:1024
	v_pk_mul_f32 v[54:55], v[48:49], v[50:51] op_sel_hi:[1,0]
	ds_read_b128 v[42:45], v51 offset:3072
	ds_read_b128 v[46:49], v51 offset:44032
	s_waitcnt lgkmcnt(0)
	v_pk_fma_f32 v[44:45], v[54:55], v[44:45], v[48:49]
	v_pk_fma_f32 v[42:43], v[52:53], v[42:43], v[46:47]
	v_pk_mul_f32 v[46:47], v[34:35], v[50:51] op_sel_hi:[1,0]
	v_cvt_pk_bf16_f32 v42, v42, v43
	v_cvt_pk_bf16_f32 v43, v44, v45
	global_store_dwordx2 v[26:27], v[42:43], off offset:1536
	v_pk_mul_f32 v[48:49], v[36:37], v[50:51] op_sel_hi:[1,0]
	ds_read_b128 v[34:37], v51 offset:4096
	ds_read_b128 v[42:45], v51 offset:45056
	s_waitcnt lgkmcnt(0)
	v_pk_fma_f32 v[36:37], v[48:49], v[36:37], v[44:45]
	v_pk_fma_f32 v[34:35], v[46:47], v[34:35], v[42:43]
	v_pk_mul_f32 v[42:43], v[38:39], v[50:51] op_sel_hi:[1,0]
	v_cvt_pk_bf16_f32 v34, v34, v35
	v_cvt_pk_bf16_f32 v35, v36, v37
	global_store_dwordx2 v[26:27], v[34:35], off offset:2048
	v_pk_mul_f32 v[44:45], v[40:41], v[50:51] op_sel_hi:[1,0]
	ds_read_b128 v[34:37], v51 offset:5120
	ds_read_b128 v[38:41], v51 offset:46080
	s_waitcnt lgkmcnt(0)
	v_pk_fma_f32 v[36:37], v[44:45], v[36:37], v[40:41]
	v_pk_fma_f32 v[34:35], v[42:43], v[34:35], v[38:39]
	s_waitcnt vmcnt(60)
; __device__ __forceinline__ void norm_mod_phase2(const Args& a, Frame& F, const float* gain, const float* modl, int sh_off, int sc_off, int nrows, const float* slab_gate) {
;     ...
;     NR_FINISH(r7, nw + 7 * 2048, (nw + 7 * 2048) >> 12);
	v_cvt_f32_f16_sdwa v43, v25 dst_sel:DWORD dst_unused:UNUSED_PAD src0_sel:WORD_1
	v_cvt_pk_bf16_f32 v34, v34, v35
	v_cvt_pk_bf16_f32 v35, v36, v37
	global_store_dwordx2 v[26:27], v[34:35], off offset:2560
	ds_read_b128 v[34:37], v51 offset:6144
	ds_read_b128 v[38:41], v51 offset:47104
	v_cvt_f32_f16_e32 v42, v25
	s_waitcnt lgkmcnt(0)
	v_pk_fma_f32 v[30:31], v[30:31], v[36:37], v[40:41]
	v_pk_fma_f32 v[4:5], v[4:5], v[34:35], v[38:39]
	v_pk_mul_f32 v[36:37], v[32:33], v[50:51] op_sel_hi:[1,0]
	v_cvt_pk_bf16_f32 v4, v4, v5
	v_cvt_pk_bf16_f32 v5, v30, v31
	global_store_dwordx2 v[26:27], v[4:5], off offset:3072
	v_pk_mul_f32 v[4:5], v[28:29], v[50:51] op_sel_hi:[1,0]
	ds_read_b128 v[28:31], v51 offset:7168
	ds_read_b128 v[32:35], v51 offset:48128
	v_cvt_f32_f16_sdwa v41, v24 dst_sel:DWORD dst_unused:UNUSED_PAD src0_sel:WORD_1
	v_cvt_f32_f16_e32 v40, v24
	s_waitcnt vmcnt(61)
	v_cvt_f32_f16_sdwa v39, v23 dst_sel:DWORD dst_unused:UNUSED_PAD src0_sel:WORD_1
	v_cvt_f32_f16_e32 v38, v23
	s_waitcnt lgkmcnt(0)
	v_pk_fma_f32 v[30:31], v[36:37], v[30:31], v[34:35]
	v_cvt_f32_f16_sdwa v37, v22 dst_sel:DWORD dst_unused:UNUSED_PAD src0_sel:WORD_1
	v_cvt_f32_f16_e32 v36, v22
	v_pk_fma_f32 v[4:5], v[4:5], v[28:29], v[32:33]
	v_mov_b32_e32 v22, v41
	v_cvt_pk_bf16_f32 v4, v4, v5
	v_cvt_pk_bf16_f32 v5, v30, v31
	global_store_dwordx2 v[26:27], v[4:5], off offset:3584
	v_mov_b32_e32 v23, v37
	s_waitcnt vmcnt(61)
	v_cvt_f32_f16_sdwa v27, v20 dst_sel:DWORD dst_unused:UNUSED_PAD src0_sel:WORD_1
	v_cvt_f32_f16_sdwa v29, v21 dst_sel:DWORD dst_unused:UNUSED_PAD src0_sel:WORD_1
	v_mov_b32_e32 v4, v40
	v_mov_b32_e32 v5, v36
	v_pk_mul_f32 v[22:23], v[22:23], v[22:23]
	v_mov_b32_e32 v24, v43
	v_mov_b32_e32 v25, v39
	v_cvt_f32_f16_e32 v26, v20
	v_cvt_f32_f16_e32 v28, v21
	s_waitcnt vmcnt(60)
	v_cvt_f32_f16_sdwa v31, v18 dst_sel:DWORD dst_unused:UNUSED_PAD src0_sel:WORD_1
	v_pk_fma_f32 v[4:5], v[4:5], v[4:5], v[22:23]
	v_mov_b32_e32 v22, v42
	v_mov_b32_e32 v23, v38
	v_pk_mul_f32 v[24:25], v[24:25], v[24:25]
	v_cvt_f32_f16_e32 v30, v18
	v_cvt_f32_f16_sdwa v33, v19 dst_sel:DWORD dst_unused:UNUSED_PAD src0_sel:WORD_1
	v_pk_fma_f32 v[22:23], v[22:23], v[22:23], v[24:25]
	v_cvt_f32_f16_e32 v32, v19
	v_pk_add_f32 v[4:5], v[4:5], v[22:23]
	v_mov_b32_e32 v22, v27
	v_mov_b32_e32 v23, v29
	v_mov_b32_e32 v20, v26
	v_mov_b32_e32 v21, v28
	v_pk_mul_f32 v[22:23], v[22:23], v[22:23]
	v_mul_f32_e32 v18, v31, v31
	v_pk_fma_f32 v[20:21], v[20:21], v[20:21], v[22:23]
	v_pk_fma_f32 v[24:25], v[30:31], v[30:31], v[18:19] op_sel_hi:[1,1,0]
	v_mul_f32_e32 v18, v33, v33
	v_pk_add_f32 v[22:23], v[20:21], v[20:21] op_sel:[0,1] op_sel_hi:[1,0]
	v_pk_fma_f32 v[34:35], v[32:33], v[32:33], v[18:19] op_sel_hi:[1,1,0]
	s_waitcnt vmcnt(59)
	v_cvt_f32_f16_sdwa v19, v16 dst_sel:DWORD dst_unused:UNUSED_PAD src0_sel:WORD_1
	v_cvt_f32_f16_e32 v18, v16
	v_cvt_f32_f16_sdwa v21, v17 dst_sel:DWORD dst_unused:UNUSED_PAD src0_sel:WORD_1
	v_cvt_f32_f16_e32 v20, v17
	v_pk_add_f32 v[4:5], v[4:5], v[4:5] op_sel:[0,1] op_sel_hi:[1,0]
	v_pk_mul_f32 v[16:17], v[18:19], v[18:19]
	v_pk_mul_f32 v[44:45], v[20:21], v[20:21]
	v_mov_b32_e32 v5, v16
	v_mov_b32_e32 v23, v17
	v_mov_b32_e32 v25, v44
	v_mov_b32_e32 v35, v45
	v_pk_add_f32 v[4:5], v[4:5], v[22:23]
	v_pk_add_f32 v[16:17], v[24:25], v[34:35]
	s_waitcnt vmcnt(58)
	v_cvt_f32_f16_sdwa v23, v14 dst_sel:DWORD dst_unused:UNUSED_PAD src0_sel:WORD_1
	v_cvt_f32_f16_sdwa v25, v15 dst_sel:DWORD dst_unused:UNUSED_PAD src0_sel:WORD_1
	v_cvt_f32_f16_e32 v22, v14
	v_cvt_f32_f16_e32 v24, v15
	v_pk_add_f32 v[4:5], v[4:5], v[16:17]
	v_mov_b32_e32 v14, v23
	v_mov_b32_e32 v15, v25
	v_pk_add_f32 v[34:35], v[4:5], v[4:5] op_sel:[0,1] op_sel_hi:[1,0]
	v_mov_b32_e32 v4, v22
	v_mov_b32_e32 v5, v24
	v_pk_mul_f32 v[14:15], v[14:15], v[14:15]
	s_waitcnt vmcnt(56)
	v_cvt_f32_f16_sdwa v17, v11 dst_sel:DWORD dst_unused:UNUSED_PAD src0_sel:WORD_1
	v_pk_fma_f32 v[4:5], v[4:5], v[4:5], v[14:15]
	v_cvt_f32_f16_sdwa v15, v13 dst_sel:DWORD dst_unused:UNUSED_PAD src0_sel:WORD_1
	v_pk_add_f32 v[44:45], v[4:5], v[4:5] op_sel:[0,1] op_sel_hi:[1,0]
	v_cvt_f32_f16_sdwa v5, v12 dst_sel:DWORD dst_unused:UNUSED_PAD src0_sel:WORD_1
	v_cvt_f32_f16_e32 v4, v12
	v_cvt_f32_f16_e32 v14, v13
	v_cvt_f32_f16_e32 v16, v11
	v_mul_f32_e32 v12, v5, v5
	v_pk_fma_f32 v[46:47], v[4:5], v[4:5], v[12:13] op_sel_hi:[1,1,0]
	v_mul_f32_e32 v12, v15, v15
	v_pk_fma_f32 v[48:49], v[14:15], v[14:15], v[12:13] op_sel_hi:[1,1,0]
	v_cvt_f32_f16_sdwa v13, v10 dst_sel:DWORD dst_unused:UNUSED_PAD src0_sel:WORD_1
	v_cvt_f32_f16_e32 v12, v10
	v_pk_mul_f32 v[50:51], v[16:17], v[16:17]
	v_pk_mul_f32 v[10:11], v[12:13], v[12:13]
	s_nop 0
	v_mov_b32_e32 v35, v10
	v_mov_b32_e32 v45, v11
	v_mov_b32_e32 v47, v50
	v_mov_b32_e32 v49, v51
	v_pk_add_f32 v[10:11], v[34:35], v[44:45]
	v_pk_add_f32 v[34:35], v[46:47], v[48:49]
	s_nop 0
	v_pk_add_f32 v[10:11], v[10:11], v[34:35]
	s_nop 0
	v_add_f32_e32 v10, v10, v11
	s_nop 1
	v_add_f32_dpp v10, v10, v10 quad_perm:[1,0,3,2] row_mask:0xf bank_mask:0xf bound_ctrl:1
	s_nop 1
	v_add_f32_dpp v10, v10, v10 quad_perm:[2,3,0,1] row_mask:0xf bank_mask:0xf bound_ctrl:1
	s_nop 1
	v_add_f32_dpp v10, v10, v10 row_half_mirror row_mask:0xf bank_mask:0xf bound_ctrl:1
	s_nop 1
	v_add_f32_dpp v10, v10, v10 row_mirror row_mask:0xf bank_mask:0xf bound_ctrl:1
	s_nop 0
	v_readlane_b32 s8, v10, 16
	v_readlane_b32 s9, v10, 48
	v_readlane_b32 s6, v10, 0
	v_readlane_b32 s7, v10, 32
	v_mov_b32_e32 v10, s8
	v_mov_b32_e32 v11, s9
	v_pk_add_f32 v[10:11], s[6:7], v[10:11]
	s_nop 0
	v_add_f32_e32 v10, v10, v11
	v_fmamk_f32 v10, v10, 0x3a000000, v252
	v_cmp_gt_f32_e32 vcc, s55, v10
	v_mul_f32_e32 v11, 0x4f800000, v10
	s_nop 0
	v_cndmask_b32_e32 v10, v10, v11, vcc
	v_sqrt_f32_e32 v11, v10
	s_nop 0
	v_add_u32_e32 v34, -1, v11
	v_fma_f32 v35, -v34, v11, v10
	v_cmp_ge_f32_e64 s[8:9], 0, v35
	v_add_u32_e32 v35, 1, v11
	s_nop 0
	v_cndmask_b32_e64 v34, v11, v34, s[8:9]
	v_fma_f32 v11, -v35, v11, v10
	v_cmp_lt_f32_e64 s[8:9], 0, v11
	s_nop 1
	v_cndmask_b32_e64 v11, v34, v35, s[8:9]
	v_mul_f32_e32 v34, 0x37800000, v11
	v_cndmask_b32_e32 v11, v11, v34, vcc
	v_cmp_class_f32_e32 vcc, v10, v253
	s_add_i32 s8, s10, 0x4000
	s_nop 0
	v_cndmask_b32_e32 v10, v11, v10, vcc
	v_div_scale_f32 v11, s[6:7], v10, v10, 1.0
	v_rcp_f32_e32 v34, v11
	s_lshl_b32 s6, s14, 1
	s_and_b32 s6, s6, 0xffffe000
	s_add_i32 s6, s6, 0
	v_fma_f32 v35, -v11, v34, 1.0
	v_fmac_f32_e32 v34, v35, v34
	v_div_scale_f32 v35, vcc, 1.0, v10, 1.0
	v_mul_f32_e32 v44, v35, v34
	v_fma_f32 v45, -v11, v44, v35
	v_fmac_f32_e32 v44, v45, v34
	v_fma_f32 v11, -v11, v44, v35
	v_div_fmas_f32 v11, v11, v34, v44
	v_div_fixup_f32 v34, v11, v10, 1.0
	v_pk_mul_f32 v[48:49], v[40:41], v[34:35] op_sel_hi:[1,0]
	v_pk_mul_f32 v[50:51], v[42:43], v[34:35] op_sel_hi:[1,0]
	v_add_u32_e32 v35, s6, v0
	ds_read_b128 v[40:43], v35
	ds_read_b128 v[44:47], v35 offset:40960
	v_lshl_add_u64 v[10:11], s[16:17], 1, v[2:3]
	v_lshl_add_u64 v[10:11], v[10:11], 0, v[6:7]
	v_pk_mul_f32 v[4:5], v[4:5], v[34:35] op_sel_hi:[1,0]
	v_pk_mul_f32 v[14:15], v[14:15], v[34:35] op_sel_hi:[1,0]
	s_waitcnt lgkmcnt(0)
; #define GAS __attribute__((address_space(1)))
; __device__ __forceinline__ void norm_mod_phase2(const Args& a, Frame& F, const float* gain, const float* modl, int sh_off, int sc_off, int nrows, const float* slab_gate) {
;     ...
;     if (ML + nw < nrows) {
;         const int r = ML + nw, rc = nw;
;         const GAS v2u* xr = (const GAS v2u*)(X + (size_t)r * D) + F.lane;
; #pragma unroll
;         for (int j = 0; j < 8; ++j) r0[j] = xr[64 * j];
;         if (slab_gate != nullptr) { const GAS f32x4* sl = (const GAS f32x4*)((const float*)(a.ws + WS_SLAB) + (size_t)rc * D) + F.lane;
; #pragma unroll
;             for (int j = 0; j < 8; ++j) { const f32x4 p = (sl[64 * j] + sl[64 * j + (size_t)MC * D / 4]) + (sl[64 * j + 2 * ((size_t)MC * D / 4)] + sl[64 * j + 3 * ((size_t)MC * D / 4)]);
	v_pk_fma_f32 v[42:43], v[42:43], v[50:51], v[46:47]
	v_pk_fma_f32 v[40:41], v[40:41], v[48:49], v[44:45]
	v_pk_mul_f32 v[44:45], v[36:37], v[34:35] op_sel_hi:[1,0]
	v_cvt_pk_bf16_f32 v40, v40, v41
	v_cvt_pk_bf16_f32 v41, v42, v43
	global_store_dwordx2 v[10:11], v[40:41], off
	v_pk_mul_f32 v[46:47], v[38:39], v[34:35] op_sel_hi:[1,0]
	ds_read_b128 v[36:39], v35 offset:1024
	ds_read_b128 v[40:43], v35 offset:41984
	s_cmp_lt_i32 s8, s47
	s_waitcnt lgkmcnt(0)
	v_pk_fma_f32 v[38:39], v[38:39], v[46:47], v[42:43]
	v_pk_fma_f32 v[36:37], v[36:37], v[44:45], v[40:41]
	v_pk_mul_f32 v[40:41], v[26:27], v[34:35] op_sel_hi:[1,0]
	v_cvt_pk_bf16_f32 v36, v36, v37
	v_cvt_pk_bf16_f32 v37, v38, v39
	global_store_dwordx2 v[10:11], v[36:37], off offset:512
	v_pk_mul_f32 v[42:43], v[28:29], v[34:35] op_sel_hi:[1,0]
	ds_read_b128 v[26:29], v35 offset:2048
	ds_read_b128 v[36:39], v35 offset:43008
	s_waitcnt lgkmcnt(0)
	v_pk_fma_f32 v[28:29], v[28:29], v[42:43], v[38:39]
	v_pk_fma_f32 v[26:27], v[26:27], v[40:41], v[36:37]
	v_pk_mul_f32 v[36:37], v[30:31], v[34:35] op_sel_hi:[1,0]
	v_cvt_pk_bf16_f32 v26, v26, v27
	v_cvt_pk_bf16_f32 v27, v28, v29
	global_store_dwordx2 v[10:11], v[26:27], off offset:1024
	v_pk_mul_f32 v[38:39], v[32:33], v[34:35] op_sel_hi:[1,0]
	ds_read_b128 v[26:29], v35 offset:3072
	ds_read_b128 v[30:33], v35 offset:44032
	s_waitcnt lgkmcnt(0)
	v_pk_fma_f32 v[28:29], v[38:39], v[28:29], v[32:33]
	v_pk_fma_f32 v[26:27], v[36:37], v[26:27], v[30:31]
	v_pk_mul_f32 v[30:31], v[18:19], v[34:35] op_sel_hi:[1,0]
	v_cvt_pk_bf16_f32 v26, v26, v27
	v_cvt_pk_bf16_f32 v27, v28, v29
	global_store_dwordx2 v[10:11], v[26:27], off offset:1536
	v_pk_mul_f32 v[32:33], v[20:21], v[34:35] op_sel_hi:[1,0]
	ds_read_b128 v[18:21], v35 offset:4096
	ds_read_b128 v[26:29], v35 offset:45056
	s_waitcnt lgkmcnt(0)
	v_pk_fma_f32 v[20:21], v[32:33], v[20:21], v[28:29]
	v_pk_fma_f32 v[18:19], v[30:31], v[18:19], v[26:27]
	v_pk_mul_f32 v[26:27], v[22:23], v[34:35] op_sel_hi:[1,0]
	v_cvt_pk_bf16_f32 v18, v18, v19
	v_cvt_pk_bf16_f32 v19, v20, v21
	global_store_dwordx2 v[10:11], v[18:19], off offset:2048
	v_pk_mul_f32 v[28:29], v[24:25], v[34:35] op_sel_hi:[1,0]
	ds_read_b128 v[18:21], v35 offset:5120
	ds_read_b128 v[22:25], v35 offset:46080
	s_waitcnt lgkmcnt(0)
	v_pk_fma_f32 v[20:21], v[28:29], v[20:21], v[24:25]
	v_pk_fma_f32 v[18:19], v[26:27], v[18:19], v[22:23]
	s_nop 0
	v_cvt_pk_bf16_f32 v18, v18, v19
	v_cvt_pk_bf16_f32 v19, v20, v21
	global_store_dwordx2 v[10:11], v[18:19], off offset:2560
	ds_read_b128 v[18:21], v35 offset:6144
	ds_read_b128 v[22:25], v35 offset:47104
	s_waitcnt lgkmcnt(0)
	v_pk_fma_f32 v[14:15], v[14:15], v[20:21], v[24:25]
	v_pk_fma_f32 v[4:5], v[4:5], v[18:19], v[22:23]
	v_pk_mul_f32 v[20:21], v[16:17], v[34:35] op_sel_hi:[1,0]
	v_cvt_pk_bf16_f32 v4, v4, v5
	v_cvt_pk_bf16_f32 v5, v14, v15
	global_store_dwordx2 v[10:11], v[4:5], off offset:3072
	v_pk_mul_f32 v[4:5], v[12:13], v[34:35] op_sel_hi:[1,0]
	ds_read_b128 v[12:15], v35 offset:7168
	ds_read_b128 v[16:19], v35 offset:48128
	s_waitcnt lgkmcnt(0)
	v_pk_fma_f32 v[14:15], v[20:21], v[14:15], v[18:19]
	v_pk_fma_f32 v[4:5], v[4:5], v[12:13], v[16:17]
	s_nop 0
	v_cvt_pk_bf16_f32 v4, v4, v5
	v_cvt_pk_bf16_f32 v5, v14, v15
	global_store_dwordx2 v[10:11], v[4:5], off offset:3584
	s_cbranch_scc0 .LBB0_1050
	s_ashr_i32 s9, s8, 31
	s_lshl_b64 s[6:7], s[8:9], 12
	v_lshl_add_u64 v[4:5], v[8:9], 0, s[6:7]
	v_lshl_add_u64 v[18:19], v[4:5], 0, v[6:7]
	global_load_dwordx2 v[22:23], v[18:19], off
	global_load_dwordx2 v[20:21], v[18:19], off offset:512
	global_load_dwordx2 v[16:17], v[18:19], off offset:1024
	global_load_dwordx2 v[12:13], v[18:19], off offset:1536
	global_load_dwordx2 v[14:15], v[18:19], off offset:2048
	global_load_dwordx2 v[10:11], v[18:19], off offset:2560
	global_load_dwordx2 v[8:9], v[18:19], off offset:3072
	global_load_dwordx2 v[4:5], v[18:19], off offset:3584
	s_andn2_b64 vcc, exec, s[4:5]
	v_lshlrev_b32_e32 v46, 2, v147
	s_cbranch_vccnz .LBB0_1049
	v_mov_b32_e32 v24, s72
	v_mov_b32_e32 v25, s73
	v_lshl_add_u64 v[24:25], s[12:13], 2, v[24:25]
	v_lshl_add_u64 v[24:25], v[24:25], 0, v[0:1]
	v_lshlrev_b32_e32 v0, 2, v46
	v_lshl_add_u64 v[26:27], s[86:87], 0, v[0:1]
	v_add_co_u32_e32 v28, vcc, 0x58400000, v24
	s_nop 1
	v_addc_co_u32_e32 v29, vcc, 0, v25, vcc
	v_add_co_u32_e32 v30, vcc, 0x58c00000, v24
	s_nop 1
	v_addc_co_u32_e32 v31, vcc, 0, v25, vcc
	v_add_co_u32_e32 v32, vcc, 0x59400000, v24
	s_nop 1
	v_addc_co_u32_e32 v33, vcc, 0, v25, vcc
	v_add_co_u32_e32 v34, vcc, 0x59c00000, v24
	s_nop 1
	v_addc_co_u32_e32 v35, vcc, 0, v25, vcc
	v_add_co_u32_e32 v36, vcc, 0x58401000, v24
	s_nop 1
	v_addc_co_u32_e32 v37, vcc, 0, v25, vcc
	v_add_co_u32_e32 v38, vcc, 0x58c01000, v24
	s_nop 1
	v_addc_co_u32_e32 v39, vcc, 0, v25, vcc
	v_add_co_u32_e32 v42, vcc, 0x59401000, v24
	s_nop 1
	v_addc_co_u32_e32 v43, vcc, 0, v25, vcc
	v_add_co_u32_e32 v44, vcc, 0x59c01000, v24
	s_nop 1
	v_addc_co_u32_e32 v45, vcc, 0, v25, vcc
	v_add_co_u32_e32 v48, vcc, 0x34000, v26
	s_nop 1
	v_addc_co_u32_e32 v49, vcc, 0, v27, vcc
	v_add_co_u32_e32 v50, vcc, 0x35000, v26
	s_nop 1
	v_addc_co_u32_e32 v51, vcc, 0, v27, vcc
	global_load_dwordx4 v[94:97], v[28:29], off
	global_load_dwordx4 v[98:101], v[30:31], off
	global_load_dwordx4 v[102:105], v[32:33], off
	global_load_dwordx4 v[106:109], v[34:35], off
	global_load_dwordx4 v[110:113], v[48:49], off
	global_load_dwordx4 v[114:117], v[28:29], off offset:1024
	global_load_dwordx4 v[118:121], v[30:31], off offset:1024
	global_load_dwordx4 v[122:125], v[32:33], off offset:1024
	global_load_dwordx4 v[126:129], v[34:35], off offset:1024
	global_load_dwordx4 v[130:133], v[48:49], off offset:1024
	global_load_dwordx4 v[134:137], v[28:29], off offset:2048
	global_load_dwordx4 v[138:141], v[30:31], off offset:2048
	global_load_dwordx4 v[142:145], v[32:33], off offset:2048
	global_load_dwordx4 v[146:149], v[34:35], off offset:2048
	global_load_dwordx4 v[150:153], v[48:49], off offset:2048
	global_load_dwordx4 v[154:157], v[28:29], off offset:3072
	global_load_dwordx4 v[158:161], v[30:31], off offset:3072
	global_load_dwordx4 v[162:165], v[32:33], off offset:3072
	global_load_dwordx4 v[170:173], v[34:35], off offset:3072
	global_load_dwordx4 v[174:177], v[48:49], off offset:3072
	s_waitcnt vmcnt(15)
; #define GAS __attribute__((address_space(1)))
; __device__ __forceinline__ unsigned xpk2(float lo, float hi) { if (XRES_F16) { const f32x2_t v = {lo, hi}; const f16x2_t h = __builtin_convertvector(v, f16x2_t); return __builtin_bit_cast(unsigned, h); } return pk2(lo, hi); }
; __device__ __forceinline__ float xlo(unsigned w) { if (XRES_F16) { const f16x2_t h = __builtin_bit_cast(f16x2_t, w); return (float)h[0]; } return __builtin_bit_cast(float, w << 16); }
; __device__ __forceinline__ float xhi(unsigned w) { if (XRES_F16) { const f16x2_t h = __builtin_bit_cast(f16x2_t, w); return (float)h[1]; } return __builtin_bit_cast(float, w & 0xffff0000u); }
; __device__ __forceinline__ void norm_mod_phase2(const Args& a, Frame& F, const float* gain, const float* modl, int sh_off, int sc_off, int nrows, const float* slab_gate) {
;     ...
;         if (slab_gate != nullptr) { const GAS f32x4* sl = (const GAS f32x4*)((const float*)(a.ws + WS_SLAB) + (size_t)rc * D) + F.lane;
; #pragma unroll
;             for (int j = 0; j < 8; ++j) { const f32x4 p = (sl[64 * j] + sl[64 * j + (size_t)MC * D / 4]) + (sl[64 * j + 2 * ((size_t)MC * D / 4)] + sl[64 * j + 3 * ((size_t)MC * D / 4)]);
;                 const f32x4 x = (f32x4){xlo(r0[j].x), xhi(r0[j].x), xlo(r0[j].y), xhi(r0[j].y)} + *(const GAS f32x4*)(slab_gate + 256 * j + 4 * F.lane) * p;
;                 v2u w; w.x = xpk2(x[0], x[1]); w.y = xpk2(x[2], x[3]); ((GAS v2u*)(X + (size_t)r * D) + F.lane)[64 * j] = w; r0[j] = w; } }
	v_pk_add_f32 v[220:221], v[94:95], v[98:99]
	v_pk_add_f32 v[222:223], v[96:97], v[100:101]
	v_pk_add_f32 v[224:225], v[102:103], v[106:107]
	v_pk_add_f32 v[226:227], v[104:105], v[108:109]
	v_cvt_f32_f16_e32 v232, v22
	v_cvt_f32_f16_sdwa v233, v22 dst_sel:DWORD dst_unused:UNUSED_PAD src0_sel:WORD_1
	v_cvt_f32_f16_e32 v234, v23
	v_cvt_f32_f16_sdwa v235, v23 dst_sel:DWORD dst_unused:UNUSED_PAD src0_sel:WORD_1
	v_pk_add_f32 v[228:229], v[220:221], v[224:225]
	v_pk_add_f32 v[230:231], v[222:223], v[226:227]
	s_nop 1
	v_pk_fma_f32 v[236:237], v[110:111], v[228:229], v[232:233]
	v_pk_fma_f32 v[238:239], v[112:113], v[230:231], v[234:235]
	s_nop 1
	v_cvt_pk_f16_f32 v22, v236, v237
	v_cvt_pk_f16_f32 v23, v238, v239
	global_store_dwordx2 v[18:19], v[22:23], off
	global_load_dwordx4 v[94:97], v[36:37], off
	global_load_dwordx4 v[98:101], v[38:39], off
	global_load_dwordx4 v[102:105], v[42:43], off
	global_load_dwordx4 v[106:109], v[44:45], off
	global_load_dwordx4 v[110:113], v[50:51], off
	s_waitcnt vmcnt(16)
	v_pk_add_f32 v[220:221], v[114:115], v[118:119]
	v_pk_add_f32 v[222:223], v[116:117], v[120:121]
	v_pk_add_f32 v[224:225], v[122:123], v[126:127]
	v_pk_add_f32 v[226:227], v[124:125], v[128:129]
	v_cvt_f32_f16_e32 v232, v20
	v_cvt_f32_f16_sdwa v233, v20 dst_sel:DWORD dst_unused:UNUSED_PAD src0_sel:WORD_1
	v_cvt_f32_f16_e32 v234, v21
	v_cvt_f32_f16_sdwa v235, v21 dst_sel:DWORD dst_unused:UNUSED_PAD src0_sel:WORD_1
	v_pk_add_f32 v[228:229], v[220:221], v[224:225]
	v_pk_add_f32 v[230:231], v[222:223], v[226:227]
	s_nop 1
	v_pk_fma_f32 v[236:237], v[130:131], v[228:229], v[232:233]
	v_pk_fma_f32 v[238:239], v[132:133], v[230:231], v[234:235]
	s_nop 1
	v_cvt_pk_f16_f32 v20, v236, v237
	v_cvt_pk_f16_f32 v21, v238, v239
	global_store_dwordx2 v[18:19], v[20:21], off offset:512
	global_load_dwordx4 v[114:117], v[36:37], off offset:1024
	global_load_dwordx4 v[118:121], v[38:39], off offset:1024
	global_load_dwordx4 v[122:125], v[42:43], off offset:1024
	global_load_dwordx4 v[126:129], v[44:45], off offset:1024
	global_load_dwordx4 v[130:133], v[50:51], off offset:1024
	s_waitcnt vmcnt(17)
	v_pk_add_f32 v[220:221], v[134:135], v[138:139]
	v_pk_add_f32 v[222:223], v[136:137], v[140:141]
	v_pk_add_f32 v[224:225], v[142:143], v[146:147]
	v_pk_add_f32 v[226:227], v[144:145], v[148:149]
	v_cvt_f32_f16_e32 v232, v16
	v_cvt_f32_f16_sdwa v233, v16 dst_sel:DWORD dst_unused:UNUSED_PAD src0_sel:WORD_1
	v_cvt_f32_f16_e32 v234, v17
	v_cvt_f32_f16_sdwa v235, v17 dst_sel:DWORD dst_unused:UNUSED_PAD src0_sel:WORD_1
	v_pk_add_f32 v[228:229], v[220:221], v[224:225]
	v_pk_add_f32 v[230:231], v[222:223], v[226:227]
	s_nop 1
	v_pk_fma_f32 v[236:237], v[150:151], v[228:229], v[232:233]
	v_pk_fma_f32 v[238:239], v[152:153], v[230:231], v[234:235]
	s_nop 1
	v_cvt_pk_f16_f32 v16, v236, v237
	v_cvt_pk_f16_f32 v17, v238, v239
	global_store_dwordx2 v[18:19], v[16:17], off offset:1024
	global_load_dwordx4 v[134:137], v[36:37], off offset:2048
	global_load_dwordx4 v[138:141], v[38:39], off offset:2048
	global_load_dwordx4 v[142:145], v[42:43], off offset:2048
	global_load_dwordx4 v[146:149], v[44:45], off offset:2048
	global_load_dwordx4 v[150:153], v[50:51], off offset:2048
	s_waitcnt vmcnt(18)
; #define GAS __attribute__((address_space(1)))
; __device__ __forceinline__ unsigned xpk2(float lo, float hi) { if (XRES_F16) { const f32x2_t v = {lo, hi}; const f16x2_t h = __builtin_convertvector(v, f16x2_t); return __builtin_bit_cast(unsigned, h); } return pk2(lo, hi); }
; __device__ __forceinline__ float xlo(unsigned w) { if (XRES_F16) { const f16x2_t h = __builtin_bit_cast(f16x2_t, w); return (float)h[0]; } return __builtin_bit_cast(float, w << 16); }
; __device__ __forceinline__ float xhi(unsigned w) { if (XRES_F16) { const f16x2_t h = __builtin_bit_cast(f16x2_t, w); return (float)h[1]; } return __builtin_bit_cast(float, w & 0xffff0000u); }
; __device__ __forceinline__ void norm_mod_phase2(const Args& a, Frame& F, const float* gain, const float* modl, int sh_off, int sc_off, int nrows, const float* slab_gate) {
;     ...
;         if (slab_gate != nullptr) { const GAS f32x4* sl = (const GAS f32x4*)((const float*)(a.ws + WS_SLAB) + (size_t)rc * D) + F.lane;
; #pragma unroll
;             for (int j = 0; j < 8; ++j) { const f32x4 p = (sl[64 * j] + sl[64 * j + (size_t)MC * D / 4]) + (sl[64 * j + 2 * ((size_t)MC * D / 4)] + sl[64 * j + 3 * ((size_t)MC * D / 4)]);
;                 const f32x4 x = (f32x4){xlo(r0[j].x), xhi(r0[j].x), xlo(r0[j].y), xhi(r0[j].y)} + *(const GAS f32x4*)(slab_gate + 256 * j + 4 * F.lane) * p;
;                 v2u w; w.x = xpk2(x[0], x[1]); w.y = xpk2(x[2], x[3]); ((GAS v2u*)(X + (size_t)r * D) + F.lane)[64 * j] = w; r0[j] = w; } }
	v_pk_add_f32 v[220:221], v[154:155], v[158:159]
	v_pk_add_f32 v[222:223], v[156:157], v[160:161]
	v_pk_add_f32 v[224:225], v[162:163], v[170:171]
	v_pk_add_f32 v[226:227], v[164:165], v[172:173]
	v_cvt_f32_f16_e32 v232, v12
	v_cvt_f32_f16_sdwa v233, v12 dst_sel:DWORD dst_unused:UNUSED_PAD src0_sel:WORD_1
	v_cvt_f32_f16_e32 v234, v13
	v_cvt_f32_f16_sdwa v235, v13 dst_sel:DWORD dst_unused:UNUSED_PAD src0_sel:WORD_1
	v_pk_add_f32 v[228:229], v[220:221], v[224:225]
	v_pk_add_f32 v[230:231], v[222:223], v[226:227]
	s_nop 1
	v_pk_fma_f32 v[236:237], v[174:175], v[228:229], v[232:233]
	v_pk_fma_f32 v[238:239], v[176:177], v[230:231], v[234:235]
	s_nop 1
	v_cvt_pk_f16_f32 v12, v236, v237
	v_cvt_pk_f16_f32 v13, v238, v239
	global_store_dwordx2 v[18:19], v[12:13], off offset:1536
	global_load_dwordx4 v[154:157], v[36:37], off offset:3072
	global_load_dwordx4 v[158:161], v[38:39], off offset:3072
	global_load_dwordx4 v[162:165], v[42:43], off offset:3072
	global_load_dwordx4 v[170:173], v[44:45], off offset:3072
	global_load_dwordx4 v[174:177], v[50:51], off offset:3072
	s_waitcnt vmcnt(18)
	v_pk_add_f32 v[220:221], v[94:95], v[98:99]
	v_pk_add_f32 v[222:223], v[96:97], v[100:101]
	v_pk_add_f32 v[224:225], v[102:103], v[106:107]
	v_pk_add_f32 v[226:227], v[104:105], v[108:109]
	v_cvt_f32_f16_e32 v232, v14
	v_cvt_f32_f16_sdwa v233, v14 dst_sel:DWORD dst_unused:UNUSED_PAD src0_sel:WORD_1
	v_cvt_f32_f16_e32 v234, v15
	v_cvt_f32_f16_sdwa v235, v15 dst_sel:DWORD dst_unused:UNUSED_PAD src0_sel:WORD_1
	v_pk_add_f32 v[228:229], v[220:221], v[224:225]
	v_pk_add_f32 v[230:231], v[222:223], v[226:227]
	s_nop 1
	v_pk_fma_f32 v[236:237], v[110:111], v[228:229], v[232:233]
	v_pk_fma_f32 v[238:239], v[112:113], v[230:231], v[234:235]
	s_nop 1
	v_cvt_pk_f16_f32 v14, v236, v237
	v_cvt_pk_f16_f32 v15, v238, v239
	global_store_dwordx2 v[18:19], v[14:15], off offset:2048
	s_waitcnt vmcnt(13)
	v_pk_add_f32 v[220:221], v[114:115], v[118:119]
	v_pk_add_f32 v[222:223], v[116:117], v[120:121]
	v_pk_add_f32 v[224:225], v[122:123], v[126:127]
	v_pk_add_f32 v[226:227], v[124:125], v[128:129]
	v_cvt_f32_f16_e32 v232, v10
	v_cvt_f32_f16_sdwa v233, v10 dst_sel:DWORD dst_unused:UNUSED_PAD src0_sel:WORD_1
	v_cvt_f32_f16_e32 v234, v11
	v_cvt_f32_f16_sdwa v235, v11 dst_sel:DWORD dst_unused:UNUSED_PAD src0_sel:WORD_1
	v_pk_add_f32 v[228:229], v[220:221], v[224:225]
	v_pk_add_f32 v[230:231], v[222:223], v[226:227]
	s_nop 1
	v_pk_fma_f32 v[236:237], v[130:131], v[228:229], v[232:233]
	v_pk_fma_f32 v[238:239], v[132:133], v[230:231], v[234:235]
	s_nop 1
	v_cvt_pk_f16_f32 v10, v236, v237
	v_cvt_pk_f16_f32 v11, v238, v239
	global_store_dwordx2 v[18:19], v[10:11], off offset:2560
	s_waitcnt vmcnt(8)
	v_pk_add_f32 v[220:221], v[134:135], v[138:139]
	v_pk_add_f32 v[222:223], v[136:137], v[140:141]
	v_pk_add_f32 v[224:225], v[142:143], v[146:147]
	v_pk_add_f32 v[226:227], v[144:145], v[148:149]
	v_cvt_f32_f16_e32 v232, v8
	v_cvt_f32_f16_sdwa v233, v8 dst_sel:DWORD dst_unused:UNUSED_PAD src0_sel:WORD_1
	v_cvt_f32_f16_e32 v234, v9
	v_cvt_f32_f16_sdwa v235, v9 dst_sel:DWORD dst_unused:UNUSED_PAD src0_sel:WORD_1
	v_pk_add_f32 v[228:229], v[220:221], v[224:225]
	v_pk_add_f32 v[230:231], v[222:223], v[226:227]
	s_nop 1
	v_pk_fma_f32 v[236:237], v[150:151], v[228:229], v[232:233]
	v_pk_fma_f32 v[238:239], v[152:153], v[230:231], v[234:235]
	s_nop 1
	v_cvt_pk_f16_f32 v8, v236, v237
	v_cvt_pk_f16_f32 v9, v238, v239
	global_store_dwordx2 v[18:19], v[8:9], off offset:3072
	s_waitcnt vmcnt(3)
	v_pk_add_f32 v[220:221], v[154:155], v[158:159]
	v_pk_add_f32 v[222:223], v[156:157], v[160:161]
	v_pk_add_f32 v[224:225], v[162:163], v[170:171]
	v_pk_add_f32 v[226:227], v[164:165], v[172:173]
	v_cvt_f32_f16_e32 v232, v4
	v_cvt_f32_f16_sdwa v233, v4 dst_sel:DWORD dst_unused:UNUSED_PAD src0_sel:WORD_1
	v_cvt_f32_f16_e32 v234, v5
	v_cvt_f32_f16_sdwa v235, v5 dst_sel:DWORD dst_unused:UNUSED_PAD src0_sel:WORD_1
	v_pk_add_f32 v[228:229], v[220:221], v[224:225]
	v_pk_add_f32 v[230:231], v[222:223], v[226:227]
	s_nop 1
	v_pk_fma_f32 v[236:237], v[174:175], v[228:229], v[232:233]
	v_pk_fma_f32 v[238:239], v[176:177], v[230:231], v[234:235]
	s_nop 1
	v_cvt_pk_f16_f32 v4, v236, v237
	v_cvt_pk_f16_f32 v5, v238, v239
	global_store_dwordx2 v[18:19], v[4:5], off offset:3584

; #define GAS __attribute__((address_space(1)))
; #define LAS __attribute__((address_space(3)))
; __device__ __forceinline__ void relaunder(Frame& F) { int t = mk_tid(); asm volatile("" : "+v"(t)); F.tid = t; F.lane = t & 63; F.wave = __builtin_amdgcn_readfirstlane(t >> 6); }
; #define FN_LOAD(dst, k_) do { const GAS v2u* xr_ = (const GAS v2u*)(X + (size_t)(nw + 2048 * (k_)) * D) + F.lane; \
;         _Pragma("unroll") for (int j = 0; j < 8; ++j) dst[j] = __builtin_nontemporal_load(xr_ + 64 * j); } while (0)
; __device__ __forceinline__ void final_norm_phase2(const Args& a, Frame& F) {
;     relaunder(F);
;     const int nw = F.vcu * NWAVES + F.wave;
;     const bf16* X = (const bf16*)(a.ws + WS_X); const float* gain = a.in[17];
;     LAS float* GL = (LAS float*)F.lds;
;     v2u r0[8], r1[8], r2[8], r3[8], r4[8], r5[8], r6[8], r7[8];
;     ...
;     FN_LOAD(r0, 0); FN_LOAD(r1, 1); FN_LOAD(r2, 2); FN_LOAD(r3, 3); FN_LOAD(r4, 4); FN_LOAD(r5, 5); FN_LOAD(r6, 6); FN_LOAD(r7, 7);
;     for (int q = F.tid; q < D / 4; q += NWAVES * 64) ((LAS f32x4*)GL)[q] = ((const GAS f32x4*)gain)[q];
.LBB0_1335:
	s_andn2_b64 vcc, exec, s[0:1]
	s_cbranch_vccnz .LBB0_1340
	s_getreg_b32 s0, hwreg(HW_REG_HW_ID, 0, 6)
	s_lshl_b32 s0, s0, 2
	s_add_i32 s0, s0, 0
	s_add_i32 s0, s0, 0x20540
	v_mov_b32_e32 v0, s0
	ds_read_b32 v0, v0
	v_mbcnt_lo_u32_b32 v1, -1, 0
	v_mbcnt_hi_u32_b32 v1, -1, v1
	s_waitcnt lgkmcnt(0)
	v_readfirstlane_b32 s0, v0
	s_nop 1
	v_lshl_add_u32 v16, s0, 6, v1
	s_nop 0
	v_readfirstlane_b32 s0, v16
	s_ashr_i32 s0, s0, 6
	s_add_i32 s0, s0, s91
	s_add_u32 s12, s26, 0x400000
	s_addc_u32 s13, s27, 0
	s_ashr_i32 s1, s0, 31
	s_lshl_b64 s[2:3], s[0:1], 12
	v_and_b32_e32 v18, 63, v16
	s_add_u32 s2, s12, s2
	v_lshlrev_b32_e32 v17, 3, v18
	s_addc_u32 s3, s13, s3
	global_load_dwordx2 v[14:15], v17, s[2:3]
	global_load_dwordx2 v[12:13], v17, s[2:3] offset:512
	global_load_dwordx2 v[10:11], v17, s[2:3] offset:1024
	global_load_dwordx2 v[8:9], v17, s[2:3] offset:1536
	global_load_dwordx2 v[6:7], v17, s[2:3] offset:2048
	global_load_dwordx2 v[4:5], v17, s[2:3] offset:2560
	global_load_dwordx2 v[2:3], v17, s[2:3] offset:3072
	global_load_dwordx2 v[0:1], v17, s[2:3] offset:3584
	s_add_i32 s2, s0, 0x800
	s_ashr_i32 s3, s2, 31
	s_lshl_b64 s[4:5], s[2:3], 12
	s_add_u32 s4, s12, s4
	s_addc_u32 s5, s13, s5
	global_load_dwordx2 v[144:145], v17, s[4:5]
	global_load_dwordx2 v[142:143], v17, s[4:5] offset:512
	global_load_dwordx2 v[140:141], v17, s[4:5] offset:1024
	global_load_dwordx2 v[138:139], v17, s[4:5] offset:1536
	global_load_dwordx2 v[136:137], v17, s[4:5] offset:2048
	global_load_dwordx2 v[134:135], v17, s[4:5] offset:2560
	global_load_dwordx2 v[132:133], v17, s[4:5] offset:3072
	global_load_dwordx2 v[130:131], v17, s[4:5] offset:3584
	s_add_i32 s4, s0, 0x1000
	s_ashr_i32 s5, s4, 31
	s_lshl_b64 s[6:7], s[4:5], 12
	s_add_u32 s6, s12, s6
	s_addc_u32 s7, s13, s7
	global_load_dwordx2 v[128:129], v17, s[6:7]
	global_load_dwordx2 v[126:127], v17, s[6:7] offset:512
	global_load_dwordx2 v[124:125], v17, s[6:7] offset:1024
	global_load_dwordx2 v[122:123], v17, s[6:7] offset:1536
	global_load_dwordx2 v[120:121], v17, s[6:7] offset:2048
	global_load_dwordx2 v[118:119], v17, s[6:7] offset:2560
	global_load_dwordx2 v[116:117], v17, s[6:7] offset:3072
	global_load_dwordx2 v[114:115], v17, s[6:7] offset:3584
	s_add_i32 s6, s0, 0x1800
	s_ashr_i32 s7, s6, 31
	s_lshl_b64 s[8:9], s[6:7], 12
	s_add_u32 s8, s12, s8
	s_addc_u32 s9, s13, s9
	global_load_dwordx2 v[112:113], v17, s[8:9]
	global_load_dwordx2 v[110:111], v17, s[8:9] offset:512
	global_load_dwordx2 v[108:109], v17, s[8:9] offset:1024
	global_load_dwordx2 v[106:107], v17, s[8:9] offset:1536
	global_load_dwordx2 v[104:105], v17, s[8:9] offset:2048
	global_load_dwordx2 v[102:103], v17, s[8:9] offset:2560
	global_load_dwordx2 v[100:101], v17, s[8:9] offset:3072
	global_load_dwordx2 v[98:99], v17, s[8:9] offset:3584
	s_add_i32 s8, s0, 0x2000
	s_ashr_i32 s9, s8, 31
	s_lshl_b64 s[10:11], s[8:9], 12
	s_add_u32 s10, s12, s10
	s_addc_u32 s11, s13, s11
	s_add_i32 s18, s0, 0x2800
	s_ashr_i32 s19, s18, 31
	global_load_dwordx2 v[96:97], v17, s[10:11]
	global_load_dwordx2 v[94:95], v17, s[10:11] offset:512
	global_load_dwordx2 v[92:93], v17, s[10:11] offset:1024
	global_load_dwordx2 v[90:91], v17, s[10:11] offset:1536
	global_load_dwordx2 v[88:89], v17, s[10:11] offset:2048
	global_load_dwordx2 v[86:87], v17, s[10:11] offset:2560
	global_load_dwordx2 v[84:85], v17, s[10:11] offset:3072
	global_load_dwordx2 v[82:83], v17, s[10:11] offset:3584
	s_lshl_b64 s[10:11], s[18:19], 12
	s_add_u32 s10, s12, s10
	s_addc_u32 s11, s13, s11
	s_add_i32 s20, s0, 0x3000
	s_ashr_i32 s21, s20, 31
	global_load_dwordx2 v[80:81], v17, s[10:11]
	global_load_dwordx2 v[78:79], v17, s[10:11] offset:512
	global_load_dwordx2 v[76:77], v17, s[10:11] offset:1024
	global_load_dwordx2 v[74:75], v17, s[10:11] offset:1536
	global_load_dwordx2 v[72:73], v17, s[10:11] offset:2048
	global_load_dwordx2 v[70:71], v17, s[10:11] offset:2560
	global_load_dwordx2 v[68:69], v17, s[10:11] offset:3072
	global_load_dwordx2 v[66:67], v17, s[10:11] offset:3584
	s_lshl_b64 s[10:11], s[20:21], 12
	s_add_u32 s10, s12, s10
	s_addc_u32 s11, s13, s11
	s_add_i32 s22, s0, 0x3800
	s_ashr_i32 s23, s22, 31
	global_load_dwordx2 v[64:65], v17, s[10:11]
	global_load_dwordx2 v[62:63], v17, s[10:11] offset:512
	global_load_dwordx2 v[60:61], v17, s[10:11] offset:1024
	global_load_dwordx2 v[58:59], v17, s[10:11] offset:1536
	global_load_dwordx2 v[56:57], v17, s[10:11] offset:2048
	global_load_dwordx2 v[54:55], v17, s[10:11] offset:2560
	global_load_dwordx2 v[52:53], v17, s[10:11] offset:3072
	global_load_dwordx2 v[50:51], v17, s[10:11] offset:3584
	s_lshl_b64 s[10:11], s[22:23], 12
	s_add_u32 s10, s12, s10
	s_addc_u32 s11, s13, s11
	global_load_dwordx2 v[46:47], v17, s[10:11]
	global_load_dwordx2 v[44:45], v17, s[10:11] offset:512
	global_load_dwordx2 v[42:43], v17, s[10:11] offset:1024
	global_load_dwordx2 v[40:41], v17, s[10:11] offset:1536
	global_load_dwordx2 v[38:39], v17, s[10:11] offset:2048
	global_load_dwordx2 v[36:37], v17, s[10:11] offset:2560
	global_load_dwordx2 v[34:35], v17, s[10:11] offset:3072
	global_load_dwordx2 v[32:33], v17, s[10:11] offset:3584
	s_movk_i32 s10, 0x200
	v_cmp_gt_i32_e32 vcc, s10, v16
	s_and_saveexec_b64 s[10:11], vcc
	s_cbranch_execz .LBB0_1339
	v_ashrrev_i32_e32 v17, 31, v16
	v_add_u32_e32 v19, 0xfffffe00, v16
	v_lshl_add_u32 v20, v16, 4, 0
	v_lshl_add_u64 v[16:17], v[16:17], 4, s[14:15]
	s_mov_b64 s[12:13], 0
	s_mov_b64 s[14:15], 0x2000
